# v33 + all wide (x2/x3/x4) flat loads/stores to global memory issued as global_*: lgkmcnt waits no longer couple to VMEM traffic (LN reductions, mLSTM units, skinny GEMMs)
# baseline (speedup 1.0000x reference)
; __device__ __forceinline__ unsigned cvt_pk_bf16(float lo, float hi) { unsigned r; asm volatile("v_cvt_pk_bf16_f32 %0, %1, %2" : "=v"(r) : "v"(lo), "v"(hi)); return r; }
; __global__ void __launch_bounds__(512) hymba_fwd(Params P0) {
;     ...
;         for (int r = gw; r < MP; r += NGW) {
;             const float* src = r < NMETA ? meta + (size_t)r * DM : (r < LTOK ? x + (size_t)(r - NMETA) * DM : nullptr);
; #pragma unroll
;             for (int j = 0; j < 8; ++j) { const int c = (lane + 64 * j) * 4; f32x4 v = {0.f, 0.f, 0.f, 0.f}; if (src) v = *(const f32x4*)(src + c);
;                 u32x2 w; w.x = cvt_pk_bf16(v[0], v[1]); w.y = cvt_pk_bf16(v[2], v[3]); *(u32x2*)(HB + (size_t)r * DM + c) = w; }
;         }
.LBB0_10:
	s_add_u32 s44, s44, s40
	s_addc_u32 s45, s45, s41
	s_add_u32 s14, s14, s42
	s_waitcnt vmcnt(0) lgkmcnt(0)
	v_cvt_pk_bf16_f32 v2, v2, v3
	v_cvt_pk_bf16_f32 v3, v4, v5
	v_lshlrev_b32_e32 v4, 1, v18
	v_mov_b32_e32 v5, v9
	s_addc_u32 s15, s15, s43
	v_lshl_add_u64 v[4:5], s[48:49], 0, v[4:5]
	s_cmpk_gt_i32 s44, 0x40ff
	global_store_dwordx2 v[4:5], v[2:3], off
	s_cbranch_scc1 .LBB0_29

; __device__ __forceinline__ unsigned cvt_pk_bf16(float lo, float hi) { unsigned r; asm volatile("v_cvt_pk_bf16_f32 %0, %1, %2" : "=v"(r) : "v"(lo), "v"(hi)); return r; }
; __global__ void __launch_bounds__(512) hymba_fwd(Params P0) {
;     ...
;             const float* src = r < NMETA ? meta + (size_t)r * DM : (r < LTOK ? x + (size_t)(r - NMETA) * DM : nullptr);
; #pragma unroll
;             for (int j = 0; j < 8; ++j) { const int c = (lane + 64 * j) * 4; f32x4 v = {0.f, 0.f, 0.f, 0.f}; if (src) v = *(const f32x4*)(src + c);
;                 u32x2 w; w.x = cvt_pk_bf16(v[0], v[1]); w.y = cvt_pk_bf16(v[2], v[3]); *(u32x2*)(HB + (size_t)r * DM + c) = w; }
.LBB0_13:
	s_cmp_lg_u64 s[46:47], 0
	v_mov_b32_e32 v2, 0
	s_cselect_b64 s[50:51], -1, 0
	s_cmp_eq_u64 s[46:47], 0
	v_mov_b32_e32 v4, 0
	v_mov_b32_e32 v5, 0
	v_mov_b32_e32 v6, 0
	v_mov_b32_e32 v7, 0
	s_cbranch_scc1 .LBB0_15
	v_mov_b32_e32 v23, v9
	v_lshl_add_u64 v[4:5], s[46:47], 0, v[22:23]
	global_load_dwordx4 v[4:7], v[4:5], off
.LBB0_15:
	s_lshl_b64 s[10:11], s[10:11], 12
	s_add_u32 s48, s59, s10
	s_addc_u32 s49, s60, s11
	s_waitcnt vmcnt(0) lgkmcnt(0)
	v_cvt_pk_bf16_f32 v4, v4, v5
	v_cvt_pk_bf16_f32 v5, v6, v7
	v_lshl_add_u64 v[6:7], s[48:49], 0, v[20:21]
	v_cndmask_b32_e64 v3, 0, 1, s[50:51]
	global_store_dwordx2 v[6:7], v[4:5], off
	v_cmp_ne_u32_e64 s[10:11], 1, v3
	s_andn2_b64 vcc, exec, s[50:51]
	v_mov_b32_e32 v3, 0
	v_mov_b32_e32 v4, 0
	v_mov_b32_e32 v5, 0
	s_cbranch_vccnz .LBB0_17
	v_mov_b32_e32 v23, v9
	v_lshl_add_u64 v[2:3], s[46:47], 0, v[22:23]
	global_load_dwordx4 v[2:5], v[2:3], off offset:1024
.LBB0_17:
	s_waitcnt vmcnt(0) lgkmcnt(0)
	v_cvt_pk_bf16_f32 v2, v2, v3
	v_cvt_pk_bf16_f32 v3, v4, v5
	v_lshl_add_u64 v[4:5], s[48:49], 0, v[24:25]
	global_store_dwordx2 v[4:5], v[2:3], off
	v_mov_b32_e32 v2, 0
	s_and_b64 vcc, exec, s[10:11]
	v_mov_b32_e32 v4, 0
	v_mov_b32_e32 v5, 0
	v_mov_b32_e32 v6, 0
	v_mov_b32_e32 v7, 0
	s_cbranch_vccnz .LBB0_19
	v_mov_b32_e32 v23, v9
	v_lshl_add_u64 v[4:5], s[46:47], 0, v[22:23]
	global_load_dwordx4 v[4:7], v[4:5], off offset:2048
.LBB0_19:
	s_waitcnt vmcnt(0) lgkmcnt(0)
	v_cvt_pk_bf16_f32 v4, v4, v5
	v_cvt_pk_bf16_f32 v5, v6, v7
	v_lshl_add_u64 v[6:7], s[48:49], 0, v[26:27]
	global_store_dwordx2 v[6:7], v[4:5], off
	s_and_b64 vcc, exec, s[10:11]
	v_mov_b32_e32 v3, 0
	v_mov_b32_e32 v4, 0
	v_mov_b32_e32 v5, 0
	s_cbranch_vccnz .LBB0_21
	v_mov_b32_e32 v23, v9
	v_lshl_add_u64 v[2:3], s[46:47], 0, v[22:23]
	global_load_dwordx4 v[2:5], v[2:3], off offset:3072
.LBB0_21:
	s_waitcnt vmcnt(0) lgkmcnt(0)
	v_cvt_pk_bf16_f32 v2, v2, v3
	v_cvt_pk_bf16_f32 v3, v4, v5
	v_lshl_add_u64 v[4:5], s[48:49], 0, v[8:9]
	global_store_dwordx2 v[4:5], v[2:3], off
	v_mov_b32_e32 v2, 0
	s_and_b64 vcc, exec, s[10:11]
	v_mov_b32_e32 v4, 0
	v_mov_b32_e32 v5, 0
	v_mov_b32_e32 v6, 0
	v_mov_b32_e32 v7, 0
	s_cbranch_vccnz .LBB0_23
	v_lshlrev_b32_e32 v4, 2, v12
	v_mov_b32_e32 v5, v9
	v_lshl_add_u64 v[4:5], s[46:47], 0, v[4:5]
	global_load_dwordx4 v[4:7], v[4:5], off
.LBB0_23:
	s_waitcnt vmcnt(0) lgkmcnt(0)
	v_cvt_pk_bf16_f32 v4, v4, v5
	v_cvt_pk_bf16_f32 v5, v6, v7
	v_lshlrev_b32_e32 v6, 1, v12
	v_mov_b32_e32 v7, v9
	v_lshl_add_u64 v[6:7], s[48:49], 0, v[6:7]
	global_store_dwordx2 v[6:7], v[4:5], off
	s_and_b64 vcc, exec, s[10:11]
	v_mov_b32_e32 v3, 0
	v_mov_b32_e32 v4, 0
	v_mov_b32_e32 v5, 0
	s_cbranch_vccnz .LBB0_25
	v_lshlrev_b32_e32 v2, 2, v14
	v_mov_b32_e32 v3, v9
	v_lshl_add_u64 v[2:3], s[46:47], 0, v[2:3]
	global_load_dwordx4 v[2:5], v[2:3], off
.LBB0_25:
	s_waitcnt vmcnt(0) lgkmcnt(0)
	v_cvt_pk_bf16_f32 v2, v2, v3
	v_cvt_pk_bf16_f32 v3, v4, v5
	v_lshlrev_b32_e32 v4, 1, v14
	v_mov_b32_e32 v5, v9
	v_lshl_add_u64 v[4:5], s[48:49], 0, v[4:5]
	global_store_dwordx2 v[4:5], v[2:3], off
	v_mov_b32_e32 v2, 0
	s_and_b64 vcc, exec, s[10:11]
	v_mov_b32_e32 v4, 0
	v_mov_b32_e32 v5, 0
	v_mov_b32_e32 v6, 0
	v_mov_b32_e32 v7, 0
	s_cbranch_vccnz .LBB0_27
	v_lshlrev_b32_e32 v4, 2, v16
	v_mov_b32_e32 v5, v9
	v_lshl_add_u64 v[4:5], s[46:47], 0, v[4:5]
	global_load_dwordx4 v[4:7], v[4:5], off
.LBB0_27:
	s_waitcnt vmcnt(0) lgkmcnt(0)
	v_cvt_pk_bf16_f32 v4, v4, v5
	v_cvt_pk_bf16_f32 v5, v6, v7
	v_lshlrev_b32_e32 v6, 1, v16
	v_mov_b32_e32 v7, v9
	v_lshl_add_u64 v[6:7], s[48:49], 0, v[6:7]
	global_store_dwordx2 v[6:7], v[4:5], off
	s_and_b64 vcc, exec, s[10:11]
	v_mov_b32_e32 v3, 0
	v_mov_b32_e32 v4, 0
	v_mov_b32_e32 v5, 0
	s_cbranch_vccnz .LBB0_10
	v_lshlrev_b32_e32 v2, 2, v18
	v_mov_b32_e32 v3, v9
	v_lshl_add_u64 v[2:3], s[46:47], 0, v[2:3]
	global_load_dwordx4 v[2:5], v[2:3], off
	s_branch .LBB0_10

; __device__ __forceinline__ unsigned cvt_pk_bf16(float lo, float hi) { unsigned r; asm volatile("v_cvt_pk_bf16_f32 %0, %1, %2" : "=v"(r) : "v"(lo), "v"(hi)); return r; }
; __device__ __forceinline__ void transpose_item(const float* __restrict__ W, int K, int N, int nblk, bf16_t* __restrict__ WT, int mode, float* scr, int item, int lane) {
;     ...
; #pragma unroll
;     for (int i = 0; i < 32; ++i) { const int kk = 2 * i + (lane >> 5); scr[kk * 33 + (lane & 31)] = wv[i]; }
;     asm volatile("s_waitcnt lgkmcnt(0)" ::: "memory");
;     const int c = lane & 7;
; #pragma unroll
;     for (int j = 0; j < 4; ++j) { const int nn = (lane >> 3) + 8 * j; const float* s = scr + (8 * c) * 33 + nn;
;         u32x4 o; o.x = cvt_pk_bf16(s[0 * 33], s[1 * 33]); o.y = cvt_pk_bf16(s[2 * 33], s[3 * 33]); o.z = cvt_pk_bf16(s[4 * 33], s[5 * 33]); o.w = cvt_pk_bf16(s[6 * 33], s[7 * 33]);
;         *(u32x4*)(WT + (size_t)(n0 + nn) * K + k0 + 8 * c) = o; }
;     asm volatile("s_waitcnt lgkmcnt(0)" ::: "memory");
; }
.LBB0_31:
	s_or_b64 exec, exec, s[12:13]
	v_add_u32_e32 v6, 0x400, v13
	s_waitcnt vmcnt(0) lgkmcnt(0)
	ds_write2_b32 v13, v8, v20 offset1:66
	ds_write2_b32 v13, v22, v21 offset0:132 offset1:198
	ds_write2_b32 v6, v24, v23 offset0:8 offset1:74
	ds_write2_b32 v6, v26, v25 offset0:140 offset1:206
	v_add_u32_e32 v6, 0x800, v13
	ds_write2_b32 v6, v28, v27 offset0:16 offset1:82
	ds_write2_b32 v6, v30, v29 offset0:148 offset1:214
	v_add_u32_e32 v6, 0xc00, v13
	ds_write2_b32 v6, v32, v31 offset0:24 offset1:90
	ds_write2_b32 v6, v34, v33 offset0:156 offset1:222
	v_add_u32_e32 v6, 0x1000, v13
	ds_write2_b32 v6, v36, v35 offset0:32 offset1:98
	ds_write2_b32 v6, v38, v37 offset0:164 offset1:230
	v_add_u32_e32 v6, 0x1400, v13
	ds_write2_b32 v6, v40, v39 offset0:40 offset1:106
	ds_write2_b32 v6, v42, v41 offset0:172 offset1:238
	v_add_u32_e32 v6, 0x1800, v13
	ds_write2_b32 v6, v44, v43 offset0:48 offset1:114
	ds_write2_b32 v6, v46, v45 offset0:180 offset1:246
	v_add_u32_e32 v6, 0x1c00, v13
	ds_write2_b32 v6, v48, v47 offset0:56 offset1:122
	ds_write2_b32 v6, v50, v49 offset0:188 offset1:254
	s_waitcnt lgkmcnt(0)
	ds_read2_b32 v[6:7], v15 offset1:33
	s_waitcnt lgkmcnt(0)
	v_cvt_pk_bf16_f32 v20, v6, v7
	ds_read2_b32 v[6:7], v15 offset0:66 offset1:99
	s_waitcnt lgkmcnt(0)
	v_cvt_pk_bf16_f32 v21, v6, v7
	ds_read2_b32 v[6:7], v15 offset0:132 offset1:165
	s_waitcnt lgkmcnt(0)
	v_cvt_pk_bf16_f32 v22, v6, v7
	ds_read2_b32 v[6:7], v15 offset0:198 offset1:231
	s_waitcnt lgkmcnt(0)
	v_cvt_pk_bf16_f32 v23, v6, v7
	v_add_u32_e32 v6, s20, v14
	s_ashr_i32 s11, s10, 31
	v_ashrrev_i32_e32 v7, 31, v6
	v_lshl_add_u64 v[24:25], s[10:11], 1, v[4:5]
	v_lshlrev_b64 v[28:29], 12, v[6:7]
	v_lshl_add_u64 v[28:29], v[24:25], 0, v[28:29]
	ds_read2_b32 v[26:27], v15 offset0:8 offset1:41
	global_store_dwordx4 v[28:29], v[20:23], off
	s_waitcnt lgkmcnt(0)
	s_nop 0
	v_cvt_pk_bf16_f32 v20, v26, v27
	ds_read2_b32 v[22:23], v15 offset0:74 offset1:107
	s_waitcnt lgkmcnt(0)
	v_cvt_pk_bf16_f32 v21, v22, v23
	ds_read2_b32 v[22:23], v15 offset0:140 offset1:173
	s_waitcnt lgkmcnt(0)
	v_cvt_pk_bf16_f32 v22, v22, v23
	ds_read2_b32 v[26:27], v15 offset0:206 offset1:239
	s_waitcnt lgkmcnt(0)
	v_cvt_pk_bf16_f32 v23, v26, v27
	v_add_u32_e32 v26, 8, v6
	v_ashrrev_i32_e32 v27, 31, v26
	v_lshlrev_b64 v[26:27], 12, v[26:27]
	ds_read2_b32 v[28:29], v15 offset0:16 offset1:49
	v_lshl_add_u64 v[26:27], v[24:25], 0, v[26:27]
	global_store_dwordx4 v[26:27], v[20:23], off
	s_waitcnt lgkmcnt(0)
	s_nop 0
	v_cvt_pk_bf16_f32 v20, v28, v29
	v_add_u32_e32 v28, 16, v6
	ds_read2_b32 v[22:23], v15 offset0:82 offset1:115
	v_ashrrev_i32_e32 v29, 31, v28
	s_waitcnt lgkmcnt(0)
	v_cvt_pk_bf16_f32 v21, v22, v23
	ds_read2_b32 v[22:23], v15 offset0:148 offset1:181
	v_lshlrev_b64 v[28:29], 12, v[28:29]
	v_add_u32_e32 v6, 24, v6
	s_waitcnt lgkmcnt(0)
	v_cvt_pk_bf16_f32 v22, v22, v23
	ds_read2_b32 v[26:27], v15 offset0:214 offset1:247
	s_waitcnt lgkmcnt(0)
	v_cvt_pk_bf16_f32 v23, v26, v27
	v_lshl_add_u64 v[28:29], v[24:25], 0, v[28:29]
	v_ashrrev_i32_e32 v7, 31, v6
	ds_read2_b32 v[26:27], v15 offset0:24 offset1:57
	global_store_dwordx4 v[28:29], v[20:23], off
	v_lshlrev_b64 v[6:7], 12, v[6:7]
	v_lshl_add_u64 v[6:7], v[24:25], 0, v[6:7]
	s_waitcnt lgkmcnt(0)
	v_cvt_pk_bf16_f32 v20, v26, v27
	ds_read2_b32 v[22:23], v15 offset0:90 offset1:123
	s_waitcnt lgkmcnt(0)
	v_cvt_pk_bf16_f32 v21, v22, v23
	ds_read2_b32 v[22:23], v15 offset0:156 offset1:189
	s_waitcnt lgkmcnt(0)
	v_cvt_pk_bf16_f32 v22, v22, v23
	ds_read2_b32 v[26:27], v15 offset0:222 offset1:255
	s_waitcnt lgkmcnt(0)
	v_cvt_pk_bf16_f32 v23, v26, v27
	global_store_dwordx4 v[6:7], v[20:23], off
	s_waitcnt lgkmcnt(0)

; __device__ __forceinline__ void transpose_item(const float* __restrict__ W, int K, int N, int nblk, bf16_t* __restrict__ WT, int mode, float* scr, int item, int lane) {
;     ...
;     float wv[32];
; #pragma unroll
;     for (int i = 0; i < 32; ++i) { const int kk = 2 * i + (lane >> 5); wv[i] = src >= 0 ? W[(size_t)(k0 + kk) * N + src] : 0.f; }
.LBB0_35:
	s_add_i32 s10, s36, 0xe700
	s_and_b32 s11, s10, 0xffc0
	s_and_b32 s10, s14, 0x7e0
	v_or_b32_e32 v6, s10, v11
	v_or_b32_e32 v19, s11, v12
	v_lshlrev_b32_e32 v8, 2, v6
	v_lshl_add_u64 v[6:7], s[34:35], 0, v[8:9]
	v_lshlrev_b32_e32 v8, 13, v19
	v_lshl_add_u64 v[6:7], v[6:7], 0, v[8:9]
	v_add_co_u32_e32 v20, vcc, 0x4000, v6
	s_lshl_b32 s20, s11, 1
	s_nop 0
	v_addc_co_u32_e32 v21, vcc, 0, v7, vcc
	v_add_co_u32_e32 v22, vcc, 0x8000, v6
	s_nop 1
	v_addc_co_u32_e32 v23, vcc, 0, v7, vcc
	v_add_co_u32_e32 v24, vcc, 0xc000, v6
	s_nop 1
	v_addc_co_u32_e32 v25, vcc, 0, v7, vcc
	v_add_co_u32_e32 v26, vcc, 0x10000, v6
	s_nop 1
	v_addc_co_u32_e32 v27, vcc, 0, v7, vcc
	v_add_co_u32_e32 v28, vcc, 0x14000, v6
	s_nop 1
	v_addc_co_u32_e32 v29, vcc, 0, v7, vcc
	v_add_co_u32_e32 v30, vcc, 0x18000, v6
	s_nop 1
	v_addc_co_u32_e32 v31, vcc, 0, v7, vcc
	v_add_co_u32_e32 v32, vcc, 0x1c000, v6
	s_nop 1
	v_addc_co_u32_e32 v33, vcc, 0, v7, vcc
	flat_load_dword v8, v[6:7]
	flat_load_dword v19, v[20:21]
	flat_load_dword v36, v[22:23]
	flat_load_dword v37, v[24:25]
	flat_load_dword v38, v[26:27]
	flat_load_dword v39, v[28:29]
	flat_load_dword v40, v[30:31]
	flat_load_dword v41, v[32:33]
	v_add_co_u32_e32 v20, vcc, 0x20000, v6
	s_nop 1
	v_addc_co_u32_e32 v21, vcc, 0, v7, vcc
	v_add_co_u32_e32 v22, vcc, 0x24000, v6
	s_nop 1
	v_addc_co_u32_e32 v23, vcc, 0, v7, vcc
	v_add_co_u32_e32 v24, vcc, 0x28000, v6
	s_nop 1
	v_addc_co_u32_e32 v25, vcc, 0, v7, vcc
	v_add_co_u32_e32 v26, vcc, 0x2c000, v6
	s_nop 1
	v_addc_co_u32_e32 v27, vcc, 0, v7, vcc
	v_add_co_u32_e32 v28, vcc, 0x30000, v6
	s_nop 1
	v_addc_co_u32_e32 v29, vcc, 0, v7, vcc
	v_add_co_u32_e32 v30, vcc, 0x34000, v6
	s_nop 1
	v_addc_co_u32_e32 v31, vcc, 0, v7, vcc
	v_add_co_u32_e32 v32, vcc, 0x38000, v6
	s_nop 1
	v_addc_co_u32_e32 v33, vcc, 0, v7, vcc
	v_add_co_u32_e32 v34, vcc, 0x3c000, v6
	s_nop 1
	v_addc_co_u32_e32 v35, vcc, 0, v7, vcc
	flat_load_dword v42, v[20:21]
	flat_load_dword v43, v[22:23]
	flat_load_dword v44, v[24:25]
	flat_load_dword v45, v[26:27]
	flat_load_dword v46, v[28:29]
	flat_load_dword v47, v[30:31]
	flat_load_dword v48, v[32:33]
	flat_load_dword v49, v[34:35]
	v_add_co_u32_e32 v20, vcc, 0x40000, v6
	s_nop 1
	v_addc_co_u32_e32 v21, vcc, 0, v7, vcc
	v_add_co_u32_e32 v22, vcc, 0x44000, v6
	s_nop 1
	v_addc_co_u32_e32 v23, vcc, 0, v7, vcc
	v_add_co_u32_e32 v24, vcc, 0x48000, v6
	s_nop 1
	v_addc_co_u32_e32 v25, vcc, 0, v7, vcc
	v_add_co_u32_e32 v26, vcc, 0x4c000, v6
	s_nop 1
	v_addc_co_u32_e32 v27, vcc, 0, v7, vcc
	v_add_co_u32_e32 v28, vcc, 0x50000, v6
	s_nop 1
	v_addc_co_u32_e32 v29, vcc, 0, v7, vcc
	v_add_co_u32_e32 v30, vcc, 0x54000, v6
	s_nop 1
	v_addc_co_u32_e32 v31, vcc, 0, v7, vcc
	v_add_co_u32_e32 v32, vcc, 0x58000, v6
	s_nop 1
	v_addc_co_u32_e32 v33, vcc, 0, v7, vcc
	v_add_co_u32_e32 v34, vcc, 0x5c000, v6
	s_nop 1
	v_addc_co_u32_e32 v35, vcc, 0, v7, vcc
	flat_load_dword v50, v[20:21]
	flat_load_dword v51, v[22:23]
	flat_load_dword v56, v[24:25]
	flat_load_dword v57, v[26:27]
	flat_load_dword v58, v[28:29]
	flat_load_dword v59, v[30:31]
	flat_load_dword v60, v[32:33]
	flat_load_dword v61, v[34:35]
	v_add_co_u32_e32 v20, vcc, 0x60000, v6
	s_nop 1
	v_addc_co_u32_e32 v21, vcc, 0, v7, vcc
	v_add_co_u32_e32 v22, vcc, 0x64000, v6
	s_nop 1
	v_addc_co_u32_e32 v23, vcc, 0, v7, vcc
	v_add_co_u32_e32 v24, vcc, 0x68000, v6
	s_nop 1
	v_addc_co_u32_e32 v25, vcc, 0, v7, vcc
	v_add_co_u32_e32 v26, vcc, 0x6c000, v6
	s_nop 1
	v_addc_co_u32_e32 v27, vcc, 0, v7, vcc
	v_add_co_u32_e32 v28, vcc, 0x70000, v6
	s_nop 1
	v_addc_co_u32_e32 v29, vcc, 0, v7, vcc
	v_add_co_u32_e32 v30, vcc, 0x74000, v6
	s_nop 1
	v_addc_co_u32_e32 v31, vcc, 0, v7, vcc
	v_add_co_u32_e32 v32, vcc, 0x78000, v6
	s_nop 1
	v_addc_co_u32_e32 v33, vcc, 0, v7, vcc
	v_add_co_u32_e32 v6, vcc, 0x7c000, v6
	s_nop 1
	v_addc_co_u32_e32 v7, vcc, 0, v7, vcc
	flat_load_dword v34, v[20:21]
	flat_load_dword v35, v[22:23]
	flat_load_dword v62, v[24:25]
	flat_load_dword v63, v[26:27]
	flat_load_dword v64, v[28:29]
	flat_load_dword v65, v[30:31]
	flat_load_dword v66, v[32:33]
	flat_load_dword v67, v[6:7]
	v_add_u32_e32 v6, 0x400, v13
	s_waitcnt vmcnt(0) lgkmcnt(0)
; __device__ __forceinline__ unsigned cvt_pk_bf16(float lo, float hi) { unsigned r; asm volatile("v_cvt_pk_bf16_f32 %0, %1, %2" : "=v"(r) : "v"(lo), "v"(hi)); return r; }
; __device__ __forceinline__ void transpose_item(const float* __restrict__ W, int K, int N, int nblk, bf16_t* __restrict__ WT, int mode, float* scr, int item, int lane) {
;     ...
; #pragma unroll
;     for (int i = 0; i < 32; ++i) { const int kk = 2 * i + (lane >> 5); scr[kk * 33 + (lane & 31)] = wv[i]; }
;     asm volatile("s_waitcnt lgkmcnt(0)" ::: "memory");
;     const int c = lane & 7;
; #pragma unroll
;     for (int j = 0; j < 4; ++j) { const int nn = (lane >> 3) + 8 * j; const float* s = scr + (8 * c) * 33 + nn;
;         u32x4 o; o.x = cvt_pk_bf16(s[0 * 33], s[1 * 33]); o.y = cvt_pk_bf16(s[2 * 33], s[3 * 33]); o.z = cvt_pk_bf16(s[4 * 33], s[5 * 33]); o.w = cvt_pk_bf16(s[6 * 33], s[7 * 33]);
;         *(u32x4*)(WT + (size_t)(n0 + nn) * K + k0 + 8 * c) = o; }
;     asm volatile("s_waitcnt lgkmcnt(0)" ::: "memory");
	ds_write2_b32 v13, v8, v19 offset1:66
	ds_write2_b32 v13, v36, v37 offset0:132 offset1:198
	ds_write2_b32 v6, v38, v39 offset0:8 offset1:74
	ds_write2_b32 v6, v40, v41 offset0:140 offset1:206
	v_add_u32_e32 v6, 0x800, v13
	ds_write2_b32 v6, v42, v43 offset0:16 offset1:82
	ds_write2_b32 v6, v44, v45 offset0:148 offset1:214
	v_add_u32_e32 v6, 0xc00, v13
	ds_write2_b32 v6, v46, v47 offset0:24 offset1:90
	ds_write2_b32 v6, v48, v49 offset0:156 offset1:222
	v_add_u32_e32 v6, 0x1000, v13
	ds_write2_b32 v6, v50, v51 offset0:32 offset1:98
	ds_write2_b32 v6, v56, v57 offset0:164 offset1:230
	v_add_u32_e32 v6, 0x1400, v13
	ds_write2_b32 v6, v58, v59 offset0:40 offset1:106
	ds_write2_b32 v6, v60, v61 offset0:172 offset1:238
	v_add_u32_e32 v6, 0x1800, v13
	ds_write2_b32 v6, v34, v35 offset0:48 offset1:114
	ds_write2_b32 v6, v62, v63 offset0:180 offset1:246
	v_add_u32_e32 v6, 0x1c00, v13
	ds_write2_b32 v6, v64, v65 offset0:56 offset1:122
	ds_write2_b32 v6, v66, v67 offset0:188 offset1:254
	s_waitcnt lgkmcnt(0)
	ds_read2_b32 v[6:7], v15 offset1:33
	s_waitcnt lgkmcnt(0)
	v_cvt_pk_bf16_f32 v20, v6, v7
	ds_read2_b32 v[6:7], v15 offset0:66 offset1:99
	s_waitcnt lgkmcnt(0)
	v_cvt_pk_bf16_f32 v21, v6, v7
	ds_read2_b32 v[6:7], v15 offset0:132 offset1:165
	v_or_b32_e32 v8, s10, v14
	s_waitcnt lgkmcnt(0)
	v_cvt_pk_bf16_f32 v22, v6, v7
	ds_read2_b32 v[6:7], v15 offset0:198 offset1:231
	v_lshl_add_u64 v[24:25], v[2:3], 0, s[20:21]
	v_lshlrev_b32_e32 v8, 12, v8
	s_waitcnt lgkmcnt(0)
	v_cvt_pk_bf16_f32 v23, v6, v7
	ds_read2_b32 v[6:7], v15 offset0:8 offset1:41
	v_lshl_add_u64 v[26:27], v[24:25], 0, v[8:9]
	global_store_dwordx4 v[26:27], v[20:23], off
	v_or_b32_e32 v8, s10, v16
	v_lshlrev_b32_e32 v8, 12, v8
	s_waitcnt lgkmcnt(0)
	v_cvt_pk_bf16_f32 v20, v6, v7
	ds_read2_b32 v[6:7], v15 offset0:74 offset1:107
	s_waitcnt lgkmcnt(0)
	v_cvt_pk_bf16_f32 v21, v6, v7
	ds_read2_b32 v[6:7], v15 offset0:140 offset1:173
	s_waitcnt lgkmcnt(0)
	v_cvt_pk_bf16_f32 v22, v6, v7
	ds_read2_b32 v[6:7], v15 offset0:206 offset1:239
	s_waitcnt lgkmcnt(0)
	v_cvt_pk_bf16_f32 v23, v6, v7
	ds_read2_b32 v[6:7], v15 offset0:16 offset1:49
	v_lshl_add_u64 v[26:27], v[24:25], 0, v[8:9]
	global_store_dwordx4 v[26:27], v[20:23], off
	v_or_b32_e32 v8, s10, v17
	v_lshlrev_b32_e32 v8, 12, v8
	s_waitcnt lgkmcnt(0)
	v_cvt_pk_bf16_f32 v20, v6, v7
	ds_read2_b32 v[6:7], v15 offset0:82 offset1:115
	s_waitcnt lgkmcnt(0)
	v_cvt_pk_bf16_f32 v21, v6, v7
	ds_read2_b32 v[6:7], v15 offset0:148 offset1:181
	s_waitcnt lgkmcnt(0)
	v_cvt_pk_bf16_f32 v22, v6, v7
	ds_read2_b32 v[6:7], v15 offset0:214 offset1:247
	s_waitcnt lgkmcnt(0)
	v_cvt_pk_bf16_f32 v23, v6, v7
	ds_read2_b32 v[6:7], v15 offset0:24 offset1:57
	v_lshl_add_u64 v[26:27], v[24:25], 0, v[8:9]
	global_store_dwordx4 v[26:27], v[20:23], off
	s_waitcnt lgkmcnt(0)
	s_nop 0
	v_cvt_pk_bf16_f32 v20, v6, v7
	ds_read2_b32 v[6:7], v15 offset0:90 offset1:123
	s_waitcnt lgkmcnt(0)
	v_cvt_pk_bf16_f32 v21, v6, v7
	ds_read2_b32 v[6:7], v15 offset0:156 offset1:189
	s_waitcnt lgkmcnt(0)
	v_cvt_pk_bf16_f32 v22, v6, v7
	ds_read2_b32 v[6:7], v15 offset0:222 offset1:255
	s_waitcnt lgkmcnt(0)
	v_cvt_pk_bf16_f32 v23, v6, v7
	v_or_b32_e32 v6, s10, v18
	v_lshlrev_b32_e32 v8, 12, v6
	v_lshl_add_u64 v[6:7], v[24:25], 0, v[8:9]
	global_store_dwordx4 v[6:7], v[20:23], off
	s_waitcnt lgkmcnt(0)
	s_cbranch_execnz .LBB0_32

; __device__ __forceinline__ void zero_pad_rows(const Params& P) {
;     u32x4* p = (u32x4*)((bf16_t*)(P.ws + WS_PROJ) + (size_t)LTOK * PW); const int n = (MP - LTOK) * PW / 8;
;     for (int i = blockIdx.x * 512 + threadIdx.x; i < n; i += gridDim.x * 512) p[i] = (u32x4){0u, 0u, 0u, 0u};
.LBB0_112:
	v_ashrrev_i32_e32 v3, 31, v2
	v_lshl_add_u64 v[4:5], v[2:3], 4, s[12:13]
	v_add_u32_e32 v2, s20, v2
	v_cmp_lt_i32_e32 vcc, s54, v2
	s_or_b64 s[14:15], vcc, s[14:15]
	global_store_dwordx4 v[4:5], v[52:55], off
	s_andn2_b64 exec, exec, s[14:15]
	s_cbranch_execnz .LBB0_112

; __device__ __forceinline__ void zero_pad_rows(const Params& P) {
;     ...
;     u32x4* g = (u32x4*)((float*)(P.ws + WS_GATES) + (size_t)LTOK * 16); const int m = (MP - LTOK) * 16 / 4;
;     for (int i = blockIdx.x * 512 + threadIdx.x; i < m; i += gridDim.x * 512) g[i] = (u32x4){0u, 0u, 0u, 0u};
.LBB0_115:
	v_ashrrev_i32_e32 v3, 31, v2
	v_lshl_add_u64 v[4:5], v[2:3], 4, s[12:13]
	v_add_u32_e32 v2, s20, v2
	v_cmp_lt_i32_e32 vcc, s55, v2
	s_or_b64 s[14:15], vcc, s[14:15]
	global_store_dwordx4 v[4:5], v[52:55], off
	s_andn2_b64 exec, exec, s[14:15]
	s_cbranch_execnz .LBB0_115

; template <int KSPLIT, class Epi>
; __device__ __forceinline__ void skinny_gemm(const bf16_t* __restrict__ A, int lda, const bf16_t* __restrict__ Wt, int K, int ntiles, char* lds, const Epi& E) {
;     int tidl_ = threadIdx.x; asm volatile("" : "+v"(tidl_));
;     const int tid = tidl_, wid = __builtin_amdgcn_readfirstlane(tid >> 6), lane = tid & 63, i = lane & 15, kq = lane >> 4;
;     const int total = ntiles * KSPLIT, klen = K / KSPLIT;
;     for (int base = 0; base < total; base += (int)gridDim.x * 8) {
;         const int slot = base + (int)blockIdx.x * 8 + wid, tile = slot / KSPLIT, ks = slot % KSPLIT;
;         const bool act = slot < total;
;         f32x4 acc = {0.f, 0.f, 0.f, 0.f};
;         if (act) {
;             const bf16_t* ap = A + (size_t)i * lda + ks * klen + 8 * kq;
;             const bf16_t* wp = Wt + (size_t)(tile * 16 + i) * K + ks * klen + 8 * kq;
;             for (int k = 0; k < klen; k += 256) {
;                 bf16x8 a[8], w[8];
; #pragma unroll
;                 for (int j = 0; j < 8; ++j) { a[j] = *(const bf16x8*)(ap + k + 32 * j); w[j] = *(const bf16x8*)(wp + k + 32 * j); }
; #pragma unroll
;                 for (int j = 0; j < 8; ++j) acc = __builtin_amdgcn_mfma_f32_16x16x32_bf16(w[j], a[j], acc, 0, 0, 0);
;             }
;         }
.LBB0_179:
	s_add_i32 s20, s10, s11
	s_lshr_b32 s6, s20, 31
	s_add_i32 s6, s20, s6
	s_ashr_i32 s18, s6, 1
	s_and_b32 s6, s6, -2
	s_sub_i32 s19, s20, s6
	v_mov_b32_e32 v4, v2
	v_mov_b32_e32 v5, v2
	v_mov_b32_e32 v3, v2
	s_cmpk_lt_i32 s20, 0x800
	v_mov_b64_e32 v[6:7], v[4:5]
	s_cselect_b64 s[6:7], -1, 0
	s_cmpk_gt_i32 s20, 0x7ff
	v_mov_b64_e32 v[4:5], v[2:3]
	s_cbranch_scc1 .LBB0_181
	v_lshl_or_b32 v4, s18, 4, v1
	s_lshl_b32 s20, s19, 10
	v_ashrrev_i32_e32 v5, 31, v4
	s_ashr_i32 s21, s20, 31
	v_lshlrev_b64 v[4:5], 12, v[4:5]
	s_lshl_b64 s[20:21], s[20:21], 1
	v_lshl_add_u64 v[4:5], s[14:15], 0, v[4:5]
	v_lshl_add_u64 v[4:5], v[4:5], 0, s[20:21]
	v_mov_b32_e32 v13, v2
	v_lshl_add_u64 v[80:81], v[4:5], 0, v[12:13]
	global_load_dwordx4 v[4:7], v[80:81], off
	v_lshl_add_u64 v[82:83], v[8:9], 0, s[20:21]
	global_load_dwordx4 v[16:19], v[80:81], off offset:64
	global_load_dwordx4 v[20:23], v[82:83], off
	global_load_dwordx4 v[24:27], v[82:83], off offset:64
	global_load_dwordx4 v[28:31], v[80:81], off offset:128
	global_load_dwordx4 v[32:35], v[80:81], off offset:192
	global_load_dwordx4 v[36:39], v[82:83], off offset:128
	global_load_dwordx4 v[40:43], v[82:83], off offset:192
	global_load_dwordx4 v[44:47], v[80:81], off offset:256
	global_load_dwordx4 v[48:51], v[82:83], off offset:256
	global_load_dwordx4 v[52:55], v[80:81], off offset:320
	global_load_dwordx4 v[56:59], v[82:83], off offset:320
	global_load_dwordx4 v[60:63], v[80:81], off offset:384
	global_load_dwordx4 v[64:67], v[80:81], off offset:448
	global_load_dwordx4 v[68:71], v[82:83], off offset:384
	global_load_dwordx4 v[72:75], v[82:83], off offset:448
	s_waitcnt vmcnt(0) lgkmcnt(0)
	v_mfma_f32_16x16x32_bf16 v[4:7], v[4:7], v[20:23], 0
	global_load_dwordx4 v[20:23], v[80:81], off offset:512
	global_load_dwordx4 v[76:79], v[80:81], off offset:576
	v_mfma_f32_16x16x32_bf16 v[4:7], v[16:19], v[24:27], v[4:7]
	global_load_dwordx4 v[16:19], v[82:83], off offset:512
	global_load_dwordx4 v[24:27], v[82:83], off offset:576
	v_mfma_f32_16x16x32_bf16 v[4:7], v[28:31], v[36:39], v[4:7]
	global_load_dwordx4 v[28:31], v[80:81], off offset:640
	global_load_dwordx4 v[36:39], v[82:83], off offset:640
	v_mfma_f32_16x16x32_bf16 v[4:7], v[32:35], v[40:43], v[4:7]
	global_load_dwordx4 v[32:35], v[80:81], off offset:704
	global_load_dwordx4 v[40:43], v[82:83], off offset:704
	v_mfma_f32_16x16x32_bf16 v[4:7], v[44:47], v[48:51], v[4:7]
	global_load_dwordx4 v[44:47], v[80:81], off offset:768
	global_load_dwordx4 v[48:51], v[80:81], off offset:832
	v_mfma_f32_16x16x32_bf16 v[4:7], v[52:55], v[56:59], v[4:7]
	global_load_dwordx4 v[52:55], v[82:83], off offset:768
	global_load_dwordx4 v[56:59], v[82:83], off offset:832
	v_mfma_f32_16x16x32_bf16 v[4:7], v[60:63], v[68:71], v[4:7]
	v_mfma_f32_16x16x32_bf16 v[4:7], v[64:67], v[72:75], v[4:7]
	global_load_dwordx4 v[60:63], v[80:81], off offset:896
	global_load_dwordx4 v[64:67], v[80:81], off offset:960
	s_waitcnt vmcnt(0) lgkmcnt(0)
	v_mfma_f32_16x16x32_bf16 v[4:7], v[20:23], v[16:19], v[4:7]
	global_load_dwordx4 v[16:19], v[82:83], off offset:896
	global_load_dwordx4 v[20:23], v[82:83], off offset:960
	v_mfma_f32_16x16x32_bf16 v[4:7], v[76:79], v[24:27], v[4:7]
	global_load_dwordx4 v[24:27], v[80:81], off offset:1024
	global_load_dwordx4 v[68:71], v[82:83], off offset:1024
	v_mfma_f32_16x16x32_bf16 v[4:7], v[28:31], v[36:39], v[4:7]
	global_load_dwordx4 v[28:31], v[80:81], off offset:1088
	v_mfma_f32_16x16x32_bf16 v[4:7], v[32:35], v[40:43], v[4:7]
	global_load_dwordx4 v[32:35], v[82:83], off offset:1088
	global_load_dwordx4 v[36:39], v[80:81], off offset:1152
	global_load_dwordx4 v[40:43], v[80:81], off offset:1216
	v_mfma_f32_16x16x32_bf16 v[4:7], v[44:47], v[52:55], v[4:7]
	v_mfma_f32_16x16x32_bf16 v[4:7], v[48:51], v[56:59], v[4:7]
	global_load_dwordx4 v[44:47], v[82:83], off offset:1152
	global_load_dwordx4 v[48:51], v[82:83], off offset:1216
	s_waitcnt vmcnt(0) lgkmcnt(0)
	v_mfma_f32_16x16x32_bf16 v[4:7], v[60:63], v[16:19], v[4:7]
	global_load_dwordx4 v[16:19], v[80:81], off offset:1280
	global_load_dwordx4 v[52:55], v[80:81], off offset:1344
	v_mfma_f32_16x16x32_bf16 v[4:7], v[64:67], v[20:23], v[4:7]
	global_load_dwordx4 v[20:23], v[82:83], off offset:1280
	global_load_dwordx4 v[56:59], v[82:83], off offset:1344
	v_mfma_f32_16x16x32_bf16 v[4:7], v[24:27], v[68:71], v[4:7]
	global_load_dwordx4 v[24:27], v[80:81], off offset:1408
	v_mfma_f32_16x16x32_bf16 v[4:7], v[28:31], v[32:35], v[4:7]
	global_load_dwordx4 v[28:31], v[82:83], off offset:1408
	v_mfma_f32_16x16x32_bf16 v[4:7], v[36:39], v[44:47], v[4:7]
	global_load_dwordx4 v[32:35], v[80:81], off offset:1472
	global_load_dwordx4 v[36:39], v[82:83], off offset:1472
	v_mfma_f32_16x16x32_bf16 v[4:7], v[40:43], v[48:51], v[4:7]
	global_load_dwordx4 v[40:43], v[80:81], off offset:1536
	global_load_dwordx4 v[44:47], v[80:81], off offset:1600
	s_waitcnt vmcnt(0) lgkmcnt(0)
	v_mfma_f32_16x16x32_bf16 v[4:7], v[16:19], v[20:23], v[4:7]
	global_load_dwordx4 v[16:19], v[82:83], off offset:1536
	global_load_dwordx4 v[20:23], v[82:83], off offset:1600
	global_load_dwordx4 v[48:51], v[80:81], off offset:1664
	v_mfma_f32_16x16x32_bf16 v[4:7], v[52:55], v[56:59], v[4:7]
	v_mfma_f32_16x16x32_bf16 v[4:7], v[24:27], v[28:31], v[4:7]
	global_load_dwordx4 v[24:27], v[82:83], off offset:1664
	v_mfma_f32_16x16x32_bf16 v[4:7], v[32:35], v[36:39], v[4:7]
	global_load_dwordx4 v[28:31], v[80:81], off offset:1728
	global_load_dwordx4 v[32:35], v[82:83], off offset:1728
	s_waitcnt vmcnt(0) lgkmcnt(0)
	v_mfma_f32_16x16x32_bf16 v[4:7], v[40:43], v[16:19], v[4:7]
	global_load_dwordx4 v[16:19], v[80:81], off offset:1792
	global_load_dwordx4 v[36:39], v[82:83], off offset:1792
	v_mfma_f32_16x16x32_bf16 v[4:7], v[44:47], v[20:23], v[4:7]
	global_load_dwordx4 v[20:23], v[80:81], off offset:1856
	v_mfma_f32_16x16x32_bf16 v[4:7], v[48:51], v[24:27], v[4:7]
	global_load_dwordx4 v[24:27], v[82:83], off offset:1856
	v_mfma_f32_16x16x32_bf16 v[4:7], v[28:31], v[32:35], v[4:7]
	global_load_dwordx4 v[28:31], v[80:81], off offset:1920
	global_load_dwordx4 v[32:35], v[82:83], off offset:1920
	s_waitcnt vmcnt(0) lgkmcnt(0)
	v_mfma_f32_16x16x32_bf16 v[4:7], v[16:19], v[36:39], v[4:7]
	global_load_dwordx4 v[16:19], v[80:81], off offset:1984
	v_mfma_f32_16x16x32_bf16 v[4:7], v[20:23], v[24:27], v[4:7]
	global_load_dwordx4 v[20:23], v[82:83], off offset:1984
	v_mfma_f32_16x16x32_bf16 v[4:7], v[28:31], v[32:35], v[4:7]
	s_waitcnt vmcnt(0) lgkmcnt(0)
	v_mfma_f32_16x16x32_bf16 v[4:7], v[16:19], v[20:23], v[4:7]

; template <int KSPLIT, class Epi>
; __device__ __forceinline__ void skinny_gemm(const bf16_t* __restrict__ A, int lda, const bf16_t* __restrict__ Wt, int K, int ntiles, char* lds, const Epi& E) {
;     int tidl_ = threadIdx.x; asm volatile("" : "+v"(tidl_));
;     const int tid = tidl_, wid = __builtin_amdgcn_readfirstlane(tid >> 6), lane = tid & 63, i = lane & 15, kq = lane >> 4;
;     const int total = ntiles * KSPLIT, klen = K / KSPLIT;
;     for (int base = 0; base < total; base += (int)gridDim.x * 8) {
;         const int slot = base + (int)blockIdx.x * 8 + wid, tile = slot / KSPLIT, ks = slot % KSPLIT;
;         const bool act = slot < total;
;         f32x4 acc = {0.f, 0.f, 0.f, 0.f};
;         if (act) {
;             const bf16_t* ap = A + (size_t)i * lda + ks * klen + 8 * kq;
;             const bf16_t* wp = Wt + (size_t)(tile * 16 + i) * K + ks * klen + 8 * kq;
;             for (int k = 0; k < klen; k += 256) {
;                 bf16x8 a[8], w[8];
; #pragma unroll
;                 for (int j = 0; j < 8; ++j) { a[j] = *(const bf16x8*)(ap + k + 32 * j); w[j] = *(const bf16x8*)(wp + k + 32 * j); }
; #pragma unroll
;                 for (int j = 0; j < 8; ++j) acc = __builtin_amdgcn_mfma_f32_16x16x32_bf16(w[j], a[j], acc, 0, 0, 0);
;             }
;         }
; template <int L, int K>
; __device__ __forceinline__ void phase_body(char* lds, int rep_) {
;     ...
;         skinny_gemm<8>(WinT + (size_t)PW * DM, DM, HB + (size_t)SEQ * DM, DM, 1, lds, SkGates{(float*)(ws + WS_GATES) + (size_t)SEQ * 16});
.LBB0_189:
	s_add_i32 s20, s8, s9
	s_ashr_i32 s6, s20, 31
	s_lshr_b32 s6, s6, 29
	s_add_i32 s6, s20, s6
	s_ashr_i32 s18, s6, 3
	s_and_b32 s6, s6, -8
	s_sub_i32 s19, s20, s6
	v_mov_b32_e32 v4, v2
	v_mov_b32_e32 v5, v2
	v_mov_b32_e32 v3, v2
	s_cmp_lt_i32 s20, 8
	v_mov_b64_e32 v[6:7], v[4:5]
	s_cselect_b64 s[6:7], -1, 0
	s_cmp_gt_i32 s20, 7
	v_mov_b64_e32 v[4:5], v[2:3]
	s_cbranch_scc1 .LBB0_191
	v_lshl_or_b32 v4, s18, 4, v1
	s_lshl_b32 s20, s19, 8
	v_ashrrev_i32_e32 v5, 31, v4
	s_ashr_i32 s21, s20, 31
	v_lshlrev_b64 v[4:5], 12, v[4:5]
	s_lshl_b64 s[20:21], s[20:21], 1
	v_lshl_add_u64 v[4:5], s[10:11], 0, v[4:5]
	v_lshl_add_u64 v[4:5], v[4:5], 0, s[20:21]
	v_mov_b32_e32 v13, v2
	v_lshl_add_u64 v[50:51], v[4:5], 0, v[12:13]
	global_load_dwordx4 v[4:7], v[50:51], off
	v_lshl_add_u64 v[52:53], v[8:9], 0, s[20:21]
	global_load_dwordx4 v[18:21], v[50:51], off offset:64
	global_load_dwordx4 v[22:25], v[52:53], off
	global_load_dwordx4 v[26:29], v[52:53], off offset:64
	global_load_dwordx4 v[30:33], v[50:51], off offset:128
	global_load_dwordx4 v[34:37], v[52:53], off offset:128
	global_load_dwordx4 v[38:41], v[50:51], off offset:192
	global_load_dwordx4 v[42:45], v[52:53], off offset:192
	s_waitcnt vmcnt(0) lgkmcnt(0)
	v_mfma_f32_16x16x32_bf16 v[4:7], v[4:7], v[22:25], 0
	global_load_dwordx4 v[22:25], v[50:51], off offset:256
	global_load_dwordx4 v[46:49], v[52:53], off offset:256
	v_mfma_f32_16x16x32_bf16 v[4:7], v[18:21], v[26:29], v[4:7]
	global_load_dwordx4 v[18:21], v[50:51], off offset:320
	global_load_dwordx4 v[26:29], v[52:53], off offset:320
	v_mfma_f32_16x16x32_bf16 v[4:7], v[30:33], v[34:37], v[4:7]
	global_load_dwordx4 v[30:33], v[50:51], off offset:384
	global_load_dwordx4 v[34:37], v[52:53], off offset:384
	v_mfma_f32_16x16x32_bf16 v[4:7], v[38:41], v[42:45], v[4:7]
	s_waitcnt vmcnt(0) lgkmcnt(0)
	v_mfma_f32_16x16x32_bf16 v[4:7], v[22:25], v[46:49], v[4:7]
	global_load_dwordx4 v[22:25], v[50:51], off offset:448
	v_mfma_f32_16x16x32_bf16 v[4:7], v[18:21], v[26:29], v[4:7]
	global_load_dwordx4 v[18:21], v[52:53], off offset:448
	v_mfma_f32_16x16x32_bf16 v[4:7], v[30:33], v[34:37], v[4:7]
	s_waitcnt vmcnt(0) lgkmcnt(0)
	v_mfma_f32_16x16x32_bf16 v[4:7], v[22:25], v[18:21], v[4:7]

; template <int KSPLIT, class Epi>
; __device__ __forceinline__ void skinny_gemm(const bf16_t* __restrict__ A, int lda, const bf16_t* __restrict__ Wt, int K, int ntiles, char* lds, const Epi& E) {
;     int tidl_ = threadIdx.x; asm volatile("" : "+v"(tidl_));
;     const int tid = tidl_, wid = __builtin_amdgcn_readfirstlane(tid >> 6), lane = tid & 63, i = lane & 15, kq = lane >> 4;
;     const int total = ntiles * KSPLIT, klen = K / KSPLIT;
;     for (int base = 0; base < total; base += (int)gridDim.x * 8) {
;         const int slot = base + (int)blockIdx.x * 8 + wid, tile = slot / KSPLIT, ks = slot % KSPLIT;
;         const bool act = slot < total;
;         f32x4 acc = {0.f, 0.f, 0.f, 0.f};
;         if (act) {
;             const bf16_t* ap = A + (size_t)i * lda + ks * klen + 8 * kq;
;             const bf16_t* wp = Wt + (size_t)(tile * 16 + i) * K + ks * klen + 8 * kq;
;             for (int k = 0; k < klen; k += 256) {
;                 bf16x8 a[8], w[8];
; #pragma unroll
;                 for (int j = 0; j < 8; ++j) { a[j] = *(const bf16x8*)(ap + k + 32 * j); w[j] = *(const bf16x8*)(wp + k + 32 * j); }
; #pragma unroll
;                 for (int j = 0; j < 8; ++j) acc = __builtin_amdgcn_mfma_f32_16x16x32_bf16(w[j], a[j], acc, 0, 0, 0);
;             }
;         }
; template <int L, int K>
; __device__ __forceinline__ void phase_body(char* lds, int rep_) {
;     ...
;         skinny_gemm<4>(HB, DM, WinT, DM, PW / 16, lds, SkProj{(bf16_t*)(ws + WS_PROJ)});
.LBB0_199:
	s_add_i32 s19, s14, s15
	s_ashr_i32 s6, s19, 31
	s_lshr_b32 s6, s6, 30
	s_add_i32 s6, s19, s6
	s_ashr_i32 s17, s6, 2
	s_and_b32 s6, s6, -4
	s_sub_i32 s18, s19, s6
	v_mov_b32_e32 v4, v2
	v_mov_b32_e32 v5, v2
	v_mov_b32_e32 v3, v2
	s_cmpk_lt_i32 s19, 0x600
	v_mov_b64_e32 v[6:7], v[4:5]
	s_cselect_b64 s[6:7], -1, 0
	s_cmpk_gt_i32 s19, 0x5ff
	v_mov_b64_e32 v[4:5], v[2:3]
	s_cbranch_scc1 .LBB0_201
	v_lshl_or_b32 v4, s17, 4, v1
	s_lshl_b32 s20, s18, 9
	v_ashrrev_i32_e32 v5, 31, v4
	s_ashr_i32 s21, s20, 31
	v_lshlrev_b64 v[4:5], 12, v[4:5]
	s_lshl_b64 s[20:21], s[20:21], 1
	v_lshl_add_u64 v[4:5], s[8:9], 0, v[4:5]
	v_lshl_add_u64 v[4:5], v[4:5], 0, s[20:21]
	v_mov_b32_e32 v13, v2
	v_lshl_add_u64 v[60:61], v[4:5], 0, v[12:13]
	global_load_dwordx4 v[4:7], v[60:61], off
	v_lshl_add_u64 v[62:63], v[8:9], 0, s[20:21]
	global_load_dwordx4 v[16:19], v[60:61], off offset:64
	global_load_dwordx4 v[20:23], v[62:63], off
	global_load_dwordx4 v[24:27], v[62:63], off offset:64
	global_load_dwordx4 v[28:31], v[60:61], off offset:128
	global_load_dwordx4 v[32:35], v[60:61], off offset:192
	global_load_dwordx4 v[36:39], v[62:63], off offset:128
	global_load_dwordx4 v[40:43], v[62:63], off offset:192
	global_load_dwordx4 v[44:47], v[60:61], off offset:256
	global_load_dwordx4 v[48:51], v[60:61], off offset:320
	global_load_dwordx4 v[52:55], v[62:63], off offset:256
	global_load_dwordx4 v[56:59], v[62:63], off offset:320
	s_waitcnt vmcnt(0) lgkmcnt(0)
	v_mfma_f32_16x16x32_bf16 v[4:7], v[4:7], v[20:23], 0
	global_load_dwordx4 v[20:23], v[60:61], off offset:384
	v_mfma_f32_16x16x32_bf16 v[4:7], v[16:19], v[24:27], v[4:7]
	global_load_dwordx4 v[16:19], v[62:63], off offset:384
	v_mfma_f32_16x16x32_bf16 v[4:7], v[28:31], v[36:39], v[4:7]
	global_load_dwordx4 v[24:27], v[60:61], off offset:448
	global_load_dwordx4 v[28:31], v[62:63], off offset:448
	v_mfma_f32_16x16x32_bf16 v[4:7], v[32:35], v[40:43], v[4:7]
	global_load_dwordx4 v[32:35], v[60:61], off offset:512
	global_load_dwordx4 v[36:39], v[60:61], off offset:576
	v_mfma_f32_16x16x32_bf16 v[4:7], v[44:47], v[52:55], v[4:7]
	global_load_dwordx4 v[40:43], v[62:63], off offset:512
	global_load_dwordx4 v[44:47], v[62:63], off offset:576
	v_mfma_f32_16x16x32_bf16 v[4:7], v[48:51], v[56:59], v[4:7]
	global_load_dwordx4 v[48:51], v[60:61], off offset:640
	s_waitcnt vmcnt(0) lgkmcnt(0)
	v_mfma_f32_16x16x32_bf16 v[4:7], v[20:23], v[16:19], v[4:7]
	global_load_dwordx4 v[16:19], v[62:63], off offset:640
	v_mfma_f32_16x16x32_bf16 v[4:7], v[24:27], v[28:31], v[4:7]
	global_load_dwordx4 v[20:23], v[60:61], off offset:704
	global_load_dwordx4 v[24:27], v[62:63], off offset:704
	v_mfma_f32_16x16x32_bf16 v[4:7], v[32:35], v[40:43], v[4:7]
	global_load_dwordx4 v[28:31], v[60:61], off offset:768
	global_load_dwordx4 v[32:35], v[62:63], off offset:768
	v_mfma_f32_16x16x32_bf16 v[4:7], v[36:39], v[44:47], v[4:7]
	global_load_dwordx4 v[36:39], v[60:61], off offset:832
	s_waitcnt vmcnt(0) lgkmcnt(0)
	v_mfma_f32_16x16x32_bf16 v[4:7], v[48:51], v[16:19], v[4:7]
	global_load_dwordx4 v[16:19], v[62:63], off offset:832
	v_mfma_f32_16x16x32_bf16 v[4:7], v[20:23], v[24:27], v[4:7]
	global_load_dwordx4 v[20:23], v[60:61], off offset:896
	global_load_dwordx4 v[24:27], v[62:63], off offset:896
	v_mfma_f32_16x16x32_bf16 v[4:7], v[28:31], v[32:35], v[4:7]
	global_load_dwordx4 v[28:31], v[60:61], off offset:960
	s_waitcnt vmcnt(0) lgkmcnt(0)
	v_mfma_f32_16x16x32_bf16 v[4:7], v[36:39], v[16:19], v[4:7]
	global_load_dwordx4 v[16:19], v[62:63], off offset:960
	v_mfma_f32_16x16x32_bf16 v[4:7], v[20:23], v[24:27], v[4:7]
	s_waitcnt vmcnt(0) lgkmcnt(0)
	v_mfma_f32_16x16x32_bf16 v[4:7], v[28:31], v[16:19], v[4:7]

; template <int KSPLIT, class Epi>
; __device__ __forceinline__ void skinny_gemm(const bf16_t* __restrict__ A, int lda, const bf16_t* __restrict__ Wt, int K, int ntiles, char* lds, const Epi& E) {
;     ...
;             __syncthreads();
;         }
;         if (act && ks == 0) E(tile, i, kq, acc);
.LBB0_205:
	s_and_b64 vcc, exec, s[6:7]
	s_barrier
	s_cbranch_vccnz .LBB0_198
	s_lshl_b32 s6, s17, 4
	s_ashr_i32 s7, s6, 31
	v_cvt_pk_bf16_f32 v4, v4, v5
	v_cvt_pk_bf16_f32 v5, v6, v7
	v_lshl_add_u64 v[6:7], s[6:7], 1, v[10:11]
	global_store_dwordx2 v[6:7], v[4:5], off
	s_branch .LBB0_198

; __device__ __forceinline__ float bflo(unsigned w) { return __uint_as_float(w << 16); }
; __device__ __forceinline__ float bfhi(unsigned w) { return __uint_as_float(w & 0xffff0000u); }
; __device__ __forceinline__ void fox_norms(const Params& P, int l, int gw, int NGW, int lane) {
;     ...
;     for (int base = gw * 8; base < LTOK; base += NGW * 8) {
;         float dmin = 0.f;
;         for (int i = 0; i < 8; ++i) { const int r = base + i; if (r >= LTOK) break;
;             const u32x4* q = (const u32x4*)(PROJ + (size_t)r * PW + C_FQ + lane * 16); const u32x4* k = (const u32x4*)(PROJ + (size_t)r * PW + C_FK + lane * 16);
;             float sq = 0.f, sk = 0.f, qk = 0.f;
; #pragma unroll
;             for (int j = 0; j < 2; ++j) { const u32x4 a = q[j], b = k[j];
;                 sq += bflo(a.x) * bflo(a.x) + bfhi(a.x) * bfhi(a.x) + bflo(a.y) * bflo(a.y) + bfhi(a.y) * bfhi(a.y) + bflo(a.z) * bflo(a.z) + bfhi(a.z) * bfhi(a.z) + bflo(a.w) * bflo(a.w) + bfhi(a.w) * bfhi(a.w);
;                 sk += bflo(b.x) * bflo(b.x) + bfhi(b.x) * bfhi(b.x) + bflo(b.y) * bflo(b.y) + bfhi(b.y) * bfhi(b.y) + bflo(b.z) * bflo(b.z) + bfhi(b.z) * bfhi(b.z) + bflo(b.w) * bflo(b.w) + bfhi(b.w) * bfhi(b.w);
;                 qk += bflo(a.x) * bflo(b.x) + bfhi(a.x) * bfhi(b.x) + bflo(a.y) * bflo(b.y) + bfhi(a.y) * bfhi(b.y) + bflo(a.z) * bflo(b.z) + bfhi(a.z) * bfhi(b.z) + bflo(a.w) * bflo(b.w) + bfhi(a.w) * bfhi(b.w); }
;             sq += __shfl_xor(sq, 1); sq += __shfl_xor(sq, 2); sq += __shfl_xor(sq, 4); sk += __shfl_xor(sk, 1); sk += __shfl_xor(sk, 2); sk += __shfl_xor(sk, 4);
;             qk += __shfl_xor(qk, 1); qk += __shfl_xor(qk, 2); qk += __shfl_xor(qk, 4);
;             mq = fmaxf(mq, sq); mk = fmaxf(mk, sk); dmin = fminf(dmin, qk * fox::SCALE - 1e-3f * fabsf(qk * fox::SCALE)); }
.LBB0_286:
	s_add_i32 s27, s23, s26
	s_cmpk_lt_i32 s27, 0x4010
	s_cselect_b64 s[16:17], -1, 0
	s_cmpk_gt_i32 s27, 0x400f
	s_cbranch_scc1 .LBB0_288
	global_load_dwordx4 v[18:21], v[10:11], off offset:16
	global_load_dwordx4 v[22:25], v[10:11], off
	global_load_dwordx4 v[26:29], v[10:11], off offset:2064
	global_load_dwordx4 v[30:33], v[10:11], off offset:2048
	v_cmp_lt_i32_e32 vcc, v12, v13
	v_max_f32_e32 v5, v5, v5
	v_max_f32_e32 v4, v4, v4
	v_cndmask_b32_e32 v17, v3, v12, vcc
	v_cmp_lt_i32_e32 vcc, v14, v13
	v_lshlrev_b32_e32 v17, 2, v17
	v_max_f32_e32 v16, v16, v16
	v_cndmask_b32_e32 v34, v3, v14, vcc
	v_lshlrev_b32_e32 v53, 2, v34
	v_cmp_lt_i32_e32 vcc, v15, v13
	s_waitcnt vmcnt(0) lgkmcnt(0)
	v_and_b32_e32 v37, 0xffff0000, v18
	v_and_b32_e32 v36, 0xffff0000, v22
	v_and_b32_e32 v45, 0xffff0000, v26
	v_and_b32_e32 v44, 0xffff0000, v30
	v_lshlrev_b32_e32 v35, 16, v18
	v_lshlrev_b32_e32 v34, 16, v22
	v_lshlrev_b32_e32 v38, 16, v23
	v_and_b32_e32 v18, 0xffff0000, v23
	v_lshlrev_b32_e32 v23, 16, v20
	v_lshlrev_b32_e32 v22, 16, v24
	v_and_b32_e32 v41, 0xffff0000, v20
	v_and_b32_e32 v40, 0xffff0000, v24
	v_lshlrev_b32_e32 v42, 16, v25
	v_and_b32_e32 v20, 0xffff0000, v25
	v_lshlrev_b32_e32 v25, 16, v26
	v_lshlrev_b32_e32 v24, 16, v30
	v_lshlrev_b32_e32 v46, 16, v31
	v_and_b32_e32 v26, 0xffff0000, v31
	v_lshlrev_b32_e32 v31, 16, v28
	v_lshlrev_b32_e32 v30, 16, v32
	v_and_b32_e32 v49, 0xffff0000, v28
	v_and_b32_e32 v48, 0xffff0000, v32
	v_lshlrev_b32_e32 v50, 16, v33
	v_and_b32_e32 v28, 0xffff0000, v33
	v_pk_mul_f32 v[32:33], v[36:37], v[44:45]
	v_lshlrev_b32_e32 v39, 16, v19
	v_lshlrev_b32_e32 v47, 16, v27
	v_pk_mul_f32 v[36:37], v[36:37], v[36:37]
	v_pk_mul_f32 v[44:45], v[44:45], v[44:45]
	v_pk_fma_f32 v[32:33], v[34:35], v[24:25], v[32:33]
	v_and_b32_e32 v19, 0xffff0000, v19
	v_and_b32_e32 v27, 0xffff0000, v27
	v_pk_fma_f32 v[34:35], v[34:35], v[34:35], v[36:37]
	v_pk_fma_f32 v[24:25], v[24:25], v[24:25], v[44:45]
	v_pk_fma_f32 v[32:33], v[38:39], v[46:47], v[32:33]
	v_pk_fma_f32 v[34:35], v[38:39], v[38:39], v[34:35]
	v_pk_fma_f32 v[24:25], v[46:47], v[46:47], v[24:25]
	v_pk_fma_f32 v[32:33], v[18:19], v[26:27], v[32:33]
	v_pk_fma_f32 v[18:19], v[18:19], v[18:19], v[34:35]
	v_pk_fma_f32 v[24:25], v[26:27], v[26:27], v[24:25]
	v_pk_fma_f32 v[26:27], v[22:23], v[30:31], v[32:33]
	v_lshlrev_b32_e32 v43, 16, v21
	v_lshlrev_b32_e32 v51, 16, v29
	v_pk_fma_f32 v[18:19], v[22:23], v[22:23], v[18:19]
	v_pk_fma_f32 v[22:23], v[30:31], v[30:31], v[24:25]
	v_pk_fma_f32 v[24:25], v[40:41], v[48:49], v[26:27]
	v_and_b32_e32 v21, 0xffff0000, v21
	v_and_b32_e32 v29, 0xffff0000, v29
	v_pk_fma_f32 v[18:19], v[40:41], v[40:41], v[18:19]
	v_pk_fma_f32 v[22:23], v[48:49], v[48:49], v[22:23]
	v_pk_fma_f32 v[24:25], v[42:43], v[50:51], v[24:25]
	v_pk_fma_f32 v[18:19], v[42:43], v[42:43], v[18:19]
	v_pk_fma_f32 v[22:23], v[50:51], v[50:51], v[22:23]
	v_pk_fma_f32 v[24:25], v[20:21], v[28:29], v[24:25]
	v_pk_fma_f32 v[18:19], v[20:21], v[20:21], v[18:19]
	v_pk_fma_f32 v[20:21], v[28:29], v[28:29], v[22:23]
	v_add_f32_e32 v22, 0, v24
	v_add_f32_e32 v18, v18, v19
	v_add_f32_e32 v19, v20, v21
	v_add_f32_e32 v22, v22, v25
	ds_bpermute_b32 v20, v17, v18
	ds_bpermute_b32 v21, v17, v19
	ds_bpermute_b32 v17, v17, v22
	v_cndmask_b32_e32 v52, v3, v15, vcc
	v_lshlrev_b32_e32 v23, 2, v52
	s_waitcnt lgkmcnt(2)
	v_add_f32_e32 v18, v18, v20
	s_waitcnt lgkmcnt(1)
	v_add_f32_e32 v19, v19, v21
	s_waitcnt lgkmcnt(0)
	v_add_f32_e32 v17, v22, v17
	ds_bpermute_b32 v22, v53, v17
	ds_bpermute_b32 v20, v53, v18
	ds_bpermute_b32 v21, v53, v19
	s_waitcnt lgkmcnt(2)
	v_add_f32_e32 v17, v17, v22
	ds_bpermute_b32 v22, v23, v17
	s_waitcnt lgkmcnt(2)
	v_add_f32_e32 v18, v18, v20
	s_waitcnt lgkmcnt(1)
	v_add_f32_e32 v19, v19, v21
	ds_bpermute_b32 v20, v23, v18
	ds_bpermute_b32 v21, v23, v19
	s_waitcnt lgkmcnt(2)
	v_add_f32_e32 v17, v17, v22
	v_mul_f32_e32 v17, 0x3db504f3, v17
	v_fma_f32 v17, |v17|, s24, v17
	s_waitcnt lgkmcnt(1)
	v_add_f32_e32 v18, v18, v20
	s_waitcnt lgkmcnt(0)
	v_add_f32_e32 v19, v19, v21
	v_max_f32_e32 v5, v5, v18
	v_max_f32_e32 v4, v4, v19
	v_min_f32_e32 v16, v16, v17

; __device__ __forceinline__ void fox_cumsum(const Params& P, int l, int head, char* lds) {
;     ...
;     double run = inc - s;
;     for (int w = 0; w < wid; ++w) run += tot[w];
; #pragma unroll
;     for (int k = 0; k < 33; ++k) { run += (double)lf[k]; CF[base + k] = (float)run; }
;     __syncthreads();
.LBB0_437:
	s_or_b64 exec, exec, s[6:7]
	s_mul_i32 s6, s2, 0x10800
	s_mul_hi_i32 s3, s2, 0x10800
	s_add_u32 s6, s10, s6
	v_add_f64 v[8:9], v[8:9], v[72:73]
	s_addc_u32 s7, s11, s3
	v_add_f64 v[6:7], v[6:7], v[8:9]
	v_lshl_add_u64 v[4:5], v[4:5], 2, s[6:7]
	s_mov_b64 s[6:7], 0x200000
	v_cvt_f32_f64_e32 v73, v[6:7]
	v_add_f64 v[6:7], v[12:13], v[6:7]
	s_mov_b32 s3, 0x200000
	v_lshl_add_u64 v[76:77], v[4:5], 0, s[6:7]
	v_cvt_f32_f64_e32 v74, v[6:7]
	v_add_f64 v[6:7], v[10:11], v[6:7]
	v_add_co_u32_e32 v4, vcc, s3, v4
	v_cvt_f32_f64_e32 v72, v[8:9]
	v_cvt_f32_f64_e32 v75, v[6:7]
	v_addc_co_u32_e32 v5, vcc, 0, v5, vcc
	v_add_f64 v[6:7], v[16:17], v[6:7]
	global_store_dwordx4 v[4:5], v[72:75], off
	v_cvt_f32_f64_e32 v4, v[6:7]
	v_add_f64 v[6:7], v[14:15], v[6:7]
	v_add_f64 v[8:9], v[20:21], v[6:7]
	v_cvt_f32_f64_e32 v5, v[6:7]
	v_cvt_f32_f64_e32 v6, v[8:9]
	v_add_f64 v[8:9], v[18:19], v[8:9]
	v_cvt_f32_f64_e32 v7, v[8:9]
	global_store_dwordx4 v[76:77], v[4:7], off offset:16
	s_nop 1
	v_add_f64 v[6:7], v[24:25], v[8:9]
	v_cvt_f32_f64_e32 v4, v[6:7]
	v_add_f64 v[6:7], v[22:23], v[6:7]
	v_add_f64 v[8:9], v[28:29], v[6:7]
	v_cvt_f32_f64_e32 v5, v[6:7]
	v_cvt_f32_f64_e32 v6, v[8:9]
	v_add_f64 v[8:9], v[26:27], v[8:9]
	v_cvt_f32_f64_e32 v7, v[8:9]
	global_store_dwordx4 v[76:77], v[4:7], off offset:32
	s_nop 1
	v_add_f64 v[6:7], v[32:33], v[8:9]
	v_cvt_f32_f64_e32 v4, v[6:7]
	v_add_f64 v[6:7], v[30:31], v[6:7]
	v_add_f64 v[8:9], v[36:37], v[6:7]
	v_cvt_f32_f64_e32 v5, v[6:7]
	v_cvt_f32_f64_e32 v6, v[8:9]
	v_add_f64 v[8:9], v[34:35], v[8:9]
	v_cvt_f32_f64_e32 v7, v[8:9]
	global_store_dwordx4 v[76:77], v[4:7], off offset:48
	s_nop 1
	v_add_f64 v[6:7], v[40:41], v[8:9]
	v_cvt_f32_f64_e32 v4, v[6:7]
	v_add_f64 v[6:7], v[38:39], v[6:7]
	v_add_f64 v[8:9], v[44:45], v[6:7]
	v_cvt_f32_f64_e32 v5, v[6:7]
	v_cvt_f32_f64_e32 v6, v[8:9]
	v_add_f64 v[8:9], v[42:43], v[8:9]
	v_cvt_f32_f64_e32 v7, v[8:9]
	global_store_dwordx4 v[76:77], v[4:7], off offset:64
	s_nop 1
	v_add_f64 v[6:7], v[48:49], v[8:9]
	v_cvt_f32_f64_e32 v4, v[6:7]
	v_add_f64 v[6:7], v[46:47], v[6:7]
	v_add_f64 v[8:9], v[52:53], v[6:7]
	v_cvt_f32_f64_e32 v5, v[6:7]
	v_cvt_f32_f64_e32 v6, v[8:9]
	v_add_f64 v[8:9], v[50:51], v[8:9]
	v_cvt_f32_f64_e32 v7, v[8:9]
	global_store_dwordx4 v[76:77], v[4:7], off offset:80
	s_nop 1
	v_add_f64 v[6:7], v[56:57], v[8:9]
	v_cvt_f32_f64_e32 v4, v[6:7]
	v_add_f64 v[6:7], v[54:55], v[6:7]
	v_add_f64 v[8:9], v[60:61], v[6:7]
	v_cvt_f32_f64_e32 v5, v[6:7]
	v_cvt_f32_f64_e32 v6, v[8:9]
	v_add_f64 v[8:9], v[58:59], v[8:9]
	v_cvt_f32_f64_e32 v7, v[8:9]
	global_store_dwordx4 v[76:77], v[4:7], off offset:96
	s_nop 1
	v_add_f64 v[6:7], v[64:65], v[8:9]
	v_cvt_f32_f64_e32 v4, v[6:7]
	v_add_f64 v[6:7], v[62:63], v[6:7]
	v_add_f64 v[8:9], v[68:69], v[6:7]
	v_cvt_f32_f64_e32 v5, v[6:7]
	v_cvt_f32_f64_e32 v6, v[8:9]
	v_add_f64 v[8:9], v[66:67], v[8:9]
	v_cvt_f32_f64_e32 v7, v[8:9]
	global_store_dwordx4 v[76:77], v[4:7], off offset:112
	s_nop 1
	v_add_f64 v[4:5], v[70:71], v[8:9]
	v_cvt_f32_f64_e32 v3, v[4:5]
	flat_store_dword v[76:77], v3 offset:128
	s_waitcnt lgkmcnt(0)
	s_barrier

; __device__ __forceinline__ unsigned cvt_pk_bf16(float lo, float hi) { unsigned r; asm volatile("v_cvt_pk_bf16_f32 %0, %1, %2" : "=v"(r) : "v"(lo), "v"(hi)); return r; }
; __device__ __forceinline__ void transpose_item(const float* __restrict__ W, int K, int N, int nblk, bf16_t* __restrict__ WT, int mode, float* scr, int item, int lane) {
;     ...
; #pragma unroll
;     for (int i = 0; i < 32; ++i) { const int kk = 2 * i + (lane >> 5); scr[kk * 33 + (lane & 31)] = wv[i]; }
;     asm volatile("s_waitcnt lgkmcnt(0)" ::: "memory");
;     const int c = lane & 7;
; #pragma unroll
;     for (int j = 0; j < 4; ++j) { const int nn = (lane >> 3) + 8 * j; const float* s = scr + (8 * c) * 33 + nn;
;         u32x4 o; o.x = cvt_pk_bf16(s[0 * 33], s[1 * 33]); o.y = cvt_pk_bf16(s[2 * 33], s[3 * 33]); o.z = cvt_pk_bf16(s[4 * 33], s[5 * 33]); o.w = cvt_pk_bf16(s[6 * 33], s[7 * 33]);
;         *(u32x4*)(WT + (size_t)(n0 + nn) * K + k0 + 8 * c) = o; }
;     asm volatile("s_waitcnt lgkmcnt(0)" ::: "memory");
.LBB0_443:
	s_or_b64 exec, exec, s[18:19]
	s_waitcnt vmcnt(0) lgkmcnt(0)
	ds_write2_b32 v16, v2, v29 offset1:66
	ds_write2_b32 v16, v31, v30 offset0:132 offset1:198
	ds_write2_b32 v21, v33, v32 offset0:8 offset1:74
	ds_write2_b32 v21, v35, v34 offset0:140 offset1:206
	ds_write2_b32 v22, v37, v36 offset0:16 offset1:82
	ds_write2_b32 v22, v39, v38 offset0:148 offset1:214
	ds_write2_b32 v23, v41, v40 offset0:24 offset1:90
	ds_write2_b32 v23, v43, v42 offset0:156 offset1:222
	ds_write2_b32 v24, v45, v44 offset0:32 offset1:98
	ds_write2_b32 v24, v47, v46 offset0:164 offset1:230
	ds_write2_b32 v25, v49, v48 offset0:40 offset1:106
	ds_write2_b32 v25, v51, v50 offset0:172 offset1:238
	ds_write2_b32 v26, v53, v52 offset0:48 offset1:114
	ds_write2_b32 v26, v55, v54 offset0:180 offset1:246
	ds_write2_b32 v27, v57, v56 offset0:56 offset1:122
	ds_write2_b32 v27, v59, v58 offset0:188 offset1:254
	s_waitcnt lgkmcnt(0)
	ds_read2_b32 v[12:13], v17 offset1:33
	s_waitcnt lgkmcnt(0)
	v_cvt_pk_bf16_f32 v28, v12, v13
	ds_read2_b32 v[12:13], v17 offset0:66 offset1:99
	s_waitcnt lgkmcnt(0)
	v_cvt_pk_bf16_f32 v29, v12, v13
	ds_read2_b32 v[12:13], v17 offset0:132 offset1:165
	s_waitcnt lgkmcnt(0)
	v_cvt_pk_bf16_f32 v30, v12, v13
	ds_read2_b32 v[12:13], v17 offset0:198 offset1:231
	s_waitcnt lgkmcnt(0)
	v_cvt_pk_bf16_f32 v31, v12, v13
	v_add_u32_e32 v12, s14, v78
	s_ashr_i32 s17, s16, 31
	v_ashrrev_i32_e32 v13, 31, v12
	v_lshl_add_u64 v[32:33], s[16:17], 1, v[10:11]
	v_lshlrev_b64 v[36:37], 12, v[12:13]
	v_lshl_add_u64 v[36:37], v[32:33], 0, v[36:37]
	global_store_dwordx4 v[36:37], v[28:31], off
	v_add_u32_e32 v36, 8, v12
	v_ashrrev_i32_e32 v37, 31, v36
	ds_read2_b32 v[34:35], v17 offset0:8 offset1:41
	s_waitcnt lgkmcnt(0)
	v_cvt_pk_bf16_f32 v28, v34, v35
	ds_read2_b32 v[30:31], v17 offset0:74 offset1:107
	v_lshlrev_b64 v[36:37], 12, v[36:37]
	s_waitcnt lgkmcnt(0)
	v_cvt_pk_bf16_f32 v29, v30, v31
	ds_read2_b32 v[30:31], v17 offset0:140 offset1:173
	v_lshl_add_u64 v[36:37], v[32:33], 0, v[36:37]
	s_waitcnt lgkmcnt(0)
	v_cvt_pk_bf16_f32 v30, v30, v31
	ds_read2_b32 v[34:35], v17 offset0:206 offset1:239
	s_waitcnt lgkmcnt(0)
	v_cvt_pk_bf16_f32 v31, v34, v35
	global_store_dwordx4 v[36:37], v[28:31], off
	v_add_u32_e32 v36, 16, v12
	ds_read2_b32 v[34:35], v17 offset0:16 offset1:49
	s_waitcnt lgkmcnt(0)
	v_cvt_pk_bf16_f32 v28, v34, v35
	ds_read2_b32 v[30:31], v17 offset0:82 offset1:115
	v_ashrrev_i32_e32 v37, 31, v36
	s_waitcnt lgkmcnt(0)
	v_cvt_pk_bf16_f32 v29, v30, v31
	ds_read2_b32 v[30:31], v17 offset0:148 offset1:181
	v_lshlrev_b64 v[36:37], 12, v[36:37]
	v_add_u32_e32 v12, 24, v12
	s_waitcnt lgkmcnt(0)
	v_cvt_pk_bf16_f32 v30, v30, v31
	ds_read2_b32 v[34:35], v17 offset0:214 offset1:247
	s_waitcnt lgkmcnt(0)
	v_cvt_pk_bf16_f32 v31, v34, v35
	v_lshl_add_u64 v[36:37], v[32:33], 0, v[36:37]
	v_ashrrev_i32_e32 v13, 31, v12
	ds_read2_b32 v[34:35], v17 offset0:24 offset1:57
	global_store_dwordx4 v[36:37], v[28:31], off
	v_lshlrev_b64 v[12:13], 12, v[12:13]
	v_lshl_add_u64 v[12:13], v[32:33], 0, v[12:13]
	s_waitcnt lgkmcnt(0)
	v_cvt_pk_bf16_f32 v28, v34, v35
	ds_read2_b32 v[30:31], v17 offset0:90 offset1:123
	s_waitcnt lgkmcnt(0)
	v_cvt_pk_bf16_f32 v29, v30, v31
	ds_read2_b32 v[30:31], v17 offset0:156 offset1:189
	s_waitcnt lgkmcnt(0)
	v_cvt_pk_bf16_f32 v30, v30, v31
	ds_read2_b32 v[34:35], v17 offset0:222 offset1:255
	s_waitcnt lgkmcnt(0)
	v_cvt_pk_bf16_f32 v31, v34, v35
	global_store_dwordx4 v[12:13], v[28:31], off
	s_waitcnt lgkmcnt(0)

; __device__ __forceinline__ void transpose_item(const float* __restrict__ W, int K, int N, int nblk, bf16_t* __restrict__ WT, int mode, float* scr, int item, int lane) {
;     ...
;     float wv[32];
; #pragma unroll
;     for (int i = 0; i < 32; ++i) { const int kk = 2 * i + (lane >> 5); wv[i] = src >= 0 ? W[(size_t)(k0 + kk) * N + src] : 0.f; }
; #pragma unroll
;     for (int i = 0; i < 32; ++i) { const int kk = 2 * i + (lane >> 5); scr[kk * 33 + (lane & 31)] = wv[i]; }
; __device__ __forceinline__ void convert_weights(const Params& P, int l, int part, char* lds, int gw, int NGW, int wid, int lane) {
;     ...
;     for (int it = lo + gw; it < hi; it += NGW) {
;         int r = it;
;         if (r < I_IN) { transpose_item(w_in, DM, NIN_SRC, NIN / 32, WinT, 1, scr, r, lane); continue; } r -= I_IN;
;         if (r < I_OUT) { transpose_item(w_out, DM, DM, DM / 32, WoutT, 0, scr, r, lane); continue; } r -= I_OUT;
;         if (r < I_UP) { transpose_item(w_up, DM, DFF, DFF / 32, WupT, 0, scr, r, lane); continue; } r -= I_UP;
;         transpose_item(w_down, DFF, DM, DM / 32, WdownT, 0, scr, r, lane);
.LBB0_445:
	s_cmpk_gt_i32 s3, 0x18ff
	s_mov_b64 s[16:17], -1
	s_cbranch_scc0 .LBB0_455
	s_cmpk_gt_u32 s3, 0x20ff
	s_cbranch_scc0 .LBB0_452
	s_cmpk_gt_u32 s3, 0x40ff
	s_cbranch_scc0 .LBB0_449
	s_and_b32 s14, s3, 0x7fffffc0
	s_and_b32 s16, s23, 0x7e0
	s_addk_i32 s14, 0xbf00
	v_or_b32_e32 v2, s16, v14
	v_or_b32_e32 v12, s14, v15
	v_lshlrev_b32_e32 v2, 2, v2
	v_lshl_add_u64 v[28:29], s[10:11], 0, v[2:3]
	v_or_b32_e32 v2, 2, v12
	v_lshlrev_b64 v[32:33], 13, v[2:3]
	v_or_b32_e32 v2, 4, v12
	v_lshlrev_b64 v[34:35], 13, v[2:3]
	v_or_b32_e32 v2, 6, v12
	v_lshlrev_b64 v[36:37], 13, v[2:3]
	v_or_b32_e32 v2, 8, v12
	v_lshlrev_b64 v[38:39], 13, v[2:3]
	v_or_b32_e32 v2, 10, v12
	v_mov_b32_e32 v13, v3
	v_lshlrev_b64 v[40:41], 13, v[2:3]
	v_or_b32_e32 v2, 12, v12
	v_lshlrev_b64 v[30:31], 13, v[12:13]
	v_lshlrev_b64 v[42:43], 13, v[2:3]
	v_or_b32_e32 v2, 14, v12
	v_lshl_add_u64 v[30:31], v[28:29], 0, v[30:31]
	v_lshlrev_b64 v[44:45], 13, v[2:3]
	v_or_b32_e32 v2, 16, v12
	v_lshl_add_u64 v[32:33], v[28:29], 0, v[32:33]
	v_lshl_add_u64 v[34:35], v[28:29], 0, v[34:35]
	v_lshl_add_u64 v[36:37], v[28:29], 0, v[36:37]
	v_lshl_add_u64 v[38:39], v[28:29], 0, v[38:39]
	v_lshl_add_u64 v[40:41], v[28:29], 0, v[40:41]
	v_lshl_add_u64 v[42:43], v[28:29], 0, v[42:43]
	v_lshl_add_u64 v[44:45], v[28:29], 0, v[44:45]
	flat_load_dword v46, v[30:31]
	flat_load_dword v47, v[32:33]
	flat_load_dword v48, v[34:35]
	flat_load_dword v49, v[36:37]
	flat_load_dword v50, v[38:39]
	flat_load_dword v51, v[40:41]
	flat_load_dword v52, v[42:43]
	flat_load_dword v53, v[44:45]
	v_lshlrev_b64 v[30:31], 13, v[2:3]
	v_or_b32_e32 v2, 18, v12
	v_lshlrev_b64 v[32:33], 13, v[2:3]
	v_or_b32_e32 v2, 20, v12
	v_lshlrev_b64 v[34:35], 13, v[2:3]
	v_or_b32_e32 v2, 22, v12
	v_lshlrev_b64 v[36:37], 13, v[2:3]
	v_or_b32_e32 v2, 24, v12
	v_lshlrev_b64 v[38:39], 13, v[2:3]
	v_or_b32_e32 v2, 26, v12
	v_lshlrev_b64 v[40:41], 13, v[2:3]
	v_or_b32_e32 v2, 28, v12
	v_lshlrev_b64 v[42:43], 13, v[2:3]
	v_or_b32_e32 v2, 30, v12
	v_lshl_add_u64 v[30:31], v[28:29], 0, v[30:31]
	v_lshlrev_b64 v[44:45], 13, v[2:3]
	v_or_b32_e32 v2, 32, v12
	v_lshl_add_u64 v[32:33], v[28:29], 0, v[32:33]
	v_lshl_add_u64 v[34:35], v[28:29], 0, v[34:35]
	v_lshl_add_u64 v[36:37], v[28:29], 0, v[36:37]
	v_lshl_add_u64 v[38:39], v[28:29], 0, v[38:39]
	v_lshl_add_u64 v[40:41], v[28:29], 0, v[40:41]
	v_lshl_add_u64 v[42:43], v[28:29], 0, v[42:43]
	v_lshl_add_u64 v[44:45], v[28:29], 0, v[44:45]
	flat_load_dword v54, v[30:31]
	flat_load_dword v55, v[32:33]
	flat_load_dword v56, v[34:35]
	flat_load_dword v57, v[36:37]
	flat_load_dword v58, v[38:39]
	flat_load_dword v59, v[40:41]
	flat_load_dword v60, v[42:43]
	flat_load_dword v61, v[44:45]
	v_lshlrev_b64 v[30:31], 13, v[2:3]
	v_or_b32_e32 v2, 34, v12
	v_lshlrev_b64 v[32:33], 13, v[2:3]
	v_or_b32_e32 v2, 36, v12
	v_lshlrev_b64 v[34:35], 13, v[2:3]
	v_or_b32_e32 v2, 38, v12
	v_lshlrev_b64 v[36:37], 13, v[2:3]
	v_or_b32_e32 v2, 40, v12
	v_lshlrev_b64 v[38:39], 13, v[2:3]
	v_or_b32_e32 v2, 42, v12
	v_lshlrev_b64 v[40:41], 13, v[2:3]
	v_or_b32_e32 v2, 44, v12
	v_lshlrev_b64 v[42:43], 13, v[2:3]
	v_or_b32_e32 v2, 46, v12
	v_lshl_add_u64 v[30:31], v[28:29], 0, v[30:31]
	v_lshlrev_b64 v[44:45], 13, v[2:3]
	v_or_b32_e32 v2, 48, v12
	v_lshl_add_u64 v[32:33], v[28:29], 0, v[32:33]
	v_lshl_add_u64 v[34:35], v[28:29], 0, v[34:35]
	v_lshl_add_u64 v[36:37], v[28:29], 0, v[36:37]
	v_lshl_add_u64 v[38:39], v[28:29], 0, v[38:39]
	v_lshl_add_u64 v[40:41], v[28:29], 0, v[40:41]
	v_lshl_add_u64 v[42:43], v[28:29], 0, v[42:43]
	v_lshl_add_u64 v[44:45], v[28:29], 0, v[44:45]
	flat_load_dword v62, v[30:31]
	flat_load_dword v63, v[32:33]
	flat_load_dword v64, v[34:35]
	flat_load_dword v65, v[36:37]
	flat_load_dword v66, v[38:39]
	flat_load_dword v67, v[40:41]
	flat_load_dword v68, v[42:43]
	flat_load_dword v69, v[44:45]
	v_lshlrev_b64 v[30:31], 13, v[2:3]
	v_or_b32_e32 v2, 50, v12
	v_lshlrev_b64 v[32:33], 13, v[2:3]
	v_or_b32_e32 v2, 52, v12
	v_lshlrev_b64 v[34:35], 13, v[2:3]
	v_or_b32_e32 v2, 54, v12
	v_lshlrev_b64 v[36:37], 13, v[2:3]
	v_or_b32_e32 v2, 56, v12
	v_lshlrev_b64 v[38:39], 13, v[2:3]
	v_or_b32_e32 v2, 58, v12
	v_lshlrev_b64 v[40:41], 13, v[2:3]
	v_or_b32_e32 v2, 60, v12
	v_lshlrev_b64 v[42:43], 13, v[2:3]
	v_or_b32_e32 v2, 62, v12
	v_lshl_add_u64 v[30:31], v[28:29], 0, v[30:31]
	v_lshlrev_b64 v[12:13], 13, v[2:3]
	v_lshl_add_u64 v[32:33], v[28:29], 0, v[32:33]
	v_lshl_add_u64 v[34:35], v[28:29], 0, v[34:35]
	v_lshl_add_u64 v[36:37], v[28:29], 0, v[36:37]
	v_lshl_add_u64 v[38:39], v[28:29], 0, v[38:39]
	v_lshl_add_u64 v[40:41], v[28:29], 0, v[40:41]
	v_lshl_add_u64 v[42:43], v[28:29], 0, v[42:43]
	v_lshl_add_u64 v[12:13], v[28:29], 0, v[12:13]
	flat_load_dword v2, v[30:31]
	flat_load_dword v28, v[32:33]
	flat_load_dword v29, v[34:35]
	flat_load_dword v44, v[36:37]
	flat_load_dword v45, v[38:39]
	flat_load_dword v70, v[40:41]
	flat_load_dword v71, v[42:43]
	flat_load_dword v72, v[12:13]
	v_lshl_add_u64 v[32:33], s[14:15], 1, v[4:5]
	s_waitcnt vmcnt(0) lgkmcnt(0)
	ds_write2_b32 v16, v46, v47 offset1:66
	ds_write2_b32 v16, v48, v49 offset0:132 offset1:198
	ds_write2_b32 v21, v50, v51 offset0:8 offset1:74
	ds_write2_b32 v21, v52, v53 offset0:140 offset1:206
	ds_write2_b32 v22, v54, v55 offset0:16 offset1:82
	ds_write2_b32 v22, v56, v57 offset0:148 offset1:214
	ds_write2_b32 v23, v58, v59 offset0:24 offset1:90
	ds_write2_b32 v23, v60, v61 offset0:156 offset1:222
	ds_write2_b32 v24, v62, v63 offset0:32 offset1:98
	ds_write2_b32 v24, v64, v65 offset0:164 offset1:230
	ds_write2_b32 v25, v66, v67 offset0:40 offset1:106
	ds_write2_b32 v25, v68, v69 offset0:172 offset1:238
	ds_write2_b32 v26, v2, v28 offset0:48 offset1:114
	ds_write2_b32 v26, v29, v44 offset0:180 offset1:246
	ds_write2_b32 v27, v45, v70 offset0:56 offset1:122
	ds_write2_b32 v27, v71, v72 offset0:188 offset1:254
	s_waitcnt lgkmcnt(0)
; __device__ __forceinline__ unsigned cvt_pk_bf16(float lo, float hi) { unsigned r; asm volatile("v_cvt_pk_bf16_f32 %0, %1, %2" : "=v"(r) : "v"(lo), "v"(hi)); return r; }
; __device__ __forceinline__ void transpose_item(const float* __restrict__ W, int K, int N, int nblk, bf16_t* __restrict__ WT, int mode, float* scr, int item, int lane) {
;     const int kb = item / nblk, nb = item % nblk, k0 = 64 * kb, n0 = 32 * nb;
;     const int n = n0 + (lane & 31); int src = n;
;     if (mode) src = n < 2048 ? n : (n < 6144 ? n + 8 : (n < 6152 ? n - 6144 + 2048 : (n < 6160 ? n : -1)));
;     float wv[32];
; #pragma unroll
;     for (int i = 0; i < 32; ++i) { const int kk = 2 * i + (lane >> 5); wv[i] = src >= 0 ? W[(size_t)(k0 + kk) * N + src] : 0.f; }
; #pragma unroll
;     for (int i = 0; i < 32; ++i) { const int kk = 2 * i + (lane >> 5); scr[kk * 33 + (lane & 31)] = wv[i]; }
;     asm volatile("s_waitcnt lgkmcnt(0)" ::: "memory");
;     const int c = lane & 7;
; #pragma unroll
;     for (int j = 0; j < 4; ++j) { const int nn = (lane >> 3) + 8 * j; const float* s = scr + (8 * c) * 33 + nn;
;         u32x4 o; o.x = cvt_pk_bf16(s[0 * 33], s[1 * 33]); o.y = cvt_pk_bf16(s[2 * 33], s[3 * 33]); o.z = cvt_pk_bf16(s[4 * 33], s[5 * 33]); o.w = cvt_pk_bf16(s[6 * 33], s[7 * 33]);
;         *(u32x4*)(WT + (size_t)(n0 + nn) * K + k0 + 8 * c) = o; }
;     asm volatile("s_waitcnt lgkmcnt(0)" ::: "memory");
; }
; __device__ __forceinline__ void convert_weights(const Params& P, int l, int part, char* lds, int gw, int NGW, int wid, int lane) {
;     ...
;         if (r < I_IN) { transpose_item(w_in, DM, NIN_SRC, NIN / 32, WinT, 1, scr, r, lane); continue; } r -= I_IN;
;         if (r < I_OUT) { transpose_item(w_out, DM, DM, DM / 32, WoutT, 0, scr, r, lane); continue; } r -= I_OUT;
;         if (r < I_UP) { transpose_item(w_up, DM, DFF, DFF / 32, WupT, 0, scr, r, lane); continue; } r -= I_UP;
;         transpose_item(w_down, DFF, DM, DM / 32, WdownT, 0, scr, r, lane);
	ds_read2_b32 v[12:13], v17 offset1:33
	s_waitcnt lgkmcnt(0)
	v_cvt_pk_bf16_f32 v28, v12, v13
	ds_read2_b32 v[12:13], v17 offset0:66 offset1:99
	s_waitcnt lgkmcnt(0)
	v_cvt_pk_bf16_f32 v29, v12, v13
	ds_read2_b32 v[12:13], v17 offset0:132 offset1:165
	v_or_b32_e32 v2, s16, v78
	s_waitcnt lgkmcnt(0)
	v_cvt_pk_bf16_f32 v30, v12, v13
	ds_read2_b32 v[12:13], v17 offset0:198 offset1:231
	v_lshlrev_b32_e32 v2, 14, v2
	s_waitcnt lgkmcnt(0)
	v_cvt_pk_bf16_f32 v31, v12, v13
	ds_read2_b32 v[12:13], v17 offset0:8 offset1:41
	v_lshl_add_u64 v[34:35], v[32:33], 0, v[2:3]
	global_store_dwordx4 v[34:35], v[28:31], off
	v_or_b32_e32 v2, s16, v18
	v_lshlrev_b32_e32 v2, 14, v2
	s_waitcnt lgkmcnt(0)
	v_cvt_pk_bf16_f32 v28, v12, v13
	ds_read2_b32 v[12:13], v17 offset0:74 offset1:107
	s_waitcnt lgkmcnt(0)
	v_cvt_pk_bf16_f32 v29, v12, v13
	ds_read2_b32 v[12:13], v17 offset0:140 offset1:173
	s_waitcnt lgkmcnt(0)
	v_cvt_pk_bf16_f32 v30, v12, v13
	ds_read2_b32 v[12:13], v17 offset0:206 offset1:239
	s_waitcnt lgkmcnt(0)
	v_cvt_pk_bf16_f32 v31, v12, v13
	ds_read2_b32 v[12:13], v17 offset0:16 offset1:49
	v_lshl_add_u64 v[34:35], v[32:33], 0, v[2:3]
	global_store_dwordx4 v[34:35], v[28:31], off
	v_or_b32_e32 v2, s16, v19
	v_lshlrev_b32_e32 v2, 14, v2
	s_waitcnt lgkmcnt(0)
	v_cvt_pk_bf16_f32 v28, v12, v13
	ds_read2_b32 v[12:13], v17 offset0:82 offset1:115
	s_waitcnt lgkmcnt(0)
	v_cvt_pk_bf16_f32 v29, v12, v13
	ds_read2_b32 v[12:13], v17 offset0:148 offset1:181
	s_waitcnt lgkmcnt(0)
	v_cvt_pk_bf16_f32 v30, v12, v13
	ds_read2_b32 v[12:13], v17 offset0:214 offset1:247
	s_waitcnt lgkmcnt(0)
	v_cvt_pk_bf16_f32 v31, v12, v13
	ds_read2_b32 v[12:13], v17 offset0:24 offset1:57
	v_lshl_add_u64 v[34:35], v[32:33], 0, v[2:3]
	global_store_dwordx4 v[34:35], v[28:31], off
	v_or_b32_e32 v2, s16, v20
	v_lshlrev_b32_e32 v2, 14, v2
	s_waitcnt lgkmcnt(0)
	v_cvt_pk_bf16_f32 v28, v12, v13
	ds_read2_b32 v[12:13], v17 offset0:90 offset1:123
	s_waitcnt lgkmcnt(0)
	v_cvt_pk_bf16_f32 v29, v12, v13
	ds_read2_b32 v[12:13], v17 offset0:156 offset1:189
	s_waitcnt lgkmcnt(0)
	v_cvt_pk_bf16_f32 v30, v12, v13
	ds_read2_b32 v[12:13], v17 offset0:222 offset1:255
	s_waitcnt lgkmcnt(0)
	v_cvt_pk_bf16_f32 v31, v12, v13
	v_lshl_add_u64 v[12:13], v[32:33], 0, v[2:3]
	global_store_dwordx4 v[12:13], v[28:31], off
	s_waitcnt lgkmcnt(0)
	s_mov_b64 s[16:17], 0
.LBB0_449:
	s_andn2_b64 vcc, exec, s[16:17]
	s_cbranch_vccnz .LBB0_451
	s_add_i32 s14, s3, 0xdf00
	s_and_b32 s16, s23, 0x1fe0
	s_bfe_u32 s14, s14, 0x80008
	v_or_b32_e32 v2, s16, v14
	v_lshl_or_b32 v28, s14, 6, v15
	v_lshlrev_b32_e32 v2, 2, v2
	v_lshl_add_u64 v[12:13], s[8:9], 0, v[2:3]
	v_lshlrev_b32_e32 v2, 15, v28
	v_lshl_add_u64 v[12:13], v[12:13], 0, v[2:3]
	v_add_co_u32_e32 v28, vcc, 0x10000, v12
	s_lshl_b32 s14, s14, 7
	s_nop 0
	v_addc_co_u32_e32 v29, vcc, 0, v13, vcc
	v_add_co_u32_e32 v30, vcc, 0x20000, v12
	s_nop 1
	v_addc_co_u32_e32 v31, vcc, 0, v13, vcc
	v_add_co_u32_e32 v32, vcc, 0x30000, v12
	s_nop 1
	v_addc_co_u32_e32 v33, vcc, 0, v13, vcc
	v_add_co_u32_e32 v34, vcc, 0x40000, v12
	s_nop 1
	v_addc_co_u32_e32 v35, vcc, 0, v13, vcc
	v_add_co_u32_e32 v36, vcc, 0x50000, v12
	s_nop 1
	v_addc_co_u32_e32 v37, vcc, 0, v13, vcc
	v_add_co_u32_e32 v38, vcc, 0x60000, v12
	s_nop 1
	v_addc_co_u32_e32 v39, vcc, 0, v13, vcc
	v_add_co_u32_e32 v40, vcc, 0x70000, v12
	s_nop 1
	v_addc_co_u32_e32 v41, vcc, 0, v13, vcc
	flat_load_dword v2, v[12:13]
	flat_load_dword v44, v[28:29]
	flat_load_dword v45, v[30:31]
	flat_load_dword v46, v[32:33]
	flat_load_dword v47, v[34:35]
	flat_load_dword v48, v[36:37]
	flat_load_dword v49, v[38:39]
	flat_load_dword v50, v[40:41]
	v_add_co_u32_e32 v28, vcc, 0x80000, v12
	s_nop 1
	v_addc_co_u32_e32 v29, vcc, 0, v13, vcc
	v_add_co_u32_e32 v30, vcc, 0x90000, v12
	s_nop 1
	v_addc_co_u32_e32 v31, vcc, 0, v13, vcc
	v_add_co_u32_e32 v32, vcc, 0xa0000, v12
	s_nop 1
	v_addc_co_u32_e32 v33, vcc, 0, v13, vcc
	v_add_co_u32_e32 v34, vcc, 0xb0000, v12
	s_nop 1
	v_addc_co_u32_e32 v35, vcc, 0, v13, vcc
	v_add_co_u32_e32 v36, vcc, 0xc0000, v12
	s_nop 1
	v_addc_co_u32_e32 v37, vcc, 0, v13, vcc
	v_add_co_u32_e32 v38, vcc, 0xd0000, v12
	s_nop 1
	v_addc_co_u32_e32 v39, vcc, 0, v13, vcc
	v_add_co_u32_e32 v40, vcc, 0xe0000, v12
	s_nop 1
	v_addc_co_u32_e32 v41, vcc, 0, v13, vcc
	v_add_co_u32_e32 v42, vcc, 0xf0000, v12
	s_nop 1
	v_addc_co_u32_e32 v43, vcc, 0, v13, vcc
	flat_load_dword v51, v[28:29]
	flat_load_dword v52, v[30:31]
	flat_load_dword v53, v[32:33]
	flat_load_dword v54, v[34:35]
	flat_load_dword v55, v[36:37]
	flat_load_dword v56, v[38:39]
	flat_load_dword v57, v[40:41]
	flat_load_dword v58, v[42:43]
	v_add_co_u32_e32 v28, vcc, 0x100000, v12
	s_nop 1
	v_addc_co_u32_e32 v29, vcc, 0, v13, vcc
	v_add_co_u32_e32 v30, vcc, 0x110000, v12
	s_nop 1
	v_addc_co_u32_e32 v31, vcc, 0, v13, vcc
	v_add_co_u32_e32 v32, vcc, 0x120000, v12
	s_nop 1
	v_addc_co_u32_e32 v33, vcc, 0, v13, vcc
	v_add_co_u32_e32 v34, vcc, 0x130000, v12
	s_nop 1
	v_addc_co_u32_e32 v35, vcc, 0, v13, vcc
	v_add_co_u32_e32 v36, vcc, 0x140000, v12
	s_nop 1
	v_addc_co_u32_e32 v37, vcc, 0, v13, vcc
	v_add_co_u32_e32 v38, vcc, 0x150000, v12
	s_nop 1
	v_addc_co_u32_e32 v39, vcc, 0, v13, vcc
	v_add_co_u32_e32 v40, vcc, 0x160000, v12
	s_nop 1
	v_addc_co_u32_e32 v41, vcc, 0, v13, vcc
	v_add_co_u32_e32 v42, vcc, 0x170000, v12
	s_nop 1
	v_addc_co_u32_e32 v43, vcc, 0, v13, vcc
	flat_load_dword v59, v[28:29]
	flat_load_dword v60, v[30:31]
	flat_load_dword v61, v[32:33]
	flat_load_dword v62, v[34:35]
	flat_load_dword v63, v[36:37]
	flat_load_dword v64, v[38:39]
	flat_load_dword v65, v[40:41]
	flat_load_dword v66, v[42:43]
	v_add_co_u32_e32 v28, vcc, 0x180000, v12
	s_nop 1
	v_addc_co_u32_e32 v29, vcc, 0, v13, vcc
	v_add_co_u32_e32 v30, vcc, 0x190000, v12
	s_nop 1
	v_addc_co_u32_e32 v31, vcc, 0, v13, vcc
	v_add_co_u32_e32 v32, vcc, 0x1a0000, v12
	s_nop 1
	v_addc_co_u32_e32 v33, vcc, 0, v13, vcc
	v_add_co_u32_e32 v34, vcc, 0x1b0000, v12
	s_nop 1
	v_addc_co_u32_e32 v35, vcc, 0, v13, vcc
	v_add_co_u32_e32 v36, vcc, 0x1c0000, v12
	s_nop 1
	v_addc_co_u32_e32 v37, vcc, 0, v13, vcc
	v_add_co_u32_e32 v38, vcc, 0x1d0000, v12
	s_nop 1
	v_addc_co_u32_e32 v39, vcc, 0, v13, vcc
	v_add_co_u32_e32 v40, vcc, 0x1e0000, v12
	s_nop 1
	v_addc_co_u32_e32 v41, vcc, 0, v13, vcc
	v_add_co_u32_e32 v12, vcc, 0x1f0000, v12
	s_nop 1
	v_addc_co_u32_e32 v13, vcc, 0, v13, vcc
	flat_load_dword v42, v[28:29]
	flat_load_dword v43, v[30:31]
	flat_load_dword v67, v[32:33]
	flat_load_dword v68, v[34:35]
	flat_load_dword v69, v[36:37]
	flat_load_dword v70, v[38:39]
	flat_load_dword v71, v[40:41]
	flat_load_dword v72, v[12:13]
	s_waitcnt vmcnt(0) lgkmcnt(0)
; __device__ __forceinline__ unsigned cvt_pk_bf16(float lo, float hi) { unsigned r; asm volatile("v_cvt_pk_bf16_f32 %0, %1, %2" : "=v"(r) : "v"(lo), "v"(hi)); return r; }
; __device__ __forceinline__ void transpose_item(const float* __restrict__ W, int K, int N, int nblk, bf16_t* __restrict__ WT, int mode, float* scr, int item, int lane) {
;     ...
;     for (int i = 0; i < 32; ++i) { const int kk = 2 * i + (lane >> 5); wv[i] = src >= 0 ? W[(size_t)(k0 + kk) * N + src] : 0.f; }
; #pragma unroll
;     for (int i = 0; i < 32; ++i) { const int kk = 2 * i + (lane >> 5); scr[kk * 33 + (lane & 31)] = wv[i]; }
;     asm volatile("s_waitcnt lgkmcnt(0)" ::: "memory");
;     const int c = lane & 7;
; #pragma unroll
;     for (int j = 0; j < 4; ++j) { const int nn = (lane >> 3) + 8 * j; const float* s = scr + (8 * c) * 33 + nn;
;         u32x4 o; o.x = cvt_pk_bf16(s[0 * 33], s[1 * 33]); o.y = cvt_pk_bf16(s[2 * 33], s[3 * 33]); o.z = cvt_pk_bf16(s[4 * 33], s[5 * 33]); o.w = cvt_pk_bf16(s[6 * 33], s[7 * 33]);
;         *(u32x4*)(WT + (size_t)(n0 + nn) * K + k0 + 8 * c) = o; }
;     asm volatile("s_waitcnt lgkmcnt(0)" ::: "memory");
	ds_write2_b32 v16, v2, v44 offset1:66
	ds_write2_b32 v16, v45, v46 offset0:132 offset1:198
	ds_write2_b32 v21, v47, v48 offset0:8 offset1:74
	ds_write2_b32 v21, v49, v50 offset0:140 offset1:206
	ds_write2_b32 v22, v51, v52 offset0:16 offset1:82
	ds_write2_b32 v22, v53, v54 offset0:148 offset1:214
	ds_write2_b32 v23, v55, v56 offset0:24 offset1:90
	ds_write2_b32 v23, v57, v58 offset0:156 offset1:222
	ds_write2_b32 v24, v59, v60 offset0:32 offset1:98
	ds_write2_b32 v24, v61, v62 offset0:164 offset1:230
	ds_write2_b32 v25, v63, v64 offset0:40 offset1:106
	ds_write2_b32 v25, v65, v66 offset0:172 offset1:238
	ds_write2_b32 v26, v42, v43 offset0:48 offset1:114
	ds_write2_b32 v26, v67, v68 offset0:180 offset1:246
	ds_write2_b32 v27, v69, v70 offset0:56 offset1:122
	ds_write2_b32 v27, v71, v72 offset0:188 offset1:254
	s_waitcnt lgkmcnt(0)
	ds_read2_b32 v[12:13], v17 offset1:33
	s_waitcnt lgkmcnt(0)
	v_cvt_pk_bf16_f32 v28, v12, v13
	ds_read2_b32 v[12:13], v17 offset0:66 offset1:99
	s_waitcnt lgkmcnt(0)
	v_cvt_pk_bf16_f32 v29, v12, v13
	ds_read2_b32 v[12:13], v17 offset0:132 offset1:165
	v_or_b32_e32 v2, s16, v78
	s_waitcnt lgkmcnt(0)
	v_cvt_pk_bf16_f32 v30, v12, v13
	ds_read2_b32 v[12:13], v17 offset0:198 offset1:231
	v_lshl_add_u64 v[32:33], v[6:7], 0, s[14:15]
	v_lshlrev_b32_e32 v2, 12, v2
	s_waitcnt lgkmcnt(0)
	v_cvt_pk_bf16_f32 v31, v12, v13
	ds_read2_b32 v[12:13], v17 offset0:8 offset1:41
	v_lshl_add_u64 v[34:35], v[32:33], 0, v[2:3]
	global_store_dwordx4 v[34:35], v[28:31], off
	v_or_b32_e32 v2, s16, v18
	v_lshlrev_b32_e32 v2, 12, v2
	s_waitcnt lgkmcnt(0)
	v_cvt_pk_bf16_f32 v28, v12, v13
	ds_read2_b32 v[12:13], v17 offset0:74 offset1:107
	s_waitcnt lgkmcnt(0)
	v_cvt_pk_bf16_f32 v29, v12, v13
	ds_read2_b32 v[12:13], v17 offset0:140 offset1:173
	s_waitcnt lgkmcnt(0)
	v_cvt_pk_bf16_f32 v30, v12, v13
	ds_read2_b32 v[12:13], v17 offset0:206 offset1:239
	s_waitcnt lgkmcnt(0)
	v_cvt_pk_bf16_f32 v31, v12, v13
	ds_read2_b32 v[12:13], v17 offset0:16 offset1:49
	v_lshl_add_u64 v[34:35], v[32:33], 0, v[2:3]
	global_store_dwordx4 v[34:35], v[28:31], off
	v_or_b32_e32 v2, s16, v19
	v_lshlrev_b32_e32 v2, 12, v2
	s_waitcnt lgkmcnt(0)
	v_cvt_pk_bf16_f32 v28, v12, v13
	ds_read2_b32 v[12:13], v17 offset0:82 offset1:115
	s_waitcnt lgkmcnt(0)
	v_cvt_pk_bf16_f32 v29, v12, v13
	ds_read2_b32 v[12:13], v17 offset0:148 offset1:181
	s_waitcnt lgkmcnt(0)
	v_cvt_pk_bf16_f32 v30, v12, v13
	ds_read2_b32 v[12:13], v17 offset0:214 offset1:247
	s_waitcnt lgkmcnt(0)
	v_cvt_pk_bf16_f32 v31, v12, v13
	ds_read2_b32 v[12:13], v17 offset0:24 offset1:57
	v_lshl_add_u64 v[34:35], v[32:33], 0, v[2:3]
	global_store_dwordx4 v[34:35], v[28:31], off
	v_or_b32_e32 v2, s16, v20
	v_lshlrev_b32_e32 v2, 12, v2
	s_waitcnt lgkmcnt(0)
	v_cvt_pk_bf16_f32 v28, v12, v13
	ds_read2_b32 v[12:13], v17 offset0:90 offset1:123
	s_waitcnt lgkmcnt(0)
	v_cvt_pk_bf16_f32 v29, v12, v13
	ds_read2_b32 v[12:13], v17 offset0:156 offset1:189
	s_waitcnt lgkmcnt(0)
	v_cvt_pk_bf16_f32 v30, v12, v13
	ds_read2_b32 v[12:13], v17 offset0:222 offset1:255
	s_waitcnt lgkmcnt(0)
	v_cvt_pk_bf16_f32 v31, v12, v13
	v_lshl_add_u64 v[12:13], v[32:33], 0, v[2:3]
	global_store_dwordx4 v[12:13], v[28:31], off
	s_waitcnt lgkmcnt(0)

; __device__ __forceinline__ void transpose_item(const float* __restrict__ W, int K, int N, int nblk, bf16_t* __restrict__ WT, int mode, float* scr, int item, int lane) {
;     const int kb = item / nblk, nb = item % nblk, k0 = 64 * kb, n0 = 32 * nb;
;     const int n = n0 + (lane & 31); int src = n;
;     if (mode) src = n < 2048 ? n : (n < 6144 ? n + 8 : (n < 6152 ? n - 6144 + 2048 : (n < 6160 ? n : -1)));
;     float wv[32];
; #pragma unroll
;     for (int i = 0; i < 32; ++i) { const int kk = 2 * i + (lane >> 5); wv[i] = src >= 0 ? W[(size_t)(k0 + kk) * N + src] : 0.f; }
.LBB0_452:
	s_andn2_b64 vcc, exec, s[16:17]
	s_cbranch_vccnz .LBB0_454
	s_add_i32 s14, s3, 0xe700
	s_and_b32 s16, s23, 0x7e0
	s_and_b32 s14, s14, 0xffc0
	v_or_b32_e32 v2, s16, v14
	v_or_b32_e32 v28, s14, v15
	v_lshlrev_b32_e32 v2, 2, v2
	v_lshl_add_u64 v[12:13], s[12:13], 0, v[2:3]
	v_lshlrev_b32_e32 v2, 13, v28
	v_lshl_add_u64 v[12:13], v[12:13], 0, v[2:3]
	v_add_co_u32_e32 v28, vcc, 0x4000, v12
	s_lshl_b32 s14, s14, 1
	s_nop 0
	v_addc_co_u32_e32 v29, vcc, 0, v13, vcc
	v_add_co_u32_e32 v30, vcc, 0x8000, v12
	s_nop 1
	v_addc_co_u32_e32 v31, vcc, 0, v13, vcc
	v_add_co_u32_e32 v32, vcc, 0xc000, v12
	s_nop 1
	v_addc_co_u32_e32 v33, vcc, 0, v13, vcc
	v_add_co_u32_e32 v34, vcc, s24, v12
	s_nop 1
	v_addc_co_u32_e32 v35, vcc, 0, v13, vcc
	v_add_co_u32_e32 v36, vcc, 0x14000, v12
	s_nop 1
	v_addc_co_u32_e32 v37, vcc, 0, v13, vcc
	v_add_co_u32_e32 v38, vcc, 0x18000, v12
	s_nop 1
	v_addc_co_u32_e32 v39, vcc, 0, v13, vcc
	v_add_co_u32_e32 v40, vcc, 0x1c000, v12
	s_nop 1
	v_addc_co_u32_e32 v41, vcc, 0, v13, vcc
	flat_load_dword v2, v[12:13]
	flat_load_dword v44, v[28:29]
	flat_load_dword v45, v[30:31]
	flat_load_dword v46, v[32:33]
	flat_load_dword v47, v[34:35]
	flat_load_dword v48, v[36:37]
	flat_load_dword v49, v[38:39]
	flat_load_dword v50, v[40:41]
	v_add_co_u32_e32 v28, vcc, s25, v12
	s_nop 1
	v_addc_co_u32_e32 v29, vcc, 0, v13, vcc
	v_add_co_u32_e32 v30, vcc, 0x24000, v12
	s_nop 1
	v_addc_co_u32_e32 v31, vcc, 0, v13, vcc
	v_add_co_u32_e32 v32, vcc, 0x28000, v12
	s_nop 1
	v_addc_co_u32_e32 v33, vcc, 0, v13, vcc
	v_add_co_u32_e32 v34, vcc, 0x2c000, v12
	s_nop 1
	v_addc_co_u32_e32 v35, vcc, 0, v13, vcc
	v_add_co_u32_e32 v36, vcc, s26, v12
	s_nop 1
	v_addc_co_u32_e32 v37, vcc, 0, v13, vcc
	v_add_co_u32_e32 v38, vcc, 0x34000, v12
	s_nop 1
	v_addc_co_u32_e32 v39, vcc, 0, v13, vcc
	v_add_co_u32_e32 v40, vcc, 0x38000, v12
	s_nop 1
	v_addc_co_u32_e32 v41, vcc, 0, v13, vcc
	v_add_co_u32_e32 v42, vcc, 0x3c000, v12
	s_nop 1
	v_addc_co_u32_e32 v43, vcc, 0, v13, vcc
	flat_load_dword v51, v[28:29]
	flat_load_dword v52, v[30:31]
	flat_load_dword v53, v[32:33]
	flat_load_dword v54, v[34:35]
	flat_load_dword v55, v[36:37]
	flat_load_dword v56, v[38:39]
	flat_load_dword v57, v[40:41]
	flat_load_dword v58, v[42:43]
	v_add_co_u32_e32 v28, vcc, s27, v12
	s_nop 1
	v_addc_co_u32_e32 v29, vcc, 0, v13, vcc
	v_add_co_u32_e32 v30, vcc, 0x44000, v12
	s_nop 1
	v_addc_co_u32_e32 v31, vcc, 0, v13, vcc
	v_add_co_u32_e32 v32, vcc, 0x48000, v12
	s_nop 1
	v_addc_co_u32_e32 v33, vcc, 0, v13, vcc
	v_add_co_u32_e32 v34, vcc, 0x4c000, v12
	s_nop 1
	v_addc_co_u32_e32 v35, vcc, 0, v13, vcc
	v_add_co_u32_e32 v36, vcc, s28, v12
	s_nop 1
	v_addc_co_u32_e32 v37, vcc, 0, v13, vcc
	v_add_co_u32_e32 v38, vcc, 0x54000, v12
	s_nop 1
	v_addc_co_u32_e32 v39, vcc, 0, v13, vcc
	v_add_co_u32_e32 v40, vcc, 0x58000, v12
	s_nop 1
	v_addc_co_u32_e32 v41, vcc, 0, v13, vcc
	v_add_co_u32_e32 v42, vcc, 0x5c000, v12
	s_nop 1
	v_addc_co_u32_e32 v43, vcc, 0, v13, vcc
	flat_load_dword v59, v[28:29]
	flat_load_dword v60, v[30:31]
	flat_load_dword v61, v[32:33]
	flat_load_dword v62, v[34:35]
	flat_load_dword v63, v[36:37]
	flat_load_dword v64, v[38:39]
	flat_load_dword v65, v[40:41]
	flat_load_dword v66, v[42:43]
	v_add_co_u32_e32 v28, vcc, s29, v12
	s_nop 1
	v_addc_co_u32_e32 v29, vcc, 0, v13, vcc
	v_add_co_u32_e32 v30, vcc, 0x64000, v12
	s_nop 1
	v_addc_co_u32_e32 v31, vcc, 0, v13, vcc
	v_add_co_u32_e32 v32, vcc, 0x68000, v12
	s_nop 1
	v_addc_co_u32_e32 v33, vcc, 0, v13, vcc
	v_add_co_u32_e32 v34, vcc, 0x6c000, v12
	s_nop 1
	v_addc_co_u32_e32 v35, vcc, 0, v13, vcc
	v_add_co_u32_e32 v36, vcc, s30, v12
	s_nop 1
	v_addc_co_u32_e32 v37, vcc, 0, v13, vcc
	v_add_co_u32_e32 v38, vcc, 0x74000, v12
	s_nop 1
	v_addc_co_u32_e32 v39, vcc, 0, v13, vcc
	v_add_co_u32_e32 v40, vcc, 0x78000, v12
	s_nop 1
	v_addc_co_u32_e32 v41, vcc, 0, v13, vcc
	v_add_co_u32_e32 v12, vcc, 0x7c000, v12
	s_nop 1
	v_addc_co_u32_e32 v13, vcc, 0, v13, vcc
	flat_load_dword v42, v[28:29]
	flat_load_dword v43, v[30:31]
	flat_load_dword v67, v[32:33]
	flat_load_dword v68, v[34:35]
	flat_load_dword v69, v[36:37]
	flat_load_dword v70, v[38:39]
	flat_load_dword v71, v[40:41]
	flat_load_dword v72, v[12:13]
	s_waitcnt vmcnt(0) lgkmcnt(0)
; __device__ __forceinline__ unsigned cvt_pk_bf16(float lo, float hi) { unsigned r; asm volatile("v_cvt_pk_bf16_f32 %0, %1, %2" : "=v"(r) : "v"(lo), "v"(hi)); return r; }
; __device__ __forceinline__ void transpose_item(const float* __restrict__ W, int K, int N, int nblk, bf16_t* __restrict__ WT, int mode, float* scr, int item, int lane) {
;     ...
; #pragma unroll
;     for (int i = 0; i < 32; ++i) { const int kk = 2 * i + (lane >> 5); scr[kk * 33 + (lane & 31)] = wv[i]; }
;     asm volatile("s_waitcnt lgkmcnt(0)" ::: "memory");
;     const int c = lane & 7;
; #pragma unroll
;     for (int j = 0; j < 4; ++j) { const int nn = (lane >> 3) + 8 * j; const float* s = scr + (8 * c) * 33 + nn;
;         u32x4 o; o.x = cvt_pk_bf16(s[0 * 33], s[1 * 33]); o.y = cvt_pk_bf16(s[2 * 33], s[3 * 33]); o.z = cvt_pk_bf16(s[4 * 33], s[5 * 33]); o.w = cvt_pk_bf16(s[6 * 33], s[7 * 33]);
;         *(u32x4*)(WT + (size_t)(n0 + nn) * K + k0 + 8 * c) = o; }
;     asm volatile("s_waitcnt lgkmcnt(0)" ::: "memory");
	ds_write2_b32 v16, v2, v44 offset1:66
	ds_write2_b32 v16, v45, v46 offset0:132 offset1:198
	ds_write2_b32 v21, v47, v48 offset0:8 offset1:74
	ds_write2_b32 v21, v49, v50 offset0:140 offset1:206
	ds_write2_b32 v22, v51, v52 offset0:16 offset1:82
	ds_write2_b32 v22, v53, v54 offset0:148 offset1:214
	ds_write2_b32 v23, v55, v56 offset0:24 offset1:90
	ds_write2_b32 v23, v57, v58 offset0:156 offset1:222
	ds_write2_b32 v24, v59, v60 offset0:32 offset1:98
	ds_write2_b32 v24, v61, v62 offset0:164 offset1:230
	ds_write2_b32 v25, v63, v64 offset0:40 offset1:106
	ds_write2_b32 v25, v65, v66 offset0:172 offset1:238
	ds_write2_b32 v26, v42, v43 offset0:48 offset1:114
	ds_write2_b32 v26, v67, v68 offset0:180 offset1:246
	ds_write2_b32 v27, v69, v70 offset0:56 offset1:122
	ds_write2_b32 v27, v71, v72 offset0:188 offset1:254
	s_waitcnt lgkmcnt(0)
	ds_read2_b32 v[12:13], v17 offset1:33
	s_waitcnt lgkmcnt(0)
	v_cvt_pk_bf16_f32 v28, v12, v13
	ds_read2_b32 v[12:13], v17 offset0:66 offset1:99
	s_waitcnt lgkmcnt(0)
	v_cvt_pk_bf16_f32 v29, v12, v13
	ds_read2_b32 v[12:13], v17 offset0:132 offset1:165
	v_or_b32_e32 v2, s16, v78
	s_waitcnt lgkmcnt(0)
	v_cvt_pk_bf16_f32 v30, v12, v13
	ds_read2_b32 v[12:13], v17 offset0:198 offset1:231
	v_lshl_add_u64 v[32:33], v[8:9], 0, s[14:15]
	v_lshlrev_b32_e32 v2, 12, v2
	s_waitcnt lgkmcnt(0)
	v_cvt_pk_bf16_f32 v31, v12, v13
	ds_read2_b32 v[12:13], v17 offset0:8 offset1:41
	v_lshl_add_u64 v[34:35], v[32:33], 0, v[2:3]
	global_store_dwordx4 v[34:35], v[28:31], off
	v_or_b32_e32 v2, s16, v18
	v_lshlrev_b32_e32 v2, 12, v2
	s_waitcnt lgkmcnt(0)
	v_cvt_pk_bf16_f32 v28, v12, v13
	ds_read2_b32 v[12:13], v17 offset0:74 offset1:107
	s_waitcnt lgkmcnt(0)
	v_cvt_pk_bf16_f32 v29, v12, v13
	ds_read2_b32 v[12:13], v17 offset0:140 offset1:173
	s_waitcnt lgkmcnt(0)
	v_cvt_pk_bf16_f32 v30, v12, v13
	ds_read2_b32 v[12:13], v17 offset0:206 offset1:239
	s_waitcnt lgkmcnt(0)
	v_cvt_pk_bf16_f32 v31, v12, v13
	ds_read2_b32 v[12:13], v17 offset0:16 offset1:49
	v_lshl_add_u64 v[34:35], v[32:33], 0, v[2:3]
	global_store_dwordx4 v[34:35], v[28:31], off
	v_or_b32_e32 v2, s16, v19
	v_lshlrev_b32_e32 v2, 12, v2
	s_waitcnt lgkmcnt(0)
	v_cvt_pk_bf16_f32 v28, v12, v13
	ds_read2_b32 v[12:13], v17 offset0:82 offset1:115
	s_waitcnt lgkmcnt(0)
	v_cvt_pk_bf16_f32 v29, v12, v13
	ds_read2_b32 v[12:13], v17 offset0:148 offset1:181
	s_waitcnt lgkmcnt(0)
	v_cvt_pk_bf16_f32 v30, v12, v13
	ds_read2_b32 v[12:13], v17 offset0:214 offset1:247
	s_waitcnt lgkmcnt(0)
	v_cvt_pk_bf16_f32 v31, v12, v13
	ds_read2_b32 v[12:13], v17 offset0:24 offset1:57
	v_lshl_add_u64 v[34:35], v[32:33], 0, v[2:3]
	global_store_dwordx4 v[34:35], v[28:31], off
	v_or_b32_e32 v2, s16, v20
	v_lshlrev_b32_e32 v2, 12, v2
	s_waitcnt lgkmcnt(0)
	v_cvt_pk_bf16_f32 v28, v12, v13
	ds_read2_b32 v[12:13], v17 offset0:90 offset1:123
	s_waitcnt lgkmcnt(0)
	v_cvt_pk_bf16_f32 v29, v12, v13
	ds_read2_b32 v[12:13], v17 offset0:156 offset1:189
	s_waitcnt lgkmcnt(0)
	v_cvt_pk_bf16_f32 v30, v12, v13
	ds_read2_b32 v[12:13], v17 offset0:222 offset1:255
	s_waitcnt lgkmcnt(0)
	v_cvt_pk_bf16_f32 v31, v12, v13
	v_lshl_add_u64 v[12:13], v[32:33], 0, v[2:3]
	global_store_dwordx4 v[12:13], v[28:31], off
	s_waitcnt lgkmcnt(0)

; __device__ __forceinline__ unsigned cvt_pk_bf16(float lo, float hi) { unsigned r; asm volatile("v_cvt_pk_bf16_f32 %0, %1, %2" : "=v"(r) : "v"(lo), "v"(hi)); return r; }
; __device__ __forceinline__ void mlstm_local_unit(const Params& P, int l, int h, int n, char* lds) {
;     ...
;     bf16_t* ct = CT + (size_t)(h * NCH + n) * 32768;
; #pragma unroll
;     for (int j = 0; j < 4; ++j) { const int e = 32 * (eb0 + j) + r32;
; #pragma unroll
;         for (int q = 0; q < 4; ++q) { u32x2 w; w.x = cvt_pk_bf16(acc[j][4 * q], acc[j][4 * q + 1]); w.y = cvt_pk_bf16(acc[j][4 * q + 2], acc[j][4 * q + 3]);
;             *(u32x2*)(ct + e * 128 + 32 * db + 8 * q + 4 * hi) = w; } }
;     __syncthreads();
.LBB0_550:
	s_or_b64 exec, exec, s[8:9]
	v_lshlrev_b64 v[66:67], 16, v[66:67]
	v_lshl_add_u64 v[66:67], s[62:63], 0, v[66:67]
	s_lshl_b32 s22, s18, 1
	v_lshlrev_b32_e32 v70, 7, v68
	v_lshl_add_u64 v[66:67], v[66:67], 0, s[22:23]
	v_lshl_add_u64 v[66:67], v[66:67], 0, v[196:197]
	v_lshl_or_b32 v68, s17, 12, v70
	v_lshl_add_u64 v[66:67], v[66:67], 0, s[50:51]
	v_ashrrev_i32_e32 v69, 31, v68
	v_lshl_add_u64 v[68:69], v[68:69], 1, v[66:67]
	v_cvt_pk_bf16_f32 v50, v50, v51
	v_cvt_pk_bf16_f32 v51, v52, v53
	global_store_dwordx2 v[68:69], v[50:51], off
	v_cvt_pk_bf16_f32 v50, v54, v55
	v_cvt_pk_bf16_f32 v51, v56, v57
	global_store_dwordx2 v[68:69], v[50:51], off offset:16
	v_cvt_pk_bf16_f32 v50, v58, v59
	v_cvt_pk_bf16_f32 v51, v60, v61
	global_store_dwordx2 v[68:69], v[50:51], off offset:32
	v_cvt_pk_bf16_f32 v50, v62, v63
	v_cvt_pk_bf16_f32 v51, v64, v65
	global_store_dwordx2 v[68:69], v[50:51], off offset:48
	v_lshl_or_b32 v50, s16, 12, v70
	v_ashrrev_i32_e32 v51, 31, v50
	v_lshl_add_u64 v[50:51], v[50:51], 1, v[66:67]
	v_cvt_pk_bf16_f32 v34, v34, v35
	v_cvt_pk_bf16_f32 v35, v36, v37
	global_store_dwordx2 v[50:51], v[34:35], off
	v_cvt_pk_bf16_f32 v34, v38, v39
	v_cvt_pk_bf16_f32 v35, v40, v41
	global_store_dwordx2 v[50:51], v[34:35], off offset:16
	v_cvt_pk_bf16_f32 v34, v42, v43
	v_cvt_pk_bf16_f32 v35, v44, v45
	global_store_dwordx2 v[50:51], v[34:35], off offset:32
	v_cvt_pk_bf16_f32 v34, v46, v47
	v_cvt_pk_bf16_f32 v35, v48, v49
	global_store_dwordx2 v[50:51], v[34:35], off offset:48
	v_lshl_or_b32 v34, s15, 12, v70
	v_ashrrev_i32_e32 v35, 31, v34
	v_lshl_add_u64 v[34:35], v[34:35], 1, v[66:67]
	v_cvt_pk_bf16_f32 v18, v18, v19
	v_cvt_pk_bf16_f32 v19, v20, v21
	global_store_dwordx2 v[34:35], v[18:19], off
	v_cvt_pk_bf16_f32 v18, v22, v23
	v_cvt_pk_bf16_f32 v19, v24, v25
	global_store_dwordx2 v[34:35], v[18:19], off offset:16
	v_cvt_pk_bf16_f32 v18, v26, v27
	v_cvt_pk_bf16_f32 v19, v28, v29
	global_store_dwordx2 v[34:35], v[18:19], off offset:32
	v_cvt_pk_bf16_f32 v18, v30, v31
	v_cvt_pk_bf16_f32 v19, v32, v33
	global_store_dwordx2 v[34:35], v[18:19], off offset:48
	v_lshl_or_b32 v18, s14, 12, v70
	v_ashrrev_i32_e32 v19, 31, v18
	v_lshl_add_u64 v[18:19], v[18:19], 1, v[66:67]
	v_cvt_pk_bf16_f32 v2, v2, v3
	v_cvt_pk_bf16_f32 v3, v4, v5
	global_store_dwordx2 v[18:19], v[2:3], off
	v_cvt_pk_bf16_f32 v2, v6, v7
	v_cvt_pk_bf16_f32 v3, v8, v9
	global_store_dwordx2 v[18:19], v[2:3], off offset:16
	v_cvt_pk_bf16_f32 v2, v10, v11
	v_cvt_pk_bf16_f32 v3, v12, v13
	s_add_i32 s3, s3, 1
	global_store_dwordx2 v[18:19], v[2:3], off offset:32
	v_cvt_pk_bf16_f32 v2, v14, v15
	v_cvt_pk_bf16_f32 v3, v16, v17
	global_store_dwordx2 v[18:19], v[2:3], off offset:48
	s_waitcnt lgkmcnt(0)
	s_barrier

; __device__ __forceinline__ void mlstm_local_unit(const Params& P, int l, int h, int n, char* lds) {
;     ...
;     u32x4 kx[2][4], vx[4];
; #pragma unroll
;     for (int i = 0; i < 2; ++i) { const int idx = tid + 512 * i, t = idx >> 4, c = idx & 15;
; #pragma unroll
;         for (int k = 0; k < 4; ++k) { const int rr = t0 + t - 3 + k; kx[i][k] = (u32x4){0u, 0u, 0u, 0u};
;             if (rr >= 0) kx[i][k] = *(const u32x4*)(PROJ + (size_t)rr * PW + C_MK + h * 128 + c * 8); } }
; #pragma unroll
;     for (int i = 0; i < 4; ++i) { const int idx = tid + 512 * i, t = idx >> 5, c = idx & 31; vx[i] = *(const u32x4*)(PROJ + (size_t)(t0 + t) * PW + C_MV + h * 256 + c * 8); }
.LBB0_559:
	s_or_b64 exec, exec, s[64:65]
	v_cmp_lt_i32_e32 vcc, -3, v2
	v_mov_b32_e32 v34, 0
	v_mov_b32_e32 v46, 0
	v_mov_b32_e32 v47, 0
	v_mov_b32_e32 v48, 0
	v_mov_b32_e32 v49, 0
	s_and_saveexec_b64 s[64:65], vcc
	s_cbranch_execz .LBB0_561
	v_add_u32_e32 v4, 2, v2
	v_mov_b64_e32 v[2:3], s[8:9]
	v_mad_u64_u32 v[2:3], s[38:39], v4, s91, v[2:3]
	s_lshl_b32 s22, s35, 1
	v_lshl_add_u64 v[2:3], v[2:3], 0, s[22:23]
	v_lshlrev_b32_e32 v196, 1, v96
	v_lshl_add_u64 v[2:3], v[2:3], 0, v[196:197]
	global_load_dwordx4 v[46:49], v[2:3], off offset:1024
.LBB0_561:
	s_or_b64 exec, exec, s[64:65]
	v_add_u32_e32 v2, s36, v97
	v_cmp_lt_i32_e32 vcc, -1, v2
	v_mov_b32_e32 v35, 0
	v_mov_b32_e32 v36, 0
	v_mov_b32_e32 v37, 0
	s_and_saveexec_b64 s[64:65], vcc
	s_cbranch_execz .LBB0_563
	v_mov_b64_e32 v[4:5], s[8:9]
	v_mad_u64_u32 v[2:3], s[38:39], v2, s91, v[4:5]
	s_lshl_b32 s22, s35, 1
	v_lshl_add_u64 v[2:3], v[2:3], 0, s[22:23]
	v_lshlrev_b32_e32 v196, 1, v96
	v_lshl_add_u64 v[2:3], v[2:3], 0, v[196:197]
	global_load_dwordx4 v[34:37], v[2:3], off offset:1024
.LBB0_563:
	s_or_b64 exec, exec, s[64:65]
	v_add_u32_e32 v86, 0x200, v74
	v_ashrrev_i32_e32 v94, 4, v86
	v_add_u32_e32 v2, s37, v94
	v_cmp_lt_i32_e32 vcc, -1, v2
	v_mov_b32_e32 v22, 0
	v_mov_b32_e32 v26, 0
	v_mov_b32_e32 v27, 0
	v_mov_b32_e32 v28, 0
	v_mov_b32_e32 v29, 0
	s_and_saveexec_b64 s[64:65], vcc
	s_cbranch_execz .LBB0_565
	v_mov_b64_e32 v[4:5], s[8:9]
	v_mad_u64_u32 v[4:5], s[38:39], v2, s91, v[4:5]
	s_lshl_b32 s22, s35, 1
	v_lshl_add_u64 v[4:5], v[4:5], 0, s[22:23]
	v_lshlrev_b32_e32 v196, 1, v96
	v_lshl_add_u64 v[4:5], v[4:5], 0, v[196:197]
	global_load_dwordx4 v[26:29], v[4:5], off offset:1024
.LBB0_565:
	s_or_b64 exec, exec, s[64:65]
	v_cmp_lt_i32_e32 vcc, -2, v2
	v_mov_b32_e32 v23, 0
	v_mov_b32_e32 v24, 0
	v_mov_b32_e32 v25, 0
	s_and_saveexec_b64 s[64:65], vcc
	s_cbranch_execz .LBB0_567
	v_add_u32_e32 v3, 1, v2
	v_mov_b64_e32 v[4:5], s[8:9]
	v_mad_u64_u32 v[4:5], s[38:39], v3, s91, v[4:5]
	s_lshl_b32 s22, s35, 1
	v_lshl_add_u64 v[4:5], v[4:5], 0, s[22:23]
	v_lshlrev_b32_e32 v196, 1, v96
	v_lshl_add_u64 v[4:5], v[4:5], 0, v[196:197]
	global_load_dwordx4 v[22:25], v[4:5], off offset:1024
.LBB0_567:
	s_or_b64 exec, exec, s[64:65]
	v_cmp_lt_i32_e32 vcc, -3, v2
	v_mov_b32_e32 v18, 0
	v_mov_b32_e32 v30, 0
	v_mov_b32_e32 v31, 0
	v_mov_b32_e32 v32, 0
	v_mov_b32_e32 v33, 0
	s_and_saveexec_b64 s[64:65], vcc
	s_cbranch_execz .LBB0_569
	v_add_u32_e32 v4, 2, v2
	v_mov_b64_e32 v[2:3], s[8:9]
	v_mad_u64_u32 v[2:3], s[38:39], v4, s91, v[2:3]
	s_lshl_b32 s22, s35, 1
	v_lshl_add_u64 v[2:3], v[2:3], 0, s[22:23]
	v_lshlrev_b32_e32 v196, 1, v96
	v_lshl_add_u64 v[2:3], v[2:3], 0, v[196:197]
	global_load_dwordx4 v[30:33], v[2:3], off offset:1024
.LBB0_569:
	s_or_b64 exec, exec, s[64:65]
	v_add_u32_e32 v2, s36, v94
	v_cmp_lt_i32_e32 vcc, -1, v2
	v_mov_b32_e32 v19, 0
	v_mov_b32_e32 v20, 0
	v_mov_b32_e32 v21, 0
	s_and_saveexec_b64 s[64:65], vcc
	s_cbranch_execz .LBB0_571
	v_mov_b64_e32 v[4:5], s[8:9]
	v_mad_u64_u32 v[2:3], s[38:39], v2, s91, v[4:5]
	s_lshl_b32 s22, s35, 1
	v_lshl_add_u64 v[2:3], v[2:3], 0, s[22:23]
	v_lshlrev_b32_e32 v196, 1, v96
	v_lshl_add_u64 v[2:3], v[2:3], 0, v[196:197]
	global_load_dwordx4 v[18:21], v[2:3], off offset:1024
.LBB0_571:
	s_or_b64 exec, exec, s[64:65]
	v_ashrrev_i32_e32 v93, 5, v74
	v_ashrrev_i32_e32 v91, 5, v86
	v_add_u32_e32 v4, s36, v93
	v_mov_b64_e32 v[2:3], s[8:9]
	v_add_u32_e32 v6, s36, v91
	v_and_b32_e32 v92, 0xf8, v75
	v_mad_i64_i32 v[4:5], s[8:9], v4, s91, v[2:3]
	s_lshl_b32 s22, s30, 9
	v_mad_i64_i32 v[6:7], s[8:9], v6, s91, v[2:3]
	v_lshl_add_u64 v[4:5], v[4:5], 0, s[22:23]
	v_lshlrev_b32_e32 v196, 1, v92
	v_lshl_add_u64 v[6:7], v[6:7], 0, s[22:23]
	v_add_u32_e32 v89, 0x400, v74
	v_add_u32_e32 v87, 0x600, v74
	v_lshl_add_u64 v[4:5], v[4:5], 0, v[196:197]
	v_lshl_add_u64 v[6:7], v[6:7], 0, v[196:197]
	v_ashrrev_i32_e32 v90, 5, v89
	v_ashrrev_i32_e32 v88, 5, v87
	global_load_dwordx4 v[14:17], v[4:5], off offset:2048
	s_nop 0
	global_load_dwordx4 v[6:9], v[6:7], off offset:2048
	v_add_u32_e32 v4, s36, v90
	v_add_u32_e32 v10, s36, v88
	v_mad_i64_i32 v[4:5], s[8:9], v4, s91, v[2:3]
	v_mad_i64_i32 v[2:3], s[8:9], v10, s91, v[2:3]
	v_lshl_add_u64 v[4:5], v[4:5], 0, s[22:23]
	v_lshl_add_u64 v[2:3], v[2:3], 0, s[22:23]
	v_lshl_add_u64 v[4:5], v[4:5], 0, v[196:197]
	v_lshl_add_u64 v[2:3], v[2:3], 0, v[196:197]
	global_load_dwordx4 v[10:13], v[4:5], off offset:2048
	s_nop 0
	global_load_dwordx4 v[2:5], v[2:3], off offset:2048
	s_cmp_gt_u32 s34, 63
	v_and_b32_e32 v95, 63, v74
	s_cbranch_scc1 .LBB0_575
; __device__ __forceinline__ float logsigmoid(float x) { return fminf(x, 0.f) - log1pf(__expf(-fabsf(x))); }
; __device__ __forceinline__ void mlstm_local_unit(const Params& P, int l, int h, int n, char* lds) {
;     ...
;     if (wid == 0) {
;         const int row = t0 + lane;
;         const float li = GATES[(size_t)row * 16 + h] + P.in[5][l * 4 + h];
;         const float lf = logsigmoid(GATES[(size_t)row * 16 + 4 + h] + P.in[6][l * 4 + h]);
;         const float b = wave_scan_add(lf, lane);
	v_or_b32_e32 v50, s36, v95
	v_ashrrev_i32_e32 v51, 31, v50
	v_lshlrev_b64 v[50:51], 6, v[50:51]
	v_lshl_add_u64 v[50:51], s[62:63], 0, v[50:51]
	s_lshl_b32 s22, s30, 2
	v_lshl_add_u64 v[50:51], v[50:51], 0, s[22:23]
	s_mov_b64 s[8:9], 0x300000
	v_lshl_add_u64 v[52:53], v[50:51], 0, s[8:9]
	s_waitcnt lgkmcnt(0)
	s_add_u32 s8, s16, s22
	s_addc_u32 s9, s17, 0
	s_add_u32 s16, s18, s22
	s_addc_u32 s17, s19, 0
	v_mov_b64_e32 v[54:55], s[16:17]
	flat_load_dword v54, v[54:55]
	s_nop 0
	flat_load_dword v53, v[52:53] offset:16
	v_and_b32_e32 v52, 64, v207
	v_add_u32_e32 v55, -1, v207
	v_cmp_lt_i32_e32 vcc, v55, v52
	s_mov_b32 s16, 0xbfb8aa3b
	s_mov_b32 s17, 0x3f2aaaab
	v_cndmask_b32_e32 v55, v55, v207, vcc
	v_add_co_u32_e32 v50, vcc, 0x300000, v50
	s_mov_b32 s18, 0x3f317218
	s_nop 0
	v_addc_co_u32_e32 v51, vcc, 0, v51, vcc
	flat_load_dword v59, v[50:51]
	v_mov_b32_e32 v56, 0x3ecc95a3
	s_mov_b32 s19, 0x7f800000
	v_mov_b32_e32 v57, 0x7f800000
	v_mov_b32_e32 v58, 0x7fc00000
	s_mov_b32 s22, 0x33800000
	v_lshlrev_b32_e32 v55, 2, v55
	s_waitcnt vmcnt(0) lgkmcnt(0)
	v_add_f32_e32 v53, v53, v54
	v_mul_f32_e64 v50, |v53|, s16
	v_exp_f32_e32 v54, v50
	v_mov_b64_e32 v[50:51], s[8:9]
	flat_load_dword v60, v[50:51]
	v_min_f32_e32 v53, 0, v53
	v_add_f32_e32 v61, 1.0, v54
	v_add_f32_e32 v62, -1.0, v61
	v_frexp_mant_f32_e32 v63, v61
	v_cvt_f64_f32_e32 v[50:51], v61
	v_sub_f32_e32 v64, v62, v61
	v_frexp_exp_i32_f64_e32 v50, v[50:51]
	v_cmp_gt_f32_e32 vcc, s17, v63
	v_sub_f32_e32 v62, v54, v62
	v_add_f32_e32 v51, 1.0, v64
	v_subbrev_co_u32_e32 v50, vcc, 0, v50, vcc
	v_add_f32_e32 v51, v62, v51
	v_sub_u32_e32 v62, 0, v50
	v_cvt_f32_i32_e32 v50, v50
	v_ldexp_f32 v61, v61, v62
	v_ldexp_f32 v51, v51, v62
	v_add_f32_e32 v62, -1.0, v61
	v_add_f32_e32 v63, 1.0, v61
	v_add_f32_e32 v64, 1.0, v62
	v_add_f32_e32 v65, -1.0, v63
	v_sub_f32_e32 v64, v61, v64
	v_sub_f32_e32 v61, v61, v65
	v_mul_f32_e32 v65, 0x3f317218, v50
	v_add_f32_e32 v64, v51, v64
	v_add_f32_e32 v51, v51, v61
	v_fma_f32 v61, v50, s18, -v65
	v_add_f32_e32 v66, v62, v64
	v_add_f32_e32 v67, v63, v51
	v_fmac_f32_e32 v61, 0xb102e308, v50
	v_sub_f32_e32 v50, v66, v62
	v_sub_f32_e32 v62, v67, v63
	v_rcp_f32_e32 v63, v67
	v_add_f32_e32 v68, v65, v61
	v_sub_f32_e32 v51, v51, v62
	v_sub_f32_e32 v62, v68, v65
	v_sub_f32_e32 v61, v61, v62
	v_mul_f32_e32 v62, v66, v63
	v_sub_f32_e32 v50, v64, v50
	v_mul_f32_e32 v64, v67, v62
	v_fma_f32 v65, v62, v67, -v64
	v_fmac_f32_e32 v65, v62, v51
	v_add_f32_e32 v69, v64, v65
	v_sub_f32_e32 v70, v66, v69
	v_sub_f32_e32 v64, v69, v64
	v_sub_f32_e32 v66, v66, v70
	v_sub_f32_e32 v64, v64, v65
	v_sub_f32_e32 v65, v66, v69
	v_add_f32_e32 v50, v50, v65
	v_add_f32_e32 v50, v64, v50
	v_add_f32_e32 v64, v70, v50
	v_mul_f32_e32 v65, v63, v64
	v_sub_f32_e32 v66, v70, v64
	v_mul_f32_e32 v69, v67, v65
	v_add_f32_e32 v50, v50, v66
	v_add_f32_e32 v66, v62, v65
	v_fma_f32 v67, v65, v67, -v69
	v_sub_f32_e32 v62, v66, v62
	v_fmac_f32_e32 v67, v65, v51
	v_sub_f32_e32 v51, v65, v62
	v_add_f32_e32 v62, v69, v67
	v_sub_f32_e32 v65, v62, v69
	v_sub_f32_e32 v69, v64, v62
	v_sub_f32_e32 v64, v64, v69
	v_sub_f32_e32 v62, v64, v62
	v_sub_f32_e32 v65, v65, v67
	v_add_f32_e32 v50, v50, v62
	v_add_f32_e32 v50, v65, v50
	v_add_f32_e32 v50, v69, v50
	v_mul_f32_e32 v50, v63, v50
	v_add_f32_e32 v50, v51, v50
	v_add_f32_e32 v51, v66, v50
	v_mul_f32_e32 v62, v51, v51
	v_fmamk_f32 v56, v62, 0x3e9b6dac, v56
	v_sub_f32_e32 v63, v51, v66
	v_ldexp_f32 v64, v51, 1
	v_mul_f32_e32 v51, v51, v62
	v_fmaak_f32 v56, v62, v56, 0x3f2aaada
	v_mul_f32_e32 v51, v51, v56
	v_add_f32_e32 v56, v64, v51
	v_sub_f32_e32 v50, v50, v63
	v_sub_f32_e32 v62, v56, v64
	v_ldexp_f32 v50, v50, 1
	v_sub_f32_e32 v51, v51, v62
	v_add_f32_e32 v50, v50, v51
	v_add_f32_e32 v51, v56, v50
	v_sub_f32_e32 v56, v51, v56
	v_add_f32_e32 v62, v68, v51
	v_sub_f32_e32 v50, v50, v56
	v_sub_f32_e32 v56, v62, v68
	v_sub_f32_e32 v63, v62, v56
	v_sub_f32_e32 v51, v51, v56
	v_add_f32_e32 v56, v61, v50
	v_sub_f32_e32 v63, v68, v63
	v_sub_f32_e32 v64, v56, v61
	v_add_f32_e32 v51, v51, v63
	v_sub_f32_e32 v63, v56, v64
	v_add_f32_e32 v51, v56, v51
	v_sub_f32_e32 v50, v50, v64
	v_sub_f32_e32 v61, v61, v63
	v_add_f32_e32 v56, v62, v51
	v_add_f32_e32 v50, v50, v61
	v_sub_f32_e32 v61, v56, v62
	v_sub_f32_e32 v51, v51, v61
	v_add_f32_e32 v50, v50, v51
	v_add_f32_e32 v50, v56, v50
	v_cmp_neq_f32_e32 vcc, s19, v54
	s_nop 1
	v_cndmask_b32_e32 v50, v57, v50, vcc
	v_cmp_ngt_f32_e32 vcc, -1.0, v54
	s_nop 1
	v_cndmask_b32_e32 v50, v58, v50, vcc
	v_cmp_neq_f32_e32 vcc, -1.0, v54
	s_nop 1
	v_cndmask_b32_e32 v50, v208, v50, vcc
	v_cmp_lt_f32_e64 vcc, |v54|, s22
	s_nop 1
	v_cndmask_b32_e32 v50, v50, v54, vcc
	v_sub_f32_e32 v50, v53, v50
	ds_bpermute_b32 v51, v55, v50
	v_add_u32_e32 v53, -2, v207
	v_cmp_lt_i32_e32 vcc, v53, v52
	v_xor_b32_e32 v54, 1, v207
	v_xor_b32_e32 v55, 4, v207
	v_cndmask_b32_e32 v53, v53, v207, vcc
	s_waitcnt lgkmcnt(0)
; __device__ __forceinline__ void mlstm_local_unit(const Params& P, int l, int h, int n, char* lds) {
;     ...
;         const float b = wave_scan_add(lf, lane);
;         const float g = __shfl(b, 63);
;         const float a = g - b + li;
;         const float ml = wave_max(a);
;         wl[lane] = __expf(a - ml);
;         if (lane == 0) { GM[(h * NCH + n) * 2] = g; GM[(h * NCH + n) * 2 + 1] = ml; }
	v_add_f32_e32 v51, v50, v51
	v_cmp_eq_u32_e32 vcc, 0, v95
	v_lshlrev_b32_e32 v53, 2, v53
	s_nop 0
	v_cndmask_b32_e32 v50, v51, v50, vcc
	ds_bpermute_b32 v51, v53, v50
	v_add_u32_e32 v53, -4, v207
	v_cmp_lt_i32_e64 s[8:9], v53, v52
	s_waitcnt lgkmcnt(0)
	v_add_f32_e32 v51, v50, v51
	v_cndmask_b32_e64 v53, v53, v207, s[8:9]
	v_cmp_gt_u32_e64 s[8:9], 2, v95
	v_lshlrev_b32_e32 v53, 2, v53
	s_nop 0
	v_cndmask_b32_e64 v50, v51, v50, s[8:9]
	ds_bpermute_b32 v51, v53, v50
	v_add_u32_e32 v53, -8, v207
	v_cmp_lt_i32_e64 s[8:9], v53, v52
	s_waitcnt lgkmcnt(0)
	v_add_f32_e32 v51, v50, v51
	v_cndmask_b32_e64 v53, v53, v207, s[8:9]
	v_cmp_gt_u32_e64 s[8:9], 4, v95
	v_lshlrev_b32_e32 v53, 2, v53
	s_nop 0
	v_cndmask_b32_e64 v50, v51, v50, s[8:9]
	ds_bpermute_b32 v51, v53, v50
	v_add_u32_e32 v53, -16, v207
	v_cmp_lt_i32_e64 s[8:9], v53, v52
	s_waitcnt lgkmcnt(0)
	v_add_f32_e32 v51, v50, v51
	v_cndmask_b32_e64 v53, v53, v207, s[8:9]
	v_cmp_gt_u32_e64 s[8:9], 8, v95
	v_lshlrev_b32_e32 v53, 2, v53
	s_nop 0
	v_cndmask_b32_e64 v50, v51, v50, s[8:9]
	ds_bpermute_b32 v51, v53, v50
	v_subrev_u32_e32 v53, 32, v207
	v_cmp_lt_i32_e64 s[8:9], v53, v52
	v_add_u32_e32 v52, 64, v52
	s_waitcnt lgkmcnt(0)
	v_add_f32_e32 v51, v50, v51
	v_cndmask_b32_e64 v53, v53, v207, s[8:9]
	v_cmp_gt_u32_e64 s[8:9], 16, v95
	v_lshlrev_b32_e32 v53, 2, v53
	s_nop 0
	v_cndmask_b32_e64 v50, v51, v50, s[8:9]
	ds_bpermute_b32 v51, v53, v50
	v_bfrev_b32_e32 v53, 0.5
	v_cmp_gt_u32_e64 s[8:9], 32, v95
	v_lshl_or_b32 v53, v207, 2, v53
	s_waitcnt lgkmcnt(0)
	v_add_f32_e32 v51, v50, v51
	v_cndmask_b32_e64 v51, v51, v50, s[8:9]
	ds_bpermute_b32 v50, v53, v51
	v_cmp_lt_i32_e64 s[8:9], v54, v52
	s_waitcnt lgkmcnt(0)
	v_sub_f32_e32 v51, v50, v51
	v_cndmask_b32_e64 v53, v207, v54, s[8:9]
	s_waitcnt vmcnt(0)
	v_add_f32_e32 v54, v59, v60
	v_lshlrev_b32_e32 v53, 2, v53
	v_add_f32_e32 v54, v54, v51
	ds_bpermute_b32 v51, v53, v54
	v_xor_b32_e32 v53, 2, v207
	v_cmp_lt_i32_e64 s[8:9], v53, v52
	s_waitcnt lgkmcnt(0)
	v_max_f32_e32 v51, v51, v51
	v_cndmask_b32_e64 v53, v207, v53, s[8:9]
	v_lshlrev_b32_e32 v53, 2, v53
	v_max_f32_e32 v51, v54, v51
	ds_bpermute_b32 v53, v53, v51
	v_cmp_lt_i32_e64 s[8:9], v55, v52
	s_waitcnt lgkmcnt(0)
	v_max_f32_e32 v53, v53, v53
	v_cndmask_b32_e64 v55, v207, v55, s[8:9]
	v_lshlrev_b32_e32 v55, 2, v55
	v_max_f32_e32 v51, v51, v53
	ds_bpermute_b32 v53, v55, v51
	v_xor_b32_e32 v55, 8, v207
	v_cmp_lt_i32_e64 s[8:9], v55, v52
	s_waitcnt lgkmcnt(0)
	v_max_f32_e32 v53, v53, v53
	v_cndmask_b32_e64 v55, v207, v55, s[8:9]
	v_lshlrev_b32_e32 v55, 2, v55
	v_max_f32_e32 v51, v51, v53
	ds_bpermute_b32 v53, v55, v51
	v_xor_b32_e32 v55, 16, v207
	v_cmp_lt_i32_e64 s[8:9], v55, v52
	s_waitcnt lgkmcnt(0)
	v_max_f32_e32 v53, v53, v53
	v_cndmask_b32_e64 v55, v207, v55, s[8:9]
	v_lshlrev_b32_e32 v55, 2, v55
	v_max_f32_e32 v51, v51, v53
	ds_bpermute_b32 v53, v55, v51
	v_xor_b32_e32 v55, 32, v207
	v_cmp_lt_i32_e64 s[8:9], v55, v52
	s_waitcnt lgkmcnt(0)
	v_max_f32_e32 v53, v53, v53
	v_cndmask_b32_e64 v52, v207, v55, s[8:9]
	v_max_f32_e32 v51, v51, v53
	v_lshlrev_b32_e32 v52, 2, v52
	ds_bpermute_b32 v52, v52, v51
	v_lshl_add_u32 v53, v95, 2, v209
	s_waitcnt lgkmcnt(0)
	v_max_f32_e32 v52, v52, v52
	v_max_f32_e32 v51, v51, v52
	v_sub_f32_e32 v52, v54, v51
	v_mul_f32_e32 v52, 0x3fb8aa3b, v52
	v_exp_f32_e32 v52, v52
	ds_write_b32 v53, v52 offset:55296
	s_and_saveexec_b64 s[8:9], vcc
	s_cbranch_execz .LBB0_574
	s_mul_i32 s16, s30, 0x101
	s_add_i32 s16, s16, s31
	s_lshl_b32 s16, s16, 1
	s_ashr_i32 s17, s16, 31
	s_lshl_b64 s[16:17], s[16:17], 2
	s_add_u32 s16, s62, s16
	s_addc_u32 s17, s63, s17
	v_mov_b32_e32 v52, s16
	v_add_co_u32_e32 v52, vcc, 0x60000, v52
	v_mov_b32_e32 v53, s17
	s_nop 0
	v_addc_co_u32_e32 v53, vcc, 0, v53, vcc
	global_store_dwordx2 v[52:53], v[50:51], off

; __device__ __forceinline__ unsigned cvt_pk_bf16(float lo, float hi) { unsigned r; asm volatile("v_cvt_pk_bf16_f32 %0, %1, %2" : "=v"(r) : "v"(lo), "v"(hi)); return r; }
; __device__ __forceinline__ float bflo(unsigned w) { return __uint_as_float(w << 16); }
; __device__ __forceinline__ float bfhi(unsigned w) { return __uint_as_float(w & 0xffff0000u); }
; __device__ __forceinline__ float sigmoidf(float x) { return 1.f / (1.f + __expf(-x)); }
; __device__ __forceinline__ int tsw(int row, int t) { return ((((t >> 1) + 4 * ((row >> 3) & 7)) & 31) << 1) | (t & 1); }
; __device__ __forceinline__ void mlstm_local_unit(const Params& P, int l, int h, int n, char* lds) {
;     ...
;     for (int i = 0; i < 2; ++i) { const int idx = tid + 512 * i, t = idx >> 4, c = idx & 15; const int ch = C_MK + h * 128 + c * 8;
;         const f32x4 b0 = *(const f32x4*)(cb + ch), b1 = *(const f32x4*)(cb + ch + 4);
;         float a[8] = {b0[0], b0[1], b0[2], b0[3], b1[0], b1[1], b1[2], b1[3]};
; #pragma unroll
;         for (int k = 0; k < 4; ++k) { const u32x4 x = kx[i][k];
;             const f32x4 w0 = *(const f32x4*)(cw + k * 1024 + ch), w1 = *(const f32x4*)(cw + k * 1024 + ch + 4);
;             a[0] += w0[0] * bflo(x.x); a[1] += w0[1] * bfhi(x.x); a[2] += w0[2] * bflo(x.y); a[3] += w0[3] * bfhi(x.y);
;             a[4] += w1[0] * bflo(x.z); a[5] += w1[1] * bfhi(x.z); a[6] += w1[2] * bflo(x.w); a[7] += w1[3] * bfhi(x.w); }
;         const float w = wl[t];
; #pragma unroll
;         for (int j = 0; j < 8; ++j) KT[(c * 8 + j) * 72 + tsw(c * 8, t)] = (bf16_t)(cvt_pk_bf16(a[j] * sigmoidf(a[j]) * w, 0.f) & 0xffffu); }
.LBB0_575:
	v_or_b32_e32 v50, s35, v96
	v_lshlrev_b32_e32 v196, 2, v50
	s_waitcnt lgkmcnt(0)
	v_lshl_add_u64 v[76:77], s[12:13], 0, v[196:197]
	s_movk_i32 s8, 0x1000
	v_add_co_u32_e32 v80, vcc, s8, v76
	s_movk_i32 s8, 0x2000
	s_nop 0
	v_addc_co_u32_e32 v81, vcc, 0, v77, vcc
	v_add_co_u32_e32 v82, vcc, s8, v76
	s_barrier
	v_lshl_add_u64 v[78:79], s[14:15], 0, v[196:197]
	global_load_dwordx4 v[58:61], v[76:77], off offset:2048
	global_load_dwordx4 v[54:57], v[78:79], off offset:2048
	global_load_dwordx4 v[50:53], v[78:79], off offset:2064
	global_load_dwordx4 v[62:65], v[76:77], off offset:2064
	v_addc_co_u32_e32 v83, vcc, 0, v77, vcc
	global_load_dwordx4 v[70:73], v[80:81], off offset:2048
	global_load_dwordx4 v[66:69], v[80:81], off offset:2064
	v_add_co_u32_e32 v84, vcc, s91, v76
	global_load_dwordx4 v[98:101], v[82:83], off offset:2048
	global_load_dwordx4 v[102:105], v[82:83], off offset:2064
	v_addc_co_u32_e32 v85, vcc, 0, v77, vcc
	global_load_dwordx4 v[106:109], v[84:85], off offset:2048
	global_load_dwordx4 v[110:113], v[84:85], off offset:2064
	s_waitcnt vmcnt(0)
	v_lshlrev_b32_e32 v114, 16, v42
	v_lshlrev_b32_e32 v116, 16, v44
	v_and_b32_e32 v44, 0xffff0000, v44
	v_and_b32_e32 v42, 0xffff0000, v42
	v_lshlrev_b32_e32 v117, 16, v45
	v_lshlrev_b32_e32 v118, 16, v38
	v_lshlrev_b32_e32 v120, 16, v40
	v_and_b32_e32 v40, 0xffff0000, v40
	v_lshlrev_b32_e32 v128, 16, v35
	v_and_b32_e32 v129, 0xffff0000, v35
	v_and_b32_e32 v38, 0xffff0000, v38
	v_lshlrev_b32_e32 v121, 16, v41
	v_lshlrev_b32_e32 v122, 16, v46
	v_lshlrev_b32_e32 v124, 16, v48
	v_and_b32_e32 v48, 0xffff0000, v48
	v_lshlrev_b32_e32 v126, 16, v34
	v_and_b32_e32 v127, 0xffff0000, v34
	v_lshlrev_b32_e32 v125, 16, v49
	v_lshlrev_b32_e32 v115, 16, v43
	v_and_b32_e32 v43, 0xffff0000, v43
	v_lshlrev_b32_e32 v119, 16, v39
	v_and_b32_e32 v39, 0xffff0000, v39
	v_and_b32_e32 v45, 0xffff0000, v45
	v_and_b32_e32 v46, 0xffff0000, v46
	v_and_b32_e32 v41, 0xffff0000, v41
	v_and_b32_e32 v49, 0xffff0000, v49
	v_lshlrev_b32_e32 v123, 16, v47
	v_and_b32_e32 v47, 0xffff0000, v47
	s_waitcnt lgkmcnt(0)
	v_fma_f32 v54, v58, v114, v54
	v_fma_f32 v55, v59, v42, v55
	v_fma_f32 v35, v63, v44, v51
	v_fma_f32 v34, v64, v117, v52
	v_fmac_f32_e32 v54, v70, v118
	v_fmac_f32_e32 v35, v67, v40
	v_fmac_f32_e32 v55, v71, v38
	v_fmac_f32_e32 v34, v68, v121
	v_fmac_f32_e32 v54, v98, v122
	v_fmac_f32_e32 v35, v103, v48
	v_lshlrev_b32_e32 v38, 16, v36
	v_and_b32_e32 v36, 0xffff0000, v36
	v_fmac_f32_e32 v34, v104, v125
	v_fmac_f32_e32 v54, v106, v126
	v_fmac_f32_e32 v35, v111, v36
	v_lshlrev_b32_e32 v36, 16, v37
	v_fmac_f32_e32 v34, v112, v36
	v_and_b32_e32 v36, 0xffff0000, v37
	v_mul_f32_e32 v37, 0xbfb8aa3b, v54
	v_exp_f32_e32 v37, v37
	v_fmac_f32_e32 v57, v61, v43
	v_fmac_f32_e32 v57, v73, v39
	v_fmac_f32_e32 v53, v65, v45
	v_add_f32_e32 v37, 1.0, v37
	v_div_scale_f32 v39, s[8:9], v37, v37, 1.0
	v_rcp_f32_e32 v40, v39
	v_fmac_f32_e32 v55, v99, v46
	v_fmac_f32_e32 v55, v107, v127
	v_fmac_f32_e32 v53, v69, v41
	v_fma_f32 v42, -v39, v40, 1.0
	v_fmac_f32_e32 v40, v42, v40
	v_div_scale_f32 v42, vcc, 1.0, v37, 1.0
	v_mul_f32_e32 v44, v42, v40
	v_fma_f32 v45, -v39, v44, v42
	v_fmac_f32_e32 v44, v45, v40
	v_fma_f32 v39, -v39, v44, v42
	v_div_fmas_f32 v39, v39, v40, v44
	v_div_fixup_f32 v37, v39, v37, 1.0
	v_mul_f32_e32 v39, 0xbfb8aa3b, v55
	v_exp_f32_e32 v39, v39
	v_fmac_f32_e32 v53, v105, v49
	v_fmac_f32_e32 v53, v113, v36
	v_lshl_add_u32 v36, v97, 2, v209
	v_fma_f32 v43, v62, v116, v50
	ds_read_b32 v36, v36 offset:55296
	v_fmac_f32_e32 v43, v66, v120
	v_add_f32_e32 v39, 1.0, v39
	v_fmac_f32_e32 v43, v102, v124
	v_div_scale_f32 v40, s[8:9], v39, v39, 1.0
	v_fmac_f32_e32 v43, v110, v38
	v_add_u32_e32 v38, v97, v75
	v_rcp_f32_e32 v44, v40
	v_and_b32_e32 v38, 62, v38
	v_lshrrev_b32_e32 v41, 3, v74
	v_mul_f32_e32 v37, v54, v37
	v_lshl_add_u32 v38, v38, 1, v209
	v_and_b32_e32 v41, 2, v41
	s_waitcnt lgkmcnt(0)
	v_mul_f32_e32 v37, v36, v37
	v_mul_u32_u24_e32 v42, 0x90, v96
	v_cvt_pk_bf16_f32 v37, v37, v197
	v_add3_u32 v38, v38, v41, v42
	ds_write_b16 v38, v37
	v_fma_f32 v37, -v40, v44, 1.0
	v_fma_f32 v56, v60, v115, v56
	v_fmac_f32_e32 v44, v37, v44
	v_div_scale_f32 v37, vcc, 1.0, v39, 1.0
	v_fmac_f32_e32 v56, v72, v119
	v_mul_f32_e32 v41, v37, v44
	v_fmac_f32_e32 v56, v100, v123
	v_fma_f32 v45, -v40, v41, v37
	v_fmac_f32_e32 v56, v108, v128
	v_fmac_f32_e32 v41, v45, v44
	v_fma_f32 v37, -v40, v41, v37
	v_mul_f32_e32 v40, 0xbfb8aa3b, v56
	v_exp_f32_e32 v40, v40
	v_div_fmas_f32 v37, v37, v44, v41
	v_div_fixup_f32 v37, v37, v39, 1.0
	v_mul_f32_e32 v37, v55, v37
	v_add_f32_e32 v39, 1.0, v40
	v_div_scale_f32 v40, s[8:9], v39, v39, 1.0
	v_rcp_f32_e32 v41, v40
	v_mul_f32_e32 v37, v36, v37
	v_cvt_pk_bf16_f32 v37, v37, v197
	ds_write_b16 v38, v37 offset:144
	v_fma_f32 v37, -v40, v41, 1.0
	v_fmac_f32_e32 v41, v37, v41
	v_div_scale_f32 v37, vcc, 1.0, v39, 1.0
	v_mul_f32_e32 v44, v37, v41
	v_fmac_f32_e32 v57, v101, v47
	v_fma_f32 v45, -v40, v44, v37
	v_fmac_f32_e32 v57, v109, v129
	v_fmac_f32_e32 v44, v45, v41
	v_fma_f32 v37, -v40, v44, v37
	v_mul_f32_e32 v40, 0xbfb8aa3b, v57
	v_exp_f32_e32 v40, v40
	v_div_fmas_f32 v37, v37, v41, v44
	v_div_fixup_f32 v37, v37, v39, 1.0
	v_mul_f32_e32 v37, v56, v37
	v_add_f32_e32 v39, 1.0, v40
	v_div_scale_f32 v40, s[8:9], v39, v39, 1.0
	v_rcp_f32_e32 v41, v40
	v_mul_f32_e32 v37, v36, v37
	v_cvt_pk_bf16_f32 v37, v37, v197
	ds_write_b16 v38, v37 offset:288
	v_fma_f32 v37, -v40, v41, 1.0
	v_fmac_f32_e32 v41, v37, v41
	v_div_scale_f32 v37, vcc, 1.0, v39, 1.0
	v_mul_f32_e32 v44, v37, v41
	v_fma_f32 v45, -v40, v44, v37
	v_fmac_f32_e32 v44, v45, v41
	v_fma_f32 v37, -v40, v44, v37
	v_mul_f32_e32 v40, 0xbfb8aa3b, v43
; __device__ __forceinline__ unsigned cvt_pk_bf16(float lo, float hi) { unsigned r; asm volatile("v_cvt_pk_bf16_f32 %0, %1, %2" : "=v"(r) : "v"(lo), "v"(hi)); return r; }
; __device__ __forceinline__ float bflo(unsigned w) { return __uint_as_float(w << 16); }
; __device__ __forceinline__ float bfhi(unsigned w) { return __uint_as_float(w & 0xffff0000u); }
; __device__ __forceinline__ float sigmoidf(float x) { return 1.f / (1.f + __expf(-x)); }
; __device__ __forceinline__ int tsw(int row, int t) { return ((((t >> 1) + 4 * ((row >> 3) & 7)) & 31) << 1) | (t & 1); }
; __device__ __forceinline__ void mlstm_local_unit(const Params& P, int l, int h, int n, char* lds) {
;     ...
;     for (int i = 0; i < 2; ++i) { const int idx = tid + 512 * i, t = idx >> 4, c = idx & 15; const int ch = C_MK + h * 128 + c * 8;
;         const f32x4 b0 = *(const f32x4*)(cb + ch), b1 = *(const f32x4*)(cb + ch + 4);
;         float a[8] = {b0[0], b0[1], b0[2], b0[3], b1[0], b1[1], b1[2], b1[3]};
; #pragma unroll
;         for (int k = 0; k < 4; ++k) { const u32x4 x = kx[i][k];
;             const f32x4 w0 = *(const f32x4*)(cw + k * 1024 + ch), w1 = *(const f32x4*)(cw + k * 1024 + ch + 4);
;             a[0] += w0[0] * bflo(x.x); a[1] += w0[1] * bfhi(x.x); a[2] += w0[2] * bflo(x.y); a[3] += w0[3] * bfhi(x.y);
;             a[4] += w1[0] * bflo(x.z); a[5] += w1[1] * bfhi(x.z); a[6] += w1[2] * bflo(x.w); a[7] += w1[3] * bfhi(x.w); }
;         const float w = wl[t];
; #pragma unroll
;         for (int j = 0; j < 8; ++j) KT[(c * 8 + j) * 72 + tsw(c * 8, t)] = (bf16_t)(cvt_pk_bf16(a[j] * sigmoidf(a[j]) * w, 0.f) & 0xffffu); }
	v_exp_f32_e32 v40, v40
	v_div_fmas_f32 v37, v37, v41, v44
	v_div_fixup_f32 v37, v37, v39, 1.0
	v_mul_f32_e32 v37, v57, v37
	v_add_f32_e32 v39, 1.0, v40
	v_div_scale_f32 v40, s[8:9], v39, v39, 1.0
	v_rcp_f32_e32 v41, v40
	v_mul_f32_e32 v37, v36, v37
	v_cvt_pk_bf16_f32 v37, v37, v197
	ds_write_b16 v38, v37 offset:432
	v_fma_f32 v37, -v40, v41, 1.0
	v_fmac_f32_e32 v41, v37, v41
	v_div_scale_f32 v37, vcc, 1.0, v39, 1.0
	v_mul_f32_e32 v44, v37, v41
	v_fma_f32 v45, -v40, v44, v37
	v_fmac_f32_e32 v44, v45, v41
	v_fma_f32 v37, -v40, v44, v37
	v_mul_f32_e32 v40, 0xbfb8aa3b, v35
	v_exp_f32_e32 v40, v40
	v_div_fmas_f32 v37, v37, v41, v44
	v_div_fixup_f32 v37, v37, v39, 1.0
	v_mul_f32_e32 v37, v43, v37
	v_add_f32_e32 v39, 1.0, v40
	v_div_scale_f32 v40, s[8:9], v39, v39, 1.0
	v_rcp_f32_e32 v41, v40
	v_mul_f32_e32 v37, v36, v37
	v_cvt_pk_bf16_f32 v37, v37, v197
	ds_write_b16 v38, v37 offset:576
	v_fma_f32 v37, -v40, v41, 1.0
	v_fmac_f32_e32 v41, v37, v41
	v_div_scale_f32 v37, vcc, 1.0, v39, 1.0
	v_mul_f32_e32 v43, v37, v41
	v_fma_f32 v44, -v40, v43, v37
	v_fmac_f32_e32 v43, v44, v41
	v_fma_f32 v37, -v40, v43, v37
	v_mul_f32_e32 v40, 0xbfb8aa3b, v34
	v_exp_f32_e32 v40, v40
	v_div_fmas_f32 v37, v37, v41, v43
	v_div_fixup_f32 v37, v37, v39, 1.0
	v_mul_f32_e32 v35, v35, v37
	v_add_f32_e32 v37, 1.0, v40
	v_div_scale_f32 v39, s[8:9], v37, v37, 1.0
	v_rcp_f32_e32 v40, v39
	v_mul_f32_e32 v35, v36, v35
	v_cvt_pk_bf16_f32 v35, v35, v197
	ds_write_b16 v38, v35 offset:720
	v_fma_f32 v35, -v39, v40, 1.0
	v_fmac_f32_e32 v40, v35, v40
	v_div_scale_f32 v35, vcc, 1.0, v37, 1.0
	v_mul_f32_e32 v41, v35, v40
	v_fma_f32 v43, -v39, v41, v35
	v_fmac_f32_e32 v41, v43, v40
	v_fma_f32 v35, -v39, v41, v35
	v_mul_f32_e32 v39, 0xbfb8aa3b, v53
	v_exp_f32_e32 v39, v39
	v_div_fmas_f32 v35, v35, v40, v41
	v_div_fixup_f32 v35, v35, v37, 1.0
	v_mul_f32_e32 v34, v34, v35
	v_add_f32_e32 v35, 1.0, v39
	v_div_scale_f32 v37, s[8:9], v35, v35, 1.0
	v_rcp_f32_e32 v39, v37
	v_mul_f32_e32 v34, v36, v34
	v_cvt_pk_bf16_f32 v34, v34, v197
	ds_write_b16 v38, v34 offset:864
	v_fma_f32 v34, -v37, v39, 1.0
	v_fmac_f32_e32 v39, v34, v39
	v_div_scale_f32 v34, vcc, 1.0, v35, 1.0
	v_mul_f32_e32 v40, v34, v39
	v_fma_f32 v41, -v37, v40, v34
	v_fmac_f32_e32 v40, v41, v39
	v_fma_f32 v34, -v37, v40, v34
	v_div_fmas_f32 v34, v34, v39, v40
	v_div_fixup_f32 v34, v34, v35, 1.0
	v_mul_f32_e32 v34, v53, v34
	v_mul_f32_e32 v34, v36, v34
	v_cvt_pk_bf16_f32 v34, v34, v197
	ds_write_b16 v38, v34 offset:1008
	global_load_dwordx4 v[44:47], v[76:77], off offset:2048
	global_load_dwordx4 v[38:41], v[78:79], off offset:2048
	global_load_dwordx4 v[34:37], v[78:79], off offset:2064
	global_load_dwordx4 v[48:51], v[76:77], off offset:2064
	global_load_dwordx4 v[52:55], v[80:81], off offset:2048
	global_load_dwordx4 v[56:59], v[80:81], off offset:2064
	global_load_dwordx4 v[60:63], v[82:83], off offset:2048
	global_load_dwordx4 v[64:67], v[82:83], off offset:2064
	global_load_dwordx4 v[70:73], v[84:85], off offset:2048
	global_load_dwordx4 v[76:79], v[84:85], off offset:2064
	v_lshlrev_b32_e32 v69, 16, v26
	v_and_b32_e32 v26, 0xffff0000, v26
	v_and_b32_e32 v68, 31, v74
	v_lshrrev_b32_e32 v43, 5, v95
	v_lshlrev_b32_e32 v196, 3, v43
	s_waitcnt vmcnt(0) lgkmcnt(0)
	v_fma_f32 v39, v45, v26, v39
	v_lshlrev_b32_e32 v26, 16, v27
	v_fma_f32 v40, v46, v26, v40
	v_and_b32_e32 v26, 0xffff0000, v27
	v_fmac_f32_e32 v41, v47, v26
	v_lshlrev_b32_e32 v26, 16, v28
	v_fma_f32 v34, v48, v26, v34
	v_and_b32_e32 v26, 0xffff0000, v28
	v_and_b32_e32 v28, 0xffff0000, v29
	v_fmac_f32_e32 v37, v51, v28
	v_lshlrev_b32_e32 v28, 16, v22
	v_and_b32_e32 v22, 0xffff0000, v22
	v_fmac_f32_e32 v39, v53, v22
	v_lshlrev_b32_e32 v22, 16, v23
	v_fmac_f32_e32 v40, v54, v22
	v_and_b32_e32 v22, 0xffff0000, v23
	v_fmac_f32_e32 v41, v55, v22
	v_lshlrev_b32_e32 v22, 16, v24
	v_fma_f32 v27, v49, v26, v35
	v_lshlrev_b32_e32 v26, 16, v29
	v_fmac_f32_e32 v34, v56, v22
	v_and_b32_e32 v22, 0xffff0000, v24
	v_fma_f32 v26, v50, v26, v36
	v_fmac_f32_e32 v27, v57, v22
	v_lshlrev_b32_e32 v22, 16, v25
	v_fma_f32 v38, v44, v69, v38
	v_fmac_f32_e32 v26, v58, v22
	v_and_b32_e32 v22, 0xffff0000, v25
	v_fmac_f32_e32 v38, v52, v28
	v_fmac_f32_e32 v37, v59, v22
	v_lshlrev_b32_e32 v22, 16, v30
	v_fmac_f32_e32 v38, v60, v22
	v_and_b32_e32 v22, 0xffff0000, v30
	v_fmac_f32_e32 v39, v61, v22
	v_lshlrev_b32_e32 v22, 16, v31
	v_fmac_f32_e32 v40, v62, v22
	v_and_b32_e32 v22, 0xffff0000, v31
	v_fmac_f32_e32 v41, v63, v22
	v_lshlrev_b32_e32 v22, 16, v32
	v_fmac_f32_e32 v34, v64, v22
	v_and_b32_e32 v22, 0xffff0000, v32
	v_fmac_f32_e32 v27, v65, v22
	v_lshlrev_b32_e32 v22, 16, v33
	v_fmac_f32_e32 v26, v66, v22
	v_and_b32_e32 v22, 0xffff0000, v33
	v_fmac_f32_e32 v37, v67, v22
	v_lshlrev_b32_e32 v22, 16, v18
	v_and_b32_e32 v18, 0xffff0000, v18
	v_fmac_f32_e32 v38, v70, v22
	v_fmac_f32_e32 v39, v71, v18
	v_lshlrev_b32_e32 v18, 16, v19
	v_fmac_f32_e32 v40, v72, v18
	v_and_b32_e32 v18, 0xffff0000, v19
	v_mul_f32_e32 v19, 0xbfb8aa3b, v38
	v_exp_f32_e32 v19, v19
	v_fmac_f32_e32 v41, v73, v18
	v_lshlrev_b32_e32 v18, 16, v20
	v_fmac_f32_e32 v34, v76, v18
	v_and_b32_e32 v18, 0xffff0000, v20
	v_fmac_f32_e32 v27, v77, v18
	v_lshlrev_b32_e32 v18, 16, v21
	v_add_f32_e32 v19, 1.0, v19
	v_fmac_f32_e32 v26, v78, v18
	v_and_b32_e32 v18, 0xffff0000, v21
	v_div_scale_f32 v21, s[8:9], v19, v19, 1.0
	v_rcp_f32_e32 v22, v21
	v_fmac_f32_e32 v37, v79, v18
	v_lshl_add_u32 v18, v94, 2, v209
	ds_read_b32 v18, v18 offset:55296
	v_fma_f32 v24, -v21, v22, 1.0
	v_fmac_f32_e32 v22, v24, v22
	v_div_scale_f32 v24, vcc, 1.0, v19, 1.0
	v_mul_f32_e32 v25, v24, v22
	v_fma_f32 v28, -v21, v25, v24
	v_fmac_f32_e32 v25, v28, v22
	v_fma_f32 v21, -v21, v25, v24
	v_div_fmas_f32 v21, v21, v22, v25
	v_mul_f32_e32 v22, 0xbfb8aa3b, v39
	v_exp_f32_e32 v22, v22
	v_div_fixup_f32 v19, v21, v19, 1.0
	v_add_u32_e32 v20, v94, v75
	v_and_b32_e32 v20, 62, v20
	v_add_f32_e32 v21, 1.0, v22
	v_div_scale_f32 v22, s[8:9], v21, v21, 1.0
	v_rcp_f32_e32 v24, v22
	v_lshrrev_b32_e32 v23, 3, v86
	v_mul_f32_e32 v19, v38, v19
	v_lshl_add_u32 v20, v20, 1, v209
	v_and_b32_e32 v23, 2, v23
	s_waitcnt lgkmcnt(0)
; __device__ __forceinline__ unsigned cvt_pk_bf16(float lo, float hi) { unsigned r; asm volatile("v_cvt_pk_bf16_f32 %0, %1, %2" : "=v"(r) : "v"(lo), "v"(hi)); return r; }
; __device__ __forceinline__ float sigmoidf(float x) { return 1.f / (1.f + __expf(-x)); }
; __device__ __forceinline__ int tsw(int row, int t) { return ((((t >> 1) + 4 * ((row >> 3) & 7)) & 31) << 1) | (t & 1); }
; __device__ __forceinline__ void mlstm_local_unit(const Params& P, int l, int h, int n, char* lds) {
;     ...
;         const float w = wl[t];
; #pragma unroll
;         for (int j = 0; j < 8; ++j) KT[(c * 8 + j) * 72 + tsw(c * 8, t)] = (bf16_t)(cvt_pk_bf16(a[j] * sigmoidf(a[j]) * w, 0.f) & 0xffffu); }
; #pragma unroll
;     for (int i = 0; i < 4; ++i) { const int idx = tid + 512 * i, t = idx >> 5, c = idx & 31;
;         const u32x4 x = vx[i];
;         bf16_t* vp = VT + (c * 8) * 72 + tsw(c * 8, t);
;         vp[0] = (bf16_t)(x.x & 0xffffu); vp[72] = (bf16_t)(x.x >> 16); vp[144] = (bf16_t)(x.y & 0xffffu); vp[216] = (bf16_t)(x.y >> 16);
;         vp[288] = (bf16_t)(x.z & 0xffffu); vp[360] = (bf16_t)(x.z >> 16); vp[432] = (bf16_t)(x.w & 0xffffu); vp[504] = (bf16_t)(x.w >> 16); }
;     __syncthreads();
	v_mul_f32_e32 v19, v18, v19
	v_cvt_pk_bf16_f32 v19, v19, v197
	v_add3_u32 v20, v20, v23, v42
	ds_write_b16 v20, v19
	v_fma_f32 v19, -v22, v24, 1.0
	v_fmac_f32_e32 v24, v19, v24
	v_div_scale_f32 v19, vcc, 1.0, v21, 1.0
	v_mul_f32_e32 v23, v19, v24
	v_fma_f32 v25, -v22, v23, v19
	v_fmac_f32_e32 v23, v25, v24
	v_fma_f32 v19, -v22, v23, v19
	v_mul_f32_e32 v22, 0xbfb8aa3b, v40
	v_exp_f32_e32 v22, v22
	v_div_fmas_f32 v19, v19, v24, v23
	v_div_fixup_f32 v19, v19, v21, 1.0
	v_mul_f32_e32 v19, v39, v19
	v_add_f32_e32 v21, 1.0, v22
	v_div_scale_f32 v22, s[8:9], v21, v21, 1.0
	v_rcp_f32_e32 v23, v22
	v_mul_f32_e32 v19, v18, v19
	v_cvt_pk_bf16_f32 v19, v19, v197
	ds_write_b16 v20, v19 offset:144
	v_fma_f32 v19, -v22, v23, 1.0
	v_fmac_f32_e32 v23, v19, v23
	v_div_scale_f32 v19, vcc, 1.0, v21, 1.0
	v_mul_f32_e32 v24, v19, v23
	v_fma_f32 v25, -v22, v24, v19
	v_fmac_f32_e32 v24, v25, v23
	v_fma_f32 v19, -v22, v24, v19
	v_mul_f32_e32 v22, 0xbfb8aa3b, v41
	v_exp_f32_e32 v22, v22
	v_div_fmas_f32 v19, v19, v23, v24
	v_div_fixup_f32 v19, v19, v21, 1.0
	v_mul_f32_e32 v19, v40, v19
	v_add_f32_e32 v21, 1.0, v22
	v_div_scale_f32 v22, s[8:9], v21, v21, 1.0
	v_rcp_f32_e32 v23, v22
	v_mul_f32_e32 v19, v18, v19
	v_cvt_pk_bf16_f32 v19, v19, v197
	ds_write_b16 v20, v19 offset:288
	v_fma_f32 v19, -v22, v23, 1.0
	v_fmac_f32_e32 v23, v19, v23
	v_div_scale_f32 v19, vcc, 1.0, v21, 1.0
	v_mul_f32_e32 v24, v19, v23
	v_fma_f32 v25, -v22, v24, v19
	v_fmac_f32_e32 v24, v25, v23
	v_fma_f32 v19, -v22, v24, v19
	v_mul_f32_e32 v22, 0xbfb8aa3b, v34
	v_exp_f32_e32 v22, v22
	v_div_fmas_f32 v19, v19, v23, v24
	v_div_fixup_f32 v19, v19, v21, 1.0
	v_mul_f32_e32 v19, v41, v19
	v_add_f32_e32 v21, 1.0, v22
	v_div_scale_f32 v22, s[8:9], v21, v21, 1.0
	v_rcp_f32_e32 v23, v22
	v_mul_f32_e32 v19, v18, v19
	v_cvt_pk_bf16_f32 v19, v19, v197
	ds_write_b16 v20, v19 offset:432
	v_fma_f32 v19, -v22, v23, 1.0
	v_fmac_f32_e32 v23, v19, v23
	v_div_scale_f32 v19, vcc, 1.0, v21, 1.0
	v_mul_f32_e32 v24, v19, v23
	v_fma_f32 v25, -v22, v24, v19
	v_fmac_f32_e32 v24, v25, v23
	v_fma_f32 v19, -v22, v24, v19
	v_mul_f32_e32 v22, 0xbfb8aa3b, v27
	v_exp_f32_e32 v22, v22
	v_div_fmas_f32 v19, v19, v23, v24
	v_div_fixup_f32 v19, v19, v21, 1.0
	v_mul_f32_e32 v19, v34, v19
	v_add_f32_e32 v21, 1.0, v22
	v_div_scale_f32 v22, s[8:9], v21, v21, 1.0
	v_rcp_f32_e32 v23, v22
	v_mul_f32_e32 v19, v18, v19
	v_cvt_pk_bf16_f32 v19, v19, v197
	ds_write_b16 v20, v19 offset:576
	v_fma_f32 v19, -v22, v23, 1.0
	v_fmac_f32_e32 v23, v19, v23
	v_div_scale_f32 v19, vcc, 1.0, v21, 1.0
	v_mul_f32_e32 v24, v19, v23
	v_fma_f32 v25, -v22, v24, v19
	v_fmac_f32_e32 v24, v25, v23
	v_fma_f32 v19, -v22, v24, v19
	v_mul_f32_e32 v22, 0xbfb8aa3b, v26
	v_exp_f32_e32 v22, v22
	v_div_fmas_f32 v19, v19, v23, v24
	v_div_fixup_f32 v19, v19, v21, 1.0
	v_mul_f32_e32 v19, v27, v19
	v_add_f32_e32 v21, 1.0, v22
	v_div_scale_f32 v22, s[8:9], v21, v21, 1.0
	v_rcp_f32_e32 v23, v22
	v_mul_f32_e32 v19, v18, v19
	v_cvt_pk_bf16_f32 v19, v19, v197
	ds_write_b16 v20, v19 offset:720
	v_fma_f32 v19, -v22, v23, 1.0
	v_fmac_f32_e32 v23, v19, v23
	v_div_scale_f32 v19, vcc, 1.0, v21, 1.0
	v_mul_f32_e32 v24, v19, v23
	v_fma_f32 v25, -v22, v24, v19
	v_fmac_f32_e32 v24, v25, v23
	v_fma_f32 v19, -v22, v24, v19
	v_mul_f32_e32 v22, 0xbfb8aa3b, v37
	v_exp_f32_e32 v22, v22
	v_div_fmas_f32 v19, v19, v23, v24
	v_div_fixup_f32 v19, v19, v21, 1.0
	v_mul_f32_e32 v19, v26, v19
	v_add_f32_e32 v21, 1.0, v22
	v_div_scale_f32 v22, s[8:9], v21, v21, 1.0
	v_rcp_f32_e32 v23, v22
	v_mul_f32_e32 v19, v18, v19
	v_cvt_pk_bf16_f32 v19, v19, v197
	ds_write_b16 v20, v19 offset:864
	v_fma_f32 v19, -v22, v23, 1.0
	v_fmac_f32_e32 v23, v19, v23
	v_div_scale_f32 v19, vcc, 1.0, v21, 1.0
	v_mul_f32_e32 v24, v19, v23
	v_fma_f32 v25, -v22, v24, v19
	v_fmac_f32_e32 v24, v25, v23
	v_fma_f32 v19, -v22, v24, v19
	v_div_fmas_f32 v19, v19, v23, v24
	v_div_fixup_f32 v19, v19, v21, 1.0
	v_mul_f32_e32 v19, v37, v19
	v_mul_f32_e32 v18, v18, v19
	v_add_u32_e32 v19, v93, v75
	v_cvt_pk_bf16_f32 v18, v18, v197
	ds_write_b16 v20, v18 offset:1008
	v_and_b32_e32 v19, 62, v19
	v_lshrrev_b32_e32 v20, 4, v74
	v_mad_u32_u24 v18, v92, s45, v209
	v_lshlrev_b32_e32 v19, 1, v19
	v_and_b32_e32 v20, 2, v20
	v_add3_u32 v19, v18, v19, v20
	ds_write_b16 v19, v14 offset:18432
	ds_write_b16_d16_hi v19, v14 offset:18576
	ds_write_b16 v19, v15 offset:18720
	ds_write_b16_d16_hi v19, v15 offset:18864
	ds_write_b16 v19, v16 offset:19008
	ds_write_b16_d16_hi v19, v16 offset:19152
	ds_write_b16 v19, v17 offset:19296
	ds_write_b16_d16_hi v19, v17 offset:19440
	v_add_u32_e32 v14, v91, v75
	v_and_b32_e32 v14, 62, v14
	v_lshrrev_b32_e32 v15, 4, v86
	v_lshlrev_b32_e32 v14, 1, v14
	v_and_b32_e32 v15, 2, v15
	v_add3_u32 v14, v18, v14, v15
	ds_write_b16 v14, v6 offset:18432
	ds_write_b16_d16_hi v14, v6 offset:18576
	ds_write_b16 v14, v7 offset:18720
	ds_write_b16_d16_hi v14, v7 offset:18864
	ds_write_b16 v14, v8 offset:19008
	ds_write_b16_d16_hi v14, v8 offset:19152
	ds_write_b16 v14, v9 offset:19296
	ds_write_b16_d16_hi v14, v9 offset:19440
	v_add_u32_e32 v6, v90, v75
	v_and_b32_e32 v6, 62, v6
	v_lshrrev_b32_e32 v7, 4, v89
	v_lshlrev_b32_e32 v6, 1, v6
	v_and_b32_e32 v7, 2, v7
	v_add3_u32 v6, v18, v6, v7
	ds_write_b16 v6, v10 offset:18432
	ds_write_b16_d16_hi v6, v10 offset:18576
	ds_write_b16 v6, v11 offset:18720
	ds_write_b16_d16_hi v6, v11 offset:18864
	ds_write_b16 v6, v12 offset:19008
	ds_write_b16_d16_hi v6, v12 offset:19152
	ds_write_b16 v6, v13 offset:19296
	ds_write_b16_d16_hi v6, v13 offset:19440
	v_add_u32_e32 v6, v88, v75
	v_and_b32_e32 v6, 62, v6
	v_lshrrev_b32_e32 v7, 4, v87
	v_lshlrev_b32_e32 v6, 1, v6
	v_and_b32_e32 v7, 2, v7
	s_ashr_i32 s8, s34, 6
	v_add3_u32 v6, v18, v6, v7
	s_and_b32 s17, s8, -4
	s_lshr_b32 s9, s34, 1
	ds_write_b16 v6, v2 offset:18432
	ds_write_b16_d16_hi v6, v2 offset:18576
	ds_write_b16 v6, v3 offset:18720
	ds_write_b16_d16_hi v6, v3 offset:18864
	ds_write_b16 v6, v4 offset:19008
	ds_write_b16_d16_hi v6, v4 offset:19152
	ds_write_b16 v6, v5 offset:19296
	ds_write_b16_d16_hi v6, v5 offset:19440
	s_and_b32 s18, s9, 0x60
	v_lshl_or_b32 v2, s17, 5, v68
	v_or_b32_e32 v66, s18, v68
	v_mul_lo_u32 v2, v2, s45
	v_add_u32_e32 v69, 0x100, v2
	v_add_u32_e32 v2, v66, v196
	v_mad_u32_u24 v67, v66, s45, v209
	v_and_b32_e32 v2, 56, v2
	v_lshl_add_u32 v2, v2, 1, v67
	s_waitcnt lgkmcnt(0)
	s_barrier
; __device__ __forceinline__ int tsw(int row, int t) { return ((((t >> 1) + 4 * ((row >> 3) & 7)) & 31) << 1) | (t & 1); }
; __device__ __forceinline__ void mlstm_local_unit(const Params& P, int l, int h, int n, char* lds) {
;     ...
;     const int db = wid & 3, eb0 = (wid >> 2) * 4;
;     f32x16 acc[4] = {};
; #pragma unroll
;     for (int ks = 0; ks < 4; ++ks) { const bf16x8 A = *(const bf16x8*)(KT + (32 * db + r32) * 72 + tsw(32 * db + r32, 16 * ks + 8 * hi));
; #pragma unroll
;         for (int j = 0; j < 4; ++j) { const bf16x8 B = *(const bf16x8*)(VT + (32 * (eb0 + j) + r32) * 72 + tsw(32 * (eb0 + j) + r32, 16 * ks + 8 * hi));
;             acc[j] = __builtin_amdgcn_mfma_f32_32x32x16_bf16(A, B, acc[j], 0, 0, 0); } }
;     if (tid < 128) { float s = 0.f;
	ds_read_b128 v[2:5], v2
	v_add_u32_e32 v6, v196, v68
	v_and_b32_e32 v6, 56, v6
	v_lshlrev_b32_e32 v10, 1, v6
	v_add_u32_e32 v6, v69, v10
	ds_read_b128 v[6:9], v6 offset:18432
	s_or_b32 s15, s17, 2
	v_lshl_or_b32 v11, s15, 5, v68
	s_or_b32 s16, s17, 1
	v_mul_lo_u32 v11, v11, s45
	v_lshl_or_b32 v75, s16, 5, v68
	v_add_u32_e32 v85, 0x100, v11
	s_waitcnt lgkmcnt(0)
	v_mfma_f32_32x32x16_bf16 v[50:65], v[2:5], v[6:9], 0
	v_mul_lo_u32 v6, v75, s45
	v_add_u32_e32 v10, v85, v10
	v_add_u32_e32 v84, 0x100, v6
	v_add_u32_e32 v6, v75, v196
	ds_read_b128 v[10:13], v10 offset:18432
	v_and_b32_e32 v6, 56, v6
	v_or_b32_e32 v88, 16, v196
	v_lshl_add_u32 v6, v6, 1, v84
	v_add_u32_e32 v80, v75, v88
	ds_read_b128 v[6:9], v6 offset:18432
	v_and_b32_e32 v80, 56, v80
	v_lshl_add_u32 v80, v80, 1, v84
	ds_read_b128 v[80:83], v80 offset:18432
	s_waitcnt lgkmcnt(2)
	v_mfma_f32_32x32x16_bf16 v[18:33], v[2:5], v[10:13], 0
	v_add_u32_e32 v10, v66, v88
	s_or_b32 s14, s8, 3
	v_and_b32_e32 v10, 56, v10
	v_lshl_or_b32 v86, s14, 5, v68
	v_lshl_add_u32 v10, v10, 1, v67
	ds_read_b128 v[70:73], v10
	v_add_u32_e32 v76, v88, v68
	s_waitcnt lgkmcnt(2)
	v_mfma_f32_32x32x16_bf16 v[34:49], v[2:5], v[6:9], 0
	v_mul_lo_u32 v6, v86, s45
	v_add_u32_e32 v87, 0x100, v6
	v_add_u32_e32 v6, v86, v196
	v_and_b32_e32 v6, 56, v6
	v_lshl_add_u32 v6, v6, 1, v87
	v_and_b32_e32 v76, 56, v76
	ds_read_b128 v[6:9], v6 offset:18432
	v_lshlrev_b32_e32 v89, 1, v76
	v_add_u32_e32 v76, v69, v89
	ds_read_b128 v[76:79], v76 offset:18432
	s_waitcnt lgkmcnt(1)
	v_mfma_f32_32x32x16_bf16 v[2:17], v[2:5], v[6:9], 0
	s_movk_i32 s8, 0x7f
	v_cmp_lt_i32_e32 vcc, s8, v74
	v_mfma_f32_32x32x16_bf16 v[34:49], v[70:73], v[80:83], v[34:49]
	v_add_u32_e32 v80, v86, v88
	v_and_b32_e32 v80, 56, v80
	v_lshl_add_u32 v80, v80, 1, v87
	ds_read_b128 v[80:83], v80 offset:18432
	v_or_b32_e32 v88, 32, v196
	s_waitcnt lgkmcnt(1)
	v_mfma_f32_32x32x16_bf16 v[50:65], v[70:73], v[76:79], v[50:65]
	v_add_u32_e32 v76, v85, v89
	ds_read_b128 v[76:79], v76 offset:18432
	s_waitcnt lgkmcnt(0)
	v_mfma_f32_32x32x16_bf16 v[18:33], v[70:73], v[76:79], v[18:33]
	v_add_u32_e32 v76, v88, v68
	v_and_b32_e32 v76, 56, v76
	v_mfma_f32_32x32x16_bf16 v[2:17], v[70:73], v[80:83], v[2:17]
	v_add_u32_e32 v70, v66, v88
	v_and_b32_e32 v70, 56, v70
	v_lshl_add_u32 v70, v70, 1, v67
	ds_read_b128 v[70:73], v70
	v_lshlrev_b32_e32 v80, 1, v76
	v_add_u32_e32 v76, v69, v80
	ds_read_b128 v[76:79], v76 offset:18432
	v_add_u32_e32 v80, v85, v80
	s_waitcnt lgkmcnt(0)
	v_mfma_f32_32x32x16_bf16 v[50:65], v[70:73], v[76:79], v[50:65]
	v_add_u32_e32 v76, v75, v88
	v_and_b32_e32 v76, 56, v76
	v_lshl_add_u32 v76, v76, 1, v84
	ds_read_b128 v[76:79], v76 offset:18432
	ds_read_b128 v[80:83], v80 offset:18432
	s_waitcnt lgkmcnt(1)
	v_mfma_f32_32x32x16_bf16 v[34:49], v[70:73], v[76:79], v[34:49]
	v_add_u32_e32 v76, v86, v88
	v_or_b32_e32 v88, 48, v196
	v_and_b32_e32 v76, 56, v76
	v_add_u32_e32 v66, v66, v88
	v_lshl_add_u32 v76, v76, 1, v87
	v_and_b32_e32 v66, 56, v66
	ds_read_b128 v[76:79], v76 offset:18432
	v_lshl_add_u32 v66, v66, 1, v67
	s_waitcnt lgkmcnt(1)
	v_mfma_f32_32x32x16_bf16 v[18:33], v[70:73], v[80:83], v[18:33]
	ds_read_b128 v[80:83], v66
	v_add_u32_e32 v66, v88, v68
	v_and_b32_e32 v66, 56, v66
	v_lshlrev_b32_e32 v66, 1, v66
	v_add_u32_e32 v67, v69, v66
	v_add_u32_e32 v66, v85, v66
	s_waitcnt lgkmcnt(1)
	v_mfma_f32_32x32x16_bf16 v[2:17], v[70:73], v[76:79], v[2:17]
	ds_read_b128 v[70:73], v67 offset:18432
	v_add_u32_e32 v67, v75, v88
	v_and_b32_e32 v67, 56, v67
	v_lshl_add_u32 v67, v67, 1, v84
	ds_read_b128 v[76:79], v67 offset:18432
	s_waitcnt lgkmcnt(1)
	v_mfma_f32_32x32x16_bf16 v[50:65], v[80:83], v[70:73], v[50:65]
	ds_read_b128 v[70:73], v66 offset:18432
	v_add_u32_e32 v66, v86, v88
	v_and_b32_e32 v66, 56, v66
	v_lshl_add_u32 v66, v66, 1, v87
	s_waitcnt lgkmcnt(1)
	v_mfma_f32_32x32x16_bf16 v[34:49], v[80:83], v[76:79], v[34:49]
	ds_read_b128 v[76:79], v66 offset:18432
	s_waitcnt lgkmcnt(1)
	v_mfma_f32_32x32x16_bf16 v[18:33], v[80:83], v[70:73], v[18:33]
	s_waitcnt lgkmcnt(0)
	v_mfma_f32_32x32x16_bf16 v[2:17], v[80:83], v[76:79], v[2:17]
	s_and_saveexec_b64 s[8:9], vcc
	s_xor_b64 s[8:9], exec, s[8:9]
	s_mul_i32 s12, s30, 0x101
	s_add_i32 s12, s12, s31
	s_ashr_i32 s13, s12, 31
	s_or_saveexec_b64 s[8:9], s[8:9]
	v_mov_b64_e32 v[66:67], s[12:13]
	s_xor_b64 exec, exec, s[8:9]
	s_cbranch_execz .LBB0_550
; __device__ __forceinline__ float bflo(unsigned w) { return __uint_as_float(w << 16); }
; __device__ __forceinline__ float bfhi(unsigned w) { return __uint_as_float(w & 0xffff0000u); }
; __device__ __forceinline__ void mlstm_local_unit(const Params& P, int l, int h, int n, char* lds) {
;     ...
;     if (tid < 128) { float s = 0.f;
; #pragma unroll
;         for (int q = 0; q < 8; ++q) { const u32x4 x = *(const u32x4*)(KT + tid * 72 + 8 * q);
;             s += (bflo(x.x) + bfhi(x.x)) + (bflo(x.y) + bfhi(x.y)) + (bflo(x.z) + bfhi(x.z)) + (bflo(x.w) + bfhi(x.w)); }
;         NLOC[(size_t)(h * NCH + n) * 128 + tid] = s; }
	v_mul_lo_u32 v66, v74, s45
	v_add_u32_e32 v69, 0x100, v66
	ds_read_b128 v[70:73], v69 offset:16
	ds_read_b128 v[76:79], v69
	ds_read_b128 v[80:83], v69 offset:32
	ds_read_b128 v[84:87], v69 offset:48
	s_mul_i32 s12, s30, 0x101
	s_waitcnt lgkmcnt(3)
	v_lshlrev_b32_e32 v67, 16, v70
	s_waitcnt lgkmcnt(2)
	v_lshlrev_b32_e32 v66, 16, v76
	v_and_b32_e32 v89, 0xffff0000, v70
	v_and_b32_e32 v88, 0xffff0000, v76
	v_pk_add_f32 v[66:67], v[66:67], v[88:89]
	v_lshlrev_b32_e32 v89, 16, v71
	v_lshlrev_b32_e32 v88, 16, v77
	v_and_b32_e32 v71, 0xffff0000, v71
	v_and_b32_e32 v70, 0xffff0000, v77
	v_pk_add_f32 v[70:71], v[88:89], v[70:71]
	v_and_b32_e32 v77, 0xffff0000, v72
	v_pk_add_f32 v[66:67], v[66:67], v[70:71]
	v_lshlrev_b32_e32 v71, 16, v72
	v_lshlrev_b32_e32 v70, 16, v78
	v_and_b32_e32 v76, 0xffff0000, v78
	v_pk_add_f32 v[70:71], v[70:71], v[76:77]
	v_and_b32_e32 v72, 0xffff0000, v79
	v_pk_add_f32 v[66:67], v[70:71], v[66:67]
	v_lshlrev_b32_e32 v71, 16, v73
	v_lshlrev_b32_e32 v70, 16, v79
	v_and_b32_e32 v73, 0xffff0000, v73
	v_pk_add_f32 v[70:71], v[70:71], v[72:73]
	s_waitcnt lgkmcnt(1)
	v_and_b32_e32 v73, 0xffff0000, v81
	v_pk_add_f32 v[66:67], v[70:71], v[66:67]
	v_lshlrev_b32_e32 v71, 16, v81
	v_lshlrev_b32_e32 v70, 16, v80
	v_and_b32_e32 v72, 0xffff0000, v80
	v_pk_add_f32 v[70:71], v[70:71], v[72:73]
	v_lshlrev_b32_e32 v73, 16, v83
	v_lshlrev_b32_e32 v72, 16, v82
	v_and_b32_e32 v77, 0xffff0000, v83
	v_and_b32_e32 v76, 0xffff0000, v82
	v_add_f32_e32 v66, 0, v66
	v_pk_add_f32 v[70:71], v[70:71], v[70:71] op_sel:[0,1] op_sel_hi:[1,0]
	v_pk_add_f32 v[80:81], v[72:73], v[76:77]
	v_add_f32_e32 v66, v66, v67
	v_pk_add_f32 v[82:83], v[80:81], v[70:71]
	s_waitcnt lgkmcnt(0)
	v_lshlrev_b32_e32 v67, 16, v84
	v_and_b32_e32 v70, 0xffff0000, v84
	v_add_f32_e32 v84, v67, v70
	ds_read_b128 v[70:73], v69 offset:64
	ds_read_b128 v[76:79], v69 offset:80
	v_lshlrev_b32_e32 v67, 16, v85
	v_and_b32_e32 v75, 0xffff0000, v85
	v_add_f32_e32 v88, v67, v75
	s_waitcnt lgkmcnt(1)
	v_lshlrev_b32_e32 v85, 16, v71
	v_and_b32_e32 v89, 0xffff0000, v71
	v_lshlrev_b32_e32 v91, 16, v70
	v_lshlrev_b32_e32 v90, 16, v86
	v_and_b32_e32 v71, 0xffff0000, v70
	v_and_b32_e32 v70, 0xffff0000, v86
	v_pk_add_f32 v[70:71], v[90:91], v[70:71]
	v_pk_add_f32 v[84:85], v[84:85], v[88:89]
	v_lshlrev_b32_e32 v67, 16, v73
	v_pk_add_f32 v[70:71], v[70:71], v[84:85]
	v_pk_mov_b32 v[84:85], v[86:87], v[72:73] op_sel:[1,0]
	v_and_b32_e32 v75, 0xffff0000, v73
	v_lshlrev_b32_e32 v73, 16, v72
	v_lshlrev_b32_e32 v72, 16, v87
	v_and_b32_e32 v85, 0xffff0000, v85
	v_and_b32_e32 v84, 0xffff0000, v84
	v_pk_add_f32 v[72:73], v[72:73], v[84:85]
	s_add_i32 s12, s12, s31
	v_pk_add_f32 v[70:71], v[72:73], v[70:71]
	v_pk_add_f32 v[72:73], v[80:81], v[82:83] op_sel:[1,0] op_sel_hi:[0,1]
	v_mov_b32_e32 v73, v75
	v_pk_add_f32 v[66:67], v[66:67], v[72:73]
	s_waitcnt lgkmcnt(0)
	v_and_b32_e32 v73, 0xffff0000, v77
	v_pk_add_f32 v[66:67], v[66:67], v[70:71]
	v_lshlrev_b32_e32 v71, 16, v77
	v_lshlrev_b32_e32 v70, 16, v76
	v_and_b32_e32 v72, 0xffff0000, v76
	v_pk_add_f32 v[70:71], v[70:71], v[72:73]
	v_lshlrev_b32_e32 v81, 16, v79
	v_pk_add_f32 v[76:77], v[70:71], v[70:71] op_sel:[0,1] op_sel_hi:[1,0]
	v_lshlrev_b32_e32 v80, 16, v78
	v_and_b32_e32 v79, 0xffff0000, v79
	ds_read_b128 v[70:73], v69 offset:96
	v_and_b32_e32 v78, 0xffff0000, v78
	v_pk_add_f32 v[80:81], v[80:81], v[78:79]
	v_pk_add_f32 v[66:67], v[66:67], v[66:67] op_sel:[0,1] op_sel_hi:[1,0]
	v_pk_add_f32 v[82:83], v[80:81], v[76:77]
	ds_read_b128 v[76:79], v69 offset:112
	s_waitcnt lgkmcnt(1)
	v_lshlrev_b32_e32 v69, 16, v70
	v_and_b32_e32 v70, 0xffff0000, v70
	v_add_f32_e32 v70, v69, v70
	v_lshlrev_b32_e32 v69, 16, v71
	v_and_b32_e32 v71, 0xffff0000, v71
	v_add_f32_e32 v84, v69, v71
	s_waitcnt lgkmcnt(0)
	v_lshlrev_b32_e32 v71, 16, v77
	v_and_b32_e32 v85, 0xffff0000, v77
	v_lshlrev_b32_e32 v87, 16, v76
	v_lshlrev_b32_e32 v86, 16, v72
	v_and_b32_e32 v77, 0xffff0000, v76
	v_and_b32_e32 v76, 0xffff0000, v72
	v_pk_add_f32 v[76:77], v[86:87], v[76:77]
	v_pk_add_f32 v[70:71], v[70:71], v[84:85]
	v_lshlrev_b32_e32 v69, 16, v79
	v_pk_add_f32 v[70:71], v[76:77], v[70:71]
	v_pk_mov_b32 v[76:77], v[72:73], v[78:79] op_sel:[1,0]
	v_and_b32_e32 v75, 0xffff0000, v79
	v_lshlrev_b32_e32 v79, 16, v78
	v_lshlrev_b32_e32 v78, 16, v73
	v_and_b32_e32 v73, 0xffff0000, v77
	v_and_b32_e32 v72, 0xffff0000, v76
	v_pk_add_f32 v[72:73], v[78:79], v[72:73]
	s_ashr_i32 s13, s12, 31
	v_pk_add_f32 v[70:71], v[72:73], v[70:71]
	v_pk_add_f32 v[72:73], v[80:81], v[82:83] op_sel:[1,0] op_sel_hi:[0,1]
	v_mov_b32_e32 v67, v69
	v_mov_b32_e32 v73, v75
	s_lshl_b64 s[30:31], s[12:13], 9
	v_pk_add_f32 v[66:67], v[66:67], v[72:73]
	s_add_u32 s30, s62, s30
	v_pk_add_f32 v[66:67], v[66:67], v[70:71]
	v_ashrrev_i32_e32 v75, 31, v74
	s_addc_u32 s31, s63, s31
	v_add_f32_e32 v69, v66, v67
	v_lshl_add_u64 v[66:67], v[74:75], 2, s[30:31]
	v_add_co_u32_e32 v66, vcc, 0x100000, v66
	s_nop 1
	v_addc_co_u32_e32 v67, vcc, 0, v67, vcc
	flat_store_dword v[66:67], v69
	v_mov_b64_e32 v[66:67], s[12:13]
	s_branch .LBB0_550

; #define PACK_CARRY() (u32x4){cvt_pk_bf16(c0, c1), cvt_pk_bf16(c2, c3), cvt_pk_bf16(c4, c5), cvt_pk_bf16(c6, c7)}
; __device__ __forceinline__ void mlstm_scan_item(const Params& P, int item) {
;     ...
;     for (int n0 = 0; n0 < 256; n0 += 16) {
;         u32x4 cl[16]; float nl[16];
; #pragma unroll
;         for (int j = 0; j < 16; ++j) cl[j] = *(const u32x4*)(p + (size_t)(n0 + j) * 32768);
;         if (hasn) {
; #pragma unroll
;             for (int j = 0; j < 16; ++j) nl[j] = np[(size_t)(n0 + j) * 128];
;         } else {
; #pragma unroll
;             for (int j = 0; j < 16; ++j) nl[j] = 0.f;
;         }
; #pragma unroll
;         for (int j = 0; j < 16; ++j) { const int n = n0 + j; const float g = GM[n * 2], ml = GM[n * 2 + 1];
;             *(u32x4*)(p + (size_t)n * 32768) = PACK_CARRY();
;             if (hasn) np[(size_t)n * 128] = ncar;
.LBB0_604:
	s_waitcnt lgkmcnt(0)
	v_lshl_add_u64 v[76:77], s[10:11], 0, v[72:73]
	s_mov_b32 s3, 0x1ae00000
	v_add_co_u32_e32 v2, vcc, s3, v76
	s_mov_b32 s3, 0x1ae10000
	s_nop 0
	v_addc_co_u32_e32 v3, vcc, 0, v77, vcc
	v_add_co_u32_e32 v4, vcc, s3, v76
	s_mov_b32 s3, 0x1ae20000
	s_nop 0
	v_addc_co_u32_e32 v5, vcc, 0, v77, vcc
	global_load_dwordx4 v[62:65], v[2:3], off
	global_load_dwordx4 v[58:61], v[4:5], off
	v_add_co_u32_e32 v2, vcc, s3, v76
	s_mov_b32 s3, 0x1ae30000
	s_nop 0
	v_addc_co_u32_e32 v3, vcc, 0, v77, vcc
	v_add_co_u32_e32 v4, vcc, s3, v76
	s_mov_b32 s3, 0x1ae40000
	s_nop 0
	v_addc_co_u32_e32 v5, vcc, 0, v77, vcc
	global_load_dwordx4 v[54:57], v[2:3], off
	global_load_dwordx4 v[50:53], v[4:5], off
	v_add_co_u32_e32 v2, vcc, s3, v76
	s_mov_b32 s3, 0x1ae50000
	s_nop 0
	v_addc_co_u32_e32 v3, vcc, 0, v77, vcc
	v_add_co_u32_e32 v4, vcc, s3, v76
	s_mov_b32 s3, 0x1ae60000
	s_nop 0
	v_addc_co_u32_e32 v5, vcc, 0, v77, vcc
	global_load_dwordx4 v[46:49], v[2:3], off
	global_load_dwordx4 v[42:45], v[4:5], off
	v_add_co_u32_e32 v2, vcc, s3, v76
	s_mov_b32 s3, 0x1ae70000
	s_nop 0
	v_addc_co_u32_e32 v3, vcc, 0, v77, vcc
	v_add_co_u32_e32 v4, vcc, s3, v76
	s_mov_b32 s3, 0x1ae80000
	s_nop 0
	v_addc_co_u32_e32 v5, vcc, 0, v77, vcc
	global_load_dwordx4 v[38:41], v[2:3], off
	global_load_dwordx4 v[34:37], v[4:5], off
	v_add_co_u32_e32 v2, vcc, s3, v76
	s_mov_b32 s3, 0x1ae90000
	s_nop 0
	v_addc_co_u32_e32 v3, vcc, 0, v77, vcc
	v_add_co_u32_e32 v4, vcc, s3, v76
	s_mov_b32 s3, 0x1aea0000
	s_nop 0
	v_addc_co_u32_e32 v5, vcc, 0, v77, vcc
	global_load_dwordx4 v[30:33], v[2:3], off
	global_load_dwordx4 v[26:29], v[4:5], off
	v_add_co_u32_e32 v2, vcc, s3, v76
	s_mov_b32 s3, 0x1aeb0000
	s_nop 0
	v_addc_co_u32_e32 v3, vcc, 0, v77, vcc
	v_add_co_u32_e32 v4, vcc, s3, v76
	s_mov_b32 s3, 0x1aec0000
	s_nop 0
	v_addc_co_u32_e32 v5, vcc, 0, v77, vcc
	global_load_dwordx4 v[22:25], v[2:3], off
	global_load_dwordx4 v[18:21], v[4:5], off
	v_add_co_u32_e32 v2, vcc, s3, v76
	v_lshl_add_u64 v[80:81], s[10:11], 0, v[70:71]
	s_nop 0
	v_addc_co_u32_e32 v3, vcc, 0, v77, vcc
	v_add_co_u32_e32 v4, vcc, 0x1aed0000, v76
	v_mov_b32_e32 v79, 0
	s_nop 0
	v_addc_co_u32_e32 v5, vcc, 0, v77, vcc
	global_load_dwordx4 v[14:17], v[2:3], off
	global_load_dwordx4 v[10:13], v[4:5], off
	v_add_co_u32_e32 v2, vcc, 0x1aee0000, v76
	v_mov_b32_e32 v78, 0
	s_nop 0
	v_addc_co_u32_e32 v3, vcc, 0, v77, vcc
	v_add_co_u32_e32 v4, vcc, 0x1aef0000, v76
	v_mov_b32_e32 v104, 0
	s_nop 0
	v_addc_co_u32_e32 v5, vcc, 0, v77, vcc
	global_load_dwordx4 v[6:9], v[2:3], off
	s_nop 0
	global_load_dwordx4 v[2:5], v[4:5], off
	v_mov_b32_e32 v105, 0
	v_mov_b32_e32 v106, 0
	v_mov_b32_e32 v107, 0
	v_mov_b32_e32 v108, 0
	v_mov_b32_e32 v109, 0
	v_mov_b32_e32 v110, 0
	v_mov_b32_e32 v111, 0
	v_mov_b32_e32 v112, 0
	v_mov_b32_e32 v113, 0
	v_mov_b32_e32 v114, 0
	v_mov_b32_e32 v115, 0
	v_mov_b32_e32 v116, 0
	v_mov_b32_e32 v118, 0
	s_and_saveexec_b64 s[18:19], s[14:15]
	s_cbranch_execz .LBB0_606
	v_add_co_u32_e32 v78, vcc, 0x100000, v80
	s_nop 1
	v_addc_co_u32_e32 v79, vcc, 0, v81, vcc
	v_add_co_u32_e32 v82, vcc, 0x101000, v80
	flat_load_dword v118, v[78:79]
	flat_load_dword v116, v[78:79] offset:512
	flat_load_dword v115, v[78:79] offset:1024
	flat_load_dword v114, v[78:79] offset:1536
	flat_load_dword v113, v[78:79] offset:2048
	flat_load_dword v112, v[78:79] offset:2560
	flat_load_dword v111, v[78:79] offset:3072
	flat_load_dword v110, v[78:79] offset:3584
	v_addc_co_u32_e32 v83, vcc, 0, v81, vcc
	flat_load_dword v109, v[82:83]
	flat_load_dword v108, v[82:83] offset:512
	flat_load_dword v107, v[82:83] offset:1024
	flat_load_dword v106, v[82:83] offset:1536
	flat_load_dword v105, v[82:83] offset:2048
	flat_load_dword v104, v[82:83] offset:2560
	flat_load_dword v78, v[82:83] offset:3072
	flat_load_dword v79, v[82:83] offset:3584
.LBB0_606:
	s_or_b64 exec, exec, s[18:19]
	v_lshl_add_u64 v[84:85], s[10:11], 0, v[74:75]
	s_mov_b32 s3, 0x60000
	v_add_co_u32_e32 v82, vcc, s3, v84
	v_lshl_add_u64 v[96:97], v[76:77], 0, s[50:51]
	s_nop 0
	v_addc_co_u32_e32 v83, vcc, 0, v85, vcc
	global_load_dwordx2 v[94:95], v[82:83], off
	global_load_dwordx2 v[214:215], v[82:83], off offset:8
	global_load_dwordx2 v[216:217], v[82:83], off offset:16
	global_load_dwordx2 v[218:219], v[82:83], off offset:24
	global_load_dwordx2 v[220:221], v[82:83], off offset:32
	global_load_dwordx2 v[222:223], v[82:83], off offset:40
	global_load_dwordx2 v[224:225], v[82:83], off offset:48
	global_load_dwordx2 v[226:227], v[82:83], off offset:56
	global_load_dwordx2 v[228:229], v[82:83], off offset:64
	global_load_dwordx2 v[230:231], v[82:83], off offset:72
	global_load_dwordx2 v[232:233], v[82:83], off offset:80
	global_load_dwordx2 v[234:235], v[82:83], off offset:88
	global_load_dwordx2 v[236:237], v[82:83], off offset:96
	global_load_dwordx2 v[238:239], v[82:83], off offset:104
	global_load_dwordx2 v[240:241], v[82:83], off offset:112
	global_load_dwordx2 v[242:243], v[82:83], off offset:120
	v_cvt_pk_bf16_f32 v100, v92, v93
	v_cvt_pk_bf16_f32 v101, v90, v91
	v_cvt_pk_bf16_f32 v102, v88, v89
	v_cvt_pk_bf16_f32 v103, v86, v87
	global_store_dwordx4 v[96:97], v[100:103], off
	s_and_saveexec_b64 s[18:19], s[14:15]
	s_cbranch_execz .LBB0_608
	v_add_co_u32_e32 v96, vcc, 0x100000, v80
	s_nop 1
	v_addc_co_u32_e32 v97, vcc, 0, v81, vcc
	flat_store_dword v[96:97], v117

; __device__ __forceinline__ float bflo(unsigned w) { return __uint_as_float(w << 16); }
; __device__ __forceinline__ float bfhi(unsigned w) { return __uint_as_float(w & 0xffff0000u); }
; #define PACK_CARRY() (u32x4){cvt_pk_bf16(c0, c1), cvt_pk_bf16(c2, c3), cvt_pk_bf16(c4, c5), cvt_pk_bf16(c6, c7)}
; __device__ __forceinline__ void mlstm_scan_item(const Params& P, int item) {
;     ...
;         for (int j = 0; j < 16; ++j) { const int n = n0 + j; const float g = GM[n * 2], ml = GM[n * 2 + 1];
;             *(u32x4*)(p + (size_t)n * 32768) = PACK_CARRY();
;             if (hasn) np[(size_t)n * 128] = ncar;
;             if (wm) MPREV[n] = m;
;             const float mn = fmaxf(g + m, ml), sp = __expf(g + m - mn), sq = __expf(ml - mn);
;             c0 = sp * c0 + sq * bflo(cl[j].x); c1 = sp * c1 + sq * bfhi(cl[j].x); c2 = sp * c2 + sq * bflo(cl[j].y); c3 = sp * c3 + sq * bfhi(cl[j].y);
;             c4 = sp * c4 + sq * bflo(cl[j].z); c5 = sp * c5 + sq * bfhi(cl[j].z); c6 = sp * c6 + sq * bflo(cl[j].w); c7 = sp * c7 + sq * bfhi(cl[j].w);
;             ncar = sp * ncar + sq * nl[j]; m = mn; }
.LBB0_610:
	s_or_b64 exec, exec, s[18:19]
	v_add_co_u32_e32 v96, vcc, 0x60000, v84
	s_waitcnt vmcnt(0) lgkmcnt(0)
	v_add_f32_e32 v94, v98, v94
	v_addc_co_u32_e32 v97, vcc, 0, v85, vcc
	v_mov_b32_e32 v96, v214
	v_mov_b32_e32 v97, v215
	v_max_f32_e32 v98, v95, v95
	v_max_f32_e32 v119, v94, v98
	v_sub_f32_e32 v95, v95, v119
	v_sub_f32_e32 v94, v94, v119
	v_mul_f32_e32 v95, 0x3fb8aa3b, v95
	v_mul_f32_e32 v94, 0x3fb8aa3b, v94
	v_exp_f32_e32 v123, v95
	v_exp_f32_e32 v124, v94
	v_lshlrev_b32_e32 v125, 16, v62
	v_mov_b32_e32 v122, v92
	v_mul_f32_e32 v92, v123, v125
	v_pk_fma_f32 v[94:95], v[122:123], v[124:125], v[92:93] op_sel_hi:[1,1,0]
	v_and_b32_e32 v125, 0xffff0000, v62
	v_mov_b32_e32 v122, v93
	v_mul_f32_e32 v62, v123, v125
	v_pk_fma_f32 v[102:103], v[122:123], v[124:125], v[62:63] op_sel_hi:[1,1,0]
	v_lshlrev_b32_e32 v125, 16, v63
	v_mov_b32_e32 v122, v90
	v_mul_f32_e32 v62, v123, v125
	v_pk_fma_f32 v[100:101], v[122:123], v[124:125], v[62:63] op_sel_hi:[1,1,0]
	v_and_b32_e32 v125, 0xffff0000, v63
	v_mov_b32_e32 v122, v91
	v_mul_f32_e32 v62, v123, v125
	v_pk_fma_f32 v[98:99], v[122:123], v[124:125], v[62:63] op_sel_hi:[1,1,0]
	v_lshlrev_b32_e32 v125, 16, v64
	v_mov_b32_e32 v122, v88
	v_mul_f32_e32 v62, v123, v125
	v_pk_fma_f32 v[92:93], v[122:123], v[124:125], v[62:63] op_sel_hi:[1,1,0]
	v_and_b32_e32 v125, 0xffff0000, v64
	v_mov_b32_e32 v122, v89
	v_mul_f32_e32 v62, v123, v125
	v_pk_fma_f32 v[90:91], v[122:123], v[124:125], v[62:63] op_sel_hi:[1,1,0]
	v_lshlrev_b32_e32 v125, 16, v65
	v_mov_b32_e32 v122, v86
	v_mul_f32_e32 v62, v123, v125
	v_pk_fma_f32 v[88:89], v[122:123], v[124:125], v[62:63] op_sel_hi:[1,1,0]
	v_and_b32_e32 v125, 0xffff0000, v65
	s_mov_b64 s[18:19], 0x1ae10000
	v_mov_b32_e32 v122, v87
	v_mul_f32_e32 v62, v123, v125
	v_mul_f32_e32 v118, v118, v123
	v_lshl_add_u64 v[120:121], v[76:77], 0, s[18:19]
	v_pk_fma_f32 v[86:87], v[122:123], v[124:125], v[62:63] op_sel_hi:[1,1,0]
	v_fmac_f32_e32 v118, v117, v124
	v_cvt_pk_bf16_f32 v62, v94, v102
	v_cvt_pk_bf16_f32 v63, v100, v98
	v_cvt_pk_bf16_f32 v64, v92, v90
	v_cvt_pk_bf16_f32 v65, v88, v86
	global_store_dwordx4 v[120:121], v[62:65], off
	s_and_saveexec_b64 s[18:19], s[14:15]
	s_cbranch_execz .LBB0_612
	v_add_co_u32_e32 v62, vcc, 0x100000, v80
	s_nop 1
	v_addc_co_u32_e32 v63, vcc, 0, v81, vcc
	flat_store_dword v[62:63], v118 offset:512

; __device__ __forceinline__ float bflo(unsigned w) { return __uint_as_float(w << 16); }
; __device__ __forceinline__ float bfhi(unsigned w) { return __uint_as_float(w & 0xffff0000u); }
; #define PACK_CARRY() (u32x4){cvt_pk_bf16(c0, c1), cvt_pk_bf16(c2, c3), cvt_pk_bf16(c4, c5), cvt_pk_bf16(c6, c7)}
; __device__ __forceinline__ void mlstm_scan_item(const Params& P, int item) {
;     ...
;         for (int j = 0; j < 16; ++j) { const int n = n0 + j; const float g = GM[n * 2], ml = GM[n * 2 + 1];
;             *(u32x4*)(p + (size_t)n * 32768) = PACK_CARRY();
;             if (hasn) np[(size_t)n * 128] = ncar;
;             if (wm) MPREV[n] = m;
;             const float mn = fmaxf(g + m, ml), sp = __expf(g + m - mn), sq = __expf(ml - mn);
;             c0 = sp * c0 + sq * bflo(cl[j].x); c1 = sp * c1 + sq * bfhi(cl[j].x); c2 = sp * c2 + sq * bflo(cl[j].y); c3 = sp * c3 + sq * bfhi(cl[j].y);
;             c4 = sp * c4 + sq * bflo(cl[j].z); c5 = sp * c5 + sq * bfhi(cl[j].z); c6 = sp * c6 + sq * bflo(cl[j].w); c7 = sp * c7 + sq * bfhi(cl[j].w);
;             ncar = sp * ncar + sq * nl[j]; m = mn; }
.LBB0_614:
	s_or_b64 exec, exec, s[18:19]
	v_add_co_u32_e32 v62, vcc, 0x60000, v84
	v_lshlrev_b32_e32 v121, 16, v58
	s_nop 0
	v_addc_co_u32_e32 v63, vcc, 0, v85, vcc
	v_mov_b32_e32 v64, v216
	v_mov_b32_e32 v65, v217
	v_add_f32_e32 v62, v119, v96
	v_max_f32_e32 v63, v97, v97
	v_max_f32_e32 v117, v62, v63
	v_sub_f32_e32 v63, v97, v117
	v_sub_f32_e32 v62, v62, v117
	v_mul_f32_e32 v63, 0x3fb8aa3b, v63
	v_mul_f32_e32 v62, 0x3fb8aa3b, v62
	v_exp_f32_e32 v95, v63
	v_exp_f32_e32 v120, v62
	s_mov_b64 s[18:19], 0x1ae20000
	v_lshl_add_u64 v[122:123], v[76:77], 0, s[18:19]
	v_mul_f32_e32 v62, v95, v121
	v_pk_fma_f32 v[62:63], v[94:95], v[120:121], v[62:63] op_sel_hi:[1,1,0]
	v_and_b32_e32 v121, 0xffff0000, v58
	v_mov_b32_e32 v103, v95
	v_mul_f32_e32 v58, v95, v121
	v_pk_fma_f32 v[102:103], v[102:103], v[120:121], v[58:59] op_sel_hi:[1,1,0]
	v_lshlrev_b32_e32 v121, 16, v59
	v_mov_b32_e32 v101, v95
	v_mul_f32_e32 v58, v95, v121
	v_pk_fma_f32 v[100:101], v[100:101], v[120:121], v[58:59] op_sel_hi:[1,1,0]
	v_and_b32_e32 v121, 0xffff0000, v59
	v_mov_b32_e32 v99, v95
	v_mul_f32_e32 v58, v95, v121
	v_pk_fma_f32 v[96:97], v[98:99], v[120:121], v[58:59] op_sel_hi:[1,1,0]
	v_lshlrev_b32_e32 v121, 16, v60
	v_mov_b32_e32 v93, v95
	v_mul_f32_e32 v58, v95, v121
	v_pk_fma_f32 v[98:99], v[92:93], v[120:121], v[58:59] op_sel_hi:[1,1,0]
	v_and_b32_e32 v121, 0xffff0000, v60
	v_mov_b32_e32 v91, v95
	v_mul_f32_e32 v58, v95, v121
	v_pk_fma_f32 v[92:93], v[90:91], v[120:121], v[58:59] op_sel_hi:[1,1,0]
	v_lshlrev_b32_e32 v121, 16, v61
	v_mov_b32_e32 v89, v95
	v_mul_f32_e32 v58, v95, v121
	v_pk_fma_f32 v[90:91], v[88:89], v[120:121], v[58:59] op_sel_hi:[1,1,0]
	v_and_b32_e32 v121, 0xffff0000, v61
	v_mov_b32_e32 v87, v95
	v_mul_f32_e32 v58, v95, v121
	v_mul_f32_e32 v116, v116, v95
	v_pk_fma_f32 v[86:87], v[86:87], v[120:121], v[58:59] op_sel_hi:[1,1,0]
	v_fmac_f32_e32 v116, v118, v120
	v_cvt_pk_bf16_f32 v58, v62, v102
	v_cvt_pk_bf16_f32 v59, v100, v96
	v_cvt_pk_bf16_f32 v60, v98, v92
	v_cvt_pk_bf16_f32 v61, v90, v86
	global_store_dwordx4 v[122:123], v[58:61], off
	s_and_saveexec_b64 s[18:19], s[14:15]
	s_cbranch_execz .LBB0_616
	v_add_co_u32_e32 v58, vcc, 0x100000, v80
	s_nop 1
	v_addc_co_u32_e32 v59, vcc, 0, v81, vcc
	flat_store_dword v[58:59], v116 offset:1024

; __device__ __forceinline__ float bflo(unsigned w) { return __uint_as_float(w << 16); }
; __device__ __forceinline__ float bfhi(unsigned w) { return __uint_as_float(w & 0xffff0000u); }
; #define PACK_CARRY() (u32x4){cvt_pk_bf16(c0, c1), cvt_pk_bf16(c2, c3), cvt_pk_bf16(c4, c5), cvt_pk_bf16(c6, c7)}
; __device__ __forceinline__ void mlstm_scan_item(const Params& P, int item) {
;     ...
;         for (int j = 0; j < 16; ++j) { const int n = n0 + j; const float g = GM[n * 2], ml = GM[n * 2 + 1];
;             *(u32x4*)(p + (size_t)n * 32768) = PACK_CARRY();
;             if (hasn) np[(size_t)n * 128] = ncar;
;             if (wm) MPREV[n] = m;
;             const float mn = fmaxf(g + m, ml), sp = __expf(g + m - mn), sq = __expf(ml - mn);
;             c0 = sp * c0 + sq * bflo(cl[j].x); c1 = sp * c1 + sq * bfhi(cl[j].x); c2 = sp * c2 + sq * bflo(cl[j].y); c3 = sp * c3 + sq * bfhi(cl[j].y);
;             c4 = sp * c4 + sq * bflo(cl[j].z); c5 = sp * c5 + sq * bfhi(cl[j].z); c6 = sp * c6 + sq * bflo(cl[j].w); c7 = sp * c7 + sq * bfhi(cl[j].w);
;             ncar = sp * ncar + sq * nl[j]; m = mn; }
.LBB0_618:
	s_or_b64 exec, exec, s[18:19]
	v_add_co_u32_e32 v58, vcc, 0x60000, v84
	v_lshlrev_b32_e32 v119, 16, v54
	s_nop 0
	v_addc_co_u32_e32 v59, vcc, 0, v85, vcc
	v_mov_b32_e32 v60, v218
	v_mov_b32_e32 v61, v219
	v_add_f32_e32 v58, v117, v64
	v_max_f32_e32 v59, v65, v65
	v_max_f32_e32 v117, v58, v59
	v_sub_f32_e32 v59, v65, v117
	v_sub_f32_e32 v58, v58, v117
	v_mul_f32_e32 v59, 0x3fb8aa3b, v59
	v_mul_f32_e32 v58, 0x3fb8aa3b, v58
	v_exp_f32_e32 v63, v59
	v_exp_f32_e32 v118, v58
	s_mov_b64 s[18:19], 0x1ae30000
	v_lshl_add_u64 v[120:121], v[76:77], 0, s[18:19]
	v_mul_f32_e32 v58, v63, v119
	v_pk_fma_f32 v[58:59], v[62:63], v[118:119], v[58:59] op_sel_hi:[1,1,0]
	v_and_b32_e32 v119, 0xffff0000, v54
	v_mov_b32_e32 v103, v63
	v_mul_f32_e32 v54, v63, v119
	v_pk_fma_f32 v[88:89], v[102:103], v[118:119], v[54:55] op_sel_hi:[1,1,0]
	v_lshlrev_b32_e32 v119, 16, v55
	v_mov_b32_e32 v101, v63
	v_mul_f32_e32 v54, v63, v119
	v_pk_fma_f32 v[64:65], v[100:101], v[118:119], v[54:55] op_sel_hi:[1,1,0]
	v_and_b32_e32 v119, 0xffff0000, v55
	v_mov_b32_e32 v97, v63
	v_mul_f32_e32 v54, v63, v119
	v_pk_fma_f32 v[96:97], v[96:97], v[118:119], v[54:55] op_sel_hi:[1,1,0]
	v_lshlrev_b32_e32 v119, 16, v56
	v_mov_b32_e32 v99, v63
	v_mul_f32_e32 v54, v63, v119
	v_pk_fma_f32 v[94:95], v[98:99], v[118:119], v[54:55] op_sel_hi:[1,1,0]
	v_and_b32_e32 v119, 0xffff0000, v56
	v_mov_b32_e32 v93, v63
	v_mul_f32_e32 v54, v63, v119
	v_pk_fma_f32 v[92:93], v[92:93], v[118:119], v[54:55] op_sel_hi:[1,1,0]
	v_lshlrev_b32_e32 v119, 16, v57
	v_mov_b32_e32 v91, v63
	v_mul_f32_e32 v54, v63, v119
	v_pk_fma_f32 v[90:91], v[90:91], v[118:119], v[54:55] op_sel_hi:[1,1,0]
	v_and_b32_e32 v119, 0xffff0000, v57
	v_mov_b32_e32 v87, v63
	v_mul_f32_e32 v54, v63, v119
	v_mul_f32_e32 v98, v115, v63
	v_pk_fma_f32 v[86:87], v[86:87], v[118:119], v[54:55] op_sel_hi:[1,1,0]
	v_fmac_f32_e32 v98, v116, v118
	v_cvt_pk_bf16_f32 v54, v58, v88
	v_cvt_pk_bf16_f32 v55, v64, v96
	v_cvt_pk_bf16_f32 v56, v94, v92
	v_cvt_pk_bf16_f32 v57, v90, v86
	global_store_dwordx4 v[120:121], v[54:57], off
	s_and_saveexec_b64 s[18:19], s[14:15]
	s_cbranch_execz .LBB0_620
	v_add_co_u32_e32 v54, vcc, 0x100000, v80
	s_nop 1
	v_addc_co_u32_e32 v55, vcc, 0, v81, vcc
	flat_store_dword v[54:55], v98 offset:1536

; __device__ __forceinline__ float bflo(unsigned w) { return __uint_as_float(w << 16); }
; __device__ __forceinline__ float bfhi(unsigned w) { return __uint_as_float(w & 0xffff0000u); }
; #define PACK_CARRY() (u32x4){cvt_pk_bf16(c0, c1), cvt_pk_bf16(c2, c3), cvt_pk_bf16(c4, c5), cvt_pk_bf16(c6, c7)}
; __device__ __forceinline__ void mlstm_scan_item(const Params& P, int item) {
;     ...
;         for (int j = 0; j < 16; ++j) { const int n = n0 + j; const float g = GM[n * 2], ml = GM[n * 2 + 1];
;             *(u32x4*)(p + (size_t)n * 32768) = PACK_CARRY();
;             if (hasn) np[(size_t)n * 128] = ncar;
;             if (wm) MPREV[n] = m;
;             const float mn = fmaxf(g + m, ml), sp = __expf(g + m - mn), sq = __expf(ml - mn);
;             c0 = sp * c0 + sq * bflo(cl[j].x); c1 = sp * c1 + sq * bfhi(cl[j].x); c2 = sp * c2 + sq * bflo(cl[j].y); c3 = sp * c3 + sq * bfhi(cl[j].y);
;             c4 = sp * c4 + sq * bflo(cl[j].z); c5 = sp * c5 + sq * bfhi(cl[j].z); c6 = sp * c6 + sq * bflo(cl[j].w); c7 = sp * c7 + sq * bfhi(cl[j].w);
;             ncar = sp * ncar + sq * nl[j]; m = mn; }
.LBB0_622:
	s_or_b64 exec, exec, s[18:19]
	v_add_co_u32_e32 v54, vcc, 0x60000, v84
	v_lshlrev_b32_e32 v101, 16, v50
	s_nop 0
	v_addc_co_u32_e32 v55, vcc, 0, v85, vcc
	v_mov_b32_e32 v56, v220
	v_mov_b32_e32 v57, v221
	v_add_f32_e32 v54, v117, v60
	v_max_f32_e32 v55, v61, v61
	v_max_f32_e32 v99, v54, v55
	v_sub_f32_e32 v55, v61, v99
	v_sub_f32_e32 v54, v54, v99
	v_mul_f32_e32 v55, 0x3fb8aa3b, v55
	v_mul_f32_e32 v54, 0x3fb8aa3b, v54
	v_exp_f32_e32 v59, v55
	v_exp_f32_e32 v100, v54
	s_mov_b64 s[18:19], 0x1ae40000
	v_lshl_add_u64 v[102:103], v[76:77], 0, s[18:19]
	v_mul_f32_e32 v54, v59, v101
	v_pk_fma_f32 v[54:55], v[58:59], v[100:101], v[54:55] op_sel_hi:[1,1,0]
	v_and_b32_e32 v101, 0xffff0000, v50
	v_mov_b32_e32 v89, v59
	v_mul_f32_e32 v50, v59, v101
	v_pk_fma_f32 v[88:89], v[88:89], v[100:101], v[50:51] op_sel_hi:[1,1,0]
	v_lshlrev_b32_e32 v101, 16, v51
	v_mov_b32_e32 v65, v59
	v_mul_f32_e32 v50, v59, v101
	v_pk_fma_f32 v[64:65], v[64:65], v[100:101], v[50:51] op_sel_hi:[1,1,0]
	v_and_b32_e32 v101, 0xffff0000, v51
	v_mov_b32_e32 v97, v59
	v_mul_f32_e32 v50, v59, v101
	v_pk_fma_f32 v[62:63], v[96:97], v[100:101], v[50:51] op_sel_hi:[1,1,0]
	v_lshlrev_b32_e32 v101, 16, v52
	v_mov_b32_e32 v95, v59
	v_mul_f32_e32 v50, v59, v101
	v_pk_fma_f32 v[60:61], v[94:95], v[100:101], v[50:51] op_sel_hi:[1,1,0]
	v_and_b32_e32 v101, 0xffff0000, v52
	v_mov_b32_e32 v93, v59
	v_mul_f32_e32 v50, v59, v101
	v_pk_fma_f32 v[92:93], v[92:93], v[100:101], v[50:51] op_sel_hi:[1,1,0]
	v_lshlrev_b32_e32 v101, 16, v53
	v_mov_b32_e32 v91, v59
	v_mul_f32_e32 v50, v59, v101
	v_pk_fma_f32 v[90:91], v[90:91], v[100:101], v[50:51] op_sel_hi:[1,1,0]
	v_and_b32_e32 v101, 0xffff0000, v53
	v_mov_b32_e32 v87, v59
	v_mul_f32_e32 v50, v59, v101
	v_mul_f32_e32 v94, v114, v59
	v_pk_fma_f32 v[86:87], v[86:87], v[100:101], v[50:51] op_sel_hi:[1,1,0]
	v_fmac_f32_e32 v94, v98, v100
	v_cvt_pk_bf16_f32 v50, v54, v88
	v_cvt_pk_bf16_f32 v51, v64, v62
	v_cvt_pk_bf16_f32 v52, v60, v92
	v_cvt_pk_bf16_f32 v53, v90, v86
	global_store_dwordx4 v[102:103], v[50:53], off
	s_and_saveexec_b64 s[18:19], s[14:15]
	s_cbranch_execz .LBB0_624
	v_add_co_u32_e32 v50, vcc, 0x100000, v80
	s_nop 1
	v_addc_co_u32_e32 v51, vcc, 0, v81, vcc
	flat_store_dword v[50:51], v94 offset:2048

; __device__ __forceinline__ float bflo(unsigned w) { return __uint_as_float(w << 16); }
; __device__ __forceinline__ float bfhi(unsigned w) { return __uint_as_float(w & 0xffff0000u); }
; #define PACK_CARRY() (u32x4){cvt_pk_bf16(c0, c1), cvt_pk_bf16(c2, c3), cvt_pk_bf16(c4, c5), cvt_pk_bf16(c6, c7)}
; __device__ __forceinline__ void mlstm_scan_item(const Params& P, int item) {
;     ...
;         for (int j = 0; j < 16; ++j) { const int n = n0 + j; const float g = GM[n * 2], ml = GM[n * 2 + 1];
;             *(u32x4*)(p + (size_t)n * 32768) = PACK_CARRY();
;             if (hasn) np[(size_t)n * 128] = ncar;
;             if (wm) MPREV[n] = m;
;             const float mn = fmaxf(g + m, ml), sp = __expf(g + m - mn), sq = __expf(ml - mn);
;             c0 = sp * c0 + sq * bflo(cl[j].x); c1 = sp * c1 + sq * bfhi(cl[j].x); c2 = sp * c2 + sq * bflo(cl[j].y); c3 = sp * c3 + sq * bfhi(cl[j].y);
;             c4 = sp * c4 + sq * bflo(cl[j].z); c5 = sp * c5 + sq * bfhi(cl[j].z); c6 = sp * c6 + sq * bflo(cl[j].w); c7 = sp * c7 + sq * bfhi(cl[j].w);
;             ncar = sp * ncar + sq * nl[j]; m = mn; }
.LBB0_626:
	s_or_b64 exec, exec, s[18:19]
	v_add_co_u32_e32 v50, vcc, 0x60000, v84
	v_lshlrev_b32_e32 v97, 16, v46
	s_nop 0
	v_addc_co_u32_e32 v51, vcc, 0, v85, vcc
	v_mov_b32_e32 v52, v222
	v_mov_b32_e32 v53, v223
	v_add_f32_e32 v50, v99, v56
	v_max_f32_e32 v51, v57, v57
	v_max_f32_e32 v95, v50, v51
	v_sub_f32_e32 v51, v57, v95
	v_sub_f32_e32 v50, v50, v95
	v_mul_f32_e32 v51, 0x3fb8aa3b, v51
	v_mul_f32_e32 v50, 0x3fb8aa3b, v50
	v_exp_f32_e32 v55, v51
	v_exp_f32_e32 v96, v50
	s_mov_b64 s[18:19], 0x1ae50000
	v_lshl_add_u64 v[98:99], v[76:77], 0, s[18:19]
	v_mul_f32_e32 v50, v55, v97
	v_pk_fma_f32 v[50:51], v[54:55], v[96:97], v[50:51] op_sel_hi:[1,1,0]
	v_and_b32_e32 v97, 0xffff0000, v46
	v_mov_b32_e32 v89, v55
	v_mul_f32_e32 v46, v55, v97
	v_pk_fma_f32 v[88:89], v[88:89], v[96:97], v[46:47] op_sel_hi:[1,1,0]
	v_lshlrev_b32_e32 v97, 16, v47
	v_mov_b32_e32 v65, v55
	v_mul_f32_e32 v46, v55, v97
	v_pk_fma_f32 v[64:65], v[64:65], v[96:97], v[46:47] op_sel_hi:[1,1,0]
	v_and_b32_e32 v97, 0xffff0000, v47
	v_mov_b32_e32 v63, v55
	v_mul_f32_e32 v46, v55, v97
	v_pk_fma_f32 v[62:63], v[62:63], v[96:97], v[46:47] op_sel_hi:[1,1,0]
	v_lshlrev_b32_e32 v97, 16, v48
	v_mov_b32_e32 v61, v55
	v_mul_f32_e32 v46, v55, v97
	v_pk_fma_f32 v[60:61], v[60:61], v[96:97], v[46:47] op_sel_hi:[1,1,0]
	v_and_b32_e32 v97, 0xffff0000, v48
	v_mov_b32_e32 v93, v55
	v_mul_f32_e32 v46, v55, v97
	v_pk_fma_f32 v[58:59], v[92:93], v[96:97], v[46:47] op_sel_hi:[1,1,0]
	v_lshlrev_b32_e32 v97, 16, v49
	v_mov_b32_e32 v91, v55
	v_mul_f32_e32 v46, v55, v97
	v_pk_fma_f32 v[56:57], v[90:91], v[96:97], v[46:47] op_sel_hi:[1,1,0]
	v_and_b32_e32 v97, 0xffff0000, v49
	v_mov_b32_e32 v87, v55
	v_mul_f32_e32 v46, v55, v97
	v_mul_f32_e32 v90, v113, v55
	v_pk_fma_f32 v[86:87], v[86:87], v[96:97], v[46:47] op_sel_hi:[1,1,0]
	v_fmac_f32_e32 v90, v94, v96
	v_cvt_pk_bf16_f32 v46, v50, v88
	v_cvt_pk_bf16_f32 v47, v64, v62
	v_cvt_pk_bf16_f32 v48, v60, v58
	v_cvt_pk_bf16_f32 v49, v56, v86
	global_store_dwordx4 v[98:99], v[46:49], off
	s_and_saveexec_b64 s[18:19], s[14:15]
	s_cbranch_execz .LBB0_628
	v_add_co_u32_e32 v46, vcc, 0x100000, v80
	s_nop 1
	v_addc_co_u32_e32 v47, vcc, 0, v81, vcc
	flat_store_dword v[46:47], v90 offset:2560

; __device__ __forceinline__ float bflo(unsigned w) { return __uint_as_float(w << 16); }
; __device__ __forceinline__ float bfhi(unsigned w) { return __uint_as_float(w & 0xffff0000u); }
; #define PACK_CARRY() (u32x4){cvt_pk_bf16(c0, c1), cvt_pk_bf16(c2, c3), cvt_pk_bf16(c4, c5), cvt_pk_bf16(c6, c7)}
; __device__ __forceinline__ void mlstm_scan_item(const Params& P, int item) {
;     ...
;         for (int j = 0; j < 16; ++j) { const int n = n0 + j; const float g = GM[n * 2], ml = GM[n * 2 + 1];
;             *(u32x4*)(p + (size_t)n * 32768) = PACK_CARRY();
;             if (hasn) np[(size_t)n * 128] = ncar;
;             if (wm) MPREV[n] = m;
;             const float mn = fmaxf(g + m, ml), sp = __expf(g + m - mn), sq = __expf(ml - mn);
;             c0 = sp * c0 + sq * bflo(cl[j].x); c1 = sp * c1 + sq * bfhi(cl[j].x); c2 = sp * c2 + sq * bflo(cl[j].y); c3 = sp * c3 + sq * bfhi(cl[j].y);
;             c4 = sp * c4 + sq * bflo(cl[j].z); c5 = sp * c5 + sq * bfhi(cl[j].z); c6 = sp * c6 + sq * bflo(cl[j].w); c7 = sp * c7 + sq * bfhi(cl[j].w);
;             ncar = sp * ncar + sq * nl[j]; m = mn; }
.LBB0_630:
	s_or_b64 exec, exec, s[18:19]
	v_add_co_u32_e32 v46, vcc, 0x60000, v84
	v_lshlrev_b32_e32 v93, 16, v42
	s_nop 0
	v_addc_co_u32_e32 v47, vcc, 0, v85, vcc
	v_mov_b32_e32 v48, v224
	v_mov_b32_e32 v49, v225
	v_add_f32_e32 v46, v95, v52
	v_max_f32_e32 v47, v53, v53
	v_max_f32_e32 v91, v46, v47
	v_sub_f32_e32 v47, v53, v91
	v_sub_f32_e32 v46, v46, v91
	v_mul_f32_e32 v47, 0x3fb8aa3b, v47
	v_mul_f32_e32 v46, 0x3fb8aa3b, v46
	v_exp_f32_e32 v51, v47
	v_exp_f32_e32 v92, v46
	s_mov_b64 s[18:19], 0x1ae60000
	v_lshl_add_u64 v[94:95], v[76:77], 0, s[18:19]
	v_mul_f32_e32 v46, v51, v93
	v_pk_fma_f32 v[46:47], v[50:51], v[92:93], v[46:47] op_sel_hi:[1,1,0]
	v_and_b32_e32 v93, 0xffff0000, v42
	v_mov_b32_e32 v89, v51
	v_mul_f32_e32 v42, v51, v93
	v_pk_fma_f32 v[52:53], v[88:89], v[92:93], v[42:43] op_sel_hi:[1,1,0]
	v_lshlrev_b32_e32 v93, 16, v43
	v_mov_b32_e32 v65, v51
	v_mul_f32_e32 v42, v51, v93
	v_pk_fma_f32 v[64:65], v[64:65], v[92:93], v[42:43] op_sel_hi:[1,1,0]
	v_and_b32_e32 v93, 0xffff0000, v43
	v_mov_b32_e32 v63, v51
	v_mul_f32_e32 v42, v51, v93
	v_pk_fma_f32 v[62:63], v[62:63], v[92:93], v[42:43] op_sel_hi:[1,1,0]
	v_lshlrev_b32_e32 v93, 16, v44
	v_mov_b32_e32 v61, v51
	v_mul_f32_e32 v42, v51, v93
	v_pk_fma_f32 v[60:61], v[60:61], v[92:93], v[42:43] op_sel_hi:[1,1,0]
	v_and_b32_e32 v93, 0xffff0000, v44
	v_mov_b32_e32 v59, v51
	v_mul_f32_e32 v42, v51, v93
	v_pk_fma_f32 v[58:59], v[58:59], v[92:93], v[42:43] op_sel_hi:[1,1,0]
	v_lshlrev_b32_e32 v93, 16, v45
	v_mov_b32_e32 v57, v51
	v_mul_f32_e32 v42, v51, v93
	v_pk_fma_f32 v[56:57], v[56:57], v[92:93], v[42:43] op_sel_hi:[1,1,0]
	v_and_b32_e32 v93, 0xffff0000, v45
	v_mov_b32_e32 v87, v51
	v_mul_f32_e32 v42, v51, v93
	v_pk_fma_f32 v[54:55], v[86:87], v[92:93], v[42:43] op_sel_hi:[1,1,0]
	v_mul_f32_e32 v86, v112, v51
	v_fmac_f32_e32 v86, v90, v92
	v_cvt_pk_bf16_f32 v42, v46, v52
	v_cvt_pk_bf16_f32 v43, v64, v62
	v_cvt_pk_bf16_f32 v44, v60, v58
	v_cvt_pk_bf16_f32 v45, v56, v54
	global_store_dwordx4 v[94:95], v[42:45], off
	s_and_saveexec_b64 s[18:19], s[14:15]
	s_cbranch_execz .LBB0_632
	v_add_co_u32_e32 v42, vcc, 0x100000, v80
	s_nop 1
	v_addc_co_u32_e32 v43, vcc, 0, v81, vcc
	flat_store_dword v[42:43], v86 offset:3072

; __device__ __forceinline__ float bflo(unsigned w) { return __uint_as_float(w << 16); }
; __device__ __forceinline__ float bfhi(unsigned w) { return __uint_as_float(w & 0xffff0000u); }
; #define PACK_CARRY() (u32x4){cvt_pk_bf16(c0, c1), cvt_pk_bf16(c2, c3), cvt_pk_bf16(c4, c5), cvt_pk_bf16(c6, c7)}
; __device__ __forceinline__ void mlstm_scan_item(const Params& P, int item) {
;     ...
;         for (int j = 0; j < 16; ++j) { const int n = n0 + j; const float g = GM[n * 2], ml = GM[n * 2 + 1];
;             *(u32x4*)(p + (size_t)n * 32768) = PACK_CARRY();
;             if (hasn) np[(size_t)n * 128] = ncar;
;             if (wm) MPREV[n] = m;
;             const float mn = fmaxf(g + m, ml), sp = __expf(g + m - mn), sq = __expf(ml - mn);
;             c0 = sp * c0 + sq * bflo(cl[j].x); c1 = sp * c1 + sq * bfhi(cl[j].x); c2 = sp * c2 + sq * bflo(cl[j].y); c3 = sp * c3 + sq * bfhi(cl[j].y);
;             c4 = sp * c4 + sq * bflo(cl[j].z); c5 = sp * c5 + sq * bfhi(cl[j].z); c6 = sp * c6 + sq * bflo(cl[j].w); c7 = sp * c7 + sq * bfhi(cl[j].w);
;             ncar = sp * ncar + sq * nl[j]; m = mn; }
.LBB0_634:
	s_or_b64 exec, exec, s[18:19]
	v_add_co_u32_e32 v42, vcc, 0x60000, v84
	v_lshlrev_b32_e32 v89, 16, v38
	s_nop 0
	v_addc_co_u32_e32 v43, vcc, 0, v85, vcc
	v_mov_b32_e32 v44, v226
	v_mov_b32_e32 v45, v227
	v_add_f32_e32 v42, v91, v48
	v_max_f32_e32 v43, v49, v49
	v_max_f32_e32 v87, v42, v43
	v_sub_f32_e32 v43, v49, v87
	v_sub_f32_e32 v42, v42, v87
	v_mul_f32_e32 v43, 0x3fb8aa3b, v43
	v_mul_f32_e32 v42, 0x3fb8aa3b, v42
	v_exp_f32_e32 v47, v43
	v_exp_f32_e32 v88, v42
	s_mov_b64 s[18:19], 0x1ae70000
	v_lshl_add_u64 v[90:91], v[76:77], 0, s[18:19]
	v_mul_f32_e32 v42, v47, v89
	v_pk_fma_f32 v[42:43], v[46:47], v[88:89], v[42:43] op_sel_hi:[1,1,0]
	v_and_b32_e32 v89, 0xffff0000, v38
	v_mov_b32_e32 v53, v47
	v_mul_f32_e32 v38, v47, v89
	v_pk_fma_f32 v[52:53], v[52:53], v[88:89], v[38:39] op_sel_hi:[1,1,0]
	v_lshlrev_b32_e32 v89, 16, v39
	v_mov_b32_e32 v65, v47
	v_mul_f32_e32 v38, v47, v89
	v_pk_fma_f32 v[50:51], v[64:65], v[88:89], v[38:39] op_sel_hi:[1,1,0]
	v_and_b32_e32 v89, 0xffff0000, v39
	v_mov_b32_e32 v63, v47
	v_mul_f32_e32 v38, v47, v89
	v_pk_fma_f32 v[48:49], v[62:63], v[88:89], v[38:39] op_sel_hi:[1,1,0]
	v_lshlrev_b32_e32 v89, 16, v40
	v_mov_b32_e32 v61, v47
	v_mul_f32_e32 v38, v47, v89
	v_pk_fma_f32 v[60:61], v[60:61], v[88:89], v[38:39] op_sel_hi:[1,1,0]
	v_and_b32_e32 v89, 0xffff0000, v40
	v_mov_b32_e32 v59, v47
	v_mul_f32_e32 v38, v47, v89
	v_pk_fma_f32 v[58:59], v[58:59], v[88:89], v[38:39] op_sel_hi:[1,1,0]
	v_lshlrev_b32_e32 v89, 16, v41
	v_mov_b32_e32 v57, v47
	v_mul_f32_e32 v38, v47, v89
	v_pk_fma_f32 v[56:57], v[56:57], v[88:89], v[38:39] op_sel_hi:[1,1,0]
	v_and_b32_e32 v89, 0xffff0000, v41
	v_mov_b32_e32 v55, v47
	v_mul_f32_e32 v38, v47, v89
	v_mul_f32_e32 v62, v111, v47
	v_pk_fma_f32 v[54:55], v[54:55], v[88:89], v[38:39] op_sel_hi:[1,1,0]
	v_fmac_f32_e32 v62, v86, v88
	v_cvt_pk_bf16_f32 v38, v42, v52
	v_cvt_pk_bf16_f32 v39, v50, v48
	v_cvt_pk_bf16_f32 v40, v60, v58
	v_cvt_pk_bf16_f32 v41, v56, v54
	global_store_dwordx4 v[90:91], v[38:41], off
	s_and_saveexec_b64 s[18:19], s[14:15]
	s_cbranch_execz .LBB0_636
	v_add_co_u32_e32 v38, vcc, 0x100000, v80
	s_nop 1
	v_addc_co_u32_e32 v39, vcc, 0, v81, vcc
	flat_store_dword v[38:39], v62 offset:3584

; __device__ __forceinline__ float bflo(unsigned w) { return __uint_as_float(w << 16); }
; __device__ __forceinline__ float bfhi(unsigned w) { return __uint_as_float(w & 0xffff0000u); }
; #define PACK_CARRY() (u32x4){cvt_pk_bf16(c0, c1), cvt_pk_bf16(c2, c3), cvt_pk_bf16(c4, c5), cvt_pk_bf16(c6, c7)}
; __device__ __forceinline__ void mlstm_scan_item(const Params& P, int item) {
;     ...
;         for (int j = 0; j < 16; ++j) { const int n = n0 + j; const float g = GM[n * 2], ml = GM[n * 2 + 1];
;             *(u32x4*)(p + (size_t)n * 32768) = PACK_CARRY();
;             if (hasn) np[(size_t)n * 128] = ncar;
;             if (wm) MPREV[n] = m;
;             const float mn = fmaxf(g + m, ml), sp = __expf(g + m - mn), sq = __expf(ml - mn);
;             c0 = sp * c0 + sq * bflo(cl[j].x); c1 = sp * c1 + sq * bfhi(cl[j].x); c2 = sp * c2 + sq * bflo(cl[j].y); c3 = sp * c3 + sq * bfhi(cl[j].y);
;             c4 = sp * c4 + sq * bflo(cl[j].z); c5 = sp * c5 + sq * bfhi(cl[j].z); c6 = sp * c6 + sq * bflo(cl[j].w); c7 = sp * c7 + sq * bfhi(cl[j].w);
;             ncar = sp * ncar + sq * nl[j]; m = mn; }
.LBB0_638:
	s_or_b64 exec, exec, s[18:19]
	v_add_co_u32_e32 v38, vcc, 0x60000, v84
	v_lshlrev_b32_e32 v65, 16, v34
	s_nop 0
	v_addc_co_u32_e32 v39, vcc, 0, v85, vcc
	v_mov_b32_e32 v40, v228
	v_mov_b32_e32 v41, v229
	v_add_f32_e32 v38, v87, v44
	v_max_f32_e32 v39, v45, v45
	v_max_f32_e32 v63, v38, v39
	v_sub_f32_e32 v39, v45, v63
	v_sub_f32_e32 v38, v38, v63
	v_mul_f32_e32 v39, 0x3fb8aa3b, v39
	v_mul_f32_e32 v38, 0x3fb8aa3b, v38
	v_exp_f32_e32 v43, v39
	v_exp_f32_e32 v64, v38
	s_mov_b64 s[18:19], 0x1ae80000
	v_lshl_add_u64 v[86:87], v[76:77], 0, s[18:19]
	v_mul_f32_e32 v38, v43, v65
	v_pk_fma_f32 v[38:39], v[42:43], v[64:65], v[38:39] op_sel_hi:[1,1,0]
	v_and_b32_e32 v65, 0xffff0000, v34
	v_mov_b32_e32 v53, v43
	v_mul_f32_e32 v34, v43, v65
	v_pk_fma_f32 v[52:53], v[52:53], v[64:65], v[34:35] op_sel_hi:[1,1,0]
	v_lshlrev_b32_e32 v65, 16, v35
	v_mov_b32_e32 v51, v43
	v_mul_f32_e32 v34, v43, v65
	v_pk_fma_f32 v[50:51], v[50:51], v[64:65], v[34:35] op_sel_hi:[1,1,0]
	v_and_b32_e32 v65, 0xffff0000, v35
	v_mov_b32_e32 v49, v43
	v_mul_f32_e32 v34, v43, v65
	v_pk_fma_f32 v[48:49], v[48:49], v[64:65], v[34:35] op_sel_hi:[1,1,0]
	v_lshlrev_b32_e32 v65, 16, v36
	v_mov_b32_e32 v61, v43
	v_mul_f32_e32 v34, v43, v65
	v_pk_fma_f32 v[46:47], v[60:61], v[64:65], v[34:35] op_sel_hi:[1,1,0]
	v_and_b32_e32 v65, 0xffff0000, v36
	v_mov_b32_e32 v59, v43
	v_mul_f32_e32 v34, v43, v65
	v_pk_fma_f32 v[44:45], v[58:59], v[64:65], v[34:35] op_sel_hi:[1,1,0]
	v_lshlrev_b32_e32 v65, 16, v37
	v_mov_b32_e32 v57, v43
	v_mul_f32_e32 v34, v43, v65
	v_pk_fma_f32 v[56:57], v[56:57], v[64:65], v[34:35] op_sel_hi:[1,1,0]
	v_and_b32_e32 v65, 0xffff0000, v37
	v_mov_b32_e32 v55, v43
	v_mul_f32_e32 v34, v43, v65
	v_mul_f32_e32 v58, v110, v43
	v_pk_fma_f32 v[54:55], v[54:55], v[64:65], v[34:35] op_sel_hi:[1,1,0]
	v_fmac_f32_e32 v58, v62, v64
	v_cvt_pk_bf16_f32 v34, v38, v52
	v_cvt_pk_bf16_f32 v35, v50, v48
	v_cvt_pk_bf16_f32 v36, v46, v44
	v_cvt_pk_bf16_f32 v37, v56, v54
	global_store_dwordx4 v[86:87], v[34:37], off
	s_and_saveexec_b64 s[18:19], s[14:15]
	s_cbranch_execz .LBB0_640
	v_add_co_u32_e32 v34, vcc, 0x101000, v80
	s_nop 1
	v_addc_co_u32_e32 v35, vcc, 0, v81, vcc
	flat_store_dword v[34:35], v58

; __device__ __forceinline__ float bflo(unsigned w) { return __uint_as_float(w << 16); }
; __device__ __forceinline__ float bfhi(unsigned w) { return __uint_as_float(w & 0xffff0000u); }
; #define PACK_CARRY() (u32x4){cvt_pk_bf16(c0, c1), cvt_pk_bf16(c2, c3), cvt_pk_bf16(c4, c5), cvt_pk_bf16(c6, c7)}
; __device__ __forceinline__ void mlstm_scan_item(const Params& P, int item) {
;     ...
;         for (int j = 0; j < 16; ++j) { const int n = n0 + j; const float g = GM[n * 2], ml = GM[n * 2 + 1];
;             *(u32x4*)(p + (size_t)n * 32768) = PACK_CARRY();
;             if (hasn) np[(size_t)n * 128] = ncar;
;             if (wm) MPREV[n] = m;
;             const float mn = fmaxf(g + m, ml), sp = __expf(g + m - mn), sq = __expf(ml - mn);
;             c0 = sp * c0 + sq * bflo(cl[j].x); c1 = sp * c1 + sq * bfhi(cl[j].x); c2 = sp * c2 + sq * bflo(cl[j].y); c3 = sp * c3 + sq * bfhi(cl[j].y);
;             c4 = sp * c4 + sq * bflo(cl[j].z); c5 = sp * c5 + sq * bfhi(cl[j].z); c6 = sp * c6 + sq * bflo(cl[j].w); c7 = sp * c7 + sq * bfhi(cl[j].w);
;             ncar = sp * ncar + sq * nl[j]; m = mn; }
.LBB0_642:
	s_or_b64 exec, exec, s[18:19]
	v_add_co_u32_e32 v34, vcc, 0x60000, v84
	v_lshlrev_b32_e32 v61, 16, v30
	s_nop 0
	v_addc_co_u32_e32 v35, vcc, 0, v85, vcc
	v_mov_b32_e32 v36, v230
	v_mov_b32_e32 v37, v231
	v_add_f32_e32 v34, v63, v40
	v_max_f32_e32 v35, v41, v41
	v_max_f32_e32 v59, v34, v35
	v_sub_f32_e32 v35, v41, v59
	v_sub_f32_e32 v34, v34, v59
	v_mul_f32_e32 v35, 0x3fb8aa3b, v35
	v_mul_f32_e32 v34, 0x3fb8aa3b, v34
	v_exp_f32_e32 v39, v35
	v_exp_f32_e32 v60, v34
	s_mov_b64 s[18:19], 0x1ae90000
	v_lshl_add_u64 v[62:63], v[76:77], 0, s[18:19]
	v_mul_f32_e32 v34, v39, v61
	v_pk_fma_f32 v[34:35], v[38:39], v[60:61], v[34:35] op_sel_hi:[1,1,0]
	v_and_b32_e32 v61, 0xffff0000, v30
	v_mov_b32_e32 v53, v39
	v_mul_f32_e32 v30, v39, v61
	v_pk_fma_f32 v[52:53], v[52:53], v[60:61], v[30:31] op_sel_hi:[1,1,0]
	v_lshlrev_b32_e32 v61, 16, v31
	v_mov_b32_e32 v51, v39
	v_mul_f32_e32 v30, v39, v61
	v_pk_fma_f32 v[50:51], v[50:51], v[60:61], v[30:31] op_sel_hi:[1,1,0]
	v_and_b32_e32 v61, 0xffff0000, v31
	v_mov_b32_e32 v49, v39
	v_mul_f32_e32 v30, v39, v61
	v_pk_fma_f32 v[48:49], v[48:49], v[60:61], v[30:31] op_sel_hi:[1,1,0]
	v_lshlrev_b32_e32 v61, 16, v32
	v_mov_b32_e32 v47, v39
	v_mul_f32_e32 v30, v39, v61
	v_pk_fma_f32 v[46:47], v[46:47], v[60:61], v[30:31] op_sel_hi:[1,1,0]
	v_and_b32_e32 v61, 0xffff0000, v32
	v_mov_b32_e32 v45, v39
	v_mul_f32_e32 v30, v39, v61
	v_pk_fma_f32 v[44:45], v[44:45], v[60:61], v[30:31] op_sel_hi:[1,1,0]
	v_lshlrev_b32_e32 v61, 16, v33
	v_mov_b32_e32 v57, v39
	v_mul_f32_e32 v30, v39, v61
	v_pk_fma_f32 v[42:43], v[56:57], v[60:61], v[30:31] op_sel_hi:[1,1,0]
	v_and_b32_e32 v61, 0xffff0000, v33
	v_mov_b32_e32 v55, v39
	v_mul_f32_e32 v30, v39, v61
	v_pk_fma_f32 v[40:41], v[54:55], v[60:61], v[30:31] op_sel_hi:[1,1,0]
	v_mul_f32_e32 v54, v109, v39
	v_fmac_f32_e32 v54, v58, v60
	v_cvt_pk_bf16_f32 v30, v34, v52
	v_cvt_pk_bf16_f32 v31, v50, v48
	v_cvt_pk_bf16_f32 v32, v46, v44
	v_cvt_pk_bf16_f32 v33, v42, v40
	global_store_dwordx4 v[62:63], v[30:33], off
	s_and_saveexec_b64 s[18:19], s[14:15]
	s_cbranch_execz .LBB0_644
	v_add_co_u32_e32 v30, vcc, 0x101000, v80
	s_nop 1
	v_addc_co_u32_e32 v31, vcc, 0, v81, vcc
	flat_store_dword v[30:31], v54 offset:512

; __device__ __forceinline__ float bflo(unsigned w) { return __uint_as_float(w << 16); }
; __device__ __forceinline__ float bfhi(unsigned w) { return __uint_as_float(w & 0xffff0000u); }
; #define PACK_CARRY() (u32x4){cvt_pk_bf16(c0, c1), cvt_pk_bf16(c2, c3), cvt_pk_bf16(c4, c5), cvt_pk_bf16(c6, c7)}
; __device__ __forceinline__ void mlstm_scan_item(const Params& P, int item) {
;     ...
;         for (int j = 0; j < 16; ++j) { const int n = n0 + j; const float g = GM[n * 2], ml = GM[n * 2 + 1];
;             *(u32x4*)(p + (size_t)n * 32768) = PACK_CARRY();
;             if (hasn) np[(size_t)n * 128] = ncar;
;             if (wm) MPREV[n] = m;
;             const float mn = fmaxf(g + m, ml), sp = __expf(g + m - mn), sq = __expf(ml - mn);
;             c0 = sp * c0 + sq * bflo(cl[j].x); c1 = sp * c1 + sq * bfhi(cl[j].x); c2 = sp * c2 + sq * bflo(cl[j].y); c3 = sp * c3 + sq * bfhi(cl[j].y);
;             c4 = sp * c4 + sq * bflo(cl[j].z); c5 = sp * c5 + sq * bfhi(cl[j].z); c6 = sp * c6 + sq * bflo(cl[j].w); c7 = sp * c7 + sq * bfhi(cl[j].w);
;             ncar = sp * ncar + sq * nl[j]; m = mn; }
.LBB0_646:
	s_or_b64 exec, exec, s[18:19]
	v_add_co_u32_e32 v30, vcc, 0x60000, v84
	v_lshlrev_b32_e32 v57, 16, v26
	s_nop 0
	v_addc_co_u32_e32 v31, vcc, 0, v85, vcc
	v_mov_b32_e32 v32, v232
	v_mov_b32_e32 v33, v233
	v_add_f32_e32 v30, v59, v36
	v_max_f32_e32 v31, v37, v37
	v_max_f32_e32 v55, v30, v31
	v_sub_f32_e32 v31, v37, v55
	v_sub_f32_e32 v30, v30, v55
	v_mul_f32_e32 v31, 0x3fb8aa3b, v31
	v_mul_f32_e32 v30, 0x3fb8aa3b, v30
	v_exp_f32_e32 v35, v31
	v_exp_f32_e32 v56, v30
	s_mov_b64 s[18:19], 0x1aea0000
	v_lshl_add_u64 v[58:59], v[76:77], 0, s[18:19]
	v_mul_f32_e32 v30, v35, v57
	v_pk_fma_f32 v[30:31], v[34:35], v[56:57], v[30:31] op_sel_hi:[1,1,0]
	v_and_b32_e32 v57, 0xffff0000, v26
	v_mov_b32_e32 v53, v35
	v_mul_f32_e32 v26, v35, v57
	v_pk_fma_f32 v[38:39], v[52:53], v[56:57], v[26:27] op_sel_hi:[1,1,0]
	v_lshlrev_b32_e32 v57, 16, v27
	v_mov_b32_e32 v51, v35
	v_mul_f32_e32 v26, v35, v57
	v_pk_fma_f32 v[36:37], v[50:51], v[56:57], v[26:27] op_sel_hi:[1,1,0]
	v_and_b32_e32 v57, 0xffff0000, v27
	v_mov_b32_e32 v49, v35
	v_mul_f32_e32 v26, v35, v57
	v_pk_fma_f32 v[48:49], v[48:49], v[56:57], v[26:27] op_sel_hi:[1,1,0]
	v_lshlrev_b32_e32 v57, 16, v28
	v_mov_b32_e32 v47, v35
	v_mul_f32_e32 v26, v35, v57
	v_pk_fma_f32 v[46:47], v[46:47], v[56:57], v[26:27] op_sel_hi:[1,1,0]
	v_and_b32_e32 v57, 0xffff0000, v28
	v_mov_b32_e32 v45, v35
	v_mul_f32_e32 v26, v35, v57
	v_pk_fma_f32 v[44:45], v[44:45], v[56:57], v[26:27] op_sel_hi:[1,1,0]
	v_lshlrev_b32_e32 v57, 16, v29
	v_mov_b32_e32 v43, v35
	v_mul_f32_e32 v26, v35, v57
	v_pk_fma_f32 v[42:43], v[42:43], v[56:57], v[26:27] op_sel_hi:[1,1,0]
	v_and_b32_e32 v57, 0xffff0000, v29
	v_mov_b32_e32 v41, v35
	v_mul_f32_e32 v26, v35, v57
	v_mul_f32_e32 v50, v108, v35
	v_pk_fma_f32 v[40:41], v[40:41], v[56:57], v[26:27] op_sel_hi:[1,1,0]
	v_fmac_f32_e32 v50, v54, v56
	v_cvt_pk_bf16_f32 v26, v30, v38
	v_cvt_pk_bf16_f32 v27, v36, v48
	v_cvt_pk_bf16_f32 v28, v46, v44
	v_cvt_pk_bf16_f32 v29, v42, v40
	global_store_dwordx4 v[58:59], v[26:29], off
	s_and_saveexec_b64 s[18:19], s[14:15]
	s_cbranch_execz .LBB0_648
	v_add_co_u32_e32 v26, vcc, 0x101000, v80
	s_nop 1
	v_addc_co_u32_e32 v27, vcc, 0, v81, vcc
	flat_store_dword v[26:27], v50 offset:1024

; __device__ __forceinline__ float bflo(unsigned w) { return __uint_as_float(w << 16); }
; __device__ __forceinline__ float bfhi(unsigned w) { return __uint_as_float(w & 0xffff0000u); }
; #define PACK_CARRY() (u32x4){cvt_pk_bf16(c0, c1), cvt_pk_bf16(c2, c3), cvt_pk_bf16(c4, c5), cvt_pk_bf16(c6, c7)}
; __device__ __forceinline__ void mlstm_scan_item(const Params& P, int item) {
;     ...
;         for (int j = 0; j < 16; ++j) { const int n = n0 + j; const float g = GM[n * 2], ml = GM[n * 2 + 1];
;             *(u32x4*)(p + (size_t)n * 32768) = PACK_CARRY();
;             if (hasn) np[(size_t)n * 128] = ncar;
;             if (wm) MPREV[n] = m;
;             const float mn = fmaxf(g + m, ml), sp = __expf(g + m - mn), sq = __expf(ml - mn);
;             c0 = sp * c0 + sq * bflo(cl[j].x); c1 = sp * c1 + sq * bfhi(cl[j].x); c2 = sp * c2 + sq * bflo(cl[j].y); c3 = sp * c3 + sq * bfhi(cl[j].y);
;             c4 = sp * c4 + sq * bflo(cl[j].z); c5 = sp * c5 + sq * bfhi(cl[j].z); c6 = sp * c6 + sq * bflo(cl[j].w); c7 = sp * c7 + sq * bfhi(cl[j].w);
;             ncar = sp * ncar + sq * nl[j]; m = mn; }
.LBB0_650:
	s_or_b64 exec, exec, s[18:19]
	v_add_co_u32_e32 v26, vcc, 0x60000, v84
	v_lshlrev_b32_e32 v53, 16, v22
	s_nop 0
	v_addc_co_u32_e32 v27, vcc, 0, v85, vcc
	v_mov_b32_e32 v28, v234
	v_mov_b32_e32 v29, v235
	v_add_f32_e32 v26, v55, v32
	v_max_f32_e32 v27, v33, v33
	v_max_f32_e32 v51, v26, v27
	v_sub_f32_e32 v27, v33, v51
	v_sub_f32_e32 v26, v26, v51
	v_mul_f32_e32 v27, 0x3fb8aa3b, v27
	v_mul_f32_e32 v26, 0x3fb8aa3b, v26
	v_exp_f32_e32 v31, v27
	v_exp_f32_e32 v52, v26
	s_mov_b64 s[18:19], 0x1aeb0000
	v_lshl_add_u64 v[54:55], v[76:77], 0, s[18:19]
	v_mul_f32_e32 v26, v31, v53
	v_pk_fma_f32 v[26:27], v[30:31], v[52:53], v[26:27] op_sel_hi:[1,1,0]
	v_and_b32_e32 v53, 0xffff0000, v22
	v_mov_b32_e32 v39, v31
	v_mul_f32_e32 v22, v31, v53
	v_pk_fma_f32 v[38:39], v[38:39], v[52:53], v[22:23] op_sel_hi:[1,1,0]
	v_lshlrev_b32_e32 v53, 16, v23
	v_mov_b32_e32 v37, v31
	v_mul_f32_e32 v22, v31, v53
	v_pk_fma_f32 v[36:37], v[36:37], v[52:53], v[22:23] op_sel_hi:[1,1,0]
	v_and_b32_e32 v53, 0xffff0000, v23
	v_mov_b32_e32 v49, v31
	v_mul_f32_e32 v22, v31, v53
	v_pk_fma_f32 v[34:35], v[48:49], v[52:53], v[22:23] op_sel_hi:[1,1,0]
	v_lshlrev_b32_e32 v53, 16, v24
	v_mov_b32_e32 v47, v31
	v_mul_f32_e32 v22, v31, v53
	v_pk_fma_f32 v[32:33], v[46:47], v[52:53], v[22:23] op_sel_hi:[1,1,0]
	v_and_b32_e32 v53, 0xffff0000, v24
	v_mov_b32_e32 v45, v31
	v_mul_f32_e32 v22, v31, v53
	v_pk_fma_f32 v[44:45], v[44:45], v[52:53], v[22:23] op_sel_hi:[1,1,0]
	v_lshlrev_b32_e32 v53, 16, v25
	v_mov_b32_e32 v43, v31
	v_mul_f32_e32 v22, v31, v53
	v_pk_fma_f32 v[42:43], v[42:43], v[52:53], v[22:23] op_sel_hi:[1,1,0]
	v_and_b32_e32 v53, 0xffff0000, v25
	v_mov_b32_e32 v41, v31
	v_mul_f32_e32 v22, v31, v53
	v_mul_f32_e32 v46, v107, v31
	v_pk_fma_f32 v[40:41], v[40:41], v[52:53], v[22:23] op_sel_hi:[1,1,0]
	v_fmac_f32_e32 v46, v50, v52
	v_cvt_pk_bf16_f32 v22, v26, v38
	v_cvt_pk_bf16_f32 v23, v36, v34
	v_cvt_pk_bf16_f32 v24, v32, v44
	v_cvt_pk_bf16_f32 v25, v42, v40
	global_store_dwordx4 v[54:55], v[22:25], off
	s_and_saveexec_b64 s[18:19], s[14:15]
	s_cbranch_execz .LBB0_652
	v_add_co_u32_e32 v22, vcc, 0x101000, v80
	s_nop 1
	v_addc_co_u32_e32 v23, vcc, 0, v81, vcc
	flat_store_dword v[22:23], v46 offset:1536

; __device__ __forceinline__ float bflo(unsigned w) { return __uint_as_float(w << 16); }
; __device__ __forceinline__ float bfhi(unsigned w) { return __uint_as_float(w & 0xffff0000u); }
; #define PACK_CARRY() (u32x4){cvt_pk_bf16(c0, c1), cvt_pk_bf16(c2, c3), cvt_pk_bf16(c4, c5), cvt_pk_bf16(c6, c7)}
; __device__ __forceinline__ void mlstm_scan_item(const Params& P, int item) {
;     ...
;         for (int j = 0; j < 16; ++j) { const int n = n0 + j; const float g = GM[n * 2], ml = GM[n * 2 + 1];
;             *(u32x4*)(p + (size_t)n * 32768) = PACK_CARRY();
;             if (hasn) np[(size_t)n * 128] = ncar;
;             if (wm) MPREV[n] = m;
;             const float mn = fmaxf(g + m, ml), sp = __expf(g + m - mn), sq = __expf(ml - mn);
;             c0 = sp * c0 + sq * bflo(cl[j].x); c1 = sp * c1 + sq * bfhi(cl[j].x); c2 = sp * c2 + sq * bflo(cl[j].y); c3 = sp * c3 + sq * bfhi(cl[j].y);
;             c4 = sp * c4 + sq * bflo(cl[j].z); c5 = sp * c5 + sq * bfhi(cl[j].z); c6 = sp * c6 + sq * bflo(cl[j].w); c7 = sp * c7 + sq * bfhi(cl[j].w);
;             ncar = sp * ncar + sq * nl[j]; m = mn; }
.LBB0_654:
	s_or_b64 exec, exec, s[18:19]
	v_add_co_u32_e32 v22, vcc, 0x60000, v84
	v_lshlrev_b32_e32 v49, 16, v18
	s_nop 0
	v_addc_co_u32_e32 v23, vcc, 0, v85, vcc
	v_mov_b32_e32 v24, v236
	v_mov_b32_e32 v25, v237
	v_add_f32_e32 v22, v51, v28
	v_max_f32_e32 v23, v29, v29
	v_max_f32_e32 v47, v22, v23
	v_sub_f32_e32 v23, v29, v47
	v_sub_f32_e32 v22, v22, v47
	v_mul_f32_e32 v23, 0x3fb8aa3b, v23
	v_mul_f32_e32 v22, 0x3fb8aa3b, v22
	v_exp_f32_e32 v27, v23
	v_exp_f32_e32 v48, v22
	s_mov_b64 s[18:19], 0x1aec0000
	v_lshl_add_u64 v[50:51], v[76:77], 0, s[18:19]
	v_mul_f32_e32 v22, v27, v49
	v_pk_fma_f32 v[22:23], v[26:27], v[48:49], v[22:23] op_sel_hi:[1,1,0]
	v_and_b32_e32 v49, 0xffff0000, v18
	v_mov_b32_e32 v39, v27
	v_mul_f32_e32 v18, v27, v49
	v_pk_fma_f32 v[38:39], v[38:39], v[48:49], v[18:19] op_sel_hi:[1,1,0]
	v_lshlrev_b32_e32 v49, 16, v19
	v_mov_b32_e32 v37, v27
	v_mul_f32_e32 v18, v27, v49
	v_pk_fma_f32 v[36:37], v[36:37], v[48:49], v[18:19] op_sel_hi:[1,1,0]
	v_and_b32_e32 v49, 0xffff0000, v19
	v_mov_b32_e32 v35, v27
	v_mul_f32_e32 v18, v27, v49
	v_pk_fma_f32 v[34:35], v[34:35], v[48:49], v[18:19] op_sel_hi:[1,1,0]
	v_lshlrev_b32_e32 v49, 16, v20
	v_mov_b32_e32 v33, v27
	v_mul_f32_e32 v18, v27, v49
	v_pk_fma_f32 v[32:33], v[32:33], v[48:49], v[18:19] op_sel_hi:[1,1,0]
	v_and_b32_e32 v49, 0xffff0000, v20
	v_mov_b32_e32 v45, v27
	v_mul_f32_e32 v18, v27, v49
	v_pk_fma_f32 v[30:31], v[44:45], v[48:49], v[18:19] op_sel_hi:[1,1,0]
	v_lshlrev_b32_e32 v49, 16, v21
	v_mov_b32_e32 v43, v27
	v_mul_f32_e32 v18, v27, v49
	v_pk_fma_f32 v[28:29], v[42:43], v[48:49], v[18:19] op_sel_hi:[1,1,0]
	v_and_b32_e32 v49, 0xffff0000, v21
	v_mov_b32_e32 v41, v27
	v_mul_f32_e32 v18, v27, v49
	v_pk_fma_f32 v[18:19], v[40:41], v[48:49], v[18:19] op_sel_hi:[1,1,0]
	v_mul_f32_e32 v40, v106, v27
	v_fmac_f32_e32 v40, v46, v48
	v_cvt_pk_bf16_f32 v42, v22, v38
	v_cvt_pk_bf16_f32 v43, v36, v34
	v_cvt_pk_bf16_f32 v44, v32, v30
	v_cvt_pk_bf16_f32 v45, v28, v18
	global_store_dwordx4 v[50:51], v[42:45], off
	s_and_saveexec_b64 s[18:19], s[14:15]
	s_cbranch_execz .LBB0_656
	v_add_co_u32_e32 v20, vcc, 0x101000, v80
	s_nop 1
	v_addc_co_u32_e32 v21, vcc, 0, v81, vcc
	flat_store_dword v[20:21], v40 offset:2048

; __device__ __forceinline__ float bflo(unsigned w) { return __uint_as_float(w << 16); }
; __device__ __forceinline__ float bfhi(unsigned w) { return __uint_as_float(w & 0xffff0000u); }
; #define PACK_CARRY() (u32x4){cvt_pk_bf16(c0, c1), cvt_pk_bf16(c2, c3), cvt_pk_bf16(c4, c5), cvt_pk_bf16(c6, c7)}
; __device__ __forceinline__ void mlstm_scan_item(const Params& P, int item) {
;     ...
;         for (int j = 0; j < 16; ++j) { const int n = n0 + j; const float g = GM[n * 2], ml = GM[n * 2 + 1];
;             *(u32x4*)(p + (size_t)n * 32768) = PACK_CARRY();
;             if (hasn) np[(size_t)n * 128] = ncar;
;             if (wm) MPREV[n] = m;
;             const float mn = fmaxf(g + m, ml), sp = __expf(g + m - mn), sq = __expf(ml - mn);
;             c0 = sp * c0 + sq * bflo(cl[j].x); c1 = sp * c1 + sq * bfhi(cl[j].x); c2 = sp * c2 + sq * bflo(cl[j].y); c3 = sp * c3 + sq * bfhi(cl[j].y);
;             c4 = sp * c4 + sq * bflo(cl[j].z); c5 = sp * c5 + sq * bfhi(cl[j].z); c6 = sp * c6 + sq * bflo(cl[j].w); c7 = sp * c7 + sq * bfhi(cl[j].w);
;             ncar = sp * ncar + sq * nl[j]; m = mn; }
.LBB0_658:
	s_or_b64 exec, exec, s[18:19]
	v_add_co_u32_e32 v20, vcc, 0x60000, v84
	v_add_f32_e32 v19, v47, v24
	s_nop 0
	v_addc_co_u32_e32 v21, vcc, 0, v85, vcc
	v_mov_b32_e32 v26, v238
	v_mov_b32_e32 v27, v239
	v_max_f32_e32 v20, v25, v25
	v_max_f32_e32 v42, v19, v20
	v_sub_f32_e32 v20, v25, v42
	v_sub_f32_e32 v19, v19, v42
	v_mul_f32_e32 v20, 0x3fb8aa3b, v20
	v_mul_f32_e32 v19, 0x3fb8aa3b, v19
	v_exp_f32_e32 v23, v20
	v_exp_f32_e32 v44, v19
	v_lshlrev_b32_e32 v45, 16, v14
	s_mov_b64 s[18:19], 0x1aed0000
	v_mul_f32_e32 v20, v23, v45
	v_pk_fma_f32 v[20:21], v[22:23], v[44:45], v[20:21] op_sel_hi:[1,1,0]
	v_and_b32_e32 v45, 0xffff0000, v14
	v_mov_b32_e32 v39, v23
	v_mul_f32_e32 v14, v23, v45
	v_pk_fma_f32 v[38:39], v[38:39], v[44:45], v[14:15] op_sel_hi:[1,1,0]
	v_lshlrev_b32_e32 v45, 16, v15
	v_mov_b32_e32 v37, v23
	v_mul_f32_e32 v14, v23, v45
	v_pk_fma_f32 v[36:37], v[36:37], v[44:45], v[14:15] op_sel_hi:[1,1,0]
	v_and_b32_e32 v45, 0xffff0000, v15
	v_mov_b32_e32 v35, v23
	v_mul_f32_e32 v14, v23, v45
	v_pk_fma_f32 v[34:35], v[34:35], v[44:45], v[14:15] op_sel_hi:[1,1,0]
	v_lshlrev_b32_e32 v45, 16, v16
	v_mov_b32_e32 v33, v23
	v_mul_f32_e32 v14, v23, v45
	v_pk_fma_f32 v[32:33], v[32:33], v[44:45], v[14:15] op_sel_hi:[1,1,0]
	v_and_b32_e32 v45, 0xffff0000, v16
	v_mov_b32_e32 v31, v23
	v_mul_f32_e32 v14, v23, v45
	v_pk_fma_f32 v[30:31], v[30:31], v[44:45], v[14:15] op_sel_hi:[1,1,0]
	v_lshlrev_b32_e32 v45, 16, v17
	v_mov_b32_e32 v29, v23
	v_mul_f32_e32 v14, v23, v45
	v_pk_fma_f32 v[24:25], v[28:29], v[44:45], v[14:15] op_sel_hi:[1,1,0]
	v_and_b32_e32 v45, 0xffff0000, v17
	v_mov_b32_e32 v19, v23
	v_mul_f32_e32 v14, v23, v45
	v_mul_f32_e32 v41, v105, v23
	v_lshl_add_u64 v[46:47], v[76:77], 0, s[18:19]
	v_pk_fma_f32 v[14:15], v[18:19], v[44:45], v[14:15] op_sel_hi:[1,1,0]
	v_fmac_f32_e32 v41, v40, v44
	v_cvt_pk_bf16_f32 v16, v20, v38
	v_cvt_pk_bf16_f32 v17, v36, v34
	v_cvt_pk_bf16_f32 v18, v32, v30
	v_cvt_pk_bf16_f32 v19, v24, v14
	global_store_dwordx4 v[46:47], v[16:19], off
	s_and_saveexec_b64 s[18:19], s[14:15]
	s_cbranch_execz .LBB0_660
	v_add_co_u32_e32 v16, vcc, 0x101000, v80
	s_nop 1
	v_addc_co_u32_e32 v17, vcc, 0, v81, vcc
	flat_store_dword v[16:17], v41 offset:2560

; __device__ __forceinline__ float bflo(unsigned w) { return __uint_as_float(w << 16); }
; __device__ __forceinline__ float bfhi(unsigned w) { return __uint_as_float(w & 0xffff0000u); }
; #define PACK_CARRY() (u32x4){cvt_pk_bf16(c0, c1), cvt_pk_bf16(c2, c3), cvt_pk_bf16(c4, c5), cvt_pk_bf16(c6, c7)}
; __device__ __forceinline__ void mlstm_scan_item(const Params& P, int item) {
;     ...
;         for (int j = 0; j < 16; ++j) { const int n = n0 + j; const float g = GM[n * 2], ml = GM[n * 2 + 1];
;             *(u32x4*)(p + (size_t)n * 32768) = PACK_CARRY();
;             if (hasn) np[(size_t)n * 128] = ncar;
;             if (wm) MPREV[n] = m;
;             const float mn = fmaxf(g + m, ml), sp = __expf(g + m - mn), sq = __expf(ml - mn);
;             c0 = sp * c0 + sq * bflo(cl[j].x); c1 = sp * c1 + sq * bfhi(cl[j].x); c2 = sp * c2 + sq * bflo(cl[j].y); c3 = sp * c3 + sq * bfhi(cl[j].y);
;             c4 = sp * c4 + sq * bflo(cl[j].z); c5 = sp * c5 + sq * bfhi(cl[j].z); c6 = sp * c6 + sq * bflo(cl[j].w); c7 = sp * c7 + sq * bfhi(cl[j].w);
;             ncar = sp * ncar + sq * nl[j]; m = mn; }
.LBB0_662:
	s_or_b64 exec, exec, s[18:19]
	v_add_co_u32_e32 v16, vcc, 0x60000, v84
	v_add_f32_e32 v15, v42, v26
	v_addc_co_u32_e32 v17, vcc, 0, v85, vcc
	v_mov_b32_e32 v18, v240
	v_mov_b32_e32 v19, v241
	v_max_f32_e32 v16, v27, v27
	v_max_f32_e32 v40, v15, v16
	v_sub_f32_e32 v16, v27, v40
	v_sub_f32_e32 v15, v15, v40
	v_mul_f32_e32 v16, 0x3fb8aa3b, v16
	v_mul_f32_e32 v15, 0x3fb8aa3b, v15
	v_exp_f32_e32 v21, v16
	v_exp_f32_e32 v42, v15
	v_lshlrev_b32_e32 v43, 16, v10
	v_lshl_add_u64 v[44:45], v[76:77], 0, s[52:53]
	v_mul_f32_e32 v16, v21, v43
	v_pk_fma_f32 v[16:17], v[20:21], v[42:43], v[16:17] op_sel_hi:[1,1,0]
	v_and_b32_e32 v43, 0xffff0000, v10
	v_mov_b32_e32 v39, v21
	v_mul_f32_e32 v10, v21, v43
	v_pk_fma_f32 v[38:39], v[38:39], v[42:43], v[10:11] op_sel_hi:[1,1,0]
	v_lshlrev_b32_e32 v43, 16, v11
	v_mov_b32_e32 v37, v21
	v_mul_f32_e32 v10, v21, v43
	v_pk_fma_f32 v[28:29], v[36:37], v[42:43], v[10:11] op_sel_hi:[1,1,0]
	v_and_b32_e32 v43, 0xffff0000, v11
	v_mov_b32_e32 v35, v21
	v_mul_f32_e32 v10, v21, v43
	v_pk_fma_f32 v[34:35], v[34:35], v[42:43], v[10:11] op_sel_hi:[1,1,0]
	v_lshlrev_b32_e32 v43, 16, v12
	v_mov_b32_e32 v33, v21
	v_mul_f32_e32 v10, v21, v43
	v_pk_fma_f32 v[22:23], v[32:33], v[42:43], v[10:11] op_sel_hi:[1,1,0]
	v_and_b32_e32 v43, 0xffff0000, v12
	v_mov_b32_e32 v31, v21
	v_mul_f32_e32 v10, v21, v43
	v_pk_fma_f32 v[26:27], v[30:31], v[42:43], v[10:11] op_sel_hi:[1,1,0]
	v_lshlrev_b32_e32 v43, 16, v13
	v_mov_b32_e32 v25, v21
	v_mul_f32_e32 v10, v21, v43
	v_pk_fma_f32 v[10:11], v[24:25], v[42:43], v[10:11] op_sel_hi:[1,1,0]
	v_and_b32_e32 v43, 0xffff0000, v13
	v_mov_b32_e32 v15, v21
	v_mul_f32_e32 v12, v21, v43
	v_mul_f32_e32 v24, v104, v21
	v_pk_fma_f32 v[12:13], v[14:15], v[42:43], v[12:13] op_sel_hi:[1,1,0]
	v_fmac_f32_e32 v24, v41, v42
	v_cvt_pk_bf16_f32 v30, v16, v38
	v_cvt_pk_bf16_f32 v31, v28, v34
	v_cvt_pk_bf16_f32 v32, v22, v26
	v_cvt_pk_bf16_f32 v33, v10, v12
	global_store_dwordx4 v[44:45], v[30:33], off
	s_and_saveexec_b64 s[18:19], s[14:15]
	s_cbranch_execz .LBB0_664
	v_add_co_u32_e32 v14, vcc, 0x101000, v80
	s_nop 1
	v_addc_co_u32_e32 v15, vcc, 0, v81, vcc
	flat_store_dword v[14:15], v24 offset:3072

; __device__ __forceinline__ float bflo(unsigned w) { return __uint_as_float(w << 16); }
; __device__ __forceinline__ float bfhi(unsigned w) { return __uint_as_float(w & 0xffff0000u); }
; #define PACK_CARRY() (u32x4){cvt_pk_bf16(c0, c1), cvt_pk_bf16(c2, c3), cvt_pk_bf16(c4, c5), cvt_pk_bf16(c6, c7)}
; __device__ __forceinline__ void mlstm_scan_item(const Params& P, int item) {
;     ...
;         for (int j = 0; j < 16; ++j) { const int n = n0 + j; const float g = GM[n * 2], ml = GM[n * 2 + 1];
;             *(u32x4*)(p + (size_t)n * 32768) = PACK_CARRY();
;             if (hasn) np[(size_t)n * 128] = ncar;
;             if (wm) MPREV[n] = m;
;             const float mn = fmaxf(g + m, ml), sp = __expf(g + m - mn), sq = __expf(ml - mn);
;             c0 = sp * c0 + sq * bflo(cl[j].x); c1 = sp * c1 + sq * bfhi(cl[j].x); c2 = sp * c2 + sq * bflo(cl[j].y); c3 = sp * c3 + sq * bfhi(cl[j].y);
;             c4 = sp * c4 + sq * bflo(cl[j].z); c5 = sp * c5 + sq * bfhi(cl[j].z); c6 = sp * c6 + sq * bflo(cl[j].w); c7 = sp * c7 + sq * bfhi(cl[j].w);
;             ncar = sp * ncar + sq * nl[j]; m = mn; }
.LBB0_666:
	s_or_b64 exec, exec, s[18:19]
	v_mov_b32_e32 v14, v242
	v_mov_b32_e32 v15, v243
	v_add_f32_e32 v11, v40, v18
	v_max_f32_e32 v13, v19, v19
	v_max_f32_e32 v25, v11, v13
	v_sub_f32_e32 v11, v11, v25
	v_mul_f32_e32 v11, 0x3fb8aa3b, v11
	v_exp_f32_e32 v30, v11
	v_sub_f32_e32 v11, v19, v25
	v_mul_f32_e32 v11, 0x3fb8aa3b, v11
	v_exp_f32_e32 v17, v11
	v_lshlrev_b32_e32 v31, 16, v6
	v_lshl_add_u64 v[32:33], v[76:77], 0, s[54:55]
	v_pk_mul_f32 v[18:19], v[16:17], v[30:31]
	v_and_b32_e32 v31, 0xffff0000, v6
	v_mov_b32_e32 v39, v17
	v_pk_mul_f32 v[20:21], v[38:39], v[30:31]
	v_mov_b32_e32 v36, v18
	v_mov_b32_e32 v37, v20
	v_mov_b32_e32 v20, v19
	v_lshlrev_b32_e32 v31, 16, v7
	v_mov_b32_e32 v29, v17
	v_pk_add_f32 v[18:19], v[36:37], v[20:21]
	v_pk_mul_f32 v[20:21], v[28:29], v[30:31]
	v_and_b32_e32 v31, 0xffff0000, v7
	v_mov_b32_e32 v35, v17
	v_pk_mul_f32 v[6:7], v[34:35], v[30:31]
	v_lshlrev_b32_e32 v31, 16, v8
	v_mov_b32_e32 v23, v17
	v_mov_b32_e32 v28, v20
	v_mov_b32_e32 v29, v6
	v_mov_b32_e32 v6, v21
	v_pk_mul_f32 v[20:21], v[22:23], v[30:31]
	v_and_b32_e32 v31, 0xffff0000, v8
	v_mov_b32_e32 v27, v17
	v_pk_mul_f32 v[22:23], v[26:27], v[30:31]
	v_lshlrev_b32_e32 v31, 16, v9
	v_mov_b32_e32 v11, v17
	v_pk_mul_f32 v[10:11], v[10:11], v[30:31]
	v_and_b32_e32 v31, 0xffff0000, v9
	v_mov_b32_e32 v13, v17
	v_pk_mul_f32 v[8:9], v[12:13], v[30:31]
	v_mov_b32_e32 v26, v20
	v_mov_b32_e32 v27, v22
	v_mov_b32_e32 v22, v21
	v_mov_b32_e32 v12, v10
	v_mov_b32_e32 v13, v8
	v_mov_b32_e32 v8, v11
	v_mul_f32_e32 v78, v78, v17
	v_pk_add_f32 v[6:7], v[28:29], v[6:7]
	v_pk_add_f32 v[20:21], v[26:27], v[22:23]
	v_pk_add_f32 v[8:9], v[12:13], v[8:9]
	v_fmac_f32_e32 v78, v24, v30
	v_cvt_pk_bf16_f32 v10, v18, v19
	v_cvt_pk_bf16_f32 v11, v6, v7
	v_cvt_pk_bf16_f32 v12, v20, v21
	v_cvt_pk_bf16_f32 v13, v8, v9
	global_store_dwordx4 v[32:33], v[10:13], off
	s_and_saveexec_b64 s[18:19], s[14:15]
	s_cbranch_execz .LBB0_668
	v_add_co_u32_e32 v10, vcc, 0x101000, v80
	s_nop 1
	v_addc_co_u32_e32 v11, vcc, 0, v81, vcc
	flat_store_dword v[10:11], v78 offset:3584

; #define PACK_CARRY() (u32x4){cvt_pk_bf16(c0, c1), cvt_pk_bf16(c2, c3), cvt_pk_bf16(c4, c5), cvt_pk_bf16(c6, c7)}
; __device__ __forceinline__ void mlstm_scan_item(const Params& P, int item) {
;     ...
;     *(u32x4*)(p + (size_t)256 * 32768) = PACK_CARRY();
;     if (hasn) np[(size_t)256 * 128] = ncar;
;     if (wm) MPREV[256] = m;
.LBB0_670:
	s_add_u32 s3, s10, s36
	s_addc_u32 s17, s11, s35
	s_add_u32 s16, s3, s37
	s_addc_u32 s17, s17, 0
	v_lshl_add_u64 v[6:7], v[68:69], 1, s[16:17]
	v_add_co_u32_e32 v6, vcc, 0x1be00000, v6
	v_cvt_pk_bf16_f32 v2, v92, v93
	v_cvt_pk_bf16_f32 v3, v90, v91
	v_cvt_pk_bf16_f32 v4, v88, v89
	v_cvt_pk_bf16_f32 v5, v86, v87
	s_nop 1
	v_addc_co_u32_e32 v7, vcc, 0, v7, vcc
	global_store_dwordx4 v[6:7], v[2:5], off
	s_and_saveexec_b64 s[16:17], s[14:15]
	s_cbranch_execz .LBB0_672
	s_add_u32 s14, s10, s34
	s_addc_u32 s15, s11, s22
	v_lshl_add_u64 v[2:3], v[66:67], 2, s[14:15]
	v_add_co_u32_e32 v2, vcc, 0x120000, v2
	s_nop 1
	v_addc_co_u32_e32 v3, vcc, 0, v3, vcc
	flat_store_dword v[2:3], v117

; __device__ __forceinline__ int crow(int r, int hi) { return (r & 3) + 8 * (r >> 2) + 4 * hi; }
; __device__ __forceinline__ int tsw(int row, int t) { return ((((t >> 1) + 4 * ((row >> 3) & 7)) & 31) << 1) | (t & 1); }
; __device__ __forceinline__ void mlstm_out_unit(const Params& P, int l, int h, int n, char* lds) {
;     ...
;     f32x16 a1[2] = {}, a2[2] = {};
; #pragma unroll
;     for (int ks = 0; ks < 4; ++ks) { const bf16x8 B = *(const bf16x8*)(VT + (32 * wid + r32) * 72 + tsw(32 * wid + r32, 16 * ks + 8 * hi));
; #pragma unroll
;         for (int ti = 0; ti < 2; ++ti) { const bf16x8 A = *(const bf16x8*)(Wl + (32 * ti + r32) * 72 + 16 * ks + 8 * hi);
;             a1[ti] = __builtin_amdgcn_mfma_f32_32x32x16_bf16(A, B, a1[ti], 0, 0, 0); } }
; #pragma unroll
;     for (int ks = 0; ks < 8; ++ks) {
; #pragma unroll
;         for (int ti = 0; ti < 2; ++ti) { const bf16x8 A = *(const bf16x8*)(Ql + (32 * ti + r32) * 136 + 16 * ks + 8 * hi);
;             a2[ti] = __builtin_amdgcn_mfma_f32_32x32x16_bf16(A, cfr[ks], a2[ti], 0, 0, 0); } }
;     __syncthreads();
; #pragma unroll
;     for (int ti = 0; ti < 2; ++ti)
; #pragma unroll
;         for (int r = 0; r < 16; ++r) { const int t = 32 * ti + fox::crow(r, hi);
;             Hb[t * 260 + 32 * wid + r32] = (a1[ti][r] + sil[t] * a2[ti][r]) * rden[t]; }
.LBB0_970:
	s_or_b64 exec, exec, s[6:7]
	v_mul_lo_u32 v2, v18, s56
	v_add_u32_e32 v20, 0x100, v2
	v_lshlrev_b32_e32 v2, 1, v19
	v_mul_u32_u24_e32 v3, 0x90, v22
	v_add3_u32 v23, s58, v2, v3
	s_waitcnt lgkmcnt(0)
	ds_read_b128 v[2:5], v23
	v_add_u32_e32 v18, v18, v19
	v_and_b32_e32 v6, 56, v18
	v_lshl_add_u32 v6, v6, 1, v20
	ds_read_b128 v[24:27], v6 offset:34816
	ds_read_b128 v[28:31], v23 offset:32
	v_add_u32_e32 v19, 16, v18
	s_waitcnt lgkmcnt(0)
	v_mfma_f32_32x32x16_bf16 v[2:17], v[2:5], v[24:27], 0
	v_and_b32_e32 v19, 56, v19
	v_lshl_add_u32 v19, v19, 1, v20
	ds_read_b128 v[50:53], v19 offset:34816
	ds_read_b128 v[32:35], v23 offset:64
	ds_read_b128 v[54:57], v23 offset:4704
	v_bitop3_b32 v19, v18, 32, 56 bitop3:0x6c
	v_lshl_add_u32 v19, v19, 1, v20
	ds_read_b128 v[58:61], v19 offset:34816
	v_add_u32_e32 v18, 48, v18
	s_waitcnt lgkmcnt(0)
	v_mfma_f32_32x32x16_bf16 v[2:17], v[28:31], v[50:53], v[2:17]
	v_and_b32_e32 v18, 56, v18
	v_lshl_add_u32 v18, v18, 1, v20
	ds_read_b128 v[28:31], v23 offset:96
	ds_read_b128 v[114:117], v18 offset:34816
	v_mul_u32_u24_e32 v18, 0x110, v22
	v_add3_u32 v18, s3, v90, v18
	s_lshl_b32 s6, s8, 2
	v_mfma_f32_32x32x16_bf16 v[2:17], v[32:35], v[58:61], v[2:17]
	s_add_u32 s6, s42, s6
	s_addc_u32 s7, s43, 0
	s_lshl_b32 s9, s65, 7
	s_addk_i32 s9, 0x100
	s_add_i32 s10, s59, 0x100
	v_add_u32_e32 v20, s10, v90
	s_lshl_b32 s26, s8, 1
	s_waitcnt lgkmcnt(0)
	v_mfma_f32_32x32x16_bf16 v[2:17], v[28:31], v[114:117], v[2:17]
	ds_read_b128 v[28:31], v18
	ds_read_b128 v[118:121], v18 offset:32
	s_waitcnt vmcnt(0) lgkmcnt(0)
	v_mfma_f32_32x32x16_bf16 v[30:45], v[28:31], v[46:49], 0
	v_mfma_f32_32x32x16_bf16 v[30:45], v[118:121], v[86:89], v[30:45]
	ds_read_b128 v[118:121], v18 offset:64
	ds_read_b128 v[122:125], v18 offset:96
	s_waitcnt lgkmcnt(1)
	v_mfma_f32_32x32x16_bf16 v[30:45], v[118:121], v[82:85], v[30:45]
	ds_read_b128 v[118:121], v18 offset:128
	s_waitcnt lgkmcnt(1)
	v_mfma_f32_32x32x16_bf16 v[30:45], v[122:125], v[78:81], v[30:45]
	ds_read_b128 v[122:125], v23 offset:4608
	ds_read_b128 v[126:129], v23 offset:4640
	ds_read_b128 v[130:133], v23 offset:4672
	ds_read_b128 v[134:137], v18 offset:160
	s_waitcnt lgkmcnt(4)
	v_mfma_f32_32x32x16_bf16 v[30:45], v[118:121], v[74:77], v[30:45]
	ds_read_b128 v[118:121], v18 offset:8704
	ds_read_b128 v[138:141], v18 offset:8736
	ds_read_b128 v[142:145], v18 offset:8768
	ds_read_b128 v[146:149], v18 offset:8800
	ds_read_b128 v[150:153], v18 offset:8832
	ds_read_b128 v[154:157], v18 offset:8864
	ds_read_b128 v[158:161], v18 offset:192
	ds_read_b128 v[162:165], v18 offset:224
	s_waitcnt lgkmcnt(8)
	v_mfma_f32_32x32x16_bf16 v[30:45], v[134:137], v[70:73], v[30:45]
	ds_read_b128 v[134:137], v18 offset:8896
	ds_read_b128 v[166:169], v18 offset:8928
	v_lshl_add_u32 v18, v22, 2, s9
	s_add_i32 s9, s49, 0x100
	v_add_u32_e32 v19, s9, v90
	s_waitcnt lgkmcnt(0)
	s_barrier
	v_mfma_f32_32x32x16_bf16 v[30:45], v[158:161], v[66:69], v[30:45]
	ds_read_b32 v19, v19
	ds_read_b32 v20, v20
	v_mfma_f32_32x32x16_bf16 v[30:45], v[162:165], v[62:65], v[30:45]
	s_waitcnt lgkmcnt(1)
	s_nop 10
	v_fma_f32 v2, v30, v19, v2
	s_waitcnt lgkmcnt(0)
	v_mul_f32_e32 v2, v20, v2
	v_mad_u32_u24 v19, v21, s60, v18
	ds_write_b32 v19, v2
	v_lshl_or_b32 v2, v21, 2, 1
	v_lshlrev_b32_e32 v19, 2, v2
	v_add_u32_e32 v20, s9, v19
	v_add_u32_e32 v19, s10, v19
	ds_read_b32 v20, v20
	ds_read_b32 v19, v19
	v_mad_u32_u24 v2, v2, s61, v18
	s_waitcnt lgkmcnt(1)
	v_fma_f32 v3, v31, v20, v3
	s_waitcnt lgkmcnt(0)
	v_mul_f32_e32 v3, v19, v3
	ds_write_b32 v2, v3
	v_or_b32_e32 v3, 8, v90
	v_add_u32_e32 v18, s9, v3
	v_add_u32_e32 v3, s10, v3
	ds_read_b32 v18, v18
	ds_read_b32 v3, v3
	s_waitcnt lgkmcnt(1)
	v_fma_f32 v4, v32, v18, v4
	s_waitcnt lgkmcnt(0)
	v_mul_f32_e32 v3, v3, v4
	ds_write_b32 v2, v3 offset:1040
	v_or_b32_e32 v3, 12, v90
	v_add_u32_e32 v4, s9, v3
	v_add_u32_e32 v3, s10, v3
	ds_read_b32 v4, v4
	ds_read_b32 v3, v3
	s_waitcnt lgkmcnt(1)
	v_fma_f32 v4, v33, v4, v5
	s_waitcnt lgkmcnt(0)
	v_mul_f32_e32 v3, v3, v4
	ds_write_b32 v2, v3 offset:2080
	v_or_b32_e32 v3, 32, v90
	v_add_u32_e32 v4, s9, v3
	v_add_u32_e32 v3, s10, v3
	ds_read_b32 v4, v4
	ds_read_b32 v3, v3
	v_mfma_f32_32x32x16_bf16 v[18:33], v[122:125], v[24:27], 0
	s_waitcnt lgkmcnt(1)
	v_fma_f32 v4, v34, v4, v6
	s_waitcnt lgkmcnt(0)
	v_mul_f32_e32 v3, v3, v4
	ds_write_b32 v2, v3 offset:7280
	v_or_b32_e32 v3, 36, v90
	v_add_u32_e32 v4, s9, v3
	v_add_u32_e32 v3, s10, v3
	ds_read_b32 v4, v4
	ds_read_b32 v3, v3
	v_mfma_f32_32x32x16_bf16 v[18:33], v[126:129], v[50:53], v[18:33]
	s_waitcnt lgkmcnt(1)
	v_fma_f32 v4, v35, v4, v7
	s_waitcnt lgkmcnt(0)
	v_mul_f32_e32 v3, v3, v4
	ds_write_b32 v2, v3 offset:8320
	v_or_b32_e32 v3, 40, v90
	v_add_u32_e32 v4, s9, v3
	v_add_u32_e32 v3, s10, v3
	ds_read_b32 v4, v4
	ds_read_b32 v3, v3
	v_mfma_f32_32x32x16_bf16 v[18:33], v[130:133], v[58:61], v[18:33]
	s_waitcnt lgkmcnt(1)
	v_fma_f32 v4, v36, v4, v8
	s_waitcnt lgkmcnt(0)
	v_mul_f32_e32 v3, v3, v4
	ds_write_b32 v2, v3 offset:9360
	v_or_b32_e32 v3, 44, v90
	v_add_u32_e32 v4, s9, v3
	v_add_u32_e32 v3, s10, v3
	ds_read_b32 v4, v4
	ds_read_b32 v3, v3
	v_mfma_f32_32x32x16_bf16 v[18:33], v[54:57], v[114:117], v[18:33]
	v_add_u32_e32 v36, s64, v109
	s_waitcnt lgkmcnt(1)
	v_fma_f32 v4, v37, v4, v9
	s_waitcnt lgkmcnt(0)
	v_mul_f32_e32 v3, v3, v4
	ds_write_b32 v2, v3 offset:10400
	v_or_b32_e32 v3, 64, v90
	v_add_u32_e32 v4, s9, v3
	v_add_u32_e32 v3, s10, v3
	ds_read_b32 v4, v4
	ds_read_b32 v3, v3
	v_mfma_f32_32x32x16_bf16 v[46:61], v[118:121], v[46:49], 0
	v_mov_b64_e32 v[8:9], s[14:15]
	s_waitcnt lgkmcnt(1)
	v_fma_f32 v4, v38, v4, v10
	s_waitcnt lgkmcnt(0)
; __device__ __forceinline__ int crow(int r, int hi) { return (r & 3) + 8 * (r >> 2) + 4 * hi; }
; __device__ __forceinline__ void mlstm_out_unit(const Params& P, int l, int h, int n, char* lds) {
;     ...
;     __syncthreads();
; #pragma unroll
;     for (int ti = 0; ti < 2; ++ti)
; #pragma unroll
;         for (int r = 0; r < 16; ++r) { const int t = 32 * ti + fox::crow(r, hi);
;             Hb[t * 260 + 32 * wid + r32] = (a1[ti][r] + sil[t] * a2[ti][r]) * rden[t]; }
;     __syncthreads();
	v_mul_f32_e32 v3, v3, v4
	ds_write_b32 v2, v3 offset:15600
	v_or_b32_e32 v3, 0x44, v90
	v_add_u32_e32 v4, s9, v3
	v_add_u32_e32 v3, s10, v3
	ds_read_b32 v4, v4
	ds_read_b32 v3, v3
	v_mfma_f32_32x32x16_bf16 v[46:61], v[138:141], v[86:89], v[46:61]
	s_waitcnt lgkmcnt(1)
	v_fma_f32 v4, v39, v4, v11
	s_waitcnt lgkmcnt(0)
	v_mul_f32_e32 v3, v3, v4
	ds_write_b32 v2, v3 offset:16640
	v_or_b32_e32 v3, 0x48, v90
	v_add_u32_e32 v4, s9, v3
	v_add_u32_e32 v3, s10, v3
	ds_read_b32 v4, v4
	ds_read_b32 v3, v3
	v_mfma_f32_32x32x16_bf16 v[46:61], v[142:145], v[82:85], v[46:61]
	s_waitcnt lgkmcnt(1)
	v_fma_f32 v4, v40, v4, v12
	s_waitcnt lgkmcnt(0)
	v_mul_f32_e32 v3, v3, v4
	ds_write_b32 v2, v3 offset:17680
	v_or_b32_e32 v3, 0x4c, v90
	v_add_u32_e32 v4, s9, v3
	v_add_u32_e32 v3, s10, v3
	ds_read_b32 v4, v4
	ds_read_b32 v3, v3
	v_mfma_f32_32x32x16_bf16 v[46:61], v[146:149], v[78:81], v[46:61]
	s_waitcnt lgkmcnt(1)
	v_fma_f32 v4, v41, v4, v13
	s_waitcnt lgkmcnt(0)
	v_mul_f32_e32 v3, v3, v4
	ds_write_b32 v2, v3 offset:18720
	v_or_b32_e32 v3, 0x60, v90
	v_add_u32_e32 v4, s9, v3
	v_add_u32_e32 v3, s10, v3
	ds_read_b32 v4, v4
	ds_read_b32 v3, v3
	v_mfma_f32_32x32x16_bf16 v[46:61], v[150:153], v[74:77], v[46:61]
	s_waitcnt lgkmcnt(1)
	v_fma_f32 v4, v42, v4, v14
	s_waitcnt lgkmcnt(0)
	v_mul_f32_e32 v3, v3, v4
	ds_write_b32 v2, v3 offset:23920
	v_or_b32_e32 v3, 0x64, v90
	v_add_u32_e32 v4, s9, v3
	v_add_u32_e32 v3, s10, v3
	ds_read_b32 v4, v4
	ds_read_b32 v3, v3
	v_mfma_f32_32x32x16_bf16 v[46:61], v[154:157], v[70:73], v[46:61]
	s_waitcnt lgkmcnt(1)
	v_fma_f32 v4, v43, v4, v15
	s_waitcnt lgkmcnt(0)
	v_mul_f32_e32 v3, v3, v4
	ds_write_b32 v2, v3 offset:24960
	v_or_b32_e32 v3, 0x68, v90
	v_add_u32_e32 v4, s9, v3
	v_add_u32_e32 v3, s10, v3
	ds_read_b32 v4, v4
	ds_read_b32 v3, v3
	v_mfma_f32_32x32x16_bf16 v[46:61], v[134:137], v[66:69], v[46:61]
	s_waitcnt lgkmcnt(1)
	v_fma_f32 v4, v44, v4, v16
	s_waitcnt lgkmcnt(0)
	v_mul_f32_e32 v3, v3, v4
	ds_write_b32 v2, v3 offset:26000
	v_or_b32_e32 v3, 0x6c, v90
	v_add_u32_e32 v4, s9, v3
	v_add_u32_e32 v3, s10, v3
	ds_read_b32 v4, v4
	ds_read_b32 v3, v3
	v_mfma_f32_32x32x16_bf16 v[46:61], v[166:169], v[62:65], v[46:61]
	s_waitcnt lgkmcnt(1)
	v_fmac_f32_e32 v17, v45, v4
	s_waitcnt lgkmcnt(0)
	v_mul_f32_e32 v3, v3, v17
	ds_write_b32 v2, v3 offset:27040
	v_or_b32_e32 v3, 0x80, v90
	v_add_u32_e32 v4, s9, v3
	v_add_u32_e32 v3, s10, v3
	ds_read_b32 v4, v4
	ds_read_b32 v3, v3
	s_waitcnt lgkmcnt(1)
	s_nop 0
	v_fma_f32 v4, v46, v4, v18
	s_waitcnt lgkmcnt(0)
	v_mul_f32_e32 v3, v3, v4
	ds_write_b32 v2, v3 offset:32240
	v_or_b32_e32 v3, 0x84, v90
	v_add_u32_e32 v4, s9, v3
	v_add_u32_e32 v3, s10, v3
	ds_read_b32 v4, v4
	ds_read_b32 v3, v3
	s_waitcnt lgkmcnt(1)
	v_fma_f32 v4, v47, v4, v19
	s_waitcnt lgkmcnt(0)
	v_mul_f32_e32 v3, v3, v4
	ds_write_b32 v2, v3 offset:33280
	v_or_b32_e32 v3, 0x88, v90
	v_add_u32_e32 v4, s9, v3
	v_add_u32_e32 v3, s10, v3
	ds_read_b32 v4, v4
	ds_read_b32 v3, v3
	s_waitcnt lgkmcnt(1)
	v_fma_f32 v4, v48, v4, v20
	s_waitcnt lgkmcnt(0)
	v_mul_f32_e32 v3, v3, v4
	ds_write_b32 v2, v3 offset:34320
	v_or_b32_e32 v3, 0x8c, v90
	v_add_u32_e32 v4, s9, v3
	v_add_u32_e32 v3, s10, v3
	ds_read_b32 v4, v4
	ds_read_b32 v3, v3
	s_waitcnt lgkmcnt(1)
	v_fma_f32 v4, v49, v4, v21
	s_waitcnt lgkmcnt(0)
	v_mul_f32_e32 v3, v3, v4
	ds_write_b32 v2, v3 offset:35360
	v_or_b32_e32 v3, 0xa0, v90
	v_add_u32_e32 v4, s9, v3
	v_add_u32_e32 v3, s10, v3
	ds_read_b32 v4, v4
	ds_read_b32 v3, v3
	s_waitcnt lgkmcnt(1)
	v_fma_f32 v4, v50, v4, v22
	s_waitcnt lgkmcnt(0)
	v_mul_f32_e32 v3, v3, v4
	ds_write_b32 v2, v3 offset:40560
	v_or_b32_e32 v3, 0xa4, v90
	v_add_u32_e32 v4, s9, v3
	v_add_u32_e32 v3, s10, v3
	ds_read_b32 v4, v4
	ds_read_b32 v3, v3
	s_waitcnt lgkmcnt(1)
	v_fma_f32 v4, v51, v4, v23
	s_waitcnt lgkmcnt(0)
	v_mul_f32_e32 v3, v3, v4
	ds_write_b32 v2, v3 offset:41600
	v_or_b32_e32 v3, 0xa8, v90
	v_add_u32_e32 v4, s9, v3
	v_add_u32_e32 v3, s10, v3
	ds_read_b32 v4, v4
	ds_read_b32 v3, v3
	s_waitcnt lgkmcnt(1)
	v_fma_f32 v4, v52, v4, v24
	s_waitcnt lgkmcnt(0)
	v_mul_f32_e32 v3, v3, v4
	ds_write_b32 v2, v3 offset:42640
	v_or_b32_e32 v3, 0xac, v90
	v_add_u32_e32 v4, s9, v3
	v_add_u32_e32 v3, s10, v3
	ds_read_b32 v4, v4
	ds_read_b32 v3, v3
	s_waitcnt lgkmcnt(1)
	v_fma_f32 v4, v53, v4, v25
	s_waitcnt lgkmcnt(0)
	v_mul_f32_e32 v3, v3, v4
	ds_write_b32 v2, v3 offset:43680
	v_or_b32_e32 v3, 0xc0, v90
	v_add_u32_e32 v4, s9, v3
	v_add_u32_e32 v3, s10, v3
	ds_read_b32 v4, v4
	ds_read_b32 v3, v3
	s_waitcnt lgkmcnt(1)
	v_fma_f32 v4, v54, v4, v26
	s_waitcnt lgkmcnt(0)
	v_mul_f32_e32 v3, v3, v4
	ds_write_b32 v2, v3 offset:48880
	v_or_b32_e32 v3, 0xc4, v90
	v_add_u32_e32 v4, s9, v3
	v_add_u32_e32 v3, s10, v3
	ds_read_b32 v4, v4
	ds_read_b32 v3, v3
	s_waitcnt lgkmcnt(1)
	v_fma_f32 v4, v55, v4, v27
	s_waitcnt lgkmcnt(0)
	v_mul_f32_e32 v3, v3, v4
	ds_write_b32 v2, v3 offset:49920
	v_or_b32_e32 v3, 0xc8, v90
	v_add_u32_e32 v4, s9, v3
	v_add_u32_e32 v3, s10, v3
	ds_read_b32 v4, v4
	ds_read_b32 v3, v3
	s_waitcnt lgkmcnt(1)
	v_fma_f32 v4, v56, v4, v28
	s_waitcnt lgkmcnt(0)
	v_mul_f32_e32 v3, v3, v4
	ds_write_b32 v2, v3 offset:50960
	v_or_b32_e32 v3, 0xcc, v90
	v_add_u32_e32 v4, s9, v3
	v_add_u32_e32 v3, s10, v3
	ds_read_b32 v4, v4
	ds_read_b32 v3, v3
	s_waitcnt lgkmcnt(1)
	v_fma_f32 v4, v57, v4, v29
	s_waitcnt lgkmcnt(0)
	v_mul_f32_e32 v3, v3, v4
	ds_write_b32 v2, v3 offset:52000
	v_or_b32_e32 v3, 0xe0, v90
	v_add_u32_e32 v4, s9, v3
	v_add_u32_e32 v3, s10, v3
	ds_read_b32 v4, v4
	ds_read_b32 v3, v3
	s_waitcnt lgkmcnt(1)
	v_fma_f32 v4, v58, v4, v30
	s_waitcnt lgkmcnt(0)
	v_mul_f32_e32 v3, v3, v4
	ds_write_b32 v2, v3 offset:57200
	v_or_b32_e32 v3, 0xe4, v90
	v_add_u32_e32 v4, s9, v3
	v_add_u32_e32 v3, s10, v3
	ds_read_b32 v4, v4
	ds_read_b32 v3, v3
	s_waitcnt lgkmcnt(1)
	v_fma_f32 v4, v59, v4, v31
	s_waitcnt lgkmcnt(0)
	v_mul_f32_e32 v3, v3, v4
	ds_write_b32 v2, v3 offset:58240
	v_or_b32_e32 v3, 0xe8, v90
	v_add_u32_e32 v4, s9, v3
	v_add_u32_e32 v3, s10, v3
	ds_read_b32 v4, v4
	ds_read_b32 v3, v3
	s_waitcnt lgkmcnt(1)
	v_fma_f32 v4, v60, v4, v32
	s_waitcnt lgkmcnt(0)
	v_mul_f32_e32 v3, v3, v4
	ds_write_b32 v2, v3 offset:59280
	v_or_b32_e32 v3, 0xec, v90
	v_add_u32_e32 v4, s9, v3
	v_add_u32_e32 v3, s10, v3
	ds_read_b32 v4, v4
	ds_read_b32 v3, v3
	v_mad_i64_i32 v[8:9], s[10:11], v36, s50, v[8:9]
	v_lshl_add_u64 v[8:9], v[8:9], 0, s[26:27]
	s_waitcnt lgkmcnt(1)
	v_fmac_f32_e32 v33, v61, v4
	v_lshlrev_b32_e32 v90, 3, v93
	s_waitcnt lgkmcnt(0)
	v_mul_f32_e32 v3, v3, v33
	v_lshl_add_u64 v[44:45], v[8:9], 0, v[90:91]
	ds_write_b32 v2, v3 offset:60320
	v_mul_lo_u32 v2, v109, s61
	v_add_co_u32_e32 v8, vcc, s51, v44
	v_add3_u32 v37, s3, v2, v92
	s_nop 0
	v_addc_co_u32_e32 v9, vcc, 0, v45, vcc
	s_waitcnt lgkmcnt(0)
	s_barrier
; __device__ __forceinline__ unsigned cvt_pk_bf16(float lo, float hi) { unsigned r; asm volatile("v_cvt_pk_bf16_f32 %0, %1, %2" : "=v"(r) : "v"(lo), "v"(hi)); return r; }
; __device__ __forceinline__ float bflo(unsigned w) { return __uint_as_float(w << 16); }
; __device__ __forceinline__ float bfhi(unsigned w) { return __uint_as_float(w & 0xffff0000u); }
; __device__ __forceinline__ float sigmoidf(float x) { return 1.f / (1.f + __expf(-x)); }
; __device__ __forceinline__ void mlstm_out_unit(const Params& P, int l, int h, int n, char* lds) {
;     ...
;     {
;         const int t = tid >> 3, p = tid & 7; f32x4 hv[8]; float ss = 0.f;
; #pragma unroll
;         for (int j = 0; j < 8; ++j) { hv[j] = *(const f32x4*)(Hb + t * 260 + 32 * j + 4 * p); ss += (hv[j][0] * hv[j][0] + hv[j][1] * hv[j][1]) + (hv[j][2] * hv[j][2] + hv[j][3] * hv[j][3]); }
;         ss += __shfl_xor(ss, 1); ss += __shfl_xor(ss, 2); ss += __shfl_xor(ss, 4);
;         const float rs = rsqrtf(ss * (1.f / 256.f) + RMS_EPS);
;         const size_t row = (size_t)(t0 + t);
; #pragma unroll
;         for (int j = 0; j < 8; ++j) { const int e = 32 * j + 4 * p; const f32x4 gn = *(const f32x4*)(mnorm + e);
;             const u32x2 mo = *(const u32x2*)(PROJ + row * PW + C_MO + h * 256 + e);
;             const float o0 = hv[j][0] * rs * gn[0] * sigmoidf(bflo(mo.x)), o1 = hv[j][1] * rs * gn[1] * sigmoidf(bfhi(mo.x));
;             const float o2 = hv[j][2] * rs * gn[2] * sigmoidf(bflo(mo.y)), o3 = hv[j][3] * rs * gn[3] * sigmoidf(bfhi(mo.y));
;             u32x2 w; w.x = cvt_pk_bf16(o0, o1); w.y = cvt_pk_bf16(o2, o3);
;             *(u32x2*)(MIX + row * DM + h * 256 + e) = w; }
	ds_read_b128 v[30:33], v37
	ds_read_b128 v[26:29], v37 offset:128
	global_load_dwordx2 v[46:47], v[8:9], off
	global_load_dwordx2 v[196:197], v[8:9], off offset:64
	global_load_dwordx2 v[198:199], v[8:9], off offset:128
	global_load_dwordx2 v[200:201], v[8:9], off offset:192
	global_load_dwordx2 v[202:203], v[8:9], off offset:256
	global_load_dwordx2 v[204:205], v[8:9], off offset:320
	global_load_dwordx2 v[206:207], v[8:9], off offset:384
	global_load_dwordx2 v[208:209], v[8:9], off offset:448
	v_mov_b32_e32 v93, v91
	v_lshl_add_u64 v[34:35], s[6:7], 0, v[92:93]
	global_load_dwordx4 v[40:43], v[34:35], off
	global_load_dwordx4 v[212:215], v[34:35], off offset:128
	global_load_dwordx4 v[216:219], v[34:35], off offset:256
	global_load_dwordx4 v[220:223], v[34:35], off offset:384
	global_load_dwordx4 v[224:227], v[34:35], off offset:512
	global_load_dwordx4 v[228:231], v[34:35], off offset:640
	global_load_dwordx4 v[232:235], v[34:35], off offset:768
	global_load_dwordx4 v[236:239], v[34:35], off offset:896
	ds_read_b128 v[22:25], v37 offset:256
	ds_read_b128 v[18:21], v37 offset:384
	s_waitcnt lgkmcnt(0)
	v_mov_b32_e32 v4, v31
	v_mov_b32_e32 v5, v27
	v_mov_b32_e32 v2, v30
	v_mov_b32_e32 v3, v26
	v_pk_mul_f32 v[4:5], v[4:5], v[4:5]
	v_mov_b32_e32 v6, v33
	v_mov_b32_e32 v7, v29
	v_pk_fma_f32 v[2:3], v[2:3], v[2:3], v[4:5]
	v_mov_b32_e32 v4, v32
	v_mov_b32_e32 v5, v28
	v_pk_mul_f32 v[6:7], v[6:7], v[6:7]
	ds_read_b128 v[14:17], v37 offset:512
	ds_read_b128 v[10:13], v37 offset:640
	v_pk_fma_f32 v[4:5], v[4:5], v[4:5], v[6:7]
	v_pk_mul_f32 v[6:7], v[22:23], v[22:23]
	v_pk_add_f32 v[2:3], v[2:3], v[4:5]
	v_pk_mul_f32 v[4:5], v[24:25], v[24:25]
	v_pk_add_f32 v[2:3], v[2:3], v[2:3] op_sel:[0,1] op_sel_hi:[1,0]
	v_pk_mov_b32 v[8:9], v[6:7], v[4:5] op_sel:[1,0]
	v_mov_b32_e32 v7, v5
	v_pk_add_f32 v[4:5], v[8:9], v[6:7]
	s_waitcnt lgkmcnt(0)
	v_mul_f32_e32 v6, v14, v14
	v_mul_f32_e32 v7, v15, v15
	v_pk_add_f32 v[4:5], v[4:5], v[4:5] op_sel:[0,1] op_sel_hi:[1,0]
	v_mov_b32_e32 v3, v6
	v_mov_b32_e32 v5, v7
	v_pk_add_f32 v[2:3], v[2:3], v[4:5]
	v_mul_f32_e32 v4, v19, v19
	v_mul_f32_e32 v6, v21, v21
	v_mul_f32_e32 v8, v16, v16
	v_mul_f32_e32 v9, v17, v17
	v_pk_fma_f32 v[4:5], v[18:19], v[18:19], v[4:5] op_sel_hi:[1,1,0]
	v_pk_fma_f32 v[6:7], v[20:21], v[20:21], v[6:7] op_sel_hi:[1,1,0]
	v_mov_b32_e32 v5, v8
	v_mov_b32_e32 v7, v9
	v_pk_add_f32 v[4:5], v[4:5], v[6:7]
	v_pk_mul_f32 v[48:49], v[12:13], v[12:13]
	v_pk_add_f32 v[38:39], v[2:3], v[4:5]
	ds_read_b128 v[6:9], v37 offset:768
	ds_read_b128 v[2:5], v37 offset:896
	v_pk_mul_f32 v[50:51], v[10:11], v[10:11]
	v_pk_add_f32 v[38:39], v[38:39], v[38:39] op_sel:[0,1] op_sel_hi:[1,0]
	v_pk_mov_b32 v[52:53], v[50:51], v[48:49] op_sel:[1,0]
	v_mov_b32_e32 v51, v49
	v_pk_add_f32 v[48:49], v[52:53], v[50:51]
	s_waitcnt lgkmcnt(0)
	v_mul_f32_e32 v37, v2, v2
	v_mul_f32_e32 v50, v3, v3
	v_pk_add_f32 v[48:49], v[48:49], v[48:49] op_sel:[0,1] op_sel_hi:[1,0]
	v_mov_b32_e32 v39, v37
	v_mov_b32_e32 v49, v50
	v_pk_add_f32 v[38:39], v[38:39], v[48:49]
	v_mul_f32_e32 v48, v7, v7
	v_mul_f32_e32 v51, v4, v4
	v_pk_fma_f32 v[48:49], v[6:7], v[6:7], v[48:49] op_sel_hi:[1,1,0]
	v_mul_f32_e32 v50, v9, v9
	v_mul_f32_e32 v52, v5, v5
	v_mov_b32_e32 v49, v51
	v_pk_fma_f32 v[50:51], v[8:9], v[8:9], v[50:51] op_sel_hi:[1,1,0]
	s_add_u32 s6, s40, s26
	v_mov_b32_e32 v51, v52
	v_pk_add_f32 v[48:49], v[48:49], v[50:51]
	s_addc_u32 s7, s41, 0
	v_pk_add_f32 v[38:39], v[38:39], v[48:49]
	s_nop 0
	v_add_f32_e32 v37, v38, v39
	ds_bpermute_b32 v38, v110, v37
	s_waitcnt lgkmcnt(0)
	v_add_f32_e32 v37, v37, v38
	ds_bpermute_b32 v38, v111, v37
	s_waitcnt vmcnt(0)
	v_lshlrev_b32_e32 v39, 16, v46
	s_waitcnt lgkmcnt(0)
	v_add_f32_e32 v37, v37, v38
	ds_bpermute_b32 v38, v112, v37
	v_mul_f32_e32 v39, 0xbfb8aa3b, v39
	v_exp_f32_e32 v39, v39
	s_waitcnt lgkmcnt(0)
	v_add_f32_e32 v37, v37, v38
	v_fmamk_f32 v37, v37, 0x3b800000, v104
	v_mul_f32_e32 v38, 0x4b800000, v37
	v_cmp_gt_f32_e32 vcc, s62, v37
	v_add_f32_e32 v39, 1.0, v39
	s_nop 0
	v_cndmask_b32_e32 v37, v37, v38, vcc
	v_rsq_f32_e32 v37, v37
	s_nop 0
	v_mul_f32_e32 v38, 0x45800000, v37
	v_cndmask_b32_e32 v38, v37, v38, vcc
	v_ashrrev_i32_e32 v37, 31, v36
	v_lshlrev_b64 v[36:37], 12, v[36:37]
	v_lshl_add_u64 v[48:49], s[6:7], 0, v[36:37]
	v_div_scale_f32 v50, s[6:7], v39, v39, 1.0
	v_rcp_f32_e32 v51, v50
	v_mul_f32_e32 v30, v30, v38
	v_mul_f32_e32 v30, v40, v30
	v_lshl_add_u64 v[36:37], v[44:45], 0, s[34:35]
	v_fma_f32 v40, -v50, v51, 1.0
	v_fmac_f32_e32 v51, v40, v51
	v_div_scale_f32 v40, vcc, 1.0, v39, 1.0
	v_mul_f32_e32 v44, v40, v51
	v_fma_f32 v45, -v50, v44, v40
	v_fmac_f32_e32 v44, v45, v51
	v_and_b32_e32 v45, 0xffff0000, v46
	v_mul_f32_e32 v45, 0xbfb8aa3b, v45
	v_exp_f32_e32 v45, v45
	v_fma_f32 v40, -v50, v44, v40
	v_div_fmas_f32 v40, v40, v51, v44
	v_div_fixup_f32 v39, v40, v39, 1.0
	v_add_f32_e32 v40, 1.0, v45
	v_div_scale_f32 v44, s[6:7], v40, v40, 1.0
	v_rcp_f32_e32 v45, v44
	v_mul_f32_e32 v30, v39, v30
	v_mul_f32_e32 v31, v31, v38
	v_mul_f32_e32 v31, v41, v31
	v_fma_f32 v39, -v44, v45, 1.0
	v_fmac_f32_e32 v45, v39, v45
	v_div_scale_f32 v39, vcc, 1.0, v40, 1.0
	v_mul_f32_e32 v41, v39, v45
	v_fma_f32 v46, -v44, v41, v39
	v_fmac_f32_e32 v41, v46, v45
	v_fma_f32 v39, -v44, v41, v39
	v_lshlrev_b32_e32 v44, 16, v47
	v_mul_f32_e32 v44, 0xbfb8aa3b, v44
	v_exp_f32_e32 v44, v44
	v_div_fmas_f32 v39, v39, v45, v41
	v_div_fixup_f32 v39, v39, v40, 1.0
	v_mul_f32_e32 v31, v39, v31
	v_add_f32_e32 v40, 1.0, v44
	v_div_scale_f32 v41, s[6:7], v40, v40, 1.0
	v_rcp_f32_e32 v44, v41
	v_mul_f32_e32 v32, v32, v38
	v_mul_f32_e32 v32, v42, v32
	v_mul_f32_e32 v33, v33, v38
	v_fma_f32 v39, -v41, v44, 1.0
; __device__ __forceinline__ unsigned cvt_pk_bf16(float lo, float hi) { unsigned r; asm volatile("v_cvt_pk_bf16_f32 %0, %1, %2" : "=v"(r) : "v"(lo), "v"(hi)); return r; }
; __device__ __forceinline__ float bflo(unsigned w) { return __uint_as_float(w << 16); }
; __device__ __forceinline__ float bfhi(unsigned w) { return __uint_as_float(w & 0xffff0000u); }
; __device__ __forceinline__ float sigmoidf(float x) { return 1.f / (1.f + __expf(-x)); }
; __device__ __forceinline__ void mlstm_out_unit(const Params& P, int l, int h, int n, char* lds) {
;     ...
;         for (int j = 0; j < 8; ++j) { const int e = 32 * j + 4 * p; const f32x4 gn = *(const f32x4*)(mnorm + e);
;             const u32x2 mo = *(const u32x2*)(PROJ + row * PW + C_MO + h * 256 + e);
;             const float o0 = hv[j][0] * rs * gn[0] * sigmoidf(bflo(mo.x)), o1 = hv[j][1] * rs * gn[1] * sigmoidf(bfhi(mo.x));
;             const float o2 = hv[j][2] * rs * gn[2] * sigmoidf(bflo(mo.y)), o3 = hv[j][3] * rs * gn[3] * sigmoidf(bfhi(mo.y));
;             u32x2 w; w.x = cvt_pk_bf16(o0, o1); w.y = cvt_pk_bf16(o2, o3);
;             *(u32x2*)(MIX + row * DM + h * 256 + e) = w; }
	v_fmac_f32_e32 v44, v39, v44
	v_div_scale_f32 v39, vcc, 1.0, v40, 1.0
	v_mul_f32_e32 v42, v39, v44
	v_fma_f32 v45, -v41, v42, v39
	v_fmac_f32_e32 v42, v45, v44
	v_fma_f32 v39, -v41, v42, v39
	v_and_b32_e32 v41, 0xffff0000, v47
	v_mul_f32_e32 v41, 0xbfb8aa3b, v41
	v_exp_f32_e32 v41, v41
	v_div_fmas_f32 v39, v39, v44, v42
	v_div_fixup_f32 v39, v39, v40, 1.0
	v_mul_f32_e32 v32, v39, v32
	v_add_f32_e32 v40, 1.0, v41
	v_div_scale_f32 v41, s[6:7], v40, v40, 1.0
	v_rcp_f32_e32 v42, v41
	v_mul_f32_e32 v33, v43, v33
	v_cvt_pk_bf16_f32 v30, v30, v31
	v_mul_f32_e32 v26, v26, v38
	v_fma_f32 v39, -v41, v42, 1.0
	v_fmac_f32_e32 v42, v39, v42
	v_div_scale_f32 v39, vcc, 1.0, v40, 1.0
	v_mul_f32_e32 v43, v39, v42
	v_fma_f32 v44, -v41, v43, v39
	v_fmac_f32_e32 v43, v44, v42
	v_fma_f32 v39, -v41, v43, v39
	v_div_fmas_f32 v39, v39, v42, v43
	v_div_fixup_f32 v39, v39, v40, 1.0
	v_mul_f32_e32 v33, v39, v33
	v_cvt_pk_bf16_f32 v31, v32, v33
	v_lshl_add_u64 v[32:33], v[48:49], 0, v[90:91]
	v_add_co_u32_e32 v40, vcc, s63, v32
	v_mul_f32_e32 v27, v27, v38
	s_nop 0
	v_addc_co_u32_e32 v41, vcc, 0, v33, vcc
	global_store_dwordx2 v[40:41], v[30:31], off
	s_nop 0
	v_mul_f32_e32 v28, v28, v38
	v_mul_f32_e32 v29, v29, v38
	v_mul_f32_e32 v22, v22, v38
	v_mul_f32_e32 v23, v23, v38
	v_mul_f32_e32 v24, v24, v38
	v_mul_f32_e32 v25, v25, v38
	v_mul_f32_e32 v18, v18, v38
	v_mul_f32_e32 v19, v19, v38
	v_mul_f32_e32 v20, v20, v38
	v_mul_f32_e32 v21, v21, v38
	v_mul_f32_e32 v14, v14, v38
	v_mul_f32_e32 v15, v15, v38
	v_mul_f32_e32 v16, v16, v38
	v_mul_f32_e32 v17, v17, v38
	v_mul_f32_e32 v10, v10, v38
	v_mul_f32_e32 v11, v11, v38
	v_mul_f32_e32 v12, v12, v38
	v_mul_f32_e32 v13, v13, v38
	v_mul_f32_e32 v6, v6, v38
	v_mul_f32_e32 v7, v7, v38
	v_mul_f32_e32 v8, v8, v38
	v_mul_f32_e32 v9, v9, v38
	v_mul_f32_e32 v2, v2, v38
	v_mul_f32_e32 v3, v3, v38
	v_mul_f32_e32 v4, v4, v38
	v_mul_f32_e32 v5, v5, v38
	s_nop 1
	v_mov_b32_e32 v44, v196
	v_mov_b32_e32 v45, v197
	v_mov_b32_e32 v40, v212
	v_mov_b32_e32 v41, v213
	v_mov_b32_e32 v42, v214
	v_mov_b32_e32 v43, v215
	v_lshlrev_b32_e32 v30, 16, v44
	v_mul_f32_e32 v30, 0xbfb8aa3b, v30
	v_exp_f32_e32 v30, v30
	v_mul_f32_e32 v26, v40, v26
	v_mul_f32_e32 v27, v41, v27
	v_mul_f32_e32 v28, v42, v28
	v_add_f32_e32 v39, 1.0, v30
	v_div_scale_f32 v46, s[6:7], v39, v39, 1.0
	v_rcp_f32_e32 v47, v46
	v_lshl_add_u64 v[30:31], v[32:33], 0, s[36:37]
	v_mul_f32_e32 v29, v43, v29
	v_fma_f32 v32, -v46, v47, 1.0
	v_fmac_f32_e32 v47, v32, v47
	v_div_scale_f32 v32, vcc, 1.0, v39, 1.0
	v_mul_f32_e32 v33, v32, v47
	v_fma_f32 v40, -v46, v33, v32
	v_fmac_f32_e32 v33, v40, v47
	v_and_b32_e32 v40, 0xffff0000, v44
	v_mul_f32_e32 v40, 0xbfb8aa3b, v40
	v_exp_f32_e32 v40, v40
	v_fma_f32 v32, -v46, v33, v32
	v_div_fmas_f32 v32, v32, v47, v33
	v_div_fixup_f32 v32, v32, v39, 1.0
	v_add_f32_e32 v33, 1.0, v40
	v_div_scale_f32 v39, s[6:7], v33, v33, 1.0
	v_rcp_f32_e32 v40, v39
	v_mul_f32_e32 v26, v32, v26
	v_fma_f32 v32, -v39, v40, 1.0
	v_fmac_f32_e32 v40, v32, v40
	v_div_scale_f32 v32, vcc, 1.0, v33, 1.0
	v_mul_f32_e32 v41, v32, v40
	v_fma_f32 v44, -v39, v41, v32
	v_fmac_f32_e32 v41, v44, v40
	v_fma_f32 v32, -v39, v41, v32
	v_lshlrev_b32_e32 v39, 16, v45
	v_mul_f32_e32 v39, 0xbfb8aa3b, v39
	v_exp_f32_e32 v39, v39
	v_div_fmas_f32 v32, v32, v40, v41
	v_div_fixup_f32 v32, v32, v33, 1.0
	v_mul_f32_e32 v27, v32, v27
	v_add_f32_e32 v33, 1.0, v39
	v_div_scale_f32 v39, s[6:7], v33, v33, 1.0
	v_rcp_f32_e32 v40, v39
	v_cvt_pk_bf16_f32 v26, v26, v27
	s_nop 0
	v_fma_f32 v32, -v39, v40, 1.0
	v_fmac_f32_e32 v40, v32, v40
	v_div_scale_f32 v32, vcc, 1.0, v33, 1.0
	v_mul_f32_e32 v41, v32, v40
	v_fma_f32 v42, -v39, v41, v32
	v_fmac_f32_e32 v41, v42, v40
	v_fma_f32 v32, -v39, v41, v32
	v_and_b32_e32 v39, 0xffff0000, v45
	v_mul_f32_e32 v39, 0xbfb8aa3b, v39
	v_exp_f32_e32 v39, v39
	v_div_fmas_f32 v32, v32, v40, v41
	v_div_fixup_f32 v32, v32, v33, 1.0
	v_mul_f32_e32 v28, v32, v28
	v_add_f32_e32 v33, 1.0, v39
	v_div_scale_f32 v39, s[6:7], v33, v33, 1.0
	v_rcp_f32_e32 v40, v39
	s_nop 0
	v_fma_f32 v32, -v39, v40, 1.0
	v_fmac_f32_e32 v40, v32, v40
	v_div_scale_f32 v32, vcc, 1.0, v33, 1.0
	v_mul_f32_e32 v41, v32, v40
	v_fma_f32 v42, -v39, v41, v32
	v_fmac_f32_e32 v41, v42, v40
	v_fma_f32 v32, -v39, v41, v32
	v_div_fmas_f32 v32, v32, v40, v41
	v_div_fixup_f32 v32, v32, v33, 1.0
	v_mul_f32_e32 v29, v32, v29
	v_cvt_pk_bf16_f32 v27, v28, v29
	global_store_dwordx2 v[30:31], v[26:27], off offset:64
	s_nop 0
	s_nop 1
	v_mov_b32_e32 v32, v198
	v_mov_b32_e32 v33, v199
	v_mov_b32_e32 v26, v216
	v_mov_b32_e32 v27, v217
	v_mov_b32_e32 v28, v218
	v_mov_b32_e32 v29, v219
	v_lshlrev_b32_e32 v39, 16, v32
	v_mul_f32_e32 v39, 0xbfb8aa3b, v39
	v_exp_f32_e32 v39, v39
	v_mul_f32_e32 v22, v26, v22
	v_and_b32_e32 v32, 0xffff0000, v32
	v_mul_f32_e32 v32, 0xbfb8aa3b, v32
	v_add_f32_e32 v39, 1.0, v39
	v_div_scale_f32 v40, s[6:7], v39, v39, 1.0
	v_rcp_f32_e32 v41, v40
	v_exp_f32_e32 v32, v32
	v_mul_f32_e32 v23, v27, v23
	v_mul_f32_e32 v24, v28, v24
	v_fma_f32 v26, -v40, v41, 1.0
	v_fmac_f32_e32 v41, v26, v41
	v_div_scale_f32 v26, vcc, 1.0, v39, 1.0
	v_mul_f32_e32 v42, v26, v41
	v_fma_f32 v43, -v40, v42, v26
	v_fmac_f32_e32 v42, v43, v41
	v_fma_f32 v26, -v40, v42, v26
	v_div_fmas_f32 v26, v26, v41, v42
	v_add_f32_e32 v32, 1.0, v32
	v_div_fixup_f32 v26, v26, v39, 1.0
	v_div_scale_f32 v39, s[6:7], v32, v32, 1.0
	v_rcp_f32_e32 v40, v39
	v_mul_f32_e32 v22, v22, v26
	v_mul_f32_e32 v25, v29, v25
	v_fma_f32 v26, -v39, v40, 1.0
	v_fmac_f32_e32 v40, v26, v40
	v_div_scale_f32 v26, vcc, 1.0, v32, 1.0
	v_mul_f32_e32 v27, v26, v40
	v_fma_f32 v41, -v39, v27, v26
	v_fmac_f32_e32 v27, v41, v40
	v_fma_f32 v26, -v39, v27, v26
	v_lshlrev_b32_e32 v39, 16, v33
; __device__ __forceinline__ unsigned cvt_pk_bf16(float lo, float hi) { unsigned r; asm volatile("v_cvt_pk_bf16_f32 %0, %1, %2" : "=v"(r) : "v"(lo), "v"(hi)); return r; }
; __device__ __forceinline__ float bflo(unsigned w) { return __uint_as_float(w << 16); }
; __device__ __forceinline__ float bfhi(unsigned w) { return __uint_as_float(w & 0xffff0000u); }
; __device__ __forceinline__ float sigmoidf(float x) { return 1.f / (1.f + __expf(-x)); }
; __device__ __forceinline__ void mlstm_out_unit(const Params& P, int l, int h, int n, char* lds) {
;     ...
;         for (int j = 0; j < 8; ++j) { const int e = 32 * j + 4 * p; const f32x4 gn = *(const f32x4*)(mnorm + e);
;             const u32x2 mo = *(const u32x2*)(PROJ + row * PW + C_MO + h * 256 + e);
;             const float o0 = hv[j][0] * rs * gn[0] * sigmoidf(bflo(mo.x)), o1 = hv[j][1] * rs * gn[1] * sigmoidf(bfhi(mo.x));
;             const float o2 = hv[j][2] * rs * gn[2] * sigmoidf(bflo(mo.y)), o3 = hv[j][3] * rs * gn[3] * sigmoidf(bfhi(mo.y));
;             u32x2 w; w.x = cvt_pk_bf16(o0, o1); w.y = cvt_pk_bf16(o2, o3);
;             *(u32x2*)(MIX + row * DM + h * 256 + e) = w; }
	v_mul_f32_e32 v39, 0xbfb8aa3b, v39
	v_exp_f32_e32 v39, v39
	v_div_fmas_f32 v26, v26, v40, v27
	v_div_fixup_f32 v26, v26, v32, 1.0
	v_mul_f32_e32 v23, v23, v26
	v_add_f32_e32 v27, 1.0, v39
	v_div_scale_f32 v32, s[6:7], v27, v27, 1.0
	v_rcp_f32_e32 v39, v32
	v_cvt_pk_bf16_f32 v22, v22, v23
	s_nop 0
	v_fma_f32 v26, -v32, v39, 1.0
	v_fmac_f32_e32 v39, v26, v39
	v_div_scale_f32 v26, vcc, 1.0, v27, 1.0
	v_mul_f32_e32 v28, v26, v39
	v_fma_f32 v40, -v32, v28, v26
	v_fmac_f32_e32 v28, v40, v39
	v_fma_f32 v26, -v32, v28, v26
	v_and_b32_e32 v32, 0xffff0000, v33
	v_mul_f32_e32 v32, 0xbfb8aa3b, v32
	v_exp_f32_e32 v32, v32
	v_div_fmas_f32 v26, v26, v39, v28
	v_div_fixup_f32 v26, v26, v27, 1.0
	v_mul_f32_e32 v24, v24, v26
	v_add_f32_e32 v27, 1.0, v32
	v_div_scale_f32 v28, s[6:7], v27, v27, 1.0
	v_rcp_f32_e32 v32, v28
	s_nop 0
	v_fma_f32 v26, -v28, v32, 1.0
	v_fmac_f32_e32 v32, v26, v32
	v_div_scale_f32 v26, vcc, 1.0, v27, 1.0
	v_mul_f32_e32 v29, v26, v32
	v_fma_f32 v33, -v28, v29, v26
	v_fmac_f32_e32 v29, v33, v32
	v_fma_f32 v26, -v28, v29, v26
	v_div_fmas_f32 v26, v26, v32, v29
	v_div_fixup_f32 v26, v26, v27, 1.0
	v_mul_f32_e32 v25, v25, v26
	v_cvt_pk_bf16_f32 v23, v24, v25
	global_store_dwordx2 v[30:31], v[22:23], off offset:128
	s_nop 0
	s_nop 1
	v_mov_b32_e32 v22, v220
	v_mov_b32_e32 v23, v221
	v_mov_b32_e32 v24, v222
	v_mov_b32_e32 v25, v223
	v_mov_b32_e32 v26, v200
	v_mov_b32_e32 v27, v201
	v_mul_f32_e32 v18, v18, v22
	v_lshlrev_b32_e32 v22, 16, v26
	v_mul_f32_e32 v22, 0xbfb8aa3b, v22
	v_exp_f32_e32 v22, v22
	v_and_b32_e32 v26, 0xffff0000, v26
	v_mul_f32_e32 v26, 0xbfb8aa3b, v26
	v_exp_f32_e32 v26, v26
	v_add_f32_e32 v22, 1.0, v22
	v_div_scale_f32 v28, s[6:7], v22, v22, 1.0
	v_rcp_f32_e32 v29, v28
	v_div_scale_f32 v32, vcc, 1.0, v22, 1.0
	v_add_f32_e32 v26, 1.0, v26
	v_fma_f32 v33, -v28, v29, 1.0
	v_fmac_f32_e32 v29, v33, v29
	v_mul_f32_e32 v33, v32, v29
	v_fma_f32 v39, -v28, v33, v32
	v_fmac_f32_e32 v33, v39, v29
	v_fma_f32 v28, -v28, v33, v32
	v_div_fmas_f32 v28, v28, v29, v33
	v_div_fixup_f32 v22, v28, v22, 1.0
	v_div_scale_f32 v28, s[6:7], v26, v26, 1.0
	v_rcp_f32_e32 v29, v28
	v_mul_f32_e32 v18, v18, v22
	v_mul_f32_e32 v19, v19, v23
	v_mul_f32_e32 v20, v20, v24
	v_fma_f32 v22, -v28, v29, 1.0
	v_fmac_f32_e32 v29, v22, v29
	v_div_scale_f32 v22, vcc, 1.0, v26, 1.0
	v_mul_f32_e32 v23, v22, v29
	v_fma_f32 v32, -v28, v23, v22
	v_fmac_f32_e32 v23, v32, v29
	v_fma_f32 v22, -v28, v23, v22
	v_lshlrev_b32_e32 v28, 16, v27
	v_mul_f32_e32 v28, 0xbfb8aa3b, v28
	v_exp_f32_e32 v28, v28
	v_div_fmas_f32 v22, v22, v29, v23
	v_div_fixup_f32 v22, v22, v26, 1.0
	v_mul_f32_e32 v19, v19, v22
	v_add_f32_e32 v23, 1.0, v28
	v_div_scale_f32 v26, s[6:7], v23, v23, 1.0
	v_rcp_f32_e32 v28, v26
	v_mul_f32_e32 v21, v21, v25
	v_cvt_pk_bf16_f32 v18, v18, v19
	v_fma_f32 v22, -v26, v28, 1.0
	v_fmac_f32_e32 v28, v22, v28
	v_div_scale_f32 v22, vcc, 1.0, v23, 1.0
	v_mul_f32_e32 v24, v22, v28
	v_fma_f32 v29, -v26, v24, v22
	v_fmac_f32_e32 v24, v29, v28
	v_fma_f32 v22, -v26, v24, v22
	v_and_b32_e32 v26, 0xffff0000, v27
	v_mul_f32_e32 v26, 0xbfb8aa3b, v26
	v_exp_f32_e32 v26, v26
	v_div_fmas_f32 v22, v22, v28, v24
	v_div_fixup_f32 v22, v22, v23, 1.0
	v_mul_f32_e32 v20, v20, v22
	v_add_f32_e32 v23, 1.0, v26
	v_div_scale_f32 v24, s[6:7], v23, v23, 1.0
	v_rcp_f32_e32 v26, v24
	s_nop 0
	v_fma_f32 v22, -v24, v26, 1.0
	v_fmac_f32_e32 v26, v22, v26
	v_div_scale_f32 v22, vcc, 1.0, v23, 1.0
	v_mul_f32_e32 v25, v22, v26
	v_fma_f32 v27, -v24, v25, v22
	v_fmac_f32_e32 v25, v27, v26
	v_fma_f32 v22, -v24, v25, v22
	v_div_fmas_f32 v22, v22, v26, v25
	v_div_fixup_f32 v22, v22, v23, 1.0
	v_mul_f32_e32 v21, v21, v22
	v_cvt_pk_bf16_f32 v19, v20, v21
	global_store_dwordx2 v[30:31], v[18:19], off offset:192
	s_nop 0
	s_nop 1
	v_mov_b32_e32 v18, v224
	v_mov_b32_e32 v19, v225
	v_mov_b32_e32 v20, v226
	v_mov_b32_e32 v21, v227
	v_mov_b32_e32 v22, v202
	v_mov_b32_e32 v23, v203
	v_mul_f32_e32 v14, v14, v18
	v_lshlrev_b32_e32 v18, 16, v22
	v_mul_f32_e32 v15, v15, v19
	v_and_b32_e32 v19, 0xffff0000, v22
	v_mul_f32_e32 v18, 0xbfb8aa3b, v18
	v_mul_f32_e32 v19, 0xbfb8aa3b, v19
	v_exp_f32_e32 v18, v18
	v_exp_f32_e32 v19, v19
	v_lshlrev_b32_e32 v22, 16, v23
	v_mul_f32_e32 v22, 0xbfb8aa3b, v22
	v_add_f32_e32 v18, 1.0, v18
	v_add_f32_e32 v19, 1.0, v19
	v_div_scale_f32 v24, s[6:7], v18, v18, 1.0
	v_div_scale_f32 v26, s[6:7], v19, v19, 1.0
	v_rcp_f32_e32 v27, v24
	v_rcp_f32_e32 v28, v26
	v_div_scale_f32 v25, vcc, 1.0, v18, 1.0
	v_fma_f32 v32, -v24, v27, 1.0
	v_fma_f32 v33, -v26, v28, 1.0
	v_fmac_f32_e32 v27, v32, v27
	v_div_scale_f32 v29, s[6:7], 1.0, v19, 1.0
	v_fmac_f32_e32 v28, v33, v28
	v_mul_f32_e32 v32, v25, v27
	v_mul_f32_e32 v33, v29, v28
	v_fma_f32 v39, -v24, v32, v25
	v_exp_f32_e32 v22, v22
	v_fma_f32 v40, -v26, v33, v29
	v_fmac_f32_e32 v32, v39, v27
	v_fmac_f32_e32 v33, v40, v28
	v_fma_f32 v24, -v24, v32, v25
	v_fma_f32 v25, -v26, v33, v29
	v_div_fmas_f32 v24, v24, v27, v32
	s_mov_b64 vcc, s[6:7]
	v_div_fixup_f32 v18, v24, v18, 1.0
	v_div_fmas_f32 v24, v25, v28, v33
	v_mul_f32_e32 v14, v14, v18
	v_div_fixup_f32 v18, v24, v19, 1.0
	v_add_f32_e32 v19, 1.0, v22
	v_div_scale_f32 v22, s[6:7], v19, v19, 1.0
	v_rcp_f32_e32 v24, v22
	v_mul_f32_e32 v15, v15, v18
	v_mul_f32_e32 v16, v16, v20
	v_mul_f32_e32 v17, v17, v21
	v_fma_f32 v18, -v22, v24, 1.0
	v_fmac_f32_e32 v24, v18, v24
	v_div_scale_f32 v18, vcc, 1.0, v19, 1.0
	v_mul_f32_e32 v20, v18, v24
	v_fma_f32 v25, -v22, v20, v18
	v_fmac_f32_e32 v20, v25, v24
	v_fma_f32 v18, -v22, v20, v18
	v_and_b32_e32 v22, 0xffff0000, v23
	v_mul_f32_e32 v22, 0xbfb8aa3b, v22
	v_exp_f32_e32 v22, v22
	v_div_fmas_f32 v18, v18, v24, v20
	v_div_fixup_f32 v18, v18, v19, 1.0
; __device__ __forceinline__ unsigned cvt_pk_bf16(float lo, float hi) { unsigned r; asm volatile("v_cvt_pk_bf16_f32 %0, %1, %2" : "=v"(r) : "v"(lo), "v"(hi)); return r; }
; __device__ __forceinline__ float bflo(unsigned w) { return __uint_as_float(w << 16); }
; __device__ __forceinline__ float bfhi(unsigned w) { return __uint_as_float(w & 0xffff0000u); }
; __device__ __forceinline__ float sigmoidf(float x) { return 1.f / (1.f + __expf(-x)); }
; __device__ __forceinline__ void mlstm_out_unit(const Params& P, int l, int h, int n, char* lds) {
;     ...
;         for (int j = 0; j < 8; ++j) { const int e = 32 * j + 4 * p; const f32x4 gn = *(const f32x4*)(mnorm + e);
;             const u32x2 mo = *(const u32x2*)(PROJ + row * PW + C_MO + h * 256 + e);
;             const float o0 = hv[j][0] * rs * gn[0] * sigmoidf(bflo(mo.x)), o1 = hv[j][1] * rs * gn[1] * sigmoidf(bfhi(mo.x));
;             const float o2 = hv[j][2] * rs * gn[2] * sigmoidf(bflo(mo.y)), o3 = hv[j][3] * rs * gn[3] * sigmoidf(bfhi(mo.y));
;             u32x2 w; w.x = cvt_pk_bf16(o0, o1); w.y = cvt_pk_bf16(o2, o3);
;             *(u32x2*)(MIX + row * DM + h * 256 + e) = w; }
	v_mul_f32_e32 v16, v16, v18
	v_add_f32_e32 v19, 1.0, v22
	v_div_scale_f32 v20, s[6:7], v19, v19, 1.0
	v_rcp_f32_e32 v22, v20
	v_cvt_pk_bf16_f32 v14, v14, v15
	s_nop 0
	v_fma_f32 v18, -v20, v22, 1.0
	v_fmac_f32_e32 v22, v18, v22
	v_div_scale_f32 v18, vcc, 1.0, v19, 1.0
	v_mul_f32_e32 v21, v18, v22
	v_fma_f32 v23, -v20, v21, v18
	v_fmac_f32_e32 v21, v23, v22
	v_fma_f32 v18, -v20, v21, v18
	v_div_fmas_f32 v18, v18, v22, v21
	v_div_fixup_f32 v18, v18, v19, 1.0
	v_mul_f32_e32 v17, v17, v18
	v_cvt_pk_bf16_f32 v15, v16, v17
	global_store_dwordx2 v[30:31], v[14:15], off offset:256
	s_nop 0
	s_nop 1
	v_mov_b32_e32 v14, v228
	v_mov_b32_e32 v15, v229
	v_mov_b32_e32 v16, v230
	v_mov_b32_e32 v17, v231
	v_mov_b32_e32 v18, v204
	v_mov_b32_e32 v19, v205
	v_mul_f32_e32 v10, v10, v14
	v_lshlrev_b32_e32 v14, 16, v18
	v_mul_f32_e32 v11, v11, v15
	v_and_b32_e32 v15, 0xffff0000, v18
	v_mul_f32_e32 v14, 0xbfb8aa3b, v14
	v_mul_f32_e32 v15, 0xbfb8aa3b, v15
	v_exp_f32_e32 v14, v14
	v_exp_f32_e32 v15, v15
	v_mul_f32_e32 v12, v12, v16
	v_lshlrev_b32_e32 v16, 16, v19
	v_add_f32_e32 v14, 1.0, v14
	v_and_b32_e32 v18, 0xffff0000, v19
	v_add_f32_e32 v15, 1.0, v15
	v_div_scale_f32 v19, s[6:7], v14, v14, 1.0
	v_mul_f32_e32 v16, 0xbfb8aa3b, v16
	v_div_scale_f32 v21, s[6:7], v15, v15, 1.0
	v_rcp_f32_e32 v24, v19
	v_exp_f32_e32 v16, v16
	v_rcp_f32_e32 v25, v21
	v_div_scale_f32 v20, vcc, 1.0, v14, 1.0
	v_fma_f32 v28, -v19, v24, 1.0
	v_add_f32_e32 v16, 1.0, v16
	v_fma_f32 v29, -v21, v25, 1.0
	v_fmac_f32_e32 v24, v28, v24
	v_div_scale_f32 v22, s[6:7], 1.0, v15, 1.0
	v_div_scale_f32 v23, s[8:9], v16, v16, 1.0
	v_fmac_f32_e32 v25, v29, v25
	v_mul_f32_e32 v28, v20, v24
	v_rcp_f32_e32 v26, v23
	v_mul_f32_e32 v29, v22, v25
	v_fma_f32 v33, -v19, v28, v20
	v_fma_f32 v39, -v21, v29, v22
	v_fmac_f32_e32 v28, v33, v24
	v_fmac_f32_e32 v29, v39, v25
	v_fma_f32 v19, -v19, v28, v20
	v_fma_f32 v20, -v21, v29, v22
	v_div_fmas_f32 v19, v19, v24, v28
	s_mov_b64 vcc, s[6:7]
	v_fma_f32 v32, -v23, v26, 1.0
	v_div_fixup_f32 v14, v19, v14, 1.0
	v_div_fmas_f32 v19, v20, v25, v29
	v_mul_f32_e32 v18, 0xbfb8aa3b, v18
	v_div_scale_f32 v27, s[8:9], 1.0, v16, 1.0
	v_fmac_f32_e32 v26, v32, v26
	v_mul_f32_e32 v10, v10, v14
	v_div_fixup_f32 v14, v19, v15, 1.0
	v_mul_f32_e32 v32, v27, v26
	v_mul_f32_e32 v11, v11, v14
	v_exp_f32_e32 v14, v18
	v_fma_f32 v40, -v23, v32, v27
	v_fmac_f32_e32 v32, v40, v26
	v_fma_f32 v21, -v23, v32, v27
	s_mov_b64 vcc, s[8:9]
	v_div_fmas_f32 v15, v21, v26, v32
	v_add_f32_e32 v14, 1.0, v14
	v_div_fixup_f32 v15, v15, v16, 1.0
	v_div_scale_f32 v16, s[6:7], v14, v14, 1.0
	v_rcp_f32_e32 v18, v16
	v_mul_f32_e32 v12, v12, v15
	v_mul_f32_e32 v13, v13, v17
	v_cvt_pk_bf16_f32 v10, v10, v11
	v_fma_f32 v15, -v16, v18, 1.0
	v_fmac_f32_e32 v18, v15, v18
	v_div_scale_f32 v15, vcc, 1.0, v14, 1.0
	v_mul_f32_e32 v17, v15, v18
	v_fma_f32 v19, -v16, v17, v15
	v_fmac_f32_e32 v17, v19, v18
	v_fma_f32 v15, -v16, v17, v15
	v_div_fmas_f32 v15, v15, v18, v17
	v_div_fixup_f32 v14, v15, v14, 1.0
	v_mul_f32_e32 v13, v13, v14
	v_cvt_pk_bf16_f32 v11, v12, v13
	global_store_dwordx2 v[30:31], v[10:11], off offset:320
	s_nop 0
	s_nop 1
	v_mov_b32_e32 v10, v232
	v_mov_b32_e32 v11, v233
	v_mov_b32_e32 v12, v234
	v_mov_b32_e32 v13, v235
	v_mov_b32_e32 v14, v206
	v_mov_b32_e32 v15, v207
	v_mul_f32_e32 v6, v6, v10
	v_lshlrev_b32_e32 v10, 16, v14
	v_mul_f32_e32 v7, v7, v11
	v_and_b32_e32 v11, 0xffff0000, v14
	v_mul_f32_e32 v10, 0xbfb8aa3b, v10
	v_mul_f32_e32 v8, v8, v12
	v_lshlrev_b32_e32 v12, 16, v15
	v_mul_f32_e32 v11, 0xbfb8aa3b, v11
	v_exp_f32_e32 v10, v10
	v_mul_f32_e32 v12, 0xbfb8aa3b, v12
	v_exp_f32_e32 v11, v11
	v_exp_f32_e32 v12, v12
	v_mul_f32_e32 v9, v9, v13
	v_and_b32_e32 v13, 0xffff0000, v15
	v_mul_f32_e32 v13, 0xbfb8aa3b, v13
	v_add_f32_e32 v10, 1.0, v10
	v_exp_f32_e32 v13, v13
	v_add_f32_e32 v11, 1.0, v11
	v_div_scale_f32 v14, s[6:7], v10, v10, 1.0
	v_add_f32_e32 v12, 1.0, v12
	v_div_scale_f32 v16, s[6:7], v11, v11, 1.0
	v_rcp_f32_e32 v22, v14
	v_div_scale_f32 v18, s[8:9], v12, v12, 1.0
	v_rcp_f32_e32 v23, v16
	v_rcp_f32_e32 v24, v18
	v_add_f32_e32 v13, 1.0, v13
; __device__ __forceinline__ unsigned cvt_pk_bf16(float lo, float hi) { unsigned r; asm volatile("v_cvt_pk_bf16_f32 %0, %1, %2" : "=v"(r) : "v"(lo), "v"(hi)); return r; }
; __device__ __forceinline__ float bflo(unsigned w) { return __uint_as_float(w << 16); }
; __device__ __forceinline__ float bfhi(unsigned w) { return __uint_as_float(w & 0xffff0000u); }
; __device__ __forceinline__ float sigmoidf(float x) { return 1.f / (1.f + __expf(-x)); }
; __device__ __forceinline__ void mlstm_out_unit(const Params& P, int l, int h, int n, char* lds) {
;     ...
;         const int t = tid >> 3, p = tid & 7; f32x4 hv[8]; float ss = 0.f;
; #pragma unroll
;         for (int j = 0; j < 8; ++j) { hv[j] = *(const f32x4*)(Hb + t * 260 + 32 * j + 4 * p); ss += (hv[j][0] * hv[j][0] + hv[j][1] * hv[j][1]) + (hv[j][2] * hv[j][2] + hv[j][3] * hv[j][3]); }
;         ss += __shfl_xor(ss, 1); ss += __shfl_xor(ss, 2); ss += __shfl_xor(ss, 4);
;         const float rs = rsqrtf(ss * (1.f / 256.f) + RMS_EPS);
;         const size_t row = (size_t)(t0 + t);
; #pragma unroll
;         for (int j = 0; j < 8; ++j) { const int e = 32 * j + 4 * p; const f32x4 gn = *(const f32x4*)(mnorm + e);
;             const u32x2 mo = *(const u32x2*)(PROJ + row * PW + C_MO + h * 256 + e);
;             const float o0 = hv[j][0] * rs * gn[0] * sigmoidf(bflo(mo.x)), o1 = hv[j][1] * rs * gn[1] * sigmoidf(bfhi(mo.x));
;             const float o2 = hv[j][2] * rs * gn[2] * sigmoidf(bflo(mo.y)), o3 = hv[j][3] * rs * gn[3] * sigmoidf(bfhi(mo.y));
;             u32x2 w; w.x = cvt_pk_bf16(o0, o1); w.y = cvt_pk_bf16(o2, o3);
;             *(u32x2*)(MIX + row * DM + h * 256 + e) = w; }
;     }
;     __syncthreads();
	v_div_scale_f32 v20, s[10:11], v13, v13, 1.0
	v_fma_f32 v26, -v14, v22, 1.0
	v_div_scale_f32 v15, vcc, 1.0, v10, 1.0
	v_rcp_f32_e32 v25, v20
	v_fma_f32 v27, -v16, v23, 1.0
	v_fmac_f32_e32 v22, v26, v22
	v_div_scale_f32 v17, s[6:7], 1.0, v11, 1.0
	v_fma_f32 v28, -v18, v24, 1.0
	v_fmac_f32_e32 v23, v27, v23
	v_mul_f32_e32 v26, v15, v22
	v_div_scale_f32 v19, s[8:9], 1.0, v12, 1.0
	v_fmac_f32_e32 v24, v28, v24
	v_mul_f32_e32 v27, v17, v23
	v_fma_f32 v32, -v14, v26, v15
	v_mul_f32_e32 v28, v19, v24
	v_fma_f32 v33, -v16, v27, v17
	v_fmac_f32_e32 v26, v32, v22
	v_fma_f32 v29, -v20, v25, 1.0
	v_fma_f32 v39, -v18, v28, v19
	v_fmac_f32_e32 v27, v33, v23
	v_fma_f32 v14, -v14, v26, v15
	v_div_scale_f32 v21, s[10:11], 1.0, v13, 1.0
	v_fmac_f32_e32 v25, v29, v25
	v_fmac_f32_e32 v28, v39, v24
	v_fma_f32 v15, -v16, v27, v17
	v_div_fmas_f32 v14, v14, v22, v26
	s_mov_b64 vcc, s[6:7]
	v_mul_f32_e32 v29, v21, v25
	v_fma_f32 v16, -v18, v28, v19
	v_div_fixup_f32 v10, v14, v10, 1.0
	v_div_fmas_f32 v14, v15, v23, v27
	s_mov_b64 vcc, s[8:9]
	v_fma_f32 v40, -v20, v29, v21
	v_mul_f32_e32 v6, v6, v10
	v_div_fixup_f32 v10, v14, v11, 1.0
	v_div_fmas_f32 v11, v16, v24, v28
	v_fmac_f32_e32 v29, v40, v25
	v_mul_f32_e32 v7, v7, v10
	v_div_fixup_f32 v10, v11, v12, 1.0
	v_mul_f32_e32 v8, v8, v10
	v_fma_f32 v10, -v20, v29, v21
	s_mov_b64 vcc, s[10:11]
	v_div_fmas_f32 v10, v10, v25, v29
	v_div_fixup_f32 v10, v10, v13, 1.0
	v_mul_f32_e32 v9, v9, v10
	v_cvt_pk_bf16_f32 v6, v6, v7
	v_cvt_pk_bf16_f32 v7, v8, v9
	global_store_dwordx2 v[30:31], v[6:7], off offset:384
	s_nop 0
	s_nop 1
	v_mov_b32_e32 v6, v236
	v_mov_b32_e32 v7, v237
	v_mov_b32_e32 v8, v238
	v_mov_b32_e32 v9, v239
	v_mov_b32_e32 v10, v208
	v_mov_b32_e32 v11, v209
	v_mul_f32_e32 v2, v2, v6
	v_lshlrev_b32_e32 v6, 16, v10
	v_mul_f32_e32 v3, v3, v7
	v_and_b32_e32 v7, 0xffff0000, v10
	v_mul_f32_e32 v6, 0xbfb8aa3b, v6
	v_mul_f32_e32 v4, v4, v8
	v_lshlrev_b32_e32 v8, 16, v11
	v_mul_f32_e32 v7, 0xbfb8aa3b, v7
	v_exp_f32_e32 v6, v6
	v_mul_f32_e32 v5, v5, v9
	v_and_b32_e32 v9, 0xffff0000, v11
	v_mul_f32_e32 v8, 0xbfb8aa3b, v8
	v_exp_f32_e32 v7, v7
	v_mul_f32_e32 v9, 0xbfb8aa3b, v9
	v_exp_f32_e32 v8, v8
	v_exp_f32_e32 v9, v9
	v_add_f32_e32 v6, 1.0, v6
	v_add_f32_e32 v7, 1.0, v7
	v_div_scale_f32 v10, s[6:7], v6, v6, 1.0
	v_add_f32_e32 v8, 1.0, v8
	v_div_scale_f32 v12, s[6:7], v7, v7, 1.0
	v_rcp_f32_e32 v18, v10
	v_add_f32_e32 v9, 1.0, v9
	v_div_scale_f32 v14, s[8:9], v8, v8, 1.0
	v_rcp_f32_e32 v19, v12
	v_div_scale_f32 v16, s[10:11], v9, v9, 1.0
	v_rcp_f32_e32 v20, v14
	v_rcp_f32_e32 v21, v16
	v_fma_f32 v22, -v10, v18, 1.0
	v_div_scale_f32 v11, vcc, 1.0, v6, 1.0
	v_fma_f32 v23, -v12, v19, 1.0
	v_fmac_f32_e32 v18, v22, v18
	v_div_scale_f32 v13, s[6:7], 1.0, v7, 1.0
	v_fma_f32 v24, -v14, v20, 1.0
	v_fmac_f32_e32 v19, v23, v19
	v_mul_f32_e32 v22, v11, v18
	v_div_scale_f32 v15, s[8:9], 1.0, v8, 1.0
	v_fma_f32 v25, -v16, v21, 1.0
	v_fmac_f32_e32 v20, v24, v20
	v_mul_f32_e32 v23, v13, v19
	v_fma_f32 v26, -v10, v22, v11
	v_div_scale_f32 v17, s[10:11], 1.0, v9, 1.0
	v_fmac_f32_e32 v21, v25, v21
	v_mul_f32_e32 v24, v15, v20
	v_fma_f32 v27, -v12, v23, v13
	v_fmac_f32_e32 v22, v26, v18
	v_mul_f32_e32 v25, v17, v21
	v_fma_f32 v28, -v14, v24, v15
	v_fmac_f32_e32 v23, v27, v19
	v_fma_f32 v10, -v10, v22, v11
	v_fma_f32 v29, -v16, v25, v17
	v_fmac_f32_e32 v24, v28, v20
	v_fma_f32 v11, -v12, v23, v13
	v_div_fmas_f32 v10, v10, v18, v22
	s_mov_b64 vcc, s[6:7]
	v_fmac_f32_e32 v25, v29, v21
	v_fma_f32 v12, -v14, v24, v15
	v_div_fixup_f32 v6, v10, v6, 1.0
	v_div_fmas_f32 v10, v11, v19, v23
	s_mov_b64 vcc, s[8:9]
	v_fma_f32 v13, -v16, v25, v17
	v_mul_f32_e32 v2, v2, v6
	v_div_fixup_f32 v6, v10, v7, 1.0
	v_div_fmas_f32 v7, v12, v20, v24
	s_mov_b64 vcc, s[10:11]
	v_mul_f32_e32 v3, v3, v6
	v_div_fixup_f32 v6, v7, v8, 1.0
	v_div_fmas_f32 v7, v13, v21, v25
	v_mul_f32_e32 v4, v4, v6
	v_div_fixup_f32 v6, v7, v9, 1.0
	v_cvt_pk_bf16_f32 v2, v2, v3
	v_mul_f32_e32 v3, v5, v6
	s_mov_b64 s[6:7], 0
	v_cvt_pk_bf16_f32 v3, v4, v3
	global_store_dwordx2 v[30:31], v[2:3], off offset:448
	s_waitcnt lgkmcnt(0)
	s_barrier

; __device__ __forceinline__ float bflo(unsigned w) { return __uint_as_float(w << 16); }
; __device__ __forceinline__ float bfhi(unsigned w) { return __uint_as_float(w & 0xffff0000u); }
; __device__ __forceinline__ void conv_silu8(const bf16_t* __restrict__ PROJ, const float* __restrict__ cw, const float* __restrict__ cb, int row, int ch, float (&y)[8]) {
;     const f32x4 b0 = *(const f32x4*)(cb + ch), b1 = *(const f32x4*)(cb + ch + 4);
;     float a[8] = {b0[0], b0[1], b0[2], b0[3], b1[0], b1[1], b1[2], b1[3]};
; #pragma unroll
;     for (int k = 0; k < 4; ++k) { const int rr = row - 3 + k;
;         if (rr >= 0) { const u32x4 x = *(const u32x4*)(PROJ + (size_t)rr * PW + ch);
;             const f32x4 w0 = *(const f32x4*)(cw + k * 1024 + ch), w1 = *(const f32x4*)(cw + k * 1024 + ch + 4);
;             a[0] += w0[0] * bflo(x.x); a[1] += w0[1] * bfhi(x.x); a[2] += w0[2] * bflo(x.y); a[3] += w0[3] * bfhi(x.y);
;             a[4] += w1[0] * bflo(x.z); a[5] += w1[1] * bfhi(x.z); a[6] += w1[2] * bflo(x.w); a[7] += w1[3] * bfhi(x.w); } }
; __device__ __forceinline__ void mlstm_out_unit(const Params& P, int l, int h, int n, char* lds) {
;     ...
;     for (int i = 0; i < 4; ++i) { const int idx = tid + 512 * i, which = idx >> 10, t = (idx >> 4) & 63, c = idx & 15; float y[8];
;         conv_silu8(PROJ, cw, cb, t0 + t, which * 512 + h * 128 + c * 8, y);
.LBB0_981:
	s_waitcnt lgkmcnt(0)
	s_add_u32 s14, s40, 0xeb00000
	v_lshlrev_b32_e32 v15, 3, v20
	v_ashrrev_i32_e32 v2, 1, v20
	s_addc_u32 s15, s41, 0
	s_lshl_b32 s22, s66, 7
	v_and_b32_e32 v17, 0x78, v15
	v_and_b32_e32 v2, 0xfffffe00, v2
	v_or3_b32 v10, s22, v2, v17
	v_ashrrev_i32_e32 v11, 31, v10
	v_lshlrev_b64 v[22:23], 2, v[10:11]
	v_lshl_add_u64 v[2:3], s[18:19], 0, v[22:23]
	global_load_dwordx4 v[6:9], v[2:3], off
	s_nop 0
	global_load_dwordx4 v[2:5], v[2:3], off offset:16
	v_bfe_u32 v16, v20, 4, 6
	v_or_b32_e32 v19, s64, v16
	v_lshl_add_u64 v[12:13], v[10:11], 1, s[14:15]
	v_lshl_add_u64 v[10:11], s[16:17], 0, v[22:23]
	v_cmp_lt_i32_e64 s[6:7], 2, v19
	v_add_u32_e32 v22, -3, v19
	s_and_saveexec_b64 s[8:9], s[6:7]
	s_cbranch_execz .LBB0_983
	v_mad_u64_u32 v[24:25], s[10:11], v22, s50, v[12:13]
	global_load_dwordx4 v[24:27], v[24:25], off
	s_nop 0
	global_load_dwordx4 v[28:31], v[10:11], off
	global_load_dwordx4 v[32:35], v[10:11], off offset:16
	s_waitcnt vmcnt(0) lgkmcnt(0)
	v_lshlrev_b32_e32 v36, 16, v24
	v_and_b32_e32 v37, 0xffff0000, v24
	v_lshlrev_b32_e32 v24, 16, v25
	v_and_b32_e32 v25, 0xffff0000, v25
	v_lshlrev_b32_e32 v38, 16, v26
	v_and_b32_e32 v39, 0xffff0000, v26
	v_lshlrev_b32_e32 v26, 16, v27
	v_and_b32_e32 v27, 0xffff0000, v27
	v_pk_fma_f32 v[6:7], v[28:29], v[36:37], v[6:7]
	v_pk_fma_f32 v[8:9], v[30:31], v[24:25], v[8:9]
	v_pk_fma_f32 v[2:3], v[32:33], v[38:39], v[2:3]
	v_pk_fma_f32 v[4:5], v[34:35], v[26:27], v[4:5]
.LBB0_983:
	s_or_b64 exec, exec, s[8:9]
	v_cmp_lt_i32_e64 s[8:9], 1, v19
	v_add_u32_e32 v23, -2, v19
	s_and_saveexec_b64 s[10:11], s[8:9]
	s_cbranch_execz .LBB0_985
	v_mad_u64_u32 v[24:25], s[12:13], v23, s50, v[12:13]
	v_add_co_u32_e32 v32, vcc, 0x1000, v10
	global_load_dwordx4 v[24:27], v[24:25], off
	s_nop 0
	v_addc_co_u32_e32 v33, vcc, 0, v11, vcc
	global_load_dwordx4 v[28:31], v[32:33], off
	s_nop 0
	global_load_dwordx4 v[32:35], v[32:33], off offset:16
	s_waitcnt vmcnt(0) lgkmcnt(0)
	v_lshlrev_b32_e32 v36, 16, v24
	v_and_b32_e32 v37, 0xffff0000, v24
	v_lshlrev_b32_e32 v24, 16, v25
	v_and_b32_e32 v25, 0xffff0000, v25
	v_lshlrev_b32_e32 v38, 16, v26
	v_and_b32_e32 v39, 0xffff0000, v26
	v_lshlrev_b32_e32 v26, 16, v27
	v_and_b32_e32 v27, 0xffff0000, v27
	v_pk_fma_f32 v[6:7], v[28:29], v[36:37], v[6:7]
	v_pk_fma_f32 v[8:9], v[30:31], v[24:25], v[8:9]
	v_pk_fma_f32 v[2:3], v[32:33], v[38:39], v[2:3]
	v_pk_fma_f32 v[4:5], v[34:35], v[26:27], v[4:5]
.LBB0_985:
	s_or_b64 exec, exec, s[10:11]
	v_cmp_lt_i32_e64 s[10:11], 0, v19
	v_add_u32_e32 v24, -1, v19
	s_and_saveexec_b64 s[12:13], s[10:11]
	s_cbranch_execz .LBB0_987
	v_mad_u64_u32 v[26:27], s[20:21], v24, s50, v[12:13]
	v_add_co_u32_e32 v34, vcc, 0x2000, v10
	global_load_dwordx4 v[26:29], v[26:27], off
	s_nop 0
	v_addc_co_u32_e32 v35, vcc, 0, v11, vcc
	global_load_dwordx4 v[30:33], v[34:35], off
	s_nop 0
	global_load_dwordx4 v[34:37], v[34:35], off offset:16
	s_waitcnt vmcnt(0) lgkmcnt(0)
	v_lshlrev_b32_e32 v38, 16, v26
	v_and_b32_e32 v39, 0xffff0000, v26
	v_lshlrev_b32_e32 v26, 16, v27
	v_and_b32_e32 v27, 0xffff0000, v27
	v_lshlrev_b32_e32 v40, 16, v28
	v_and_b32_e32 v41, 0xffff0000, v28
	v_lshlrev_b32_e32 v28, 16, v29
	v_and_b32_e32 v29, 0xffff0000, v29
	v_pk_fma_f32 v[6:7], v[30:31], v[38:39], v[6:7]
	v_pk_fma_f32 v[8:9], v[32:33], v[26:27], v[8:9]
	v_pk_fma_f32 v[2:3], v[34:35], v[40:41], v[2:3]
	v_pk_fma_f32 v[4:5], v[36:37], v[28:29], v[4:5]
.LBB0_987:
	s_or_b64 exec, exec, s[12:13]
	s_cmp_gt_i32 s68, -1
	s_cselect_b64 s[20:21], -1, 0
	s_cmp_lt_i32 s68, 0
	s_cbranch_scc1 .LBB0_989
	v_mad_u64_u32 v[12:13], s[12:13], v19, s50, v[12:13]
	v_add_co_u32_e32 v30, vcc, 0x3000, v10
	global_load_dwordx4 v[26:29], v[12:13], off
	s_nop 0
	v_addc_co_u32_e32 v31, vcc, 0, v11, vcc
	global_load_dwordx4 v[10:13], v[30:31], off
	s_nop 0
	global_load_dwordx4 v[30:33], v[30:31], off offset:16
	s_waitcnt vmcnt(0) lgkmcnt(0)
	v_lshlrev_b32_e32 v34, 16, v26
	v_and_b32_e32 v35, 0xffff0000, v26
	v_lshlrev_b32_e32 v26, 16, v27
	v_and_b32_e32 v27, 0xffff0000, v27
	v_lshlrev_b32_e32 v36, 16, v28
	v_and_b32_e32 v37, 0xffff0000, v28
	v_lshlrev_b32_e32 v28, 16, v29
	v_and_b32_e32 v29, 0xffff0000, v29
	v_pk_fma_f32 v[6:7], v[10:11], v[34:35], v[6:7]
	v_pk_fma_f32 v[8:9], v[12:13], v[26:27], v[8:9]
	v_pk_fma_f32 v[2:3], v[30:31], v[36:37], v[2:3]
	v_pk_fma_f32 v[4:5], v[32:33], v[28:29], v[4:5]
; __device__ __forceinline__ unsigned cvt_pk_bf16(float lo, float hi) { unsigned r; asm volatile("v_cvt_pk_bf16_f32 %0, %1, %2" : "=v"(r) : "v"(lo), "v"(hi)); return r; }
; __device__ __forceinline__ float bflo(unsigned w) { return __uint_as_float(w << 16); }
; __device__ __forceinline__ float bfhi(unsigned w) { return __uint_as_float(w & 0xffff0000u); }
; __device__ __forceinline__ float sigmoidf(float x) { return 1.f / (1.f + __expf(-x)); }
; __device__ __forceinline__ void conv_silu8(const bf16_t* __restrict__ PROJ, const float* __restrict__ cw, const float* __restrict__ cb, int row, int ch, float (&y)[8]) {
;     const f32x4 b0 = *(const f32x4*)(cb + ch), b1 = *(const f32x4*)(cb + ch + 4);
;     float a[8] = {b0[0], b0[1], b0[2], b0[3], b1[0], b1[1], b1[2], b1[3]};
; #pragma unroll
;     for (int k = 0; k < 4; ++k) { const int rr = row - 3 + k;
;         if (rr >= 0) { const u32x4 x = *(const u32x4*)(PROJ + (size_t)rr * PW + ch);
;             const f32x4 w0 = *(const f32x4*)(cw + k * 1024 + ch), w1 = *(const f32x4*)(cw + k * 1024 + ch + 4);
;             a[0] += w0[0] * bflo(x.x); a[1] += w0[1] * bfhi(x.x); a[2] += w0[2] * bflo(x.y); a[3] += w0[3] * bfhi(x.y);
;             a[4] += w1[0] * bflo(x.z); a[5] += w1[1] * bfhi(x.z); a[6] += w1[2] * bflo(x.w); a[7] += w1[3] * bfhi(x.w); } }
; #pragma unroll
;     for (int i = 0; i < 8; ++i) y[i] = a[i] * sigmoidf(a[i]);
; __device__ __forceinline__ void mlstm_out_unit(const Params& P, int l, int h, int n, char* lds) {
;     ...
;     for (int i = 0; i < 4; ++i) { const int idx = tid + 512 * i, which = idx >> 10, t = (idx >> 4) & 63, c = idx & 15; float y[8];
;         conv_silu8(PROJ, cw, cb, t0 + t, which * 512 + h * 128 + c * 8, y);
;         const float sc = which ? 1.f : 0.08838834764831845f;
;         u32x4 w; w.x = cvt_pk_bf16(y[0] * sc, y[1] * sc); w.y = cvt_pk_bf16(y[2] * sc, y[3] * sc); w.z = cvt_pk_bf16(y[4] * sc, y[5] * sc); w.w = cvt_pk_bf16(y[6] * sc, y[7] * sc);
;         *(u32x4*)((which ? Kl : Ql) + t * 136 + c * 8) = w; }
.LBB0_989:
	s_waitcnt vmcnt(0) lgkmcnt(0)
	v_mul_f32_e32 v10, 0xbfb8aa3b, v6
	v_exp_f32_e32 v10, v10
	v_mul_f32_e32 v11, 0xbfb8aa3b, v7
	v_exp_f32_e32 v11, v11
	v_add_f32_e32 v10, 1.0, v10
	v_div_scale_f32 v12, s[12:13], v10, v10, 1.0
	v_rcp_f32_e32 v13, v12
	v_div_scale_f32 v18, vcc, 1.0, v10, 1.0
	v_add_f32_e32 v11, 1.0, v11
	v_fma_f32 v21, -v12, v13, 1.0
	v_fmac_f32_e32 v13, v21, v13
	v_mul_f32_e32 v21, v18, v13
	v_fma_f32 v25, -v12, v21, v18
	v_fmac_f32_e32 v21, v25, v13
	v_fma_f32 v12, -v12, v21, v18
	v_div_scale_f32 v18, s[12:13], v11, v11, 1.0
	v_rcp_f32_e32 v25, v18
	v_div_fmas_f32 v12, v12, v13, v21
	v_div_fixup_f32 v10, v12, v10, 1.0
	v_mul_f32_e32 v13, 0xbfb8aa3b, v8
	v_mul_f32_e32 v6, v6, v10
	v_fma_f32 v10, -v18, v25, 1.0
	v_exp_f32_e32 v13, v13
	v_fmac_f32_e32 v25, v10, v25
	v_div_scale_f32 v10, vcc, 1.0, v11, 1.0
	v_mul_f32_e32 v12, v10, v25
	v_fma_f32 v21, -v18, v12, v10
	v_fmac_f32_e32 v12, v21, v25
	v_add_f32_e32 v13, 1.0, v13
	v_fma_f32 v10, -v18, v12, v10
	v_div_scale_f32 v18, s[12:13], v13, v13, 1.0
	v_rcp_f32_e32 v21, v18
	v_div_fmas_f32 v10, v10, v25, v12
	v_div_fixup_f32 v10, v10, v11, 1.0
	v_mul_f32_e32 v12, 0xbfb8aa3b, v9
	v_mul_f32_e32 v7, v7, v10
	v_fma_f32 v10, -v18, v21, 1.0
	v_exp_f32_e32 v12, v12
	v_fmac_f32_e32 v21, v10, v21
	v_div_scale_f32 v10, vcc, 1.0, v13, 1.0
	v_mul_f32_e32 v11, v10, v21
	v_fma_f32 v25, -v18, v11, v10
	v_fmac_f32_e32 v11, v25, v21
	v_add_f32_e32 v12, 1.0, v12
	v_fma_f32 v10, -v18, v11, v10
	v_div_scale_f32 v18, s[12:13], v12, v12, 1.0
	v_rcp_f32_e32 v25, v18
	v_div_fmas_f32 v10, v10, v21, v11
	v_div_fixup_f32 v10, v10, v13, 1.0
	v_mul_f32_e32 v13, 0xbfb8aa3b, v2
	v_mul_f32_e32 v8, v8, v10
	v_fma_f32 v10, -v18, v25, 1.0
	v_exp_f32_e32 v13, v13
	v_fmac_f32_e32 v25, v10, v25
	v_div_scale_f32 v10, vcc, 1.0, v12, 1.0
	v_mul_f32_e32 v11, v10, v25
	v_fma_f32 v21, -v18, v11, v10
	v_fmac_f32_e32 v11, v21, v25
	v_add_f32_e32 v13, 1.0, v13
	v_fma_f32 v10, -v18, v11, v10
	v_div_scale_f32 v18, s[12:13], v13, v13, 1.0
	v_rcp_f32_e32 v21, v18
	v_div_fmas_f32 v10, v10, v25, v11
	v_div_fixup_f32 v10, v10, v12, 1.0
	v_mul_f32_e32 v12, 0xbfb8aa3b, v3
	v_mul_f32_e32 v9, v9, v10
	v_fma_f32 v10, -v18, v21, 1.0
	v_exp_f32_e32 v12, v12
	v_fmac_f32_e32 v21, v10, v21
	v_div_scale_f32 v10, vcc, 1.0, v13, 1.0
	v_mul_f32_e32 v11, v10, v21
	v_fma_f32 v25, -v18, v11, v10
	v_fmac_f32_e32 v11, v25, v21
	v_add_f32_e32 v12, 1.0, v12
	v_fma_f32 v10, -v18, v11, v10
	v_div_scale_f32 v18, s[12:13], v12, v12, 1.0
	v_rcp_f32_e32 v25, v18
	v_div_fmas_f32 v10, v10, v21, v11
	v_div_fixup_f32 v10, v10, v13, 1.0
	v_mul_f32_e32 v13, 0xbfb8aa3b, v4
	v_mul_f32_e32 v10, v2, v10
	v_fma_f32 v2, -v18, v25, 1.0
	v_exp_f32_e32 v13, v13
	v_fmac_f32_e32 v25, v2, v25
	v_div_scale_f32 v2, vcc, 1.0, v12, 1.0
	v_mul_f32_e32 v11, v2, v25
	v_fma_f32 v21, -v18, v11, v2
	v_fmac_f32_e32 v11, v21, v25
	v_add_f32_e32 v13, 1.0, v13
	v_fma_f32 v2, -v18, v11, v2
	v_div_scale_f32 v18, s[12:13], v13, v13, 1.0
	v_rcp_f32_e32 v21, v18
	v_div_fmas_f32 v2, v2, v25, v11
	v_div_fixup_f32 v2, v2, v12, 1.0
	v_mul_f32_e32 v12, 0xbfb8aa3b, v5
	v_mul_f32_e32 v11, v3, v2
	v_fma_f32 v2, -v18, v21, 1.0
	v_exp_f32_e32 v12, v12
	v_fmac_f32_e32 v21, v2, v21
	v_div_scale_f32 v2, vcc, 1.0, v13, 1.0
	v_mul_f32_e32 v3, v2, v21
	v_fma_f32 v25, -v18, v3, v2
	v_fmac_f32_e32 v3, v25, v21
	v_add_f32_e32 v12, 1.0, v12
	v_fma_f32 v2, -v18, v3, v2
	v_div_scale_f32 v18, s[12:13], v12, v12, 1.0
	v_rcp_f32_e32 v25, v18
	v_div_fmas_f32 v2, v2, v21, v3
	v_div_fixup_f32 v2, v2, v13, 1.0
	v_mul_f32_e32 v13, v4, v2
	v_fma_f32 v2, -v18, v25, 1.0
	v_fmac_f32_e32 v25, v2, v25
	v_div_scale_f32 v2, vcc, 1.0, v12, 1.0
	v_mul_f32_e32 v3, v2, v25
	v_fma_f32 v4, -v18, v3, v2
	v_fmac_f32_e32 v3, v4, v25
	v_fma_f32 v2, -v18, v3, v2
	v_div_fmas_f32 v2, v2, v25, v3
	v_cmp_gt_u32_e32 vcc, s52, v20
	v_div_fixup_f32 v2, v2, v12, 1.0
	v_mul_f32_e32 v5, v5, v2
	v_cndmask_b32_e32 v12, 1.0, v108, vcc
	v_mul_f32_e32 v2, v12, v6
	v_mul_f32_e32 v3, v12, v7
	v_cvt_pk_bf16_f32 v2, v2, v3
	v_mul_f32_e32 v3, v12, v8
	v_mul_f32_e32 v4, v12, v9
	v_cvt_pk_bf16_f32 v3, v3, v4
	v_mul_f32_e32 v4, v12, v10
	v_mul_f32_e32 v6, v12, v11
	v_cvt_pk_bf16_f32 v4, v4, v6
	v_mul_f32_e32 v6, v12, v13
	v_mul_f32_e32 v5, v12, v5
	v_cvt_pk_bf16_f32 v5, v6, v5
	v_mov_b32_e32 v6, s53
	v_cndmask_b32_e32 v6, v6, v94, vcc
	v_mul_u32_u24_e32 v25, 0x110, v16
	v_lshlrev_b32_e32 v18, 1, v17
	v_add3_u32 v6, v6, v25, v18
	v_add_u32_e32 v16, 0x200, v20
	ds_write_b128 v6, v[2:5]
	v_ashrrev_i32_e32 v2, 1, v16
	v_and_b32_e32 v2, 0xfffffe00, v2
	v_or3_b32 v10, s22, v2, v17
	v_ashrrev_i32_e32 v11, 31, v10
	v_lshlrev_b64 v[28:29], 2, v[10:11]
	v_lshl_add_u64 v[2:3], s[18:19], 0, v[28:29]
	global_load_dwordx4 v[6:9], v[2:3], off
	s_nop 0
	global_load_dwordx4 v[2:5], v[2:3], off offset:16
	v_bfe_u32 v21, v16, 4, 6
	v_or_b32_e32 v26, s64, v21
	v_lshl_add_u64 v[12:13], v[10:11], 1, s[14:15]
	v_lshl_add_u64 v[10:11], s[16:17], 0, v[28:29]
	v_cmp_lt_i32_e32 vcc, 2, v26
	s_and_saveexec_b64 s[12:13], vcc
	s_cbranch_execnz .LBB0_1045
	s_or_b64 exec, exec, s[12:13]
	v_cmp_lt_i32_e32 vcc, 1, v26
	s_and_saveexec_b64 s[12:13], vcc
	s_cbranch_execnz .LBB0_1046

; __device__ __forceinline__ unsigned cvt_pk_bf16(float lo, float hi) { unsigned r; asm volatile("v_cvt_pk_bf16_f32 %0, %1, %2" : "=v"(r) : "v"(lo), "v"(hi)); return r; }
; __device__ __forceinline__ float bflo(unsigned w) { return __uint_as_float(w << 16); }
; __device__ __forceinline__ float bfhi(unsigned w) { return __uint_as_float(w & 0xffff0000u); }
; __device__ __forceinline__ float sigmoidf(float x) { return 1.f / (1.f + __expf(-x)); }
; __device__ __forceinline__ void conv_silu8(const bf16_t* __restrict__ PROJ, const float* __restrict__ cw, const float* __restrict__ cb, int row, int ch, float (&y)[8]) {
;     const f32x4 b0 = *(const f32x4*)(cb + ch), b1 = *(const f32x4*)(cb + ch + 4);
;     float a[8] = {b0[0], b0[1], b0[2], b0[3], b1[0], b1[1], b1[2], b1[3]};
; #pragma unroll
;     for (int k = 0; k < 4; ++k) { const int rr = row - 3 + k;
;         if (rr >= 0) { const u32x4 x = *(const u32x4*)(PROJ + (size_t)rr * PW + ch);
;             const f32x4 w0 = *(const f32x4*)(cw + k * 1024 + ch), w1 = *(const f32x4*)(cw + k * 1024 + ch + 4);
;             a[0] += w0[0] * bflo(x.x); a[1] += w0[1] * bfhi(x.x); a[2] += w0[2] * bflo(x.y); a[3] += w0[3] * bfhi(x.y);
;             a[4] += w1[0] * bflo(x.z); a[5] += w1[1] * bfhi(x.z); a[6] += w1[2] * bflo(x.w); a[7] += w1[3] * bfhi(x.w); } }
; #pragma unroll
;     for (int i = 0; i < 8; ++i) y[i] = a[i] * sigmoidf(a[i]);
; __device__ __forceinline__ void mlstm_out_unit(const Params& P, int l, int h, int n, char* lds) {
;     ...
;     for (int i = 0; i < 4; ++i) { const int idx = tid + 512 * i, which = idx >> 10, t = (idx >> 4) & 63, c = idx & 15; float y[8];
;         conv_silu8(PROJ, cw, cb, t0 + t, which * 512 + h * 128 + c * 8, y);
;         const float sc = which ? 1.f : 0.08838834764831845f;
;         u32x4 w; w.x = cvt_pk_bf16(y[0] * sc, y[1] * sc); w.y = cvt_pk_bf16(y[2] * sc, y[3] * sc); w.z = cvt_pk_bf16(y[4] * sc, y[5] * sc); w.w = cvt_pk_bf16(y[6] * sc, y[7] * sc);
;         *(u32x4*)((which ? Kl : Ql) + t * 136 + c * 8) = w; }
.LBB0_992:
	v_add_u32_e32 v27, -1, v26
	v_mad_u64_u32 v[28:29], s[68:69], v27, s50, v[12:13]
	v_add_co_u32_e32 v36, vcc, 0x2000, v10
	global_load_dwordx4 v[28:31], v[28:29], off
	s_nop 0
	v_addc_co_u32_e32 v37, vcc, 0, v11, vcc
	global_load_dwordx4 v[32:35], v[36:37], off
	s_nop 0
	global_load_dwordx4 v[36:39], v[36:37], off offset:16
	s_waitcnt vmcnt(0) lgkmcnt(0)
	v_lshlrev_b32_e32 v40, 16, v28
	v_and_b32_e32 v41, 0xffff0000, v28
	v_lshlrev_b32_e32 v28, 16, v29
	v_and_b32_e32 v29, 0xffff0000, v29
	v_lshlrev_b32_e32 v42, 16, v30
	v_and_b32_e32 v43, 0xffff0000, v30
	v_lshlrev_b32_e32 v30, 16, v31
	v_and_b32_e32 v31, 0xffff0000, v31
	v_pk_fma_f32 v[6:7], v[32:33], v[40:41], v[6:7]
	v_pk_fma_f32 v[8:9], v[34:35], v[28:29], v[8:9]
	v_pk_fma_f32 v[2:3], v[36:37], v[42:43], v[2:3]
	v_pk_fma_f32 v[4:5], v[38:39], v[30:31], v[4:5]
.LBB0_993:
	s_or_b64 exec, exec, s[12:13]
	v_cndmask_b32_e64 v27, 0, 1, s[20:21]
	v_cmp_ne_u32_e64 s[12:13], 1, v27
	s_andn2_b64 vcc, exec, s[20:21]
	s_cbranch_vccnz .LBB0_995
	v_mad_u64_u32 v[12:13], s[20:21], v26, s50, v[12:13]
	v_add_co_u32_e32 v30, vcc, 0x3000, v10
	global_load_dwordx4 v[26:29], v[12:13], off
	s_nop 0
	v_addc_co_u32_e32 v31, vcc, 0, v11, vcc
	global_load_dwordx4 v[10:13], v[30:31], off
	s_nop 0
	global_load_dwordx4 v[30:33], v[30:31], off offset:16
	s_waitcnt vmcnt(0) lgkmcnt(0)
	v_lshlrev_b32_e32 v34, 16, v26
	v_and_b32_e32 v35, 0xffff0000, v26
	v_lshlrev_b32_e32 v26, 16, v27
	v_and_b32_e32 v27, 0xffff0000, v27
	v_lshlrev_b32_e32 v36, 16, v28
	v_and_b32_e32 v37, 0xffff0000, v28
	v_lshlrev_b32_e32 v28, 16, v29
	v_and_b32_e32 v29, 0xffff0000, v29
	v_pk_fma_f32 v[6:7], v[10:11], v[34:35], v[6:7]
	v_pk_fma_f32 v[8:9], v[12:13], v[26:27], v[8:9]
	v_pk_fma_f32 v[2:3], v[30:31], v[36:37], v[2:3]
	v_pk_fma_f32 v[4:5], v[32:33], v[28:29], v[4:5]
.LBB0_995:
	s_waitcnt vmcnt(0) lgkmcnt(0)
	v_mul_f32_e32 v10, 0xbfb8aa3b, v6
	v_exp_f32_e32 v10, v10
	v_mul_f32_e32 v11, 0xbfb8aa3b, v7
	v_exp_f32_e32 v11, v11
	v_add_f32_e32 v10, 1.0, v10
	v_div_scale_f32 v12, s[20:21], v10, v10, 1.0
	v_rcp_f32_e32 v13, v12
	v_div_scale_f32 v26, vcc, 1.0, v10, 1.0
	v_add_f32_e32 v11, 1.0, v11
	v_fma_f32 v27, -v12, v13, 1.0
	v_fmac_f32_e32 v13, v27, v13
	v_mul_f32_e32 v27, v26, v13
	v_fma_f32 v28, -v12, v27, v26
	v_fmac_f32_e32 v27, v28, v13
	v_fma_f32 v12, -v12, v27, v26
	v_div_scale_f32 v26, s[20:21], v11, v11, 1.0
	v_rcp_f32_e32 v28, v26
	v_div_fmas_f32 v12, v12, v13, v27
	v_div_fixup_f32 v10, v12, v10, 1.0
	v_mul_f32_e32 v13, 0xbfb8aa3b, v8
	v_mul_f32_e32 v6, v6, v10
	v_fma_f32 v10, -v26, v28, 1.0
	v_exp_f32_e32 v13, v13
	v_fmac_f32_e32 v28, v10, v28
	v_div_scale_f32 v10, vcc, 1.0, v11, 1.0
	v_mul_f32_e32 v12, v10, v28
	v_fma_f32 v27, -v26, v12, v10
	v_fmac_f32_e32 v12, v27, v28
	v_add_f32_e32 v13, 1.0, v13
	v_fma_f32 v10, -v26, v12, v10
	v_div_scale_f32 v26, s[20:21], v13, v13, 1.0
	v_rcp_f32_e32 v27, v26
	v_div_fmas_f32 v10, v10, v28, v12
	v_div_fixup_f32 v10, v10, v11, 1.0
	v_mul_f32_e32 v12, 0xbfb8aa3b, v9
	v_mul_f32_e32 v7, v7, v10
	v_fma_f32 v10, -v26, v27, 1.0
	v_exp_f32_e32 v12, v12
	v_fmac_f32_e32 v27, v10, v27
	v_div_scale_f32 v10, vcc, 1.0, v13, 1.0
	v_mul_f32_e32 v11, v10, v27
	v_fma_f32 v28, -v26, v11, v10
	v_fmac_f32_e32 v11, v28, v27
	v_add_f32_e32 v12, 1.0, v12
	v_fma_f32 v10, -v26, v11, v10
	v_div_scale_f32 v26, s[20:21], v12, v12, 1.0
	v_rcp_f32_e32 v28, v26
	v_div_fmas_f32 v10, v10, v27, v11
	v_div_fixup_f32 v10, v10, v13, 1.0
	v_mul_f32_e32 v13, 0xbfb8aa3b, v2
	v_mul_f32_e32 v8, v8, v10
	v_fma_f32 v10, -v26, v28, 1.0
	v_exp_f32_e32 v13, v13
	v_fmac_f32_e32 v28, v10, v28
	v_div_scale_f32 v10, vcc, 1.0, v12, 1.0
	v_mul_f32_e32 v11, v10, v28
	v_fma_f32 v27, -v26, v11, v10
	v_fmac_f32_e32 v11, v27, v28
	v_add_f32_e32 v13, 1.0, v13
	v_fma_f32 v10, -v26, v11, v10
	v_div_scale_f32 v26, s[20:21], v13, v13, 1.0
	v_rcp_f32_e32 v27, v26
	v_div_fmas_f32 v10, v10, v28, v11
	v_div_fixup_f32 v10, v10, v12, 1.0
	v_mul_f32_e32 v12, 0xbfb8aa3b, v3
	v_mul_f32_e32 v9, v9, v10
	v_fma_f32 v10, -v26, v27, 1.0
	v_exp_f32_e32 v12, v12
	v_fmac_f32_e32 v27, v10, v27
	v_div_scale_f32 v10, vcc, 1.0, v13, 1.0
	v_mul_f32_e32 v11, v10, v27
	v_fma_f32 v28, -v26, v11, v10
	v_fmac_f32_e32 v11, v28, v27
	v_add_f32_e32 v12, 1.0, v12
	v_fma_f32 v10, -v26, v11, v10
	v_div_scale_f32 v26, s[20:21], v12, v12, 1.0
	v_rcp_f32_e32 v28, v26
	v_div_fmas_f32 v10, v10, v27, v11
	v_div_fixup_f32 v10, v10, v13, 1.0
	v_mul_f32_e32 v13, 0xbfb8aa3b, v4
	v_mul_f32_e32 v10, v2, v10
	v_fma_f32 v2, -v26, v28, 1.0
	v_exp_f32_e32 v13, v13
	v_fmac_f32_e32 v28, v2, v28
	v_div_scale_f32 v2, vcc, 1.0, v12, 1.0
	v_mul_f32_e32 v11, v2, v28
	v_fma_f32 v27, -v26, v11, v2
	v_fmac_f32_e32 v11, v27, v28
	v_add_f32_e32 v13, 1.0, v13
	v_fma_f32 v2, -v26, v11, v2
	v_div_scale_f32 v26, s[20:21], v13, v13, 1.0
	v_rcp_f32_e32 v27, v26
	v_div_fmas_f32 v2, v2, v28, v11
	v_div_fixup_f32 v2, v2, v12, 1.0
	v_mul_f32_e32 v12, 0xbfb8aa3b, v5
	v_mul_f32_e32 v11, v3, v2
	v_fma_f32 v2, -v26, v27, 1.0
	v_exp_f32_e32 v12, v12
	v_fmac_f32_e32 v27, v2, v27
	v_div_scale_f32 v2, vcc, 1.0, v13, 1.0
	v_mul_f32_e32 v3, v2, v27
	v_fma_f32 v28, -v26, v3, v2
	v_fmac_f32_e32 v3, v28, v27
	v_add_f32_e32 v12, 1.0, v12
	v_fma_f32 v2, -v26, v3, v2
	v_div_scale_f32 v26, s[20:21], v12, v12, 1.0
	v_rcp_f32_e32 v28, v26
	v_div_fmas_f32 v2, v2, v27, v3
	v_div_fixup_f32 v2, v2, v13, 1.0
	v_mul_f32_e32 v13, v4, v2
	v_fma_f32 v2, -v26, v28, 1.0
	v_fmac_f32_e32 v28, v2, v28
	v_div_scale_f32 v2, vcc, 1.0, v12, 1.0
	v_mul_f32_e32 v3, v2, v28
	v_fma_f32 v4, -v26, v3, v2
	v_fmac_f32_e32 v3, v4, v28
	v_fma_f32 v2, -v26, v3, v2
	v_div_fmas_f32 v2, v2, v28, v3
	v_cmp_gt_u32_e32 vcc, s52, v16
	v_div_fixup_f32 v2, v2, v12, 1.0
	v_mul_f32_e32 v5, v5, v2
	v_cndmask_b32_e32 v12, 1.0, v108, vcc
	v_mul_f32_e32 v2, v12, v6
	v_mul_f32_e32 v3, v12, v7
	v_cvt_pk_bf16_f32 v2, v2, v3
	v_mul_f32_e32 v3, v12, v8
	v_mul_f32_e32 v4, v12, v9
	v_cvt_pk_bf16_f32 v3, v3, v4
	v_mul_f32_e32 v4, v12, v10
	v_mul_f32_e32 v6, v12, v11
	v_cvt_pk_bf16_f32 v4, v4, v6
	v_mul_f32_e32 v6, v12, v13
	v_mul_f32_e32 v5, v12, v5
	v_cvt_pk_bf16_f32 v5, v6, v5
	v_mov_b32_e32 v6, s53
	v_cndmask_b32_e32 v6, v6, v94, vcc
	v_mul_u32_u24_e32 v7, 0x110, v21
	v_add3_u32 v6, v6, v7, v18
	v_add_u32_e32 v21, 0x400, v20
	ds_write_b128 v6, v[2:5]
	v_ashrrev_i32_e32 v2, 1, v21
	v_and_b32_e32 v2, 0xfffffe00, v2
	v_or3_b32 v10, s22, v2, v17
	v_ashrrev_i32_e32 v11, 31, v10
	v_lshlrev_b64 v[26:27], 2, v[10:11]
	v_lshl_add_u64 v[2:3], s[18:19], 0, v[26:27]
	global_load_dwordx4 v[6:9], v[2:3], off
	s_nop 0
	global_load_dwordx4 v[2:5], v[2:3], off offset:16
	v_lshl_add_u64 v[12:13], v[10:11], 1, s[14:15]
	v_lshl_add_u64 v[10:11], s[16:17], 0, v[26:27]
	s_and_saveexec_b64 s[20:21], s[6:7]
	s_cbranch_execnz .LBB0_1047
	s_or_b64 exec, exec, s[20:21]
	s_and_saveexec_b64 s[6:7], s[8:9]
	s_cbranch_execnz .LBB0_1048

; __device__ __forceinline__ unsigned cvt_pk_bf16(float lo, float hi) { unsigned r; asm volatile("v_cvt_pk_bf16_f32 %0, %1, %2" : "=v"(r) : "v"(lo), "v"(hi)); return r; }
; __device__ __forceinline__ float bflo(unsigned w) { return __uint_as_float(w << 16); }
; __device__ __forceinline__ float bfhi(unsigned w) { return __uint_as_float(w & 0xffff0000u); }
; __device__ __forceinline__ float sigmoidf(float x) { return 1.f / (1.f + __expf(-x)); }
; __device__ __forceinline__ void conv_silu8(const bf16_t* __restrict__ PROJ, const float* __restrict__ cw, const float* __restrict__ cb, int row, int ch, float (&y)[8]) {
;     const f32x4 b0 = *(const f32x4*)(cb + ch), b1 = *(const f32x4*)(cb + ch + 4);
;     float a[8] = {b0[0], b0[1], b0[2], b0[3], b1[0], b1[1], b1[2], b1[3]};
; #pragma unroll
;     for (int k = 0; k < 4; ++k) { const int rr = row - 3 + k;
;         if (rr >= 0) { const u32x4 x = *(const u32x4*)(PROJ + (size_t)rr * PW + ch);
;             const f32x4 w0 = *(const f32x4*)(cw + k * 1024 + ch), w1 = *(const f32x4*)(cw + k * 1024 + ch + 4);
;             a[0] += w0[0] * bflo(x.x); a[1] += w0[1] * bfhi(x.x); a[2] += w0[2] * bflo(x.y); a[3] += w0[3] * bfhi(x.y);
;             a[4] += w1[0] * bflo(x.z); a[5] += w1[1] * bfhi(x.z); a[6] += w1[2] * bflo(x.w); a[7] += w1[3] * bfhi(x.w); } }
; #pragma unroll
;     for (int i = 0; i < 8; ++i) y[i] = a[i] * sigmoidf(a[i]);
; __device__ __forceinline__ void mlstm_out_unit(const Params& P, int l, int h, int n, char* lds) {
;     ...
;     for (int i = 0; i < 4; ++i) { const int idx = tid + 512 * i, which = idx >> 10, t = (idx >> 4) & 63, c = idx & 15; float y[8];
;         conv_silu8(PROJ, cw, cb, t0 + t, which * 512 + h * 128 + c * 8, y);
;         const float sc = which ? 1.f : 0.08838834764831845f;
;         u32x4 w; w.x = cvt_pk_bf16(y[0] * sc, y[1] * sc); w.y = cvt_pk_bf16(y[2] * sc, y[3] * sc); w.z = cvt_pk_bf16(y[4] * sc, y[5] * sc); w.w = cvt_pk_bf16(y[6] * sc, y[7] * sc);
;         *(u32x4*)((which ? Kl : Ql) + t * 136 + c * 8) = w; }
.LBB0_999:
	v_mad_u64_u32 v[12:13], s[6:7], v19, s50, v[12:13]
	v_add_co_u32_e32 v22, vcc, 0x3000, v10
	global_load_dwordx4 v[26:29], v[12:13], off
	s_nop 0
	v_addc_co_u32_e32 v23, vcc, 0, v11, vcc
	global_load_dwordx4 v[10:13], v[22:23], off
	global_load_dwordx4 v[30:33], v[22:23], off offset:16
	s_waitcnt vmcnt(0) lgkmcnt(0)
	v_lshlrev_b32_e32 v22, 16, v26
	v_and_b32_e32 v23, 0xffff0000, v26
	v_lshlrev_b32_e32 v26, 16, v27
	v_and_b32_e32 v27, 0xffff0000, v27
	v_lshlrev_b32_e32 v34, 16, v28
	v_and_b32_e32 v35, 0xffff0000, v28
	v_lshlrev_b32_e32 v28, 16, v29
	v_and_b32_e32 v29, 0xffff0000, v29
	v_pk_fma_f32 v[6:7], v[10:11], v[22:23], v[6:7]
	v_pk_fma_f32 v[8:9], v[12:13], v[26:27], v[8:9]
	v_pk_fma_f32 v[2:3], v[30:31], v[34:35], v[2:3]
	v_pk_fma_f32 v[4:5], v[32:33], v[28:29], v[4:5]
.LBB0_1000:
	s_waitcnt vmcnt(0) lgkmcnt(0)
	v_mul_f32_e32 v10, 0xbfb8aa3b, v6
	v_exp_f32_e32 v10, v10
	v_mul_f32_e32 v11, 0xbfb8aa3b, v7
	v_exp_f32_e32 v11, v11
	v_add_f32_e32 v10, 1.0, v10
	v_div_scale_f32 v12, s[6:7], v10, v10, 1.0
	v_rcp_f32_e32 v13, v12
	v_div_scale_f32 v19, vcc, 1.0, v10, 1.0
	v_add_f32_e32 v11, 1.0, v11
	v_fma_f32 v22, -v12, v13, 1.0
	v_fmac_f32_e32 v13, v22, v13
	v_mul_f32_e32 v22, v19, v13
	v_fma_f32 v23, -v12, v22, v19
	v_fmac_f32_e32 v22, v23, v13
	v_fma_f32 v12, -v12, v22, v19
	v_div_scale_f32 v19, s[6:7], v11, v11, 1.0
	v_rcp_f32_e32 v23, v19
	v_div_fmas_f32 v12, v12, v13, v22
	v_div_fixup_f32 v10, v12, v10, 1.0
	v_mul_f32_e32 v13, 0xbfb8aa3b, v8
	v_mul_f32_e32 v6, v6, v10
	v_fma_f32 v10, -v19, v23, 1.0
	v_exp_f32_e32 v13, v13
	v_fmac_f32_e32 v23, v10, v23
	v_div_scale_f32 v10, vcc, 1.0, v11, 1.0
	v_mul_f32_e32 v12, v10, v23
	v_fma_f32 v22, -v19, v12, v10
	v_fmac_f32_e32 v12, v22, v23
	v_add_f32_e32 v13, 1.0, v13
	v_fma_f32 v10, -v19, v12, v10
	v_div_scale_f32 v19, s[6:7], v13, v13, 1.0
	v_rcp_f32_e32 v22, v19
	v_div_fmas_f32 v10, v10, v23, v12
	v_div_fixup_f32 v10, v10, v11, 1.0
	v_mul_f32_e32 v12, 0xbfb8aa3b, v9
	v_mul_f32_e32 v7, v7, v10
	v_fma_f32 v10, -v19, v22, 1.0
	v_exp_f32_e32 v12, v12
	v_fmac_f32_e32 v22, v10, v22
	v_div_scale_f32 v10, vcc, 1.0, v13, 1.0
	v_mul_f32_e32 v11, v10, v22
	v_fma_f32 v23, -v19, v11, v10
	v_fmac_f32_e32 v11, v23, v22
	v_add_f32_e32 v12, 1.0, v12
	v_fma_f32 v10, -v19, v11, v10
	v_div_scale_f32 v19, s[6:7], v12, v12, 1.0
	v_rcp_f32_e32 v23, v19
	v_div_fmas_f32 v10, v10, v22, v11
	v_div_fixup_f32 v10, v10, v13, 1.0
	v_mul_f32_e32 v13, 0xbfb8aa3b, v2
	v_mul_f32_e32 v8, v8, v10
	v_fma_f32 v10, -v19, v23, 1.0
	v_exp_f32_e32 v13, v13
	v_fmac_f32_e32 v23, v10, v23
	v_div_scale_f32 v10, vcc, 1.0, v12, 1.0
	v_mul_f32_e32 v11, v10, v23
	v_fma_f32 v22, -v19, v11, v10
	v_fmac_f32_e32 v11, v22, v23
	v_add_f32_e32 v13, 1.0, v13
	v_fma_f32 v10, -v19, v11, v10
	v_div_scale_f32 v19, s[6:7], v13, v13, 1.0
	v_rcp_f32_e32 v22, v19
	v_div_fmas_f32 v10, v10, v23, v11
	v_div_fixup_f32 v10, v10, v12, 1.0
	v_mul_f32_e32 v12, 0xbfb8aa3b, v3
	v_mul_f32_e32 v9, v9, v10
	v_fma_f32 v10, -v19, v22, 1.0
	v_exp_f32_e32 v12, v12
	v_fmac_f32_e32 v22, v10, v22
	v_div_scale_f32 v10, vcc, 1.0, v13, 1.0
	v_mul_f32_e32 v11, v10, v22
	v_fma_f32 v23, -v19, v11, v10
	v_fmac_f32_e32 v11, v23, v22
	v_add_f32_e32 v12, 1.0, v12
	v_fma_f32 v10, -v19, v11, v10
	v_div_scale_f32 v19, s[6:7], v12, v12, 1.0
	v_rcp_f32_e32 v23, v19
	v_div_fmas_f32 v10, v10, v22, v11
	v_div_fixup_f32 v10, v10, v13, 1.0
	v_mul_f32_e32 v13, 0xbfb8aa3b, v4
	v_mul_f32_e32 v10, v2, v10
	v_fma_f32 v2, -v19, v23, 1.0
	v_exp_f32_e32 v13, v13
	v_fmac_f32_e32 v23, v2, v23
	v_div_scale_f32 v2, vcc, 1.0, v12, 1.0
	v_mul_f32_e32 v11, v2, v23
	v_fma_f32 v22, -v19, v11, v2
	v_fmac_f32_e32 v11, v22, v23
	v_add_f32_e32 v13, 1.0, v13
	v_fma_f32 v2, -v19, v11, v2
	v_div_scale_f32 v19, s[6:7], v13, v13, 1.0
	v_rcp_f32_e32 v22, v19
	v_div_fmas_f32 v2, v2, v23, v11
	v_div_fixup_f32 v2, v2, v12, 1.0
	v_mul_f32_e32 v12, 0xbfb8aa3b, v5
	v_mul_f32_e32 v11, v3, v2
	v_fma_f32 v2, -v19, v22, 1.0
	v_exp_f32_e32 v12, v12
	v_fmac_f32_e32 v22, v2, v22
	v_div_scale_f32 v2, vcc, 1.0, v13, 1.0
	v_mul_f32_e32 v3, v2, v22
	v_fma_f32 v23, -v19, v3, v2
	v_fmac_f32_e32 v3, v23, v22
	v_add_f32_e32 v12, 1.0, v12
	v_fma_f32 v2, -v19, v3, v2
	v_div_scale_f32 v19, s[6:7], v12, v12, 1.0
	v_rcp_f32_e32 v23, v19
	v_div_fmas_f32 v2, v2, v22, v3
	v_div_fixup_f32 v2, v2, v13, 1.0
	v_mul_f32_e32 v13, v4, v2
	v_fma_f32 v2, -v19, v23, 1.0
	v_fmac_f32_e32 v23, v2, v23
	v_div_scale_f32 v2, vcc, 1.0, v12, 1.0
	v_mul_f32_e32 v3, v2, v23
	v_fma_f32 v4, -v19, v3, v2
	v_fmac_f32_e32 v3, v4, v23
	v_fma_f32 v2, -v19, v3, v2
	v_div_fmas_f32 v2, v2, v23, v3
	v_cmp_lt_u32_e32 vcc, s55, v20
	v_div_fixup_f32 v2, v2, v12, 1.0
	v_mul_f32_e32 v5, v5, v2
	v_cndmask_b32_e32 v12, 1.0, v108, vcc
	v_mul_f32_e32 v2, v12, v6
	v_mul_f32_e32 v3, v12, v7
	v_cvt_pk_bf16_f32 v2, v2, v3
	v_mul_f32_e32 v3, v12, v8
	v_mul_f32_e32 v4, v12, v9
	v_cvt_pk_bf16_f32 v3, v3, v4
	v_mul_f32_e32 v4, v12, v10
	v_mul_f32_e32 v6, v12, v11
	v_cvt_pk_bf16_f32 v4, v4, v6
	v_mul_f32_e32 v6, v12, v13
	v_mul_f32_e32 v5, v12, v5
	v_cvt_pk_bf16_f32 v5, v6, v5
	v_mov_b32_e32 v6, s53
	v_cndmask_b32_e32 v6, v6, v94, vcc
	v_add3_u32 v6, v6, v25, v18
	v_add_u32_e32 v19, 0x600, v20
	ds_write_b128 v6, v[2:5]
	v_ashrrev_i32_e32 v2, 1, v19
	v_and_b32_e32 v2, 0xfffffe00, v2
	v_or3_b32 v10, s22, v2, v17
	v_ashrrev_i32_e32 v11, 31, v10
	v_lshlrev_b64 v[24:25], 2, v[10:11]
	v_lshl_add_u64 v[2:3], s[18:19], 0, v[24:25]
	global_load_dwordx4 v[6:9], v[2:3], off
	s_nop 0
	global_load_dwordx4 v[2:5], v[2:3], off offset:16
	v_bfe_u32 v17, v19, 4, 6
	v_or_b32_e32 v22, s64, v17
	v_lshl_add_u64 v[12:13], v[10:11], 1, s[14:15]
	v_lshl_add_u64 v[10:11], s[16:17], 0, v[24:25]
	v_cmp_lt_i32_e32 vcc, 2, v22
	s_and_saveexec_b64 s[6:7], vcc
	s_cbranch_execnz .LBB0_1050
	s_or_b64 exec, exec, s[6:7]
	v_cmp_lt_i32_e32 vcc, 1, v22
	s_and_saveexec_b64 s[6:7], vcc
	s_cbranch_execnz .LBB0_1051

; __device__ __forceinline__ unsigned cvt_pk_bf16(float lo, float hi) { unsigned r; asm volatile("v_cvt_pk_bf16_f32 %0, %1, %2" : "=v"(r) : "v"(lo), "v"(hi)); return r; }
; __device__ __forceinline__ float bflo(unsigned w) { return __uint_as_float(w << 16); }
; __device__ __forceinline__ void conv_silu8(const bf16_t* __restrict__ PROJ, const float* __restrict__ cw, const float* __restrict__ cb, int row, int ch, float (&y)[8]) {
;     const f32x4 b0 = *(const f32x4*)(cb + ch), b1 = *(const f32x4*)(cb + ch + 4);
;     float a[8] = {b0[0], b0[1], b0[2], b0[3], b1[0], b1[1], b1[2], b1[3]};
; #pragma unroll
;     for (int k = 0; k < 4; ++k) { const int rr = row - 3 + k;
;         if (rr >= 0) { const u32x4 x = *(const u32x4*)(PROJ + (size_t)rr * PW + ch);
;             const f32x4 w0 = *(const f32x4*)(cw + k * 1024 + ch), w1 = *(const f32x4*)(cw + k * 1024 + ch + 4);
;             a[0] += w0[0] * bflo(x.x); a[1] += w0[1] * bfhi(x.x); a[2] += w0[2] * bflo(x.y); a[3] += w0[3] * bfhi(x.y);
;             a[4] += w1[0] * bflo(x.z); a[5] += w1[1] * bfhi(x.z); a[6] += w1[2] * bflo(x.w); a[7] += w1[3] * bfhi(x.w); } }
; #pragma unroll
;     for (int i = 0; i < 8; ++i) y[i] = a[i] * sigmoidf(a[i]);
; __device__ __forceinline__ void mlstm_out_unit(const Params& P, int l, int h, int n, char* lds) {
;     ...
;     for (int i = 0; i < 4; ++i) { const int idx = tid + 512 * i, which = idx >> 10, t = (idx >> 4) & 63, c = idx & 15; float y[8];
;         conv_silu8(PROJ, cw, cb, t0 + t, which * 512 + h * 128 + c * 8, y);
;         const float sc = which ? 1.f : 0.08838834764831845f;
;         u32x4 w; w.x = cvt_pk_bf16(y[0] * sc, y[1] * sc); w.y = cvt_pk_bf16(y[2] * sc, y[3] * sc); w.z = cvt_pk_bf16(y[4] * sc, y[5] * sc); w.w = cvt_pk_bf16(y[6] * sc, y[7] * sc);
;         *(u32x4*)((which ? Kl : Ql) + t * 136 + c * 8) = w; }
; #pragma unroll
;     for (int i = 0; i < 4; ++i) { const int idx = tid + 512 * i, t = idx >> 5, c = idx & 31;
;         const u32x4 x = *(const u32x4*)(PROJ + (size_t)(t0 + t) * PW + C_MV + h * 256 + c * 8);
;         bf16_t* vp = VT + (c * 8) * 72 + tsw(c * 8, t);
;         vp[0] = (bf16_t)(x.x & 0xffffu); vp[72] = (bf16_t)(x.x >> 16); vp[144] = (bf16_t)(x.y & 0xffffu); vp[216] = (bf16_t)(x.y >> 16);
;         vp[288] = (bf16_t)(x.z & 0xffffu); vp[360] = (bf16_t)(x.z >> 16); vp[432] = (bf16_t)(x.w & 0xffffu); vp[504] = (bf16_t)(x.w >> 16); }
.LBB0_1004:
	v_mad_u64_u32 v[12:13], s[6:7], v22, s50, v[12:13]
	v_add_co_u32_e32 v26, vcc, 0x3000, v10
	global_load_dwordx4 v[22:25], v[12:13], off
	s_nop 0
	v_addc_co_u32_e32 v27, vcc, 0, v11, vcc
	global_load_dwordx4 v[10:13], v[26:27], off
	s_nop 0
	global_load_dwordx4 v[26:29], v[26:27], off offset:16
	s_waitcnt vmcnt(0) lgkmcnt(0)
	v_lshlrev_b32_e32 v30, 16, v22
	v_and_b32_e32 v31, 0xffff0000, v22
	v_lshlrev_b32_e32 v22, 16, v23
	v_and_b32_e32 v23, 0xffff0000, v23
	v_lshlrev_b32_e32 v32, 16, v24
	v_and_b32_e32 v33, 0xffff0000, v24
	v_lshlrev_b32_e32 v24, 16, v25
	v_and_b32_e32 v25, 0xffff0000, v25
	v_pk_fma_f32 v[6:7], v[10:11], v[30:31], v[6:7]
	v_pk_fma_f32 v[8:9], v[12:13], v[22:23], v[8:9]
	v_pk_fma_f32 v[2:3], v[26:27], v[32:33], v[2:3]
	v_pk_fma_f32 v[4:5], v[28:29], v[24:25], v[4:5]
.LBB0_1005:
	s_waitcnt vmcnt(0) lgkmcnt(0)
	v_mul_f32_e32 v10, 0xbfb8aa3b, v6
	v_exp_f32_e32 v10, v10
	v_mul_f32_e32 v23, 0xbfb8aa3b, v7
	v_exp_f32_e32 v23, v23
	s_lshl_b64 s[6:7], s[44:45], 16
	v_add_f32_e32 v10, 1.0, v10
	v_div_scale_f32 v11, s[8:9], v10, v10, 1.0
	v_rcp_f32_e32 v12, v11
	v_div_scale_f32 v13, vcc, 1.0, v10, 1.0
	s_add_u32 s6, s40, s6
	v_fma_f32 v22, -v11, v12, 1.0
	v_fmac_f32_e32 v12, v22, v12
	v_mul_f32_e32 v22, v13, v12
	v_fma_f32 v24, -v11, v22, v13
	v_fmac_f32_e32 v22, v24, v12
	v_fma_f32 v11, -v11, v22, v13
	v_add_f32_e32 v13, 1.0, v23
	v_div_scale_f32 v23, s[8:9], v13, v13, 1.0
	v_rcp_f32_e32 v24, v23
	v_div_fmas_f32 v11, v11, v12, v22
	v_mul_f32_e32 v12, 0xbfb8aa3b, v8
	v_div_fixup_f32 v10, v11, v10, 1.0
	v_exp_f32_e32 v12, v12
	v_mul_f32_e32 v6, v6, v10
	v_fma_f32 v10, -v23, v24, 1.0
	v_fmac_f32_e32 v24, v10, v24
	v_div_scale_f32 v10, vcc, 1.0, v13, 1.0
	v_mul_f32_e32 v11, v10, v24
	v_fma_f32 v22, -v23, v11, v10
	v_add_f32_e32 v12, 1.0, v12
	v_fmac_f32_e32 v11, v22, v24
	v_div_scale_f32 v22, s[8:9], v12, v12, 1.0
	v_fma_f32 v10, -v23, v11, v10
	v_rcp_f32_e32 v23, v22
	v_div_fmas_f32 v10, v10, v24, v11
	v_div_fixup_f32 v10, v10, v13, 1.0
	v_mul_f32_e32 v13, 0xbfb8aa3b, v9
	v_mul_f32_e32 v7, v7, v10
	v_fma_f32 v10, -v22, v23, 1.0
	v_exp_f32_e32 v13, v13
	v_fmac_f32_e32 v23, v10, v23
	v_div_scale_f32 v10, vcc, 1.0, v12, 1.0
	v_mul_f32_e32 v11, v10, v23
	v_fma_f32 v24, -v22, v11, v10
	v_fmac_f32_e32 v11, v24, v23
	v_add_f32_e32 v13, 1.0, v13
	v_fma_f32 v10, -v22, v11, v10
	v_div_scale_f32 v22, s[8:9], v13, v13, 1.0
	v_rcp_f32_e32 v24, v22
	v_div_fmas_f32 v10, v10, v23, v11
	v_div_fixup_f32 v10, v10, v12, 1.0
	v_mul_f32_e32 v12, 0xbfb8aa3b, v2
	v_mul_f32_e32 v8, v8, v10
	v_fma_f32 v10, -v22, v24, 1.0
	v_exp_f32_e32 v12, v12
	v_fmac_f32_e32 v24, v10, v24
	v_div_scale_f32 v10, vcc, 1.0, v13, 1.0
	v_mul_f32_e32 v11, v10, v24
	v_fma_f32 v23, -v22, v11, v10
	v_fmac_f32_e32 v11, v23, v24
	v_add_f32_e32 v12, 1.0, v12
	v_fma_f32 v10, -v22, v11, v10
	v_div_scale_f32 v22, s[8:9], v12, v12, 1.0
	v_rcp_f32_e32 v23, v22
	v_div_fmas_f32 v10, v10, v24, v11
	v_div_fixup_f32 v10, v10, v13, 1.0
	v_mul_f32_e32 v13, 0xbfb8aa3b, v3
	v_mul_f32_e32 v9, v9, v10
	v_fma_f32 v10, -v22, v23, 1.0
	v_exp_f32_e32 v13, v13
	v_fmac_f32_e32 v23, v10, v23
	v_div_scale_f32 v10, vcc, 1.0, v12, 1.0
	v_mul_f32_e32 v11, v10, v23
	v_fma_f32 v24, -v22, v11, v10
	v_fmac_f32_e32 v11, v24, v23
	v_add_f32_e32 v13, 1.0, v13
	v_fma_f32 v10, -v22, v11, v10
	v_div_scale_f32 v22, s[8:9], v13, v13, 1.0
	v_rcp_f32_e32 v24, v22
	v_div_fmas_f32 v10, v10, v23, v11
	v_div_fixup_f32 v10, v10, v12, 1.0
	v_mul_f32_e32 v12, 0xbfb8aa3b, v4
	v_mul_f32_e32 v10, v2, v10
	v_fma_f32 v2, -v22, v24, 1.0
	v_exp_f32_e32 v12, v12
	v_fmac_f32_e32 v24, v2, v24
	v_div_scale_f32 v2, vcc, 1.0, v13, 1.0
	v_mul_f32_e32 v11, v2, v24
	v_fma_f32 v23, -v22, v11, v2
	v_fmac_f32_e32 v11, v23, v24
	v_add_f32_e32 v12, 1.0, v12
	v_fma_f32 v2, -v22, v11, v2
	v_div_scale_f32 v22, s[8:9], v12, v12, 1.0
	v_rcp_f32_e32 v23, v22
	v_div_fmas_f32 v2, v2, v24, v11
	v_div_fixup_f32 v2, v2, v13, 1.0
	v_mul_f32_e32 v13, 0xbfb8aa3b, v5
	v_mul_f32_e32 v11, v3, v2
	v_fma_f32 v2, -v22, v23, 1.0
	v_exp_f32_e32 v13, v13
	v_fmac_f32_e32 v23, v2, v23
	v_div_scale_f32 v2, vcc, 1.0, v12, 1.0
	v_mul_f32_e32 v3, v2, v23
	v_fma_f32 v24, -v22, v3, v2
	v_fmac_f32_e32 v3, v24, v23
	v_add_f32_e32 v13, 1.0, v13
	v_fma_f32 v2, -v22, v3, v2
	v_div_scale_f32 v22, s[8:9], v13, v13, 1.0
	v_rcp_f32_e32 v24, v22
	v_div_fmas_f32 v2, v2, v23, v3
	v_div_fixup_f32 v2, v2, v12, 1.0
	v_mul_f32_e32 v12, v4, v2
	v_fma_f32 v2, -v22, v24, 1.0
	v_fmac_f32_e32 v24, v2, v24
	v_div_scale_f32 v2, vcc, 1.0, v13, 1.0
	v_mul_f32_e32 v3, v2, v24
	v_fma_f32 v4, -v22, v3, v2
	v_fmac_f32_e32 v3, v4, v24
	v_fma_f32 v2, -v22, v3, v2
	v_div_fmas_f32 v2, v2, v24, v3
	v_cmp_gt_u32_e32 vcc, s52, v19
	v_div_fixup_f32 v2, v2, v13, 1.0
	v_mul_f32_e32 v5, v5, v2
	v_cndmask_b32_e32 v13, 1.0, v108, vcc
	v_mul_f32_e32 v2, v13, v6
	v_mul_f32_e32 v3, v13, v7
	v_cvt_pk_bf16_f32 v2, v2, v3
	v_mul_f32_e32 v3, v13, v8
	v_mul_f32_e32 v4, v13, v9
	v_cvt_pk_bf16_f32 v3, v3, v4
	v_mul_f32_e32 v4, v13, v10
	v_mul_f32_e32 v6, v13, v11
	v_cvt_pk_bf16_f32 v4, v4, v6
	v_mul_f32_e32 v6, v13, v12
	v_mul_f32_e32 v5, v13, v5
	v_cvt_pk_bf16_f32 v5, v6, v5
	v_mov_b32_e32 v6, s53
	v_cndmask_b32_e32 v6, v6, v94, vcc
	v_mul_u32_u24_e32 v7, 0x110, v17
	v_add3_u32 v6, v6, v7, v18
	v_ashrrev_i32_e32 v9, 5, v20
	ds_write_b128 v6, v[2:5]
	v_add_u32_e32 v2, s64, v9
	v_mov_b64_e32 v[6:7], s[14:15]
	s_addc_u32 s7, s41, s7
	v_and_b32_e32 v8, 0xf8, v15
	v_mad_i64_i32 v[2:3], s[8:9], v2, s50, v[6:7]
	s_lshl_b32 s26, s66, 9
	v_lshl_add_u64 v[2:3], v[2:3], 0, s[26:27]
	v_lshlrev_b32_e32 v90, 1, v8
	v_lshl_add_u64 v[2:3], v[2:3], 0, v[90:91]
	global_load_dwordx4 v[2:5], v[2:3], off offset:2048
	v_add_u32_e32 v10, v9, v15
	v_and_b32_e32 v10, 62, v10
	v_lshlrev_b32_e32 v9, 1, v9
	v_mad_u32_u24 v8, v8, s56, v94
	v_lshlrev_b32_e32 v10, 1, v10
	v_and_b32_e32 v9, 2, v9
	v_add3_u32 v9, v8, v10, v9
	v_and_b32_e32 v22, 31, v20
	v_lshl_or_b32 v18, s65, 5, v22
	s_cmp_gt_i32 s65, 3
	s_waitcnt vmcnt(0) lgkmcnt(0)
; __device__ __forceinline__ int tsw(int row, int t) { return ((((t >> 1) + 4 * ((row >> 3) & 7)) & 31) << 1) | (t & 1); }
; __device__ __forceinline__ void mlstm_out_unit(const Params& P, int l, int h, int n, char* lds) {
;     ...
;     for (int i = 0; i < 4; ++i) { const int idx = tid + 512 * i, t = idx >> 5, c = idx & 31;
;         const u32x4 x = *(const u32x4*)(PROJ + (size_t)(t0 + t) * PW + C_MV + h * 256 + c * 8);
;         bf16_t* vp = VT + (c * 8) * 72 + tsw(c * 8, t);
;         vp[0] = (bf16_t)(x.x & 0xffffu); vp[72] = (bf16_t)(x.x >> 16); vp[144] = (bf16_t)(x.y & 0xffffu); vp[216] = (bf16_t)(x.y >> 16);
;         vp[288] = (bf16_t)(x.z & 0xffffu); vp[360] = (bf16_t)(x.z >> 16); vp[432] = (bf16_t)(x.w & 0xffffu); vp[504] = (bf16_t)(x.w >> 16); }
;     bf16x8 cfr[8];
; #pragma unroll
;     for (int ks = 0; ks < 8; ++ks) cfr[ks] = *(const bf16x8*)(ct + (size_t)(32 * wid + r32) * 128 + 16 * ks + 8 * hi);
;     __syncthreads();
;     if (wid < 4) {
;         const int ti = wid >> 1, si = wid & 1;
;         f32x16 acc = {};
;         if (si <= ti) {
; #pragma unroll
;             for (int ks = 0; ks < 8; ++ks) { const bf16x8 A = *(const bf16x8*)(Ql + (32 * ti + r32) * 136 + 16 * ks + 8 * hi);
;                 const bf16x8 B = *(const bf16x8*)(Kl + (32 * si + r32) * 136 + 16 * ks + 8 * hi);
;                 acc = __builtin_amdgcn_mfma_f32_32x32x16_bf16(A, B, acc, 0, 0, 0); }
	ds_write_b16 v9, v2 offset:34816
	ds_write_b16_d16_hi v9, v2 offset:34960
	ds_write_b16 v9, v3 offset:35104
	ds_write_b16_d16_hi v9, v3 offset:35248
	ds_write_b16 v9, v4 offset:35392
	ds_write_b16_d16_hi v9, v4 offset:35536
	ds_write_b16 v9, v5 offset:35680
	ds_write_b16_d16_hi v9, v5 offset:35824
	v_ashrrev_i32_e32 v9, 5, v16
	v_add_u32_e32 v2, s64, v9
	v_mad_i64_i32 v[2:3], s[8:9], v2, s50, v[6:7]
	v_lshl_add_u64 v[2:3], v[2:3], 0, s[26:27]
	v_lshl_add_u64 v[2:3], v[2:3], 0, v[90:91]
	global_load_dwordx4 v[2:5], v[2:3], off offset:2048
	v_add_u32_e32 v10, v9, v15
	v_and_b32_e32 v10, 62, v10
	v_lshlrev_b32_e32 v9, 1, v9
	v_lshlrev_b32_e32 v10, 1, v10
	v_and_b32_e32 v9, 2, v9
	v_add3_u32 v9, v8, v10, v9
	v_ashrrev_i32_e32 v10, 5, v19
	v_add_u32_e32 v12, s64, v10
	v_ashrrev_i32_e32 v19, 31, v18
	s_waitcnt vmcnt(0) lgkmcnt(0)
	ds_write_b16 v9, v2 offset:34816
	ds_write_b16_d16_hi v9, v2 offset:34960
	ds_write_b16 v9, v3 offset:35104
	ds_write_b16_d16_hi v9, v3 offset:35248
	ds_write_b16 v9, v4 offset:35392
	ds_write_b16_d16_hi v9, v4 offset:35536
	ds_write_b16 v9, v5 offset:35680
	ds_write_b16_d16_hi v9, v5 offset:35824
	v_ashrrev_i32_e32 v9, 5, v21
	v_add_u32_e32 v2, s64, v9
	v_mad_i64_i32 v[2:3], s[8:9], v2, s50, v[6:7]
	v_lshl_add_u64 v[2:3], v[2:3], 0, s[26:27]
	v_lshl_add_u64 v[2:3], v[2:3], 0, v[90:91]
	global_load_dwordx4 v[2:5], v[2:3], off offset:2048
	v_add_u32_e32 v11, v9, v15
	v_lshlrev_b32_e32 v9, 1, v9
	v_and_b32_e32 v11, 62, v11
	v_and_b32_e32 v9, 2, v9
	v_mad_i64_i32 v[6:7], s[8:9], v12, s50, v[6:7]
	v_lshlrev_b32_e32 v11, 1, v11
	v_lshl_add_u64 v[6:7], v[6:7], 0, s[26:27]
	v_add3_u32 v9, v8, v11, v9
	v_lshl_add_u64 v[6:7], v[6:7], 0, v[90:91]
	s_waitcnt vmcnt(0) lgkmcnt(0)
	ds_write_b16 v9, v2 offset:34816
	ds_write_b16_d16_hi v9, v2 offset:34960
	ds_write_b16 v9, v3 offset:35104
	ds_write_b16_d16_hi v9, v3 offset:35248
	ds_write_b16 v9, v4 offset:35392
	ds_write_b16_d16_hi v9, v4 offset:35536
	ds_write_b16 v9, v5 offset:35680
	ds_write_b16_d16_hi v9, v5 offset:35824
	global_load_dwordx4 v[2:5], v[6:7], off offset:2048
	v_add_u32_e32 v6, v10, v15
	v_lshlrev_b32_e32 v7, 1, v10
	v_and_b32_e32 v6, 62, v6
	v_lshrrev_b32_e32 v21, 5, v14
	v_and_b32_e32 v9, 2, v7
	v_lshlrev_b32_e32 v10, 1, v6
	v_lshlrev_b64 v[6:7], 8, v[18:19]
	v_lshl_add_u64 v[6:7], s[6:7], 0, v[6:7]
	v_lshlrev_b32_e32 v90, 4, v21
	v_add3_u32 v10, v8, v10, v9
	v_lshl_add_u64 v[6:7], v[6:7], 0, v[90:91]
	v_lshl_add_u64 v[8:9], v[6:7], 0, s[30:31]
	v_add_co_u32_e32 v6, vcc, s57, v6
	s_waitcnt vmcnt(0) lgkmcnt(0)
	ds_write_b16 v10, v2 offset:34816
	ds_write_b16_d16_hi v10, v2 offset:34960
	ds_write_b16 v10, v3 offset:35104
	ds_write_b16_d16_hi v10, v3 offset:35248
	ds_write_b16 v10, v4 offset:35392
	ds_write_b16_d16_hi v10, v4 offset:35536
	ds_write_b16 v10, v5 offset:35680
	ds_write_b16_d16_hi v10, v5 offset:35824
	v_addc_co_u32_e32 v7, vcc, 0, v7, vcc
	global_load_dwordx4 v[86:89], v[8:9], off offset:32
	global_load_dwordx4 v[82:85], v[8:9], off offset:64
	global_load_dwordx4 v[78:81], v[8:9], off offset:96
	global_load_dwordx4 v[74:77], v[8:9], off offset:128
	global_load_dwordx4 v[70:73], v[8:9], off offset:160
	global_load_dwordx4 v[66:69], v[8:9], off offset:192
	global_load_dwordx4 v[46:49], v[6:7], off
	global_load_dwordx4 v[62:65], v[8:9], off offset:224
	v_lshlrev_b32_e32 v19, 3, v21
	s_waitcnt lgkmcnt(0)
	s_barrier
	s_cbranch_scc1 .LBB0_1043
	s_ashr_i32 s8, s67, 7
	s_bfe_u32 s9, s67, 0x10006
	s_cmp_le_i32 s9, s8
	s_mov_b64 s[6:7], -1
	s_cbranch_scc0 .LBB0_1008
	s_lshl_b32 s10, s8, 5
	v_or_b32_e32 v2, s10, v22
	v_mul_lo_u32 v2, v2, s54
	v_lshlrev_b32_e32 v6, 1, v19
	v_add3_u32 v40, s3, v2, v6
	ds_read_b128 v[2:5], v40
	v_lshl_or_b32 v23, s9, 5, v22
	v_mul_u32_u24_e32 v7, 0x110, v23
	v_add3_u32 v41, s3, v7, v6
	ds_read_b128 v[6:9], v41 offset:17408
	ds_read_b128 v[24:27], v41 offset:17440
	ds_read_b128 v[28:31], v40 offset:32
	s_mov_b64 s[6:7], 0
	s_waitcnt lgkmcnt(0)
	v_mfma_f32_32x32x16_bf16 v[2:17], v[2:5], v[6:9], 0
	v_mfma_f32_32x32x16_bf16 v[2:17], v[28:31], v[24:27], v[2:17]
	ds_read_b128 v[24:27], v40 offset:64
	ds_read_b128 v[28:31], v41 offset:17472
	ds_read_b128 v[32:35], v41 offset:17504
	ds_read_b128 v[36:39], v40 offset:96
	s_waitcnt lgkmcnt(0)
	v_mfma_f32_32x32x16_bf16 v[2:17], v[24:27], v[28:31], v[2:17]
	v_mfma_f32_32x32x16_bf16 v[2:17], v[36:39], v[32:35], v[2:17]
	ds_read_b128 v[24:27], v40 offset:128
	ds_read_b128 v[28:31], v41 offset:17536
	ds_read_b128 v[32:35], v41 offset:17568
	ds_read_b128 v[36:39], v40 offset:160
	s_waitcnt lgkmcnt(0)
	v_mfma_f32_32x32x16_bf16 v[2:17], v[24:27], v[28:31], v[2:17]
	v_mfma_f32_32x32x16_bf16 v[2:17], v[36:39], v[32:35], v[2:17]
	ds_read_b128 v[24:27], v40 offset:192
	ds_read_b128 v[28:31], v41 offset:17600
	ds_read_b128 v[32:35], v40 offset:224
	ds_read_b128 v[36:39], v41 offset:17632
	s_waitcnt lgkmcnt(0)
	v_mfma_f32_32x32x16_bf16 v[2:17], v[24:27], v[28:31], v[2:17]
	v_mov_b32_e32 v25, s10
	v_mfma_f32_32x32x16_bf16 v[2:17], v[32:35], v[36:39], v[2:17]

; __device__ __forceinline__ float bflo(unsigned w) { return __uint_as_float(w << 16); }
; __device__ __forceinline__ float bfhi(unsigned w) { return __uint_as_float(w & 0xffff0000u); }
; __device__ __forceinline__ void conv_silu8(const bf16_t* __restrict__ PROJ, const float* __restrict__ cw, const float* __restrict__ cb, int row, int ch, float (&y)[8]) {
;     ...
;     for (int k = 0; k < 4; ++k) { const int rr = row - 3 + k;
;         if (rr >= 0) { const u32x4 x = *(const u32x4*)(PROJ + (size_t)rr * PW + ch);
;             const f32x4 w0 = *(const f32x4*)(cw + k * 1024 + ch), w1 = *(const f32x4*)(cw + k * 1024 + ch + 4);
;             a[0] += w0[0] * bflo(x.x); a[1] += w0[1] * bfhi(x.x); a[2] += w0[2] * bflo(x.y); a[3] += w0[3] * bfhi(x.y);
;             a[4] += w1[0] * bflo(x.z); a[5] += w1[1] * bfhi(x.z); a[6] += w1[2] * bflo(x.w); a[7] += w1[3] * bfhi(x.w); } }
.LBB0_1045:
	v_add_u32_e32 v27, -3, v26
	v_mad_u64_u32 v[28:29], s[68:69], v27, s50, v[12:13]
	global_load_dwordx4 v[28:31], v[28:29], off
	s_nop 0
	global_load_dwordx4 v[32:35], v[10:11], off
	global_load_dwordx4 v[36:39], v[10:11], off offset:16
	s_waitcnt vmcnt(0) lgkmcnt(0)
	v_lshlrev_b32_e32 v40, 16, v28
	v_and_b32_e32 v41, 0xffff0000, v28
	v_lshlrev_b32_e32 v28, 16, v29
	v_and_b32_e32 v29, 0xffff0000, v29
	v_lshlrev_b32_e32 v42, 16, v30
	v_and_b32_e32 v43, 0xffff0000, v30
	v_lshlrev_b32_e32 v30, 16, v31
	v_and_b32_e32 v31, 0xffff0000, v31
	v_pk_fma_f32 v[6:7], v[32:33], v[40:41], v[6:7]
	v_pk_fma_f32 v[8:9], v[34:35], v[28:29], v[8:9]
	v_pk_fma_f32 v[2:3], v[36:37], v[42:43], v[2:3]
	v_pk_fma_f32 v[4:5], v[38:39], v[30:31], v[4:5]
	s_or_b64 exec, exec, s[12:13]
	v_cmp_lt_i32_e32 vcc, 1, v26
	s_and_saveexec_b64 s[12:13], vcc
	s_cbranch_execz .LBB0_991
.LBB0_1046:
	v_add_u32_e32 v27, -2, v26
	v_mad_u64_u32 v[28:29], s[68:69], v27, s50, v[12:13]
	v_add_co_u32_e32 v36, vcc, 0x1000, v10
	global_load_dwordx4 v[28:31], v[28:29], off
	s_nop 0
	v_addc_co_u32_e32 v37, vcc, 0, v11, vcc
	global_load_dwordx4 v[32:35], v[36:37], off
	s_nop 0
	global_load_dwordx4 v[36:39], v[36:37], off offset:16
	s_waitcnt vmcnt(0) lgkmcnt(0)
	v_lshlrev_b32_e32 v40, 16, v28
	v_and_b32_e32 v41, 0xffff0000, v28
	v_lshlrev_b32_e32 v28, 16, v29
	v_and_b32_e32 v29, 0xffff0000, v29
	v_lshlrev_b32_e32 v42, 16, v30
	v_and_b32_e32 v43, 0xffff0000, v30
	v_lshlrev_b32_e32 v30, 16, v31
	v_and_b32_e32 v31, 0xffff0000, v31
	v_pk_fma_f32 v[6:7], v[32:33], v[40:41], v[6:7]
	v_pk_fma_f32 v[8:9], v[34:35], v[28:29], v[8:9]
	v_pk_fma_f32 v[2:3], v[36:37], v[42:43], v[2:3]
	v_pk_fma_f32 v[4:5], v[38:39], v[30:31], v[4:5]
	s_or_b64 exec, exec, s[12:13]
	v_cmp_lt_i32_e32 vcc, 0, v26
	s_and_saveexec_b64 s[12:13], vcc
	s_cbranch_execnz .LBB0_992
	s_branch .LBB0_993
.LBB0_1047:
	v_mad_u64_u32 v[26:27], s[6:7], v22, s50, v[12:13]
	global_load_dwordx4 v[26:29], v[26:27], off
	s_nop 0
	global_load_dwordx4 v[30:33], v[10:11], off
	global_load_dwordx4 v[34:37], v[10:11], off offset:16
	s_waitcnt vmcnt(0) lgkmcnt(0)
	v_lshlrev_b32_e32 v38, 16, v26
	v_and_b32_e32 v39, 0xffff0000, v26
	v_lshlrev_b32_e32 v26, 16, v27
	v_and_b32_e32 v27, 0xffff0000, v27
	v_lshlrev_b32_e32 v40, 16, v28
	v_and_b32_e32 v41, 0xffff0000, v28
	v_lshlrev_b32_e32 v28, 16, v29
	v_and_b32_e32 v29, 0xffff0000, v29
	v_pk_fma_f32 v[6:7], v[30:31], v[38:39], v[6:7]
	v_pk_fma_f32 v[8:9], v[32:33], v[26:27], v[8:9]
	v_pk_fma_f32 v[2:3], v[34:35], v[40:41], v[2:3]
	v_pk_fma_f32 v[4:5], v[36:37], v[28:29], v[4:5]
	s_or_b64 exec, exec, s[20:21]
	s_and_saveexec_b64 s[6:7], s[8:9]
	s_cbranch_execz .LBB0_997
.LBB0_1048:
	v_mad_u64_u32 v[22:23], s[8:9], v23, s50, v[12:13]
	global_load_dwordx4 v[26:29], v[22:23], off
	v_add_co_u32_e32 v22, vcc, 0x1000, v10
	s_waitcnt vmcnt(0) lgkmcnt(0)
	v_lshlrev_b32_e32 v38, 16, v28
	v_addc_co_u32_e32 v23, vcc, 0, v11, vcc
	global_load_dwordx4 v[30:33], v[22:23], off
	global_load_dwordx4 v[34:37], v[22:23], off offset:16
	v_lshlrev_b32_e32 v22, 16, v26
	v_and_b32_e32 v23, 0xffff0000, v26
	v_lshlrev_b32_e32 v26, 16, v27
	v_and_b32_e32 v27, 0xffff0000, v27
	v_and_b32_e32 v39, 0xffff0000, v28
	v_lshlrev_b32_e32 v28, 16, v29
	v_and_b32_e32 v29, 0xffff0000, v29
	s_waitcnt vmcnt(0) lgkmcnt(0)
	v_pk_fma_f32 v[6:7], v[30:31], v[22:23], v[6:7]
	v_pk_fma_f32 v[8:9], v[32:33], v[26:27], v[8:9]
	v_pk_fma_f32 v[2:3], v[34:35], v[38:39], v[2:3]
	v_pk_fma_f32 v[4:5], v[36:37], v[28:29], v[4:5]
	s_or_b64 exec, exec, s[6:7]
	s_and_saveexec_b64 s[6:7], s[10:11]
	s_cbranch_execz .LBB0_998
; __device__ __forceinline__ float bflo(unsigned w) { return __uint_as_float(w << 16); }
; __device__ __forceinline__ float bfhi(unsigned w) { return __uint_as_float(w & 0xffff0000u); }
; __device__ __forceinline__ void conv_silu8(const bf16_t* __restrict__ PROJ, const float* __restrict__ cw, const float* __restrict__ cb, int row, int ch, float (&y)[8]) {
;     ...
;     for (int k = 0; k < 4; ++k) { const int rr = row - 3 + k;
;         if (rr >= 0) { const u32x4 x = *(const u32x4*)(PROJ + (size_t)rr * PW + ch);
;             const f32x4 w0 = *(const f32x4*)(cw + k * 1024 + ch), w1 = *(const f32x4*)(cw + k * 1024 + ch + 4);
;             a[0] += w0[0] * bflo(x.x); a[1] += w0[1] * bfhi(x.x); a[2] += w0[2] * bflo(x.y); a[3] += w0[3] * bfhi(x.y);
;             a[4] += w1[0] * bflo(x.z); a[5] += w1[1] * bfhi(x.z); a[6] += w1[2] * bflo(x.w); a[7] += w1[3] * bfhi(x.w); } }
.LBB0_1049:
	v_mad_u64_u32 v[22:23], s[8:9], v24, s50, v[12:13]
	global_load_dwordx4 v[26:29], v[22:23], off
	v_add_co_u32_e32 v22, vcc, 0x2000, v10
	s_waitcnt vmcnt(0) lgkmcnt(0)
	v_lshlrev_b32_e32 v38, 16, v28
	v_addc_co_u32_e32 v23, vcc, 0, v11, vcc
	global_load_dwordx4 v[30:33], v[22:23], off
	global_load_dwordx4 v[34:37], v[22:23], off offset:16
	v_lshlrev_b32_e32 v22, 16, v26
	v_and_b32_e32 v23, 0xffff0000, v26
	v_lshlrev_b32_e32 v26, 16, v27
	v_and_b32_e32 v27, 0xffff0000, v27
	v_and_b32_e32 v39, 0xffff0000, v28
	v_lshlrev_b32_e32 v28, 16, v29
	v_and_b32_e32 v29, 0xffff0000, v29
	s_waitcnt vmcnt(0) lgkmcnt(0)
	v_pk_fma_f32 v[6:7], v[30:31], v[22:23], v[6:7]
	v_pk_fma_f32 v[8:9], v[32:33], v[26:27], v[8:9]
	v_pk_fma_f32 v[2:3], v[34:35], v[38:39], v[2:3]
	v_pk_fma_f32 v[4:5], v[36:37], v[28:29], v[4:5]
	s_or_b64 exec, exec, s[6:7]
	s_and_b64 vcc, exec, s[12:13]
	s_cbranch_vccz .LBB0_999
	s_branch .LBB0_1000
.LBB0_1050:
	v_add_u32_e32 v23, -3, v22
	v_mad_u64_u32 v[24:25], s[8:9], v23, s50, v[12:13]
	global_load_dwordx4 v[24:27], v[24:25], off
	s_nop 0
	global_load_dwordx4 v[28:31], v[10:11], off
	global_load_dwordx4 v[32:35], v[10:11], off offset:16
	s_waitcnt vmcnt(0) lgkmcnt(0)
	v_lshlrev_b32_e32 v36, 16, v24
	v_and_b32_e32 v37, 0xffff0000, v24
	v_lshlrev_b32_e32 v24, 16, v25
	v_and_b32_e32 v25, 0xffff0000, v25
	v_lshlrev_b32_e32 v38, 16, v26
	v_and_b32_e32 v39, 0xffff0000, v26
	v_lshlrev_b32_e32 v26, 16, v27
	v_and_b32_e32 v27, 0xffff0000, v27
	v_pk_fma_f32 v[6:7], v[28:29], v[36:37], v[6:7]
	v_pk_fma_f32 v[8:9], v[30:31], v[24:25], v[8:9]
	v_pk_fma_f32 v[2:3], v[32:33], v[38:39], v[2:3]
	v_pk_fma_f32 v[4:5], v[34:35], v[26:27], v[4:5]
	s_or_b64 exec, exec, s[6:7]
	v_cmp_lt_i32_e32 vcc, 1, v22
	s_and_saveexec_b64 s[6:7], vcc
	s_cbranch_execz .LBB0_1002
.LBB0_1051:
	v_add_u32_e32 v23, -2, v22
	v_mad_u64_u32 v[24:25], s[8:9], v23, s50, v[12:13]
	v_add_co_u32_e32 v32, vcc, 0x1000, v10
	global_load_dwordx4 v[24:27], v[24:25], off
	s_nop 0
	v_addc_co_u32_e32 v33, vcc, 0, v11, vcc
	global_load_dwordx4 v[28:31], v[32:33], off
	s_nop 0
	global_load_dwordx4 v[32:35], v[32:33], off offset:16
	s_waitcnt vmcnt(0) lgkmcnt(0)
	v_lshlrev_b32_e32 v36, 16, v24
	v_and_b32_e32 v37, 0xffff0000, v24
	v_lshlrev_b32_e32 v24, 16, v25
	v_and_b32_e32 v25, 0xffff0000, v25
	v_lshlrev_b32_e32 v38, 16, v26
	v_and_b32_e32 v39, 0xffff0000, v26
	v_lshlrev_b32_e32 v26, 16, v27
	v_and_b32_e32 v27, 0xffff0000, v27
	v_pk_fma_f32 v[6:7], v[28:29], v[36:37], v[6:7]
	v_pk_fma_f32 v[8:9], v[30:31], v[24:25], v[8:9]
	v_pk_fma_f32 v[2:3], v[32:33], v[38:39], v[2:3]
	v_pk_fma_f32 v[4:5], v[34:35], v[26:27], v[4:5]
	s_or_b64 exec, exec, s[6:7]
	v_cmp_lt_i32_e32 vcc, 0, v22
	s_and_saveexec_b64 s[6:7], vcc
	s_cbranch_execz .LBB0_1003
.LBB0_1052:
	v_add_u32_e32 v23, -1, v22
	v_mad_u64_u32 v[24:25], s[8:9], v23, s50, v[12:13]
	v_add_co_u32_e32 v32, vcc, 0x2000, v10
	global_load_dwordx4 v[24:27], v[24:25], off
	s_nop 0
	v_addc_co_u32_e32 v33, vcc, 0, v11, vcc
	global_load_dwordx4 v[28:31], v[32:33], off
	s_nop 0
	global_load_dwordx4 v[32:35], v[32:33], off offset:16
	s_waitcnt vmcnt(0) lgkmcnt(0)
	v_lshlrev_b32_e32 v36, 16, v24
	v_and_b32_e32 v37, 0xffff0000, v24
	v_lshlrev_b32_e32 v24, 16, v25
	v_and_b32_e32 v25, 0xffff0000, v25
	v_lshlrev_b32_e32 v38, 16, v26
	v_and_b32_e32 v39, 0xffff0000, v26
	v_lshlrev_b32_e32 v26, 16, v27
	v_and_b32_e32 v27, 0xffff0000, v27
	v_pk_fma_f32 v[6:7], v[28:29], v[36:37], v[6:7]
	v_pk_fma_f32 v[8:9], v[30:31], v[24:25], v[8:9]
	v_pk_fma_f32 v[2:3], v[32:33], v[38:39], v[2:3]
	v_pk_fma_f32 v[4:5], v[34:35], v[26:27], v[4:5]
	s_or_b64 exec, exec, s[6:7]
	s_and_b64 vcc, exec, s[12:13]
	s_cbranch_vccz .LBB0_1004
	s_branch .LBB0_1005

; template <int KSPLIT, class Epi>
; __device__ __forceinline__ void skinny_gemm(const bf16_t* __restrict__ A, int lda, const bf16_t* __restrict__ Wt, int K, int ntiles, char* lds, const Epi& E) {
;     ...
;             const bf16_t* ap = A + (size_t)i * lda + ks * klen + 8 * kq;
;             const bf16_t* wp = Wt + (size_t)(tile * 16 + i) * K + ks * klen + 8 * kq;
;             for (int k = 0; k < klen; k += 256) {
;                 bf16x8 a[8], w[8];
; #pragma unroll
;                 for (int j = 0; j < 8; ++j) { a[j] = *(const bf16x8*)(ap + k + 32 * j); w[j] = *(const bf16x8*)(wp + k + 32 * j); }
; #pragma unroll
;                 for (int j = 0; j < 8; ++j) acc = __builtin_amdgcn_mfma_f32_16x16x32_bf16(w[j], a[j], acc, 0, 0, 0);
;             }
.LBB0_1104:
	s_add_i32 s22, s18, s19
	s_ashr_i32 s6, s22, 31
	s_lshr_b32 s6, s6, 29
	s_add_i32 s6, s22, s6
	s_ashr_i32 s20, s6, 3
	s_and_b32 s6, s6, -8
	s_sub_i32 s21, s22, s6
	v_mov_b32_e32 v4, v2
	v_mov_b32_e32 v5, v2
	v_mov_b32_e32 v3, v2
	s_cmpk_lt_i32 s22, 0x400
	v_mov_b64_e32 v[6:7], v[4:5]
	s_cselect_b64 s[6:7], -1, 0
	s_cmpk_gt_i32 s22, 0x3ff
	v_mov_b64_e32 v[4:5], v[2:3]
	s_cbranch_scc1 .LBB0_1106
	v_lshl_or_b32 v4, s20, 4, v1
	s_lshl_b32 s22, s21, 8
	v_ashrrev_i32_e32 v5, 31, v4
	s_ashr_i32 s23, s22, 31
	v_lshlrev_b64 v[4:5], 12, v[4:5]
	s_lshl_b64 s[22:23], s[22:23], 1
	v_lshl_add_u64 v[4:5], s[8:9], 0, v[4:5]
	v_lshl_add_u64 v[4:5], v[4:5], 0, s[22:23]
	v_mov_b32_e32 v15, v2
	v_lshl_add_u64 v[52:53], v[4:5], 0, v[14:15]
	global_load_dwordx4 v[4:7], v[52:53], off
	v_lshl_add_u64 v[54:55], v[8:9], 0, s[22:23]
	global_load_dwordx4 v[20:23], v[52:53], off offset:64
	global_load_dwordx4 v[24:27], v[54:55], off
	global_load_dwordx4 v[28:31], v[54:55], off offset:64
	global_load_dwordx4 v[32:35], v[52:53], off offset:128
	global_load_dwordx4 v[36:39], v[54:55], off offset:128
	global_load_dwordx4 v[40:43], v[52:53], off offset:192
	global_load_dwordx4 v[44:47], v[54:55], off offset:192
	s_waitcnt vmcnt(0) lgkmcnt(0)
	v_mfma_f32_16x16x32_bf16 v[4:7], v[4:7], v[24:27], 0
	global_load_dwordx4 v[24:27], v[52:53], off offset:256
	global_load_dwordx4 v[48:51], v[54:55], off offset:256
	v_mfma_f32_16x16x32_bf16 v[4:7], v[20:23], v[28:31], v[4:7]
	global_load_dwordx4 v[20:23], v[52:53], off offset:320
	global_load_dwordx4 v[28:31], v[54:55], off offset:320
	v_mfma_f32_16x16x32_bf16 v[4:7], v[32:35], v[36:39], v[4:7]
	global_load_dwordx4 v[32:35], v[52:53], off offset:384
	global_load_dwordx4 v[36:39], v[54:55], off offset:384
	v_mfma_f32_16x16x32_bf16 v[4:7], v[40:43], v[44:47], v[4:7]
	s_waitcnt vmcnt(0) lgkmcnt(0)
	v_mfma_f32_16x16x32_bf16 v[4:7], v[24:27], v[48:51], v[4:7]
	global_load_dwordx4 v[24:27], v[52:53], off offset:448
	v_mfma_f32_16x16x32_bf16 v[4:7], v[20:23], v[28:31], v[4:7]
	global_load_dwordx4 v[20:23], v[54:55], off offset:448
	v_mfma_f32_16x16x32_bf16 v[4:7], v[32:35], v[36:39], v[4:7]
	s_waitcnt vmcnt(0) lgkmcnt(0)
	v_mfma_f32_16x16x32_bf16 v[4:7], v[24:27], v[20:23], v[4:7]

; template <int KSPLIT, class Epi>
; __device__ __forceinline__ void skinny_gemm(const bf16_t* __restrict__ A, int lda, const bf16_t* __restrict__ Wt, int K, int ntiles, char* lds, const Epi& E) {
;     ...
;             __syncthreads();
;         }
;         if (act && ks == 0) E(tile, i, kq, acc);
.LBB0_1110:
	s_and_b64 vcc, exec, s[6:7]
	s_barrier
	s_cbranch_vccnz .LBB0_1103
	v_lshl_or_b32 v20, s20, 4, v16
	v_ashrrev_i32_e32 v21, 31, v20
	v_lshl_add_u64 v[22:23], v[20:21], 1, v[10:11]
	global_load_dwordx2 v[22:23], v[22:23], off
	v_lshl_add_u64 v[20:21], v[20:21], 2, v[12:13]
	s_waitcnt vmcnt(0) lgkmcnt(0)
	v_lshlrev_b32_e32 v24, 16, v22
	v_and_b32_e32 v25, 0xffff0000, v22
	v_lshlrev_b32_e32 v22, 16, v23
	v_and_b32_e32 v23, 0xffff0000, v23
	v_pk_fma_f32 v[4:5], v[24:25], s[16:17], v[4:5] op_sel_hi:[1,0,1]
	v_pk_fma_f32 v[6:7], v[22:23], s[16:17], v[6:7] op_sel_hi:[1,0,1]
	global_store_dwordx4 v[20:21], v[4:7], off
	s_branch .LBB0_1103

; __device__ __forceinline__ void ln_load(f32x4 (&v)[8], const float* z, int lane) {
; #pragma unroll
;     for (int j = 0; j < 8; ++j) v[j] = ((const f32x4*)z)[lane + 64 * j];
; }
; __device__ __forceinline__ void ln_apply(f32x4 (&v)[8], const float* __restrict__ g, const float* __restrict__ b, bf16_t* hb, float* fo, int lane) {
;     float s = 0.f;
; #pragma unroll
;     for (int j = 0; j < 8; ++j) s += (v[j][0] + v[j][1]) + (v[j][2] + v[j][3]);
;     const float mean = wave_sum(s) * (1.f / DM); float q = 0.f;
; #pragma unroll
;     for (int j = 0; j < 8; ++j) { v[j] = v[j] - mean; q += (v[j][0] * v[j][0] + v[j][1] * v[j][1]) + (v[j][2] * v[j][2] + v[j][3] * v[j][3]); }
;     const float rstd = rsqrtf(wave_sum(q) * (1.f / DM) + LN_EPS);
; #pragma unroll
;     for (int j = 0; j < 8; ++j) { const int c = (lane + 64 * j) * 4; const f32x4 gg = *(const f32x4*)(g + c), bb = *(const f32x4*)(b + c);
.LBB0_1194:
	s_cmp_lt_i32 s80, 7
	s_cselect_b64 s[6:7], -1, 0
	s_cmp_gt_i32 s81, 6
	s_cselect_b64 s[8:9], -1, 0
	s_and_b64 s[6:7], s[6:7], s[8:9]
	s_andn2_b64 vcc, exec, s[6:7]
	s_cbranch_vccnz .LBB0_1204
	v_mov_b32_e32 v1, v194
	s_lshl_b32 s6, s2, 3
	v_readfirstlane_b32 s3, v1
	s_ashr_i32 s3, s3, 6
	s_add_i32 s6, s3, s6
	s_mov_b64 s[16:17], s[0:1]
	s_cmpk_gt_i32 s6, 0x400f
	s_cbranch_scc1 .LBB0_1204
	s_load_dword s3, s[0:1], 0xa0
	s_load_dwordx2 s[12:13], s[16:17], 0x90
	v_and_b32_e32 v86, 63, v1
	v_lshlrev_b32_e32 v84, 4, v86
	v_mov_b32_e32 v85, 0
	s_waitcnt lgkmcnt(0)
	s_lshl_b32 s3, s3, 3
	s_add_u32 s14, s12, 0xeb00000
	s_addc_u32 s15, s13, 0
	s_ashr_i32 s7, s6, 31
	s_lshl_b64 s[8:9], s[6:7], 13
	s_add_u32 s8, s14, s8
	s_addc_u32 s9, s15, s9
	v_lshl_add_u64 v[30:31], s[8:9], 0, v[84:85]
	s_movk_i32 s7, 0x1000
	global_load_dwordx4 v[2:5], v[30:31], off
	global_load_dwordx4 v[90:93], v[30:31], off offset:1024
	global_load_dwordx4 v[6:9], v[30:31], off offset:2048
	v_add_co_u32_e32 v32, vcc, s7, v30
	v_mbcnt_lo_u32_b32 v62, -1, 0
	s_nop 0
	v_addc_co_u32_e32 v33, vcc, 0, v31, vcc
	global_load_dwordx4 v[10:13], v[32:33], off
	global_load_dwordx4 v[14:17], v[32:33], off offset:1024
	global_load_dwordx4 v[18:21], v[32:33], off offset:3072
	global_load_dwordx4 v[22:25], v[32:33], off offset:2048
	global_load_dwordx4 v[26:29], v[30:31], off offset:3072
	v_mbcnt_hi_u32_b32 v62, -1, v62
	v_and_b32_e32 v63, 64, v62
	v_xor_b32_e32 v64, 1, v62
	v_add_u32_e32 v63, 64, v63
	v_xor_b32_e32 v65, 2, v62
	v_cmp_lt_i32_e32 vcc, v64, v63
	v_xor_b32_e32 v66, 4, v62
	s_load_dwordx4 s[8:11], s[16:17], 0x58
	v_cndmask_b32_e32 v64, v62, v64, vcc
	v_cmp_lt_i32_e32 vcc, v65, v63
	v_xor_b32_e32 v67, 8, v62
	v_xor_b32_e32 v70, 16, v62
	v_cndmask_b32_e32 v65, v62, v65, vcc
	v_cmp_lt_i32_e32 vcc, v66, v63
	v_xor_b32_e32 v71, 32, v62
	v_or_b32_e32 v68, 0x1000, v84
	v_cndmask_b32_e32 v66, v62, v66, vcc
	v_cmp_lt_i32_e32 vcc, v67, v63
	v_or_b32_e32 v72, 0x1400, v84
	v_or_b32_e32 v76, 0x1800, v84
	v_cndmask_b32_e32 v67, v62, v67, vcc
	v_cmp_lt_i32_e32 vcc, v70, v63
	v_lshlrev_b32_e32 v98, 2, v64
	v_lshlrev_b32_e32 v99, 2, v65
	v_cndmask_b32_e32 v70, v62, v70, vcc
	v_cmp_lt_i32_e32 vcc, v71, v63
	s_waitcnt lgkmcnt(0)
	v_lshl_add_u64 v[64:65], s[10:11], 0, v[84:85]
	v_lshl_add_u64 v[78:79], s[14:15], 0, v[84:85]
	v_cndmask_b32_e32 v62, v62, v71, vcc
	v_lshlrev_b32_e32 v103, 2, v62
	v_lshl_add_u64 v[62:63], s[8:9], 0, v[84:85]
	v_or_b32_e32 v84, 0x1c00, v84
	v_lshl_add_u64 v[80:81], s[8:9], 0, v[84:85]
	v_lshl_add_u64 v[82:83], s[10:11], 0, v[84:85]
	v_lshlrev_b32_e32 v84, 3, v86
	s_mov_b64 s[18:19], 0x6900000
	v_mov_b32_e32 v69, v85
	v_mov_b32_e32 v73, v85
	v_mov_b32_e32 v77, v85
	v_lshl_add_u64 v[84:85], s[12:13], 0, v[84:85]
	v_mov_b32_e32 v1, 0x3727c5ac
	s_mov_b32 s16, 0x800000
	v_lshlrev_b32_e32 v100, 2, v66
	v_lshlrev_b32_e32 v101, 2, v67
	v_lshlrev_b32_e32 v102, 2, v70
	v_lshl_add_u64 v[66:67], s[8:9], 0, v[68:69]
	v_lshl_add_u64 v[68:69], s[10:11], 0, v[68:69]
	v_lshl_add_u64 v[70:71], s[8:9], 0, v[72:73]
	v_lshl_add_u64 v[72:73], s[10:11], 0, v[72:73]
	v_lshl_add_u64 v[74:75], s[8:9], 0, v[76:77]
	v_lshl_add_u64 v[76:77], s[10:11], 0, v[76:77]
	v_lshl_add_u64 v[84:85], v[84:85], 0, s[18:19]
	s_waitcnt vmcnt(0)
	v_mov_b32_e32 v87, v2
	v_mov_b32_e32 v89, v4
	v_mov_b32_e32 v86, v90
	v_mov_b32_e32 v2, v91
	v_mov_b32_e32 v88, v92
	v_mov_b32_e32 v4, v93
	v_mov_b32_e32 v90, v7
	v_mov_b32_e32 v91, v8
	v_mov_b32_e32 v7, v9
	v_mov_b32_e32 v8, v11
	v_mov_b32_e32 v92, v13
	v_mov_b32_e32 v94, v15
	v_mov_b32_e32 v95, v16
	v_mov_b32_e32 v15, v17
	v_mov_b32_e32 v16, v19
	v_mov_b32_e32 v96, v21
	s_branch .LBB0_1199
.LBB0_1197:
	v_mov_b32_e32 v104, v38
	v_mov_b32_e32 v105, v42
	v_mov_b32_e32 v106, v39
	v_mov_b32_e32 v107, v43
	v_pk_add_f32 v[104:105], v[104:105], v[106:107]
	v_mov_b32_e32 v106, v40
	v_mov_b32_e32 v107, v44
	v_mov_b32_e32 v108, v41
	v_mov_b32_e32 v109, v45
	v_pk_add_f32 v[106:107], v[106:107], v[108:109]
	v_mov_b32_e32 v108, v34
	v_pk_add_f32 v[104:105], v[104:105], v[106:107]
	v_mov_b32_e32 v106, v35
	v_mov_b32_e32 v107, v36
	v_mov_b32_e32 v109, v37
	v_pk_add_f32 v[106:107], v[106:107], v[108:109]
	v_add_f32_e32 v9, 0, v105
	v_pk_add_f32 v[106:107], v[106:107], v[106:107] op_sel_hi:[0,1]
	v_add_f32_e32 v105, v104, v9
	v_add_f32_e32 v109, v30, v31
	v_add_f32_e32 v111, v32, v33
	v_mov_b32_e32 v108, v58
	v_mov_b32_e32 v110, v59
	v_mov_b32_e32 v106, v60
	v_mov_b32_e32 v104, v61
	v_pk_add_f32 v[108:109], v[108:109], v[110:111]
	v_pk_add_f32 v[104:105], v[106:107], v[104:105]
	v_mov_b32_e32 v106, v55
	v_pk_add_f32 v[104:105], v[108:109], v[104:105]
	v_mov_b32_e32 v107, v56
	v_mov_b32_e32 v108, v54
	v_mov_b32_e32 v109, v57
	v_pk_add_f32 v[106:107], v[106:107], v[108:109]
	v_pk_add_f32 v[104:105], v[104:105], v[104:105] op_sel_hi:[0,1]
	v_pk_add_f32 v[106:107], v[106:107], v[106:107] op_sel_hi:[0,1]
	v_add_f32_e32 v109, v50, v51
	v_add_f32_e32 v111, v52, v53
	v_mov_b32_e32 v108, v46
	v_mov_b32_e32 v110, v47
	v_mov_b32_e32 v106, v48
	v_mov_b32_e32 v104, v49
	v_pk_add_f32 v[108:109], v[108:109], v[110:111]
	v_pk_add_f32 v[104:105], v[106:107], v[104:105]
	s_ashr_i32 s9, s8, 31
	v_pk_add_f32 v[104:105], v[108:109], v[104:105]
	s_lshl_b64 s[8:9], s[8:9], 12
	v_add_f32_e32 v9, v104, v105
	ds_bpermute_b32 v11, v98, v9
	s_waitcnt lgkmcnt(0)
	v_add_f32_e32 v9, v9, v11
	ds_bpermute_b32 v11, v99, v9
	s_waitcnt lgkmcnt(0)
	v_add_f32_e32 v9, v9, v11
	ds_bpermute_b32 v11, v100, v9
	s_waitcnt lgkmcnt(0)
	v_add_f32_e32 v9, v9, v11
	ds_bpermute_b32 v11, v101, v9
	s_waitcnt lgkmcnt(0)
	v_add_f32_e32 v9, v9, v11
	ds_bpermute_b32 v11, v102, v9
	s_waitcnt lgkmcnt(0)
; __device__ __forceinline__ void ln_apply(f32x4 (&v)[8], const float* __restrict__ g, const float* __restrict__ b, bf16_t* hb, float* fo, int lane) {
;     ...
;     const float mean = wave_sum(s) * (1.f / DM); float q = 0.f;
; #pragma unroll
;     for (int j = 0; j < 8; ++j) { v[j] = v[j] - mean; q += (v[j][0] * v[j][0] + v[j][1] * v[j][1]) + (v[j][2] * v[j][2] + v[j][3] * v[j][3]); }
;     const float rstd = rsqrtf(wave_sum(q) * (1.f / DM) + LN_EPS);
; #pragma unroll
;     for (int j = 0; j < 8; ++j) { const int c = (lane + 64 * j) * 4; const f32x4 gg = *(const f32x4*)(g + c), bb = *(const f32x4*)(b + c);
	v_add_f32_e32 v9, v9, v11
	ds_bpermute_b32 v11, v103, v9
	s_waitcnt lgkmcnt(0)
	v_add_f32_e32 v9, v9, v11
	v_fmamk_f32 v43, v9, 0xba000000, v43
	v_fmamk_f32 v39, v9, 0xba000000, v39
	v_fmamk_f32 v45, v9, 0xba000000, v45
	v_fmac_f32_e32 v42, 0xba000000, v9
	v_fmamk_f32 v41, v9, 0xba000000, v41
	v_fmac_f32_e32 v38, 0xba000000, v9
	v_mov_b32_e32 v106, v43
	v_mov_b32_e32 v107, v39
	v_fmamk_f32 v44, v9, 0xba000000, v44
	v_fmamk_f32 v40, v9, 0xba000000, v40
	v_mov_b32_e32 v104, v42
	v_mov_b32_e32 v105, v38
	v_pk_mul_f32 v[106:107], v[106:107], v[106:107]
	v_mov_b32_e32 v108, v45
	v_mov_b32_e32 v109, v41
	v_pk_fma_f32 v[104:105], v[104:105], v[104:105], v[106:107]
	v_mov_b32_e32 v106, v44
	v_mov_b32_e32 v107, v40
	v_pk_mul_f32 v[108:109], v[108:109], v[108:109]
	v_fmamk_f32 v37, v9, 0xba000000, v37
	v_pk_fma_f32 v[106:107], v[106:107], v[106:107], v[108:109]
	v_fmamk_f32 v36, v9, 0xba000000, v36
	v_pk_add_f32 v[104:105], v[104:105], v[106:107]
	v_fmamk_f32 v35, v9, 0xba000000, v35
	v_fmac_f32_e32 v34, 0xba000000, v9
	v_pk_add_f32 v[104:105], v[104:105], v[104:105] op_sel_hi:[0,1]
	v_pk_mul_f32 v[106:107], v[36:37], v[36:37]
	v_pk_mul_f32 v[108:109], v[34:35], v[34:35]
	v_fmac_f32_e32 v30, 0xba000000, v9
	v_pk_mov_b32 v[110:111], v[108:109], v[106:107] op_sel:[1,0]
	v_mov_b32_e32 v109, v107
	v_fmamk_f32 v32, v9, 0xba000000, v32
	v_fmamk_f32 v31, v9, 0xba000000, v31
	v_mul_f32_e32 v104, v30, v30
	v_pk_add_f32 v[106:107], v[110:111], v[108:109]
	v_fmamk_f32 v33, v9, 0xba000000, v33
	v_pk_fma_f32 v[108:109], v[30:31], v[30:31], v[104:105] op_sel_hi:[1,1,0]
	v_mul_f32_e32 v104, v32, v32
	v_pk_add_f32 v[106:107], v[106:107], v[106:107] op_sel_hi:[0,1]
	v_pk_fma_f32 v[110:111], v[32:33], v[32:33], v[104:105] op_sel_hi:[1,1,0]
	v_fmamk_f32 v61, v9, 0xba000000, v61
	v_fmamk_f32 v60, v9, 0xba000000, v60
	v_fmamk_f32 v59, v9, 0xba000000, v59
	v_fmac_f32_e32 v58, 0xba000000, v9
	v_mul_f32_e32 v108, v58, v58
	v_mul_f32_e32 v110, v59, v59
	v_mul_f32_e32 v106, v60, v60
	v_mul_f32_e32 v104, v61, v61
	v_pk_add_f32 v[108:109], v[108:109], v[110:111]
	v_pk_add_f32 v[104:105], v[106:107], v[104:105]
	v_fmamk_f32 v57, v9, 0xba000000, v57
	v_pk_add_f32 v[112:113], v[108:109], v[104:105]
	global_load_dwordx4 v[104:107], v[62:63], off
	global_load_dwordx4 v[108:111], v[64:65], off
	v_fmamk_f32 v56, v9, 0xba000000, v56
	v_fmamk_f32 v55, v9, 0xba000000, v55
	v_fmac_f32_e32 v54, 0xba000000, v9
	v_pk_add_f32 v[112:113], v[112:113], v[112:113] op_sel_hi:[0,1]
	v_pk_mul_f32 v[114:115], v[56:57], v[56:57]
	v_pk_mul_f32 v[116:117], v[54:55], v[54:55]
	v_fmac_f32_e32 v50, 0xba000000, v9
	v_pk_mov_b32 v[118:119], v[116:117], v[114:115] op_sel:[1,0]
	v_mov_b32_e32 v117, v115
	v_fmamk_f32 v52, v9, 0xba000000, v52
	v_fmamk_f32 v51, v9, 0xba000000, v51
	v_mul_f32_e32 v112, v50, v50
	v_pk_add_f32 v[114:115], v[118:119], v[116:117]
	v_fmamk_f32 v53, v9, 0xba000000, v53
	v_pk_fma_f32 v[116:117], v[50:51], v[50:51], v[112:113] op_sel_hi:[1,1,0]
	v_mul_f32_e32 v112, v52, v52
	v_pk_add_f32 v[114:115], v[114:115], v[114:115] op_sel_hi:[0,1]
	v_pk_fma_f32 v[118:119], v[52:53], v[52:53], v[112:113] op_sel_hi:[1,1,0]
	v_fmamk_f32 v49, v9, 0xba000000, v49
	v_fmamk_f32 v48, v9, 0xba000000, v48
	v_fmamk_f32 v47, v9, 0xba000000, v47
	v_fmac_f32_e32 v46, 0xba000000, v9
	v_mul_f32_e32 v116, v46, v46
	v_mul_f32_e32 v118, v47, v47
	v_mul_f32_e32 v114, v48, v48
	v_mul_f32_e32 v112, v49, v49
	v_pk_add_f32 v[116:117], v[116:117], v[118:119]
	v_pk_add_f32 v[112:113], v[114:115], v[112:113]
	s_nop 0
	v_pk_add_f32 v[112:113], v[116:117], v[112:113]
	s_nop 0
	v_add_f32_e32 v9, v112, v113
	ds_bpermute_b32 v11, v98, v9
	s_waitcnt lgkmcnt(0)
	v_add_f32_e32 v9, v9, v11
	ds_bpermute_b32 v11, v99, v9
	s_waitcnt lgkmcnt(0)
	v_add_f32_e32 v9, v9, v11
	ds_bpermute_b32 v11, v100, v9
	s_waitcnt lgkmcnt(0)
	v_add_f32_e32 v9, v9, v11
	ds_bpermute_b32 v11, v101, v9
	s_waitcnt lgkmcnt(0)
	v_add_f32_e32 v9, v9, v11
	ds_bpermute_b32 v11, v102, v9
	s_waitcnt lgkmcnt(0)
	v_add_f32_e32 v9, v9, v11
	ds_bpermute_b32 v11, v103, v9
	s_waitcnt lgkmcnt(0)
; __device__ __forceinline__ unsigned cvt_pk_bf16(float lo, float hi) { unsigned r; asm volatile("v_cvt_pk_bf16_f32 %0, %1, %2" : "=v"(r) : "v"(lo), "v"(hi)); return r; }
; __device__ __forceinline__ void ln_apply(f32x4 (&v)[8], const float* __restrict__ g, const float* __restrict__ b, bf16_t* hb, float* fo, int lane) {
;     ...
;     const float rstd = rsqrtf(wave_sum(q) * (1.f / DM) + LN_EPS);
; #pragma unroll
;     for (int j = 0; j < 8; ++j) { const int c = (lane + 64 * j) * 4; const f32x4 gg = *(const f32x4*)(g + c), bb = *(const f32x4*)(b + c);
;         const f32x4 y = v[j] * rstd * gg + bb;
;         if (hb) { u32x2 w; w.x = cvt_pk_bf16(y[0], y[1]); w.y = cvt_pk_bf16(y[2], y[3]); *(u32x2*)(hb + c) = w; }
;         if (fo) *(f32x4*)(fo + c) = y; }
	v_add_f32_e32 v9, v9, v11
	v_fmamk_f32 v9, v9, 0x3a000000, v1
	v_mul_f32_e32 v11, 0x4b800000, v9
	v_cmp_gt_f32_e32 vcc, s16, v9
	s_nop 1
	v_cndmask_b32_e32 v9, v9, v11, vcc
	v_rsq_f32_e32 v9, v9
	s_nop 0
	v_mul_f32_e32 v11, 0x45800000, v9
	v_cndmask_b32_e32 v112, v9, v11, vcc
	v_pk_mul_f32 v[114:115], v[42:43], v[112:113] op_sel_hi:[1,0]
	v_pk_mul_f32 v[116:117], v[44:45], v[112:113] op_sel_hi:[1,0]
	s_waitcnt vmcnt(0)
	v_pk_fma_f32 v[104:105], v[104:105], v[114:115], v[108:109]
	v_pk_fma_f32 v[106:107], v[106:107], v[116:117], v[110:111]
	v_cvt_pk_bf16_f32 v114, v104, v105
	v_pk_mul_f32 v[118:119], v[38:39], v[112:113] op_sel_hi:[1,0]
	v_cvt_pk_bf16_f32 v115, v106, v107
	global_load_dwordx4 v[104:107], v[62:63], off offset:1024
	global_load_dwordx4 v[108:111], v[64:65], off offset:1024
	v_pk_mul_f32 v[120:121], v[40:41], v[112:113] op_sel_hi:[1,0]
	v_lshl_add_u64 v[116:117], v[84:85], 0, s[8:9]
	global_store_dwordx2 v[116:117], v[114:115], off
	s_waitcnt vmcnt(0) lgkmcnt(0)
	v_pk_fma_f32 v[106:107], v[106:107], v[120:121], v[110:111]
	v_pk_fma_f32 v[104:105], v[104:105], v[118:119], v[108:109]
	v_pk_mul_f32 v[118:119], v[34:35], v[112:113] op_sel_hi:[1,0]
	v_cvt_pk_bf16_f32 v114, v104, v105
	v_cvt_pk_bf16_f32 v115, v106, v107
	global_load_dwordx4 v[104:107], v[62:63], off offset:2048
	global_load_dwordx4 v[108:111], v[64:65], off offset:2048
	v_pk_mul_f32 v[120:121], v[36:37], v[112:113] op_sel_hi:[1,0]
	global_store_dwordx2 v[116:117], v[114:115], off offset:512
	s_waitcnt vmcnt(0) lgkmcnt(0)
	v_pk_fma_f32 v[106:107], v[106:107], v[120:121], v[110:111]
	v_pk_fma_f32 v[104:105], v[104:105], v[118:119], v[108:109]
	v_pk_mul_f32 v[118:119], v[30:31], v[112:113] op_sel_hi:[1,0]
	v_cvt_pk_bf16_f32 v114, v104, v105
	v_cvt_pk_bf16_f32 v115, v106, v107
	global_load_dwordx4 v[104:107], v[62:63], off offset:3072
	global_load_dwordx4 v[108:111], v[64:65], off offset:3072
	v_pk_mul_f32 v[120:121], v[32:33], v[112:113] op_sel_hi:[1,0]
	global_store_dwordx2 v[116:117], v[114:115], off offset:1024
	s_waitcnt vmcnt(0) lgkmcnt(0)
	v_pk_fma_f32 v[106:107], v[106:107], v[120:121], v[110:111]
	v_pk_fma_f32 v[104:105], v[104:105], v[118:119], v[108:109]
	v_pk_mul_f32 v[118:119], v[58:59], v[112:113] op_sel_hi:[1,0]
	v_cvt_pk_bf16_f32 v114, v104, v105
	v_cvt_pk_bf16_f32 v115, v106, v107
	global_load_dwordx4 v[104:107], v[66:67], off
	global_load_dwordx4 v[108:111], v[68:69], off
	v_pk_mul_f32 v[120:121], v[60:61], v[112:113] op_sel_hi:[1,0]
	global_store_dwordx2 v[116:117], v[114:115], off offset:1536
	s_waitcnt vmcnt(0) lgkmcnt(0)
	v_pk_fma_f32 v[106:107], v[106:107], v[120:121], v[110:111]
	v_pk_fma_f32 v[104:105], v[104:105], v[118:119], v[108:109]
	v_pk_mul_f32 v[118:119], v[54:55], v[112:113] op_sel_hi:[1,0]
	v_cvt_pk_bf16_f32 v114, v104, v105
	v_cvt_pk_bf16_f32 v115, v106, v107
	global_load_dwordx4 v[104:107], v[70:71], off
	global_load_dwordx4 v[108:111], v[72:73], off
	v_pk_mul_f32 v[120:121], v[56:57], v[112:113] op_sel_hi:[1,0]
	global_store_dwordx2 v[116:117], v[114:115], off offset:2048
	s_waitcnt vmcnt(0) lgkmcnt(0)
	v_pk_fma_f32 v[106:107], v[106:107], v[120:121], v[110:111]
	v_pk_fma_f32 v[104:105], v[104:105], v[118:119], v[108:109]
	v_pk_mul_f32 v[118:119], v[50:51], v[112:113] op_sel_hi:[1,0]
	v_cvt_pk_bf16_f32 v114, v104, v105
	v_cvt_pk_bf16_f32 v115, v106, v107
	global_load_dwordx4 v[104:107], v[74:75], off
	global_load_dwordx4 v[108:111], v[76:77], off
	v_pk_mul_f32 v[120:121], v[52:53], v[112:113] op_sel_hi:[1,0]
	global_store_dwordx2 v[116:117], v[114:115], off offset:2560
	s_waitcnt vmcnt(0) lgkmcnt(0)
	v_pk_fma_f32 v[106:107], v[120:121], v[106:107], v[110:111]
	v_pk_fma_f32 v[104:105], v[118:119], v[104:105], v[108:109]
	v_pk_mul_f32 v[118:119], v[46:47], v[112:113] op_sel_hi:[1,0]
	v_cvt_pk_bf16_f32 v114, v104, v105
	v_cvt_pk_bf16_f32 v115, v106, v107
	global_load_dwordx4 v[104:107], v[80:81], off
	global_load_dwordx4 v[108:111], v[82:83], off
	v_pk_mul_f32 v[112:113], v[48:49], v[112:113] op_sel_hi:[1,0]
	global_store_dwordx2 v[116:117], v[114:115], off offset:3072
	s_waitcnt vmcnt(0) lgkmcnt(0)
	v_pk_fma_f32 v[104:105], v[118:119], v[104:105], v[108:109]
	v_pk_fma_f32 v[106:107], v[112:113], v[106:107], v[110:111]
	v_cvt_pk_bf16_f32 v104, v104, v105
	s_nop 0
	v_cvt_pk_bf16_f32 v105, v106, v107
	global_store_dwordx2 v[116:117], v[104:105], off offset:3584

; __device__ __forceinline__ void ln_load(f32x4 (&v)[8], const float* z, int lane) {
; #pragma unroll
;     for (int j = 0; j < 8; ++j) v[j] = ((const f32x4*)z)[lane + 64 * j];
; }
; __device__ __forceinline__ void ln_apply(f32x4 (&v)[8], const float* __restrict__ g, const float* __restrict__ b, bf16_t* hb, float* fo, int lane) {
;     float s = 0.f;
; #pragma unroll
;     for (int j = 0; j < 8; ++j) s += (v[j][0] + v[j][1]) + (v[j][2] + v[j][3]);
;     const float mean = wave_sum(s) * (1.f / DM); float q = 0.f;
; #pragma unroll
;     for (int j = 0; j < 8; ++j) { v[j] = v[j] - mean; q += (v[j][0] * v[j][0] + v[j][1] * v[j][1]) + (v[j][2] * v[j][2] + v[j][3] * v[j][3]); }
;     const float rstd = rsqrtf(wave_sum(q) * (1.f / DM) + LN_EPS);
; #pragma unroll
;     for (int j = 0; j < 8; ++j) { const int c = (lane + 64 * j) * 4; const f32x4 gg = *(const f32x4*)(g + c), bb = *(const f32x4*)(b + c);
.LBB0_1199:
	s_add_i32 s8, s6, s3
	s_cmpk_gt_i32 s8, 0x400f
	s_cbranch_scc1 .LBB0_1201
	s_ashr_i32 s9, s8, 31
	s_lshl_b64 s[10:11], s[8:9], 13
	v_lshl_add_u64 v[46:47], v[78:79], 0, s[10:11]
	v_add_co_u32_e32 v104, vcc, 0x1000, v46
	global_load_dwordx4 v[42:45], v[46:47], off
	global_load_dwordx4 v[38:41], v[46:47], off offset:1024
	global_load_dwordx4 v[34:37], v[46:47], off offset:2048
	global_load_dwordx4 v[30:33], v[46:47], off offset:3072
	v_addc_co_u32_e32 v105, vcc, 0, v47, vcc
	global_load_dwordx4 v[58:61], v[104:105], off
	global_load_dwordx4 v[54:57], v[104:105], off offset:1024
	global_load_dwordx4 v[50:53], v[104:105], off offset:2048
	global_load_dwordx4 v[46:49], v[104:105], off offset:3072
.LBB0_1201:
	v_pk_add_f32 v[104:105], v[86:87], v[2:3]
	v_pk_add_f32 v[106:107], v[88:89], v[4:5]
	v_add_f32_e32 v11, v26, v27
	v_pk_add_f32 v[104:105], v[104:105], v[106:107]
	v_add_f32_e32 v19, v22, v23
	v_add_f32_e32 v9, 0, v105
	v_add_f32_e32 v93, v104, v9
	v_pk_add_f32 v[104:105], v[90:91], v[6:7]
	v_add_f32_e32 v9, v28, v29
	v_pk_add_f32 v[104:105], v[104:105], v[104:105] op_sel_hi:[0,1]
	v_mov_b32_e32 v13, v105
	v_pk_add_f32 v[106:107], v[10:11], v[8:9]
	v_pk_add_f32 v[104:105], v[12:13], v[92:93]
	v_add_f32_e32 v17, v24, v25
	v_pk_add_f32 v[104:105], v[106:107], v[104:105]
	v_pk_add_f32 v[106:107], v[94:95], v[14:15]
	v_pk_add_f32 v[104:105], v[104:105], v[104:105] op_sel_hi:[0,1]
	v_pk_add_f32 v[106:107], v[106:107], v[106:107] op_sel_hi:[0,1]
	v_mov_b32_e32 v21, v107
	v_mov_b32_e32 v97, v105
	v_pk_add_f32 v[108:109], v[18:19], v[16:17]
	v_pk_add_f32 v[104:105], v[20:21], v[96:97]
	s_ashr_i32 s7, s6, 31
	v_pk_add_f32 v[104:105], v[108:109], v[104:105]
	s_lshl_b64 s[10:11], s[6:7], 12
	v_add_f32_e32 v9, v104, v105
	ds_bpermute_b32 v11, v98, v9
	s_cmpk_gt_i32 s8, 0x400f
	s_waitcnt lgkmcnt(0)
	v_add_f32_e32 v9, v9, v11
	ds_bpermute_b32 v11, v99, v9
	s_waitcnt lgkmcnt(0)
	v_add_f32_e32 v9, v9, v11
	ds_bpermute_b32 v11, v100, v9
	s_waitcnt lgkmcnt(0)
	v_add_f32_e32 v9, v9, v11
	ds_bpermute_b32 v11, v101, v9
	s_waitcnt lgkmcnt(0)
	v_add_f32_e32 v9, v9, v11
	ds_bpermute_b32 v11, v102, v9
	s_waitcnt lgkmcnt(0)
	v_add_f32_e32 v9, v9, v11
	ds_bpermute_b32 v11, v103, v9
	s_waitcnt lgkmcnt(0)
	v_add_f32_e32 v9, v9, v11
	v_fmac_f32_e32 v3, 0xba000000, v9
	v_fmac_f32_e32 v2, 0xba000000, v9
	v_fmac_f32_e32 v87, 0xba000000, v9
	v_fmac_f32_e32 v86, 0xba000000, v9
	v_mov_b32_e32 v106, v3
	v_mov_b32_e32 v107, v2
	v_fmac_f32_e32 v5, 0xba000000, v9
	v_fmac_f32_e32 v4, 0xba000000, v9
	v_mov_b32_e32 v104, v87
	v_mov_b32_e32 v105, v86
	v_pk_mul_f32 v[106:107], v[106:107], v[106:107]
	v_fmac_f32_e32 v89, 0xba000000, v9
	v_fmac_f32_e32 v88, 0xba000000, v9
	v_pk_fma_f32 v[104:105], v[104:105], v[104:105], v[106:107]
	v_mov_b32_e32 v106, v5
	v_mov_b32_e32 v107, v4
	v_mov_b32_e32 v108, v89
	v_mov_b32_e32 v109, v88
	v_pk_mul_f32 v[106:107], v[106:107], v[106:107]
	v_fmac_f32_e32 v7, 0xba000000, v9
	v_pk_fma_f32 v[106:107], v[108:109], v[108:109], v[106:107]
	v_fmac_f32_e32 v91, 0xba000000, v9
	v_fmac_f32_e32 v90, 0xba000000, v9
	v_fmac_f32_e32 v6, 0xba000000, v9
	v_pk_add_f32 v[104:105], v[104:105], v[106:107]
	v_mov_b32_e32 v112, v91
	v_mov_b32_e32 v113, v7
	v_mov_b32_e32 v114, v6
	v_mov_b32_e32 v115, v90
	v_pk_add_f32 v[104:105], v[104:105], v[104:105] op_sel_hi:[0,1]
	v_pk_mul_f32 v[106:107], v[112:113], v[112:113]
	v_pk_mul_f32 v[108:109], v[114:115], v[114:115]
	v_fmac_f32_e32 v26, 0xba000000, v9
	v_pk_mov_b32 v[110:111], v[108:109], v[106:107] op_sel:[1,0]
	v_mov_b32_e32 v109, v107
	v_fmac_f32_e32 v28, 0xba000000, v9
	v_fmac_f32_e32 v27, 0xba000000, v9
	v_mul_f32_e32 v104, v26, v26
	v_pk_add_f32 v[106:107], v[110:111], v[108:109]
	v_fmac_f32_e32 v29, 0xba000000, v9
	v_pk_fma_f32 v[108:109], v[26:27], v[26:27], v[104:105] op_sel_hi:[1,1,0]
	v_mul_f32_e32 v104, v28, v28
	v_pk_add_f32 v[106:107], v[106:107], v[106:107] op_sel_hi:[0,1]
	v_pk_fma_f32 v[110:111], v[28:29], v[28:29], v[104:105] op_sel_hi:[1,1,0]
	v_fmac_f32_e32 v92, 0xba000000, v9
	v_fmac_f32_e32 v12, 0xba000000, v9
	v_fmac_f32_e32 v8, 0xba000000, v9
	v_fmac_f32_e32 v10, 0xba000000, v9
	v_mul_f32_e32 v108, v10, v10
	v_mul_f32_e32 v110, v8, v8
	v_mul_f32_e32 v106, v12, v12
	v_mul_f32_e32 v104, v92, v92
	v_pk_add_f32 v[108:109], v[108:109], v[110:111]
	v_pk_add_f32 v[104:105], v[106:107], v[104:105]
	v_fmac_f32_e32 v15, 0xba000000, v9
	v_pk_add_f32 v[104:105], v[108:109], v[104:105]
	v_fmac_f32_e32 v95, 0xba000000, v9
	v_pk_add_f32 v[116:117], v[104:105], v[104:105] op_sel_hi:[0,1]
	global_load_dwordx4 v[104:107], v[62:63], off
	global_load_dwordx4 v[108:111], v[64:65], off
	v_fmac_f32_e32 v94, 0xba000000, v9
	v_fmac_f32_e32 v14, 0xba000000, v9
	v_mov_b32_e32 v118, v95
	v_mov_b32_e32 v119, v15
	v_mov_b32_e32 v122, v14
	v_mov_b32_e32 v123, v94
	v_pk_mul_f32 v[120:121], v[118:119], v[118:119]
	v_pk_mul_f32 v[124:125], v[122:123], v[122:123]
	v_fmac_f32_e32 v22, 0xba000000, v9
	v_pk_mov_b32 v[126:127], v[124:125], v[120:121] op_sel:[1,0]
	v_mov_b32_e32 v125, v121
	v_fmac_f32_e32 v24, 0xba000000, v9
	v_fmac_f32_e32 v23, 0xba000000, v9
	v_mul_f32_e32 v116, v22, v22
	v_pk_add_f32 v[120:121], v[126:127], v[124:125]
	v_fmac_f32_e32 v25, 0xba000000, v9
	v_pk_fma_f32 v[124:125], v[22:23], v[22:23], v[116:117] op_sel_hi:[1,1,0]
	v_mul_f32_e32 v116, v24, v24
	v_pk_add_f32 v[120:121], v[120:121], v[120:121] op_sel_hi:[0,1]
	v_pk_fma_f32 v[126:127], v[24:25], v[24:25], v[116:117] op_sel_hi:[1,1,0]
	v_fmac_f32_e32 v96, 0xba000000, v9
	v_fmac_f32_e32 v20, 0xba000000, v9
	v_fmac_f32_e32 v16, 0xba000000, v9
	v_fmac_f32_e32 v18, 0xba000000, v9
	v_mul_f32_e32 v124, v18, v18
	v_mul_f32_e32 v126, v16, v16
	v_mul_f32_e32 v120, v20, v20
	v_mul_f32_e32 v116, v96, v96
	v_pk_add_f32 v[124:125], v[124:125], v[126:127]
	v_pk_add_f32 v[116:117], v[120:121], v[116:117]
	v_mov_b32_e32 v120, v89
	v_pk_add_f32 v[116:117], v[124:125], v[116:117]
	v_mov_b32_e32 v121, v5
	v_add_f32_e32 v9, v116, v117
	ds_bpermute_b32 v11, v98, v9
	v_mov_b32_e32 v116, v87
	v_mov_b32_e32 v117, v3
	v_mov_b32_e32 v126, v86
	v_mov_b32_e32 v127, v2
	s_waitcnt lgkmcnt(0)
; __device__ __forceinline__ unsigned cvt_pk_bf16(float lo, float hi) { unsigned r; asm volatile("v_cvt_pk_bf16_f32 %0, %1, %2" : "=v"(r) : "v"(lo), "v"(hi)); return r; }
; __device__ __forceinline__ void ln_apply(f32x4 (&v)[8], const float* __restrict__ g, const float* __restrict__ b, bf16_t* hb, float* fo, int lane) {
;     ...
;     const float rstd = rsqrtf(wave_sum(q) * (1.f / DM) + LN_EPS);
; #pragma unroll
;     for (int j = 0; j < 8; ++j) { const int c = (lane + 64 * j) * 4; const f32x4 gg = *(const f32x4*)(g + c), bb = *(const f32x4*)(b + c);
;         const f32x4 y = v[j] * rstd * gg + bb;
;         if (hb) { u32x2 w; w.x = cvt_pk_bf16(y[0], y[1]); w.y = cvt_pk_bf16(y[2], y[3]); *(u32x2*)(hb + c) = w; }
;         if (fo) *(f32x4*)(fo + c) = y; }
; }
	v_add_f32_e32 v9, v9, v11
	ds_bpermute_b32 v11, v99, v9
	v_mov_b32_e32 v128, v88
	v_mov_b32_e32 v129, v4
	v_mov_b32_e32 v13, v92
	v_mov_b32_e32 v19, v16
	s_waitcnt lgkmcnt(0)
	v_add_f32_e32 v9, v9, v11
	ds_bpermute_b32 v11, v100, v9
	v_mov_b32_e32 v21, v96
	s_waitcnt lgkmcnt(0)
	v_add_f32_e32 v9, v9, v11
	ds_bpermute_b32 v11, v101, v9
	s_waitcnt lgkmcnt(0)
	v_add_f32_e32 v9, v9, v11
	ds_bpermute_b32 v11, v102, v9
	s_waitcnt lgkmcnt(0)
	v_add_f32_e32 v9, v9, v11
	ds_bpermute_b32 v11, v103, v9
	s_waitcnt lgkmcnt(0)
	v_add_f32_e32 v9, v9, v11
	v_fmamk_f32 v9, v9, 0x3a000000, v1
	v_mul_f32_e32 v11, 0x4b800000, v9
	v_cmp_gt_f32_e32 vcc, s16, v9
	s_nop 1
	v_cndmask_b32_e32 v9, v9, v11, vcc
	v_rsq_f32_e32 v9, v9
	s_nop 0
	v_mul_f32_e32 v11, 0x45800000, v9
	v_cndmask_b32_e32 v124, v9, v11, vcc
	v_pk_mul_f32 v[116:117], v[116:117], v[124:125] op_sel_hi:[1,0]
	v_pk_mul_f32 v[120:121], v[120:121], v[124:125] op_sel_hi:[1,0]
	s_waitcnt vmcnt(0)
	v_pk_fma_f32 v[104:105], v[104:105], v[116:117], v[108:109]
	v_pk_fma_f32 v[106:107], v[106:107], v[120:121], v[110:111]
	v_cvt_pk_bf16_f32 v116, v104, v105
	v_pk_mul_f32 v[126:127], v[126:127], v[124:125] op_sel_hi:[1,0]
	v_cvt_pk_bf16_f32 v117, v106, v107
	global_load_dwordx4 v[104:107], v[62:63], off offset:1024
	global_load_dwordx4 v[108:111], v[64:65], off offset:1024
	v_pk_mul_f32 v[128:129], v[128:129], v[124:125] op_sel_hi:[1,0]
	v_lshl_add_u64 v[120:121], v[84:85], 0, s[10:11]
	global_store_dwordx2 v[120:121], v[116:117], off
	v_pk_mul_f32 v[114:115], v[114:115], v[124:125] op_sel_hi:[1,0]
	v_pk_mul_f32 v[112:113], v[112:113], v[124:125] op_sel_hi:[1,0]
	v_mov_b32_e32 v11, v8
	s_mov_b64 s[10:11], -1
	s_waitcnt vmcnt(0) lgkmcnt(0)
	v_pk_fma_f32 v[106:107], v[106:107], v[128:129], v[110:111]
	v_pk_fma_f32 v[104:105], v[104:105], v[126:127], v[108:109]
	s_nop 0
	v_cvt_pk_bf16_f32 v116, v104, v105
	v_cvt_pk_bf16_f32 v117, v106, v107
	global_load_dwordx4 v[104:107], v[62:63], off offset:2048
	global_load_dwordx4 v[108:111], v[64:65], off offset:2048
	s_waitcnt vmcnt(0) lgkmcnt(0)
	v_pk_fma_f32 v[106:107], v[106:107], v[112:113], v[110:111]
	v_pk_fma_f32 v[104:105], v[104:105], v[114:115], v[108:109]
	global_store_dwordx2 v[120:121], v[116:117], off offset:512
	v_cvt_pk_bf16_f32 v112, v104, v105
	v_cvt_pk_bf16_f32 v113, v106, v107
	global_load_dwordx4 v[104:107], v[62:63], off offset:3072
	global_load_dwordx4 v[108:111], v[64:65], off offset:3072
	v_pk_mul_f32 v[114:115], v[26:27], v[124:125] op_sel_hi:[1,0]
	v_pk_mul_f32 v[116:117], v[28:29], v[124:125] op_sel_hi:[1,0]
	global_store_dwordx2 v[120:121], v[112:113], off offset:1024
	s_waitcnt vmcnt(0) lgkmcnt(0)
	v_pk_fma_f32 v[106:107], v[106:107], v[116:117], v[110:111]
	v_pk_fma_f32 v[104:105], v[104:105], v[114:115], v[108:109]
	v_pk_mul_f32 v[114:115], v[10:11], v[124:125] op_sel_hi:[1,0]
	v_cvt_pk_bf16_f32 v112, v104, v105
	v_cvt_pk_bf16_f32 v113, v106, v107
	global_load_dwordx4 v[104:107], v[66:67], off
	global_load_dwordx4 v[108:111], v[68:69], off
	v_pk_mul_f32 v[116:117], v[12:13], v[124:125] op_sel_hi:[1,0]
	global_store_dwordx2 v[120:121], v[112:113], off offset:1536
	s_waitcnt vmcnt(0) lgkmcnt(0)
	v_pk_fma_f32 v[106:107], v[106:107], v[116:117], v[110:111]
	v_pk_fma_f32 v[104:105], v[104:105], v[114:115], v[108:109]
	v_pk_mul_f32 v[114:115], v[122:123], v[124:125] op_sel_hi:[1,0]
	v_cvt_pk_bf16_f32 v112, v104, v105
	v_cvt_pk_bf16_f32 v113, v106, v107
	global_load_dwordx4 v[104:107], v[70:71], off
	global_load_dwordx4 v[108:111], v[72:73], off
	v_pk_mul_f32 v[116:117], v[118:119], v[124:125] op_sel_hi:[1,0]
	global_store_dwordx2 v[120:121], v[112:113], off offset:2048
	s_waitcnt vmcnt(0) lgkmcnt(0)
	v_pk_fma_f32 v[106:107], v[106:107], v[116:117], v[110:111]
	v_pk_fma_f32 v[104:105], v[104:105], v[114:115], v[108:109]
	v_pk_mul_f32 v[114:115], v[22:23], v[124:125] op_sel_hi:[1,0]
	v_cvt_pk_bf16_f32 v112, v104, v105
	v_cvt_pk_bf16_f32 v113, v106, v107
	global_load_dwordx4 v[104:107], v[74:75], off
	global_load_dwordx4 v[108:111], v[76:77], off
	v_pk_mul_f32 v[116:117], v[24:25], v[124:125] op_sel_hi:[1,0]
	global_store_dwordx2 v[120:121], v[112:113], off offset:2560
	s_waitcnt vmcnt(0) lgkmcnt(0)
	v_pk_fma_f32 v[106:107], v[116:117], v[106:107], v[110:111]
	v_pk_fma_f32 v[104:105], v[114:115], v[104:105], v[108:109]
	v_pk_mul_f32 v[114:115], v[18:19], v[124:125] op_sel_hi:[1,0]
	v_cvt_pk_bf16_f32 v112, v104, v105
	v_cvt_pk_bf16_f32 v113, v106, v107
	global_load_dwordx4 v[104:107], v[80:81], off
	global_load_dwordx4 v[108:111], v[82:83], off
	v_pk_mul_f32 v[116:117], v[20:21], v[124:125] op_sel_hi:[1,0]
	global_store_dwordx2 v[120:121], v[112:113], off offset:3072
	s_waitcnt vmcnt(0) lgkmcnt(0)
	v_pk_fma_f32 v[104:105], v[114:115], v[104:105], v[108:109]
	v_pk_fma_f32 v[106:107], v[116:117], v[106:107], v[110:111]
	v_cvt_pk_bf16_f32 v104, v104, v105
	s_nop 0
	v_cvt_pk_bf16_f32 v105, v106, v107
	global_store_dwordx2 v[120:121], v[104:105], off offset:3584
	s_cbranch_scc1 .LBB0_1198
	s_add_i32 s12, s8, s3
	s_cmpk_gt_i32 s12, 0x400f
	s_cselect_b64 s[10:11], -1, 0
	s_and_b64 vcc, exec, s[10:11]
	s_cbranch_vccnz .LBB0_1197
	s_ashr_i32 s13, s12, 31
	s_lshl_b64 s[6:7], s[12:13], 13
	v_lshl_add_u64 v[86:87], v[78:79], 0, s[6:7]
	global_load_dwordx4 v[2:5], v[86:87], off
	global_load_dwordx4 v[90:93], v[86:87], off offset:1024
	global_load_dwordx4 v[6:9], v[86:87], off offset:2048
	v_add_co_u32_e32 v88, vcc, 0x1000, v86
	s_mov_b32 s6, s12
	s_nop 0
	v_addc_co_u32_e32 v89, vcc, 0, v87, vcc
	global_load_dwordx4 v[10:13], v[88:89], off
	global_load_dwordx4 v[14:17], v[88:89], off offset:1024
	global_load_dwordx4 v[18:21], v[88:89], off offset:3072
	global_load_dwordx4 v[22:25], v[88:89], off offset:2048
	global_load_dwordx4 v[26:29], v[86:87], off offset:3072
	s_waitcnt vmcnt(0) lgkmcnt(0)
	v_mov_b32_e32 v87, v2
	v_mov_b32_e32 v89, v4
	v_mov_b32_e32 v86, v90
	v_mov_b32_e32 v2, v91
	v_mov_b32_e32 v88, v92
	v_mov_b32_e32 v4, v93
	v_mov_b32_e32 v90, v7
	v_mov_b32_e32 v91, v8
	v_mov_b32_e32 v7, v9
	v_mov_b32_e32 v8, v11
	v_mov_b32_e32 v92, v13
	v_mov_b32_e32 v94, v15
	v_mov_b32_e32 v95, v16
	v_mov_b32_e32 v15, v17
	v_mov_b32_e32 v16, v19
	v_mov_b32_e32 v96, v21
	s_branch .LBB0_1197

; template <int KSPLIT, class Epi>
; __device__ __forceinline__ void skinny_gemm(const bf16_t* __restrict__ A, int lda, const bf16_t* __restrict__ Wt, int K, int ntiles, char* lds, const Epi& E) {
;     ...
;             const bf16_t* ap = A + (size_t)i * lda + ks * klen + 8 * kq;
;             const bf16_t* wp = Wt + (size_t)(tile * 16 + i) * K + ks * klen + 8 * kq;
;             for (int k = 0; k < klen; k += 256) {
;                 bf16x8 a[8], w[8];
; #pragma unroll
;                 for (int j = 0; j < 8; ++j) { a[j] = *(const bf16x8*)(ap + k + 32 * j); w[j] = *(const bf16x8*)(wp + k + 32 * j); }
; #pragma unroll
;                 for (int j = 0; j < 8; ++j) acc = __builtin_amdgcn_mfma_f32_16x16x32_bf16(w[j], a[j], acc, 0, 0, 0);
;             }
.LBB0_1265:
	s_add_i32 s19, s15, s16
	s_ashr_i32 s6, s19, 31
	s_lshr_b32 s6, s6, 30
	s_add_i32 s6, s19, s6
	s_ashr_i32 s17, s6, 2
	s_and_b32 s6, s6, -4
	s_sub_i32 s18, s19, s6
	v_mov_b32_e32 v4, v2
	v_mov_b32_e32 v5, v2
	v_mov_b32_e32 v3, v2
	s_cmpk_lt_i32 s19, 0x800
	v_mov_b64_e32 v[6:7], v[4:5]
	s_cselect_b64 s[6:7], -1, 0
	s_cmpk_gt_i32 s19, 0x7ff
	v_mov_b64_e32 v[4:5], v[2:3]
	s_cbranch_scc1 .LBB0_1267
	v_lshl_or_b32 v4, s17, 4, v1
	s_lshl_b32 s20, s18, 9
	v_ashrrev_i32_e32 v5, 31, v4
	s_ashr_i32 s21, s20, 31
	v_lshlrev_b64 v[4:5], 12, v[4:5]
	s_lshl_b64 s[20:21], s[20:21], 1
	v_lshl_add_u64 v[4:5], s[8:9], 0, v[4:5]
	v_lshl_add_u64 v[4:5], v[4:5], 0, s[20:21]
	v_mov_b32_e32 v13, v2
	v_lshl_add_u64 v[60:61], v[4:5], 0, v[12:13]
	global_load_dwordx4 v[4:7], v[60:61], off
	v_lshl_add_u64 v[62:63], v[8:9], 0, s[20:21]
	global_load_dwordx4 v[16:19], v[60:61], off offset:64
	global_load_dwordx4 v[20:23], v[62:63], off
	global_load_dwordx4 v[24:27], v[62:63], off offset:64
	global_load_dwordx4 v[28:31], v[60:61], off offset:128
	global_load_dwordx4 v[32:35], v[60:61], off offset:192
	global_load_dwordx4 v[36:39], v[62:63], off offset:128
	global_load_dwordx4 v[40:43], v[62:63], off offset:192
	global_load_dwordx4 v[44:47], v[60:61], off offset:256
	global_load_dwordx4 v[48:51], v[60:61], off offset:320
	global_load_dwordx4 v[52:55], v[62:63], off offset:256
	global_load_dwordx4 v[56:59], v[62:63], off offset:320
	s_waitcnt vmcnt(0) lgkmcnt(0)
	v_mfma_f32_16x16x32_bf16 v[4:7], v[4:7], v[20:23], 0
	global_load_dwordx4 v[20:23], v[60:61], off offset:384
	v_mfma_f32_16x16x32_bf16 v[4:7], v[16:19], v[24:27], v[4:7]
	global_load_dwordx4 v[16:19], v[62:63], off offset:384
	v_mfma_f32_16x16x32_bf16 v[4:7], v[28:31], v[36:39], v[4:7]
	global_load_dwordx4 v[24:27], v[60:61], off offset:448
	global_load_dwordx4 v[28:31], v[62:63], off offset:448
	v_mfma_f32_16x16x32_bf16 v[4:7], v[32:35], v[40:43], v[4:7]
	global_load_dwordx4 v[32:35], v[60:61], off offset:512
	global_load_dwordx4 v[36:39], v[60:61], off offset:576
	v_mfma_f32_16x16x32_bf16 v[4:7], v[44:47], v[52:55], v[4:7]
	global_load_dwordx4 v[40:43], v[62:63], off offset:512
	global_load_dwordx4 v[44:47], v[62:63], off offset:576
	v_mfma_f32_16x16x32_bf16 v[4:7], v[48:51], v[56:59], v[4:7]
	global_load_dwordx4 v[48:51], v[60:61], off offset:640
	s_waitcnt vmcnt(0) lgkmcnt(0)
	v_mfma_f32_16x16x32_bf16 v[4:7], v[20:23], v[16:19], v[4:7]
	global_load_dwordx4 v[16:19], v[62:63], off offset:640
	v_mfma_f32_16x16x32_bf16 v[4:7], v[24:27], v[28:31], v[4:7]
	global_load_dwordx4 v[20:23], v[60:61], off offset:704
	global_load_dwordx4 v[24:27], v[62:63], off offset:704
	v_mfma_f32_16x16x32_bf16 v[4:7], v[32:35], v[40:43], v[4:7]
	global_load_dwordx4 v[28:31], v[60:61], off offset:768
	global_load_dwordx4 v[32:35], v[62:63], off offset:768
	v_mfma_f32_16x16x32_bf16 v[4:7], v[36:39], v[44:47], v[4:7]
	global_load_dwordx4 v[36:39], v[60:61], off offset:832
	s_waitcnt vmcnt(0) lgkmcnt(0)
	v_mfma_f32_16x16x32_bf16 v[4:7], v[48:51], v[16:19], v[4:7]
	global_load_dwordx4 v[16:19], v[62:63], off offset:832
	v_mfma_f32_16x16x32_bf16 v[4:7], v[20:23], v[24:27], v[4:7]
	global_load_dwordx4 v[20:23], v[60:61], off offset:896
	global_load_dwordx4 v[24:27], v[62:63], off offset:896
	v_mfma_f32_16x16x32_bf16 v[4:7], v[28:31], v[32:35], v[4:7]
	global_load_dwordx4 v[28:31], v[60:61], off offset:960
	s_waitcnt vmcnt(0) lgkmcnt(0)
	v_mfma_f32_16x16x32_bf16 v[4:7], v[36:39], v[16:19], v[4:7]
	global_load_dwordx4 v[16:19], v[62:63], off offset:960
	v_mfma_f32_16x16x32_bf16 v[4:7], v[20:23], v[24:27], v[4:7]
	s_waitcnt vmcnt(0) lgkmcnt(0)
	v_mfma_f32_16x16x32_bf16 v[4:7], v[28:31], v[16:19], v[4:7]

; template <int KSPLIT, class Epi>
; __device__ __forceinline__ void skinny_gemm(const bf16_t* __restrict__ A, int lda, const bf16_t* __restrict__ Wt, int K, int ntiles, char* lds, const Epi& E) {
;     ...
;             __syncthreads();
;         }
;         if (act && ks == 0) E(tile, i, kq, acc);
.LBB0_1271:
	s_and_b64 vcc, exec, s[6:7]
	s_barrier
	s_cbranch_vccnz .LBB0_1264
	v_max_f32_e32 v3, v4, v4
	v_max_f32_e32 v4, v5, v5
	v_max_f32_e32 v5, v6, v6
	v_max_f32_e32 v6, v7, v7
	v_max_f32_e32 v4, 0, v4
	v_max_f32_e32 v5, 0, v5
	v_max_f32_e32 v6, 0, v6
	s_lshl_b32 s6, s17, 4
	v_max_f32_e32 v3, 0, v3
	v_mul_f32_e32 v4, v4, v4
	v_mul_f32_e32 v5, v5, v5
	v_mul_f32_e32 v6, v6, v6
	s_ashr_i32 s7, s6, 31
	v_mul_f32_e32 v3, v3, v3
	v_cvt_pk_bf16_f32 v4, v3, v4
	v_cvt_pk_bf16_f32 v5, v5, v6
	v_lshl_add_u64 v[6:7], s[6:7], 1, v[10:11]
	global_store_dwordx2 v[6:7], v[4:5], off
	s_branch .LBB0_1264

; template <int KSPLIT, class Epi>
; __device__ __forceinline__ void skinny_gemm(const bf16_t* __restrict__ A, int lda, const bf16_t* __restrict__ Wt, int K, int ntiles, char* lds, const Epi& E) {
;     ...
;             const bf16_t* ap = A + (size_t)i * lda + ks * klen + 8 * kq;
;             const bf16_t* wp = Wt + (size_t)(tile * 16 + i) * K + ks * klen + 8 * kq;
;             for (int k = 0; k < klen; k += 256) {
;                 bf16x8 a[8], w[8];
; #pragma unroll
;                 for (int j = 0; j < 8; ++j) { a[j] = *(const bf16x8*)(ap + k + 32 * j); w[j] = *(const bf16x8*)(wp + k + 32 * j); }
; #pragma unroll
;                 for (int j = 0; j < 8; ++j) acc = __builtin_amdgcn_mfma_f32_16x16x32_bf16(w[j], a[j], acc, 0, 0, 0);
;             }
.LBB0_1358:
	s_add_i32 s22, s18, s19
	s_ashr_i32 s6, s22, 31
	s_lshr_b32 s6, s6, 29
	s_add_i32 s6, s22, s6
	s_ashr_i32 s20, s6, 3
	s_and_b32 s6, s6, -8
	s_sub_i32 s21, s22, s6
	v_mov_b32_e32 v4, v2
	v_mov_b32_e32 v5, v2
	v_mov_b32_e32 v3, v2
	s_cmpk_lt_i32 s22, 0x400
	v_mov_b64_e32 v[6:7], v[4:5]
	s_cselect_b64 s[6:7], -1, 0
	s_cmpk_gt_i32 s22, 0x3ff
	v_mov_b64_e32 v[4:5], v[2:3]
	s_cbranch_scc1 .LBB0_1360
	v_lshl_or_b32 v4, s20, 4, v1
	s_lshl_b32 s22, s21, 10
	v_ashrrev_i32_e32 v5, 31, v4
	s_ashr_i32 s23, s22, 31
	v_lshlrev_b64 v[4:5], 14, v[4:5]
	s_lshl_b64 s[22:23], s[22:23], 1
	v_lshl_add_u64 v[4:5], s[12:13], 0, v[4:5]
	v_lshl_add_u64 v[4:5], v[4:5], 0, s[22:23]
	v_mov_b32_e32 v15, v2
	v_lshl_add_u64 v[84:85], v[4:5], 0, v[14:15]
	global_load_dwordx4 v[4:7], v[84:85], off
	v_lshl_add_u64 v[86:87], v[8:9], 0, s[22:23]
	global_load_dwordx4 v[20:23], v[84:85], off offset:64
	global_load_dwordx4 v[24:27], v[86:87], off
	global_load_dwordx4 v[28:31], v[86:87], off offset:64
	global_load_dwordx4 v[32:35], v[84:85], off offset:128
	global_load_dwordx4 v[36:39], v[84:85], off offset:192
	global_load_dwordx4 v[40:43], v[86:87], off offset:128
	global_load_dwordx4 v[44:47], v[86:87], off offset:192
	global_load_dwordx4 v[48:51], v[84:85], off offset:256
	global_load_dwordx4 v[52:55], v[86:87], off offset:256
	global_load_dwordx4 v[56:59], v[84:85], off offset:320
	global_load_dwordx4 v[60:63], v[86:87], off offset:320
	global_load_dwordx4 v[64:67], v[84:85], off offset:384
	global_load_dwordx4 v[68:71], v[84:85], off offset:448
	global_load_dwordx4 v[72:75], v[86:87], off offset:384
	global_load_dwordx4 v[76:79], v[86:87], off offset:448
	s_waitcnt vmcnt(0) lgkmcnt(0)
	v_mfma_f32_16x16x32_bf16 v[4:7], v[4:7], v[24:27], 0
	global_load_dwordx4 v[24:27], v[84:85], off offset:512
	global_load_dwordx4 v[80:83], v[84:85], off offset:576
	v_mfma_f32_16x16x32_bf16 v[4:7], v[20:23], v[28:31], v[4:7]
	global_load_dwordx4 v[20:23], v[86:87], off offset:512
	global_load_dwordx4 v[28:31], v[86:87], off offset:576
	v_mfma_f32_16x16x32_bf16 v[4:7], v[32:35], v[40:43], v[4:7]
	global_load_dwordx4 v[32:35], v[84:85], off offset:640
	global_load_dwordx4 v[40:43], v[86:87], off offset:640
	v_mfma_f32_16x16x32_bf16 v[4:7], v[36:39], v[44:47], v[4:7]
	global_load_dwordx4 v[36:39], v[84:85], off offset:704
	global_load_dwordx4 v[44:47], v[86:87], off offset:704
	v_mfma_f32_16x16x32_bf16 v[4:7], v[48:51], v[52:55], v[4:7]
	global_load_dwordx4 v[48:51], v[84:85], off offset:768
	global_load_dwordx4 v[52:55], v[84:85], off offset:832
	v_mfma_f32_16x16x32_bf16 v[4:7], v[56:59], v[60:63], v[4:7]
	global_load_dwordx4 v[56:59], v[86:87], off offset:768
	global_load_dwordx4 v[60:63], v[86:87], off offset:832
	v_mfma_f32_16x16x32_bf16 v[4:7], v[64:67], v[72:75], v[4:7]
	v_mfma_f32_16x16x32_bf16 v[4:7], v[68:71], v[76:79], v[4:7]
	global_load_dwordx4 v[64:67], v[84:85], off offset:896
	global_load_dwordx4 v[68:71], v[84:85], off offset:960
	s_waitcnt vmcnt(0) lgkmcnt(0)
	v_mfma_f32_16x16x32_bf16 v[4:7], v[24:27], v[20:23], v[4:7]
	global_load_dwordx4 v[20:23], v[86:87], off offset:896
	global_load_dwordx4 v[24:27], v[86:87], off offset:960
	v_mfma_f32_16x16x32_bf16 v[4:7], v[80:83], v[28:31], v[4:7]
	global_load_dwordx4 v[28:31], v[84:85], off offset:1024
	global_load_dwordx4 v[72:75], v[86:87], off offset:1024
	v_mfma_f32_16x16x32_bf16 v[4:7], v[32:35], v[40:43], v[4:7]
	global_load_dwordx4 v[32:35], v[84:85], off offset:1088
	v_mfma_f32_16x16x32_bf16 v[4:7], v[36:39], v[44:47], v[4:7]
	global_load_dwordx4 v[36:39], v[86:87], off offset:1088
	global_load_dwordx4 v[40:43], v[84:85], off offset:1152
	global_load_dwordx4 v[44:47], v[84:85], off offset:1216
	v_mfma_f32_16x16x32_bf16 v[4:7], v[48:51], v[56:59], v[4:7]
	v_mfma_f32_16x16x32_bf16 v[4:7], v[52:55], v[60:63], v[4:7]
	global_load_dwordx4 v[48:51], v[86:87], off offset:1152
	global_load_dwordx4 v[52:55], v[86:87], off offset:1216
	s_waitcnt vmcnt(0) lgkmcnt(0)
	v_mfma_f32_16x16x32_bf16 v[4:7], v[64:67], v[20:23], v[4:7]
	global_load_dwordx4 v[20:23], v[84:85], off offset:1280
	global_load_dwordx4 v[56:59], v[84:85], off offset:1344
	v_mfma_f32_16x16x32_bf16 v[4:7], v[68:71], v[24:27], v[4:7]
	global_load_dwordx4 v[24:27], v[86:87], off offset:1280
	global_load_dwordx4 v[60:63], v[86:87], off offset:1344
	v_mfma_f32_16x16x32_bf16 v[4:7], v[28:31], v[72:75], v[4:7]
	global_load_dwordx4 v[28:31], v[84:85], off offset:1408
	v_mfma_f32_16x16x32_bf16 v[4:7], v[32:35], v[36:39], v[4:7]
	global_load_dwordx4 v[32:35], v[86:87], off offset:1408
	v_mfma_f32_16x16x32_bf16 v[4:7], v[40:43], v[48:51], v[4:7]
	global_load_dwordx4 v[36:39], v[84:85], off offset:1472
	global_load_dwordx4 v[40:43], v[86:87], off offset:1472
	v_mfma_f32_16x16x32_bf16 v[4:7], v[44:47], v[52:55], v[4:7]
	global_load_dwordx4 v[44:47], v[84:85], off offset:1536
	global_load_dwordx4 v[48:51], v[84:85], off offset:1600
	s_waitcnt vmcnt(0) lgkmcnt(0)
	v_mfma_f32_16x16x32_bf16 v[4:7], v[20:23], v[24:27], v[4:7]
	global_load_dwordx4 v[20:23], v[86:87], off offset:1536
	global_load_dwordx4 v[24:27], v[86:87], off offset:1600
	global_load_dwordx4 v[52:55], v[84:85], off offset:1664
	v_mfma_f32_16x16x32_bf16 v[4:7], v[56:59], v[60:63], v[4:7]
	v_mfma_f32_16x16x32_bf16 v[4:7], v[28:31], v[32:35], v[4:7]
	global_load_dwordx4 v[28:31], v[86:87], off offset:1664
	v_mfma_f32_16x16x32_bf16 v[4:7], v[36:39], v[40:43], v[4:7]
	global_load_dwordx4 v[32:35], v[84:85], off offset:1728
	global_load_dwordx4 v[36:39], v[86:87], off offset:1728
	s_waitcnt vmcnt(0) lgkmcnt(0)
	v_mfma_f32_16x16x32_bf16 v[4:7], v[44:47], v[20:23], v[4:7]
	global_load_dwordx4 v[20:23], v[84:85], off offset:1792
	global_load_dwordx4 v[40:43], v[86:87], off offset:1792
	v_mfma_f32_16x16x32_bf16 v[4:7], v[48:51], v[24:27], v[4:7]
	global_load_dwordx4 v[24:27], v[84:85], off offset:1856
	v_mfma_f32_16x16x32_bf16 v[4:7], v[52:55], v[28:31], v[4:7]
	global_load_dwordx4 v[28:31], v[86:87], off offset:1856
	v_mfma_f32_16x16x32_bf16 v[4:7], v[32:35], v[36:39], v[4:7]
	global_load_dwordx4 v[32:35], v[84:85], off offset:1920
	global_load_dwordx4 v[36:39], v[86:87], off offset:1920
	s_waitcnt vmcnt(0) lgkmcnt(0)
	v_mfma_f32_16x16x32_bf16 v[4:7], v[20:23], v[40:43], v[4:7]
	global_load_dwordx4 v[20:23], v[84:85], off offset:1984
	v_mfma_f32_16x16x32_bf16 v[4:7], v[24:27], v[28:31], v[4:7]
	global_load_dwordx4 v[24:27], v[86:87], off offset:1984
	v_mfma_f32_16x16x32_bf16 v[4:7], v[32:35], v[36:39], v[4:7]
	s_waitcnt vmcnt(0) lgkmcnt(0)
	v_mfma_f32_16x16x32_bf16 v[4:7], v[20:23], v[24:27], v[4:7]

; #define PH_BEGIN const Params P = load_params(); unsigned char* ws = P.ws;
; __device__ __forceinline__ void ln_load(f32x4 (&v)[8], const float* z, int lane) {
; #pragma unroll
;     for (int j = 0; j < 8; ++j) v[j] = ((const f32x4*)z)[lane + 64 * j];
; }
; __device__ __forceinline__ void ln_apply(f32x4 (&v)[8], const float* __restrict__ g, const float* __restrict__ b, bf16_t* hb, float* fo, int lane) {
;     float s = 0.f;
; #pragma unroll
;     for (int j = 0; j < 8; ++j) s += (v[j][0] + v[j][1]) + (v[j][2] + v[j][3]);
;     const float mean = wave_sum(s) * (1.f / DM); float q = 0.f;
; #pragma unroll
;     for (int j = 0; j < 8; ++j) { v[j] = v[j] - mean; q += (v[j][0] * v[j][0] + v[j][1] * v[j][1]) + (v[j][2] * v[j][2] + v[j][3] * v[j][3]); }
; template <int L, int K>
; __device__ __forceinline__ void phase_body(char* lds, int rep_) {
;     ...
;     if constexpr (K == 8) { PH_BEGIN
;         const float* g2 = P.in[15] + L * DM; const float* b2 = P.in[16] + L * DM; const float* ZS = (const float*)(ws + WS_ZS); bf16_t* HB = (bf16_t*)(ws + WS_HB);
;         if (L == 0) {
;             const float* lg_ = g2; const float* lb_ = b2;
;     ...
;             LN_ROWS(gw, LTOK, NGW, ZR_, HR_, FR_);
.LBB0_1448:
	s_cmp_lt_i32 s80, 10
	s_cselect_b64 s[6:7], -1, 0
	s_cmp_gt_i32 s81, 9
	s_cselect_b64 s[8:9], -1, 0
	s_and_b64 s[6:7], s[6:7], s[8:9]
	s_andn2_b64 vcc, exec, s[6:7]
	s_cbranch_vccnz .LBB0_1546
	v_mov_b32_e32 v1, v194
	s_mov_b64 s[18:19], s[0:1]
	v_readfirstlane_b32 s3, v1
	s_ashr_i32 s22, s3, 6
	s_load_dword s3, s[0:1], 0xa0
	s_load_dwordx2 s[16:17], s[18:19], 0x10
	s_load_dwordx2 s[6:7], s[18:19], 0x50
	s_load_dwordx4 s[8:11], s[18:19], 0x88
	s_lshl_b32 s12, s2, 3
	v_and_b32_e32 v62, 63, v1
	s_add_i32 s20, s22, s12
	s_waitcnt lgkmcnt(0)
	s_lshl_b32 s21, s3, 3
	s_cmpk_gt_i32 s20, 0x400f
	v_lshlrev_b32_e32 v64, 3, v62
	s_cbranch_scc1 .LBB0_1458
	s_add_u32 s23, s10, 0x20000
	s_addc_u32 s24, s11, 0
	s_ashr_i32 s12, s20, 31
	s_add_i32 s14, s20, -16
	s_cmp_gt_i32 s20, 15
	s_cselect_b32 s13, 0, s12
	s_cselect_b32 s12, s14, s20
	s_cselect_b32 s14, s9, s24
	s_cselect_b32 s15, s8, s23
	s_lshl_b64 s[12:13], s[12:13], 13
	s_add_u32 s12, s15, s12
	s_addc_u32 s13, s14, s13
	v_mov_b32_e32 v67, 0
	v_lshlrev_b32_e32 v66, 4, v62
	v_lshl_add_u64 v[30:31], s[12:13], 0, v[66:67]
	s_movk_i32 s25, 0x1000
	global_load_dwordx4 v[2:5], v[30:31], off
	global_load_dwordx4 v[94:97], v[30:31], off offset:1024
	global_load_dwordx4 v[6:9], v[30:31], off offset:2048
	v_add_co_u32_e32 v32, vcc, s25, v30
	v_mbcnt_lo_u32_b32 v65, -1, 0
	s_nop 0
	v_addc_co_u32_e32 v33, vcc, 0, v31, vcc
	global_load_dwordx4 v[10:13], v[32:33], off
	global_load_dwordx4 v[14:17], v[32:33], off offset:1024
	global_load_dwordx4 v[18:21], v[32:33], off offset:3072
	global_load_dwordx4 v[22:25], v[32:33], off offset:2048
	global_load_dwordx4 v[26:29], v[30:31], off offset:3072
	v_mbcnt_hi_u32_b32 v70, -1, v65
	v_mov_b32_e32 v65, v67
	v_and_b32_e32 v71, 64, v70
	v_xor_b32_e32 v72, 1, v70
	v_lshl_add_u64 v[68:69], s[10:11], 0, v[64:65]
	v_add_u32_e32 v65, 64, v71
	v_xor_b32_e32 v73, 2, v70
	v_cmp_lt_i32_e32 vcc, v72, v65
	v_xor_b32_e32 v74, 4, v70
	s_load_dwordx4 s[12:15], s[18:19], 0x78
	v_cndmask_b32_e32 v71, v70, v72, vcc
	v_cmp_lt_i32_e32 vcc, v73, v65
	v_xor_b32_e32 v75, 8, v70
	v_xor_b32_e32 v78, 16, v70
	v_cndmask_b32_e32 v72, v70, v73, vcc
	v_cmp_lt_i32_e32 vcc, v74, v65
	v_xor_b32_e32 v79, 32, v70
	s_mov_b64 s[28:29], 0x6900000
	v_cndmask_b32_e32 v73, v70, v74, vcc
	v_cmp_lt_i32_e32 vcc, v75, v65
	v_or_b32_e32 v76, 0x1000, v66
	v_mov_b32_e32 v77, v67
	v_cndmask_b32_e32 v74, v70, v75, vcc
	v_cmp_lt_i32_e32 vcc, v78, v65
	v_or_b32_e32 v80, 0x1400, v66
	v_mov_b32_e32 v81, v67
	v_cndmask_b32_e32 v75, v70, v78, vcc
	v_cmp_lt_i32_e32 vcc, v79, v65
	v_or_b32_e32 v84, 0x1800, v66
	v_mov_b32_e32 v85, v67
	v_cndmask_b32_e32 v70, v70, v79, vcc
	v_lshlrev_b32_e32 v65, 2, v71
	v_lshlrev_b32_e32 v102, 2, v72
	v_lshlrev_b32_e32 v103, 2, v73
	v_lshlrev_b32_e32 v106, 2, v70
	s_waitcnt lgkmcnt(0)
	v_lshl_add_u64 v[70:71], s[12:13], 0, v[66:67]
	v_lshl_add_u64 v[72:73], s[14:15], 0, v[66:67]
	v_or_b32_e32 v66, 0x1c00, v66
	v_mov_b32_e32 v63, 0x3727c5ac
	s_mov_b32 s26, 0x800000
	s_mov_b32 s18, s20
	v_lshl_add_u64 v[68:69], v[68:69], 0, s[28:29]
	v_lshlrev_b32_e32 v104, 2, v74
	v_lshlrev_b32_e32 v105, 2, v75
	v_lshl_add_u64 v[74:75], s[12:13], 0, v[76:77]
	v_lshl_add_u64 v[76:77], s[14:15], 0, v[76:77]
	v_lshl_add_u64 v[78:79], s[12:13], 0, v[80:81]
	v_lshl_add_u64 v[80:81], s[14:15], 0, v[80:81]
	v_lshl_add_u64 v[82:83], s[12:13], 0, v[84:85]
	v_lshl_add_u64 v[84:85], s[14:15], 0, v[84:85]
	v_lshl_add_u64 v[86:87], s[12:13], 0, v[66:67]
	v_lshl_add_u64 v[88:89], s[14:15], 0, v[66:67]
	s_waitcnt vmcnt(0)
	v_mov_b32_e32 v91, v2
	v_mov_b32_e32 v93, v4
	v_mov_b32_e32 v90, v94
	v_mov_b32_e32 v2, v95
	v_mov_b32_e32 v92, v96
	v_mov_b32_e32 v4, v97
	v_mov_b32_e32 v94, v7
	v_mov_b32_e32 v95, v8
	v_mov_b32_e32 v7, v9
	v_mov_b32_e32 v8, v11
	v_mov_b32_e32 v96, v13
	v_mov_b32_e32 v98, v15
	v_mov_b32_e32 v99, v16
	v_mov_b32_e32 v15, v17
	v_mov_b32_e32 v16, v19
	v_mov_b32_e32 v100, v21
	s_branch .LBB0_1453
.LBB0_1451:
	v_mov_b32_e32 v108, v38
	v_mov_b32_e32 v109, v42
	v_mov_b32_e32 v110, v39
	v_mov_b32_e32 v111, v43
	v_pk_add_f32 v[108:109], v[108:109], v[110:111]
	v_mov_b32_e32 v110, v40
	v_mov_b32_e32 v111, v44
	v_mov_b32_e32 v112, v41
	v_mov_b32_e32 v113, v45
	v_pk_add_f32 v[110:111], v[110:111], v[112:113]
	v_mov_b32_e32 v112, v34
	v_pk_add_f32 v[108:109], v[108:109], v[110:111]
	v_mov_b32_e32 v110, v35
	v_mov_b32_e32 v111, v36
	v_mov_b32_e32 v113, v37
	v_pk_add_f32 v[110:111], v[110:111], v[112:113]
	v_add_f32_e32 v9, 0, v109
	v_pk_add_f32 v[110:111], v[110:111], v[110:111] op_sel_hi:[0,1]
	v_add_f32_e32 v109, v108, v9
	v_add_f32_e32 v113, v30, v31
	v_add_f32_e32 v115, v32, v33
	v_mov_b32_e32 v112, v58
	v_mov_b32_e32 v114, v59
	v_mov_b32_e32 v110, v60
	v_mov_b32_e32 v108, v61
	v_pk_add_f32 v[112:113], v[112:113], v[114:115]
	v_pk_add_f32 v[108:109], v[110:111], v[108:109]
	v_mov_b32_e32 v110, v55
	v_pk_add_f32 v[108:109], v[112:113], v[108:109]
	v_mov_b32_e32 v111, v56
	v_mov_b32_e32 v112, v54
	v_mov_b32_e32 v113, v57
	v_pk_add_f32 v[110:111], v[110:111], v[112:113]
	v_pk_add_f32 v[108:109], v[108:109], v[108:109] op_sel_hi:[0,1]
	v_pk_add_f32 v[110:111], v[110:111], v[110:111] op_sel_hi:[0,1]
	v_add_f32_e32 v113, v50, v51
	v_add_f32_e32 v115, v52, v53
	v_mov_b32_e32 v112, v46
	v_mov_b32_e32 v114, v47
	v_mov_b32_e32 v110, v48
	v_mov_b32_e32 v108, v49
	v_pk_add_f32 v[112:113], v[112:113], v[114:115]
	v_pk_add_f32 v[108:109], v[110:111], v[108:109]
	s_ashr_i32 s13, s12, 31
	v_pk_add_f32 v[108:109], v[112:113], v[108:109]
	s_lshl_b64 s[12:13], s[12:13], 12
	v_add_f32_e32 v9, v108, v109
	ds_bpermute_b32 v11, v65, v9
	s_waitcnt lgkmcnt(0)
	v_add_f32_e32 v9, v9, v11
	ds_bpermute_b32 v11, v102, v9
	s_waitcnt lgkmcnt(0)
; __device__ __forceinline__ void ln_apply(f32x4 (&v)[8], const float* __restrict__ g, const float* __restrict__ b, bf16_t* hb, float* fo, int lane) {
;     ...
;     const float mean = wave_sum(s) * (1.f / DM); float q = 0.f;
; #pragma unroll
;     for (int j = 0; j < 8; ++j) { v[j] = v[j] - mean; q += (v[j][0] * v[j][0] + v[j][1] * v[j][1]) + (v[j][2] * v[j][2] + v[j][3] * v[j][3]); }
;     const float rstd = rsqrtf(wave_sum(q) * (1.f / DM) + LN_EPS);
; #pragma unroll
;     for (int j = 0; j < 8; ++j) { const int c = (lane + 64 * j) * 4; const f32x4 gg = *(const f32x4*)(g + c), bb = *(const f32x4*)(b + c);
	v_add_f32_e32 v9, v9, v11
	ds_bpermute_b32 v11, v103, v9
	s_waitcnt lgkmcnt(0)
	v_add_f32_e32 v9, v9, v11
	ds_bpermute_b32 v11, v104, v9
	s_waitcnt lgkmcnt(0)
	v_add_f32_e32 v9, v9, v11
	ds_bpermute_b32 v11, v105, v9
	s_waitcnt lgkmcnt(0)
	v_add_f32_e32 v9, v9, v11
	ds_bpermute_b32 v11, v106, v9
	s_waitcnt lgkmcnt(0)
	v_add_f32_e32 v9, v9, v11
	v_fmamk_f32 v43, v9, 0xba000000, v43
	v_fmamk_f32 v39, v9, 0xba000000, v39
	v_fmamk_f32 v45, v9, 0xba000000, v45
	v_fmac_f32_e32 v42, 0xba000000, v9
	v_fmamk_f32 v41, v9, 0xba000000, v41
	v_fmac_f32_e32 v38, 0xba000000, v9
	v_mov_b32_e32 v110, v43
	v_mov_b32_e32 v111, v39
	v_fmamk_f32 v44, v9, 0xba000000, v44
	v_fmamk_f32 v40, v9, 0xba000000, v40
	v_mov_b32_e32 v108, v42
	v_mov_b32_e32 v109, v38
	v_pk_mul_f32 v[110:111], v[110:111], v[110:111]
	v_mov_b32_e32 v112, v45
	v_mov_b32_e32 v113, v41
	v_pk_fma_f32 v[108:109], v[108:109], v[108:109], v[110:111]
	v_mov_b32_e32 v110, v44
	v_mov_b32_e32 v111, v40
	v_pk_mul_f32 v[112:113], v[112:113], v[112:113]
	v_fmamk_f32 v37, v9, 0xba000000, v37
	v_pk_fma_f32 v[110:111], v[110:111], v[110:111], v[112:113]
	v_fmamk_f32 v36, v9, 0xba000000, v36
	v_fmamk_f32 v35, v9, 0xba000000, v35
	v_fmac_f32_e32 v34, 0xba000000, v9
	v_pk_add_f32 v[108:109], v[108:109], v[110:111]
	v_pk_mul_f32 v[110:111], v[36:37], v[36:37]
	v_pk_mul_f32 v[112:113], v[34:35], v[34:35]
	v_fmac_f32_e32 v30, 0xba000000, v9
	v_pk_mov_b32 v[114:115], v[112:113], v[110:111] op_sel:[1,0]
	v_mov_b32_e32 v113, v111
	v_fmamk_f32 v32, v9, 0xba000000, v32
	v_fmamk_f32 v31, v9, 0xba000000, v31
	v_mul_f32_e32 v66, v30, v30
	v_pk_add_f32 v[110:111], v[114:115], v[112:113]
	v_fmamk_f32 v33, v9, 0xba000000, v33
	v_pk_fma_f32 v[112:113], v[30:31], v[30:31], v[66:67] op_sel_hi:[1,1,0]
	v_mul_f32_e32 v66, v32, v32
	v_pk_add_f32 v[108:109], v[108:109], v[108:109] op_sel_hi:[0,1]
	v_pk_add_f32 v[110:111], v[110:111], v[110:111] op_sel_hi:[0,1]
	v_pk_fma_f32 v[114:115], v[32:33], v[32:33], v[66:67] op_sel_hi:[1,1,0]
	v_fmamk_f32 v61, v9, 0xba000000, v61
	v_fmamk_f32 v60, v9, 0xba000000, v60
	v_fmamk_f32 v59, v9, 0xba000000, v59
	v_fmac_f32_e32 v58, 0xba000000, v9
	v_mul_f32_e32 v112, v58, v58
	v_mul_f32_e32 v114, v59, v59
	v_mul_f32_e32 v110, v60, v60
	v_mul_f32_e32 v108, v61, v61
	v_pk_add_f32 v[112:113], v[112:113], v[114:115]
	v_pk_add_f32 v[108:109], v[110:111], v[108:109]
	v_fmamk_f32 v57, v9, 0xba000000, v57
	v_pk_add_f32 v[116:117], v[112:113], v[108:109]
	global_load_dwordx4 v[108:111], v[70:71], off
	global_load_dwordx4 v[112:115], v[72:73], off
	v_fmamk_f32 v56, v9, 0xba000000, v56
	v_fmamk_f32 v55, v9, 0xba000000, v55
	v_fmac_f32_e32 v54, 0xba000000, v9
	v_pk_mul_f32 v[118:119], v[56:57], v[56:57]
	v_pk_mul_f32 v[120:121], v[54:55], v[54:55]
	v_fmac_f32_e32 v50, 0xba000000, v9
	v_pk_mov_b32 v[122:123], v[120:121], v[118:119] op_sel:[1,0]
	v_mov_b32_e32 v121, v119
	v_fmamk_f32 v52, v9, 0xba000000, v52
	v_fmamk_f32 v51, v9, 0xba000000, v51
	v_mul_f32_e32 v66, v50, v50
	v_pk_add_f32 v[118:119], v[122:123], v[120:121]
	v_fmamk_f32 v53, v9, 0xba000000, v53
	v_pk_fma_f32 v[120:121], v[50:51], v[50:51], v[66:67] op_sel_hi:[1,1,0]
	v_mul_f32_e32 v66, v52, v52
	v_pk_add_f32 v[116:117], v[116:117], v[116:117] op_sel_hi:[0,1]
	v_pk_add_f32 v[118:119], v[118:119], v[118:119] op_sel_hi:[0,1]
	v_pk_fma_f32 v[122:123], v[52:53], v[52:53], v[66:67] op_sel_hi:[1,1,0]
	v_fmamk_f32 v49, v9, 0xba000000, v49
	v_fmamk_f32 v48, v9, 0xba000000, v48
	v_fmamk_f32 v47, v9, 0xba000000, v47
	v_fmac_f32_e32 v46, 0xba000000, v9
	v_mul_f32_e32 v120, v46, v46
	v_mul_f32_e32 v122, v47, v47
	v_mul_f32_e32 v118, v48, v48
	v_mul_f32_e32 v116, v49, v49
	v_pk_add_f32 v[120:121], v[120:121], v[122:123]
	v_pk_add_f32 v[116:117], v[118:119], v[116:117]
	s_nop 0
	v_pk_add_f32 v[116:117], v[120:121], v[116:117]
	s_nop 0
	v_add_f32_e32 v9, v116, v117
	ds_bpermute_b32 v11, v65, v9
	s_waitcnt lgkmcnt(0)
	v_add_f32_e32 v9, v9, v11
	ds_bpermute_b32 v11, v102, v9
	s_waitcnt lgkmcnt(0)
	v_add_f32_e32 v9, v9, v11
	ds_bpermute_b32 v11, v103, v9
	s_waitcnt lgkmcnt(0)
	v_add_f32_e32 v9, v9, v11
	ds_bpermute_b32 v11, v104, v9
	s_waitcnt lgkmcnt(0)
	v_add_f32_e32 v9, v9, v11
	ds_bpermute_b32 v11, v105, v9
	s_waitcnt lgkmcnt(0)
	v_add_f32_e32 v9, v9, v11
	ds_bpermute_b32 v11, v106, v9
	s_waitcnt lgkmcnt(0)
; __device__ __forceinline__ unsigned cvt_pk_bf16(float lo, float hi) { unsigned r; asm volatile("v_cvt_pk_bf16_f32 %0, %1, %2" : "=v"(r) : "v"(lo), "v"(hi)); return r; }
; __device__ __forceinline__ void ln_apply(f32x4 (&v)[8], const float* __restrict__ g, const float* __restrict__ b, bf16_t* hb, float* fo, int lane) {
;     float s = 0.f;
; #pragma unroll
;     for (int j = 0; j < 8; ++j) s += (v[j][0] + v[j][1]) + (v[j][2] + v[j][3]);
;     const float mean = wave_sum(s) * (1.f / DM); float q = 0.f;
; #pragma unroll
;     for (int j = 0; j < 8; ++j) { v[j] = v[j] - mean; q += (v[j][0] * v[j][0] + v[j][1] * v[j][1]) + (v[j][2] * v[j][2] + v[j][3] * v[j][3]); }
;     const float rstd = rsqrtf(wave_sum(q) * (1.f / DM) + LN_EPS);
; #pragma unroll
;     for (int j = 0; j < 8; ++j) { const int c = (lane + 64 * j) * 4; const f32x4 gg = *(const f32x4*)(g + c), bb = *(const f32x4*)(b + c);
;         const f32x4 y = v[j] * rstd * gg + bb;
;         if (hb) { u32x2 w; w.x = cvt_pk_bf16(y[0], y[1]); w.y = cvt_pk_bf16(y[2], y[3]); *(u32x2*)(hb + c) = w; }
;         if (fo) *(f32x4*)(fo + c) = y; }
; }
	v_add_f32_e32 v9, v9, v11
	v_fmamk_f32 v9, v9, 0x3a000000, v63
	v_mul_f32_e32 v11, 0x4b800000, v9
	v_cmp_gt_f32_e32 vcc, s26, v9
	s_nop 1
	v_cndmask_b32_e32 v9, v9, v11, vcc
	v_rsq_f32_e32 v9, v9
	s_nop 0
	v_mul_f32_e32 v11, 0x45800000, v9
	v_cndmask_b32_e32 v66, v9, v11, vcc
	v_pk_mul_f32 v[116:117], v[42:43], v[66:67] op_sel_hi:[1,0]
	v_pk_mul_f32 v[118:119], v[44:45], v[66:67] op_sel_hi:[1,0]
	s_waitcnt vmcnt(0)
	v_pk_fma_f32 v[108:109], v[108:109], v[116:117], v[112:113]
	v_pk_fma_f32 v[110:111], v[110:111], v[118:119], v[114:115]
	v_cvt_pk_bf16_f32 v116, v108, v109
	v_pk_mul_f32 v[120:121], v[38:39], v[66:67] op_sel_hi:[1,0]
	v_cvt_pk_bf16_f32 v117, v110, v111
	global_load_dwordx4 v[108:111], v[70:71], off offset:1024
	global_load_dwordx4 v[112:115], v[72:73], off offset:1024
	v_pk_mul_f32 v[122:123], v[40:41], v[66:67] op_sel_hi:[1,0]
	v_lshl_add_u64 v[118:119], v[68:69], 0, s[12:13]
	global_store_dwordx2 v[118:119], v[116:117], off
	s_waitcnt vmcnt(0) lgkmcnt(0)
	v_pk_fma_f32 v[110:111], v[110:111], v[122:123], v[114:115]
	v_pk_fma_f32 v[108:109], v[108:109], v[120:121], v[112:113]
	v_pk_mul_f32 v[120:121], v[34:35], v[66:67] op_sel_hi:[1,0]
	v_cvt_pk_bf16_f32 v116, v108, v109
	v_cvt_pk_bf16_f32 v117, v110, v111
	global_load_dwordx4 v[108:111], v[70:71], off offset:2048
	global_load_dwordx4 v[112:115], v[72:73], off offset:2048
	v_pk_mul_f32 v[122:123], v[36:37], v[66:67] op_sel_hi:[1,0]
	global_store_dwordx2 v[118:119], v[116:117], off offset:512
	s_waitcnt vmcnt(0) lgkmcnt(0)
	v_pk_fma_f32 v[110:111], v[110:111], v[122:123], v[114:115]
	v_pk_fma_f32 v[108:109], v[108:109], v[120:121], v[112:113]
	v_pk_mul_f32 v[120:121], v[30:31], v[66:67] op_sel_hi:[1,0]
	v_cvt_pk_bf16_f32 v116, v108, v109
	v_cvt_pk_bf16_f32 v117, v110, v111
	global_load_dwordx4 v[108:111], v[70:71], off offset:3072
	global_load_dwordx4 v[112:115], v[72:73], off offset:3072
	v_pk_mul_f32 v[122:123], v[32:33], v[66:67] op_sel_hi:[1,0]
	global_store_dwordx2 v[118:119], v[116:117], off offset:1024
	s_waitcnt vmcnt(0) lgkmcnt(0)
	v_pk_fma_f32 v[110:111], v[110:111], v[122:123], v[114:115]
	v_pk_fma_f32 v[108:109], v[108:109], v[120:121], v[112:113]
	v_pk_mul_f32 v[120:121], v[58:59], v[66:67] op_sel_hi:[1,0]
	v_cvt_pk_bf16_f32 v116, v108, v109
	v_cvt_pk_bf16_f32 v117, v110, v111
	global_load_dwordx4 v[108:111], v[74:75], off
	global_load_dwordx4 v[112:115], v[76:77], off
	v_pk_mul_f32 v[122:123], v[60:61], v[66:67] op_sel_hi:[1,0]
	global_store_dwordx2 v[118:119], v[116:117], off offset:1536
	s_waitcnt vmcnt(0) lgkmcnt(0)
	v_pk_fma_f32 v[110:111], v[110:111], v[122:123], v[114:115]
	v_pk_fma_f32 v[108:109], v[108:109], v[120:121], v[112:113]
	v_pk_mul_f32 v[120:121], v[54:55], v[66:67] op_sel_hi:[1,0]
	v_cvt_pk_bf16_f32 v116, v108, v109
	v_cvt_pk_bf16_f32 v117, v110, v111
	global_load_dwordx4 v[108:111], v[78:79], off
	global_load_dwordx4 v[112:115], v[80:81], off
	v_pk_mul_f32 v[122:123], v[56:57], v[66:67] op_sel_hi:[1,0]
	global_store_dwordx2 v[118:119], v[116:117], off offset:2048
	s_waitcnt vmcnt(0) lgkmcnt(0)
	v_pk_fma_f32 v[110:111], v[110:111], v[122:123], v[114:115]
	v_pk_fma_f32 v[108:109], v[108:109], v[120:121], v[112:113]
	v_pk_mul_f32 v[120:121], v[50:51], v[66:67] op_sel_hi:[1,0]
	v_cvt_pk_bf16_f32 v116, v108, v109
	v_cvt_pk_bf16_f32 v117, v110, v111
	global_load_dwordx4 v[108:111], v[82:83], off
	global_load_dwordx4 v[112:115], v[84:85], off
	v_pk_mul_f32 v[122:123], v[52:53], v[66:67] op_sel_hi:[1,0]
	global_store_dwordx2 v[118:119], v[116:117], off offset:2560
	s_waitcnt vmcnt(0) lgkmcnt(0)
	v_pk_fma_f32 v[110:111], v[122:123], v[110:111], v[114:115]
	v_pk_fma_f32 v[108:109], v[120:121], v[108:109], v[112:113]
	v_pk_mul_f32 v[120:121], v[46:47], v[66:67] op_sel_hi:[1,0]
	v_cvt_pk_bf16_f32 v116, v108, v109
	v_cvt_pk_bf16_f32 v117, v110, v111
	global_load_dwordx4 v[108:111], v[86:87], off
	global_load_dwordx4 v[112:115], v[88:89], off
	v_pk_mul_f32 v[122:123], v[48:49], v[66:67] op_sel_hi:[1,0]
	global_store_dwordx2 v[118:119], v[116:117], off offset:3072
	s_waitcnt vmcnt(0) lgkmcnt(0)
	v_pk_fma_f32 v[108:109], v[120:121], v[108:109], v[112:113]
	v_pk_fma_f32 v[110:111], v[122:123], v[110:111], v[114:115]
	v_cvt_pk_bf16_f32 v108, v108, v109
	s_nop 0
	v_cvt_pk_bf16_f32 v109, v110, v111
	global_store_dwordx2 v[118:119], v[108:109], off offset:3584

; __device__ __forceinline__ unsigned cvt_pk_bf16(float lo, float hi) { unsigned r; asm volatile("v_cvt_pk_bf16_f32 %0, %1, %2" : "=v"(r) : "v"(lo), "v"(hi)); return r; }
; __device__ __forceinline__ void ln_load(f32x4 (&v)[8], const float* z, int lane) {
; #pragma unroll
;     for (int j = 0; j < 8; ++j) v[j] = ((const f32x4*)z)[lane + 64 * j];
; }
; __device__ __forceinline__ void ln_apply(f32x4 (&v)[8], const float* __restrict__ g, const float* __restrict__ b, bf16_t* hb, float* fo, int lane) {
;     float s = 0.f;
; #pragma unroll
;     for (int j = 0; j < 8; ++j) s += (v[j][0] + v[j][1]) + (v[j][2] + v[j][3]);
;     const float mean = wave_sum(s) * (1.f / DM); float q = 0.f;
; #pragma unroll
;     for (int j = 0; j < 8; ++j) { v[j] = v[j] - mean; q += (v[j][0] * v[j][0] + v[j][1] * v[j][1]) + (v[j][2] * v[j][2] + v[j][3] * v[j][3]); }
;     const float rstd = rsqrtf(wave_sum(q) * (1.f / DM) + LN_EPS);
; #pragma unroll
;     for (int j = 0; j < 8; ++j) { const int c = (lane + 64 * j) * 4; const f32x4 gg = *(const f32x4*)(g + c), bb = *(const f32x4*)(b + c);
;         const f32x4 y = v[j] * rstd * gg + bb;
;         if (hb) { u32x2 w; w.x = cvt_pk_bf16(y[0], y[1]); w.y = cvt_pk_bf16(y[2], y[3]); *(u32x2*)(hb + c) = w; }
;         if (fo) *(f32x4*)(fo + c) = y; }
; }
.LBB0_1453:
	s_add_i32 s12, s18, s21
	s_cmpk_gt_i32 s12, 0x400f
	s_cbranch_scc1 .LBB0_1455
	s_ashr_i32 s13, s12, 31
	s_add_i32 s14, s12, -16
	s_cmp_gt_i32 s12, 15
	s_cselect_b32 s15, 0, s13
	s_cselect_b32 s14, s14, s12
	s_cselect_b32 s13, s9, s24
	s_cselect_b32 s19, s8, s23
	s_lshl_b64 s[14:15], s[14:15], 13
	s_add_u32 s14, s19, s14
	s_addc_u32 s15, s13, s15
	v_lshlrev_b32_e32 v66, 4, v62
	v_lshl_add_u64 v[46:47], s[14:15], 0, v[66:67]
	v_add_co_u32_e32 v108, vcc, 0x1000, v46
	global_load_dwordx4 v[42:45], v[46:47], off
	global_load_dwordx4 v[38:41], v[46:47], off offset:1024
	global_load_dwordx4 v[34:37], v[46:47], off offset:2048
	global_load_dwordx4 v[30:33], v[46:47], off offset:3072
	v_addc_co_u32_e32 v109, vcc, 0, v47, vcc
	global_load_dwordx4 v[58:61], v[108:109], off
	global_load_dwordx4 v[54:57], v[108:109], off offset:1024
	global_load_dwordx4 v[50:53], v[108:109], off offset:2048
	global_load_dwordx4 v[46:49], v[108:109], off offset:3072
.LBB0_1455:
	v_pk_add_f32 v[108:109], v[90:91], v[2:3]
	v_pk_add_f32 v[110:111], v[92:93], v[4:5]
	v_add_f32_e32 v11, v26, v27
	v_pk_add_f32 v[108:109], v[108:109], v[110:111]
	v_add_f32_e32 v19, v22, v23
	v_add_f32_e32 v9, 0, v109
	v_add_f32_e32 v97, v108, v9
	v_pk_add_f32 v[108:109], v[94:95], v[6:7]
	v_add_f32_e32 v9, v28, v29
	v_pk_add_f32 v[108:109], v[108:109], v[108:109] op_sel_hi:[0,1]
	v_mov_b32_e32 v13, v109
	v_pk_add_f32 v[110:111], v[10:11], v[8:9]
	v_pk_add_f32 v[108:109], v[12:13], v[96:97]
	v_add_f32_e32 v17, v24, v25
	v_pk_add_f32 v[108:109], v[110:111], v[108:109]
	v_pk_add_f32 v[110:111], v[98:99], v[14:15]
	v_pk_add_f32 v[108:109], v[108:109], v[108:109] op_sel_hi:[0,1]
	v_pk_add_f32 v[110:111], v[110:111], v[110:111] op_sel_hi:[0,1]
	v_mov_b32_e32 v21, v111
	v_mov_b32_e32 v101, v109
	v_pk_add_f32 v[112:113], v[18:19], v[16:17]
	v_pk_add_f32 v[108:109], v[20:21], v[100:101]
	s_ashr_i32 s19, s18, 31
	v_pk_add_f32 v[108:109], v[112:113], v[108:109]
	s_lshl_b64 s[14:15], s[18:19], 12
	v_add_f32_e32 v9, v108, v109
	ds_bpermute_b32 v11, v65, v9
	s_cmpk_gt_i32 s12, 0x400f
	s_waitcnt lgkmcnt(0)
	v_add_f32_e32 v9, v9, v11
	ds_bpermute_b32 v11, v102, v9
	s_waitcnt lgkmcnt(0)
	v_add_f32_e32 v9, v9, v11
	ds_bpermute_b32 v11, v103, v9
	s_waitcnt lgkmcnt(0)
	v_add_f32_e32 v9, v9, v11
	ds_bpermute_b32 v11, v104, v9
	s_waitcnt lgkmcnt(0)
	v_add_f32_e32 v9, v9, v11
	ds_bpermute_b32 v11, v105, v9
	s_waitcnt lgkmcnt(0)
	v_add_f32_e32 v9, v9, v11
	ds_bpermute_b32 v11, v106, v9
	s_waitcnt lgkmcnt(0)
	v_add_f32_e32 v9, v9, v11
	v_fmac_f32_e32 v3, 0xba000000, v9
	v_fmac_f32_e32 v2, 0xba000000, v9
	v_fmac_f32_e32 v91, 0xba000000, v9
	v_fmac_f32_e32 v90, 0xba000000, v9
	v_mov_b32_e32 v110, v3
	v_mov_b32_e32 v111, v2
	v_fmac_f32_e32 v5, 0xba000000, v9
	v_fmac_f32_e32 v4, 0xba000000, v9
	v_mov_b32_e32 v108, v91
	v_mov_b32_e32 v109, v90
	v_pk_mul_f32 v[110:111], v[110:111], v[110:111]
	v_fmac_f32_e32 v93, 0xba000000, v9
	v_fmac_f32_e32 v92, 0xba000000, v9
	v_pk_fma_f32 v[108:109], v[108:109], v[108:109], v[110:111]
	v_mov_b32_e32 v110, v5
	v_mov_b32_e32 v111, v4
	v_mov_b32_e32 v112, v93
	v_mov_b32_e32 v113, v92
	v_pk_mul_f32 v[110:111], v[110:111], v[110:111]
	v_fmac_f32_e32 v7, 0xba000000, v9
	v_fmac_f32_e32 v95, 0xba000000, v9
	v_fmac_f32_e32 v94, 0xba000000, v9
	v_fmac_f32_e32 v6, 0xba000000, v9
	v_pk_fma_f32 v[110:111], v[112:113], v[112:113], v[110:111]
	v_mov_b32_e32 v116, v95
	v_mov_b32_e32 v117, v7
	v_mov_b32_e32 v118, v6
	v_mov_b32_e32 v119, v94
	v_pk_add_f32 v[108:109], v[108:109], v[110:111]
	v_pk_mul_f32 v[110:111], v[116:117], v[116:117]
	v_pk_mul_f32 v[112:113], v[118:119], v[118:119]
	v_fmac_f32_e32 v26, 0xba000000, v9
	v_pk_mov_b32 v[114:115], v[112:113], v[110:111] op_sel:[1,0]
	v_mov_b32_e32 v113, v111
	v_fmac_f32_e32 v28, 0xba000000, v9
	v_fmac_f32_e32 v27, 0xba000000, v9
	v_mul_f32_e32 v66, v26, v26
	v_pk_add_f32 v[110:111], v[114:115], v[112:113]
	v_fmac_f32_e32 v29, 0xba000000, v9
	v_pk_fma_f32 v[112:113], v[26:27], v[26:27], v[66:67] op_sel_hi:[1,1,0]
	v_mul_f32_e32 v66, v28, v28
	v_pk_add_f32 v[108:109], v[108:109], v[108:109] op_sel_hi:[0,1]
	v_pk_add_f32 v[110:111], v[110:111], v[110:111] op_sel_hi:[0,1]
	v_pk_fma_f32 v[114:115], v[28:29], v[28:29], v[66:67] op_sel_hi:[1,1,0]
	v_fmac_f32_e32 v96, 0xba000000, v9
	v_fmac_f32_e32 v12, 0xba000000, v9
	v_fmac_f32_e32 v8, 0xba000000, v9
	v_fmac_f32_e32 v10, 0xba000000, v9
	v_mul_f32_e32 v112, v10, v10
	v_mul_f32_e32 v114, v8, v8
	v_mul_f32_e32 v110, v12, v12
	v_mul_f32_e32 v108, v96, v96
	v_pk_add_f32 v[112:113], v[112:113], v[114:115]
	v_pk_add_f32 v[108:109], v[110:111], v[108:109]
	v_fmac_f32_e32 v15, 0xba000000, v9
	v_pk_add_f32 v[108:109], v[112:113], v[108:109]
	v_fmac_f32_e32 v99, 0xba000000, v9
	v_pk_add_f32 v[120:121], v[108:109], v[108:109] op_sel_hi:[0,1]
	global_load_dwordx4 v[108:111], v[70:71], off
	global_load_dwordx4 v[112:115], v[72:73], off
	v_fmac_f32_e32 v98, 0xba000000, v9
	v_fmac_f32_e32 v14, 0xba000000, v9
	v_mov_b32_e32 v122, v99
	v_mov_b32_e32 v123, v15
	v_mov_b32_e32 v126, v14
	v_mov_b32_e32 v127, v98
	v_pk_mul_f32 v[124:125], v[122:123], v[122:123]
	v_pk_mul_f32 v[128:129], v[126:127], v[126:127]
	v_fmac_f32_e32 v22, 0xba000000, v9
	v_pk_mov_b32 v[130:131], v[128:129], v[124:125] op_sel:[1,0]
	v_mov_b32_e32 v129, v125
	v_fmac_f32_e32 v24, 0xba000000, v9
	v_fmac_f32_e32 v23, 0xba000000, v9
	v_mul_f32_e32 v66, v22, v22
	v_pk_add_f32 v[124:125], v[130:131], v[128:129]
	v_fmac_f32_e32 v25, 0xba000000, v9
	v_pk_fma_f32 v[128:129], v[22:23], v[22:23], v[66:67] op_sel_hi:[1,1,0]
	v_mul_f32_e32 v66, v24, v24
	v_pk_add_f32 v[124:125], v[124:125], v[124:125] op_sel_hi:[0,1]
	v_pk_fma_f32 v[130:131], v[24:25], v[24:25], v[66:67] op_sel_hi:[1,1,0]
	v_fmac_f32_e32 v100, 0xba000000, v9
	v_fmac_f32_e32 v20, 0xba000000, v9
	v_fmac_f32_e32 v16, 0xba000000, v9
	v_fmac_f32_e32 v18, 0xba000000, v9
	v_mul_f32_e32 v128, v18, v18
	v_mul_f32_e32 v130, v16, v16
	v_mul_f32_e32 v124, v20, v20
	v_mul_f32_e32 v120, v100, v100
	v_pk_add_f32 v[128:129], v[128:129], v[130:131]
	v_pk_add_f32 v[120:121], v[124:125], v[120:121]
	v_mov_b32_e32 v124, v93
	v_pk_add_f32 v[120:121], v[128:129], v[120:121]
	v_mov_b32_e32 v125, v5
	v_add_f32_e32 v9, v120, v121
	ds_bpermute_b32 v11, v65, v9
	v_mov_b32_e32 v120, v91
	v_mov_b32_e32 v121, v3
	v_mov_b32_e32 v128, v90
	v_mov_b32_e32 v129, v2
	s_waitcnt lgkmcnt(0)
; __device__ __forceinline__ unsigned cvt_pk_bf16(float lo, float hi) { unsigned r; asm volatile("v_cvt_pk_bf16_f32 %0, %1, %2" : "=v"(r) : "v"(lo), "v"(hi)); return r; }
; __device__ __forceinline__ void ln_apply(f32x4 (&v)[8], const float* __restrict__ g, const float* __restrict__ b, bf16_t* hb, float* fo, int lane) {
;     float s = 0.f;
; #pragma unroll
;     for (int j = 0; j < 8; ++j) s += (v[j][0] + v[j][1]) + (v[j][2] + v[j][3]);
;     const float mean = wave_sum(s) * (1.f / DM); float q = 0.f;
; #pragma unroll
;     for (int j = 0; j < 8; ++j) { v[j] = v[j] - mean; q += (v[j][0] * v[j][0] + v[j][1] * v[j][1]) + (v[j][2] * v[j][2] + v[j][3] * v[j][3]); }
;     const float rstd = rsqrtf(wave_sum(q) * (1.f / DM) + LN_EPS);
; #pragma unroll
;     for (int j = 0; j < 8; ++j) { const int c = (lane + 64 * j) * 4; const f32x4 gg = *(const f32x4*)(g + c), bb = *(const f32x4*)(b + c);
;         const f32x4 y = v[j] * rstd * gg + bb;
;         if (hb) { u32x2 w; w.x = cvt_pk_bf16(y[0], y[1]); w.y = cvt_pk_bf16(y[2], y[3]); *(u32x2*)(hb + c) = w; }
;         if (fo) *(f32x4*)(fo + c) = y; }
; }
	v_add_f32_e32 v9, v9, v11
	ds_bpermute_b32 v11, v102, v9
	v_mov_b32_e32 v130, v92
	v_mov_b32_e32 v131, v4
	v_mov_b32_e32 v13, v96
	v_mov_b32_e32 v19, v16
	s_waitcnt lgkmcnt(0)
	v_add_f32_e32 v9, v9, v11
	ds_bpermute_b32 v11, v103, v9
	v_mov_b32_e32 v21, v100
	s_waitcnt lgkmcnt(0)
	v_add_f32_e32 v9, v9, v11
	ds_bpermute_b32 v11, v104, v9
	s_waitcnt lgkmcnt(0)
	v_add_f32_e32 v9, v9, v11
	ds_bpermute_b32 v11, v105, v9
	s_waitcnt lgkmcnt(0)
	v_add_f32_e32 v9, v9, v11
	ds_bpermute_b32 v11, v106, v9
	s_waitcnt lgkmcnt(0)
	v_add_f32_e32 v9, v9, v11
	v_fmamk_f32 v9, v9, 0x3a000000, v63
	v_mul_f32_e32 v11, 0x4b800000, v9
	v_cmp_gt_f32_e32 vcc, s26, v9
	s_nop 1
	v_cndmask_b32_e32 v9, v9, v11, vcc
	v_rsq_f32_e32 v9, v9
	s_nop 0
	v_mul_f32_e32 v11, 0x45800000, v9
	v_cndmask_b32_e32 v66, v9, v11, vcc
	v_pk_mul_f32 v[120:121], v[120:121], v[66:67] op_sel_hi:[1,0]
	v_pk_mul_f32 v[124:125], v[124:125], v[66:67] op_sel_hi:[1,0]
	s_waitcnt vmcnt(0)
	v_pk_fma_f32 v[108:109], v[108:109], v[120:121], v[112:113]
	v_pk_fma_f32 v[110:111], v[110:111], v[124:125], v[114:115]
	v_cvt_pk_bf16_f32 v120, v108, v109
	v_pk_mul_f32 v[128:129], v[128:129], v[66:67] op_sel_hi:[1,0]
	v_cvt_pk_bf16_f32 v121, v110, v111
	global_load_dwordx4 v[108:111], v[70:71], off offset:1024
	global_load_dwordx4 v[112:115], v[72:73], off offset:1024
	v_pk_mul_f32 v[130:131], v[130:131], v[66:67] op_sel_hi:[1,0]
	v_lshl_add_u64 v[124:125], v[68:69], 0, s[14:15]
	global_store_dwordx2 v[124:125], v[120:121], off
	v_pk_mul_f32 v[118:119], v[118:119], v[66:67] op_sel_hi:[1,0]
	v_pk_mul_f32 v[116:117], v[116:117], v[66:67] op_sel_hi:[1,0]
	v_mov_b32_e32 v11, v8
	s_mov_b64 s[14:15], -1
	s_waitcnt vmcnt(0) lgkmcnt(0)
	v_pk_fma_f32 v[110:111], v[110:111], v[130:131], v[114:115]
	v_pk_fma_f32 v[108:109], v[108:109], v[128:129], v[112:113]
	s_nop 0
	v_cvt_pk_bf16_f32 v120, v108, v109
	v_cvt_pk_bf16_f32 v121, v110, v111
	global_load_dwordx4 v[108:111], v[70:71], off offset:2048
	global_load_dwordx4 v[112:115], v[72:73], off offset:2048
	s_waitcnt vmcnt(0) lgkmcnt(0)
	v_pk_fma_f32 v[110:111], v[110:111], v[116:117], v[114:115]
	v_pk_fma_f32 v[108:109], v[108:109], v[118:119], v[112:113]
	global_store_dwordx2 v[124:125], v[120:121], off offset:512
	v_cvt_pk_bf16_f32 v116, v108, v109
	v_cvt_pk_bf16_f32 v117, v110, v111
	global_load_dwordx4 v[108:111], v[70:71], off offset:3072
	global_load_dwordx4 v[112:115], v[72:73], off offset:3072
	v_pk_mul_f32 v[118:119], v[26:27], v[66:67] op_sel_hi:[1,0]
	v_pk_mul_f32 v[120:121], v[28:29], v[66:67] op_sel_hi:[1,0]
	global_store_dwordx2 v[124:125], v[116:117], off offset:1024
	s_waitcnt vmcnt(0) lgkmcnt(0)
	v_pk_fma_f32 v[110:111], v[110:111], v[120:121], v[114:115]
	v_pk_fma_f32 v[108:109], v[108:109], v[118:119], v[112:113]
	v_pk_mul_f32 v[118:119], v[10:11], v[66:67] op_sel_hi:[1,0]
	v_cvt_pk_bf16_f32 v116, v108, v109
	v_cvt_pk_bf16_f32 v117, v110, v111
	global_load_dwordx4 v[108:111], v[74:75], off
	global_load_dwordx4 v[112:115], v[76:77], off
	v_pk_mul_f32 v[120:121], v[12:13], v[66:67] op_sel_hi:[1,0]
	global_store_dwordx2 v[124:125], v[116:117], off offset:1536
	s_waitcnt vmcnt(0) lgkmcnt(0)
	v_pk_fma_f32 v[110:111], v[110:111], v[120:121], v[114:115]
	v_pk_fma_f32 v[108:109], v[108:109], v[118:119], v[112:113]
	v_pk_mul_f32 v[118:119], v[126:127], v[66:67] op_sel_hi:[1,0]
	v_cvt_pk_bf16_f32 v116, v108, v109
	v_cvt_pk_bf16_f32 v117, v110, v111
	global_load_dwordx4 v[108:111], v[78:79], off
	global_load_dwordx4 v[112:115], v[80:81], off
	v_pk_mul_f32 v[120:121], v[122:123], v[66:67] op_sel_hi:[1,0]
	global_store_dwordx2 v[124:125], v[116:117], off offset:2048
	s_waitcnt vmcnt(0) lgkmcnt(0)
	v_pk_fma_f32 v[110:111], v[110:111], v[120:121], v[114:115]
	v_pk_fma_f32 v[108:109], v[108:109], v[118:119], v[112:113]
	v_pk_mul_f32 v[118:119], v[22:23], v[66:67] op_sel_hi:[1,0]
	v_cvt_pk_bf16_f32 v116, v108, v109
	v_cvt_pk_bf16_f32 v117, v110, v111
	global_load_dwordx4 v[108:111], v[82:83], off
	global_load_dwordx4 v[112:115], v[84:85], off
	v_pk_mul_f32 v[120:121], v[24:25], v[66:67] op_sel_hi:[1,0]
	global_store_dwordx2 v[124:125], v[116:117], off offset:2560
	s_waitcnt vmcnt(0) lgkmcnt(0)
	v_pk_fma_f32 v[110:111], v[120:121], v[110:111], v[114:115]
	v_pk_fma_f32 v[108:109], v[118:119], v[108:109], v[112:113]
	v_pk_mul_f32 v[118:119], v[18:19], v[66:67] op_sel_hi:[1,0]
	v_cvt_pk_bf16_f32 v116, v108, v109
	v_cvt_pk_bf16_f32 v117, v110, v111
	global_load_dwordx4 v[108:111], v[86:87], off
	global_load_dwordx4 v[112:115], v[88:89], off
	v_pk_mul_f32 v[120:121], v[20:21], v[66:67] op_sel_hi:[1,0]
	global_store_dwordx2 v[124:125], v[116:117], off offset:3072
	s_waitcnt vmcnt(0) lgkmcnt(0)
	v_pk_fma_f32 v[108:109], v[118:119], v[108:109], v[112:113]
	v_pk_fma_f32 v[110:111], v[120:121], v[110:111], v[114:115]
	v_cvt_pk_bf16_f32 v108, v108, v109
	s_nop 0
	v_cvt_pk_bf16_f32 v109, v110, v111
	global_store_dwordx2 v[124:125], v[108:109], off offset:3584
	s_cbranch_scc1 .LBB0_1452
	s_add_i32 s13, s12, s21
	s_cmpk_gt_i32 s13, 0x400f
	s_cselect_b64 s[14:15], -1, 0
	s_and_b64 vcc, exec, s[14:15]
	s_cbranch_vccnz .LBB0_1451
	s_ashr_i32 s18, s13, 31
	s_add_i32 s27, s13, -16
	s_cmp_gt_i32 s13, 15
	s_cselect_b32 s19, 0, s18
	s_cselect_b32 s18, s27, s13
	s_cselect_b32 s27, s9, s24
	s_cselect_b32 s28, s8, s23
	s_lshl_b64 s[18:19], s[18:19], 13
	s_add_u32 s18, s28, s18
	s_addc_u32 s19, s27, s19
	v_lshlrev_b32_e32 v66, 4, v62
	v_lshl_add_u64 v[90:91], s[18:19], 0, v[66:67]
	global_load_dwordx4 v[2:5], v[90:91], off
	global_load_dwordx4 v[94:97], v[90:91], off offset:1024
	global_load_dwordx4 v[6:9], v[90:91], off offset:2048
	v_add_co_u32_e32 v92, vcc, s25, v90
	s_mov_b32 s18, s13
	s_nop 0
	v_addc_co_u32_e32 v93, vcc, 0, v91, vcc
	global_load_dwordx4 v[10:13], v[92:93], off
	global_load_dwordx4 v[14:17], v[92:93], off offset:1024
	global_load_dwordx4 v[18:21], v[92:93], off offset:3072
	global_load_dwordx4 v[22:25], v[92:93], off offset:2048
	global_load_dwordx4 v[26:29], v[90:91], off offset:3072
	s_waitcnt vmcnt(0) lgkmcnt(0)
	v_mov_b32_e32 v91, v2
	v_mov_b32_e32 v93, v4
	v_mov_b32_e32 v90, v94
	v_mov_b32_e32 v2, v95
	v_mov_b32_e32 v92, v96
	v_mov_b32_e32 v4, v97
	v_mov_b32_e32 v94, v7
	v_mov_b32_e32 v95, v8
	v_mov_b32_e32 v7, v9
	v_mov_b32_e32 v8, v11
	v_mov_b32_e32 v96, v13
	v_mov_b32_e32 v98, v15
	v_mov_b32_e32 v99, v16
	v_mov_b32_e32 v15, v17
	v_mov_b32_e32 v16, v19
	v_mov_b32_e32 v100, v21
	s_branch .LBB0_1451

; __device__ __forceinline__ unsigned cvt_pk_bf16(float lo, float hi) { unsigned r; asm volatile("v_cvt_pk_bf16_f32 %0, %1, %2" : "=v"(r) : "v"(lo), "v"(hi)); return r; }
; __device__ __forceinline__ void transpose_item(const float* __restrict__ W, int K, int N, int nblk, bf16_t* __restrict__ WT, int mode, float* scr, int item, int lane) {
;     ...
;     for (int i = 0; i < 32; ++i) { const int kk = 2 * i + (lane >> 5); scr[kk * 33 + (lane & 31)] = wv[i]; }
;     asm volatile("s_waitcnt lgkmcnt(0)" ::: "memory");
;     const int c = lane & 7;
; #pragma unroll
;     for (int j = 0; j < 4; ++j) { const int nn = (lane >> 3) + 8 * j; const float* s = scr + (8 * c) * 33 + nn;
;         u32x4 o; o.x = cvt_pk_bf16(s[0 * 33], s[1 * 33]); o.y = cvt_pk_bf16(s[2 * 33], s[3 * 33]); o.z = cvt_pk_bf16(s[4 * 33], s[5 * 33]); o.w = cvt_pk_bf16(s[6 * 33], s[7 * 33]);
;         *(u32x4*)(WT + (size_t)(n0 + nn) * K + k0 + 8 * c) = o; }
;     asm volatile("s_waitcnt lgkmcnt(0)" ::: "memory");
.LBB0_1460:
	s_or_b64 exec, exec, s[16:17]
	s_waitcnt vmcnt(0) lgkmcnt(0)
	ds_write2_b32 v11, v2, v25 offset1:66
	ds_write2_b32 v11, v27, v26 offset0:132 offset1:198
	ds_write2_b32 v17, v29, v28 offset0:8 offset1:74
	ds_write2_b32 v17, v31, v30 offset0:140 offset1:206
	ds_write2_b32 v18, v33, v32 offset0:16 offset1:82
	ds_write2_b32 v18, v35, v34 offset0:148 offset1:214
	ds_write2_b32 v19, v37, v36 offset0:24 offset1:90
	ds_write2_b32 v19, v39, v38 offset0:156 offset1:222
	ds_write2_b32 v20, v41, v40 offset0:32 offset1:98
	ds_write2_b32 v20, v43, v42 offset0:164 offset1:230
	ds_write2_b32 v21, v45, v44 offset0:40 offset1:106
	ds_write2_b32 v21, v47, v46 offset0:172 offset1:238
	ds_write2_b32 v22, v49, v48 offset0:48 offset1:114
	ds_write2_b32 v22, v51, v50 offset0:180 offset1:246
	ds_write2_b32 v23, v53, v52 offset0:56 offset1:122
	ds_write2_b32 v23, v55, v54 offset0:188 offset1:254
	s_waitcnt lgkmcnt(0)
	ds_read2_b32 v[8:9], v13 offset1:33
	s_waitcnt lgkmcnt(0)
	v_cvt_pk_bf16_f32 v24, v8, v9
	ds_read2_b32 v[8:9], v13 offset0:66 offset1:99
	s_waitcnt lgkmcnt(0)
	v_cvt_pk_bf16_f32 v25, v8, v9
	ds_read2_b32 v[8:9], v13 offset0:132 offset1:165
	s_waitcnt lgkmcnt(0)
	v_cvt_pk_bf16_f32 v26, v8, v9
	ds_read2_b32 v[8:9], v13 offset0:198 offset1:231
	s_waitcnt lgkmcnt(0)
	v_cvt_pk_bf16_f32 v27, v8, v9
	v_add_u32_e32 v8, s12, v12
	s_ashr_i32 s15, s14, 31
	v_ashrrev_i32_e32 v9, 31, v8
	v_lshl_add_u64 v[28:29], s[14:15], 1, v[6:7]
	v_lshlrev_b64 v[32:33], 12, v[8:9]
	v_lshl_add_u64 v[32:33], v[28:29], 0, v[32:33]
	global_store_dwordx4 v[32:33], v[24:27], off
	v_add_u32_e32 v32, 8, v8
	v_ashrrev_i32_e32 v33, 31, v32
	ds_read2_b32 v[30:31], v13 offset0:8 offset1:41
	s_waitcnt lgkmcnt(0)
	v_cvt_pk_bf16_f32 v24, v30, v31
	ds_read2_b32 v[26:27], v13 offset0:74 offset1:107
	v_lshlrev_b64 v[32:33], 12, v[32:33]
	s_waitcnt lgkmcnt(0)
	v_cvt_pk_bf16_f32 v25, v26, v27
	ds_read2_b32 v[26:27], v13 offset0:140 offset1:173
	v_lshl_add_u64 v[32:33], v[28:29], 0, v[32:33]
	s_waitcnt lgkmcnt(0)
	v_cvt_pk_bf16_f32 v26, v26, v27
	ds_read2_b32 v[30:31], v13 offset0:206 offset1:239
	s_waitcnt lgkmcnt(0)
	v_cvt_pk_bf16_f32 v27, v30, v31
	global_store_dwordx4 v[32:33], v[24:27], off
	v_add_u32_e32 v32, 16, v8
	ds_read2_b32 v[30:31], v13 offset0:16 offset1:49
	s_waitcnt lgkmcnt(0)
	v_cvt_pk_bf16_f32 v24, v30, v31
	ds_read2_b32 v[26:27], v13 offset0:82 offset1:115
	v_ashrrev_i32_e32 v33, 31, v32
	s_waitcnt lgkmcnt(0)
	v_cvt_pk_bf16_f32 v25, v26, v27
	ds_read2_b32 v[26:27], v13 offset0:148 offset1:181
	v_lshlrev_b64 v[32:33], 12, v[32:33]
	v_add_u32_e32 v8, 24, v8
	s_waitcnt lgkmcnt(0)
	v_cvt_pk_bf16_f32 v26, v26, v27
	ds_read2_b32 v[30:31], v13 offset0:214 offset1:247
	s_waitcnt lgkmcnt(0)
	v_cvt_pk_bf16_f32 v27, v30, v31
	v_lshl_add_u64 v[32:33], v[28:29], 0, v[32:33]
	v_ashrrev_i32_e32 v9, 31, v8
	ds_read2_b32 v[30:31], v13 offset0:24 offset1:57
	global_store_dwordx4 v[32:33], v[24:27], off
	v_lshlrev_b64 v[8:9], 12, v[8:9]
	v_lshl_add_u64 v[8:9], v[28:29], 0, v[8:9]
	s_waitcnt lgkmcnt(0)
	v_cvt_pk_bf16_f32 v24, v30, v31
	ds_read2_b32 v[26:27], v13 offset0:90 offset1:123
	s_waitcnt lgkmcnt(0)
	v_cvt_pk_bf16_f32 v25, v26, v27
	ds_read2_b32 v[26:27], v13 offset0:156 offset1:189
	s_waitcnt lgkmcnt(0)
	v_cvt_pk_bf16_f32 v26, v26, v27
	ds_read2_b32 v[30:31], v13 offset0:222 offset1:255
	s_waitcnt lgkmcnt(0)
	v_cvt_pk_bf16_f32 v27, v30, v31
	global_store_dwordx4 v[8:9], v[24:27], off
	s_waitcnt lgkmcnt(0)

; __device__ __forceinline__ void transpose_item(const float* __restrict__ W, int K, int N, int nblk, bf16_t* __restrict__ WT, int mode, float* scr, int item, int lane) {
;     const int kb = item / nblk, nb = item % nblk, k0 = 64 * kb, n0 = 32 * nb;
;     const int n = n0 + (lane & 31); int src = n;
;     if (mode) src = n < 2048 ? n : (n < 6144 ? n + 8 : (n < 6152 ? n - 6144 + 2048 : (n < 6160 ? n : -1)));
;     float wv[32];
; #pragma unroll
;     for (int i = 0; i < 32; ++i) { const int kk = 2 * i + (lane >> 5); wv[i] = src >= 0 ? W[(size_t)(k0 + kk) * N + src] : 0.f; }
.LBB0_1464:
	s_add_i32 s12, s20, 0xe700
	s_and_b32 s14, s18, 0x7e0
	s_and_b32 s12, s12, 0xffc0
	v_or_b32_e32 v2, s14, v1
	v_or_b32_e32 v24, s12, v10
	v_lshlrev_b32_e32 v2, 2, v2
	v_lshl_add_u64 v[8:9], s[6:7], 0, v[2:3]
	v_lshlrev_b32_e32 v2, 13, v24
	v_lshl_add_u64 v[8:9], v[8:9], 0, v[2:3]
	v_add_co_u32_e32 v24, vcc, 0x4000, v8
	s_lshl_b32 s12, s12, 1
	s_nop 0
	v_addc_co_u32_e32 v25, vcc, 0, v9, vcc
	v_add_co_u32_e32 v26, vcc, 0x8000, v8
	s_nop 1
	v_addc_co_u32_e32 v27, vcc, 0, v9, vcc
	v_add_co_u32_e32 v28, vcc, 0xc000, v8
	s_nop 1
	v_addc_co_u32_e32 v29, vcc, 0, v9, vcc
	v_add_co_u32_e32 v30, vcc, 0x10000, v8
	s_nop 1
	v_addc_co_u32_e32 v31, vcc, 0, v9, vcc
	v_add_co_u32_e32 v32, vcc, 0x14000, v8
	s_nop 1
	v_addc_co_u32_e32 v33, vcc, 0, v9, vcc
	v_add_co_u32_e32 v34, vcc, 0x18000, v8
	s_nop 1
	v_addc_co_u32_e32 v35, vcc, 0, v9, vcc
	v_add_co_u32_e32 v36, vcc, 0x1c000, v8
	s_nop 1
	v_addc_co_u32_e32 v37, vcc, 0, v9, vcc
	flat_load_dword v2, v[8:9]
	flat_load_dword v40, v[24:25]
	flat_load_dword v41, v[26:27]
	flat_load_dword v42, v[28:29]
	flat_load_dword v43, v[30:31]
	flat_load_dword v44, v[32:33]
	flat_load_dword v45, v[34:35]
	flat_load_dword v46, v[36:37]
	v_add_co_u32_e32 v24, vcc, 0x20000, v8
	s_nop 1
	v_addc_co_u32_e32 v25, vcc, 0, v9, vcc
	v_add_co_u32_e32 v26, vcc, 0x24000, v8
	s_nop 1
	v_addc_co_u32_e32 v27, vcc, 0, v9, vcc
	v_add_co_u32_e32 v28, vcc, 0x28000, v8
	s_nop 1
	v_addc_co_u32_e32 v29, vcc, 0, v9, vcc
	v_add_co_u32_e32 v30, vcc, 0x2c000, v8
	s_nop 1
	v_addc_co_u32_e32 v31, vcc, 0, v9, vcc
	v_add_co_u32_e32 v32, vcc, 0x30000, v8
	s_nop 1
	v_addc_co_u32_e32 v33, vcc, 0, v9, vcc
	v_add_co_u32_e32 v34, vcc, 0x34000, v8
	s_nop 1
	v_addc_co_u32_e32 v35, vcc, 0, v9, vcc
	v_add_co_u32_e32 v36, vcc, 0x38000, v8
	s_nop 1
	v_addc_co_u32_e32 v37, vcc, 0, v9, vcc
	v_add_co_u32_e32 v38, vcc, 0x3c000, v8
	s_nop 1
	v_addc_co_u32_e32 v39, vcc, 0, v9, vcc
	flat_load_dword v47, v[24:25]
	flat_load_dword v48, v[26:27]
	flat_load_dword v49, v[28:29]
	flat_load_dword v50, v[30:31]
	flat_load_dword v51, v[32:33]
	flat_load_dword v52, v[34:35]
	flat_load_dword v53, v[36:37]
	flat_load_dword v54, v[38:39]
	v_add_co_u32_e32 v24, vcc, 0x40000, v8
	s_nop 1
	v_addc_co_u32_e32 v25, vcc, 0, v9, vcc
	v_add_co_u32_e32 v26, vcc, 0x44000, v8
	s_nop 1
	v_addc_co_u32_e32 v27, vcc, 0, v9, vcc
	v_add_co_u32_e32 v28, vcc, 0x48000, v8
	s_nop 1
	v_addc_co_u32_e32 v29, vcc, 0, v9, vcc
	v_add_co_u32_e32 v30, vcc, 0x4c000, v8
	s_nop 1
	v_addc_co_u32_e32 v31, vcc, 0, v9, vcc
	v_add_co_u32_e32 v32, vcc, 0x50000, v8
	s_nop 1
	v_addc_co_u32_e32 v33, vcc, 0, v9, vcc
	v_add_co_u32_e32 v34, vcc, 0x54000, v8
	s_nop 1
	v_addc_co_u32_e32 v35, vcc, 0, v9, vcc
	v_add_co_u32_e32 v36, vcc, 0x58000, v8
	s_nop 1
	v_addc_co_u32_e32 v37, vcc, 0, v9, vcc
	v_add_co_u32_e32 v38, vcc, 0x5c000, v8
	s_nop 1
	v_addc_co_u32_e32 v39, vcc, 0, v9, vcc
	flat_load_dword v55, v[24:25]
	flat_load_dword v56, v[26:27]
	flat_load_dword v57, v[28:29]
	flat_load_dword v58, v[30:31]
	flat_load_dword v59, v[32:33]
	flat_load_dword v60, v[34:35]
	flat_load_dword v61, v[36:37]
	flat_load_dword v62, v[38:39]
	v_add_co_u32_e32 v24, vcc, 0x60000, v8
	s_nop 1
	v_addc_co_u32_e32 v25, vcc, 0, v9, vcc
	v_add_co_u32_e32 v26, vcc, 0x64000, v8
	s_nop 1
	v_addc_co_u32_e32 v27, vcc, 0, v9, vcc
	v_add_co_u32_e32 v28, vcc, 0x68000, v8
	s_nop 1
	v_addc_co_u32_e32 v29, vcc, 0, v9, vcc
	v_add_co_u32_e32 v30, vcc, 0x6c000, v8
	s_nop 1
	v_addc_co_u32_e32 v31, vcc, 0, v9, vcc
	v_add_co_u32_e32 v32, vcc, 0x70000, v8
	s_nop 1
	v_addc_co_u32_e32 v33, vcc, 0, v9, vcc
	v_add_co_u32_e32 v34, vcc, 0x74000, v8
	s_nop 1
	v_addc_co_u32_e32 v35, vcc, 0, v9, vcc
	v_add_co_u32_e32 v36, vcc, 0x78000, v8
	s_nop 1
	v_addc_co_u32_e32 v37, vcc, 0, v9, vcc
	v_add_co_u32_e32 v8, vcc, 0x7c000, v8
	s_nop 1
	v_addc_co_u32_e32 v9, vcc, 0, v9, vcc
	flat_load_dword v38, v[24:25]
	flat_load_dword v39, v[26:27]
	flat_load_dword v63, v[28:29]
	flat_load_dword v64, v[30:31]
	flat_load_dword v65, v[32:33]
	flat_load_dword v66, v[34:35]
	flat_load_dword v67, v[36:37]
	flat_load_dword v68, v[8:9]
	s_waitcnt vmcnt(0) lgkmcnt(0)
; __device__ __forceinline__ unsigned cvt_pk_bf16(float lo, float hi) { unsigned r; asm volatile("v_cvt_pk_bf16_f32 %0, %1, %2" : "=v"(r) : "v"(lo), "v"(hi)); return r; }
; __device__ __forceinline__ void transpose_item(const float* __restrict__ W, int K, int N, int nblk, bf16_t* __restrict__ WT, int mode, float* scr, int item, int lane) {
;     ...
;     for (int i = 0; i < 32; ++i) { const int kk = 2 * i + (lane >> 5); scr[kk * 33 + (lane & 31)] = wv[i]; }
;     asm volatile("s_waitcnt lgkmcnt(0)" ::: "memory");
;     const int c = lane & 7;
; #pragma unroll
;     for (int j = 0; j < 4; ++j) { const int nn = (lane >> 3) + 8 * j; const float* s = scr + (8 * c) * 33 + nn;
;         u32x4 o; o.x = cvt_pk_bf16(s[0 * 33], s[1 * 33]); o.y = cvt_pk_bf16(s[2 * 33], s[3 * 33]); o.z = cvt_pk_bf16(s[4 * 33], s[5 * 33]); o.w = cvt_pk_bf16(s[6 * 33], s[7 * 33]);
;         *(u32x4*)(WT + (size_t)(n0 + nn) * K + k0 + 8 * c) = o; }
;     asm volatile("s_waitcnt lgkmcnt(0)" ::: "memory");
	ds_write2_b32 v11, v2, v40 offset1:66
	ds_write2_b32 v11, v41, v42 offset0:132 offset1:198
	ds_write2_b32 v17, v43, v44 offset0:8 offset1:74
	ds_write2_b32 v17, v45, v46 offset0:140 offset1:206
	ds_write2_b32 v18, v47, v48 offset0:16 offset1:82
	ds_write2_b32 v18, v49, v50 offset0:148 offset1:214
	ds_write2_b32 v19, v51, v52 offset0:24 offset1:90
	ds_write2_b32 v19, v53, v54 offset0:156 offset1:222
	ds_write2_b32 v20, v55, v56 offset0:32 offset1:98
	ds_write2_b32 v20, v57, v58 offset0:164 offset1:230
	ds_write2_b32 v21, v59, v60 offset0:40 offset1:106
	ds_write2_b32 v21, v61, v62 offset0:172 offset1:238
	ds_write2_b32 v22, v38, v39 offset0:48 offset1:114
	ds_write2_b32 v22, v63, v64 offset0:180 offset1:246
	ds_write2_b32 v23, v65, v66 offset0:56 offset1:122
	ds_write2_b32 v23, v67, v68 offset0:188 offset1:254
	s_waitcnt lgkmcnt(0)
	ds_read2_b32 v[8:9], v13 offset1:33
	s_waitcnt lgkmcnt(0)
	v_cvt_pk_bf16_f32 v24, v8, v9
	ds_read2_b32 v[8:9], v13 offset0:66 offset1:99
	s_waitcnt lgkmcnt(0)
	v_cvt_pk_bf16_f32 v25, v8, v9
	ds_read2_b32 v[8:9], v13 offset0:132 offset1:165
	v_or_b32_e32 v2, s14, v12
	s_waitcnt lgkmcnt(0)
	v_cvt_pk_bf16_f32 v26, v8, v9
	ds_read2_b32 v[8:9], v13 offset0:198 offset1:231
	v_lshl_add_u64 v[28:29], v[4:5], 0, s[12:13]
	v_lshlrev_b32_e32 v2, 12, v2
	s_waitcnt lgkmcnt(0)
	v_cvt_pk_bf16_f32 v27, v8, v9
	ds_read2_b32 v[8:9], v13 offset0:8 offset1:41
	v_lshl_add_u64 v[30:31], v[28:29], 0, v[2:3]
	global_store_dwordx4 v[30:31], v[24:27], off
	v_or_b32_e32 v2, s14, v14
	v_lshlrev_b32_e32 v2, 12, v2
	s_waitcnt lgkmcnt(0)
	v_cvt_pk_bf16_f32 v24, v8, v9
	ds_read2_b32 v[8:9], v13 offset0:74 offset1:107
	s_waitcnt lgkmcnt(0)
	v_cvt_pk_bf16_f32 v25, v8, v9
	ds_read2_b32 v[8:9], v13 offset0:140 offset1:173
	s_waitcnt lgkmcnt(0)
	v_cvt_pk_bf16_f32 v26, v8, v9
	ds_read2_b32 v[8:9], v13 offset0:206 offset1:239
	s_waitcnt lgkmcnt(0)
	v_cvt_pk_bf16_f32 v27, v8, v9
	ds_read2_b32 v[8:9], v13 offset0:16 offset1:49
	v_lshl_add_u64 v[30:31], v[28:29], 0, v[2:3]
	global_store_dwordx4 v[30:31], v[24:27], off
	v_or_b32_e32 v2, s14, v15
	v_lshlrev_b32_e32 v2, 12, v2
	s_waitcnt lgkmcnt(0)
	v_cvt_pk_bf16_f32 v24, v8, v9
	ds_read2_b32 v[8:9], v13 offset0:82 offset1:115
	s_waitcnt lgkmcnt(0)
	v_cvt_pk_bf16_f32 v25, v8, v9
	ds_read2_b32 v[8:9], v13 offset0:148 offset1:181
	s_waitcnt lgkmcnt(0)
	v_cvt_pk_bf16_f32 v26, v8, v9
	ds_read2_b32 v[8:9], v13 offset0:214 offset1:247
	s_waitcnt lgkmcnt(0)
	v_cvt_pk_bf16_f32 v27, v8, v9
	ds_read2_b32 v[8:9], v13 offset0:24 offset1:57
	v_lshl_add_u64 v[30:31], v[28:29], 0, v[2:3]
	global_store_dwordx4 v[30:31], v[24:27], off
	v_or_b32_e32 v2, s14, v16
	v_lshlrev_b32_e32 v2, 12, v2
	s_waitcnt lgkmcnt(0)
	v_cvt_pk_bf16_f32 v24, v8, v9
	ds_read2_b32 v[8:9], v13 offset0:90 offset1:123
	s_waitcnt lgkmcnt(0)
	v_cvt_pk_bf16_f32 v25, v8, v9
	ds_read2_b32 v[8:9], v13 offset0:156 offset1:189
	s_waitcnt lgkmcnt(0)
	v_cvt_pk_bf16_f32 v26, v8, v9
	ds_read2_b32 v[8:9], v13 offset0:222 offset1:255
	s_waitcnt lgkmcnt(0)
	v_cvt_pk_bf16_f32 v27, v8, v9
	v_lshl_add_u64 v[8:9], v[28:29], 0, v[2:3]
	global_store_dwordx4 v[8:9], v[24:27], off
	s_waitcnt lgkmcnt(0)
	s_cbranch_execnz .LBB0_1461

; __device__ __forceinline__ void zero_pad_rows(const Params& P) {
;     u32x4* p = (u32x4*)((bf16_t*)(P.ws + WS_PROJ) + (size_t)LTOK * PW); const int n = (MP - LTOK) * PW / 8;
;     for (int i = blockIdx.x * 512 + threadIdx.x; i < n; i += gridDim.x * 512) p[i] = (u32x4){0u, 0u, 0u, 0u};
.LBB0_1541:
	v_ashrrev_i32_e32 v9, 31, v8
	v_lshl_add_u64 v[10:11], v[8:9], 4, s[8:9]
	v_add_u32_e32 v8, s14, v8
	v_cmp_lt_i32_e32 vcc, s15, v8
	s_or_b64 s[12:13], vcc, s[12:13]
	global_store_dwordx4 v[10:11], v[2:5], off
	s_andn2_b64 exec, exec, s[12:13]
	s_cbranch_execnz .LBB0_1541

; __device__ __forceinline__ void zero_pad_rows(const Params& P) {
;     ...
;     u32x4* g = (u32x4*)((float*)(P.ws + WS_GATES) + (size_t)LTOK * 16); const int m = (MP - LTOK) * 16 / 4;
;     for (int i = blockIdx.x * 512 + threadIdx.x; i < m; i += gridDim.x * 512) g[i] = (u32x4){0u, 0u, 0u, 0u};
.LBB0_1544:
	v_ashrrev_i32_e32 v7, 31, v6
	v_lshl_add_u64 v[8:9], v[6:7], 4, s[8:9]
	v_add_u32_e32 v6, s3, v6
	v_cmp_lt_i32_e32 vcc, s12, v6
	s_or_b64 s[10:11], vcc, s[10:11]
	global_store_dwordx4 v[8:9], v[2:5], off
	s_andn2_b64 exec, exec, s[10:11]
	s_cbranch_execnz .LBB0_1544

; template <int KSPLIT, class Epi>
; __device__ __forceinline__ void skinny_gemm(const bf16_t* __restrict__ A, int lda, const bf16_t* __restrict__ Wt, int K, int ntiles, char* lds, const Epi& E) {
;     ...
;     for (int base = 0; base < total; base += (int)gridDim.x * 8) {
;         const int slot = base + (int)blockIdx.x * 8 + wid, tile = slot / KSPLIT, ks = slot % KSPLIT;
;         const bool act = slot < total;
;         f32x4 acc = {0.f, 0.f, 0.f, 0.f};
;         if (act) {
;             const bf16_t* ap = A + (size_t)i * lda + ks * klen + 8 * kq;
;             const bf16_t* wp = Wt + (size_t)(tile * 16 + i) * K + ks * klen + 8 * kq;
;             for (int k = 0; k < klen; k += 256) {
;                 bf16x8 a[8], w[8];
; #pragma unroll
;                 for (int j = 0; j < 8; ++j) { a[j] = *(const bf16x8*)(ap + k + 32 * j); w[j] = *(const bf16x8*)(wp + k + 32 * j); }
; #pragma unroll
;                 for (int j = 0; j < 8; ++j) acc = __builtin_amdgcn_mfma_f32_16x16x32_bf16(w[j], a[j], acc, 0, 0, 0);
;             }
;         }
.LBB0_1607:
	s_add_i32 s22, s12, s13
	s_lshr_b32 s6, s22, 31
	s_add_i32 s6, s22, s6
	s_ashr_i32 s20, s6, 1
	s_and_b32 s6, s6, -2
	s_sub_i32 s21, s22, s6
	v_mov_b32_e32 v4, v2
	v_mov_b32_e32 v5, v2
	v_mov_b32_e32 v3, v2
	s_cmpk_lt_i32 s22, 0x800
	v_mov_b64_e32 v[6:7], v[4:5]
	s_cselect_b64 s[6:7], -1, 0
	s_cmpk_gt_i32 s22, 0x7ff
	v_mov_b64_e32 v[4:5], v[2:3]
	s_cbranch_scc1 .LBB0_1609
	v_lshl_or_b32 v4, s20, 4, v1
	s_lshl_b32 s22, s21, 10
	v_ashrrev_i32_e32 v5, 31, v4
	s_ashr_i32 s23, s22, 31
	v_lshlrev_b64 v[4:5], 12, v[4:5]
	s_lshl_b64 s[22:23], s[22:23], 1
	v_lshl_add_u64 v[4:5], s[16:17], 0, v[4:5]
	v_lshl_add_u64 v[4:5], v[4:5], 0, s[22:23]
	v_mov_b32_e32 v13, v2
	v_lshl_add_u64 v[80:81], v[4:5], 0, v[12:13]
	global_load_dwordx4 v[4:7], v[80:81], off
	v_lshl_add_u64 v[82:83], v[8:9], 0, s[22:23]
	global_load_dwordx4 v[16:19], v[80:81], off offset:64
	global_load_dwordx4 v[20:23], v[82:83], off
	global_load_dwordx4 v[24:27], v[82:83], off offset:64
	global_load_dwordx4 v[28:31], v[80:81], off offset:128
	global_load_dwordx4 v[32:35], v[80:81], off offset:192
	global_load_dwordx4 v[36:39], v[82:83], off offset:128
	global_load_dwordx4 v[40:43], v[82:83], off offset:192
	global_load_dwordx4 v[44:47], v[80:81], off offset:256
	global_load_dwordx4 v[48:51], v[82:83], off offset:256
	global_load_dwordx4 v[52:55], v[80:81], off offset:320
	global_load_dwordx4 v[56:59], v[82:83], off offset:320
	global_load_dwordx4 v[60:63], v[80:81], off offset:384
	global_load_dwordx4 v[64:67], v[80:81], off offset:448
	global_load_dwordx4 v[68:71], v[82:83], off offset:384
	global_load_dwordx4 v[72:75], v[82:83], off offset:448
	s_waitcnt vmcnt(0) lgkmcnt(0)
	v_mfma_f32_16x16x32_bf16 v[4:7], v[4:7], v[20:23], 0
	global_load_dwordx4 v[20:23], v[80:81], off offset:512
	global_load_dwordx4 v[76:79], v[80:81], off offset:576
	v_mfma_f32_16x16x32_bf16 v[4:7], v[16:19], v[24:27], v[4:7]
	global_load_dwordx4 v[16:19], v[82:83], off offset:512
	global_load_dwordx4 v[24:27], v[82:83], off offset:576
	v_mfma_f32_16x16x32_bf16 v[4:7], v[28:31], v[36:39], v[4:7]
	global_load_dwordx4 v[28:31], v[80:81], off offset:640
	global_load_dwordx4 v[36:39], v[82:83], off offset:640
	v_mfma_f32_16x16x32_bf16 v[4:7], v[32:35], v[40:43], v[4:7]
	global_load_dwordx4 v[32:35], v[80:81], off offset:704
	global_load_dwordx4 v[40:43], v[82:83], off offset:704
	v_mfma_f32_16x16x32_bf16 v[4:7], v[44:47], v[48:51], v[4:7]
	global_load_dwordx4 v[44:47], v[80:81], off offset:768
	global_load_dwordx4 v[48:51], v[80:81], off offset:832
	v_mfma_f32_16x16x32_bf16 v[4:7], v[52:55], v[56:59], v[4:7]
	global_load_dwordx4 v[52:55], v[82:83], off offset:768
	global_load_dwordx4 v[56:59], v[82:83], off offset:832
	v_mfma_f32_16x16x32_bf16 v[4:7], v[60:63], v[68:71], v[4:7]
	v_mfma_f32_16x16x32_bf16 v[4:7], v[64:67], v[72:75], v[4:7]
	global_load_dwordx4 v[60:63], v[80:81], off offset:896
	global_load_dwordx4 v[64:67], v[80:81], off offset:960
	s_waitcnt vmcnt(0) lgkmcnt(0)
	v_mfma_f32_16x16x32_bf16 v[4:7], v[20:23], v[16:19], v[4:7]
	global_load_dwordx4 v[16:19], v[82:83], off offset:896
	global_load_dwordx4 v[20:23], v[82:83], off offset:960
	v_mfma_f32_16x16x32_bf16 v[4:7], v[76:79], v[24:27], v[4:7]
	global_load_dwordx4 v[24:27], v[80:81], off offset:1024
	global_load_dwordx4 v[68:71], v[82:83], off offset:1024
	v_mfma_f32_16x16x32_bf16 v[4:7], v[28:31], v[36:39], v[4:7]
	global_load_dwordx4 v[28:31], v[80:81], off offset:1088
	v_mfma_f32_16x16x32_bf16 v[4:7], v[32:35], v[40:43], v[4:7]
	global_load_dwordx4 v[32:35], v[82:83], off offset:1088
	global_load_dwordx4 v[36:39], v[80:81], off offset:1152
	global_load_dwordx4 v[40:43], v[80:81], off offset:1216
	v_mfma_f32_16x16x32_bf16 v[4:7], v[44:47], v[52:55], v[4:7]
	v_mfma_f32_16x16x32_bf16 v[4:7], v[48:51], v[56:59], v[4:7]
	global_load_dwordx4 v[44:47], v[82:83], off offset:1152
	global_load_dwordx4 v[48:51], v[82:83], off offset:1216
	s_waitcnt vmcnt(0) lgkmcnt(0)
	v_mfma_f32_16x16x32_bf16 v[4:7], v[60:63], v[16:19], v[4:7]
	global_load_dwordx4 v[16:19], v[80:81], off offset:1280
	global_load_dwordx4 v[52:55], v[80:81], off offset:1344
	v_mfma_f32_16x16x32_bf16 v[4:7], v[64:67], v[20:23], v[4:7]
	global_load_dwordx4 v[20:23], v[82:83], off offset:1280
	global_load_dwordx4 v[56:59], v[82:83], off offset:1344
	v_mfma_f32_16x16x32_bf16 v[4:7], v[24:27], v[68:71], v[4:7]
	global_load_dwordx4 v[24:27], v[80:81], off offset:1408
	v_mfma_f32_16x16x32_bf16 v[4:7], v[28:31], v[32:35], v[4:7]
	global_load_dwordx4 v[28:31], v[82:83], off offset:1408
	v_mfma_f32_16x16x32_bf16 v[4:7], v[36:39], v[44:47], v[4:7]
	global_load_dwordx4 v[32:35], v[80:81], off offset:1472
	global_load_dwordx4 v[36:39], v[82:83], off offset:1472
	v_mfma_f32_16x16x32_bf16 v[4:7], v[40:43], v[48:51], v[4:7]
	global_load_dwordx4 v[40:43], v[80:81], off offset:1536
	global_load_dwordx4 v[44:47], v[80:81], off offset:1600
	s_waitcnt vmcnt(0) lgkmcnt(0)
	v_mfma_f32_16x16x32_bf16 v[4:7], v[16:19], v[20:23], v[4:7]
	global_load_dwordx4 v[16:19], v[82:83], off offset:1536
	global_load_dwordx4 v[20:23], v[82:83], off offset:1600
	global_load_dwordx4 v[48:51], v[80:81], off offset:1664
	v_mfma_f32_16x16x32_bf16 v[4:7], v[52:55], v[56:59], v[4:7]
	v_mfma_f32_16x16x32_bf16 v[4:7], v[24:27], v[28:31], v[4:7]
	global_load_dwordx4 v[24:27], v[82:83], off offset:1664
	v_mfma_f32_16x16x32_bf16 v[4:7], v[32:35], v[36:39], v[4:7]
	global_load_dwordx4 v[28:31], v[80:81], off offset:1728
	global_load_dwordx4 v[32:35], v[82:83], off offset:1728
	s_waitcnt vmcnt(0) lgkmcnt(0)
	v_mfma_f32_16x16x32_bf16 v[4:7], v[40:43], v[16:19], v[4:7]
	global_load_dwordx4 v[16:19], v[80:81], off offset:1792
	global_load_dwordx4 v[36:39], v[82:83], off offset:1792
	v_mfma_f32_16x16x32_bf16 v[4:7], v[44:47], v[20:23], v[4:7]
	global_load_dwordx4 v[20:23], v[80:81], off offset:1856
	v_mfma_f32_16x16x32_bf16 v[4:7], v[48:51], v[24:27], v[4:7]
	global_load_dwordx4 v[24:27], v[82:83], off offset:1856
	v_mfma_f32_16x16x32_bf16 v[4:7], v[28:31], v[32:35], v[4:7]
	global_load_dwordx4 v[28:31], v[80:81], off offset:1920
	global_load_dwordx4 v[32:35], v[82:83], off offset:1920
	s_waitcnt vmcnt(0) lgkmcnt(0)
	v_mfma_f32_16x16x32_bf16 v[4:7], v[16:19], v[36:39], v[4:7]
	global_load_dwordx4 v[16:19], v[80:81], off offset:1984
	v_mfma_f32_16x16x32_bf16 v[4:7], v[20:23], v[24:27], v[4:7]
	global_load_dwordx4 v[20:23], v[82:83], off offset:1984
	v_mfma_f32_16x16x32_bf16 v[4:7], v[28:31], v[32:35], v[4:7]
	s_waitcnt vmcnt(0) lgkmcnt(0)
	v_mfma_f32_16x16x32_bf16 v[4:7], v[16:19], v[20:23], v[4:7]

; template <int KSPLIT, class Epi>
; __device__ __forceinline__ void skinny_gemm(const bf16_t* __restrict__ A, int lda, const bf16_t* __restrict__ Wt, int K, int ntiles, char* lds, const Epi& E) {
;     ...
;     for (int base = 0; base < total; base += (int)gridDim.x * 8) {
;         const int slot = base + (int)blockIdx.x * 8 + wid, tile = slot / KSPLIT, ks = slot % KSPLIT;
;         const bool act = slot < total;
;         f32x4 acc = {0.f, 0.f, 0.f, 0.f};
;         if (act) {
;             const bf16_t* ap = A + (size_t)i * lda + ks * klen + 8 * kq;
;             const bf16_t* wp = Wt + (size_t)(tile * 16 + i) * K + ks * klen + 8 * kq;
;             for (int k = 0; k < klen; k += 256) {
;                 bf16x8 a[8], w[8];
; #pragma unroll
;                 for (int j = 0; j < 8; ++j) { a[j] = *(const bf16x8*)(ap + k + 32 * j); w[j] = *(const bf16x8*)(wp + k + 32 * j); }
; #pragma unroll
;                 for (int j = 0; j < 8; ++j) acc = __builtin_amdgcn_mfma_f32_16x16x32_bf16(w[j], a[j], acc, 0, 0, 0);
;             }
;         }
.LBB0_1617:
	s_add_i32 s22, s10, s11
	s_ashr_i32 s6, s22, 31
	s_lshr_b32 s6, s6, 29
	s_add_i32 s6, s22, s6
	s_ashr_i32 s20, s6, 3
	s_and_b32 s6, s6, -8
	s_sub_i32 s21, s22, s6
	v_mov_b32_e32 v4, v2
	v_mov_b32_e32 v5, v2
	v_mov_b32_e32 v3, v2
	s_cmp_lt_i32 s22, 8
	v_mov_b64_e32 v[6:7], v[4:5]
	s_cselect_b64 s[6:7], -1, 0
	s_cmp_gt_i32 s22, 7
	v_mov_b64_e32 v[4:5], v[2:3]
	s_cbranch_scc1 .LBB0_1619
	v_lshl_or_b32 v4, s20, 4, v1
	s_lshl_b32 s22, s21, 8
	v_ashrrev_i32_e32 v5, 31, v4
	s_ashr_i32 s23, s22, 31
	v_lshlrev_b64 v[4:5], 12, v[4:5]
	s_lshl_b64 s[22:23], s[22:23], 1
	v_lshl_add_u64 v[4:5], s[12:13], 0, v[4:5]
	v_lshl_add_u64 v[4:5], v[4:5], 0, s[22:23]
	v_mov_b32_e32 v13, v2
	v_lshl_add_u64 v[50:51], v[4:5], 0, v[12:13]
	global_load_dwordx4 v[4:7], v[50:51], off
	v_lshl_add_u64 v[52:53], v[8:9], 0, s[22:23]
	global_load_dwordx4 v[18:21], v[50:51], off offset:64
	global_load_dwordx4 v[22:25], v[52:53], off
	global_load_dwordx4 v[26:29], v[52:53], off offset:64
	global_load_dwordx4 v[30:33], v[50:51], off offset:128
	global_load_dwordx4 v[34:37], v[52:53], off offset:128
	global_load_dwordx4 v[38:41], v[50:51], off offset:192
	global_load_dwordx4 v[42:45], v[52:53], off offset:192
	s_waitcnt vmcnt(0) lgkmcnt(0)
	v_mfma_f32_16x16x32_bf16 v[4:7], v[4:7], v[22:25], 0
	global_load_dwordx4 v[22:25], v[50:51], off offset:256
	global_load_dwordx4 v[46:49], v[52:53], off offset:256
	v_mfma_f32_16x16x32_bf16 v[4:7], v[18:21], v[26:29], v[4:7]
	global_load_dwordx4 v[18:21], v[50:51], off offset:320
	global_load_dwordx4 v[26:29], v[52:53], off offset:320
	v_mfma_f32_16x16x32_bf16 v[4:7], v[30:33], v[34:37], v[4:7]
	global_load_dwordx4 v[30:33], v[50:51], off offset:384
	global_load_dwordx4 v[34:37], v[52:53], off offset:384
	v_mfma_f32_16x16x32_bf16 v[4:7], v[38:41], v[42:45], v[4:7]
	s_waitcnt vmcnt(0) lgkmcnt(0)
	v_mfma_f32_16x16x32_bf16 v[4:7], v[22:25], v[46:49], v[4:7]
	global_load_dwordx4 v[22:25], v[50:51], off offset:448
	v_mfma_f32_16x16x32_bf16 v[4:7], v[18:21], v[26:29], v[4:7]
	global_load_dwordx4 v[18:21], v[52:53], off offset:448
	v_mfma_f32_16x16x32_bf16 v[4:7], v[30:33], v[34:37], v[4:7]
	s_waitcnt vmcnt(0) lgkmcnt(0)
	v_mfma_f32_16x16x32_bf16 v[4:7], v[22:25], v[18:21], v[4:7]

; template <int KSPLIT, class Epi>
; __device__ __forceinline__ void skinny_gemm(const bf16_t* __restrict__ A, int lda, const bf16_t* __restrict__ Wt, int K, int ntiles, char* lds, const Epi& E) {
;     ...
;     for (int base = 0; base < total; base += (int)gridDim.x * 8) {
;         const int slot = base + (int)blockIdx.x * 8 + wid, tile = slot / KSPLIT, ks = slot % KSPLIT;
;         const bool act = slot < total;
;         f32x4 acc = {0.f, 0.f, 0.f, 0.f};
;         if (act) {
;             const bf16_t* ap = A + (size_t)i * lda + ks * klen + 8 * kq;
;             const bf16_t* wp = Wt + (size_t)(tile * 16 + i) * K + ks * klen + 8 * kq;
;             for (int k = 0; k < klen; k += 256) {
;                 bf16x8 a[8], w[8];
; #pragma unroll
;                 for (int j = 0; j < 8; ++j) { a[j] = *(const bf16x8*)(ap + k + 32 * j); w[j] = *(const bf16x8*)(wp + k + 32 * j); }
; #pragma unroll
;                 for (int j = 0; j < 8; ++j) acc = __builtin_amdgcn_mfma_f32_16x16x32_bf16(w[j], a[j], acc, 0, 0, 0);
;             }
;         }
.LBB0_1627:
	s_add_i32 s21, s16, s17
	s_ashr_i32 s6, s21, 31
	s_lshr_b32 s6, s6, 30
	s_add_i32 s6, s21, s6
	s_ashr_i32 s19, s6, 2
	s_and_b32 s6, s6, -4
	s_sub_i32 s20, s21, s6
	v_mov_b32_e32 v4, v2
	v_mov_b32_e32 v5, v2
	v_mov_b32_e32 v3, v2
	s_cmpk_lt_i32 s21, 0x600
	v_mov_b64_e32 v[6:7], v[4:5]
	s_cselect_b64 s[6:7], -1, 0
	s_cmpk_gt_i32 s21, 0x5ff
	v_mov_b64_e32 v[4:5], v[2:3]
	s_cbranch_scc1 .LBB0_1629
	v_lshl_or_b32 v4, s19, 4, v1
	s_lshl_b32 s22, s20, 9
	v_ashrrev_i32_e32 v5, 31, v4
	s_ashr_i32 s23, s22, 31
	v_lshlrev_b64 v[4:5], 12, v[4:5]
	s_lshl_b64 s[22:23], s[22:23], 1
	v_lshl_add_u64 v[4:5], s[10:11], 0, v[4:5]
	v_lshl_add_u64 v[4:5], v[4:5], 0, s[22:23]
	v_mov_b32_e32 v13, v2
	v_lshl_add_u64 v[60:61], v[4:5], 0, v[12:13]
	global_load_dwordx4 v[4:7], v[60:61], off
	v_lshl_add_u64 v[62:63], v[8:9], 0, s[22:23]
	global_load_dwordx4 v[16:19], v[60:61], off offset:64
	global_load_dwordx4 v[20:23], v[62:63], off
	global_load_dwordx4 v[24:27], v[62:63], off offset:64
	global_load_dwordx4 v[28:31], v[60:61], off offset:128
	global_load_dwordx4 v[32:35], v[60:61], off offset:192
	global_load_dwordx4 v[36:39], v[62:63], off offset:128
	global_load_dwordx4 v[40:43], v[62:63], off offset:192
	global_load_dwordx4 v[44:47], v[60:61], off offset:256
	global_load_dwordx4 v[48:51], v[60:61], off offset:320
	global_load_dwordx4 v[52:55], v[62:63], off offset:256
	global_load_dwordx4 v[56:59], v[62:63], off offset:320
	s_waitcnt vmcnt(0) lgkmcnt(0)
	v_mfma_f32_16x16x32_bf16 v[4:7], v[4:7], v[20:23], 0
	global_load_dwordx4 v[20:23], v[60:61], off offset:384
	v_mfma_f32_16x16x32_bf16 v[4:7], v[16:19], v[24:27], v[4:7]
	global_load_dwordx4 v[16:19], v[62:63], off offset:384
	v_mfma_f32_16x16x32_bf16 v[4:7], v[28:31], v[36:39], v[4:7]
	global_load_dwordx4 v[24:27], v[60:61], off offset:448
	global_load_dwordx4 v[28:31], v[62:63], off offset:448
	v_mfma_f32_16x16x32_bf16 v[4:7], v[32:35], v[40:43], v[4:7]
	global_load_dwordx4 v[32:35], v[60:61], off offset:512
	global_load_dwordx4 v[36:39], v[60:61], off offset:576
	v_mfma_f32_16x16x32_bf16 v[4:7], v[44:47], v[52:55], v[4:7]
	global_load_dwordx4 v[40:43], v[62:63], off offset:512
	global_load_dwordx4 v[44:47], v[62:63], off offset:576
	v_mfma_f32_16x16x32_bf16 v[4:7], v[48:51], v[56:59], v[4:7]
	global_load_dwordx4 v[48:51], v[60:61], off offset:640
	s_waitcnt vmcnt(0) lgkmcnt(0)
	v_mfma_f32_16x16x32_bf16 v[4:7], v[20:23], v[16:19], v[4:7]
	global_load_dwordx4 v[16:19], v[62:63], off offset:640
	v_mfma_f32_16x16x32_bf16 v[4:7], v[24:27], v[28:31], v[4:7]
	global_load_dwordx4 v[20:23], v[60:61], off offset:704
	global_load_dwordx4 v[24:27], v[62:63], off offset:704
	v_mfma_f32_16x16x32_bf16 v[4:7], v[32:35], v[40:43], v[4:7]
	global_load_dwordx4 v[28:31], v[60:61], off offset:768
	global_load_dwordx4 v[32:35], v[62:63], off offset:768
	v_mfma_f32_16x16x32_bf16 v[4:7], v[36:39], v[44:47], v[4:7]
	global_load_dwordx4 v[36:39], v[60:61], off offset:832
	s_waitcnt vmcnt(0) lgkmcnt(0)
	v_mfma_f32_16x16x32_bf16 v[4:7], v[48:51], v[16:19], v[4:7]
	global_load_dwordx4 v[16:19], v[62:63], off offset:832
	v_mfma_f32_16x16x32_bf16 v[4:7], v[20:23], v[24:27], v[4:7]
	global_load_dwordx4 v[20:23], v[60:61], off offset:896
	global_load_dwordx4 v[24:27], v[62:63], off offset:896
	v_mfma_f32_16x16x32_bf16 v[4:7], v[28:31], v[32:35], v[4:7]
	global_load_dwordx4 v[28:31], v[60:61], off offset:960
	s_waitcnt vmcnt(0) lgkmcnt(0)
	v_mfma_f32_16x16x32_bf16 v[4:7], v[36:39], v[16:19], v[4:7]
	global_load_dwordx4 v[16:19], v[62:63], off offset:960
	v_mfma_f32_16x16x32_bf16 v[4:7], v[20:23], v[24:27], v[4:7]
	s_waitcnt vmcnt(0) lgkmcnt(0)
	v_mfma_f32_16x16x32_bf16 v[4:7], v[28:31], v[16:19], v[4:7]

; template <int KSPLIT, class Epi>
; __device__ __forceinline__ void skinny_gemm(const bf16_t* __restrict__ A, int lda, const bf16_t* __restrict__ Wt, int K, int ntiles, char* lds, const Epi& E) {
;     ...
;             __syncthreads();
;         }
;         if (act && ks == 0) E(tile, i, kq, acc);
;     }
; }
.LBB0_1633:
	s_and_b64 vcc, exec, s[6:7]
	s_barrier
	s_cbranch_vccnz .LBB0_1626
	s_lshl_b32 s6, s19, 4
	s_ashr_i32 s7, s6, 31
	v_cvt_pk_bf16_f32 v4, v4, v5
	v_cvt_pk_bf16_f32 v5, v6, v7
	v_lshl_add_u64 v[6:7], s[6:7], 1, v[10:11]
	global_store_dwordx2 v[6:7], v[4:5], off
	s_branch .LBB0_1626

; __device__ __forceinline__ void transpose_item(const float* __restrict__ W, int K, int N, int nblk, bf16_t* __restrict__ WT, int mode, float* scr, int item, int lane) {
;     const int kb = item / nblk, nb = item % nblk, k0 = 64 * kb, n0 = 32 * nb;
;     const int n = n0 + (lane & 31); int src = n;
;     if (mode) src = n < 2048 ? n : (n < 6144 ? n + 8 : (n < 6152 ? n - 6144 + 2048 : (n < 6160 ? n : -1)));
;     float wv[32];
; #pragma unroll
;     for (int i = 0; i < 32; ++i) { const int kk = 2 * i + (lane >> 5); wv[i] = src >= 0 ? W[(size_t)(k0 + kk) * N + src] : 0.f; }
; #pragma unroll
;     for (int i = 0; i < 32; ++i) { const int kk = 2 * i + (lane >> 5); scr[kk * 33 + (lane & 31)] = wv[i]; }
; __device__ __forceinline__ void convert_weights(const Params& P, int l, int part, char* lds, int gw, int NGW, int wid, int lane) {
;     ...
;     for (int it = lo + gw; it < hi; it += NGW) {
;         int r = it;
;         if (r < I_IN) { transpose_item(w_in, DM, NIN_SRC, NIN / 32, WinT, 1, scr, r, lane); continue; } r -= I_IN;
;         if (r < I_OUT) { transpose_item(w_out, DM, DM, DM / 32, WoutT, 0, scr, r, lane); continue; } r -= I_OUT;
;         if (r < I_UP) { transpose_item(w_up, DM, DFF, DFF / 32, WupT, 0, scr, r, lane); continue; } r -= I_UP;
;         transpose_item(w_down, DFF, DM, DM / 32, WdownT, 0, scr, r, lane);
.LBB0_1873:
	s_cmpk_gt_i32 s3, 0x18ff
	s_mov_b64 s[16:17], -1
	s_cbranch_scc0 .LBB0_1883
	s_cmpk_gt_u32 s3, 0x20ff
	s_cbranch_scc0 .LBB0_1880
	s_cmpk_gt_u32 s3, 0x40ff
	s_cbranch_scc0 .LBB0_1877
	s_and_b32 s14, s3, 0x7fffffc0
	s_and_b32 s16, s23, 0x7e0
	s_addk_i32 s14, 0xbf00
	v_or_b32_e32 v2, s16, v14
	v_or_b32_e32 v12, s14, v15
	v_lshlrev_b32_e32 v2, 2, v2
	v_lshl_add_u64 v[28:29], s[12:13], 0, v[2:3]
	v_or_b32_e32 v2, 2, v12
	v_lshlrev_b64 v[32:33], 13, v[2:3]
	v_or_b32_e32 v2, 4, v12
	v_lshlrev_b64 v[34:35], 13, v[2:3]
	v_or_b32_e32 v2, 6, v12
	v_lshlrev_b64 v[36:37], 13, v[2:3]
	v_or_b32_e32 v2, 8, v12
	v_lshlrev_b64 v[38:39], 13, v[2:3]
	v_or_b32_e32 v2, 10, v12
	v_mov_b32_e32 v13, v3
	v_lshlrev_b64 v[40:41], 13, v[2:3]
	v_or_b32_e32 v2, 12, v12
	v_lshlrev_b64 v[30:31], 13, v[12:13]
	v_lshlrev_b64 v[42:43], 13, v[2:3]
	v_or_b32_e32 v2, 14, v12
	v_lshl_add_u64 v[30:31], v[28:29], 0, v[30:31]
	v_lshlrev_b64 v[44:45], 13, v[2:3]
	v_or_b32_e32 v2, 16, v12
	v_lshl_add_u64 v[32:33], v[28:29], 0, v[32:33]
	v_lshl_add_u64 v[34:35], v[28:29], 0, v[34:35]
	v_lshl_add_u64 v[36:37], v[28:29], 0, v[36:37]
	v_lshl_add_u64 v[38:39], v[28:29], 0, v[38:39]
	v_lshl_add_u64 v[40:41], v[28:29], 0, v[40:41]
	v_lshl_add_u64 v[42:43], v[28:29], 0, v[42:43]
	v_lshl_add_u64 v[44:45], v[28:29], 0, v[44:45]
	flat_load_dword v46, v[30:31]
	flat_load_dword v47, v[32:33]
	flat_load_dword v48, v[34:35]
	flat_load_dword v49, v[36:37]
	flat_load_dword v50, v[38:39]
	flat_load_dword v51, v[40:41]
	flat_load_dword v52, v[42:43]
	flat_load_dword v53, v[44:45]
	v_lshlrev_b64 v[30:31], 13, v[2:3]
	v_or_b32_e32 v2, 18, v12
	v_lshlrev_b64 v[32:33], 13, v[2:3]
	v_or_b32_e32 v2, 20, v12
	v_lshlrev_b64 v[34:35], 13, v[2:3]
	v_or_b32_e32 v2, 22, v12
	v_lshlrev_b64 v[36:37], 13, v[2:3]
	v_or_b32_e32 v2, 24, v12
	v_lshlrev_b64 v[38:39], 13, v[2:3]
	v_or_b32_e32 v2, 26, v12
	v_lshlrev_b64 v[40:41], 13, v[2:3]
	v_or_b32_e32 v2, 28, v12
	v_lshlrev_b64 v[42:43], 13, v[2:3]
	v_or_b32_e32 v2, 30, v12
	v_lshl_add_u64 v[30:31], v[28:29], 0, v[30:31]
	v_lshlrev_b64 v[44:45], 13, v[2:3]
	v_or_b32_e32 v2, 32, v12
	v_lshl_add_u64 v[32:33], v[28:29], 0, v[32:33]
	v_lshl_add_u64 v[34:35], v[28:29], 0, v[34:35]
	v_lshl_add_u64 v[36:37], v[28:29], 0, v[36:37]
	v_lshl_add_u64 v[38:39], v[28:29], 0, v[38:39]
	v_lshl_add_u64 v[40:41], v[28:29], 0, v[40:41]
	v_lshl_add_u64 v[42:43], v[28:29], 0, v[42:43]
	v_lshl_add_u64 v[44:45], v[28:29], 0, v[44:45]
	flat_load_dword v54, v[30:31]
	flat_load_dword v55, v[32:33]
	flat_load_dword v56, v[34:35]
	flat_load_dword v57, v[36:37]
	flat_load_dword v58, v[38:39]
	flat_load_dword v59, v[40:41]
	flat_load_dword v60, v[42:43]
	flat_load_dword v61, v[44:45]
	v_lshlrev_b64 v[30:31], 13, v[2:3]
	v_or_b32_e32 v2, 34, v12
	v_lshlrev_b64 v[32:33], 13, v[2:3]
	v_or_b32_e32 v2, 36, v12
	v_lshlrev_b64 v[34:35], 13, v[2:3]
	v_or_b32_e32 v2, 38, v12
	v_lshlrev_b64 v[36:37], 13, v[2:3]
	v_or_b32_e32 v2, 40, v12
	v_lshlrev_b64 v[38:39], 13, v[2:3]
	v_or_b32_e32 v2, 42, v12
	v_lshlrev_b64 v[40:41], 13, v[2:3]
	v_or_b32_e32 v2, 44, v12
	v_lshlrev_b64 v[42:43], 13, v[2:3]
	v_or_b32_e32 v2, 46, v12
	v_lshl_add_u64 v[30:31], v[28:29], 0, v[30:31]
	v_lshlrev_b64 v[44:45], 13, v[2:3]
	v_or_b32_e32 v2, 48, v12
	v_lshl_add_u64 v[32:33], v[28:29], 0, v[32:33]
	v_lshl_add_u64 v[34:35], v[28:29], 0, v[34:35]
	v_lshl_add_u64 v[36:37], v[28:29], 0, v[36:37]
	v_lshl_add_u64 v[38:39], v[28:29], 0, v[38:39]
	v_lshl_add_u64 v[40:41], v[28:29], 0, v[40:41]
	v_lshl_add_u64 v[42:43], v[28:29], 0, v[42:43]
	v_lshl_add_u64 v[44:45], v[28:29], 0, v[44:45]
	flat_load_dword v62, v[30:31]
	flat_load_dword v63, v[32:33]
	flat_load_dword v64, v[34:35]
	flat_load_dword v65, v[36:37]
	flat_load_dword v66, v[38:39]
	flat_load_dword v67, v[40:41]
	flat_load_dword v68, v[42:43]
	flat_load_dword v69, v[44:45]
	v_lshlrev_b64 v[30:31], 13, v[2:3]
	v_or_b32_e32 v2, 50, v12
	v_lshlrev_b64 v[32:33], 13, v[2:3]
	v_or_b32_e32 v2, 52, v12
	v_lshlrev_b64 v[34:35], 13, v[2:3]
	v_or_b32_e32 v2, 54, v12
	v_lshlrev_b64 v[36:37], 13, v[2:3]
	v_or_b32_e32 v2, 56, v12
	v_lshlrev_b64 v[38:39], 13, v[2:3]
	v_or_b32_e32 v2, 58, v12
	v_lshlrev_b64 v[40:41], 13, v[2:3]
	v_or_b32_e32 v2, 60, v12
	v_lshlrev_b64 v[42:43], 13, v[2:3]
	v_or_b32_e32 v2, 62, v12
	v_lshl_add_u64 v[30:31], v[28:29], 0, v[30:31]
	v_lshlrev_b64 v[12:13], 13, v[2:3]
	v_lshl_add_u64 v[32:33], v[28:29], 0, v[32:33]
	v_lshl_add_u64 v[34:35], v[28:29], 0, v[34:35]
	v_lshl_add_u64 v[36:37], v[28:29], 0, v[36:37]
	v_lshl_add_u64 v[38:39], v[28:29], 0, v[38:39]
	v_lshl_add_u64 v[40:41], v[28:29], 0, v[40:41]
	v_lshl_add_u64 v[42:43], v[28:29], 0, v[42:43]
	v_lshl_add_u64 v[12:13], v[28:29], 0, v[12:13]
	flat_load_dword v2, v[30:31]
	flat_load_dword v28, v[32:33]
	flat_load_dword v29, v[34:35]
	flat_load_dword v44, v[36:37]
	flat_load_dword v45, v[38:39]
	flat_load_dword v70, v[40:41]
	flat_load_dword v71, v[42:43]
	flat_load_dword v72, v[12:13]
	v_lshl_add_u64 v[32:33], s[14:15], 1, v[4:5]
	s_waitcnt vmcnt(0) lgkmcnt(0)
	ds_write2_b32 v16, v46, v47 offset1:66
	ds_write2_b32 v16, v48, v49 offset0:132 offset1:198
	ds_write2_b32 v21, v50, v51 offset0:8 offset1:74
	ds_write2_b32 v21, v52, v53 offset0:140 offset1:206
	ds_write2_b32 v22, v54, v55 offset0:16 offset1:82
	ds_write2_b32 v22, v56, v57 offset0:148 offset1:214
	ds_write2_b32 v23, v58, v59 offset0:24 offset1:90
	ds_write2_b32 v23, v60, v61 offset0:156 offset1:222
	ds_write2_b32 v24, v62, v63 offset0:32 offset1:98
	ds_write2_b32 v24, v64, v65 offset0:164 offset1:230
	ds_write2_b32 v25, v66, v67 offset0:40 offset1:106
	ds_write2_b32 v25, v68, v69 offset0:172 offset1:238
	ds_write2_b32 v26, v2, v28 offset0:48 offset1:114
	ds_write2_b32 v26, v29, v44 offset0:180 offset1:246
	ds_write2_b32 v27, v45, v70 offset0:56 offset1:122
	ds_write2_b32 v27, v71, v72 offset0:188 offset1:254
	s_waitcnt lgkmcnt(0)
; __device__ __forceinline__ unsigned cvt_pk_bf16(float lo, float hi) { unsigned r; asm volatile("v_cvt_pk_bf16_f32 %0, %1, %2" : "=v"(r) : "v"(lo), "v"(hi)); return r; }
; __device__ __forceinline__ void transpose_item(const float* __restrict__ W, int K, int N, int nblk, bf16_t* __restrict__ WT, int mode, float* scr, int item, int lane) {
;     const int kb = item / nblk, nb = item % nblk, k0 = 64 * kb, n0 = 32 * nb;
;     const int n = n0 + (lane & 31); int src = n;
;     if (mode) src = n < 2048 ? n : (n < 6144 ? n + 8 : (n < 6152 ? n - 6144 + 2048 : (n < 6160 ? n : -1)));
;     float wv[32];
; #pragma unroll
;     for (int i = 0; i < 32; ++i) { const int kk = 2 * i + (lane >> 5); wv[i] = src >= 0 ? W[(size_t)(k0 + kk) * N + src] : 0.f; }
; #pragma unroll
;     for (int i = 0; i < 32; ++i) { const int kk = 2 * i + (lane >> 5); scr[kk * 33 + (lane & 31)] = wv[i]; }
;     asm volatile("s_waitcnt lgkmcnt(0)" ::: "memory");
;     const int c = lane & 7;
; #pragma unroll
;     for (int j = 0; j < 4; ++j) { const int nn = (lane >> 3) + 8 * j; const float* s = scr + (8 * c) * 33 + nn;
;         u32x4 o; o.x = cvt_pk_bf16(s[0 * 33], s[1 * 33]); o.y = cvt_pk_bf16(s[2 * 33], s[3 * 33]); o.z = cvt_pk_bf16(s[4 * 33], s[5 * 33]); o.w = cvt_pk_bf16(s[6 * 33], s[7 * 33]);
;         *(u32x4*)(WT + (size_t)(n0 + nn) * K + k0 + 8 * c) = o; }
;     asm volatile("s_waitcnt lgkmcnt(0)" ::: "memory");
; __device__ __forceinline__ void convert_weights(const Params& P, int l, int part, char* lds, int gw, int NGW, int wid, int lane) {
;     ...
;         if (r < I_UP) { transpose_item(w_up, DM, DFF, DFF / 32, WupT, 0, scr, r, lane); continue; } r -= I_UP;
	ds_read2_b32 v[12:13], v17 offset1:33
	s_waitcnt lgkmcnt(0)
	v_cvt_pk_bf16_f32 v28, v12, v13
	ds_read2_b32 v[12:13], v17 offset0:66 offset1:99
	s_waitcnt lgkmcnt(0)
	v_cvt_pk_bf16_f32 v29, v12, v13
	ds_read2_b32 v[12:13], v17 offset0:132 offset1:165
	v_or_b32_e32 v2, s16, v78
	s_waitcnt lgkmcnt(0)
	v_cvt_pk_bf16_f32 v30, v12, v13
	ds_read2_b32 v[12:13], v17 offset0:198 offset1:231
	v_lshlrev_b32_e32 v2, 14, v2
	s_waitcnt lgkmcnt(0)
	v_cvt_pk_bf16_f32 v31, v12, v13
	ds_read2_b32 v[12:13], v17 offset0:8 offset1:41
	v_lshl_add_u64 v[34:35], v[32:33], 0, v[2:3]
	global_store_dwordx4 v[34:35], v[28:31], off
	v_or_b32_e32 v2, s16, v18
	v_lshlrev_b32_e32 v2, 14, v2
	s_waitcnt lgkmcnt(0)
	v_cvt_pk_bf16_f32 v28, v12, v13
	ds_read2_b32 v[12:13], v17 offset0:74 offset1:107
	s_waitcnt lgkmcnt(0)
	v_cvt_pk_bf16_f32 v29, v12, v13
	ds_read2_b32 v[12:13], v17 offset0:140 offset1:173
	s_waitcnt lgkmcnt(0)
	v_cvt_pk_bf16_f32 v30, v12, v13
	ds_read2_b32 v[12:13], v17 offset0:206 offset1:239
	s_waitcnt lgkmcnt(0)
	v_cvt_pk_bf16_f32 v31, v12, v13
	ds_read2_b32 v[12:13], v17 offset0:16 offset1:49
	v_lshl_add_u64 v[34:35], v[32:33], 0, v[2:3]
	global_store_dwordx4 v[34:35], v[28:31], off
	v_or_b32_e32 v2, s16, v19
	v_lshlrev_b32_e32 v2, 14, v2
	s_waitcnt lgkmcnt(0)
	v_cvt_pk_bf16_f32 v28, v12, v13
	ds_read2_b32 v[12:13], v17 offset0:82 offset1:115
	s_waitcnt lgkmcnt(0)
	v_cvt_pk_bf16_f32 v29, v12, v13
	ds_read2_b32 v[12:13], v17 offset0:148 offset1:181
	s_waitcnt lgkmcnt(0)
	v_cvt_pk_bf16_f32 v30, v12, v13
	ds_read2_b32 v[12:13], v17 offset0:214 offset1:247
	s_waitcnt lgkmcnt(0)
	v_cvt_pk_bf16_f32 v31, v12, v13
	ds_read2_b32 v[12:13], v17 offset0:24 offset1:57
	v_lshl_add_u64 v[34:35], v[32:33], 0, v[2:3]
	global_store_dwordx4 v[34:35], v[28:31], off
	v_or_b32_e32 v2, s16, v20
	v_lshlrev_b32_e32 v2, 14, v2
	s_waitcnt lgkmcnt(0)
	v_cvt_pk_bf16_f32 v28, v12, v13
	ds_read2_b32 v[12:13], v17 offset0:90 offset1:123
	s_waitcnt lgkmcnt(0)
	v_cvt_pk_bf16_f32 v29, v12, v13
	ds_read2_b32 v[12:13], v17 offset0:156 offset1:189
	s_waitcnt lgkmcnt(0)
	v_cvt_pk_bf16_f32 v30, v12, v13
	ds_read2_b32 v[12:13], v17 offset0:222 offset1:255
	s_waitcnt lgkmcnt(0)
	v_cvt_pk_bf16_f32 v31, v12, v13
	v_lshl_add_u64 v[12:13], v[32:33], 0, v[2:3]
	global_store_dwordx4 v[12:13], v[28:31], off
	s_waitcnt lgkmcnt(0)
	s_mov_b64 s[16:17], 0
.LBB0_1877:
	s_andn2_b64 vcc, exec, s[16:17]
	s_cbranch_vccnz .LBB0_1879
	s_add_i32 s14, s3, 0xdf00
	s_and_b32 s16, s23, 0x1fe0
	s_bfe_u32 s14, s14, 0x80008
	v_or_b32_e32 v2, s16, v14
	v_lshl_or_b32 v28, s14, 6, v15
	v_lshlrev_b32_e32 v2, 2, v2
	v_lshl_add_u64 v[12:13], s[10:11], 0, v[2:3]
	v_lshlrev_b32_e32 v2, 15, v28
	v_lshl_add_u64 v[12:13], v[12:13], 0, v[2:3]
	v_add_co_u32_e32 v28, vcc, 0x10000, v12
	s_lshl_b32 s14, s14, 7
	s_nop 0
	v_addc_co_u32_e32 v29, vcc, 0, v13, vcc
	v_add_co_u32_e32 v30, vcc, 0x20000, v12
	s_nop 1
	v_addc_co_u32_e32 v31, vcc, 0, v13, vcc
	v_add_co_u32_e32 v32, vcc, 0x30000, v12
	s_nop 1
	v_addc_co_u32_e32 v33, vcc, 0, v13, vcc
	v_add_co_u32_e32 v34, vcc, 0x40000, v12
	s_nop 1
	v_addc_co_u32_e32 v35, vcc, 0, v13, vcc
	v_add_co_u32_e32 v36, vcc, 0x50000, v12
	s_nop 1
	v_addc_co_u32_e32 v37, vcc, 0, v13, vcc
	v_add_co_u32_e32 v38, vcc, 0x60000, v12
	s_nop 1
	v_addc_co_u32_e32 v39, vcc, 0, v13, vcc
	v_add_co_u32_e32 v40, vcc, 0x70000, v12
	s_nop 1
	v_addc_co_u32_e32 v41, vcc, 0, v13, vcc
	flat_load_dword v2, v[12:13]
	flat_load_dword v44, v[28:29]
	flat_load_dword v45, v[30:31]
	flat_load_dword v46, v[32:33]
	flat_load_dword v47, v[34:35]
	flat_load_dword v48, v[36:37]
	flat_load_dword v49, v[38:39]
	flat_load_dword v50, v[40:41]
	v_add_co_u32_e32 v28, vcc, 0x80000, v12
	s_nop 1
	v_addc_co_u32_e32 v29, vcc, 0, v13, vcc
	v_add_co_u32_e32 v30, vcc, 0x90000, v12
	s_nop 1
	v_addc_co_u32_e32 v31, vcc, 0, v13, vcc
	v_add_co_u32_e32 v32, vcc, 0xa0000, v12
	s_nop 1
	v_addc_co_u32_e32 v33, vcc, 0, v13, vcc
	v_add_co_u32_e32 v34, vcc, 0xb0000, v12
	s_nop 1
	v_addc_co_u32_e32 v35, vcc, 0, v13, vcc
	v_add_co_u32_e32 v36, vcc, 0xc0000, v12
	s_nop 1
	v_addc_co_u32_e32 v37, vcc, 0, v13, vcc
	v_add_co_u32_e32 v38, vcc, 0xd0000, v12
	s_nop 1
	v_addc_co_u32_e32 v39, vcc, 0, v13, vcc
	v_add_co_u32_e32 v40, vcc, 0xe0000, v12
	s_nop 1
	v_addc_co_u32_e32 v41, vcc, 0, v13, vcc
	v_add_co_u32_e32 v42, vcc, 0xf0000, v12
	s_nop 1
	v_addc_co_u32_e32 v43, vcc, 0, v13, vcc
	flat_load_dword v51, v[28:29]
	flat_load_dword v52, v[30:31]
	flat_load_dword v53, v[32:33]
	flat_load_dword v54, v[34:35]
	flat_load_dword v55, v[36:37]
	flat_load_dword v56, v[38:39]
	flat_load_dword v57, v[40:41]
	flat_load_dword v58, v[42:43]
	v_add_co_u32_e32 v28, vcc, 0x100000, v12
	s_nop 1
	v_addc_co_u32_e32 v29, vcc, 0, v13, vcc
	v_add_co_u32_e32 v30, vcc, 0x110000, v12
	s_nop 1
	v_addc_co_u32_e32 v31, vcc, 0, v13, vcc
	v_add_co_u32_e32 v32, vcc, 0x120000, v12
	s_nop 1
	v_addc_co_u32_e32 v33, vcc, 0, v13, vcc
	v_add_co_u32_e32 v34, vcc, 0x130000, v12
	s_nop 1
	v_addc_co_u32_e32 v35, vcc, 0, v13, vcc
	v_add_co_u32_e32 v36, vcc, 0x140000, v12
	s_nop 1
	v_addc_co_u32_e32 v37, vcc, 0, v13, vcc
	v_add_co_u32_e32 v38, vcc, 0x150000, v12
	s_nop 1
	v_addc_co_u32_e32 v39, vcc, 0, v13, vcc
	v_add_co_u32_e32 v40, vcc, 0x160000, v12
	s_nop 1
	v_addc_co_u32_e32 v41, vcc, 0, v13, vcc
	v_add_co_u32_e32 v42, vcc, 0x170000, v12
	s_nop 1
	v_addc_co_u32_e32 v43, vcc, 0, v13, vcc
	flat_load_dword v59, v[28:29]
	flat_load_dword v60, v[30:31]
	flat_load_dword v61, v[32:33]
	flat_load_dword v62, v[34:35]
	flat_load_dword v63, v[36:37]
	flat_load_dword v64, v[38:39]
	flat_load_dword v65, v[40:41]
	flat_load_dword v66, v[42:43]
	v_add_co_u32_e32 v28, vcc, 0x180000, v12
	s_nop 1
	v_addc_co_u32_e32 v29, vcc, 0, v13, vcc
	v_add_co_u32_e32 v30, vcc, 0x190000, v12
	s_nop 1
	v_addc_co_u32_e32 v31, vcc, 0, v13, vcc
	v_add_co_u32_e32 v32, vcc, 0x1a0000, v12
	s_nop 1
	v_addc_co_u32_e32 v33, vcc, 0, v13, vcc
	v_add_co_u32_e32 v34, vcc, 0x1b0000, v12
	s_nop 1
	v_addc_co_u32_e32 v35, vcc, 0, v13, vcc
	v_add_co_u32_e32 v36, vcc, 0x1c0000, v12
	s_nop 1
	v_addc_co_u32_e32 v37, vcc, 0, v13, vcc
	v_add_co_u32_e32 v38, vcc, 0x1d0000, v12
	s_nop 1
	v_addc_co_u32_e32 v39, vcc, 0, v13, vcc
	v_add_co_u32_e32 v40, vcc, 0x1e0000, v12
	s_nop 1
	v_addc_co_u32_e32 v41, vcc, 0, v13, vcc
	v_add_co_u32_e32 v12, vcc, 0x1f0000, v12
	s_nop 1
	v_addc_co_u32_e32 v13, vcc, 0, v13, vcc
	flat_load_dword v42, v[28:29]
	flat_load_dword v43, v[30:31]
	flat_load_dword v67, v[32:33]
	flat_load_dword v68, v[34:35]
	flat_load_dword v69, v[36:37]
	flat_load_dword v70, v[38:39]
	flat_load_dword v71, v[40:41]
	flat_load_dword v72, v[12:13]
	s_waitcnt vmcnt(0) lgkmcnt(0)
; __device__ __forceinline__ unsigned cvt_pk_bf16(float lo, float hi) { unsigned r; asm volatile("v_cvt_pk_bf16_f32 %0, %1, %2" : "=v"(r) : "v"(lo), "v"(hi)); return r; }
; __device__ __forceinline__ void transpose_item(const float* __restrict__ W, int K, int N, int nblk, bf16_t* __restrict__ WT, int mode, float* scr, int item, int lane) {
;     ...
;     for (int i = 0; i < 32; ++i) { const int kk = 2 * i + (lane >> 5); scr[kk * 33 + (lane & 31)] = wv[i]; }
;     asm volatile("s_waitcnt lgkmcnt(0)" ::: "memory");
;     const int c = lane & 7;
; #pragma unroll
;     for (int j = 0; j < 4; ++j) { const int nn = (lane >> 3) + 8 * j; const float* s = scr + (8 * c) * 33 + nn;
;         u32x4 o; o.x = cvt_pk_bf16(s[0 * 33], s[1 * 33]); o.y = cvt_pk_bf16(s[2 * 33], s[3 * 33]); o.z = cvt_pk_bf16(s[4 * 33], s[5 * 33]); o.w = cvt_pk_bf16(s[6 * 33], s[7 * 33]);
;         *(u32x4*)(WT + (size_t)(n0 + nn) * K + k0 + 8 * c) = o; }
;     asm volatile("s_waitcnt lgkmcnt(0)" ::: "memory");
	ds_write2_b32 v16, v2, v44 offset1:66
	ds_write2_b32 v16, v45, v46 offset0:132 offset1:198
	ds_write2_b32 v21, v47, v48 offset0:8 offset1:74
	ds_write2_b32 v21, v49, v50 offset0:140 offset1:206
	ds_write2_b32 v22, v51, v52 offset0:16 offset1:82
	ds_write2_b32 v22, v53, v54 offset0:148 offset1:214
	ds_write2_b32 v23, v55, v56 offset0:24 offset1:90
	ds_write2_b32 v23, v57, v58 offset0:156 offset1:222
	ds_write2_b32 v24, v59, v60 offset0:32 offset1:98
	ds_write2_b32 v24, v61, v62 offset0:164 offset1:230
	ds_write2_b32 v25, v63, v64 offset0:40 offset1:106
	ds_write2_b32 v25, v65, v66 offset0:172 offset1:238
	ds_write2_b32 v26, v42, v43 offset0:48 offset1:114
	ds_write2_b32 v26, v67, v68 offset0:180 offset1:246
	ds_write2_b32 v27, v69, v70 offset0:56 offset1:122
	ds_write2_b32 v27, v71, v72 offset0:188 offset1:254
	s_waitcnt lgkmcnt(0)
	ds_read2_b32 v[12:13], v17 offset1:33
	s_waitcnt lgkmcnt(0)
	v_cvt_pk_bf16_f32 v28, v12, v13
	ds_read2_b32 v[12:13], v17 offset0:66 offset1:99
	s_waitcnt lgkmcnt(0)
	v_cvt_pk_bf16_f32 v29, v12, v13
	ds_read2_b32 v[12:13], v17 offset0:132 offset1:165
	v_or_b32_e32 v2, s16, v78
	s_waitcnt lgkmcnt(0)
	v_cvt_pk_bf16_f32 v30, v12, v13
	ds_read2_b32 v[12:13], v17 offset0:198 offset1:231
	v_lshl_add_u64 v[32:33], v[6:7], 0, s[14:15]
	v_lshlrev_b32_e32 v2, 12, v2
	s_waitcnt lgkmcnt(0)
	v_cvt_pk_bf16_f32 v31, v12, v13
	ds_read2_b32 v[12:13], v17 offset0:8 offset1:41
	v_lshl_add_u64 v[34:35], v[32:33], 0, v[2:3]
	global_store_dwordx4 v[34:35], v[28:31], off
	v_or_b32_e32 v2, s16, v18
	v_lshlrev_b32_e32 v2, 12, v2
	s_waitcnt lgkmcnt(0)
	v_cvt_pk_bf16_f32 v28, v12, v13
	ds_read2_b32 v[12:13], v17 offset0:74 offset1:107
	s_waitcnt lgkmcnt(0)
	v_cvt_pk_bf16_f32 v29, v12, v13
	ds_read2_b32 v[12:13], v17 offset0:140 offset1:173
	s_waitcnt lgkmcnt(0)
	v_cvt_pk_bf16_f32 v30, v12, v13
	ds_read2_b32 v[12:13], v17 offset0:206 offset1:239
	s_waitcnt lgkmcnt(0)
	v_cvt_pk_bf16_f32 v31, v12, v13
	ds_read2_b32 v[12:13], v17 offset0:16 offset1:49
	v_lshl_add_u64 v[34:35], v[32:33], 0, v[2:3]
	global_store_dwordx4 v[34:35], v[28:31], off
	v_or_b32_e32 v2, s16, v19
	v_lshlrev_b32_e32 v2, 12, v2
	s_waitcnt lgkmcnt(0)
	v_cvt_pk_bf16_f32 v28, v12, v13
	ds_read2_b32 v[12:13], v17 offset0:82 offset1:115
	s_waitcnt lgkmcnt(0)
	v_cvt_pk_bf16_f32 v29, v12, v13
	ds_read2_b32 v[12:13], v17 offset0:148 offset1:181
	s_waitcnt lgkmcnt(0)
	v_cvt_pk_bf16_f32 v30, v12, v13
	ds_read2_b32 v[12:13], v17 offset0:214 offset1:247
	s_waitcnt lgkmcnt(0)
	v_cvt_pk_bf16_f32 v31, v12, v13
	ds_read2_b32 v[12:13], v17 offset0:24 offset1:57
	v_lshl_add_u64 v[34:35], v[32:33], 0, v[2:3]
	global_store_dwordx4 v[34:35], v[28:31], off
	v_or_b32_e32 v2, s16, v20
	v_lshlrev_b32_e32 v2, 12, v2
	s_waitcnt lgkmcnt(0)
	v_cvt_pk_bf16_f32 v28, v12, v13
	ds_read2_b32 v[12:13], v17 offset0:90 offset1:123
	s_waitcnt lgkmcnt(0)
	v_cvt_pk_bf16_f32 v29, v12, v13
	ds_read2_b32 v[12:13], v17 offset0:156 offset1:189
	s_waitcnt lgkmcnt(0)
	v_cvt_pk_bf16_f32 v30, v12, v13
	ds_read2_b32 v[12:13], v17 offset0:222 offset1:255
	s_waitcnt lgkmcnt(0)
	v_cvt_pk_bf16_f32 v31, v12, v13
	v_lshl_add_u64 v[12:13], v[32:33], 0, v[2:3]
	global_store_dwordx4 v[12:13], v[28:31], off
	s_waitcnt lgkmcnt(0)

; __device__ __forceinline__ void transpose_item(const float* __restrict__ W, int K, int N, int nblk, bf16_t* __restrict__ WT, int mode, float* scr, int item, int lane) {
;     const int kb = item / nblk, nb = item % nblk, k0 = 64 * kb, n0 = 32 * nb;
;     const int n = n0 + (lane & 31); int src = n;
;     if (mode) src = n < 2048 ? n : (n < 6144 ? n + 8 : (n < 6152 ? n - 6144 + 2048 : (n < 6160 ? n : -1)));
;     float wv[32];
; #pragma unroll
;     for (int i = 0; i < 32; ++i) { const int kk = 2 * i + (lane >> 5); wv[i] = src >= 0 ? W[(size_t)(k0 + kk) * N + src] : 0.f; }
; __device__ __forceinline__ void convert_weights(const Params& P, int l, int part, char* lds, int gw, int NGW, int wid, int lane) {
;     ...
;         if (r < I_OUT) { transpose_item(w_out, DM, DM, DM / 32, WoutT, 0, scr, r, lane); continue; } r -= I_OUT;
.LBB0_1880:
	s_andn2_b64 vcc, exec, s[16:17]
	s_cbranch_vccnz .LBB0_1882
	s_add_i32 s14, s3, 0xe700
	s_and_b32 s16, s23, 0x7e0
	s_and_b32 s14, s14, 0xffc0
	v_or_b32_e32 v2, s16, v14
	v_or_b32_e32 v28, s14, v15
	v_lshlrev_b32_e32 v2, 2, v2
	v_lshl_add_u64 v[12:13], s[8:9], 0, v[2:3]
	v_lshlrev_b32_e32 v2, 13, v28
	v_lshl_add_u64 v[12:13], v[12:13], 0, v[2:3]
	v_add_co_u32_e32 v28, vcc, 0x4000, v12
	s_lshl_b32 s14, s14, 1
	s_nop 0
	v_addc_co_u32_e32 v29, vcc, 0, v13, vcc
	v_add_co_u32_e32 v30, vcc, 0x8000, v12
	s_nop 1
	v_addc_co_u32_e32 v31, vcc, 0, v13, vcc
	v_add_co_u32_e32 v32, vcc, 0xc000, v12
	s_nop 1
	v_addc_co_u32_e32 v33, vcc, 0, v13, vcc
	v_add_co_u32_e32 v34, vcc, s24, v12
	s_nop 1
	v_addc_co_u32_e32 v35, vcc, 0, v13, vcc
	v_add_co_u32_e32 v36, vcc, 0x14000, v12
	s_nop 1
	v_addc_co_u32_e32 v37, vcc, 0, v13, vcc
	v_add_co_u32_e32 v38, vcc, 0x18000, v12
	s_nop 1
	v_addc_co_u32_e32 v39, vcc, 0, v13, vcc
	v_add_co_u32_e32 v40, vcc, 0x1c000, v12
	s_nop 1
	v_addc_co_u32_e32 v41, vcc, 0, v13, vcc
	flat_load_dword v2, v[12:13]
	flat_load_dword v44, v[28:29]
	flat_load_dword v45, v[30:31]
	flat_load_dword v46, v[32:33]
	flat_load_dword v47, v[34:35]
	flat_load_dword v48, v[36:37]
	flat_load_dword v49, v[38:39]
	flat_load_dword v50, v[40:41]
	v_add_co_u32_e32 v28, vcc, s25, v12
	s_nop 1
	v_addc_co_u32_e32 v29, vcc, 0, v13, vcc
	v_add_co_u32_e32 v30, vcc, 0x24000, v12
	s_nop 1
	v_addc_co_u32_e32 v31, vcc, 0, v13, vcc
	v_add_co_u32_e32 v32, vcc, 0x28000, v12
	s_nop 1
	v_addc_co_u32_e32 v33, vcc, 0, v13, vcc
	v_add_co_u32_e32 v34, vcc, 0x2c000, v12
	s_nop 1
	v_addc_co_u32_e32 v35, vcc, 0, v13, vcc
	v_add_co_u32_e32 v36, vcc, s26, v12
	s_nop 1
	v_addc_co_u32_e32 v37, vcc, 0, v13, vcc
	v_add_co_u32_e32 v38, vcc, 0x34000, v12
	s_nop 1
	v_addc_co_u32_e32 v39, vcc, 0, v13, vcc
	v_add_co_u32_e32 v40, vcc, 0x38000, v12
	s_nop 1
	v_addc_co_u32_e32 v41, vcc, 0, v13, vcc
	v_add_co_u32_e32 v42, vcc, 0x3c000, v12
	s_nop 1
	v_addc_co_u32_e32 v43, vcc, 0, v13, vcc
	flat_load_dword v51, v[28:29]
	flat_load_dword v52, v[30:31]
	flat_load_dword v53, v[32:33]
	flat_load_dword v54, v[34:35]
	flat_load_dword v55, v[36:37]
	flat_load_dword v56, v[38:39]
	flat_load_dword v57, v[40:41]
	flat_load_dword v58, v[42:43]
	v_add_co_u32_e32 v28, vcc, s27, v12
	s_nop 1
	v_addc_co_u32_e32 v29, vcc, 0, v13, vcc
	v_add_co_u32_e32 v30, vcc, 0x44000, v12
	s_nop 1
	v_addc_co_u32_e32 v31, vcc, 0, v13, vcc
	v_add_co_u32_e32 v32, vcc, 0x48000, v12
	s_nop 1
	v_addc_co_u32_e32 v33, vcc, 0, v13, vcc
	v_add_co_u32_e32 v34, vcc, 0x4c000, v12
	s_nop 1
	v_addc_co_u32_e32 v35, vcc, 0, v13, vcc
	v_add_co_u32_e32 v36, vcc, s28, v12
	s_nop 1
	v_addc_co_u32_e32 v37, vcc, 0, v13, vcc
	v_add_co_u32_e32 v38, vcc, 0x54000, v12
	s_nop 1
	v_addc_co_u32_e32 v39, vcc, 0, v13, vcc
	v_add_co_u32_e32 v40, vcc, 0x58000, v12
	s_nop 1
	v_addc_co_u32_e32 v41, vcc, 0, v13, vcc
	v_add_co_u32_e32 v42, vcc, 0x5c000, v12
	s_nop 1
	v_addc_co_u32_e32 v43, vcc, 0, v13, vcc
	flat_load_dword v59, v[28:29]
	flat_load_dword v60, v[30:31]
	flat_load_dword v61, v[32:33]
	flat_load_dword v62, v[34:35]
	flat_load_dword v63, v[36:37]
	flat_load_dword v64, v[38:39]
	flat_load_dword v65, v[40:41]
	flat_load_dword v66, v[42:43]
	v_add_co_u32_e32 v28, vcc, s29, v12
	s_nop 1
	v_addc_co_u32_e32 v29, vcc, 0, v13, vcc
	v_add_co_u32_e32 v30, vcc, 0x64000, v12
	s_nop 1
	v_addc_co_u32_e32 v31, vcc, 0, v13, vcc
	v_add_co_u32_e32 v32, vcc, 0x68000, v12
	s_nop 1
	v_addc_co_u32_e32 v33, vcc, 0, v13, vcc
	v_add_co_u32_e32 v34, vcc, 0x6c000, v12
	s_nop 1
	v_addc_co_u32_e32 v35, vcc, 0, v13, vcc
	v_add_co_u32_e32 v36, vcc, s30, v12
	s_nop 1
	v_addc_co_u32_e32 v37, vcc, 0, v13, vcc
	v_add_co_u32_e32 v38, vcc, 0x74000, v12
	s_nop 1
	v_addc_co_u32_e32 v39, vcc, 0, v13, vcc
	v_add_co_u32_e32 v40, vcc, 0x78000, v12
	s_nop 1
	v_addc_co_u32_e32 v41, vcc, 0, v13, vcc
	v_add_co_u32_e32 v12, vcc, 0x7c000, v12
	s_nop 1
	v_addc_co_u32_e32 v13, vcc, 0, v13, vcc
	flat_load_dword v42, v[28:29]
	flat_load_dword v43, v[30:31]
	flat_load_dword v67, v[32:33]
	flat_load_dword v68, v[34:35]
	flat_load_dword v69, v[36:37]
	flat_load_dword v70, v[38:39]
	flat_load_dword v71, v[40:41]
	flat_load_dword v72, v[12:13]
	s_waitcnt vmcnt(0) lgkmcnt(0)
; __device__ __forceinline__ unsigned cvt_pk_bf16(float lo, float hi) { unsigned r; asm volatile("v_cvt_pk_bf16_f32 %0, %1, %2" : "=v"(r) : "v"(lo), "v"(hi)); return r; }
; __device__ __forceinline__ void transpose_item(const float* __restrict__ W, int K, int N, int nblk, bf16_t* __restrict__ WT, int mode, float* scr, int item, int lane) {
;     ...
;     for (int i = 0; i < 32; ++i) { const int kk = 2 * i + (lane >> 5); scr[kk * 33 + (lane & 31)] = wv[i]; }
;     asm volatile("s_waitcnt lgkmcnt(0)" ::: "memory");
;     const int c = lane & 7;
; #pragma unroll
;     for (int j = 0; j < 4; ++j) { const int nn = (lane >> 3) + 8 * j; const float* s = scr + (8 * c) * 33 + nn;
;         u32x4 o; o.x = cvt_pk_bf16(s[0 * 33], s[1 * 33]); o.y = cvt_pk_bf16(s[2 * 33], s[3 * 33]); o.z = cvt_pk_bf16(s[4 * 33], s[5 * 33]); o.w = cvt_pk_bf16(s[6 * 33], s[7 * 33]);
;         *(u32x4*)(WT + (size_t)(n0 + nn) * K + k0 + 8 * c) = o; }
;     asm volatile("s_waitcnt lgkmcnt(0)" ::: "memory");
	ds_write2_b32 v16, v2, v44 offset1:66
	ds_write2_b32 v16, v45, v46 offset0:132 offset1:198
	ds_write2_b32 v21, v47, v48 offset0:8 offset1:74
	ds_write2_b32 v21, v49, v50 offset0:140 offset1:206
	ds_write2_b32 v22, v51, v52 offset0:16 offset1:82
	ds_write2_b32 v22, v53, v54 offset0:148 offset1:214
	ds_write2_b32 v23, v55, v56 offset0:24 offset1:90
	ds_write2_b32 v23, v57, v58 offset0:156 offset1:222
	ds_write2_b32 v24, v59, v60 offset0:32 offset1:98
	ds_write2_b32 v24, v61, v62 offset0:164 offset1:230
	ds_write2_b32 v25, v63, v64 offset0:40 offset1:106
	ds_write2_b32 v25, v65, v66 offset0:172 offset1:238
	ds_write2_b32 v26, v42, v43 offset0:48 offset1:114
	ds_write2_b32 v26, v67, v68 offset0:180 offset1:246
	ds_write2_b32 v27, v69, v70 offset0:56 offset1:122
	ds_write2_b32 v27, v71, v72 offset0:188 offset1:254
	s_waitcnt lgkmcnt(0)
	ds_read2_b32 v[12:13], v17 offset1:33
	s_waitcnt lgkmcnt(0)
	v_cvt_pk_bf16_f32 v28, v12, v13
	ds_read2_b32 v[12:13], v17 offset0:66 offset1:99
	s_waitcnt lgkmcnt(0)
	v_cvt_pk_bf16_f32 v29, v12, v13
	ds_read2_b32 v[12:13], v17 offset0:132 offset1:165
	v_or_b32_e32 v2, s16, v78
	s_waitcnt lgkmcnt(0)
	v_cvt_pk_bf16_f32 v30, v12, v13
	ds_read2_b32 v[12:13], v17 offset0:198 offset1:231
	v_lshl_add_u64 v[32:33], v[8:9], 0, s[14:15]
	v_lshlrev_b32_e32 v2, 12, v2
	s_waitcnt lgkmcnt(0)
	v_cvt_pk_bf16_f32 v31, v12, v13
	ds_read2_b32 v[12:13], v17 offset0:8 offset1:41
	v_lshl_add_u64 v[34:35], v[32:33], 0, v[2:3]
	global_store_dwordx4 v[34:35], v[28:31], off
	v_or_b32_e32 v2, s16, v18
	v_lshlrev_b32_e32 v2, 12, v2
	s_waitcnt lgkmcnt(0)
	v_cvt_pk_bf16_f32 v28, v12, v13
	ds_read2_b32 v[12:13], v17 offset0:74 offset1:107
	s_waitcnt lgkmcnt(0)
	v_cvt_pk_bf16_f32 v29, v12, v13
	ds_read2_b32 v[12:13], v17 offset0:140 offset1:173
	s_waitcnt lgkmcnt(0)
	v_cvt_pk_bf16_f32 v30, v12, v13
	ds_read2_b32 v[12:13], v17 offset0:206 offset1:239
	s_waitcnt lgkmcnt(0)
	v_cvt_pk_bf16_f32 v31, v12, v13
	ds_read2_b32 v[12:13], v17 offset0:16 offset1:49
	v_lshl_add_u64 v[34:35], v[32:33], 0, v[2:3]
	global_store_dwordx4 v[34:35], v[28:31], off
	v_or_b32_e32 v2, s16, v19
	v_lshlrev_b32_e32 v2, 12, v2
	s_waitcnt lgkmcnt(0)
	v_cvt_pk_bf16_f32 v28, v12, v13
	ds_read2_b32 v[12:13], v17 offset0:82 offset1:115
	s_waitcnt lgkmcnt(0)
	v_cvt_pk_bf16_f32 v29, v12, v13
	ds_read2_b32 v[12:13], v17 offset0:148 offset1:181
	s_waitcnt lgkmcnt(0)
	v_cvt_pk_bf16_f32 v30, v12, v13
	ds_read2_b32 v[12:13], v17 offset0:214 offset1:247
	s_waitcnt lgkmcnt(0)
	v_cvt_pk_bf16_f32 v31, v12, v13
	ds_read2_b32 v[12:13], v17 offset0:24 offset1:57
	v_lshl_add_u64 v[34:35], v[32:33], 0, v[2:3]
	global_store_dwordx4 v[34:35], v[28:31], off
	v_or_b32_e32 v2, s16, v20
	v_lshlrev_b32_e32 v2, 12, v2
	s_waitcnt lgkmcnt(0)
	v_cvt_pk_bf16_f32 v28, v12, v13
	ds_read2_b32 v[12:13], v17 offset0:90 offset1:123
	s_waitcnt lgkmcnt(0)
	v_cvt_pk_bf16_f32 v29, v12, v13
	ds_read2_b32 v[12:13], v17 offset0:156 offset1:189
	s_waitcnt lgkmcnt(0)
	v_cvt_pk_bf16_f32 v30, v12, v13
	ds_read2_b32 v[12:13], v17 offset0:222 offset1:255
	s_waitcnt lgkmcnt(0)
	v_cvt_pk_bf16_f32 v31, v12, v13
	v_lshl_add_u64 v[12:13], v[32:33], 0, v[2:3]
	global_store_dwordx4 v[12:13], v[28:31], off
	s_waitcnt lgkmcnt(0)

; __device__ __forceinline__ unsigned cvt_pk_bf16(float lo, float hi) { unsigned r; asm volatile("v_cvt_pk_bf16_f32 %0, %1, %2" : "=v"(r) : "v"(lo), "v"(hi)); return r; }
; __device__ __forceinline__ void mlstm_local_unit(const Params& P, int l, int h, int n, char* lds) {
;     ...
;     bf16_t* ct = CT + (size_t)(h * NCH + n) * 32768;
; #pragma unroll
;     for (int j = 0; j < 4; ++j) { const int e = 32 * (eb0 + j) + r32;
; #pragma unroll
;         for (int q = 0; q < 4; ++q) { u32x2 w; w.x = cvt_pk_bf16(acc[j][4 * q], acc[j][4 * q + 1]); w.y = cvt_pk_bf16(acc[j][4 * q + 2], acc[j][4 * q + 3]);
;             *(u32x2*)(ct + e * 128 + 32 * db + 8 * q + 4 * hi) = w; } }
;     __syncthreads();
.LBB0_1978:
	s_or_b64 exec, exec, s[8:9]
	v_lshlrev_b64 v[66:67], 16, v[68:69]
	v_lshl_add_u64 v[66:67], s[60:61], 0, v[66:67]
	s_lshl_b32 s22, s18, 1
	v_lshlrev_b32_e32 v70, 7, v70
	v_lshl_add_u64 v[66:67], v[66:67], 0, s[22:23]
	v_lshl_add_u64 v[66:67], v[66:67], 0, v[196:197]
	v_lshl_or_b32 v68, s17, 12, v70
	v_lshl_add_u64 v[66:67], v[66:67], 0, s[50:51]
	v_ashrrev_i32_e32 v69, 31, v68
	v_lshl_add_u64 v[68:69], v[68:69], 1, v[66:67]
	v_cvt_pk_bf16_f32 v50, v50, v51
	v_cvt_pk_bf16_f32 v51, v52, v53
	global_store_dwordx2 v[68:69], v[50:51], off
	v_cvt_pk_bf16_f32 v50, v54, v55
	v_cvt_pk_bf16_f32 v51, v56, v57
	global_store_dwordx2 v[68:69], v[50:51], off offset:16
	v_cvt_pk_bf16_f32 v50, v58, v59
	v_cvt_pk_bf16_f32 v51, v60, v61
	global_store_dwordx2 v[68:69], v[50:51], off offset:32
	v_cvt_pk_bf16_f32 v50, v62, v63
	v_cvt_pk_bf16_f32 v51, v64, v65
	global_store_dwordx2 v[68:69], v[50:51], off offset:48
	v_lshl_or_b32 v50, s16, 12, v70
	v_ashrrev_i32_e32 v51, 31, v50
	v_lshl_add_u64 v[50:51], v[50:51], 1, v[66:67]
	v_cvt_pk_bf16_f32 v34, v34, v35
	v_cvt_pk_bf16_f32 v35, v36, v37
	global_store_dwordx2 v[50:51], v[34:35], off
	v_cvt_pk_bf16_f32 v34, v38, v39
	v_cvt_pk_bf16_f32 v35, v40, v41
	global_store_dwordx2 v[50:51], v[34:35], off offset:16
	v_cvt_pk_bf16_f32 v34, v42, v43
	v_cvt_pk_bf16_f32 v35, v44, v45
	global_store_dwordx2 v[50:51], v[34:35], off offset:32
	v_cvt_pk_bf16_f32 v34, v46, v47
	v_cvt_pk_bf16_f32 v35, v48, v49
	global_store_dwordx2 v[50:51], v[34:35], off offset:48
	v_lshl_or_b32 v34, s15, 12, v70
	v_ashrrev_i32_e32 v35, 31, v34
	v_lshl_add_u64 v[34:35], v[34:35], 1, v[66:67]
	v_cvt_pk_bf16_f32 v18, v18, v19
	v_cvt_pk_bf16_f32 v19, v20, v21
	global_store_dwordx2 v[34:35], v[18:19], off
	v_cvt_pk_bf16_f32 v18, v22, v23
	v_cvt_pk_bf16_f32 v19, v24, v25
	global_store_dwordx2 v[34:35], v[18:19], off offset:16
	v_cvt_pk_bf16_f32 v18, v26, v27
	v_cvt_pk_bf16_f32 v19, v28, v29
	global_store_dwordx2 v[34:35], v[18:19], off offset:32
	v_cvt_pk_bf16_f32 v18, v30, v31
	v_cvt_pk_bf16_f32 v19, v32, v33
	global_store_dwordx2 v[34:35], v[18:19], off offset:48
	v_lshl_or_b32 v18, s14, 12, v70
	v_ashrrev_i32_e32 v19, 31, v18
	v_lshl_add_u64 v[18:19], v[18:19], 1, v[66:67]
	v_cvt_pk_bf16_f32 v2, v2, v3
	v_cvt_pk_bf16_f32 v3, v4, v5
	global_store_dwordx2 v[18:19], v[2:3], off
	v_cvt_pk_bf16_f32 v2, v6, v7
	v_cvt_pk_bf16_f32 v3, v8, v9
	global_store_dwordx2 v[18:19], v[2:3], off offset:16
	v_cvt_pk_bf16_f32 v2, v10, v11
	v_cvt_pk_bf16_f32 v3, v12, v13
	s_add_i32 s3, s3, 1
	global_store_dwordx2 v[18:19], v[2:3], off offset:32
	v_cvt_pk_bf16_f32 v2, v14, v15
	v_cvt_pk_bf16_f32 v3, v16, v17
	global_store_dwordx2 v[18:19], v[2:3], off offset:48
	s_waitcnt lgkmcnt(0)
	s_barrier

; __device__ __forceinline__ void mlstm_local_unit(const Params& P, int l, int h, int n, char* lds) {
;     ...
;     u32x4 kx[2][4], vx[4];
; #pragma unroll
;     for (int i = 0; i < 2; ++i) { const int idx = tid + 512 * i, t = idx >> 4, c = idx & 15;
; #pragma unroll
;         for (int k = 0; k < 4; ++k) { const int rr = t0 + t - 3 + k; kx[i][k] = (u32x4){0u, 0u, 0u, 0u};
;             if (rr >= 0) kx[i][k] = *(const u32x4*)(PROJ + (size_t)rr * PW + C_MK + h * 128 + c * 8); } }
; #pragma unroll
;     for (int i = 0; i < 4; ++i) { const int idx = tid + 512 * i, t = idx >> 5, c = idx & 31; vx[i] = *(const u32x4*)(PROJ + (size_t)(t0 + t) * PW + C_MV + h * 256 + c * 8); }
.LBB0_1987:
	s_or_b64 exec, exec, s[62:63]
	v_cmp_lt_i32_e32 vcc, -3, v2
	v_mov_b32_e32 v34, 0
	v_mov_b32_e32 v46, 0
	v_mov_b32_e32 v47, 0
	v_mov_b32_e32 v48, 0
	v_mov_b32_e32 v49, 0
	s_and_saveexec_b64 s[62:63], vcc
	s_cbranch_execz .LBB0_1989
	v_add_u32_e32 v4, 2, v2
	v_mov_b64_e32 v[2:3], s[8:9]
	v_mad_u64_u32 v[2:3], s[38:39], v4, s91, v[2:3]
	s_lshl_b32 s22, s35, 1
	v_lshl_add_u64 v[2:3], v[2:3], 0, s[22:23]
	v_lshlrev_b32_e32 v196, 1, v88
	v_lshl_add_u64 v[2:3], v[2:3], 0, v[196:197]
	global_load_dwordx4 v[46:49], v[2:3], off offset:1024
.LBB0_1989:
	s_or_b64 exec, exec, s[62:63]
	v_add_u32_e32 v2, s36, v89
	v_cmp_lt_i32_e32 vcc, -1, v2
	v_mov_b32_e32 v35, 0
	v_mov_b32_e32 v36, 0
	v_mov_b32_e32 v37, 0
	s_and_saveexec_b64 s[62:63], vcc
	s_cbranch_execz .LBB0_1991
	v_mov_b64_e32 v[4:5], s[8:9]
	v_mad_u64_u32 v[2:3], s[38:39], v2, s91, v[4:5]
	s_lshl_b32 s22, s35, 1
	v_lshl_add_u64 v[2:3], v[2:3], 0, s[22:23]
	v_lshlrev_b32_e32 v196, 1, v88
	v_lshl_add_u64 v[2:3], v[2:3], 0, v[196:197]
	global_load_dwordx4 v[34:37], v[2:3], off offset:1024
.LBB0_1991:
	s_or_b64 exec, exec, s[62:63]
	v_add_u32_e32 v78, 0x200, v66
	v_ashrrev_i32_e32 v86, 4, v78
	v_add_u32_e32 v2, s37, v86
	v_cmp_lt_i32_e32 vcc, -1, v2
	v_mov_b32_e32 v22, 0
	v_mov_b32_e32 v26, 0
	v_mov_b32_e32 v27, 0
	v_mov_b32_e32 v28, 0
	v_mov_b32_e32 v29, 0
	s_and_saveexec_b64 s[62:63], vcc
	s_cbranch_execz .LBB0_1993
	v_mov_b64_e32 v[4:5], s[8:9]
	v_mad_u64_u32 v[4:5], s[38:39], v2, s91, v[4:5]
	s_lshl_b32 s22, s35, 1
	v_lshl_add_u64 v[4:5], v[4:5], 0, s[22:23]
	v_lshlrev_b32_e32 v196, 1, v88
	v_lshl_add_u64 v[4:5], v[4:5], 0, v[196:197]
	global_load_dwordx4 v[26:29], v[4:5], off offset:1024
.LBB0_1993:
	s_or_b64 exec, exec, s[62:63]
	v_cmp_lt_i32_e32 vcc, -2, v2
	v_mov_b32_e32 v23, 0
	v_mov_b32_e32 v24, 0
	v_mov_b32_e32 v25, 0
	s_and_saveexec_b64 s[62:63], vcc
	s_cbranch_execz .LBB0_1995
	v_add_u32_e32 v3, 1, v2
	v_mov_b64_e32 v[4:5], s[8:9]
	v_mad_u64_u32 v[4:5], s[38:39], v3, s91, v[4:5]
	s_lshl_b32 s22, s35, 1
	v_lshl_add_u64 v[4:5], v[4:5], 0, s[22:23]
	v_lshlrev_b32_e32 v196, 1, v88
	v_lshl_add_u64 v[4:5], v[4:5], 0, v[196:197]
	global_load_dwordx4 v[22:25], v[4:5], off offset:1024
.LBB0_1995:
	s_or_b64 exec, exec, s[62:63]
	v_cmp_lt_i32_e32 vcc, -3, v2
	v_mov_b32_e32 v18, 0
	v_mov_b32_e32 v30, 0
	v_mov_b32_e32 v31, 0
	v_mov_b32_e32 v32, 0
	v_mov_b32_e32 v33, 0
	s_and_saveexec_b64 s[62:63], vcc
	s_cbranch_execz .LBB0_1997
	v_add_u32_e32 v4, 2, v2
	v_mov_b64_e32 v[2:3], s[8:9]
	v_mad_u64_u32 v[2:3], s[38:39], v4, s91, v[2:3]
	s_lshl_b32 s22, s35, 1
	v_lshl_add_u64 v[2:3], v[2:3], 0, s[22:23]
	v_lshlrev_b32_e32 v196, 1, v88
	v_lshl_add_u64 v[2:3], v[2:3], 0, v[196:197]
	global_load_dwordx4 v[30:33], v[2:3], off offset:1024
.LBB0_1997:
	s_or_b64 exec, exec, s[62:63]
	v_add_u32_e32 v2, s36, v86
	v_cmp_lt_i32_e32 vcc, -1, v2
	v_mov_b32_e32 v19, 0
	v_mov_b32_e32 v20, 0
	v_mov_b32_e32 v21, 0
	s_and_saveexec_b64 s[62:63], vcc
	s_cbranch_execz .LBB0_1999
	v_mov_b64_e32 v[4:5], s[8:9]
	v_mad_u64_u32 v[2:3], s[38:39], v2, s91, v[4:5]
	s_lshl_b32 s22, s35, 1
	v_lshl_add_u64 v[2:3], v[2:3], 0, s[22:23]
	v_lshlrev_b32_e32 v196, 1, v88
	v_lshl_add_u64 v[2:3], v[2:3], 0, v[196:197]
	global_load_dwordx4 v[18:21], v[2:3], off offset:1024
.LBB0_1999:
	s_or_b64 exec, exec, s[62:63]
	v_ashrrev_i32_e32 v85, 5, v66
	v_ashrrev_i32_e32 v83, 5, v78
	v_add_u32_e32 v4, s36, v85
	v_mov_b64_e32 v[2:3], s[8:9]
	v_add_u32_e32 v6, s36, v83
	v_and_b32_e32 v84, 0xf8, v67
	v_mad_i64_i32 v[4:5], s[8:9], v4, s91, v[2:3]
	s_lshl_b32 s22, s30, 9
	v_mad_i64_i32 v[6:7], s[8:9], v6, s91, v[2:3]
	v_lshl_add_u64 v[4:5], v[4:5], 0, s[22:23]
	v_lshlrev_b32_e32 v196, 1, v84
	v_lshl_add_u64 v[6:7], v[6:7], 0, s[22:23]
	v_add_u32_e32 v81, 0x400, v66
	v_add_u32_e32 v79, 0x600, v66
	v_lshl_add_u64 v[4:5], v[4:5], 0, v[196:197]
	v_lshl_add_u64 v[6:7], v[6:7], 0, v[196:197]
	v_ashrrev_i32_e32 v82, 5, v81
	v_ashrrev_i32_e32 v80, 5, v79
	global_load_dwordx4 v[14:17], v[4:5], off offset:2048
	s_nop 0
	global_load_dwordx4 v[6:9], v[6:7], off offset:2048
	v_add_u32_e32 v4, s36, v82
	v_add_u32_e32 v10, s36, v80
	v_mad_i64_i32 v[4:5], s[8:9], v4, s91, v[2:3]
	v_mad_i64_i32 v[2:3], s[8:9], v10, s91, v[2:3]
	v_lshl_add_u64 v[4:5], v[4:5], 0, s[22:23]
	v_lshl_add_u64 v[2:3], v[2:3], 0, s[22:23]
	v_lshl_add_u64 v[4:5], v[4:5], 0, v[196:197]
	v_lshl_add_u64 v[2:3], v[2:3], 0, v[196:197]
	global_load_dwordx4 v[10:13], v[4:5], off offset:2048
	s_nop 0
	global_load_dwordx4 v[2:5], v[2:3], off offset:2048
	s_cmp_gt_u32 s34, 63
	v_and_b32_e32 v87, 63, v66
	s_cbranch_scc1 .LBB0_2003
; __device__ __forceinline__ float logsigmoid(float x) { return fminf(x, 0.f) - log1pf(__expf(-fabsf(x))); }
; __device__ __forceinline__ void mlstm_local_unit(const Params& P, int l, int h, int n, char* lds) {
;     ...
;     if (wid == 0) {
;         const int row = t0 + lane;
;         const float li = GATES[(size_t)row * 16 + h] + P.in[5][l * 4 + h];
;         const float lf = logsigmoid(GATES[(size_t)row * 16 + 4 + h] + P.in[6][l * 4 + h]);
	v_or_b32_e32 v50, s36, v87
	v_ashrrev_i32_e32 v51, 31, v50
	v_lshlrev_b64 v[50:51], 6, v[50:51]
	v_lshl_add_u64 v[50:51], s[60:61], 0, v[50:51]
	s_lshl_b32 s22, s30, 2
	v_lshl_add_u64 v[50:51], v[50:51], 0, s[22:23]
	s_mov_b64 s[8:9], 0x300000
	v_lshl_add_u64 v[52:53], v[50:51], 0, s[8:9]
	s_waitcnt lgkmcnt(0)
	s_add_u32 s8, s16, s22
	s_addc_u32 s9, s17, 0
	s_add_u32 s16, s18, s22
	s_addc_u32 s17, s19, 0
	v_mov_b64_e32 v[54:55], s[16:17]
	flat_load_dword v54, v[54:55] offset:16
	s_nop 0
	flat_load_dword v53, v[52:53] offset:16
	v_and_b32_e32 v52, 64, v207
	v_add_u32_e32 v55, -1, v207
	v_cmp_lt_i32_e32 vcc, v55, v52
	s_mov_b32 s16, 0xbfb8aa3b
	s_mov_b32 s17, 0x3f2aaaab
	v_cndmask_b32_e32 v55, v55, v207, vcc
	v_add_co_u32_e32 v50, vcc, 0x300000, v50
	s_mov_b32 s18, 0x3f317218
	s_nop 0
	v_addc_co_u32_e32 v51, vcc, 0, v51, vcc
	flat_load_dword v59, v[50:51]
	v_mov_b32_e32 v56, 0x3ecc95a3
	s_mov_b32 s19, 0x7f800000
	v_mov_b32_e32 v57, 0x7f800000
	v_mov_b32_e32 v58, 0x7fc00000
	s_mov_b32 s22, 0x33800000
	v_lshlrev_b32_e32 v55, 2, v55
	s_waitcnt vmcnt(0) lgkmcnt(0)
	v_add_f32_e32 v53, v53, v54
	v_mul_f32_e64 v50, |v53|, s16
	v_exp_f32_e32 v54, v50
	v_mov_b64_e32 v[50:51], s[8:9]
	flat_load_dword v60, v[50:51] offset:16
	v_min_f32_e32 v53, 0, v53
	v_add_f32_e32 v61, 1.0, v54
	v_add_f32_e32 v62, -1.0, v61
	v_frexp_mant_f32_e32 v63, v61
	v_cvt_f64_f32_e32 v[50:51], v61
	v_sub_f32_e32 v64, v62, v61
	v_frexp_exp_i32_f64_e32 v50, v[50:51]
	v_cmp_gt_f32_e32 vcc, s17, v63
	v_sub_f32_e32 v62, v54, v62
	v_add_f32_e32 v51, 1.0, v64
	v_subbrev_co_u32_e32 v50, vcc, 0, v50, vcc
	v_add_f32_e32 v51, v62, v51
	v_sub_u32_e32 v62, 0, v50
	v_cvt_f32_i32_e32 v50, v50
	v_ldexp_f32 v61, v61, v62
	v_ldexp_f32 v51, v51, v62
	v_add_f32_e32 v62, -1.0, v61
	v_add_f32_e32 v63, 1.0, v61
	v_add_f32_e32 v64, 1.0, v62
	v_add_f32_e32 v65, -1.0, v63
	v_sub_f32_e32 v64, v61, v64
	v_sub_f32_e32 v61, v61, v65
	v_mul_f32_e32 v65, 0x3f317218, v50
	v_add_f32_e32 v64, v51, v64
	v_add_f32_e32 v51, v51, v61
	v_fma_f32 v61, v50, s18, -v65
	v_add_f32_e32 v68, v62, v64
	v_add_f32_e32 v69, v63, v51
	v_fmac_f32_e32 v61, 0xb102e308, v50
	v_sub_f32_e32 v50, v68, v62
	v_sub_f32_e32 v62, v69, v63
	v_rcp_f32_e32 v63, v69
	v_add_f32_e32 v70, v65, v61
	v_sub_f32_e32 v51, v51, v62
	v_sub_f32_e32 v62, v70, v65
	v_sub_f32_e32 v61, v61, v62
	v_mul_f32_e32 v62, v68, v63
	v_sub_f32_e32 v50, v64, v50
	v_mul_f32_e32 v64, v69, v62
	v_fma_f32 v65, v62, v69, -v64
	v_fmac_f32_e32 v65, v62, v51
	v_add_f32_e32 v71, v64, v65
	v_sub_f32_e32 v72, v68, v71
	v_sub_f32_e32 v64, v71, v64
	v_sub_f32_e32 v68, v68, v72
	v_sub_f32_e32 v64, v64, v65
	v_sub_f32_e32 v65, v68, v71
	v_add_f32_e32 v50, v50, v65
	v_add_f32_e32 v50, v64, v50
	v_add_f32_e32 v64, v72, v50
	v_mul_f32_e32 v65, v63, v64
	v_sub_f32_e32 v68, v72, v64
	v_mul_f32_e32 v71, v69, v65
	v_add_f32_e32 v50, v50, v68
	v_add_f32_e32 v68, v62, v65
	v_fma_f32 v69, v65, v69, -v71
	v_sub_f32_e32 v62, v68, v62
	v_fmac_f32_e32 v69, v65, v51
	v_sub_f32_e32 v51, v65, v62
	v_add_f32_e32 v62, v71, v69
	v_sub_f32_e32 v65, v62, v71
	v_sub_f32_e32 v71, v64, v62
	v_sub_f32_e32 v64, v64, v71
	v_sub_f32_e32 v62, v64, v62
	v_sub_f32_e32 v65, v65, v69
	v_add_f32_e32 v50, v50, v62
	v_add_f32_e32 v50, v65, v50
	v_add_f32_e32 v50, v71, v50
	v_mul_f32_e32 v50, v63, v50
	v_add_f32_e32 v50, v51, v50
	v_add_f32_e32 v51, v68, v50
	v_mul_f32_e32 v62, v51, v51
	v_fmamk_f32 v56, v62, 0x3e9b6dac, v56
	v_sub_f32_e32 v63, v51, v68
	v_ldexp_f32 v64, v51, 1
	v_mul_f32_e32 v51, v51, v62
	v_fmaak_f32 v56, v62, v56, 0x3f2aaada
	v_mul_f32_e32 v51, v51, v56
	v_add_f32_e32 v56, v64, v51
	v_sub_f32_e32 v50, v50, v63
	v_sub_f32_e32 v62, v56, v64
	v_ldexp_f32 v50, v50, 1
	v_sub_f32_e32 v51, v51, v62
	v_add_f32_e32 v50, v50, v51
	v_add_f32_e32 v51, v56, v50
	v_sub_f32_e32 v56, v51, v56
	v_add_f32_e32 v62, v70, v51
	v_sub_f32_e32 v50, v50, v56
	v_sub_f32_e32 v56, v62, v70
	v_sub_f32_e32 v63, v62, v56
	v_sub_f32_e32 v51, v51, v56
	v_add_f32_e32 v56, v61, v50
	v_sub_f32_e32 v63, v70, v63
	v_sub_f32_e32 v64, v56, v61
	v_add_f32_e32 v51, v51, v63
	v_sub_f32_e32 v63, v56, v64
	v_add_f32_e32 v51, v56, v51
	v_sub_f32_e32 v50, v50, v64
	v_sub_f32_e32 v61, v61, v63
	v_add_f32_e32 v56, v62, v51
	v_add_f32_e32 v50, v50, v61
	v_sub_f32_e32 v61, v56, v62
	v_sub_f32_e32 v51, v51, v61
	v_add_f32_e32 v50, v50, v51
	v_add_f32_e32 v50, v56, v50
	v_cmp_neq_f32_e32 vcc, s19, v54
	s_nop 1
	v_cndmask_b32_e32 v50, v57, v50, vcc
	v_cmp_ngt_f32_e32 vcc, -1.0, v54
	s_nop 1
	v_cndmask_b32_e32 v50, v58, v50, vcc
	v_cmp_neq_f32_e32 vcc, -1.0, v54
	s_nop 1
	v_cndmask_b32_e32 v50, v208, v50, vcc
	v_cmp_lt_f32_e64 vcc, |v54|, s22
	s_nop 1
	v_cndmask_b32_e32 v50, v50, v54, vcc
	v_sub_f32_e32 v50, v53, v50
	ds_bpermute_b32 v51, v55, v50
	v_add_u32_e32 v53, -2, v207
	v_cmp_lt_i32_e32 vcc, v53, v52
	v_xor_b32_e32 v54, 1, v207
	v_xor_b32_e32 v55, 4, v207
	v_cndmask_b32_e32 v53, v53, v207, vcc
	s_waitcnt lgkmcnt(0)
; __device__ __forceinline__ float wave_scan_add(float x, int lane) {
; #pragma unroll
;     for (int o = 1; o < 64; o <<= 1) { const float y = __shfl_up(x, o); if (lane >= o) x += y; }
;     return x;
; }
; __device__ __forceinline__ void mlstm_local_unit(const Params& P, int l, int h, int n, char* lds) {
;     ...
;         const float b = wave_scan_add(lf, lane);
;         const float g = __shfl(b, 63);
;         const float a = g - b + li;
;         const float ml = wave_max(a);
;         wl[lane] = __expf(a - ml);
;         if (lane == 0) { GM[(h * NCH + n) * 2] = g; GM[(h * NCH + n) * 2 + 1] = ml; }
	v_add_f32_e32 v51, v50, v51
	v_cmp_eq_u32_e32 vcc, 0, v87
	v_lshlrev_b32_e32 v53, 2, v53
	s_nop 0
	v_cndmask_b32_e32 v50, v51, v50, vcc
	ds_bpermute_b32 v51, v53, v50
	v_add_u32_e32 v53, -4, v207
	v_cmp_lt_i32_e64 s[8:9], v53, v52
	s_waitcnt lgkmcnt(0)
	v_add_f32_e32 v51, v50, v51
	v_cndmask_b32_e64 v53, v53, v207, s[8:9]
	v_cmp_gt_u32_e64 s[8:9], 2, v87
	v_lshlrev_b32_e32 v53, 2, v53
	s_nop 0
	v_cndmask_b32_e64 v50, v51, v50, s[8:9]
	ds_bpermute_b32 v51, v53, v50
	v_add_u32_e32 v53, -8, v207
	v_cmp_lt_i32_e64 s[8:9], v53, v52
	s_waitcnt lgkmcnt(0)
	v_add_f32_e32 v51, v50, v51
	v_cndmask_b32_e64 v53, v53, v207, s[8:9]
	v_cmp_gt_u32_e64 s[8:9], 4, v87
	v_lshlrev_b32_e32 v53, 2, v53
	s_nop 0
	v_cndmask_b32_e64 v50, v51, v50, s[8:9]
	ds_bpermute_b32 v51, v53, v50
	v_add_u32_e32 v53, -16, v207
	v_cmp_lt_i32_e64 s[8:9], v53, v52
	s_waitcnt lgkmcnt(0)
	v_add_f32_e32 v51, v50, v51
	v_cndmask_b32_e64 v53, v53, v207, s[8:9]
	v_cmp_gt_u32_e64 s[8:9], 8, v87
	v_lshlrev_b32_e32 v53, 2, v53
	s_nop 0
	v_cndmask_b32_e64 v50, v51, v50, s[8:9]
	ds_bpermute_b32 v51, v53, v50
	v_subrev_u32_e32 v53, 32, v207
	v_cmp_lt_i32_e64 s[8:9], v53, v52
	v_add_u32_e32 v52, 64, v52
	s_waitcnt lgkmcnt(0)
	v_add_f32_e32 v51, v50, v51
	v_cndmask_b32_e64 v53, v53, v207, s[8:9]
	v_cmp_gt_u32_e64 s[8:9], 16, v87
	v_lshlrev_b32_e32 v53, 2, v53
	s_nop 0
	v_cndmask_b32_e64 v50, v51, v50, s[8:9]
	ds_bpermute_b32 v51, v53, v50
	v_bfrev_b32_e32 v53, 0.5
	v_cmp_gt_u32_e64 s[8:9], 32, v87
	v_lshl_or_b32 v53, v207, 2, v53
	s_waitcnt lgkmcnt(0)
	v_add_f32_e32 v51, v50, v51
	v_cndmask_b32_e64 v51, v51, v50, s[8:9]
	ds_bpermute_b32 v50, v53, v51
	v_cmp_lt_i32_e64 s[8:9], v54, v52
	s_waitcnt lgkmcnt(0)
	v_sub_f32_e32 v51, v50, v51
	v_cndmask_b32_e64 v53, v207, v54, s[8:9]
	s_waitcnt vmcnt(0)
	v_add_f32_e32 v54, v59, v60
	v_lshlrev_b32_e32 v53, 2, v53
	v_add_f32_e32 v54, v54, v51
	ds_bpermute_b32 v51, v53, v54
	v_xor_b32_e32 v53, 2, v207
	v_cmp_lt_i32_e64 s[8:9], v53, v52
	s_waitcnt lgkmcnt(0)
	v_max_f32_e32 v51, v51, v51
	v_cndmask_b32_e64 v53, v207, v53, s[8:9]
	v_lshlrev_b32_e32 v53, 2, v53
	v_max_f32_e32 v51, v54, v51
	ds_bpermute_b32 v53, v53, v51
	v_cmp_lt_i32_e64 s[8:9], v55, v52
	s_waitcnt lgkmcnt(0)
	v_max_f32_e32 v53, v53, v53
	v_cndmask_b32_e64 v55, v207, v55, s[8:9]
	v_lshlrev_b32_e32 v55, 2, v55
	v_max_f32_e32 v51, v51, v53
	ds_bpermute_b32 v53, v55, v51
	v_xor_b32_e32 v55, 8, v207
	v_cmp_lt_i32_e64 s[8:9], v55, v52
	s_waitcnt lgkmcnt(0)
	v_max_f32_e32 v53, v53, v53
	v_cndmask_b32_e64 v55, v207, v55, s[8:9]
	v_lshlrev_b32_e32 v55, 2, v55
	v_max_f32_e32 v51, v51, v53
	ds_bpermute_b32 v53, v55, v51
	v_xor_b32_e32 v55, 16, v207
	v_cmp_lt_i32_e64 s[8:9], v55, v52
	s_waitcnt lgkmcnt(0)
	v_max_f32_e32 v53, v53, v53
	v_cndmask_b32_e64 v55, v207, v55, s[8:9]
	v_lshlrev_b32_e32 v55, 2, v55
	v_max_f32_e32 v51, v51, v53
	ds_bpermute_b32 v53, v55, v51
	v_xor_b32_e32 v55, 32, v207
	v_cmp_lt_i32_e64 s[8:9], v55, v52
	s_waitcnt lgkmcnt(0)
	v_max_f32_e32 v53, v53, v53
	v_cndmask_b32_e64 v52, v207, v55, s[8:9]
	v_max_f32_e32 v51, v51, v53
	v_lshlrev_b32_e32 v52, 2, v52
	ds_bpermute_b32 v52, v52, v51
	v_lshl_add_u32 v53, v87, 2, v209
	s_waitcnt lgkmcnt(0)
	v_max_f32_e32 v52, v52, v52
	v_max_f32_e32 v51, v51, v52
	v_sub_f32_e32 v52, v54, v51
	v_mul_f32_e32 v52, 0x3fb8aa3b, v52
	v_exp_f32_e32 v52, v52
	ds_write_b32 v53, v52 offset:55296
	s_and_saveexec_b64 s[8:9], vcc
	s_cbranch_execz .LBB0_2002
	s_mul_i32 s16, s30, 0x101
	s_add_i32 s16, s16, s31
	s_lshl_b32 s16, s16, 1
	s_ashr_i32 s17, s16, 31
	s_lshl_b64 s[16:17], s[16:17], 2
	s_add_u32 s16, s60, s16
	s_addc_u32 s17, s61, s17
	v_mov_b32_e32 v52, s16
	v_add_co_u32_e32 v52, vcc, 0x60000, v52
	v_mov_b32_e32 v53, s17
	s_nop 0
	v_addc_co_u32_e32 v53, vcc, 0, v53, vcc
	global_store_dwordx2 v[52:53], v[50:51], off

; __device__ __forceinline__ float bflo(unsigned w) { return __uint_as_float(w << 16); }
; __device__ __forceinline__ float bfhi(unsigned w) { return __uint_as_float(w & 0xffff0000u); }
; __device__ __forceinline__ void mlstm_local_unit(const Params& P, int l, int h, int n, char* lds) {
;     ...
;     for (int i = 0; i < 2; ++i) { const int idx = tid + 512 * i, t = idx >> 4, c = idx & 15; const int ch = C_MK + h * 128 + c * 8;
;         const f32x4 b0 = *(const f32x4*)(cb + ch), b1 = *(const f32x4*)(cb + ch + 4);
;         float a[8] = {b0[0], b0[1], b0[2], b0[3], b1[0], b1[1], b1[2], b1[3]};
; #pragma unroll
;         for (int k = 0; k < 4; ++k) { const u32x4 x = kx[i][k];
;             const f32x4 w0 = *(const f32x4*)(cw + k * 1024 + ch), w1 = *(const f32x4*)(cw + k * 1024 + ch + 4);
;             a[0] += w0[0] * bflo(x.x); a[1] += w0[1] * bfhi(x.x); a[2] += w0[2] * bflo(x.y); a[3] += w0[3] * bfhi(x.y);
;             a[4] += w1[0] * bflo(x.z); a[5] += w1[1] * bfhi(x.z); a[6] += w1[2] * bflo(x.w); a[7] += w1[3] * bfhi(x.w); }
;         const float w = wl[t];
.LBB0_2003:
	v_or_b32_e32 v50, s35, v88
	v_mov_b32_e32 v51, 0x800
	v_lshl_or_b32 v196, v50, 2, v51
	s_waitcnt lgkmcnt(0)
	v_lshl_add_u64 v[50:51], s[14:15], 0, v[196:197]
	s_mov_b64 s[8:9], 0x1000
	v_lshl_add_u64 v[64:65], v[50:51], 0, s[8:9]
	v_lshl_add_u64 v[76:77], s[12:13], 0, v[196:197]
	s_mov_b64 s[8:9], 0x4000
	v_lshl_add_u64 v[62:63], v[76:77], 0, s[8:9]
	s_movk_i32 s8, 0x1000
	v_add_co_u32_e32 v68, vcc, s8, v50
	s_movk_i32 s8, 0x4000
	s_nop 0
	v_addc_co_u32_e32 v69, vcc, 0, v51, vcc
	v_add_co_u32_e32 v70, vcc, s8, v76
	s_movk_i32 s8, 0x5000
	v_add_co_u32_e64 v72, s[8:9], s8, v76
	v_addc_co_u32_e32 v71, vcc, 0, v77, vcc
	s_nop 0
	v_addc_co_u32_e64 v73, s[8:9], 0, v77, s[8:9]
	s_movk_i32 s8, 0x6000
	s_barrier
	global_load_dwordx4 v[54:57], v[68:69], off
	global_load_dwordx4 v[50:53], v[64:65], off offset:16
	global_load_dwordx4 v[58:61], v[62:63], off offset:16
	global_load_dwordx4 v[90:93], v[72:73], off offset:16
	global_load_dwordx4 v[94:97], v[70:71], off
	global_load_dwordx4 v[98:101], v[72:73], off
	v_add_co_u32_e32 v74, vcc, s8, v76
	s_movk_i32 s8, 0x7000
	s_nop 0
	v_addc_co_u32_e32 v75, vcc, 0, v77, vcc
	global_load_dwordx4 v[102:105], v[74:75], off
	global_load_dwordx4 v[106:109], v[74:75], off offset:16
	v_add_co_u32_e32 v76, vcc, s8, v76
	s_waitcnt vmcnt(0)
	v_lshlrev_b32_e32 v119, 16, v43
	v_addc_co_u32_e32 v77, vcc, 0, v77, vcc
	global_load_dwordx4 v[110:113], v[76:77], off
	global_load_dwordx4 v[114:117], v[76:77], off offset:16
	v_and_b32_e32 v43, 0xffff0000, v43
	v_lshlrev_b32_e32 v118, 16, v42
	v_and_b32_e32 v42, 0xffff0000, v42
	v_lshlrev_b32_e32 v120, 16, v44
	v_and_b32_e32 v44, 0xffff0000, v44
	v_and_b32_e32 v125, 0xffff0000, v39
	v_lshlrev_b32_e32 v124, 16, v39
	v_lshlrev_b32_e32 v126, 16, v40
	v_and_b32_e32 v127, 0xffff0000, v40
	v_lshlrev_b32_e32 v121, 16, v45
	v_and_b32_e32 v45, 0xffff0000, v45
	v_lshlrev_b32_e32 v122, 16, v38
	v_and_b32_e32 v123, 0xffff0000, v38
	v_lshlrev_b32_e32 v128, 16, v41
	v_and_b32_e32 v41, 0xffff0000, v41
	v_lshlrev_b32_e32 v129, 16, v46
	v_and_b32_e32 v46, 0xffff0000, v46
	v_lshlrev_b32_e32 v130, 16, v47
	s_waitcnt lgkmcnt(0)
	v_fma_f32 v40, v58, v120, v50
	v_fmac_f32_e32 v57, v97, v43
	v_fma_f32 v39, v59, v44, v51
	v_fma_f32 v44, v95, v42, v55
	v_fmac_f32_e32 v57, v101, v125
	v_and_b32_e32 v42, 0xffff0000, v47
	v_fmac_f32_e32 v40, v90, v126
	v_fmac_f32_e32 v57, v105, v42
	v_lshlrev_b32_e32 v42, 16, v48
	v_fma_f32 v38, v60, v121, v52
	v_fmac_f32_e32 v53, v61, v45
	v_fmac_f32_e32 v39, v91, v127
	v_fmac_f32_e32 v40, v106, v42
	v_and_b32_e32 v42, 0xffff0000, v48
	v_fmac_f32_e32 v38, v92, v128
	v_fmac_f32_e32 v53, v93, v41
	v_fma_f32 v41, v94, v118, v54
	v_fmac_f32_e32 v39, v107, v42
	v_lshlrev_b32_e32 v42, 16, v49
	v_fma_f32 v45, v96, v119, v56
	v_fmac_f32_e32 v41, v98, v122
	v_fmac_f32_e32 v44, v99, v123
	v_fmac_f32_e32 v38, v108, v42
	v_and_b32_e32 v42, 0xffff0000, v49
	v_fmac_f32_e32 v45, v100, v124
	v_fmac_f32_e32 v41, v102, v129
	v_fmac_f32_e32 v44, v103, v46
	v_fmac_f32_e32 v53, v109, v42
	v_lshlrev_b32_e32 v42, 16, v34
	v_and_b32_e32 v34, 0xffff0000, v34
	v_fmac_f32_e32 v45, v104, v130
	s_waitcnt vmcnt(0)
	v_fmac_f32_e32 v41, v110, v42
	v_fmac_f32_e32 v44, v111, v34
	v_lshlrev_b32_e32 v34, 16, v35
	v_fmac_f32_e32 v45, v112, v34
	v_and_b32_e32 v34, 0xffff0000, v35
	v_mul_f32_e32 v35, 0xbfb8aa3b, v41
	v_exp_f32_e32 v35, v35
	v_fmac_f32_e32 v57, v113, v34
	v_lshlrev_b32_e32 v34, 16, v36
	v_fmac_f32_e32 v40, v114, v34
	v_and_b32_e32 v34, 0xffff0000, v36
	v_fmac_f32_e32 v39, v115, v34
	v_lshlrev_b32_e32 v34, 16, v37
	v_add_f32_e32 v35, 1.0, v35
	v_fmac_f32_e32 v38, v116, v34
	v_and_b32_e32 v34, 0xffff0000, v37
	v_div_scale_f32 v37, s[8:9], v35, v35, 1.0
	v_rcp_f32_e32 v42, v37
	v_fmac_f32_e32 v53, v117, v34
	v_lshl_add_u32 v34, v89, 2, v209
	ds_read_b32 v34, v34 offset:55296
	v_fma_f32 v46, -v37, v42, 1.0
	v_fmac_f32_e32 v42, v46, v42
	v_div_scale_f32 v46, vcc, 1.0, v35, 1.0
	v_mul_f32_e32 v47, v46, v42
	v_fma_f32 v48, -v37, v47, v46
	v_fmac_f32_e32 v47, v48, v42
	v_fma_f32 v37, -v37, v47, v46
	v_div_fmas_f32 v37, v37, v42, v47
	v_div_fixup_f32 v35, v37, v35, 1.0
	v_mul_f32_e32 v37, 0xbfb8aa3b, v44
	v_exp_f32_e32 v37, v37
	v_mul_f32_e32 v35, v41, v35
	v_add_u32_e32 v36, v89, v67
	v_and_b32_e32 v36, 62, v36
	v_add_f32_e32 v37, 1.0, v37
	v_div_scale_f32 v41, s[8:9], v37, v37, 1.0
	v_rcp_f32_e32 v46, v41
	v_lshrrev_b32_e32 v43, 3, v66
	v_lshl_add_u32 v36, v36, 1, v209
	v_and_b32_e32 v43, 2, v43
	s_waitcnt lgkmcnt(0)
; __device__ __forceinline__ unsigned cvt_pk_bf16(float lo, float hi) { unsigned r; asm volatile("v_cvt_pk_bf16_f32 %0, %1, %2" : "=v"(r) : "v"(lo), "v"(hi)); return r; }
; __device__ __forceinline__ float bflo(unsigned w) { return __uint_as_float(w << 16); }
; __device__ __forceinline__ float bfhi(unsigned w) { return __uint_as_float(w & 0xffff0000u); }
; __device__ __forceinline__ float sigmoidf(float x) { return 1.f / (1.f + __expf(-x)); }
; __device__ __forceinline__ int tsw(int row, int t) { return ((((t >> 1) + 4 * ((row >> 3) & 7)) & 31) << 1) | (t & 1); }
; __device__ __forceinline__ void mlstm_local_unit(const Params& P, int l, int h, int n, char* lds) {
;     ...
;     for (int i = 0; i < 2; ++i) { const int idx = tid + 512 * i, t = idx >> 4, c = idx & 15; const int ch = C_MK + h * 128 + c * 8;
;         const f32x4 b0 = *(const f32x4*)(cb + ch), b1 = *(const f32x4*)(cb + ch + 4);
;         float a[8] = {b0[0], b0[1], b0[2], b0[3], b1[0], b1[1], b1[2], b1[3]};
; #pragma unroll
;         for (int k = 0; k < 4; ++k) { const u32x4 x = kx[i][k];
;             const f32x4 w0 = *(const f32x4*)(cw + k * 1024 + ch), w1 = *(const f32x4*)(cw + k * 1024 + ch + 4);
;             a[0] += w0[0] * bflo(x.x); a[1] += w0[1] * bfhi(x.x); a[2] += w0[2] * bflo(x.y); a[3] += w0[3] * bfhi(x.y);
;             a[4] += w1[0] * bflo(x.z); a[5] += w1[1] * bfhi(x.z); a[6] += w1[2] * bflo(x.w); a[7] += w1[3] * bfhi(x.w); }
;         const float w = wl[t];
; #pragma unroll
;         for (int j = 0; j < 8; ++j) KT[(c * 8 + j) * 72 + tsw(c * 8, t)] = (bf16_t)(cvt_pk_bf16(a[j] * sigmoidf(a[j]) * w, 0.f) & 0xffffu); }
	v_mul_f32_e32 v35, v34, v35
	v_mul_u32_u24_e32 v42, 0x90, v88
	v_cvt_pk_bf16_f32 v35, v35, v197
	v_add3_u32 v36, v36, v43, v42
	ds_write_b16 v36, v35
	v_fma_f32 v35, -v41, v46, 1.0
	v_fmac_f32_e32 v46, v35, v46
	v_div_scale_f32 v35, vcc, 1.0, v37, 1.0
	v_mul_f32_e32 v43, v35, v46
	v_fma_f32 v47, -v41, v43, v35
	v_fmac_f32_e32 v43, v47, v46
	v_fma_f32 v35, -v41, v43, v35
	v_mul_f32_e32 v41, 0xbfb8aa3b, v45
	v_exp_f32_e32 v41, v41
	v_div_fmas_f32 v35, v35, v46, v43
	v_div_fixup_f32 v35, v35, v37, 1.0
	v_mul_f32_e32 v35, v44, v35
	v_add_f32_e32 v37, 1.0, v41
	v_div_scale_f32 v41, s[8:9], v37, v37, 1.0
	v_rcp_f32_e32 v43, v41
	v_mul_f32_e32 v35, v34, v35
	v_cvt_pk_bf16_f32 v35, v35, v197
	ds_write_b16 v36, v35 offset:144
	v_fma_f32 v35, -v41, v43, 1.0
	v_fmac_f32_e32 v43, v35, v43
	v_div_scale_f32 v35, vcc, 1.0, v37, 1.0
	v_mul_f32_e32 v44, v35, v43
	v_fma_f32 v46, -v41, v44, v35
	v_fmac_f32_e32 v44, v46, v43
	v_fma_f32 v35, -v41, v44, v35
	v_mul_f32_e32 v41, 0xbfb8aa3b, v57
	v_exp_f32_e32 v41, v41
	v_div_fmas_f32 v35, v35, v43, v44
	v_div_fixup_f32 v35, v35, v37, 1.0
	v_mul_f32_e32 v35, v45, v35
	v_add_f32_e32 v37, 1.0, v41
	v_div_scale_f32 v41, s[8:9], v37, v37, 1.0
	v_rcp_f32_e32 v43, v41
	v_mul_f32_e32 v35, v34, v35
	v_cvt_pk_bf16_f32 v35, v35, v197
	ds_write_b16 v36, v35 offset:288
	v_fma_f32 v35, -v41, v43, 1.0
	v_fmac_f32_e32 v43, v35, v43
	v_div_scale_f32 v35, vcc, 1.0, v37, 1.0
	v_mul_f32_e32 v44, v35, v43
	v_fma_f32 v45, -v41, v44, v35
	v_fmac_f32_e32 v44, v45, v43
	v_fma_f32 v35, -v41, v44, v35
	v_mul_f32_e32 v41, 0xbfb8aa3b, v40
	v_exp_f32_e32 v41, v41
	v_div_fmas_f32 v35, v35, v43, v44
	v_div_fixup_f32 v35, v35, v37, 1.0
	v_mul_f32_e32 v35, v57, v35
	v_add_f32_e32 v37, 1.0, v41
	v_div_scale_f32 v41, s[8:9], v37, v37, 1.0
	v_rcp_f32_e32 v43, v41
	v_mul_f32_e32 v35, v34, v35
	v_cvt_pk_bf16_f32 v35, v35, v197
	ds_write_b16 v36, v35 offset:432
	v_fma_f32 v35, -v41, v43, 1.0
	v_fmac_f32_e32 v43, v35, v43
	v_div_scale_f32 v35, vcc, 1.0, v37, 1.0
	v_mul_f32_e32 v44, v35, v43
	v_fma_f32 v45, -v41, v44, v35
	v_fmac_f32_e32 v44, v45, v43
	v_fma_f32 v35, -v41, v44, v35
	v_mul_f32_e32 v41, 0xbfb8aa3b, v39
	v_exp_f32_e32 v41, v41
	v_div_fmas_f32 v35, v35, v43, v44
	v_div_fixup_f32 v35, v35, v37, 1.0
	v_mul_f32_e32 v35, v40, v35
	v_add_f32_e32 v37, 1.0, v41
	v_div_scale_f32 v40, s[8:9], v37, v37, 1.0
	v_rcp_f32_e32 v41, v40
	v_mul_f32_e32 v35, v34, v35
	v_cvt_pk_bf16_f32 v35, v35, v197
	ds_write_b16 v36, v35 offset:576
	v_fma_f32 v35, -v40, v41, 1.0
	v_fmac_f32_e32 v41, v35, v41
	v_div_scale_f32 v35, vcc, 1.0, v37, 1.0
	v_mul_f32_e32 v43, v35, v41
	v_fma_f32 v44, -v40, v43, v35
	v_fmac_f32_e32 v43, v44, v41
	v_fma_f32 v35, -v40, v43, v35
	v_mul_f32_e32 v40, 0xbfb8aa3b, v38
	v_exp_f32_e32 v40, v40
	v_div_fmas_f32 v35, v35, v41, v43
	v_div_fixup_f32 v35, v35, v37, 1.0
	v_mul_f32_e32 v35, v39, v35
	v_add_f32_e32 v37, 1.0, v40
	v_div_scale_f32 v39, s[8:9], v37, v37, 1.0
	v_rcp_f32_e32 v40, v39
	v_mul_f32_e32 v35, v34, v35
	v_cvt_pk_bf16_f32 v35, v35, v197
	ds_write_b16 v36, v35 offset:720
	v_fma_f32 v35, -v39, v40, 1.0
	v_fmac_f32_e32 v40, v35, v40
	v_div_scale_f32 v35, vcc, 1.0, v37, 1.0
	v_mul_f32_e32 v41, v35, v40
	v_fma_f32 v43, -v39, v41, v35
	v_fmac_f32_e32 v41, v43, v40
	v_fma_f32 v35, -v39, v41, v35
	v_mul_f32_e32 v39, 0xbfb8aa3b, v53
	v_exp_f32_e32 v39, v39
	v_div_fmas_f32 v35, v35, v40, v41
	v_div_fixup_f32 v35, v35, v37, 1.0
	v_mul_f32_e32 v35, v38, v35
	v_add_f32_e32 v37, 1.0, v39
	v_div_scale_f32 v38, s[8:9], v37, v37, 1.0
	v_rcp_f32_e32 v39, v38
	v_mul_f32_e32 v35, v34, v35
	v_cvt_pk_bf16_f32 v35, v35, v197
	ds_write_b16 v36, v35 offset:864
	v_fma_f32 v35, -v38, v39, 1.0
	v_fmac_f32_e32 v39, v35, v39
	v_div_scale_f32 v35, vcc, 1.0, v37, 1.0
	v_mul_f32_e32 v40, v35, v39
	v_fma_f32 v41, -v38, v40, v35
	v_fmac_f32_e32 v40, v41, v39
	v_fma_f32 v35, -v38, v40, v35
	v_div_fmas_f32 v35, v35, v39, v40
	v_div_fixup_f32 v35, v35, v37, 1.0
	v_mul_f32_e32 v35, v53, v35
	v_mul_f32_e32 v34, v34, v35
	v_cvt_pk_bf16_f32 v34, v34, v197
	ds_write_b16 v36, v34 offset:1008
	global_load_dwordx4 v[38:41], v[68:69], off
	global_load_dwordx4 v[44:47], v[70:71], off
	global_load_dwordx4 v[34:37], v[64:65], off offset:16
	global_load_dwordx4 v[48:51], v[62:63], off offset:16
	global_load_dwordx4 v[52:55], v[72:73], off
	global_load_dwordx4 v[56:59], v[72:73], off offset:16
	s_nop 0
	global_load_dwordx4 v[60:63], v[74:75], off
	s_nop 0
	global_load_dwordx4 v[72:75], v[74:75], off offset:16
	s_nop 0
	global_load_dwordx4 v[88:91], v[76:77], off
	global_load_dwordx4 v[92:95], v[76:77], off offset:16
	v_lshlrev_b32_e32 v64, 16, v26
	v_and_b32_e32 v26, 0xffff0000, v26
	v_and_b32_e32 v70, 31, v66
	v_lshrrev_b32_e32 v43, 5, v87
	v_lshlrev_b32_e32 v196, 3, v43
	s_waitcnt vmcnt(0) lgkmcnt(0)
; __device__ __forceinline__ unsigned cvt_pk_bf16(float lo, float hi) { unsigned r; asm volatile("v_cvt_pk_bf16_f32 %0, %1, %2" : "=v"(r) : "v"(lo), "v"(hi)); return r; }
; __device__ __forceinline__ float bflo(unsigned w) { return __uint_as_float(w << 16); }
; __device__ __forceinline__ float bfhi(unsigned w) { return __uint_as_float(w & 0xffff0000u); }
; __device__ __forceinline__ float sigmoidf(float x) { return 1.f / (1.f + __expf(-x)); }
; __device__ __forceinline__ int tsw(int row, int t) { return ((((t >> 1) + 4 * ((row >> 3) & 7)) & 31) << 1) | (t & 1); }
; __device__ __forceinline__ void mlstm_local_unit(const Params& P, int l, int h, int n, char* lds) {
;     ...
;     for (int i = 0; i < 2; ++i) { const int idx = tid + 512 * i, t = idx >> 4, c = idx & 15; const int ch = C_MK + h * 128 + c * 8;
;         const f32x4 b0 = *(const f32x4*)(cb + ch), b1 = *(const f32x4*)(cb + ch + 4);
;         float a[8] = {b0[0], b0[1], b0[2], b0[3], b1[0], b1[1], b1[2], b1[3]};
; #pragma unroll
;         for (int k = 0; k < 4; ++k) { const u32x4 x = kx[i][k];
;             const f32x4 w0 = *(const f32x4*)(cw + k * 1024 + ch), w1 = *(const f32x4*)(cw + k * 1024 + ch + 4);
;             a[0] += w0[0] * bflo(x.x); a[1] += w0[1] * bfhi(x.x); a[2] += w0[2] * bflo(x.y); a[3] += w0[3] * bfhi(x.y);
;             a[4] += w1[0] * bflo(x.z); a[5] += w1[1] * bfhi(x.z); a[6] += w1[2] * bflo(x.w); a[7] += w1[3] * bfhi(x.w); }
;         const float w = wl[t];
; #pragma unroll
;         for (int j = 0; j < 8; ++j) KT[(c * 8 + j) * 72 + tsw(c * 8, t)] = (bf16_t)(cvt_pk_bf16(a[j] * sigmoidf(a[j]) * w, 0.f) & 0xffffu); }
	v_fma_f32 v39, v45, v26, v39
	v_lshlrev_b32_e32 v26, 16, v27
	v_fma_f32 v40, v46, v26, v40
	v_and_b32_e32 v26, 0xffff0000, v27
	v_fmac_f32_e32 v41, v47, v26
	v_lshlrev_b32_e32 v26, 16, v28
	v_fma_f32 v34, v48, v26, v34
	v_and_b32_e32 v26, 0xffff0000, v28
	v_and_b32_e32 v28, 0xffff0000, v29
	v_fmac_f32_e32 v37, v51, v28
	v_lshlrev_b32_e32 v28, 16, v22
	v_and_b32_e32 v22, 0xffff0000, v22
	v_fmac_f32_e32 v39, v53, v22
	v_lshlrev_b32_e32 v22, 16, v23
	v_fmac_f32_e32 v40, v54, v22
	v_and_b32_e32 v22, 0xffff0000, v23
	v_fmac_f32_e32 v41, v55, v22
	v_lshlrev_b32_e32 v22, 16, v24
	v_fma_f32 v27, v49, v26, v35
	v_lshlrev_b32_e32 v26, 16, v29
	v_fmac_f32_e32 v34, v56, v22
	v_and_b32_e32 v22, 0xffff0000, v24
	v_fma_f32 v26, v50, v26, v36
	v_fmac_f32_e32 v27, v57, v22
	v_lshlrev_b32_e32 v22, 16, v25
	v_fma_f32 v38, v44, v64, v38
	v_fmac_f32_e32 v26, v58, v22
	v_and_b32_e32 v22, 0xffff0000, v25
	v_fmac_f32_e32 v38, v52, v28
	v_fmac_f32_e32 v37, v59, v22
	v_lshlrev_b32_e32 v22, 16, v30
	v_fmac_f32_e32 v38, v60, v22
	v_and_b32_e32 v22, 0xffff0000, v30
	v_fmac_f32_e32 v39, v61, v22
	v_lshlrev_b32_e32 v22, 16, v31
	v_fmac_f32_e32 v40, v62, v22
	v_and_b32_e32 v22, 0xffff0000, v31
	v_fmac_f32_e32 v41, v63, v22
	v_lshlrev_b32_e32 v22, 16, v32
	v_fmac_f32_e32 v34, v72, v22
	v_and_b32_e32 v22, 0xffff0000, v32
	v_fmac_f32_e32 v27, v73, v22
	v_lshlrev_b32_e32 v22, 16, v33
	v_fmac_f32_e32 v26, v74, v22
	v_and_b32_e32 v22, 0xffff0000, v33
	v_fmac_f32_e32 v37, v75, v22
	v_lshlrev_b32_e32 v22, 16, v18
	v_and_b32_e32 v18, 0xffff0000, v18
	v_fmac_f32_e32 v38, v88, v22
	v_fmac_f32_e32 v39, v89, v18
	v_lshlrev_b32_e32 v18, 16, v19
	v_fmac_f32_e32 v40, v90, v18
	v_and_b32_e32 v18, 0xffff0000, v19
	v_mul_f32_e32 v19, 0xbfb8aa3b, v38
	v_exp_f32_e32 v19, v19
	v_fmac_f32_e32 v41, v91, v18
	v_lshlrev_b32_e32 v18, 16, v20
	v_fmac_f32_e32 v34, v92, v18
	v_and_b32_e32 v18, 0xffff0000, v20
	v_fmac_f32_e32 v27, v93, v18
	v_lshlrev_b32_e32 v18, 16, v21
	v_add_f32_e32 v19, 1.0, v19
	v_fmac_f32_e32 v26, v94, v18
	v_and_b32_e32 v18, 0xffff0000, v21
	v_div_scale_f32 v21, s[8:9], v19, v19, 1.0
	v_rcp_f32_e32 v22, v21
	v_fmac_f32_e32 v37, v95, v18
	v_lshl_add_u32 v18, v86, 2, v209
	ds_read_b32 v18, v18 offset:55296
	v_fma_f32 v24, -v21, v22, 1.0
	v_fmac_f32_e32 v22, v24, v22
	v_div_scale_f32 v24, vcc, 1.0, v19, 1.0
	v_mul_f32_e32 v25, v24, v22
	v_fma_f32 v28, -v21, v25, v24
	v_fmac_f32_e32 v25, v28, v22
	v_fma_f32 v21, -v21, v25, v24
	v_div_fmas_f32 v21, v21, v22, v25
	v_mul_f32_e32 v22, 0xbfb8aa3b, v39
	v_exp_f32_e32 v22, v22
	v_div_fixup_f32 v19, v21, v19, 1.0
	v_add_u32_e32 v20, v86, v67
	v_and_b32_e32 v20, 62, v20
	v_add_f32_e32 v21, 1.0, v22
	v_div_scale_f32 v22, s[8:9], v21, v21, 1.0
	v_rcp_f32_e32 v24, v22
	v_lshrrev_b32_e32 v23, 3, v78
	v_mul_f32_e32 v19, v38, v19
	v_lshl_add_u32 v20, v20, 1, v209
	v_and_b32_e32 v23, 2, v23
	s_waitcnt lgkmcnt(0)
	v_mul_f32_e32 v19, v18, v19
	v_cvt_pk_bf16_f32 v19, v19, v197
	v_add3_u32 v20, v20, v23, v42
	ds_write_b16 v20, v19
	v_fma_f32 v19, -v22, v24, 1.0
	v_fmac_f32_e32 v24, v19, v24
	v_div_scale_f32 v19, vcc, 1.0, v21, 1.0
	v_mul_f32_e32 v23, v19, v24
	v_fma_f32 v25, -v22, v23, v19
	v_fmac_f32_e32 v23, v25, v24
	v_fma_f32 v19, -v22, v23, v19
	v_mul_f32_e32 v22, 0xbfb8aa3b, v40
	v_exp_f32_e32 v22, v22
	v_div_fmas_f32 v19, v19, v24, v23
	v_div_fixup_f32 v19, v19, v21, 1.0
	v_mul_f32_e32 v19, v39, v19
	v_add_f32_e32 v21, 1.0, v22
	v_div_scale_f32 v22, s[8:9], v21, v21, 1.0
	v_rcp_f32_e32 v23, v22
	v_mul_f32_e32 v19, v18, v19
	v_cvt_pk_bf16_f32 v19, v19, v197
	ds_write_b16 v20, v19 offset:144
	v_fma_f32 v19, -v22, v23, 1.0
	v_fmac_f32_e32 v23, v19, v23
	v_div_scale_f32 v19, vcc, 1.0, v21, 1.0
	v_mul_f32_e32 v24, v19, v23
	v_fma_f32 v25, -v22, v24, v19
	v_fmac_f32_e32 v24, v25, v23
	v_fma_f32 v19, -v22, v24, v19
	v_mul_f32_e32 v22, 0xbfb8aa3b, v41
	v_exp_f32_e32 v22, v22
	v_div_fmas_f32 v19, v19, v23, v24
	v_div_fixup_f32 v19, v19, v21, 1.0
	v_mul_f32_e32 v19, v40, v19
	v_add_f32_e32 v21, 1.0, v22
	v_div_scale_f32 v22, s[8:9], v21, v21, 1.0
	v_rcp_f32_e32 v23, v22
	v_mul_f32_e32 v19, v18, v19
	v_cvt_pk_bf16_f32 v19, v19, v197
	ds_write_b16 v20, v19 offset:288
	v_fma_f32 v19, -v22, v23, 1.0
	v_fmac_f32_e32 v23, v19, v23
	v_div_scale_f32 v19, vcc, 1.0, v21, 1.0
	v_mul_f32_e32 v24, v19, v23
	v_fma_f32 v25, -v22, v24, v19
	v_fmac_f32_e32 v24, v25, v23
	v_fma_f32 v19, -v22, v24, v19
	v_mul_f32_e32 v22, 0xbfb8aa3b, v34
	v_exp_f32_e32 v22, v22
	v_div_fmas_f32 v19, v19, v23, v24
	v_div_fixup_f32 v19, v19, v21, 1.0
	v_mul_f32_e32 v19, v41, v19
	v_add_f32_e32 v21, 1.0, v22
	v_div_scale_f32 v22, s[8:9], v21, v21, 1.0
	v_rcp_f32_e32 v23, v22
	v_mul_f32_e32 v19, v18, v19
	v_cvt_pk_bf16_f32 v19, v19, v197
	ds_write_b16 v20, v19 offset:432
	v_fma_f32 v19, -v22, v23, 1.0
	v_fmac_f32_e32 v23, v19, v23
	v_div_scale_f32 v19, vcc, 1.0, v21, 1.0
	v_mul_f32_e32 v24, v19, v23
	v_fma_f32 v25, -v22, v24, v19
	v_fmac_f32_e32 v24, v25, v23
	v_fma_f32 v19, -v22, v24, v19
	v_mul_f32_e32 v22, 0xbfb8aa3b, v27
	v_exp_f32_e32 v22, v22
	v_div_fmas_f32 v19, v19, v23, v24
	v_div_fixup_f32 v19, v19, v21, 1.0
	v_mul_f32_e32 v19, v34, v19
	v_add_f32_e32 v21, 1.0, v22
	v_div_scale_f32 v22, s[8:9], v21, v21, 1.0
	v_rcp_f32_e32 v23, v22
	v_mul_f32_e32 v19, v18, v19
	v_cvt_pk_bf16_f32 v19, v19, v197
	ds_write_b16 v20, v19 offset:576
	v_fma_f32 v19, -v22, v23, 1.0
	v_fmac_f32_e32 v23, v19, v23
	v_div_scale_f32 v19, vcc, 1.0, v21, 1.0
	v_mul_f32_e32 v24, v19, v23
	v_fma_f32 v25, -v22, v24, v19
	v_fmac_f32_e32 v24, v25, v23
	v_fma_f32 v19, -v22, v24, v19
	v_mul_f32_e32 v22, 0xbfb8aa3b, v26
	v_exp_f32_e32 v22, v22
	v_div_fmas_f32 v19, v19, v23, v24
	v_div_fixup_f32 v19, v19, v21, 1.0
; __device__ __forceinline__ int tsw(int row, int t) { return ((((t >> 1) + 4 * ((row >> 3) & 7)) & 31) << 1) | (t & 1); }
; __device__ __forceinline__ void mlstm_local_unit(const Params& P, int l, int h, int n, char* lds) {
;     ...
; #pragma unroll
;     for (int i = 0; i < 4; ++i) { const int idx = tid + 512 * i, t = idx >> 5, c = idx & 31;
;         const u32x4 x = vx[i];
;         bf16_t* vp = VT + (c * 8) * 72 + tsw(c * 8, t);
;         vp[0] = (bf16_t)(x.x & 0xffffu); vp[72] = (bf16_t)(x.x >> 16); vp[144] = (bf16_t)(x.y & 0xffffu); vp[216] = (bf16_t)(x.y >> 16);
;         vp[288] = (bf16_t)(x.z & 0xffffu); vp[360] = (bf16_t)(x.z >> 16); vp[432] = (bf16_t)(x.w & 0xffffu); vp[504] = (bf16_t)(x.w >> 16); }
;     __syncthreads();
;     const int db = wid & 3, eb0 = (wid >> 2) * 4;
;     f32x16 acc[4] = {};
; #pragma unroll
;     for (int ks = 0; ks < 4; ++ks) { const bf16x8 A = *(const bf16x8*)(KT + (32 * db + r32) * 72 + tsw(32 * db + r32, 16 * ks + 8 * hi));
; #pragma unroll
;         for (int j = 0; j < 4; ++j) { const bf16x8 B = *(const bf16x8*)(VT + (32 * (eb0 + j) + r32) * 72 + tsw(32 * (eb0 + j) + r32, 16 * ks + 8 * hi));
;             acc[j] = __builtin_amdgcn_mfma_f32_32x32x16_bf16(A, B, acc[j], 0, 0, 0); } }
	v_mul_f32_e32 v19, v27, v19
	v_add_f32_e32 v21, 1.0, v22
	v_div_scale_f32 v22, s[8:9], v21, v21, 1.0
	v_rcp_f32_e32 v23, v22
	v_mul_f32_e32 v19, v18, v19
	v_cvt_pk_bf16_f32 v19, v19, v197
	ds_write_b16 v20, v19 offset:720
	v_fma_f32 v19, -v22, v23, 1.0
	v_fmac_f32_e32 v23, v19, v23
	v_div_scale_f32 v19, vcc, 1.0, v21, 1.0
	v_mul_f32_e32 v24, v19, v23
	v_fma_f32 v25, -v22, v24, v19
	v_fmac_f32_e32 v24, v25, v23
	v_fma_f32 v19, -v22, v24, v19
	v_mul_f32_e32 v22, 0xbfb8aa3b, v37
	v_exp_f32_e32 v22, v22
	v_div_fmas_f32 v19, v19, v23, v24
	v_div_fixup_f32 v19, v19, v21, 1.0
	v_mul_f32_e32 v19, v26, v19
	v_add_f32_e32 v21, 1.0, v22
	v_div_scale_f32 v22, s[8:9], v21, v21, 1.0
	v_rcp_f32_e32 v23, v22
	v_mul_f32_e32 v19, v18, v19
	v_cvt_pk_bf16_f32 v19, v19, v197
	ds_write_b16 v20, v19 offset:864
	v_fma_f32 v19, -v22, v23, 1.0
	v_fmac_f32_e32 v23, v19, v23
	v_div_scale_f32 v19, vcc, 1.0, v21, 1.0
	v_mul_f32_e32 v24, v19, v23
	v_fma_f32 v25, -v22, v24, v19
	v_fmac_f32_e32 v24, v25, v23
	v_fma_f32 v19, -v22, v24, v19
	v_div_fmas_f32 v19, v19, v23, v24
	v_div_fixup_f32 v19, v19, v21, 1.0
	v_mul_f32_e32 v19, v37, v19
	v_mul_f32_e32 v18, v18, v19
	v_add_u32_e32 v19, v85, v67
	v_cvt_pk_bf16_f32 v18, v18, v197
	ds_write_b16 v20, v18 offset:1008
	v_and_b32_e32 v19, 62, v19
	v_lshrrev_b32_e32 v20, 4, v66
	v_mad_u32_u24 v18, v84, s45, v209
	v_lshlrev_b32_e32 v19, 1, v19
	v_and_b32_e32 v20, 2, v20
	v_add3_u32 v19, v18, v19, v20
	ds_write_b16 v19, v14 offset:18432
	ds_write_b16_d16_hi v19, v14 offset:18576
	ds_write_b16 v19, v15 offset:18720
	ds_write_b16_d16_hi v19, v15 offset:18864
	ds_write_b16 v19, v16 offset:19008
	ds_write_b16_d16_hi v19, v16 offset:19152
	ds_write_b16 v19, v17 offset:19296
	ds_write_b16_d16_hi v19, v17 offset:19440
	v_add_u32_e32 v14, v83, v67
	v_and_b32_e32 v14, 62, v14
	v_lshrrev_b32_e32 v15, 4, v78
	v_lshlrev_b32_e32 v14, 1, v14
	v_and_b32_e32 v15, 2, v15
	v_add3_u32 v14, v18, v14, v15
	ds_write_b16 v14, v6 offset:18432
	ds_write_b16_d16_hi v14, v6 offset:18576
	ds_write_b16 v14, v7 offset:18720
	ds_write_b16_d16_hi v14, v7 offset:18864
	ds_write_b16 v14, v8 offset:19008
	ds_write_b16_d16_hi v14, v8 offset:19152
	ds_write_b16 v14, v9 offset:19296
	ds_write_b16_d16_hi v14, v9 offset:19440
	v_add_u32_e32 v6, v82, v67
	v_and_b32_e32 v6, 62, v6
	v_lshrrev_b32_e32 v7, 4, v81
	v_lshlrev_b32_e32 v6, 1, v6
	v_and_b32_e32 v7, 2, v7
	v_add3_u32 v6, v18, v6, v7
	ds_write_b16 v6, v10 offset:18432
	ds_write_b16_d16_hi v6, v10 offset:18576
	ds_write_b16 v6, v11 offset:18720
	ds_write_b16_d16_hi v6, v11 offset:18864
	ds_write_b16 v6, v12 offset:19008
	ds_write_b16_d16_hi v6, v12 offset:19152
	ds_write_b16 v6, v13 offset:19296
	ds_write_b16_d16_hi v6, v13 offset:19440
	v_add_u32_e32 v6, v80, v67
	v_and_b32_e32 v6, 62, v6
	v_lshrrev_b32_e32 v7, 4, v79
	v_lshlrev_b32_e32 v6, 1, v6
	v_and_b32_e32 v7, 2, v7
	s_ashr_i32 s8, s34, 6
	v_add3_u32 v6, v18, v6, v7
	s_and_b32 s17, s8, -4
	s_lshr_b32 s9, s34, 1
	ds_write_b16 v6, v2 offset:18432
	ds_write_b16_d16_hi v6, v2 offset:18576
	ds_write_b16 v6, v3 offset:18720
	ds_write_b16_d16_hi v6, v3 offset:18864
	ds_write_b16 v6, v4 offset:19008
	ds_write_b16_d16_hi v6, v4 offset:19152
	ds_write_b16 v6, v5 offset:19296
	ds_write_b16_d16_hi v6, v5 offset:19440
	s_and_b32 s18, s9, 0x60
	v_lshl_or_b32 v2, s17, 5, v70
	v_or_b32_e32 v67, s18, v70
	v_mul_lo_u32 v2, v2, s45
	v_add_u32_e32 v69, 0x100, v2
	v_add_u32_e32 v2, v67, v196
	v_mad_u32_u24 v68, v67, s45, v209
	v_and_b32_e32 v2, 56, v2
	v_lshl_add_u32 v2, v2, 1, v68
	s_waitcnt lgkmcnt(0)
	s_barrier
	ds_read_b128 v[2:5], v2
	v_add_u32_e32 v6, v196, v70
	v_and_b32_e32 v6, 56, v6
	v_lshlrev_b32_e32 v10, 1, v6
	v_add_u32_e32 v6, v69, v10
	ds_read_b128 v[6:9], v6 offset:18432
	s_or_b32 s15, s17, 2
	v_lshl_or_b32 v11, s15, 5, v70
	s_or_b32 s16, s17, 1
	v_mul_lo_u32 v11, v11, s45
	v_lshl_or_b32 v71, s16, 5, v70
	v_add_u32_e32 v85, 0x100, v11
	s_waitcnt lgkmcnt(0)
	v_mfma_f32_32x32x16_bf16 v[50:65], v[2:5], v[6:9], 0
	v_mul_lo_u32 v6, v71, s45
	v_add_u32_e32 v10, v85, v10
	v_add_u32_e32 v84, 0x100, v6
	v_add_u32_e32 v6, v71, v196
	ds_read_b128 v[10:13], v10 offset:18432
	v_and_b32_e32 v6, 56, v6
	v_or_b32_e32 v88, 16, v196
	v_lshl_add_u32 v6, v6, 1, v84
	v_add_u32_e32 v80, v71, v88
	ds_read_b128 v[6:9], v6 offset:18432
	v_and_b32_e32 v80, 56, v80
	v_lshl_add_u32 v80, v80, 1, v84
	ds_read_b128 v[80:83], v80 offset:18432
	s_waitcnt lgkmcnt(2)
	v_mfma_f32_32x32x16_bf16 v[18:33], v[2:5], v[10:13], 0
	v_add_u32_e32 v10, v67, v88
	s_or_b32 s14, s8, 3
	v_and_b32_e32 v10, 56, v10
	v_lshl_or_b32 v86, s14, 5, v70
	v_lshl_add_u32 v10, v10, 1, v68
	ds_read_b128 v[72:75], v10
	v_add_u32_e32 v76, v88, v70
	s_waitcnt lgkmcnt(2)
	v_mfma_f32_32x32x16_bf16 v[34:49], v[2:5], v[6:9], 0
	v_mul_lo_u32 v6, v86, s45
	v_add_u32_e32 v87, 0x100, v6
	v_add_u32_e32 v6, v86, v196
	v_and_b32_e32 v6, 56, v6
	v_lshl_add_u32 v6, v6, 1, v87
	v_and_b32_e32 v76, 56, v76
	ds_read_b128 v[6:9], v6 offset:18432
	v_lshlrev_b32_e32 v89, 1, v76
	v_add_u32_e32 v76, v69, v89
	ds_read_b128 v[76:79], v76 offset:18432
	s_waitcnt lgkmcnt(1)
	v_mfma_f32_32x32x16_bf16 v[2:17], v[2:5], v[6:9], 0
	s_movk_i32 s8, 0x7f
	v_cmp_lt_i32_e32 vcc, s8, v66
	v_mfma_f32_32x32x16_bf16 v[34:49], v[72:75], v[80:83], v[34:49]
	v_add_u32_e32 v80, v86, v88
	v_and_b32_e32 v80, 56, v80
	v_lshl_add_u32 v80, v80, 1, v87
	ds_read_b128 v[80:83], v80 offset:18432
	v_or_b32_e32 v88, 32, v196
	s_waitcnt lgkmcnt(1)
	v_mfma_f32_32x32x16_bf16 v[50:65], v[72:75], v[76:79], v[50:65]
	v_add_u32_e32 v76, v85, v89
	ds_read_b128 v[76:79], v76 offset:18432
	s_waitcnt lgkmcnt(0)
; __device__ __forceinline__ int tsw(int row, int t) { return ((((t >> 1) + 4 * ((row >> 3) & 7)) & 31) << 1) | (t & 1); }
; __device__ __forceinline__ void mlstm_local_unit(const Params& P, int l, int h, int n, char* lds) {
;     ...
;     for (int ks = 0; ks < 4; ++ks) { const bf16x8 A = *(const bf16x8*)(KT + (32 * db + r32) * 72 + tsw(32 * db + r32, 16 * ks + 8 * hi));
; #pragma unroll
;         for (int j = 0; j < 4; ++j) { const bf16x8 B = *(const bf16x8*)(VT + (32 * (eb0 + j) + r32) * 72 + tsw(32 * (eb0 + j) + r32, 16 * ks + 8 * hi));
;             acc[j] = __builtin_amdgcn_mfma_f32_32x32x16_bf16(A, B, acc[j], 0, 0, 0); } }
;     if (tid < 128) { float s = 0.f;
	v_mfma_f32_32x32x16_bf16 v[18:33], v[72:75], v[76:79], v[18:33]
	v_add_u32_e32 v76, v88, v70
	v_and_b32_e32 v76, 56, v76
	v_mfma_f32_32x32x16_bf16 v[2:17], v[72:75], v[80:83], v[2:17]
	v_add_u32_e32 v72, v67, v88
	v_and_b32_e32 v72, 56, v72
	v_lshl_add_u32 v72, v72, 1, v68
	ds_read_b128 v[72:75], v72
	v_lshlrev_b32_e32 v80, 1, v76
	v_add_u32_e32 v76, v69, v80
	ds_read_b128 v[76:79], v76 offset:18432
	v_add_u32_e32 v80, v85, v80
	s_waitcnt lgkmcnt(0)
	v_mfma_f32_32x32x16_bf16 v[50:65], v[72:75], v[76:79], v[50:65]
	v_add_u32_e32 v76, v71, v88
	v_and_b32_e32 v76, 56, v76
	v_lshl_add_u32 v76, v76, 1, v84
	ds_read_b128 v[76:79], v76 offset:18432
	ds_read_b128 v[80:83], v80 offset:18432
	s_waitcnt lgkmcnt(1)
	v_mfma_f32_32x32x16_bf16 v[34:49], v[72:75], v[76:79], v[34:49]
	v_add_u32_e32 v76, v86, v88
	v_or_b32_e32 v88, 48, v196
	v_and_b32_e32 v76, 56, v76
	v_add_u32_e32 v67, v67, v88
	v_lshl_add_u32 v76, v76, 1, v87
	v_and_b32_e32 v67, 56, v67
	ds_read_b128 v[76:79], v76 offset:18432
	v_lshl_add_u32 v67, v67, 1, v68
	s_waitcnt lgkmcnt(1)
	v_mfma_f32_32x32x16_bf16 v[18:33], v[72:75], v[80:83], v[18:33]
	ds_read_b128 v[80:83], v67
	v_add_u32_e32 v67, v88, v70
	v_and_b32_e32 v67, 56, v67
	v_lshlrev_b32_e32 v67, 1, v67
	v_add_u32_e32 v68, v69, v67
	v_add_u32_e32 v67, v85, v67
	s_waitcnt lgkmcnt(1)
	v_mfma_f32_32x32x16_bf16 v[2:17], v[72:75], v[76:79], v[2:17]
	ds_read_b128 v[72:75], v68 offset:18432
	v_add_u32_e32 v68, v71, v88
	v_and_b32_e32 v68, 56, v68
	v_lshl_add_u32 v68, v68, 1, v84
	ds_read_b128 v[76:79], v68 offset:18432
	s_waitcnt lgkmcnt(1)
	v_mfma_f32_32x32x16_bf16 v[50:65], v[80:83], v[72:75], v[50:65]
	ds_read_b128 v[72:75], v67 offset:18432
	v_add_u32_e32 v67, v86, v88
	v_and_b32_e32 v67, 56, v67
	v_lshl_add_u32 v67, v67, 1, v87
	s_waitcnt lgkmcnt(1)
	v_mfma_f32_32x32x16_bf16 v[34:49], v[80:83], v[76:79], v[34:49]
	ds_read_b128 v[76:79], v67 offset:18432
	s_waitcnt lgkmcnt(1)
	v_mfma_f32_32x32x16_bf16 v[18:33], v[80:83], v[72:75], v[18:33]
	s_waitcnt lgkmcnt(0)
	v_mfma_f32_32x32x16_bf16 v[2:17], v[80:83], v[76:79], v[2:17]
	s_and_saveexec_b64 s[8:9], vcc
	s_xor_b64 s[8:9], exec, s[8:9]
	s_mul_i32 s12, s30, 0x101
	s_add_i32 s12, s12, s31
	s_ashr_i32 s13, s12, 31
	s_or_saveexec_b64 s[8:9], s[8:9]
	v_mov_b64_e32 v[68:69], s[12:13]
	s_xor_b64 exec, exec, s[8:9]
	s_cbranch_execz .LBB0_1978
; __device__ __forceinline__ float bflo(unsigned w) { return __uint_as_float(w << 16); }
; __device__ __forceinline__ float bfhi(unsigned w) { return __uint_as_float(w & 0xffff0000u); }
; __device__ __forceinline__ void mlstm_local_unit(const Params& P, int l, int h, int n, char* lds) {
;     ...
;     if (tid < 128) { float s = 0.f;
; #pragma unroll
;         for (int q = 0; q < 8; ++q) { const u32x4 x = *(const u32x4*)(KT + tid * 72 + 8 * q);
;             s += (bflo(x.x) + bfhi(x.x)) + (bflo(x.y) + bfhi(x.y)) + (bflo(x.z) + bfhi(x.z)) + (bflo(x.w) + bfhi(x.w)); }
;         NLOC[(size_t)(h * NCH + n) * 128 + tid] = s; }
	v_mul_lo_u32 v67, v66, s45
	v_add_u32_e32 v67, 0x100, v67
	ds_read_b128 v[72:75], v67 offset:16
	ds_read_b128 v[76:79], v67
	ds_read_b128 v[80:83], v67 offset:32
	ds_read_b128 v[84:87], v67 offset:48
	s_mul_i32 s12, s30, 0x101
	s_waitcnt lgkmcnt(3)
	v_lshlrev_b32_e32 v69, 16, v72
	s_waitcnt lgkmcnt(2)
	v_lshlrev_b32_e32 v68, 16, v76
	v_and_b32_e32 v89, 0xffff0000, v72
	v_and_b32_e32 v88, 0xffff0000, v76
	v_pk_add_f32 v[68:69], v[68:69], v[88:89]
	v_lshlrev_b32_e32 v89, 16, v73
	v_lshlrev_b32_e32 v88, 16, v77
	v_and_b32_e32 v73, 0xffff0000, v73
	v_and_b32_e32 v72, 0xffff0000, v77
	v_pk_add_f32 v[72:73], v[88:89], v[72:73]
	v_and_b32_e32 v77, 0xffff0000, v74
	v_pk_add_f32 v[68:69], v[68:69], v[72:73]
	v_lshlrev_b32_e32 v73, 16, v74
	v_lshlrev_b32_e32 v72, 16, v78
	v_and_b32_e32 v76, 0xffff0000, v78
	v_pk_add_f32 v[72:73], v[72:73], v[76:77]
	v_and_b32_e32 v74, 0xffff0000, v79
	v_pk_add_f32 v[68:69], v[72:73], v[68:69]
	v_lshlrev_b32_e32 v73, 16, v75
	v_lshlrev_b32_e32 v72, 16, v79
	v_and_b32_e32 v75, 0xffff0000, v75
	v_pk_add_f32 v[72:73], v[72:73], v[74:75]
	s_waitcnt lgkmcnt(1)
	v_and_b32_e32 v75, 0xffff0000, v81
	v_pk_add_f32 v[68:69], v[72:73], v[68:69]
	v_lshlrev_b32_e32 v73, 16, v81
	v_lshlrev_b32_e32 v72, 16, v80
	v_and_b32_e32 v74, 0xffff0000, v80
	v_pk_add_f32 v[72:73], v[72:73], v[74:75]
	v_lshlrev_b32_e32 v75, 16, v83
	v_lshlrev_b32_e32 v74, 16, v82
	v_and_b32_e32 v77, 0xffff0000, v83
	v_and_b32_e32 v76, 0xffff0000, v82
	v_pk_add_f32 v[72:73], v[72:73], v[72:73] op_sel:[0,1] op_sel_hi:[1,0]
	v_pk_add_f32 v[80:81], v[74:75], v[76:77]
	v_add_f32_e32 v68, 0, v68
	v_pk_add_f32 v[82:83], v[80:81], v[72:73]
	ds_read_b128 v[72:75], v67 offset:64
	ds_read_b128 v[76:79], v67 offset:80
	v_add_f32_e32 v68, v68, v69
	s_waitcnt lgkmcnt(2)
	v_lshlrev_b32_e32 v69, 16, v84
	v_and_b32_e32 v71, 0xffff0000, v84
	v_add_f32_e32 v84, v69, v71
	v_lshlrev_b32_e32 v69, 16, v85
	v_and_b32_e32 v71, 0xffff0000, v85
	v_add_f32_e32 v88, v69, v71
	s_waitcnt lgkmcnt(1)
	v_lshlrev_b32_e32 v85, 16, v73
	v_and_b32_e32 v89, 0xffff0000, v73
	v_lshlrev_b32_e32 v91, 16, v72
	v_lshlrev_b32_e32 v90, 16, v86
	v_and_b32_e32 v73, 0xffff0000, v72
	v_and_b32_e32 v72, 0xffff0000, v86
	v_pk_add_f32 v[72:73], v[90:91], v[72:73]
	v_pk_add_f32 v[84:85], v[84:85], v[88:89]
	v_lshlrev_b32_e32 v69, 16, v75
	v_pk_add_f32 v[72:73], v[72:73], v[84:85]
	v_pk_mov_b32 v[84:85], v[86:87], v[74:75] op_sel:[1,0]
	v_and_b32_e32 v71, 0xffff0000, v75
	v_lshlrev_b32_e32 v75, 16, v74
	v_lshlrev_b32_e32 v74, 16, v87
	v_and_b32_e32 v85, 0xffff0000, v85
	v_and_b32_e32 v84, 0xffff0000, v84
	v_pk_add_f32 v[74:75], v[74:75], v[84:85]
	s_add_i32 s12, s12, s31
	v_pk_add_f32 v[72:73], v[74:75], v[72:73]
	v_pk_add_f32 v[74:75], v[80:81], v[82:83] op_sel:[1,0] op_sel_hi:[0,1]
	v_mov_b32_e32 v75, v71
	v_pk_add_f32 v[68:69], v[68:69], v[74:75]
	s_waitcnt lgkmcnt(0)
	v_and_b32_e32 v75, 0xffff0000, v77
	v_pk_add_f32 v[68:69], v[68:69], v[72:73]
	v_lshlrev_b32_e32 v73, 16, v77
	v_lshlrev_b32_e32 v72, 16, v76
	v_and_b32_e32 v74, 0xffff0000, v76
	v_pk_add_f32 v[72:73], v[72:73], v[74:75]
	v_lshlrev_b32_e32 v81, 16, v79
	v_pk_add_f32 v[76:77], v[72:73], v[72:73] op_sel:[0,1] op_sel_hi:[1,0]
	v_lshlrev_b32_e32 v80, 16, v78
	v_and_b32_e32 v79, 0xffff0000, v79
	ds_read_b128 v[72:75], v67 offset:96
	v_and_b32_e32 v78, 0xffff0000, v78
	v_pk_add_f32 v[80:81], v[80:81], v[78:79]
	s_ashr_i32 s13, s12, 31
	v_pk_add_f32 v[82:83], v[80:81], v[76:77]
	ds_read_b128 v[76:79], v67 offset:112
	s_waitcnt lgkmcnt(1)
	v_lshlrev_b32_e32 v67, 16, v72
	v_and_b32_e32 v71, 0xffff0000, v72
	v_add_f32_e32 v72, v67, v71
	v_lshlrev_b32_e32 v67, 16, v73
	v_and_b32_e32 v71, 0xffff0000, v73
	v_add_f32_e32 v84, v67, v71
	s_waitcnt lgkmcnt(0)
	v_lshlrev_b32_e32 v73, 16, v77
	v_and_b32_e32 v85, 0xffff0000, v77
	v_lshlrev_b32_e32 v87, 16, v76
	v_lshlrev_b32_e32 v86, 16, v74
	v_and_b32_e32 v77, 0xffff0000, v76
	v_and_b32_e32 v76, 0xffff0000, v74
	v_pk_add_f32 v[76:77], v[86:87], v[76:77]
	v_pk_add_f32 v[72:73], v[72:73], v[84:85]
	v_lshlrev_b32_e32 v67, 16, v79
	v_pk_add_f32 v[72:73], v[76:77], v[72:73]
	v_pk_mov_b32 v[76:77], v[74:75], v[78:79] op_sel:[1,0]
	v_and_b32_e32 v71, 0xffff0000, v79
	v_lshlrev_b32_e32 v79, 16, v78
	v_lshlrev_b32_e32 v78, 16, v75
	v_and_b32_e32 v75, 0xffff0000, v77
	v_and_b32_e32 v74, 0xffff0000, v76
	v_pk_add_f32 v[74:75], v[78:79], v[74:75]
	s_lshl_b64 s[30:31], s[12:13], 9
	v_pk_add_f32 v[72:73], v[74:75], v[72:73]
	v_pk_add_f32 v[68:69], v[68:69], v[68:69] op_sel:[0,1] op_sel_hi:[1,0]
	v_pk_add_f32 v[74:75], v[80:81], v[82:83] op_sel:[1,0] op_sel_hi:[0,1]
	s_add_u32 s30, s60, s30
	v_mov_b32_e32 v69, v67
	v_mov_b32_e32 v75, v71
	v_ashrrev_i32_e32 v67, 31, v66
	s_addc_u32 s31, s61, s31
	v_pk_add_f32 v[68:69], v[68:69], v[74:75]
	v_lshl_add_u64 v[66:67], v[66:67], 2, s[30:31]
	v_pk_add_f32 v[68:69], v[68:69], v[72:73]
	v_add_co_u32_e32 v66, vcc, 0x100000, v66
	v_add_f32_e32 v68, v68, v69
	s_nop 0
	v_addc_co_u32_e32 v67, vcc, 0, v67, vcc
	flat_store_dword v[66:67], v68
	v_mov_b64_e32 v[68:69], s[12:13]
	s_branch .LBB0_1978

; __device__ __forceinline__ float bflo(unsigned w) { return __uint_as_float(w << 16); }
; __device__ __forceinline__ float bfhi(unsigned w) { return __uint_as_float(w & 0xffff0000u); }
; #define PACK_CARRY() (u32x4){cvt_pk_bf16(c0, c1), cvt_pk_bf16(c2, c3), cvt_pk_bf16(c4, c5), cvt_pk_bf16(c6, c7)}
; __device__ __forceinline__ void mlstm_scan_item(const Params& P, int item) {
;     ...
;         for (int j = 0; j < 16; ++j) { const int n = n0 + j; const float g = GM[n * 2], ml = GM[n * 2 + 1];
;             *(u32x4*)(p + (size_t)n * 32768) = PACK_CARRY();
;             if (hasn) np[(size_t)n * 128] = ncar;
;             if (wm) MPREV[n] = m;
;             const float mn = fmaxf(g + m, ml), sp = __expf(g + m - mn), sq = __expf(ml - mn);
;             c0 = sp * c0 + sq * bflo(cl[j].x); c1 = sp * c1 + sq * bfhi(cl[j].x); c2 = sp * c2 + sq * bflo(cl[j].y); c3 = sp * c3 + sq * bfhi(cl[j].y);
;             c4 = sp * c4 + sq * bflo(cl[j].z); c5 = sp * c5 + sq * bfhi(cl[j].z); c6 = sp * c6 + sq * bflo(cl[j].w); c7 = sp * c7 + sq * bfhi(cl[j].w);
;             ncar = sp * ncar + sq * nl[j]; m = mn; }
.LBB0_2090:
	s_or_b64 exec, exec, s[18:19]
	v_add_co_u32_e32 v16, vcc, 0x60000, v84
	v_add_f32_e32 v15, v42, v26
	v_addc_co_u32_e32 v17, vcc, 0, v85, vcc
	v_mov_b32_e32 v18, v240
	v_mov_b32_e32 v19, v241
	v_max_f32_e32 v16, v27, v27
	v_max_f32_e32 v40, v15, v16
	v_sub_f32_e32 v16, v27, v40
	v_sub_f32_e32 v15, v15, v40
	v_mul_f32_e32 v16, 0x3fb8aa3b, v16
	v_mul_f32_e32 v15, 0x3fb8aa3b, v15
	v_exp_f32_e32 v21, v16
	v_exp_f32_e32 v42, v15
	v_lshlrev_b32_e32 v43, 16, v10
	s_mov_b64 s[18:19], 0x1aee0000
	v_mul_f32_e32 v16, v21, v43
	v_pk_fma_f32 v[16:17], v[20:21], v[42:43], v[16:17] op_sel_hi:[1,1,0]
	v_and_b32_e32 v43, 0xffff0000, v10
	v_mov_b32_e32 v39, v21
	v_mul_f32_e32 v10, v21, v43
	v_pk_fma_f32 v[38:39], v[38:39], v[42:43], v[10:11] op_sel_hi:[1,1,0]
	v_lshlrev_b32_e32 v43, 16, v11
	v_mov_b32_e32 v37, v21
	v_mul_f32_e32 v10, v21, v43
	v_pk_fma_f32 v[28:29], v[36:37], v[42:43], v[10:11] op_sel_hi:[1,1,0]
	v_and_b32_e32 v43, 0xffff0000, v11
	v_mov_b32_e32 v35, v21
	v_mul_f32_e32 v10, v21, v43
	v_pk_fma_f32 v[34:35], v[34:35], v[42:43], v[10:11] op_sel_hi:[1,1,0]
	v_lshlrev_b32_e32 v43, 16, v12
	v_mov_b32_e32 v33, v21
	v_mul_f32_e32 v10, v21, v43
	v_pk_fma_f32 v[22:23], v[32:33], v[42:43], v[10:11] op_sel_hi:[1,1,0]
	v_and_b32_e32 v43, 0xffff0000, v12
	v_mov_b32_e32 v31, v21
	v_mul_f32_e32 v10, v21, v43
	v_pk_fma_f32 v[26:27], v[30:31], v[42:43], v[10:11] op_sel_hi:[1,1,0]
	v_lshlrev_b32_e32 v43, 16, v13
	v_mov_b32_e32 v25, v21
	v_mul_f32_e32 v10, v21, v43
	v_pk_fma_f32 v[10:11], v[24:25], v[42:43], v[10:11] op_sel_hi:[1,1,0]
	v_and_b32_e32 v43, 0xffff0000, v13
	v_mov_b32_e32 v15, v21
	v_mul_f32_e32 v12, v21, v43
	v_mul_f32_e32 v24, v104, v21
	v_lshl_add_u64 v[44:45], v[76:77], 0, s[18:19]
	v_pk_fma_f32 v[12:13], v[14:15], v[42:43], v[12:13] op_sel_hi:[1,1,0]
	v_fmac_f32_e32 v24, v41, v42
	v_cvt_pk_bf16_f32 v30, v16, v38
	v_cvt_pk_bf16_f32 v31, v28, v34
	v_cvt_pk_bf16_f32 v32, v22, v26
	v_cvt_pk_bf16_f32 v33, v10, v12
	global_store_dwordx4 v[44:45], v[30:33], off
	s_and_saveexec_b64 s[18:19], s[14:15]
	s_cbranch_execz .LBB0_2092
	v_add_co_u32_e32 v14, vcc, 0x101000, v80
	s_nop 1
	v_addc_co_u32_e32 v15, vcc, 0, v81, vcc
	flat_store_dword v[14:15], v24 offset:3072

; __device__ __forceinline__ float bflo(unsigned w) { return __uint_as_float(w << 16); }
; __device__ __forceinline__ float bfhi(unsigned w) { return __uint_as_float(w & 0xffff0000u); }
; #define PACK_CARRY() (u32x4){cvt_pk_bf16(c0, c1), cvt_pk_bf16(c2, c3), cvt_pk_bf16(c4, c5), cvt_pk_bf16(c6, c7)}
; __device__ __forceinline__ void mlstm_scan_item(const Params& P, int item) {
;     ...
;         for (int j = 0; j < 16; ++j) { const int n = n0 + j; const float g = GM[n * 2], ml = GM[n * 2 + 1];
;             *(u32x4*)(p + (size_t)n * 32768) = PACK_CARRY();
;             if (hasn) np[(size_t)n * 128] = ncar;
;             if (wm) MPREV[n] = m;
;             const float mn = fmaxf(g + m, ml), sp = __expf(g + m - mn), sq = __expf(ml - mn);
;             c0 = sp * c0 + sq * bflo(cl[j].x); c1 = sp * c1 + sq * bfhi(cl[j].x); c2 = sp * c2 + sq * bflo(cl[j].y); c3 = sp * c3 + sq * bfhi(cl[j].y);
;             c4 = sp * c4 + sq * bflo(cl[j].z); c5 = sp * c5 + sq * bfhi(cl[j].z); c6 = sp * c6 + sq * bflo(cl[j].w); c7 = sp * c7 + sq * bfhi(cl[j].w);
;             ncar = sp * ncar + sq * nl[j]; m = mn; }
.LBB0_2094:
	s_or_b64 exec, exec, s[18:19]
	v_mov_b32_e32 v14, v242
	v_mov_b32_e32 v15, v243
	v_add_f32_e32 v11, v40, v18
	v_max_f32_e32 v13, v19, v19
	v_max_f32_e32 v25, v11, v13
	v_sub_f32_e32 v11, v11, v25
	v_mul_f32_e32 v11, 0x3fb8aa3b, v11
	v_exp_f32_e32 v30, v11
	v_sub_f32_e32 v11, v19, v25
	v_mul_f32_e32 v11, 0x3fb8aa3b, v11
	v_exp_f32_e32 v17, v11
	v_lshlrev_b32_e32 v31, 16, v6
	v_lshl_add_u64 v[32:33], v[76:77], 0, s[52:53]
	v_pk_mul_f32 v[18:19], v[16:17], v[30:31]
	v_and_b32_e32 v31, 0xffff0000, v6
	v_mov_b32_e32 v39, v17
	v_pk_mul_f32 v[20:21], v[38:39], v[30:31]
	v_mov_b32_e32 v36, v18
	v_mov_b32_e32 v37, v20
	v_mov_b32_e32 v20, v19
	v_lshlrev_b32_e32 v31, 16, v7
	v_mov_b32_e32 v29, v17
	v_pk_add_f32 v[18:19], v[36:37], v[20:21]
	v_pk_mul_f32 v[20:21], v[28:29], v[30:31]
	v_and_b32_e32 v31, 0xffff0000, v7
	v_mov_b32_e32 v35, v17
	v_pk_mul_f32 v[6:7], v[34:35], v[30:31]
	v_lshlrev_b32_e32 v31, 16, v8
	v_mov_b32_e32 v23, v17
	v_mov_b32_e32 v28, v20
	v_mov_b32_e32 v29, v6
	v_mov_b32_e32 v6, v21
	v_pk_mul_f32 v[20:21], v[22:23], v[30:31]
	v_and_b32_e32 v31, 0xffff0000, v8
	v_mov_b32_e32 v27, v17
	v_pk_mul_f32 v[22:23], v[26:27], v[30:31]
	v_lshlrev_b32_e32 v31, 16, v9
	v_mov_b32_e32 v11, v17
	v_pk_mul_f32 v[10:11], v[10:11], v[30:31]
	v_and_b32_e32 v31, 0xffff0000, v9
	v_mov_b32_e32 v13, v17
	v_pk_mul_f32 v[8:9], v[12:13], v[30:31]
	v_mov_b32_e32 v26, v20
	v_mov_b32_e32 v27, v22
	v_mov_b32_e32 v22, v21
	v_mov_b32_e32 v12, v10
	v_mov_b32_e32 v13, v8
	v_mov_b32_e32 v8, v11
	v_mul_f32_e32 v78, v78, v17
	v_pk_add_f32 v[6:7], v[28:29], v[6:7]
	v_pk_add_f32 v[20:21], v[26:27], v[22:23]
	v_pk_add_f32 v[8:9], v[12:13], v[8:9]
	v_fmac_f32_e32 v78, v24, v30
	v_cvt_pk_bf16_f32 v10, v18, v19
	v_cvt_pk_bf16_f32 v11, v6, v7
	v_cvt_pk_bf16_f32 v12, v20, v21
	v_cvt_pk_bf16_f32 v13, v8, v9
	global_store_dwordx4 v[32:33], v[10:13], off
	s_and_saveexec_b64 s[18:19], s[14:15]
	s_cbranch_execz .LBB0_2096
	v_add_co_u32_e32 v10, vcc, 0x101000, v80
	s_nop 1
	v_addc_co_u32_e32 v11, vcc, 0, v81, vcc
	flat_store_dword v[10:11], v78 offset:3584

; __device__ __forceinline__ int crow(int r, int hi) { return (r & 3) + 8 * (r >> 2) + 4 * hi; }
; __device__ __forceinline__ int tsw(int row, int t) { return ((((t >> 1) + 4 * ((row >> 3) & 7)) & 31) << 1) | (t & 1); }
; __device__ __forceinline__ void mlstm_out_unit(const Params& P, int l, int h, int n, char* lds) {
;     ...
;     f32x16 a1[2] = {}, a2[2] = {};
; #pragma unroll
;     for (int ks = 0; ks < 4; ++ks) { const bf16x8 B = *(const bf16x8*)(VT + (32 * wid + r32) * 72 + tsw(32 * wid + r32, 16 * ks + 8 * hi));
; #pragma unroll
;         for (int ti = 0; ti < 2; ++ti) { const bf16x8 A = *(const bf16x8*)(Wl + (32 * ti + r32) * 72 + 16 * ks + 8 * hi);
;             a1[ti] = __builtin_amdgcn_mfma_f32_32x32x16_bf16(A, B, a1[ti], 0, 0, 0); } }
; #pragma unroll
;     for (int ks = 0; ks < 8; ++ks) {
; #pragma unroll
;         for (int ti = 0; ti < 2; ++ti) { const bf16x8 A = *(const bf16x8*)(Ql + (32 * ti + r32) * 136 + 16 * ks + 8 * hi);
;             a2[ti] = __builtin_amdgcn_mfma_f32_32x32x16_bf16(A, cfr[ks], a2[ti], 0, 0, 0); } }
;     __syncthreads();
; #pragma unroll
;     for (int ti = 0; ti < 2; ++ti)
; #pragma unroll
;         for (int r = 0; r < 16; ++r) { const int t = 32 * ti + fox::crow(r, hi);
;             Hb[t * 260 + 32 * wid + r32] = (a1[ti][r] + sil[t] * a2[ti][r]) * rden[t]; }
.LBB0_2398:
	s_or_b64 exec, exec, s[6:7]
	v_mul_lo_u32 v2, v18, s56
	v_add_u32_e32 v20, 0x100, v2
	v_lshlrev_b32_e32 v2, 1, v19
	v_mul_u32_u24_e32 v3, 0x90, v22
	v_add3_u32 v23, s58, v2, v3
	s_waitcnt lgkmcnt(0)
	ds_read_b128 v[2:5], v23
	v_add_u32_e32 v18, v18, v19
	v_and_b32_e32 v6, 56, v18
	v_lshl_add_u32 v6, v6, 1, v20
	ds_read_b128 v[24:27], v6 offset:34816
	ds_read_b128 v[28:31], v23 offset:32
	v_add_u32_e32 v19, 16, v18
	s_waitcnt lgkmcnt(0)
	v_mfma_f32_32x32x16_bf16 v[2:17], v[2:5], v[24:27], 0
	v_and_b32_e32 v19, 56, v19
	v_lshl_add_u32 v19, v19, 1, v20
	ds_read_b128 v[50:53], v19 offset:34816
	ds_read_b128 v[32:35], v23 offset:64
	ds_read_b128 v[54:57], v23 offset:4704
	v_bitop3_b32 v19, v18, 32, 56 bitop3:0x6c
	v_lshl_add_u32 v19, v19, 1, v20
	ds_read_b128 v[58:61], v19 offset:34816
	v_add_u32_e32 v18, 48, v18
	s_waitcnt lgkmcnt(0)
	v_mfma_f32_32x32x16_bf16 v[2:17], v[28:31], v[50:53], v[2:17]
	v_and_b32_e32 v18, 56, v18
	v_lshl_add_u32 v18, v18, 1, v20
	ds_read_b128 v[28:31], v23 offset:96
	ds_read_b128 v[114:117], v18 offset:34816
	v_mul_u32_u24_e32 v18, 0x110, v22
	v_add3_u32 v18, s3, v90, v18
	s_lshl_b32 s6, s8, 2
	v_mfma_f32_32x32x16_bf16 v[2:17], v[32:35], v[58:61], v[2:17]
	s_add_u32 s6, s42, s6
	s_addc_u32 s7, s43, 0
	s_lshl_b32 s9, s65, 7
	s_addk_i32 s9, 0x100
	s_add_i32 s10, s59, 0x100
	v_add_u32_e32 v20, s10, v90
	s_lshl_b32 s26, s8, 1
	s_waitcnt lgkmcnt(0)
	v_mfma_f32_32x32x16_bf16 v[2:17], v[28:31], v[114:117], v[2:17]
	ds_read_b128 v[28:31], v18
	ds_read_b128 v[118:121], v18 offset:32
	s_waitcnt vmcnt(0) lgkmcnt(0)
	v_mfma_f32_32x32x16_bf16 v[30:45], v[28:31], v[46:49], 0
	v_mfma_f32_32x32x16_bf16 v[30:45], v[118:121], v[86:89], v[30:45]
	ds_read_b128 v[118:121], v18 offset:64
	ds_read_b128 v[122:125], v18 offset:96
	s_waitcnt lgkmcnt(1)
	v_mfma_f32_32x32x16_bf16 v[30:45], v[118:121], v[82:85], v[30:45]
	ds_read_b128 v[118:121], v18 offset:128
	s_waitcnt lgkmcnt(1)
	v_mfma_f32_32x32x16_bf16 v[30:45], v[122:125], v[78:81], v[30:45]
	ds_read_b128 v[122:125], v23 offset:4608
	ds_read_b128 v[126:129], v23 offset:4640
	ds_read_b128 v[130:133], v23 offset:4672
	ds_read_b128 v[134:137], v18 offset:160
	s_waitcnt lgkmcnt(4)
	v_mfma_f32_32x32x16_bf16 v[30:45], v[118:121], v[74:77], v[30:45]
	ds_read_b128 v[118:121], v18 offset:8704
	ds_read_b128 v[138:141], v18 offset:8736
	ds_read_b128 v[142:145], v18 offset:8768
	ds_read_b128 v[146:149], v18 offset:8800
	ds_read_b128 v[150:153], v18 offset:8832
	ds_read_b128 v[154:157], v18 offset:8864
	ds_read_b128 v[158:161], v18 offset:192
	ds_read_b128 v[162:165], v18 offset:224
	s_waitcnt lgkmcnt(8)
	v_mfma_f32_32x32x16_bf16 v[30:45], v[134:137], v[70:73], v[30:45]
	ds_read_b128 v[134:137], v18 offset:8896
	ds_read_b128 v[166:169], v18 offset:8928
	v_lshl_add_u32 v18, v22, 2, s9
	s_add_i32 s9, s49, 0x100
	v_add_u32_e32 v19, s9, v90
	s_waitcnt lgkmcnt(0)
	s_barrier
	v_mfma_f32_32x32x16_bf16 v[30:45], v[158:161], v[66:69], v[30:45]
	ds_read_b32 v19, v19
	ds_read_b32 v20, v20
	v_mfma_f32_32x32x16_bf16 v[30:45], v[162:165], v[62:65], v[30:45]
	s_waitcnt lgkmcnt(1)
	s_nop 10
	v_fma_f32 v2, v30, v19, v2
	s_waitcnt lgkmcnt(0)
	v_mul_f32_e32 v2, v20, v2
	v_mad_u32_u24 v19, v21, s60, v18
	ds_write_b32 v19, v2
	v_lshl_or_b32 v2, v21, 2, 1
	v_lshlrev_b32_e32 v19, 2, v2
	v_add_u32_e32 v20, s9, v19
	v_add_u32_e32 v19, s10, v19
	ds_read_b32 v20, v20
	ds_read_b32 v19, v19
	v_mad_u32_u24 v2, v2, s61, v18
	s_waitcnt lgkmcnt(1)
	v_fma_f32 v3, v31, v20, v3
	s_waitcnt lgkmcnt(0)
	v_mul_f32_e32 v3, v19, v3
	ds_write_b32 v2, v3
	v_or_b32_e32 v3, 8, v90
	v_add_u32_e32 v18, s9, v3
	v_add_u32_e32 v3, s10, v3
	ds_read_b32 v18, v18
	ds_read_b32 v3, v3
	s_waitcnt lgkmcnt(1)
	v_fma_f32 v4, v32, v18, v4
	s_waitcnt lgkmcnt(0)
	v_mul_f32_e32 v3, v3, v4
	ds_write_b32 v2, v3 offset:1040
	v_or_b32_e32 v3, 12, v90
	v_add_u32_e32 v4, s9, v3
	v_add_u32_e32 v3, s10, v3
	ds_read_b32 v4, v4
	ds_read_b32 v3, v3
	s_waitcnt lgkmcnt(1)
	v_fma_f32 v4, v33, v4, v5
	s_waitcnt lgkmcnt(0)
	v_mul_f32_e32 v3, v3, v4
	ds_write_b32 v2, v3 offset:2080
	v_or_b32_e32 v3, 32, v90
	v_add_u32_e32 v4, s9, v3
	v_add_u32_e32 v3, s10, v3
	ds_read_b32 v4, v4
	ds_read_b32 v3, v3
	v_mfma_f32_32x32x16_bf16 v[18:33], v[122:125], v[24:27], 0
	s_waitcnt lgkmcnt(1)
	v_fma_f32 v4, v34, v4, v6
	s_waitcnt lgkmcnt(0)
	v_mul_f32_e32 v3, v3, v4
	ds_write_b32 v2, v3 offset:7280
	v_or_b32_e32 v3, 36, v90
	v_add_u32_e32 v4, s9, v3
	v_add_u32_e32 v3, s10, v3
	ds_read_b32 v4, v4
	ds_read_b32 v3, v3
	v_mfma_f32_32x32x16_bf16 v[18:33], v[126:129], v[50:53], v[18:33]
	v_add_u32_e32 v34, s64, v109
	s_waitcnt lgkmcnt(1)
	v_fma_f32 v4, v35, v4, v7
	s_waitcnt lgkmcnt(0)
	v_mul_f32_e32 v3, v3, v4
	ds_write_b32 v2, v3 offset:8320
	v_or_b32_e32 v3, 40, v90
	v_add_u32_e32 v4, s9, v3
	v_add_u32_e32 v3, s10, v3
	ds_read_b32 v4, v4
	ds_read_b32 v3, v3
	v_mfma_f32_32x32x16_bf16 v[18:33], v[130:133], v[58:61], v[18:33]
	s_waitcnt lgkmcnt(1)
	v_fma_f32 v4, v36, v4, v8
	s_waitcnt lgkmcnt(0)
	v_mul_f32_e32 v3, v3, v4
	ds_write_b32 v2, v3 offset:9360
	v_or_b32_e32 v3, 44, v90
	v_add_u32_e32 v4, s9, v3
	v_add_u32_e32 v3, s10, v3
	ds_read_b32 v4, v4
	ds_read_b32 v3, v3
	v_mfma_f32_32x32x16_bf16 v[18:33], v[54:57], v[114:117], v[18:33]
	s_waitcnt lgkmcnt(1)
	v_fma_f32 v4, v37, v4, v9
	s_waitcnt lgkmcnt(0)
	v_mul_f32_e32 v3, v3, v4
	ds_write_b32 v2, v3 offset:10400
	v_or_b32_e32 v3, 64, v90
	v_add_u32_e32 v4, s9, v3
	v_add_u32_e32 v3, s10, v3
	ds_read_b32 v4, v4
	ds_read_b32 v3, v3
	v_mfma_f32_32x32x16_bf16 v[46:61], v[118:121], v[46:49], 0
	s_waitcnt lgkmcnt(1)
	v_fma_f32 v4, v38, v4, v10
	s_waitcnt lgkmcnt(0)
; __device__ __forceinline__ int crow(int r, int hi) { return (r & 3) + 8 * (r >> 2) + 4 * hi; }
; __device__ __forceinline__ void mlstm_out_unit(const Params& P, int l, int h, int n, char* lds) {
;     ...
;     __syncthreads();
; #pragma unroll
;     for (int ti = 0; ti < 2; ++ti)
; #pragma unroll
;         for (int r = 0; r < 16; ++r) { const int t = 32 * ti + fox::crow(r, hi);
;             Hb[t * 260 + 32 * wid + r32] = (a1[ti][r] + sil[t] * a2[ti][r]) * rden[t]; }
;     __syncthreads();
;     {
;         const int t = tid >> 3, p = tid & 7; f32x4 hv[8]; float ss = 0.f;
	v_mul_f32_e32 v3, v3, v4
	ds_write_b32 v2, v3 offset:15600
	v_or_b32_e32 v3, 0x44, v90
	v_add_u32_e32 v4, s9, v3
	v_add_u32_e32 v3, s10, v3
	ds_read_b32 v4, v4
	ds_read_b32 v3, v3
	v_mfma_f32_32x32x16_bf16 v[46:61], v[138:141], v[86:89], v[46:61]
	s_waitcnt lgkmcnt(1)
	v_fma_f32 v4, v39, v4, v11
	s_waitcnt lgkmcnt(0)
	v_mul_f32_e32 v3, v3, v4
	ds_write_b32 v2, v3 offset:16640
	v_or_b32_e32 v3, 0x48, v90
	v_add_u32_e32 v4, s9, v3
	v_add_u32_e32 v3, s10, v3
	ds_read_b32 v4, v4
	ds_read_b32 v3, v3
	v_mfma_f32_32x32x16_bf16 v[46:61], v[142:145], v[82:85], v[46:61]
	v_mov_b64_e32 v[10:11], s[14:15]
	s_waitcnt lgkmcnt(1)
	v_fma_f32 v4, v40, v4, v12
	s_waitcnt lgkmcnt(0)
	v_mul_f32_e32 v3, v3, v4
	ds_write_b32 v2, v3 offset:17680
	v_or_b32_e32 v3, 0x4c, v90
	v_add_u32_e32 v4, s9, v3
	v_add_u32_e32 v3, s10, v3
	ds_read_b32 v4, v4
	ds_read_b32 v3, v3
	v_mfma_f32_32x32x16_bf16 v[46:61], v[146:149], v[78:81], v[46:61]
	s_waitcnt lgkmcnt(1)
	v_fma_f32 v4, v41, v4, v13
	s_waitcnt lgkmcnt(0)
	v_mul_f32_e32 v3, v3, v4
	ds_write_b32 v2, v3 offset:18720
	v_or_b32_e32 v3, 0x60, v90
	v_add_u32_e32 v4, s9, v3
	v_add_u32_e32 v3, s10, v3
	ds_read_b32 v4, v4
	ds_read_b32 v3, v3
	v_mfma_f32_32x32x16_bf16 v[46:61], v[150:153], v[74:77], v[46:61]
	s_waitcnt lgkmcnt(1)
	v_fma_f32 v4, v42, v4, v14
	s_waitcnt lgkmcnt(0)
	v_mul_f32_e32 v3, v3, v4
	ds_write_b32 v2, v3 offset:23920
	v_or_b32_e32 v3, 0x64, v90
	v_add_u32_e32 v4, s9, v3
	v_add_u32_e32 v3, s10, v3
	ds_read_b32 v4, v4
	ds_read_b32 v3, v3
	v_mfma_f32_32x32x16_bf16 v[46:61], v[154:157], v[70:73], v[46:61]
	s_waitcnt lgkmcnt(1)
	v_fma_f32 v4, v43, v4, v15
	s_waitcnt lgkmcnt(0)
	v_mul_f32_e32 v3, v3, v4
	ds_write_b32 v2, v3 offset:24960
	v_or_b32_e32 v3, 0x68, v90
	v_add_u32_e32 v4, s9, v3
	v_add_u32_e32 v3, s10, v3
	ds_read_b32 v4, v4
	ds_read_b32 v3, v3
	v_mfma_f32_32x32x16_bf16 v[46:61], v[134:137], v[66:69], v[46:61]
	s_waitcnt lgkmcnt(1)
	v_fma_f32 v4, v44, v4, v16
	s_waitcnt lgkmcnt(0)
	v_mul_f32_e32 v3, v3, v4
	ds_write_b32 v2, v3 offset:26000
	v_or_b32_e32 v3, 0x6c, v90
	v_add_u32_e32 v4, s9, v3
	v_add_u32_e32 v3, s10, v3
	ds_read_b32 v4, v4
	ds_read_b32 v3, v3
	v_mfma_f32_32x32x16_bf16 v[46:61], v[166:169], v[62:65], v[46:61]
	s_waitcnt lgkmcnt(1)
	v_fmac_f32_e32 v17, v45, v4
	s_waitcnt lgkmcnt(0)
	v_mul_f32_e32 v3, v3, v17
	ds_write_b32 v2, v3 offset:27040
	v_or_b32_e32 v3, 0x80, v90
	v_add_u32_e32 v4, s9, v3
	v_add_u32_e32 v3, s10, v3
	ds_read_b32 v4, v4
	ds_read_b32 v3, v3
	s_waitcnt lgkmcnt(1)
	s_nop 0
	v_fma_f32 v4, v46, v4, v18
	s_waitcnt lgkmcnt(0)
	v_mul_f32_e32 v3, v3, v4
	ds_write_b32 v2, v3 offset:32240
	v_or_b32_e32 v3, 0x84, v90
	v_add_u32_e32 v4, s9, v3
	v_add_u32_e32 v3, s10, v3
	ds_read_b32 v4, v4
	ds_read_b32 v3, v3
	s_waitcnt lgkmcnt(1)
	v_fma_f32 v4, v47, v4, v19
	s_waitcnt lgkmcnt(0)
	v_mul_f32_e32 v3, v3, v4
	ds_write_b32 v2, v3 offset:33280
	v_or_b32_e32 v3, 0x88, v90
	v_add_u32_e32 v4, s9, v3
	v_add_u32_e32 v3, s10, v3
	ds_read_b32 v4, v4
	ds_read_b32 v3, v3
	s_waitcnt lgkmcnt(1)
	v_fma_f32 v4, v48, v4, v20
	s_waitcnt lgkmcnt(0)
	v_mul_f32_e32 v3, v3, v4
	ds_write_b32 v2, v3 offset:34320
	v_or_b32_e32 v3, 0x8c, v90
	v_add_u32_e32 v4, s9, v3
	v_add_u32_e32 v3, s10, v3
	ds_read_b32 v4, v4
	ds_read_b32 v3, v3
	s_waitcnt lgkmcnt(1)
	v_fma_f32 v4, v49, v4, v21
	s_waitcnt lgkmcnt(0)
	v_mul_f32_e32 v3, v3, v4
	ds_write_b32 v2, v3 offset:35360
	v_or_b32_e32 v3, 0xa0, v90
	v_add_u32_e32 v4, s9, v3
	v_add_u32_e32 v3, s10, v3
	ds_read_b32 v4, v4
	ds_read_b32 v3, v3
	s_waitcnt lgkmcnt(1)
	v_fma_f32 v4, v50, v4, v22
	s_waitcnt lgkmcnt(0)
	v_mul_f32_e32 v3, v3, v4
	ds_write_b32 v2, v3 offset:40560
	v_or_b32_e32 v3, 0xa4, v90
	v_add_u32_e32 v4, s9, v3
	v_add_u32_e32 v3, s10, v3
	ds_read_b32 v4, v4
	ds_read_b32 v3, v3
	s_waitcnt lgkmcnt(1)
	v_fma_f32 v4, v51, v4, v23
	s_waitcnt lgkmcnt(0)
	v_mul_f32_e32 v3, v3, v4
	ds_write_b32 v2, v3 offset:41600
	v_or_b32_e32 v3, 0xa8, v90
	v_add_u32_e32 v4, s9, v3
	v_add_u32_e32 v3, s10, v3
	ds_read_b32 v4, v4
	ds_read_b32 v3, v3
	s_waitcnt lgkmcnt(1)
	v_fma_f32 v4, v52, v4, v24
	s_waitcnt lgkmcnt(0)
	v_mul_f32_e32 v3, v3, v4
	ds_write_b32 v2, v3 offset:42640
	v_or_b32_e32 v3, 0xac, v90
	v_add_u32_e32 v4, s9, v3
	v_add_u32_e32 v3, s10, v3
	ds_read_b32 v4, v4
	ds_read_b32 v3, v3
	s_waitcnt lgkmcnt(1)
	v_fma_f32 v4, v53, v4, v25
	s_waitcnt lgkmcnt(0)
	v_mul_f32_e32 v3, v3, v4
	ds_write_b32 v2, v3 offset:43680
	v_or_b32_e32 v3, 0xc0, v90
	v_add_u32_e32 v4, s9, v3
	v_add_u32_e32 v3, s10, v3
	ds_read_b32 v4, v4
	ds_read_b32 v3, v3
	s_waitcnt lgkmcnt(1)
	v_fma_f32 v4, v54, v4, v26
	s_waitcnt lgkmcnt(0)
	v_mul_f32_e32 v3, v3, v4
	ds_write_b32 v2, v3 offset:48880
	v_or_b32_e32 v3, 0xc4, v90
	v_add_u32_e32 v4, s9, v3
	v_add_u32_e32 v3, s10, v3
	ds_read_b32 v4, v4
	ds_read_b32 v3, v3
	s_waitcnt lgkmcnt(1)
	v_fma_f32 v4, v55, v4, v27
	s_waitcnt lgkmcnt(0)
	v_mul_f32_e32 v3, v3, v4
	ds_write_b32 v2, v3 offset:49920
	v_or_b32_e32 v3, 0xc8, v90
	v_add_u32_e32 v4, s9, v3
	v_add_u32_e32 v3, s10, v3
	ds_read_b32 v4, v4
	ds_read_b32 v3, v3
	s_waitcnt lgkmcnt(1)
	v_fma_f32 v4, v56, v4, v28
	s_waitcnt lgkmcnt(0)
	v_mul_f32_e32 v3, v3, v4
	ds_write_b32 v2, v3 offset:50960
	v_or_b32_e32 v3, 0xcc, v90
	v_add_u32_e32 v4, s9, v3
	v_add_u32_e32 v3, s10, v3
	ds_read_b32 v4, v4
	ds_read_b32 v3, v3
	s_waitcnt lgkmcnt(1)
	v_fma_f32 v4, v57, v4, v29
	s_waitcnt lgkmcnt(0)
	v_mul_f32_e32 v3, v3, v4
	ds_write_b32 v2, v3 offset:52000
	v_or_b32_e32 v3, 0xe0, v90
	v_add_u32_e32 v4, s9, v3
	v_add_u32_e32 v3, s10, v3
	ds_read_b32 v4, v4
	ds_read_b32 v3, v3
	s_waitcnt lgkmcnt(1)
	v_fma_f32 v4, v58, v4, v30
	s_waitcnt lgkmcnt(0)
	v_mul_f32_e32 v3, v3, v4
	ds_write_b32 v2, v3 offset:57200
	v_or_b32_e32 v3, 0xe4, v90
	v_add_u32_e32 v4, s9, v3
	v_add_u32_e32 v3, s10, v3
	ds_read_b32 v4, v4
	ds_read_b32 v3, v3
	s_waitcnt lgkmcnt(1)
	v_fma_f32 v4, v59, v4, v31
	s_waitcnt lgkmcnt(0)
	v_mul_f32_e32 v3, v3, v4
	ds_write_b32 v2, v3 offset:58240
	v_or_b32_e32 v3, 0xe8, v90
	v_add_u32_e32 v4, s9, v3
	v_add_u32_e32 v3, s10, v3
	ds_read_b32 v4, v4
	ds_read_b32 v3, v3
	s_waitcnt lgkmcnt(1)
	v_fma_f32 v4, v60, v4, v32
	s_waitcnt lgkmcnt(0)
	v_mul_f32_e32 v3, v3, v4
	ds_write_b32 v2, v3 offset:59280
	v_or_b32_e32 v3, 0xec, v90
	v_add_u32_e32 v4, s9, v3
	v_add_u32_e32 v3, s10, v3
	ds_read_b32 v4, v4
	ds_read_b32 v3, v3
	v_mad_i64_i32 v[10:11], s[10:11], v34, s50, v[10:11]
	v_lshl_add_u64 v[10:11], v[10:11], 0, s[26:27]
	s_waitcnt lgkmcnt(1)
	v_fmac_f32_e32 v33, v61, v4
	s_waitcnt lgkmcnt(0)
	v_mul_f32_e32 v3, v3, v33
	ds_write_b32 v2, v3 offset:60320
	v_mul_lo_u32 v2, v109, s61
	v_add3_u32 v35, s3, v2, v92
	s_waitcnt lgkmcnt(0)
	s_barrier
; __device__ __forceinline__ float bflo(unsigned w) { return __uint_as_float(w << 16); }
; __device__ __forceinline__ float bfhi(unsigned w) { return __uint_as_float(w & 0xffff0000u); }
; __device__ __forceinline__ float sigmoidf(float x) { return 1.f / (1.f + __expf(-x)); }
; __device__ __forceinline__ void mlstm_out_unit(const Params& P, int l, int h, int n, char* lds) {
;     ...
;     {
;         const int t = tid >> 3, p = tid & 7; f32x4 hv[8]; float ss = 0.f;
; #pragma unroll
;         for (int j = 0; j < 8; ++j) { hv[j] = *(const f32x4*)(Hb + t * 260 + 32 * j + 4 * p); ss += (hv[j][0] * hv[j][0] + hv[j][1] * hv[j][1]) + (hv[j][2] * hv[j][2] + hv[j][3] * hv[j][3]); }
;         ss += __shfl_xor(ss, 1); ss += __shfl_xor(ss, 2); ss += __shfl_xor(ss, 4);
;         const float rs = rsqrtf(ss * (1.f / 256.f) + RMS_EPS);
;         const size_t row = (size_t)(t0 + t);
; #pragma unroll
;         for (int j = 0; j < 8; ++j) { const int e = 32 * j + 4 * p; const f32x4 gn = *(const f32x4*)(mnorm + e);
;             const u32x2 mo = *(const u32x2*)(PROJ + row * PW + C_MO + h * 256 + e);
;             const float o0 = hv[j][0] * rs * gn[0] * sigmoidf(bflo(mo.x)), o1 = hv[j][1] * rs * gn[1] * sigmoidf(bfhi(mo.x));
;             const float o2 = hv[j][2] * rs * gn[2] * sigmoidf(bflo(mo.y)), o3 = hv[j][3] * rs * gn[3] * sigmoidf(bfhi(mo.y));
	ds_read_b128 v[30:33], v35
	ds_read_b128 v[26:29], v35 offset:128
	ds_read_b128 v[22:25], v35 offset:256
	ds_read_b128 v[18:21], v35 offset:384
	v_lshlrev_b32_e32 v90, 3, v93
	s_waitcnt lgkmcnt(3)
	v_mov_b32_e32 v4, v31
	s_waitcnt lgkmcnt(2)
	v_mov_b32_e32 v5, v27
	v_mov_b32_e32 v2, v30
	v_mov_b32_e32 v3, v26
	v_pk_mul_f32 v[4:5], v[4:5], v[4:5]
	v_mov_b32_e32 v6, v33
	v_mov_b32_e32 v7, v29
	v_pk_fma_f32 v[2:3], v[2:3], v[2:3], v[4:5]
	v_mov_b32_e32 v4, v32
	v_mov_b32_e32 v5, v28
	v_pk_mul_f32 v[6:7], v[6:7], v[6:7]
	v_lshl_add_u64 v[42:43], v[10:11], 0, v[90:91]
	v_pk_fma_f32 v[4:5], v[4:5], v[4:5], v[6:7]
	s_waitcnt lgkmcnt(1)
	v_pk_mul_f32 v[6:7], v[22:23], v[22:23]
	v_pk_add_f32 v[2:3], v[2:3], v[4:5]
	v_pk_mul_f32 v[4:5], v[24:25], v[24:25]
	v_add_co_u32_e32 v10, vcc, s51, v42
	v_pk_mov_b32 v[8:9], v[6:7], v[4:5] op_sel:[1,0]
	v_mov_b32_e32 v7, v5
	v_addc_co_u32_e32 v11, vcc, 0, v43, vcc
	v_pk_add_f32 v[4:5], v[8:9], v[6:7]
	ds_read_b128 v[14:17], v35 offset:512
	ds_read_b128 v[6:9], v35 offset:640
	global_load_dwordx2 v[44:45], v[10:11], off
	global_load_dwordx2 v[196:197], v[10:11], off offset:64
	global_load_dwordx2 v[198:199], v[10:11], off offset:128
	global_load_dwordx2 v[200:201], v[10:11], off offset:192
	global_load_dwordx2 v[202:203], v[10:11], off offset:256
	global_load_dwordx2 v[204:205], v[10:11], off offset:320
	global_load_dwordx2 v[206:207], v[10:11], off offset:384
	global_load_dwordx2 v[208:209], v[10:11], off offset:448
	v_mov_b32_e32 v93, v91
	v_lshl_add_u64 v[46:47], s[6:7], 0, v[92:93]
	v_add_co_u32_e32 v10, vcc, s51, v46
	s_waitcnt lgkmcnt(0)
	v_mul_f32_e32 v12, v14, v14
	v_addc_co_u32_e32 v11, vcc, 0, v47, vcc
	global_load_dwordx4 v[38:41], v[10:11], off
	global_load_dwordx4 v[212:215], v[10:11], off offset:128
	global_load_dwordx4 v[216:219], v[10:11], off offset:256
	global_load_dwordx4 v[220:223], v[10:11], off offset:384
	global_load_dwordx4 v[224:227], v[10:11], off offset:512
	global_load_dwordx4 v[228:231], v[10:11], off offset:640
	global_load_dwordx4 v[232:235], v[10:11], off offset:768
	global_load_dwordx4 v[236:239], v[10:11], off offset:896
	v_mul_f32_e32 v13, v15, v15
	v_pk_add_f32 v[2:3], v[2:3], v[2:3] op_sel:[0,1] op_sel_hi:[1,0]
	v_pk_add_f32 v[4:5], v[4:5], v[4:5] op_sel:[0,1] op_sel_hi:[1,0]
	v_mov_b32_e32 v3, v12
	v_mov_b32_e32 v5, v13
	v_pk_add_f32 v[2:3], v[2:3], v[4:5]
	v_mul_f32_e32 v4, v19, v19
	v_mul_f32_e32 v10, v21, v21
	v_mul_f32_e32 v36, v16, v16
	v_mul_f32_e32 v37, v17, v17
	v_pk_fma_f32 v[4:5], v[18:19], v[18:19], v[4:5] op_sel_hi:[1,1,0]
	v_pk_fma_f32 v[10:11], v[20:21], v[20:21], v[10:11] op_sel_hi:[1,1,0]
	v_mov_b32_e32 v5, v36
	v_mov_b32_e32 v11, v37
	v_pk_add_f32 v[4:5], v[4:5], v[10:11]
	v_pk_mul_f32 v[48:49], v[8:9], v[8:9]
	v_pk_add_f32 v[36:37], v[2:3], v[4:5]
	ds_read_b128 v[10:13], v35 offset:768
	ds_read_b128 v[2:5], v35 offset:896
	v_pk_mul_f32 v[50:51], v[6:7], v[6:7]
	v_pk_add_f32 v[36:37], v[36:37], v[36:37] op_sel:[0,1] op_sel_hi:[1,0]
	v_pk_mov_b32 v[52:53], v[50:51], v[48:49] op_sel:[1,0]
	v_mov_b32_e32 v51, v49
	v_pk_add_f32 v[48:49], v[52:53], v[50:51]
	s_waitcnt lgkmcnt(0)
	v_mul_f32_e32 v35, v2, v2
	v_mul_f32_e32 v50, v3, v3
	v_pk_add_f32 v[48:49], v[48:49], v[48:49] op_sel:[0,1] op_sel_hi:[1,0]
	v_mov_b32_e32 v37, v35
	v_mov_b32_e32 v49, v50
	v_pk_add_f32 v[36:37], v[36:37], v[48:49]
	v_mul_f32_e32 v48, v11, v11
	v_mul_f32_e32 v51, v4, v4
	v_pk_fma_f32 v[48:49], v[10:11], v[10:11], v[48:49] op_sel_hi:[1,1,0]
	v_mul_f32_e32 v50, v13, v13
	v_mul_f32_e32 v52, v5, v5
	v_mov_b32_e32 v49, v51
	v_pk_fma_f32 v[50:51], v[12:13], v[12:13], v[50:51] op_sel_hi:[1,1,0]
	s_add_u32 s6, s40, s26
	v_mov_b32_e32 v51, v52
	v_pk_add_f32 v[48:49], v[48:49], v[50:51]
	s_addc_u32 s7, s41, 0
	v_pk_add_f32 v[36:37], v[36:37], v[48:49]
	s_nop 0
	v_add_f32_e32 v35, v36, v37
	ds_bpermute_b32 v36, v110, v35
	s_waitcnt lgkmcnt(0)
	v_add_f32_e32 v35, v35, v36
	ds_bpermute_b32 v36, v111, v35
	s_waitcnt lgkmcnt(0)
	v_add_f32_e32 v35, v35, v36
	ds_bpermute_b32 v36, v112, v35
	s_waitcnt lgkmcnt(0)
	v_add_f32_e32 v35, v35, v36
	v_fmamk_f32 v35, v35, 0x3b800000, v104
	v_mul_f32_e32 v36, 0x4b800000, v35
	v_cmp_gt_f32_e32 vcc, s62, v35
	s_waitcnt vmcnt(0)
	v_lshlrev_b32_e32 v37, 16, v44
	v_cndmask_b32_e32 v35, v35, v36, vcc
	v_rsq_f32_e32 v35, v35
	v_mul_f32_e32 v37, 0xbfb8aa3b, v37
	v_exp_f32_e32 v37, v37
	v_mul_f32_e32 v36, 0x45800000, v35
	v_cndmask_b32_e32 v36, v35, v36, vcc
	v_ashrrev_i32_e32 v35, 31, v34
	v_lshlrev_b64 v[34:35], 12, v[34:35]
	v_add_f32_e32 v37, 1.0, v37
	v_lshl_add_u64 v[48:49], s[6:7], 0, v[34:35]
	v_div_scale_f32 v50, s[6:7], v37, v37, 1.0
	v_rcp_f32_e32 v51, v50
	v_mul_f32_e32 v30, v30, v36
	v_mul_f32_e32 v30, v38, v30
	v_lshl_add_u64 v[34:35], v[42:43], 0, s[30:31]
	v_fma_f32 v38, -v50, v51, 1.0
	v_fmac_f32_e32 v51, v38, v51
	v_div_scale_f32 v38, vcc, 1.0, v37, 1.0
	v_mul_f32_e32 v42, v38, v51
	v_fma_f32 v43, -v50, v42, v38
	v_fmac_f32_e32 v42, v43, v51
	v_and_b32_e32 v43, 0xffff0000, v44
	v_mul_f32_e32 v43, 0xbfb8aa3b, v43
	v_exp_f32_e32 v43, v43
	v_fma_f32 v38, -v50, v42, v38
	v_div_fmas_f32 v38, v38, v51, v42
	v_div_fixup_f32 v37, v38, v37, 1.0
	v_add_f32_e32 v38, 1.0, v43
	v_div_scale_f32 v42, s[6:7], v38, v38, 1.0
	v_rcp_f32_e32 v43, v42
	v_mul_f32_e32 v30, v37, v30
	v_mul_f32_e32 v31, v31, v36
	v_mul_f32_e32 v31, v39, v31
	v_fma_f32 v37, -v42, v43, 1.0
	v_fmac_f32_e32 v43, v37, v43
	v_div_scale_f32 v37, vcc, 1.0, v38, 1.0
	v_mul_f32_e32 v39, v37, v43
	v_fma_f32 v44, -v42, v39, v37
	v_fmac_f32_e32 v39, v44, v43
	v_fma_f32 v37, -v42, v39, v37
	v_lshlrev_b32_e32 v42, 16, v45
	v_mul_f32_e32 v42, 0xbfb8aa3b, v42
	v_exp_f32_e32 v42, v42
	v_div_fmas_f32 v37, v37, v43, v39
; __device__ __forceinline__ unsigned cvt_pk_bf16(float lo, float hi) { unsigned r; asm volatile("v_cvt_pk_bf16_f32 %0, %1, %2" : "=v"(r) : "v"(lo), "v"(hi)); return r; }
; __device__ __forceinline__ float bflo(unsigned w) { return __uint_as_float(w << 16); }
; __device__ __forceinline__ float bfhi(unsigned w) { return __uint_as_float(w & 0xffff0000u); }
; __device__ __forceinline__ float sigmoidf(float x) { return 1.f / (1.f + __expf(-x)); }
; __device__ __forceinline__ void mlstm_out_unit(const Params& P, int l, int h, int n, char* lds) {
;     ...
;         for (int j = 0; j < 8; ++j) { const int e = 32 * j + 4 * p; const f32x4 gn = *(const f32x4*)(mnorm + e);
;             const u32x2 mo = *(const u32x2*)(PROJ + row * PW + C_MO + h * 256 + e);
;             const float o0 = hv[j][0] * rs * gn[0] * sigmoidf(bflo(mo.x)), o1 = hv[j][1] * rs * gn[1] * sigmoidf(bfhi(mo.x));
;             const float o2 = hv[j][2] * rs * gn[2] * sigmoidf(bflo(mo.y)), o3 = hv[j][3] * rs * gn[3] * sigmoidf(bfhi(mo.y));
;             u32x2 w; w.x = cvt_pk_bf16(o0, o1); w.y = cvt_pk_bf16(o2, o3);
;             *(u32x2*)(MIX + row * DM + h * 256 + e) = w; }
	v_div_fixup_f32 v37, v37, v38, 1.0
	v_mul_f32_e32 v31, v37, v31
	v_add_f32_e32 v38, 1.0, v42
	v_div_scale_f32 v39, s[6:7], v38, v38, 1.0
	v_rcp_f32_e32 v42, v39
	v_mul_f32_e32 v32, v32, v36
	v_mul_f32_e32 v32, v40, v32
	v_mul_f32_e32 v33, v33, v36
	v_fma_f32 v37, -v39, v42, 1.0
	v_fmac_f32_e32 v42, v37, v42
	v_div_scale_f32 v37, vcc, 1.0, v38, 1.0
	v_mul_f32_e32 v40, v37, v42
	v_fma_f32 v43, -v39, v40, v37
	v_fmac_f32_e32 v40, v43, v42
	v_fma_f32 v37, -v39, v40, v37
	v_and_b32_e32 v39, 0xffff0000, v45
	v_mul_f32_e32 v39, 0xbfb8aa3b, v39
	v_exp_f32_e32 v39, v39
	v_div_fmas_f32 v37, v37, v42, v40
	v_div_fixup_f32 v37, v37, v38, 1.0
	v_mul_f32_e32 v32, v37, v32
	v_add_f32_e32 v38, 1.0, v39
	v_div_scale_f32 v39, s[6:7], v38, v38, 1.0
	v_rcp_f32_e32 v40, v39
	v_mul_f32_e32 v33, v41, v33
	v_cvt_pk_bf16_f32 v30, v30, v31
	v_mul_f32_e32 v26, v26, v36
	v_fma_f32 v37, -v39, v40, 1.0
	v_fmac_f32_e32 v40, v37, v40
	v_div_scale_f32 v37, vcc, 1.0, v38, 1.0
	v_mul_f32_e32 v41, v37, v40
	v_fma_f32 v42, -v39, v41, v37
	v_fmac_f32_e32 v41, v42, v40
	v_fma_f32 v37, -v39, v41, v37
	v_div_fmas_f32 v37, v37, v40, v41
	v_div_fixup_f32 v37, v37, v38, 1.0
	v_lshl_add_u64 v[42:43], v[48:49], 0, v[90:91]
	v_mul_f32_e32 v33, v37, v33
	v_cvt_pk_bf16_f32 v31, v32, v33
	v_add_co_u32_e32 v32, vcc, s63, v42
	v_mul_f32_e32 v27, v27, v36
	s_nop 0
	v_addc_co_u32_e32 v33, vcc, 0, v43, vcc
	global_store_dwordx2 v[32:33], v[30:31], off
	v_lshl_add_u64 v[32:33], v[46:47], 0, s[30:31]
	v_mul_f32_e32 v28, v28, v36
	v_mul_f32_e32 v29, v29, v36
	v_mul_f32_e32 v22, v22, v36
	v_mul_f32_e32 v23, v23, v36
	v_mul_f32_e32 v24, v24, v36
	v_mul_f32_e32 v25, v25, v36
	v_mul_f32_e32 v18, v18, v36
	v_mul_f32_e32 v19, v19, v36
	v_mul_f32_e32 v20, v20, v36
	v_mul_f32_e32 v21, v21, v36
	v_mul_f32_e32 v14, v14, v36
	v_mul_f32_e32 v15, v15, v36
	v_mul_f32_e32 v16, v16, v36
	v_mul_f32_e32 v17, v17, v36
	v_mul_f32_e32 v6, v6, v36
	v_mul_f32_e32 v7, v7, v36
	v_mul_f32_e32 v8, v8, v36
	v_mul_f32_e32 v9, v9, v36
	v_mul_f32_e32 v10, v10, v36
	v_mul_f32_e32 v11, v11, v36
	v_mul_f32_e32 v12, v12, v36
	v_mul_f32_e32 v13, v13, v36
	v_mul_f32_e32 v2, v2, v36
	v_mul_f32_e32 v3, v3, v36
	v_mul_f32_e32 v4, v4, v36
	v_mul_f32_e32 v5, v5, v36
	s_nop 1
	v_mov_b32_e32 v44, v196
	v_mov_b32_e32 v45, v197
	v_mov_b32_e32 v38, v212
	v_mov_b32_e32 v39, v213
	v_mov_b32_e32 v40, v214
	v_mov_b32_e32 v41, v215
	v_lshlrev_b32_e32 v30, 16, v44
	v_mul_f32_e32 v30, 0xbfb8aa3b, v30
	v_exp_f32_e32 v30, v30
	v_mul_f32_e32 v26, v38, v26
	v_mul_f32_e32 v27, v39, v27
	v_mul_f32_e32 v28, v40, v28
	v_add_f32_e32 v37, 1.0, v30
	v_div_scale_f32 v46, s[6:7], v37, v37, 1.0
	v_rcp_f32_e32 v47, v46
	v_lshl_add_u64 v[30:31], v[42:43], 0, s[36:37]
	v_mul_f32_e32 v29, v41, v29
	v_fma_f32 v38, -v46, v47, 1.0
	v_fmac_f32_e32 v47, v38, v47
	v_div_scale_f32 v38, vcc, 1.0, v37, 1.0
	v_mul_f32_e32 v42, v38, v47
	v_fma_f32 v43, -v46, v42, v38
	v_fmac_f32_e32 v42, v43, v47
	v_and_b32_e32 v43, 0xffff0000, v44
	v_mul_f32_e32 v43, 0xbfb8aa3b, v43
	v_exp_f32_e32 v43, v43
	v_fma_f32 v38, -v46, v42, v38
	v_div_fmas_f32 v38, v38, v47, v42
	v_div_fixup_f32 v37, v38, v37, 1.0
	v_add_f32_e32 v38, 1.0, v43
	v_div_scale_f32 v42, s[6:7], v38, v38, 1.0
	v_rcp_f32_e32 v43, v42
	v_mul_f32_e32 v26, v37, v26
	v_fma_f32 v37, -v42, v43, 1.0
	v_fmac_f32_e32 v43, v37, v43
	v_div_scale_f32 v37, vcc, 1.0, v38, 1.0
	v_mul_f32_e32 v39, v37, v43
	v_fma_f32 v44, -v42, v39, v37
	v_fmac_f32_e32 v39, v44, v43
	v_fma_f32 v37, -v42, v39, v37
	v_lshlrev_b32_e32 v42, 16, v45
	v_mul_f32_e32 v42, 0xbfb8aa3b, v42
	v_exp_f32_e32 v42, v42
	v_div_fmas_f32 v37, v37, v43, v39
	v_div_fixup_f32 v37, v37, v38, 1.0
	v_mul_f32_e32 v27, v37, v27
	v_add_f32_e32 v38, 1.0, v42
	v_div_scale_f32 v39, s[6:7], v38, v38, 1.0
	v_rcp_f32_e32 v42, v39
	v_cvt_pk_bf16_f32 v26, v26, v27
	s_nop 0
	v_fma_f32 v37, -v39, v42, 1.0
	v_fmac_f32_e32 v42, v37, v42
	v_div_scale_f32 v37, vcc, 1.0, v38, 1.0
	v_mul_f32_e32 v40, v37, v42
	v_fma_f32 v43, -v39, v40, v37
	v_fmac_f32_e32 v40, v43, v42
	v_fma_f32 v37, -v39, v40, v37
	v_and_b32_e32 v39, 0xffff0000, v45
	v_mul_f32_e32 v39, 0xbfb8aa3b, v39
	v_exp_f32_e32 v39, v39
	v_div_fmas_f32 v37, v37, v42, v40
	v_div_fixup_f32 v37, v37, v38, 1.0
	v_mul_f32_e32 v28, v37, v28
	v_add_f32_e32 v38, 1.0, v39
	v_div_scale_f32 v39, s[6:7], v38, v38, 1.0
	v_rcp_f32_e32 v40, v39
	s_nop 0
	v_fma_f32 v37, -v39, v40, 1.0
	v_fmac_f32_e32 v40, v37, v40
	v_div_scale_f32 v37, vcc, 1.0, v38, 1.0
	v_mul_f32_e32 v41, v37, v40
	v_fma_f32 v42, -v39, v41, v37
	v_fmac_f32_e32 v41, v42, v40
	v_fma_f32 v37, -v39, v41, v37
	v_div_fmas_f32 v37, v37, v40, v41
	v_div_fixup_f32 v37, v37, v38, 1.0
	v_mul_f32_e32 v29, v37, v29
	v_cvt_pk_bf16_f32 v27, v28, v29
	global_store_dwordx2 v[30:31], v[26:27], off offset:64
	s_nop 0
	s_nop 1
	v_mov_b32_e32 v38, v198
	v_mov_b32_e32 v39, v199
	v_mov_b32_e32 v26, v216
	v_mov_b32_e32 v27, v217
	v_mov_b32_e32 v28, v218
	v_mov_b32_e32 v29, v219
	v_lshlrev_b32_e32 v37, 16, v38
	v_mul_f32_e32 v37, 0xbfb8aa3b, v37
	v_exp_f32_e32 v37, v37
	v_mul_f32_e32 v22, v26, v22
	v_and_b32_e32 v38, 0xffff0000, v38
	v_mul_f32_e32 v38, 0xbfb8aa3b, v38
	v_add_f32_e32 v37, 1.0, v37
	v_div_scale_f32 v40, s[6:7], v37, v37, 1.0
	v_rcp_f32_e32 v41, v40
	v_exp_f32_e32 v38, v38
	v_mul_f32_e32 v23, v27, v23
	v_mul_f32_e32 v24, v28, v24
	v_fma_f32 v26, -v40, v41, 1.0
	v_fmac_f32_e32 v41, v26, v41
	v_div_scale_f32 v26, vcc, 1.0, v37, 1.0
	v_mul_f32_e32 v42, v26, v41
	v_fma_f32 v43, -v40, v42, v26
	v_fmac_f32_e32 v42, v43, v41
	v_fma_f32 v26, -v40, v42, v26
	v_div_fmas_f32 v26, v26, v41, v42
	v_div_fixup_f32 v26, v26, v37, 1.0
	v_add_f32_e32 v37, 1.0, v38
	v_div_scale_f32 v38, s[6:7], v37, v37, 1.0
; __device__ __forceinline__ unsigned cvt_pk_bf16(float lo, float hi) { unsigned r; asm volatile("v_cvt_pk_bf16_f32 %0, %1, %2" : "=v"(r) : "v"(lo), "v"(hi)); return r; }
; __device__ __forceinline__ float bflo(unsigned w) { return __uint_as_float(w << 16); }
; __device__ __forceinline__ float bfhi(unsigned w) { return __uint_as_float(w & 0xffff0000u); }
; __device__ __forceinline__ float sigmoidf(float x) { return 1.f / (1.f + __expf(-x)); }
; __device__ __forceinline__ void mlstm_out_unit(const Params& P, int l, int h, int n, char* lds) {
;     ...
;         for (int j = 0; j < 8; ++j) { const int e = 32 * j + 4 * p; const f32x4 gn = *(const f32x4*)(mnorm + e);
;             const u32x2 mo = *(const u32x2*)(PROJ + row * PW + C_MO + h * 256 + e);
;             const float o0 = hv[j][0] * rs * gn[0] * sigmoidf(bflo(mo.x)), o1 = hv[j][1] * rs * gn[1] * sigmoidf(bfhi(mo.x));
;             const float o2 = hv[j][2] * rs * gn[2] * sigmoidf(bflo(mo.y)), o3 = hv[j][3] * rs * gn[3] * sigmoidf(bfhi(mo.y));
;             u32x2 w; w.x = cvt_pk_bf16(o0, o1); w.y = cvt_pk_bf16(o2, o3);
;             *(u32x2*)(MIX + row * DM + h * 256 + e) = w; }
	v_rcp_f32_e32 v40, v38
	v_mul_f32_e32 v22, v22, v26
	v_mul_f32_e32 v25, v29, v25
	v_fma_f32 v26, -v38, v40, 1.0
	v_fmac_f32_e32 v40, v26, v40
	v_div_scale_f32 v26, vcc, 1.0, v37, 1.0
	v_mul_f32_e32 v27, v26, v40
	v_fma_f32 v41, -v38, v27, v26
	v_fmac_f32_e32 v27, v41, v40
	v_fma_f32 v26, -v38, v27, v26
	v_lshlrev_b32_e32 v38, 16, v39
	v_mul_f32_e32 v38, 0xbfb8aa3b, v38
	v_exp_f32_e32 v38, v38
	v_div_fmas_f32 v26, v26, v40, v27
	v_div_fixup_f32 v26, v26, v37, 1.0
	v_mul_f32_e32 v23, v23, v26
	v_add_f32_e32 v27, 1.0, v38
	v_div_scale_f32 v37, s[6:7], v27, v27, 1.0
	v_rcp_f32_e32 v38, v37
	v_cvt_pk_bf16_f32 v22, v22, v23
	s_nop 0
	v_fma_f32 v26, -v37, v38, 1.0
	v_fmac_f32_e32 v38, v26, v38
	v_div_scale_f32 v26, vcc, 1.0, v27, 1.0
	v_mul_f32_e32 v28, v26, v38
	v_fma_f32 v40, -v37, v28, v26
	v_fmac_f32_e32 v28, v40, v38
	v_fma_f32 v26, -v37, v28, v26
	v_and_b32_e32 v37, 0xffff0000, v39
	v_mul_f32_e32 v37, 0xbfb8aa3b, v37
	v_exp_f32_e32 v37, v37
	v_div_fmas_f32 v26, v26, v38, v28
	v_div_fixup_f32 v26, v26, v27, 1.0
	v_mul_f32_e32 v24, v24, v26
	v_add_f32_e32 v27, 1.0, v37
	v_div_scale_f32 v28, s[6:7], v27, v27, 1.0
	v_rcp_f32_e32 v37, v28
	s_nop 0
	v_fma_f32 v26, -v28, v37, 1.0
	v_fmac_f32_e32 v37, v26, v37
	v_div_scale_f32 v26, vcc, 1.0, v27, 1.0
	v_mul_f32_e32 v29, v26, v37
	v_fma_f32 v38, -v28, v29, v26
	v_fmac_f32_e32 v29, v38, v37
	v_fma_f32 v26, -v28, v29, v26
	v_div_fmas_f32 v26, v26, v37, v29
	v_div_fixup_f32 v26, v26, v27, 1.0
	v_mul_f32_e32 v25, v25, v26
	v_cvt_pk_bf16_f32 v23, v24, v25
	global_store_dwordx2 v[30:31], v[22:23], off offset:128
	s_nop 0
	s_nop 1
	v_mov_b32_e32 v26, v200
	v_mov_b32_e32 v27, v201
	v_mov_b32_e32 v22, v220
	v_mov_b32_e32 v23, v221
	v_mov_b32_e32 v24, v222
	v_mov_b32_e32 v25, v223
	v_lshlrev_b32_e32 v28, 16, v26
	v_mul_f32_e32 v28, 0xbfb8aa3b, v28
	v_exp_f32_e32 v28, v28
	v_mul_f32_e32 v18, v18, v22
	v_and_b32_e32 v26, 0xffff0000, v26
	v_mul_f32_e32 v26, 0xbfb8aa3b, v26
	v_add_f32_e32 v22, 1.0, v28
	v_div_scale_f32 v28, s[6:7], v22, v22, 1.0
	v_rcp_f32_e32 v29, v28
	v_div_scale_f32 v37, vcc, 1.0, v22, 1.0
	v_exp_f32_e32 v26, v26
	v_fma_f32 v38, -v28, v29, 1.0
	v_fmac_f32_e32 v29, v38, v29
	v_mul_f32_e32 v38, v37, v29
	v_fma_f32 v39, -v28, v38, v37
	v_fmac_f32_e32 v38, v39, v29
	v_fma_f32 v28, -v28, v38, v37
	v_div_fmas_f32 v28, v28, v29, v38
	v_add_f32_e32 v26, 1.0, v26
	v_div_fixup_f32 v22, v28, v22, 1.0
	v_div_scale_f32 v28, s[6:7], v26, v26, 1.0
	v_rcp_f32_e32 v29, v28
	v_mul_f32_e32 v18, v18, v22
	v_mul_f32_e32 v19, v19, v23
	v_mul_f32_e32 v20, v20, v24
	v_fma_f32 v22, -v28, v29, 1.0
	v_fmac_f32_e32 v29, v22, v29
	v_div_scale_f32 v22, vcc, 1.0, v26, 1.0
	v_mul_f32_e32 v23, v22, v29
	v_fma_f32 v37, -v28, v23, v22
	v_fmac_f32_e32 v23, v37, v29
	v_fma_f32 v22, -v28, v23, v22
	v_lshlrev_b32_e32 v28, 16, v27
	v_mul_f32_e32 v28, 0xbfb8aa3b, v28
	v_exp_f32_e32 v28, v28
	v_div_fmas_f32 v22, v22, v29, v23
	v_div_fixup_f32 v22, v22, v26, 1.0
	v_mul_f32_e32 v19, v19, v22
	v_add_f32_e32 v23, 1.0, v28
	v_div_scale_f32 v26, s[6:7], v23, v23, 1.0
	v_rcp_f32_e32 v28, v26
	v_mul_f32_e32 v21, v21, v25
	v_cvt_pk_bf16_f32 v18, v18, v19
	v_fma_f32 v22, -v26, v28, 1.0
	v_fmac_f32_e32 v28, v22, v28
	v_div_scale_f32 v22, vcc, 1.0, v23, 1.0
	v_mul_f32_e32 v24, v22, v28
	v_fma_f32 v29, -v26, v24, v22
	v_fmac_f32_e32 v24, v29, v28
	v_fma_f32 v22, -v26, v24, v22
	v_and_b32_e32 v26, 0xffff0000, v27
	v_mul_f32_e32 v26, 0xbfb8aa3b, v26
	v_exp_f32_e32 v26, v26
	v_div_fmas_f32 v22, v22, v28, v24
	v_div_fixup_f32 v22, v22, v23, 1.0
	v_mul_f32_e32 v20, v20, v22
	v_add_f32_e32 v23, 1.0, v26
	v_div_scale_f32 v24, s[6:7], v23, v23, 1.0
	v_rcp_f32_e32 v26, v24
	s_nop 0
	v_fma_f32 v22, -v24, v26, 1.0
	v_fmac_f32_e32 v26, v22, v26
	v_div_scale_f32 v22, vcc, 1.0, v23, 1.0
	v_mul_f32_e32 v25, v22, v26
	v_fma_f32 v27, -v24, v25, v22
	v_fmac_f32_e32 v25, v27, v26
	v_fma_f32 v22, -v24, v25, v22
	v_div_fmas_f32 v22, v22, v26, v25
	v_div_fixup_f32 v22, v22, v23, 1.0
	v_mul_f32_e32 v21, v21, v22
	v_cvt_pk_bf16_f32 v19, v20, v21
	global_store_dwordx2 v[30:31], v[18:19], off offset:192
	s_nop 0
	s_nop 1
	v_mov_b32_e32 v22, v202
	v_mov_b32_e32 v23, v203
	v_mov_b32_e32 v18, v224
	v_mov_b32_e32 v19, v225
	v_mov_b32_e32 v20, v226
	v_mov_b32_e32 v21, v227
	v_lshlrev_b32_e32 v24, 16, v22
	v_and_b32_e32 v22, 0xffff0000, v22
	v_mul_f32_e32 v24, 0xbfb8aa3b, v24
	v_mul_f32_e32 v22, 0xbfb8aa3b, v22
	v_exp_f32_e32 v24, v24
	v_exp_f32_e32 v22, v22
	v_mul_f32_e32 v14, v14, v18
	v_mul_f32_e32 v15, v15, v19
	v_add_f32_e32 v18, 1.0, v24
	v_add_f32_e32 v19, 1.0, v22
	v_div_scale_f32 v22, s[6:7], v18, v18, 1.0
	v_rcp_f32_e32 v26, v22
	v_div_scale_f32 v24, vcc, 1.0, v18, 1.0
	v_div_scale_f32 v25, s[6:7], v19, v19, 1.0
	v_fma_f32 v29, -v22, v26, 1.0
	v_fmac_f32_e32 v26, v29, v26
	v_mul_f32_e32 v29, v24, v26
	v_fma_f32 v38, -v22, v29, v24
	v_rcp_f32_e32 v27, v25
	v_fmac_f32_e32 v29, v38, v26
	v_fma_f32 v22, -v22, v29, v24
	v_div_fmas_f32 v22, v22, v26, v29
	v_div_fixup_f32 v18, v22, v18, 1.0
	v_fma_f32 v37, -v25, v27, 1.0
	v_mul_f32_e32 v14, v14, v18
	v_lshlrev_b32_e32 v18, 16, v23
	v_div_scale_f32 v28, s[6:7], 1.0, v19, 1.0
	v_fmac_f32_e32 v27, v37, v27
	v_mul_f32_e32 v18, 0xbfb8aa3b, v18
	v_mul_f32_e32 v37, v28, v27
	v_exp_f32_e32 v18, v18
	v_fma_f32 v39, -v25, v37, v28
	v_fmac_f32_e32 v37, v39, v27
	v_fma_f32 v24, -v25, v37, v28
	s_mov_b64 vcc, s[6:7]
	v_div_fmas_f32 v22, v24, v27, v37
	v_add_f32_e32 v18, 1.0, v18
	v_div_fixup_f32 v19, v22, v19, 1.0
	v_div_scale_f32 v22, s[6:7], v18, v18, 1.0
	v_rcp_f32_e32 v24, v22
	v_mul_f32_e32 v15, v15, v19
	v_mul_f32_e32 v16, v16, v20
	v_mul_f32_e32 v17, v17, v21
	v_fma_f32 v19, -v22, v24, 1.0
	v_fmac_f32_e32 v24, v19, v24
; __device__ __forceinline__ unsigned cvt_pk_bf16(float lo, float hi) { unsigned r; asm volatile("v_cvt_pk_bf16_f32 %0, %1, %2" : "=v"(r) : "v"(lo), "v"(hi)); return r; }
; __device__ __forceinline__ float bflo(unsigned w) { return __uint_as_float(w << 16); }
; __device__ __forceinline__ float bfhi(unsigned w) { return __uint_as_float(w & 0xffff0000u); }
; __device__ __forceinline__ float sigmoidf(float x) { return 1.f / (1.f + __expf(-x)); }
; __device__ __forceinline__ void mlstm_out_unit(const Params& P, int l, int h, int n, char* lds) {
;     ...
;         for (int j = 0; j < 8; ++j) { const int e = 32 * j + 4 * p; const f32x4 gn = *(const f32x4*)(mnorm + e);
;             const u32x2 mo = *(const u32x2*)(PROJ + row * PW + C_MO + h * 256 + e);
;             const float o0 = hv[j][0] * rs * gn[0] * sigmoidf(bflo(mo.x)), o1 = hv[j][1] * rs * gn[1] * sigmoidf(bfhi(mo.x));
;             const float o2 = hv[j][2] * rs * gn[2] * sigmoidf(bflo(mo.y)), o3 = hv[j][3] * rs * gn[3] * sigmoidf(bfhi(mo.y));
;             u32x2 w; w.x = cvt_pk_bf16(o0, o1); w.y = cvt_pk_bf16(o2, o3);
;             *(u32x2*)(MIX + row * DM + h * 256 + e) = w; }
	v_div_scale_f32 v19, vcc, 1.0, v18, 1.0
	v_mul_f32_e32 v20, v19, v24
	v_fma_f32 v25, -v22, v20, v19
	v_fmac_f32_e32 v20, v25, v24
	v_fma_f32 v19, -v22, v20, v19
	v_and_b32_e32 v22, 0xffff0000, v23
	v_mul_f32_e32 v22, 0xbfb8aa3b, v22
	v_exp_f32_e32 v22, v22
	v_div_fmas_f32 v19, v19, v24, v20
	v_div_fixup_f32 v18, v19, v18, 1.0
	v_mul_f32_e32 v16, v16, v18
	v_add_f32_e32 v19, 1.0, v22
	v_div_scale_f32 v20, s[6:7], v19, v19, 1.0
	v_rcp_f32_e32 v22, v20
	v_cvt_pk_bf16_f32 v14, v14, v15
	s_nop 0
	v_fma_f32 v18, -v20, v22, 1.0
	v_fmac_f32_e32 v22, v18, v22
	v_div_scale_f32 v18, vcc, 1.0, v19, 1.0
	v_mul_f32_e32 v21, v18, v22
	v_fma_f32 v23, -v20, v21, v18
	v_fmac_f32_e32 v21, v23, v22
	v_fma_f32 v18, -v20, v21, v18
	v_div_fmas_f32 v18, v18, v22, v21
	v_div_fixup_f32 v18, v18, v19, 1.0
	v_mul_f32_e32 v17, v17, v18
	v_cvt_pk_bf16_f32 v15, v16, v17
	global_store_dwordx2 v[30:31], v[14:15], off offset:256
	s_nop 0
	s_nop 1
	v_mov_b32_e32 v14, v228
	v_mov_b32_e32 v15, v229
	v_mov_b32_e32 v16, v230
	v_mov_b32_e32 v17, v231
	v_mov_b32_e32 v18, v204
	v_mov_b32_e32 v19, v205
	v_mul_f32_e32 v6, v6, v14
	v_lshlrev_b32_e32 v14, 16, v18
	v_mul_f32_e32 v7, v7, v15
	v_and_b32_e32 v15, 0xffff0000, v18
	v_lshlrev_b32_e32 v18, 16, v19
	v_mul_f32_e32 v14, 0xbfb8aa3b, v14
	v_mul_f32_e32 v15, 0xbfb8aa3b, v15
	v_mul_f32_e32 v18, 0xbfb8aa3b, v18
	v_exp_f32_e32 v14, v14
	v_exp_f32_e32 v15, v15
	v_exp_f32_e32 v18, v18
	v_mul_f32_e32 v8, v8, v16
	v_add_f32_e32 v14, 1.0, v14
	v_add_f32_e32 v15, 1.0, v15
	v_add_f32_e32 v16, 1.0, v18
	v_div_scale_f32 v18, s[6:7], v14, v14, 1.0
	v_div_scale_f32 v21, s[6:7], v15, v15, 1.0
	v_rcp_f32_e32 v24, v18
	v_rcp_f32_e32 v25, v21
	v_div_scale_f32 v20, vcc, 1.0, v14, 1.0
	v_fma_f32 v28, -v18, v24, 1.0
	v_fma_f32 v29, -v21, v25, 1.0
	v_fmac_f32_e32 v24, v28, v24
	v_div_scale_f32 v22, s[6:7], 1.0, v15, 1.0
	v_fmac_f32_e32 v25, v29, v25
	v_mul_f32_e32 v28, v20, v24
	v_div_scale_f32 v23, s[8:9], v16, v16, 1.0
	v_mul_f32_e32 v29, v22, v25
	v_fma_f32 v38, -v18, v28, v20
	v_rcp_f32_e32 v26, v23
	v_fma_f32 v39, -v21, v29, v22
	v_fmac_f32_e32 v28, v38, v24
	v_fmac_f32_e32 v29, v39, v25
	v_fma_f32 v18, -v18, v28, v20
	v_fma_f32 v20, -v21, v29, v22
	v_div_fmas_f32 v18, v18, v24, v28
	s_mov_b64 vcc, s[6:7]
	v_div_fixup_f32 v14, v18, v14, 1.0
	v_div_fmas_f32 v18, v20, v25, v29
	v_fma_f32 v37, -v23, v26, 1.0
	v_mul_f32_e32 v6, v6, v14
	v_div_fixup_f32 v14, v18, v15, 1.0
	v_and_b32_e32 v15, 0xffff0000, v19
	v_div_scale_f32 v27, s[8:9], 1.0, v16, 1.0
	v_fmac_f32_e32 v26, v37, v26
	v_mul_f32_e32 v15, 0xbfb8aa3b, v15
	v_mul_f32_e32 v37, v27, v26
	v_exp_f32_e32 v15, v15
	v_mul_f32_e32 v7, v7, v14
	v_fma_f32 v14, -v23, v37, v27
	v_fmac_f32_e32 v37, v14, v26
	v_fma_f32 v14, -v23, v37, v27
	s_mov_b64 vcc, s[8:9]
	v_div_fmas_f32 v14, v14, v26, v37
	v_add_f32_e32 v15, 1.0, v15
	v_div_fixup_f32 v14, v14, v16, 1.0
	v_div_scale_f32 v16, s[6:7], v15, v15, 1.0
	v_rcp_f32_e32 v18, v16
	v_mul_f32_e32 v8, v8, v14
	v_mul_f32_e32 v9, v9, v17
	v_cvt_pk_bf16_f32 v6, v6, v7
	v_fma_f32 v14, -v16, v18, 1.0
	v_fmac_f32_e32 v18, v14, v18
	v_div_scale_f32 v14, vcc, 1.0, v15, 1.0
	v_mul_f32_e32 v17, v14, v18
	v_fma_f32 v19, -v16, v17, v14
	v_fmac_f32_e32 v17, v19, v18
	v_fma_f32 v14, -v16, v17, v14
	v_div_fmas_f32 v14, v14, v18, v17
	v_div_fixup_f32 v14, v14, v15, 1.0
	v_mul_f32_e32 v9, v9, v14
	v_cvt_pk_bf16_f32 v7, v8, v9
	global_store_dwordx2 v[30:31], v[6:7], off offset:320
	s_nop 0
	s_nop 1
	v_mov_b32_e32 v6, v232
	v_mov_b32_e32 v7, v233
	v_mov_b32_e32 v8, v234
	v_mov_b32_e32 v9, v235
	v_mov_b32_e32 v14, v206
	v_mov_b32_e32 v15, v207
	v_mul_f32_e32 v6, v10, v6
	v_lshlrev_b32_e32 v10, 16, v14
	v_mul_f32_e32 v7, v11, v7
	v_and_b32_e32 v11, 0xffff0000, v14
	v_mul_f32_e32 v10, 0xbfb8aa3b, v10
	v_mul_f32_e32 v8, v12, v8
	v_lshlrev_b32_e32 v12, 16, v15
	v_mul_f32_e32 v9, v13, v9
	v_and_b32_e32 v13, 0xffff0000, v15
	v_mul_f32_e32 v11, 0xbfb8aa3b, v11
	v_exp_f32_e32 v10, v10
	v_mul_f32_e32 v12, 0xbfb8aa3b, v12
	v_mul_f32_e32 v13, 0xbfb8aa3b, v13
	v_exp_f32_e32 v11, v11
	v_exp_f32_e32 v12, v12
	v_exp_f32_e32 v13, v13
	v_add_f32_e32 v10, 1.0, v10
	v_add_f32_e32 v11, 1.0, v11
	v_div_scale_f32 v14, s[6:7], v10, v10, 1.0
	v_add_f32_e32 v12, 1.0, v12
	v_add_f32_e32 v13, 1.0, v13
; __device__ __forceinline__ unsigned cvt_pk_bf16(float lo, float hi) { unsigned r; asm volatile("v_cvt_pk_bf16_f32 %0, %1, %2" : "=v"(r) : "v"(lo), "v"(hi)); return r; }
; __device__ __forceinline__ float bflo(unsigned w) { return __uint_as_float(w << 16); }
; __device__ __forceinline__ float bfhi(unsigned w) { return __uint_as_float(w & 0xffff0000u); }
; __device__ __forceinline__ float sigmoidf(float x) { return 1.f / (1.f + __expf(-x)); }
; __device__ __forceinline__ void mlstm_out_unit(const Params& P, int l, int h, int n, char* lds) {
;     ...
;         for (int j = 0; j < 8; ++j) { const int e = 32 * j + 4 * p; const f32x4 gn = *(const f32x4*)(mnorm + e);
;             const u32x2 mo = *(const u32x2*)(PROJ + row * PW + C_MO + h * 256 + e);
;             const float o0 = hv[j][0] * rs * gn[0] * sigmoidf(bflo(mo.x)), o1 = hv[j][1] * rs * gn[1] * sigmoidf(bfhi(mo.x));
;             const float o2 = hv[j][2] * rs * gn[2] * sigmoidf(bflo(mo.y)), o3 = hv[j][3] * rs * gn[3] * sigmoidf(bfhi(mo.y));
;             u32x2 w; w.x = cvt_pk_bf16(o0, o1); w.y = cvt_pk_bf16(o2, o3);
;             *(u32x2*)(MIX + row * DM + h * 256 + e) = w; }
;     }
;     __syncthreads();
	v_div_scale_f32 v16, s[6:7], v11, v11, 1.0
	v_rcp_f32_e32 v21, v14
	v_div_scale_f32 v18, s[8:9], v12, v12, 1.0
	v_div_scale_f32 v20, s[10:11], v13, v13, 1.0
	v_rcp_f32_e32 v22, v16
	v_rcp_f32_e32 v23, v18
	v_rcp_f32_e32 v24, v20
	v_fma_f32 v25, -v14, v21, 1.0
	v_div_scale_f32 v15, vcc, 1.0, v10, 1.0
	v_fma_f32 v26, -v16, v22, 1.0
	v_fmac_f32_e32 v21, v25, v21
	v_div_scale_f32 v17, s[6:7], 1.0, v11, 1.0
	v_fma_f32 v27, -v18, v23, 1.0
	v_fma_f32 v28, -v20, v24, 1.0
	v_fmac_f32_e32 v22, v26, v22
	v_mul_f32_e32 v25, v15, v21
	v_div_scale_f32 v19, s[8:9], 1.0, v12, 1.0
	v_fmac_f32_e32 v23, v27, v23
	v_fmac_f32_e32 v24, v28, v24
	v_mul_f32_e32 v26, v17, v22
	v_fma_f32 v28, -v14, v25, v15
	v_mul_f32_e32 v27, v19, v23
	v_fma_f32 v29, -v16, v26, v17
	v_fmac_f32_e32 v25, v28, v21
	v_fma_f32 v37, -v18, v27, v19
	v_fmac_f32_e32 v26, v29, v22
	v_fma_f32 v14, -v14, v25, v15
	v_fmac_f32_e32 v27, v37, v23
	v_fma_f32 v15, -v16, v26, v17
	v_div_fmas_f32 v14, v14, v21, v25
	s_mov_b64 vcc, s[6:7]
	v_fma_f32 v16, -v18, v27, v19
	v_div_fixup_f32 v10, v14, v10, 1.0
	v_div_fmas_f32 v14, v15, v22, v26
	s_mov_b64 vcc, s[8:9]
	v_mul_f32_e32 v6, v6, v10
	v_div_fixup_f32 v10, v14, v11, 1.0
	v_div_fmas_f32 v11, v16, v23, v27
	v_mul_f32_e32 v7, v7, v10
	v_div_fixup_f32 v10, v11, v12, 1.0
	v_mul_f32_e32 v8, v8, v10
	v_div_scale_f32 v10, vcc, 1.0, v13, 1.0
	v_mul_f32_e32 v11, v10, v24
	v_fma_f32 v12, -v20, v11, v10
	v_fmac_f32_e32 v11, v12, v24
	v_fma_f32 v10, -v20, v11, v10
	v_div_fmas_f32 v10, v10, v24, v11
	v_div_fixup_f32 v10, v10, v13, 1.0
	v_mul_f32_e32 v9, v9, v10
	v_cvt_pk_bf16_f32 v6, v6, v7
	v_cvt_pk_bf16_f32 v7, v8, v9
	global_store_dwordx2 v[30:31], v[6:7], off offset:384
	s_nop 0
	s_nop 1
	v_mov_b32_e32 v6, v236
	v_mov_b32_e32 v7, v237
	v_mov_b32_e32 v8, v238
	v_mov_b32_e32 v9, v239
	v_mov_b32_e32 v10, v208
	v_mov_b32_e32 v11, v209
	v_mul_f32_e32 v2, v2, v6
	v_lshlrev_b32_e32 v6, 16, v10
	v_mul_f32_e32 v3, v3, v7
	v_and_b32_e32 v7, 0xffff0000, v10
	v_mul_f32_e32 v6, 0xbfb8aa3b, v6
	v_mul_f32_e32 v4, v4, v8
	v_lshlrev_b32_e32 v8, 16, v11
	v_mul_f32_e32 v7, 0xbfb8aa3b, v7
	v_exp_f32_e32 v6, v6
	v_mul_f32_e32 v5, v5, v9
	v_and_b32_e32 v9, 0xffff0000, v11
	v_mul_f32_e32 v8, 0xbfb8aa3b, v8
	v_exp_f32_e32 v7, v7
	v_mul_f32_e32 v9, 0xbfb8aa3b, v9
	v_exp_f32_e32 v8, v8
	v_exp_f32_e32 v9, v9
	v_add_f32_e32 v6, 1.0, v6
	v_add_f32_e32 v7, 1.0, v7
	v_div_scale_f32 v10, s[6:7], v6, v6, 1.0
	v_add_f32_e32 v8, 1.0, v8
	v_div_scale_f32 v12, s[6:7], v7, v7, 1.0
	v_rcp_f32_e32 v18, v10
	v_add_f32_e32 v9, 1.0, v9
	v_div_scale_f32 v14, s[8:9], v8, v8, 1.0
	v_rcp_f32_e32 v19, v12
	v_div_scale_f32 v16, s[10:11], v9, v9, 1.0
	v_rcp_f32_e32 v20, v14
	v_rcp_f32_e32 v21, v16
	v_fma_f32 v22, -v10, v18, 1.0
	v_div_scale_f32 v11, vcc, 1.0, v6, 1.0
	v_fma_f32 v23, -v12, v19, 1.0
	v_fmac_f32_e32 v18, v22, v18
	v_div_scale_f32 v13, s[6:7], 1.0, v7, 1.0
	v_fma_f32 v24, -v14, v20, 1.0
	v_fmac_f32_e32 v19, v23, v19
	v_mul_f32_e32 v22, v11, v18
	v_div_scale_f32 v15, s[8:9], 1.0, v8, 1.0
	v_fma_f32 v25, -v16, v21, 1.0
	v_fmac_f32_e32 v20, v24, v20
	v_mul_f32_e32 v23, v13, v19
	v_fma_f32 v26, -v10, v22, v11
	v_div_scale_f32 v17, s[10:11], 1.0, v9, 1.0
	v_fmac_f32_e32 v21, v25, v21
	v_mul_f32_e32 v24, v15, v20
	v_fma_f32 v27, -v12, v23, v13
	v_fmac_f32_e32 v22, v26, v18
	v_mul_f32_e32 v25, v17, v21
	v_fma_f32 v28, -v14, v24, v15
	v_fmac_f32_e32 v23, v27, v19
	v_fma_f32 v10, -v10, v22, v11
	v_fma_f32 v29, -v16, v25, v17
	v_fmac_f32_e32 v24, v28, v20
	v_fma_f32 v11, -v12, v23, v13
	v_div_fmas_f32 v10, v10, v18, v22
	s_mov_b64 vcc, s[6:7]
	v_fmac_f32_e32 v25, v29, v21
	v_fma_f32 v12, -v14, v24, v15
	v_div_fixup_f32 v6, v10, v6, 1.0
	v_div_fmas_f32 v10, v11, v19, v23
	s_mov_b64 vcc, s[8:9]
	v_fma_f32 v13, -v16, v25, v17
	v_mul_f32_e32 v2, v2, v6
	v_div_fixup_f32 v6, v10, v7, 1.0
	v_div_fmas_f32 v7, v12, v20, v24
	s_mov_b64 vcc, s[10:11]
	v_mul_f32_e32 v3, v3, v6
	v_div_fixup_f32 v6, v7, v8, 1.0
	v_div_fmas_f32 v7, v13, v21, v25
	v_mul_f32_e32 v4, v4, v6
	v_div_fixup_f32 v6, v7, v9, 1.0
	v_cvt_pk_bf16_f32 v2, v2, v3
	v_mul_f32_e32 v3, v5, v6
	s_mov_b64 s[6:7], 0
	v_cvt_pk_bf16_f32 v3, v4, v3
	global_store_dwordx2 v[30:31], v[2:3], off offset:448
	s_waitcnt lgkmcnt(0)
	s_barrier

; __device__ __forceinline__ float bflo(unsigned w) { return __uint_as_float(w << 16); }
; __device__ __forceinline__ float bfhi(unsigned w) { return __uint_as_float(w & 0xffff0000u); }
; __device__ __forceinline__ void conv_silu8(const bf16_t* __restrict__ PROJ, const float* __restrict__ cw, const float* __restrict__ cb, int row, int ch, float (&y)[8]) {
;     const f32x4 b0 = *(const f32x4*)(cb + ch), b1 = *(const f32x4*)(cb + ch + 4);
;     float a[8] = {b0[0], b0[1], b0[2], b0[3], b1[0], b1[1], b1[2], b1[3]};
; #pragma unroll
;     for (int k = 0; k < 4; ++k) { const int rr = row - 3 + k;
;         if (rr >= 0) { const u32x4 x = *(const u32x4*)(PROJ + (size_t)rr * PW + ch);
;             const f32x4 w0 = *(const f32x4*)(cw + k * 1024 + ch), w1 = *(const f32x4*)(cw + k * 1024 + ch + 4);
;             a[0] += w0[0] * bflo(x.x); a[1] += w0[1] * bfhi(x.x); a[2] += w0[2] * bflo(x.y); a[3] += w0[3] * bfhi(x.y);
;             a[4] += w1[0] * bflo(x.z); a[5] += w1[1] * bfhi(x.z); a[6] += w1[2] * bflo(x.w); a[7] += w1[3] * bfhi(x.w); } }
.LBB0_2409:
	s_waitcnt lgkmcnt(0)
	s_add_u32 s14, s40, 0xeb00000
	s_addc_u32 s15, s41, 0
	s_add_u32 s16, s16, 0x4000
	s_addc_u32 s17, s17, 0
	s_add_u32 s18, s18, 0x1000
	v_lshlrev_b32_e32 v15, 3, v20
	v_ashrrev_i32_e32 v2, 1, v20
	s_addc_u32 s19, s19, 0
	s_lshl_b32 s22, s66, 7
	v_and_b32_e32 v17, 0x78, v15
	v_and_b32_e32 v2, 0xfffffe00, v2
	v_or3_b32 v10, s22, v2, v17
	v_ashrrev_i32_e32 v11, 31, v10
	v_lshlrev_b64 v[22:23], 2, v[10:11]
	v_lshl_add_u64 v[2:3], s[18:19], 0, v[22:23]
	global_load_dwordx4 v[6:9], v[2:3], off
	s_nop 0
	global_load_dwordx4 v[2:5], v[2:3], off offset:16
	v_bfe_u32 v16, v20, 4, 6
	v_or_b32_e32 v19, s64, v16
	v_lshl_add_u64 v[12:13], v[10:11], 1, s[14:15]
	v_lshl_add_u64 v[10:11], s[16:17], 0, v[22:23]
	v_cmp_lt_i32_e64 s[6:7], 2, v19
	v_add_u32_e32 v22, -3, v19
	s_and_saveexec_b64 s[8:9], s[6:7]
	s_cbranch_execz .LBB0_2411
	v_mad_u64_u32 v[24:25], s[10:11], v22, s50, v[12:13]
	global_load_dwordx4 v[24:27], v[24:25], off
	s_nop 0
	global_load_dwordx4 v[28:31], v[10:11], off
	global_load_dwordx4 v[32:35], v[10:11], off offset:16
	s_waitcnt vmcnt(0) lgkmcnt(0)
	v_lshlrev_b32_e32 v36, 16, v24
	v_and_b32_e32 v37, 0xffff0000, v24
	v_lshlrev_b32_e32 v24, 16, v25
	v_and_b32_e32 v25, 0xffff0000, v25
	v_lshlrev_b32_e32 v38, 16, v26
	v_and_b32_e32 v39, 0xffff0000, v26
	v_lshlrev_b32_e32 v26, 16, v27
	v_and_b32_e32 v27, 0xffff0000, v27
	v_pk_fma_f32 v[6:7], v[28:29], v[36:37], v[6:7]
	v_pk_fma_f32 v[8:9], v[30:31], v[24:25], v[8:9]
	v_pk_fma_f32 v[2:3], v[32:33], v[38:39], v[2:3]
	v_pk_fma_f32 v[4:5], v[34:35], v[26:27], v[4:5]

; __device__ __forceinline__ unsigned cvt_pk_bf16(float lo, float hi) { unsigned r; asm volatile("v_cvt_pk_bf16_f32 %0, %1, %2" : "=v"(r) : "v"(lo), "v"(hi)); return r; }
; __device__ __forceinline__ float bflo(unsigned w) { return __uint_as_float(w << 16); }
; __device__ __forceinline__ void conv_silu8(const bf16_t* __restrict__ PROJ, const float* __restrict__ cw, const float* __restrict__ cb, int row, int ch, float (&y)[8]) {
;     const f32x4 b0 = *(const f32x4*)(cb + ch), b1 = *(const f32x4*)(cb + ch + 4);
;     float a[8] = {b0[0], b0[1], b0[2], b0[3], b1[0], b1[1], b1[2], b1[3]};
; #pragma unroll
;     for (int k = 0; k < 4; ++k) { const int rr = row - 3 + k;
;         if (rr >= 0) { const u32x4 x = *(const u32x4*)(PROJ + (size_t)rr * PW + ch);
;             const f32x4 w0 = *(const f32x4*)(cw + k * 1024 + ch), w1 = *(const f32x4*)(cw + k * 1024 + ch + 4);
;             a[0] += w0[0] * bflo(x.x); a[1] += w0[1] * bfhi(x.x); a[2] += w0[2] * bflo(x.y); a[3] += w0[3] * bfhi(x.y);
;             a[4] += w1[0] * bflo(x.z); a[5] += w1[1] * bfhi(x.z); a[6] += w1[2] * bflo(x.w); a[7] += w1[3] * bfhi(x.w); } }
; #pragma unroll
;     for (int i = 0; i < 8; ++i) y[i] = a[i] * sigmoidf(a[i]);
; __device__ __forceinline__ void mlstm_out_unit(const Params& P, int l, int h, int n, char* lds) {
;     ...
;     for (int i = 0; i < 4; ++i) { const int idx = tid + 512 * i, which = idx >> 10, t = (idx >> 4) & 63, c = idx & 15; float y[8];
;         conv_silu8(PROJ, cw, cb, t0 + t, which * 512 + h * 128 + c * 8, y);
;         const float sc = which ? 1.f : 0.08838834764831845f;
;         u32x4 w; w.x = cvt_pk_bf16(y[0] * sc, y[1] * sc); w.y = cvt_pk_bf16(y[2] * sc, y[3] * sc); w.z = cvt_pk_bf16(y[4] * sc, y[5] * sc); w.w = cvt_pk_bf16(y[6] * sc, y[7] * sc);
;         *(u32x4*)((which ? Kl : Ql) + t * 136 + c * 8) = w; }
; #pragma unroll
;     for (int i = 0; i < 4; ++i) { const int idx = tid + 512 * i, t = idx >> 5, c = idx & 31;
;         const u32x4 x = *(const u32x4*)(PROJ + (size_t)(t0 + t) * PW + C_MV + h * 256 + c * 8);
;         bf16_t* vp = VT + (c * 8) * 72 + tsw(c * 8, t);
;         vp[0] = (bf16_t)(x.x & 0xffffu); vp[72] = (bf16_t)(x.x >> 16); vp[144] = (bf16_t)(x.y & 0xffffu); vp[216] = (bf16_t)(x.y >> 16);
;         vp[288] = (bf16_t)(x.z & 0xffffu); vp[360] = (bf16_t)(x.z >> 16); vp[432] = (bf16_t)(x.w & 0xffffu); vp[504] = (bf16_t)(x.w >> 16); }
.LBB0_2433:
	s_waitcnt vmcnt(0) lgkmcnt(0)
	v_mul_f32_e32 v10, 0xbfb8aa3b, v6
	v_exp_f32_e32 v10, v10
	v_mul_f32_e32 v23, 0xbfb8aa3b, v7
	v_exp_f32_e32 v23, v23
	s_lshl_b64 s[6:7], s[44:45], 16
	v_add_f32_e32 v10, 1.0, v10
	v_div_scale_f32 v11, s[8:9], v10, v10, 1.0
	v_rcp_f32_e32 v12, v11
	v_div_scale_f32 v13, vcc, 1.0, v10, 1.0
	s_add_u32 s6, s40, s6
	v_fma_f32 v22, -v11, v12, 1.0
	v_fmac_f32_e32 v12, v22, v12
	v_mul_f32_e32 v22, v13, v12
	v_fma_f32 v24, -v11, v22, v13
	v_fmac_f32_e32 v22, v24, v12
	v_fma_f32 v11, -v11, v22, v13
	v_add_f32_e32 v13, 1.0, v23
	v_div_scale_f32 v23, s[8:9], v13, v13, 1.0
	v_rcp_f32_e32 v24, v23
	v_div_fmas_f32 v11, v11, v12, v22
	v_mul_f32_e32 v12, 0xbfb8aa3b, v8
	v_div_fixup_f32 v10, v11, v10, 1.0
	v_exp_f32_e32 v12, v12
	v_mul_f32_e32 v6, v6, v10
	v_fma_f32 v10, -v23, v24, 1.0
	v_fmac_f32_e32 v24, v10, v24
	v_div_scale_f32 v10, vcc, 1.0, v13, 1.0
	v_mul_f32_e32 v11, v10, v24
	v_fma_f32 v22, -v23, v11, v10
	v_add_f32_e32 v12, 1.0, v12
	v_fmac_f32_e32 v11, v22, v24
	v_div_scale_f32 v22, s[8:9], v12, v12, 1.0
	v_fma_f32 v10, -v23, v11, v10
	v_rcp_f32_e32 v23, v22
	v_div_fmas_f32 v10, v10, v24, v11
	v_div_fixup_f32 v10, v10, v13, 1.0
	v_mul_f32_e32 v13, 0xbfb8aa3b, v9
	v_mul_f32_e32 v7, v7, v10
	v_fma_f32 v10, -v22, v23, 1.0
	v_exp_f32_e32 v13, v13
	v_fmac_f32_e32 v23, v10, v23
	v_div_scale_f32 v10, vcc, 1.0, v12, 1.0
	v_mul_f32_e32 v11, v10, v23
	v_fma_f32 v24, -v22, v11, v10
	v_fmac_f32_e32 v11, v24, v23
	v_add_f32_e32 v13, 1.0, v13
	v_fma_f32 v10, -v22, v11, v10
	v_div_scale_f32 v22, s[8:9], v13, v13, 1.0
	v_rcp_f32_e32 v24, v22
	v_div_fmas_f32 v10, v10, v23, v11
	v_div_fixup_f32 v10, v10, v12, 1.0
	v_mul_f32_e32 v12, 0xbfb8aa3b, v2
	v_mul_f32_e32 v8, v8, v10
	v_fma_f32 v10, -v22, v24, 1.0
	v_exp_f32_e32 v12, v12
	v_fmac_f32_e32 v24, v10, v24
	v_div_scale_f32 v10, vcc, 1.0, v13, 1.0
	v_mul_f32_e32 v11, v10, v24
	v_fma_f32 v23, -v22, v11, v10
	v_fmac_f32_e32 v11, v23, v24
	v_add_f32_e32 v12, 1.0, v12
	v_fma_f32 v10, -v22, v11, v10
	v_div_scale_f32 v22, s[8:9], v12, v12, 1.0
	v_rcp_f32_e32 v23, v22
	v_div_fmas_f32 v10, v10, v24, v11
	v_div_fixup_f32 v10, v10, v13, 1.0
	v_mul_f32_e32 v13, 0xbfb8aa3b, v3
	v_mul_f32_e32 v9, v9, v10
	v_fma_f32 v10, -v22, v23, 1.0
	v_exp_f32_e32 v13, v13
	v_fmac_f32_e32 v23, v10, v23
	v_div_scale_f32 v10, vcc, 1.0, v12, 1.0
	v_mul_f32_e32 v11, v10, v23
	v_fma_f32 v24, -v22, v11, v10
	v_fmac_f32_e32 v11, v24, v23
	v_add_f32_e32 v13, 1.0, v13
	v_fma_f32 v10, -v22, v11, v10
	v_div_scale_f32 v22, s[8:9], v13, v13, 1.0
	v_rcp_f32_e32 v24, v22
	v_div_fmas_f32 v10, v10, v23, v11
	v_div_fixup_f32 v10, v10, v12, 1.0
	v_mul_f32_e32 v12, 0xbfb8aa3b, v4
	v_mul_f32_e32 v10, v2, v10
	v_fma_f32 v2, -v22, v24, 1.0
	v_exp_f32_e32 v12, v12
	v_fmac_f32_e32 v24, v2, v24
	v_div_scale_f32 v2, vcc, 1.0, v13, 1.0
	v_mul_f32_e32 v11, v2, v24
	v_fma_f32 v23, -v22, v11, v2
	v_fmac_f32_e32 v11, v23, v24
	v_add_f32_e32 v12, 1.0, v12
	v_fma_f32 v2, -v22, v11, v2
	v_div_scale_f32 v22, s[8:9], v12, v12, 1.0
	v_rcp_f32_e32 v23, v22
	v_div_fmas_f32 v2, v2, v24, v11
	v_div_fixup_f32 v2, v2, v13, 1.0
	v_mul_f32_e32 v13, 0xbfb8aa3b, v5
	v_mul_f32_e32 v11, v3, v2
	v_fma_f32 v2, -v22, v23, 1.0
	v_exp_f32_e32 v13, v13
	v_fmac_f32_e32 v23, v2, v23
	v_div_scale_f32 v2, vcc, 1.0, v12, 1.0
	v_mul_f32_e32 v3, v2, v23
	v_fma_f32 v24, -v22, v3, v2
	v_fmac_f32_e32 v3, v24, v23
	v_add_f32_e32 v13, 1.0, v13
	v_fma_f32 v2, -v22, v3, v2
	v_div_scale_f32 v22, s[8:9], v13, v13, 1.0
	v_rcp_f32_e32 v24, v22
	v_div_fmas_f32 v2, v2, v23, v3
	v_div_fixup_f32 v2, v2, v12, 1.0
	v_mul_f32_e32 v12, v4, v2
	v_fma_f32 v2, -v22, v24, 1.0
	v_fmac_f32_e32 v24, v2, v24
	v_div_scale_f32 v2, vcc, 1.0, v13, 1.0
	v_mul_f32_e32 v3, v2, v24
	v_fma_f32 v4, -v22, v3, v2
	v_fmac_f32_e32 v3, v4, v24
	v_fma_f32 v2, -v22, v3, v2
	v_div_fmas_f32 v2, v2, v24, v3
	v_cmp_gt_u32_e32 vcc, s52, v19
	v_div_fixup_f32 v2, v2, v13, 1.0
	v_mul_f32_e32 v5, v5, v2
	v_cndmask_b32_e32 v13, 1.0, v108, vcc
	v_mul_f32_e32 v2, v13, v6
	v_mul_f32_e32 v3, v13, v7
	v_cvt_pk_bf16_f32 v2, v2, v3
	v_mul_f32_e32 v3, v13, v8
	v_mul_f32_e32 v4, v13, v9
	v_cvt_pk_bf16_f32 v3, v3, v4
	v_mul_f32_e32 v4, v13, v10
	v_mul_f32_e32 v6, v13, v11
	v_cvt_pk_bf16_f32 v4, v4, v6
	v_mul_f32_e32 v6, v13, v12
	v_mul_f32_e32 v5, v13, v5
	v_cvt_pk_bf16_f32 v5, v6, v5
	v_mov_b32_e32 v6, s53
	v_cndmask_b32_e32 v6, v6, v94, vcc
	v_mul_u32_u24_e32 v7, 0x110, v17
	v_add3_u32 v6, v6, v7, v18
	v_ashrrev_i32_e32 v9, 5, v20
	ds_write_b128 v6, v[2:5]
	v_add_u32_e32 v2, s64, v9
	v_mov_b64_e32 v[6:7], s[14:15]
	s_addc_u32 s7, s41, s7
	v_and_b32_e32 v8, 0xf8, v15
	v_mad_i64_i32 v[2:3], s[8:9], v2, s50, v[6:7]
	s_lshl_b32 s26, s66, 9
	v_lshl_add_u64 v[2:3], v[2:3], 0, s[26:27]
	v_lshlrev_b32_e32 v90, 1, v8
	v_lshl_add_u64 v[2:3], v[2:3], 0, v[90:91]
	global_load_dwordx4 v[2:5], v[2:3], off offset:2048
	v_add_u32_e32 v10, v9, v15
	v_and_b32_e32 v10, 62, v10
	v_lshlrev_b32_e32 v9, 1, v9
	v_mad_u32_u24 v8, v8, s56, v94
	v_lshlrev_b32_e32 v10, 1, v10
	v_and_b32_e32 v9, 2, v9
	v_add3_u32 v9, v8, v10, v9
	v_and_b32_e32 v22, 31, v20
	v_lshl_or_b32 v18, s65, 5, v22
	s_cmp_gt_i32 s65, 3
	s_waitcnt vmcnt(0) lgkmcnt(0)
; __device__ __forceinline__ int tsw(int row, int t) { return ((((t >> 1) + 4 * ((row >> 3) & 7)) & 31) << 1) | (t & 1); }
; __device__ __forceinline__ void mlstm_out_unit(const Params& P, int l, int h, int n, char* lds) {
;     ...
;     for (int i = 0; i < 4; ++i) { const int idx = tid + 512 * i, t = idx >> 5, c = idx & 31;
;         const u32x4 x = *(const u32x4*)(PROJ + (size_t)(t0 + t) * PW + C_MV + h * 256 + c * 8);
;         bf16_t* vp = VT + (c * 8) * 72 + tsw(c * 8, t);
;         vp[0] = (bf16_t)(x.x & 0xffffu); vp[72] = (bf16_t)(x.x >> 16); vp[144] = (bf16_t)(x.y & 0xffffu); vp[216] = (bf16_t)(x.y >> 16);
;         vp[288] = (bf16_t)(x.z & 0xffffu); vp[360] = (bf16_t)(x.z >> 16); vp[432] = (bf16_t)(x.w & 0xffffu); vp[504] = (bf16_t)(x.w >> 16); }
;     bf16x8 cfr[8];
; #pragma unroll
;     for (int ks = 0; ks < 8; ++ks) cfr[ks] = *(const bf16x8*)(ct + (size_t)(32 * wid + r32) * 128 + 16 * ks + 8 * hi);
;     __syncthreads();
;     if (wid < 4) {
;         const int ti = wid >> 1, si = wid & 1;
;         f32x16 acc = {};
;         if (si <= ti) {
; #pragma unroll
;             for (int ks = 0; ks < 8; ++ks) { const bf16x8 A = *(const bf16x8*)(Ql + (32 * ti + r32) * 136 + 16 * ks + 8 * hi);
;                 const bf16x8 B = *(const bf16x8*)(Kl + (32 * si + r32) * 136 + 16 * ks + 8 * hi);
;                 acc = __builtin_amdgcn_mfma_f32_32x32x16_bf16(A, B, acc, 0, 0, 0); }
	ds_write_b16 v9, v2 offset:34816
	ds_write_b16_d16_hi v9, v2 offset:34960
	ds_write_b16 v9, v3 offset:35104
	ds_write_b16_d16_hi v9, v3 offset:35248
	ds_write_b16 v9, v4 offset:35392
	ds_write_b16_d16_hi v9, v4 offset:35536
	ds_write_b16 v9, v5 offset:35680
	ds_write_b16_d16_hi v9, v5 offset:35824
	v_ashrrev_i32_e32 v9, 5, v16
	v_add_u32_e32 v2, s64, v9
	v_mad_i64_i32 v[2:3], s[8:9], v2, s50, v[6:7]
	v_lshl_add_u64 v[2:3], v[2:3], 0, s[26:27]
	v_lshl_add_u64 v[2:3], v[2:3], 0, v[90:91]
	global_load_dwordx4 v[2:5], v[2:3], off offset:2048
	v_add_u32_e32 v10, v9, v15
	v_and_b32_e32 v10, 62, v10
	v_lshlrev_b32_e32 v9, 1, v9
	v_lshlrev_b32_e32 v10, 1, v10
	v_and_b32_e32 v9, 2, v9
	v_add3_u32 v9, v8, v10, v9
	v_ashrrev_i32_e32 v10, 5, v19
	v_add_u32_e32 v12, s64, v10
	v_ashrrev_i32_e32 v19, 31, v18
	s_waitcnt vmcnt(0) lgkmcnt(0)
	ds_write_b16 v9, v2 offset:34816
	ds_write_b16_d16_hi v9, v2 offset:34960
	ds_write_b16 v9, v3 offset:35104
	ds_write_b16_d16_hi v9, v3 offset:35248
	ds_write_b16 v9, v4 offset:35392
	ds_write_b16_d16_hi v9, v4 offset:35536
	ds_write_b16 v9, v5 offset:35680
	ds_write_b16_d16_hi v9, v5 offset:35824
	v_ashrrev_i32_e32 v9, 5, v21
	v_add_u32_e32 v2, s64, v9
	v_mad_i64_i32 v[2:3], s[8:9], v2, s50, v[6:7]
	v_lshl_add_u64 v[2:3], v[2:3], 0, s[26:27]
	v_lshl_add_u64 v[2:3], v[2:3], 0, v[90:91]
	global_load_dwordx4 v[2:5], v[2:3], off offset:2048
	v_add_u32_e32 v11, v9, v15
	v_lshlrev_b32_e32 v9, 1, v9
	v_and_b32_e32 v11, 62, v11
	v_and_b32_e32 v9, 2, v9
	v_mad_i64_i32 v[6:7], s[8:9], v12, s50, v[6:7]
	v_lshlrev_b32_e32 v11, 1, v11
	v_lshl_add_u64 v[6:7], v[6:7], 0, s[26:27]
	v_add3_u32 v9, v8, v11, v9
	v_lshl_add_u64 v[6:7], v[6:7], 0, v[90:91]
	s_waitcnt vmcnt(0) lgkmcnt(0)
	ds_write_b16 v9, v2 offset:34816
	ds_write_b16_d16_hi v9, v2 offset:34960
	ds_write_b16 v9, v3 offset:35104
	ds_write_b16_d16_hi v9, v3 offset:35248
	ds_write_b16 v9, v4 offset:35392
	ds_write_b16_d16_hi v9, v4 offset:35536
	ds_write_b16 v9, v5 offset:35680
	ds_write_b16_d16_hi v9, v5 offset:35824
	global_load_dwordx4 v[2:5], v[6:7], off offset:2048
	v_add_u32_e32 v6, v10, v15
	v_lshlrev_b32_e32 v7, 1, v10
	v_and_b32_e32 v6, 62, v6
	v_lshrrev_b32_e32 v21, 5, v14
	v_and_b32_e32 v9, 2, v7
	v_lshlrev_b32_e32 v10, 1, v6
	v_lshlrev_b64 v[6:7], 8, v[18:19]
	v_lshl_add_u64 v[6:7], s[6:7], 0, v[6:7]
	v_lshlrev_b32_e32 v90, 4, v21
	v_add3_u32 v10, v8, v10, v9
	v_lshl_add_u64 v[6:7], v[6:7], 0, v[90:91]
	v_lshl_add_u64 v[8:9], v[6:7], 0, s[34:35]
	v_add_co_u32_e32 v6, vcc, s57, v6
	s_waitcnt vmcnt(0) lgkmcnt(0)
	ds_write_b16 v10, v2 offset:34816
	ds_write_b16_d16_hi v10, v2 offset:34960
	ds_write_b16 v10, v3 offset:35104
	ds_write_b16_d16_hi v10, v3 offset:35248
	ds_write_b16 v10, v4 offset:35392
	ds_write_b16_d16_hi v10, v4 offset:35536
	ds_write_b16 v10, v5 offset:35680
	ds_write_b16_d16_hi v10, v5 offset:35824
	v_addc_co_u32_e32 v7, vcc, 0, v7, vcc
	global_load_dwordx4 v[86:89], v[8:9], off offset:32
	global_load_dwordx4 v[82:85], v[8:9], off offset:64
	global_load_dwordx4 v[78:81], v[8:9], off offset:96
	global_load_dwordx4 v[74:77], v[8:9], off offset:128
	global_load_dwordx4 v[70:73], v[8:9], off offset:160
	global_load_dwordx4 v[66:69], v[8:9], off offset:192
	global_load_dwordx4 v[46:49], v[6:7], off
	global_load_dwordx4 v[62:65], v[8:9], off offset:224
	v_lshlrev_b32_e32 v19, 3, v21
	s_waitcnt lgkmcnt(0)
	s_barrier
	s_cbranch_scc1 .LBB0_2471
	s_ashr_i32 s8, s67, 7
	s_bfe_u32 s9, s67, 0x10006
	s_cmp_le_i32 s9, s8
	s_mov_b64 s[6:7], -1
	s_cbranch_scc0 .LBB0_2436
	s_lshl_b32 s10, s8, 5
	v_or_b32_e32 v2, s10, v22
	v_mul_lo_u32 v2, v2, s54
	v_lshlrev_b32_e32 v6, 1, v19
	v_add3_u32 v40, s3, v2, v6
	ds_read_b128 v[2:5], v40
	v_lshl_or_b32 v23, s9, 5, v22
	v_mul_u32_u24_e32 v7, 0x110, v23
	v_add3_u32 v41, s3, v7, v6
	ds_read_b128 v[6:9], v41 offset:17408
	ds_read_b128 v[24:27], v41 offset:17440
	ds_read_b128 v[28:31], v40 offset:32
	s_mov_b64 s[6:7], 0
	s_waitcnt lgkmcnt(0)
	v_mfma_f32_32x32x16_bf16 v[2:17], v[2:5], v[6:9], 0
	v_mfma_f32_32x32x16_bf16 v[2:17], v[28:31], v[24:27], v[2:17]
	ds_read_b128 v[24:27], v40 offset:64
	ds_read_b128 v[28:31], v41 offset:17472
	ds_read_b128 v[32:35], v41 offset:17504
	ds_read_b128 v[36:39], v40 offset:96
	s_waitcnt lgkmcnt(0)
	v_mfma_f32_32x32x16_bf16 v[2:17], v[24:27], v[28:31], v[2:17]
	v_mfma_f32_32x32x16_bf16 v[2:17], v[36:39], v[32:35], v[2:17]
	ds_read_b128 v[24:27], v40 offset:128
	ds_read_b128 v[28:31], v41 offset:17536
	ds_read_b128 v[32:35], v41 offset:17568
	ds_read_b128 v[36:39], v40 offset:160
	s_waitcnt lgkmcnt(0)
	v_mfma_f32_32x32x16_bf16 v[2:17], v[24:27], v[28:31], v[2:17]
	v_mfma_f32_32x32x16_bf16 v[2:17], v[36:39], v[32:35], v[2:17]
	ds_read_b128 v[24:27], v40 offset:192
	ds_read_b128 v[28:31], v41 offset:17600
	ds_read_b128 v[32:35], v40 offset:224
	ds_read_b128 v[36:39], v41 offset:17632
	s_waitcnt lgkmcnt(0)
	v_mfma_f32_32x32x16_bf16 v[2:17], v[24:27], v[28:31], v[2:17]
	v_mov_b32_e32 v25, s10
	v_mfma_f32_32x32x16_bf16 v[2:17], v[32:35], v[36:39], v[2:17]

; template <int KSPLIT, class Epi>
; __device__ __forceinline__ void skinny_gemm(const bf16_t* __restrict__ A, int lda, const bf16_t* __restrict__ Wt, int K, int ntiles, char* lds, const Epi& E) {
;     ...
;     for (int base = 0; base < total; base += (int)gridDim.x * 8) {
;         const int slot = base + (int)blockIdx.x * 8 + wid, tile = slot / KSPLIT, ks = slot % KSPLIT;
;         const bool act = slot < total;
;         f32x4 acc = {0.f, 0.f, 0.f, 0.f};
;         if (act) {
;             const bf16_t* ap = A + (size_t)i * lda + ks * klen + 8 * kq;
;             const bf16_t* wp = Wt + (size_t)(tile * 16 + i) * K + ks * klen + 8 * kq;
;             for (int k = 0; k < klen; k += 256) {
;                 bf16x8 a[8], w[8];
; #pragma unroll
;                 for (int j = 0; j < 8; ++j) { a[j] = *(const bf16x8*)(ap + k + 32 * j); w[j] = *(const bf16x8*)(wp + k + 32 * j); }
; #pragma unroll
;                 for (int j = 0; j < 8; ++j) acc = __builtin_amdgcn_mfma_f32_16x16x32_bf16(w[j], a[j], acc, 0, 0, 0);
;             }
.LBB0_2532:
	s_add_i32 s24, s20, s21
	s_ashr_i32 s6, s24, 31
	s_lshr_b32 s6, s6, 29
	s_add_i32 s6, s24, s6
	s_ashr_i32 s22, s6, 3
	s_and_b32 s6, s6, -8
	s_sub_i32 s23, s24, s6
	v_mov_b32_e32 v4, v2
	v_mov_b32_e32 v5, v2
	v_mov_b32_e32 v3, v2
	s_cmpk_lt_i32 s24, 0x400
	v_mov_b64_e32 v[6:7], v[4:5]
	s_cselect_b64 s[6:7], -1, 0
	s_cmpk_gt_i32 s24, 0x3ff
	v_mov_b64_e32 v[4:5], v[2:3]
	s_cbranch_scc1 .LBB0_2534
	v_lshl_or_b32 v4, s22, 4, v1
	s_lshl_b32 s24, s23, 8
	v_ashrrev_i32_e32 v5, 31, v4
	s_ashr_i32 s25, s24, 31
	v_lshlrev_b64 v[4:5], 12, v[4:5]
	s_lshl_b64 s[24:25], s[24:25], 1
	v_lshl_add_u64 v[4:5], s[10:11], 0, v[4:5]
	v_lshl_add_u64 v[4:5], v[4:5], 0, s[24:25]
	v_mov_b32_e32 v15, v2
	v_lshl_add_u64 v[52:53], v[4:5], 0, v[14:15]
	global_load_dwordx4 v[4:7], v[52:53], off
	v_lshl_add_u64 v[54:55], v[8:9], 0, s[24:25]
	global_load_dwordx4 v[20:23], v[52:53], off offset:64
	global_load_dwordx4 v[24:27], v[54:55], off
	global_load_dwordx4 v[28:31], v[54:55], off offset:64
	global_load_dwordx4 v[32:35], v[52:53], off offset:128
	global_load_dwordx4 v[36:39], v[54:55], off offset:128
	global_load_dwordx4 v[40:43], v[52:53], off offset:192
	global_load_dwordx4 v[44:47], v[54:55], off offset:192
	s_waitcnt vmcnt(0) lgkmcnt(0)
	v_mfma_f32_16x16x32_bf16 v[4:7], v[4:7], v[24:27], 0
	global_load_dwordx4 v[24:27], v[52:53], off offset:256
	global_load_dwordx4 v[48:51], v[54:55], off offset:256
	v_mfma_f32_16x16x32_bf16 v[4:7], v[20:23], v[28:31], v[4:7]
	global_load_dwordx4 v[20:23], v[52:53], off offset:320
	global_load_dwordx4 v[28:31], v[54:55], off offset:320
	v_mfma_f32_16x16x32_bf16 v[4:7], v[32:35], v[36:39], v[4:7]
	global_load_dwordx4 v[32:35], v[52:53], off offset:384
	global_load_dwordx4 v[36:39], v[54:55], off offset:384
	v_mfma_f32_16x16x32_bf16 v[4:7], v[40:43], v[44:47], v[4:7]
	s_waitcnt vmcnt(0) lgkmcnt(0)
	v_mfma_f32_16x16x32_bf16 v[4:7], v[24:27], v[48:51], v[4:7]
	global_load_dwordx4 v[24:27], v[52:53], off offset:448
	v_mfma_f32_16x16x32_bf16 v[4:7], v[20:23], v[28:31], v[4:7]
	global_load_dwordx4 v[20:23], v[54:55], off offset:448
	v_mfma_f32_16x16x32_bf16 v[4:7], v[32:35], v[36:39], v[4:7]
	s_waitcnt vmcnt(0) lgkmcnt(0)
	v_mfma_f32_16x16x32_bf16 v[4:7], v[24:27], v[20:23], v[4:7]

; template <int KSPLIT, class Epi>
; __device__ __forceinline__ void skinny_gemm(const bf16_t* __restrict__ A, int lda, const bf16_t* __restrict__ Wt, int K, int ntiles, char* lds, const Epi& E) {
;     ...
;         if (KSPLIT > 1) {
;             float* red = (float*)lds;
;             if (act) *(f32x4*)(red + wid * 256 + lane * 4) = acc;
;             __syncthreads();
;             if (act && ks == 0) {
; #pragma unroll
;                 for (int j = 1; j < KSPLIT; ++j) acc += *(const f32x4*)(red + (wid + j) * 256 + lane * 4); }
;             __syncthreads();
;         }
;         if (act && ks == 0) E(tile, i, kq, acc);
;     }
; }
.LBB0_2538:
	s_and_b64 vcc, exec, s[6:7]
	s_barrier
	s_cbranch_vccnz .LBB0_2531
	v_lshl_or_b32 v20, s22, 4, v16
	v_ashrrev_i32_e32 v21, 31, v20
	v_lshl_add_u64 v[22:23], v[20:21], 1, v[10:11]
	global_load_dwordx2 v[22:23], v[22:23], off
	v_lshl_add_u64 v[20:21], v[20:21], 2, v[12:13]
	s_waitcnt vmcnt(0) lgkmcnt(0)
	v_lshlrev_b32_e32 v24, 16, v22
	v_and_b32_e32 v25, 0xffff0000, v22
	v_lshlrev_b32_e32 v22, 16, v23
	v_and_b32_e32 v23, 0xffff0000, v23
	v_pk_fma_f32 v[4:5], v[24:25], s[18:19], v[4:5] op_sel_hi:[1,0,1]
	v_pk_fma_f32 v[6:7], v[22:23], s[18:19], v[6:7] op_sel_hi:[1,0,1]
	global_store_dwordx4 v[20:21], v[4:7], off
	s_branch .LBB0_2531

; __device__ __forceinline__ unsigned cvt_pk_bf16(float lo, float hi) { unsigned r; asm volatile("v_cvt_pk_bf16_f32 %0, %1, %2" : "=v"(r) : "v"(lo), "v"(hi)); return r; }
; __device__ __forceinline__ void ln_load(f32x4 (&v)[8], const float* z, int lane) {
; #pragma unroll
;     for (int j = 0; j < 8; ++j) v[j] = ((const f32x4*)z)[lane + 64 * j];
; }
; __device__ __forceinline__ void ln_apply(f32x4 (&v)[8], const float* __restrict__ g, const float* __restrict__ b, bf16_t* hb, float* fo, int lane) {
;     float s = 0.f;
; #pragma unroll
;     for (int j = 0; j < 8; ++j) s += (v[j][0] + v[j][1]) + (v[j][2] + v[j][3]);
;     const float mean = wave_sum(s) * (1.f / DM); float q = 0.f;
; #pragma unroll
;     for (int j = 0; j < 8; ++j) { v[j] = v[j] - mean; q += (v[j][0] * v[j][0] + v[j][1] * v[j][1]) + (v[j][2] * v[j][2] + v[j][3] * v[j][3]); }
;     const float rstd = rsqrtf(wave_sum(q) * (1.f / DM) + LN_EPS);
; #pragma unroll
;     for (int j = 0; j < 8; ++j) { const int c = (lane + 64 * j) * 4; const f32x4 gg = *(const f32x4*)(g + c), bb = *(const f32x4*)(b + c);
;         const f32x4 y = v[j] * rstd * gg + bb;
;         if (hb) { u32x2 w; w.x = cvt_pk_bf16(y[0], y[1]); w.y = cvt_pk_bf16(y[2], y[3]); *(u32x2*)(hb + c) = w; }
;         if (fo) *(f32x4*)(fo + c) = y; }
; }
.LBB0_2622:
	s_cmp_lt_i32 s80, 16
	s_cselect_b64 s[6:7], -1, 0
	s_and_b64 s[8:9], s[6:7], s[40:41]
	s_andn2_b64 vcc, exec, s[8:9]
	s_cbranch_vccnz .LBB0_2632
	v_mov_b32_e32 v1, v194
	s_lshl_b32 s8, s2, 3
	v_readfirstlane_b32 s3, v1
	s_ashr_i32 s3, s3, 6
	s_add_i32 s8, s3, s8
	s_mov_b64 s[12:13], s[0:1]
	s_cmpk_gt_i32 s8, 0x400f
	s_cbranch_scc1 .LBB0_2632
	s_load_dword s3, s[0:1], 0xa0
	s_load_dwordx2 s[10:11], s[12:13], 0x90
	s_load_dwordx4 s[20:23], s[12:13], 0x58
	v_and_b32_e32 v98, 63, v1
	v_lshlrev_b32_e32 v96, 4, v98
	s_waitcnt lgkmcnt(0)
	s_lshl_b32 s3, s3, 3
	s_add_u32 s16, s10, 0xeb00000
	s_addc_u32 s17, s11, 0
	s_add_u32 s12, s22, 0x2000
	s_addc_u32 s13, s23, 0
	s_add_u32 s14, s20, 0x2000
	s_addc_u32 s15, s21, 0
	s_ashr_i32 s9, s8, 31
	s_lshl_b64 s[18:19], s[8:9], 13
	s_add_u32 s18, s16, s18
	s_addc_u32 s19, s17, s19
	v_mov_b32_e32 v97, 0
	v_lshl_add_u64 v[30:31], s[18:19], 0, v[96:97]
	s_movk_i32 s9, 0x1000
	v_add_co_u32_e32 v32, vcc, s9, v30
	global_load_dwordx4 v[2:5], v[30:31], off
	global_load_dwordx4 v[102:105], v[30:31], off offset:1024
	global_load_dwordx4 v[6:9], v[30:31], off offset:2048
	v_addc_co_u32_e32 v33, vcc, 0, v31, vcc
	global_load_dwordx4 v[10:13], v[32:33], off
	global_load_dwordx4 v[14:17], v[32:33], off offset:1024
	global_load_dwordx4 v[18:21], v[32:33], off offset:2048
	global_load_dwordx4 v[22:25], v[32:33], off offset:3072
	global_load_dwordx4 v[26:29], v[30:31], off offset:3072
	v_mbcnt_lo_u32_b32 v62, -1, 0
	v_mbcnt_hi_u32_b32 v62, -1, v62
	v_and_b32_e32 v63, 64, v62
	v_xor_b32_e32 v64, 1, v62
	v_add_u32_e32 v63, 64, v63
	v_xor_b32_e32 v65, 2, v62
	v_cmp_lt_i32_e32 vcc, v64, v63
	v_xor_b32_e32 v66, 4, v62
	v_xor_b32_e32 v67, 8, v62
	v_cndmask_b32_e32 v64, v62, v64, vcc
	v_cmp_lt_i32_e32 vcc, v65, v63
	v_xor_b32_e32 v68, 16, v62
	v_xor_b32_e32 v69, 32, v62
	v_cndmask_b32_e32 v65, v62, v65, vcc
	v_cmp_lt_i32_e32 vcc, v66, v63
	v_or_b32_e32 v80, 0x400, v96
	v_or_b32_e32 v82, 0x800, v96
	v_cndmask_b32_e32 v66, v62, v66, vcc
	v_cmp_lt_i32_e32 vcc, v67, v63
	v_or_b32_e32 v84, 0xc00, v96
	v_or_b32_e32 v86, 0x1000, v96
	v_cndmask_b32_e32 v67, v62, v67, vcc
	v_cmp_lt_i32_e32 vcc, v68, v63
	v_or_b32_e32 v88, 0x1400, v96
	v_or_b32_e32 v90, 0x1800, v96
	v_cndmask_b32_e32 v68, v62, v68, vcc
	v_cmp_lt_i32_e32 vcc, v69, v63
	v_lshlrev_b32_e32 v110, 2, v64
	v_lshlrev_b32_e32 v111, 2, v65
	v_cndmask_b32_e32 v62, v62, v69, vcc
	v_lshlrev_b32_e32 v115, 2, v62
	v_lshl_add_u64 v[62:63], s[16:17], 0, v[96:97]
	v_lshl_add_u64 v[64:65], s[12:13], 0, v[96:97]
	v_lshl_add_u64 v[78:79], s[14:15], 0, v[96:97]
	v_or_b32_e32 v96, 0x1c00, v96
	v_lshl_add_u64 v[92:93], s[14:15], 0, v[96:97]
	v_lshl_add_u64 v[94:95], s[12:13], 0, v[96:97]
	v_lshlrev_b32_e32 v96, 3, v98
	s_mov_b64 s[20:21], 0x6900000
	v_mov_b32_e32 v81, v97
	v_mov_b32_e32 v83, v97
	v_mov_b32_e32 v85, v97
	v_mov_b32_e32 v87, v97
	v_mov_b32_e32 v89, v97
	v_mov_b32_e32 v91, v97
	v_lshl_add_u64 v[96:97], s[10:11], 0, v[96:97]
	v_mov_b32_e32 v1, 0x3727c5ac
	s_mov_b32 s18, 0x800000
	v_lshlrev_b32_e32 v112, 2, v66
	v_lshlrev_b32_e32 v113, 2, v67
	v_lshlrev_b32_e32 v114, 2, v68
	v_lshl_add_u64 v[66:67], s[12:13], 0, v[80:81]
	v_lshl_add_u64 v[68:69], s[12:13], 0, v[82:83]
	v_lshl_add_u64 v[70:71], s[12:13], 0, v[84:85]
	v_lshl_add_u64 v[72:73], s[12:13], 0, v[86:87]
	v_lshl_add_u64 v[74:75], s[12:13], 0, v[88:89]
	v_lshl_add_u64 v[76:77], s[12:13], 0, v[90:91]
	v_lshl_add_u64 v[80:81], s[14:15], 0, v[80:81]
	v_lshl_add_u64 v[82:83], s[14:15], 0, v[82:83]
	v_lshl_add_u64 v[84:85], s[14:15], 0, v[84:85]
	v_lshl_add_u64 v[86:87], s[14:15], 0, v[86:87]
	v_lshl_add_u64 v[88:89], s[14:15], 0, v[88:89]
	v_lshl_add_u64 v[90:91], s[14:15], 0, v[90:91]
	v_lshl_add_u64 v[96:97], v[96:97], 0, s[20:21]
	s_waitcnt vmcnt(0) lgkmcnt(0)
	v_mov_b32_e32 v99, v2
	v_mov_b32_e32 v101, v4
	v_mov_b32_e32 v98, v102
	v_mov_b32_e32 v2, v103
	v_mov_b32_e32 v100, v104
	v_mov_b32_e32 v4, v105
	v_mov_b32_e32 v102, v7
	v_mov_b32_e32 v103, v8
	v_mov_b32_e32 v7, v9
	v_mov_b32_e32 v8, v11
	v_mov_b32_e32 v104, v13
	v_mov_b32_e32 v106, v15
	v_mov_b32_e32 v107, v16
	v_mov_b32_e32 v15, v17
	v_mov_b32_e32 v16, v23
	v_mov_b32_e32 v108, v25
	s_branch .LBB0_2627
.LBB0_2625:
	v_mov_b32_e32 v116, v38
	v_mov_b32_e32 v117, v42
	v_mov_b32_e32 v118, v39
	v_mov_b32_e32 v119, v43
	v_pk_add_f32 v[116:117], v[116:117], v[118:119]
	v_mov_b32_e32 v118, v40
	v_mov_b32_e32 v119, v44
	v_mov_b32_e32 v120, v41
	v_mov_b32_e32 v121, v45
	v_pk_add_f32 v[118:119], v[118:119], v[120:121]
	v_mov_b32_e32 v120, v34
	v_pk_add_f32 v[116:117], v[116:117], v[118:119]
	v_mov_b32_e32 v118, v35
	v_mov_b32_e32 v119, v36
	v_mov_b32_e32 v121, v37
	v_pk_add_f32 v[118:119], v[118:119], v[120:121]
	v_add_f32_e32 v9, 0, v117
	v_pk_add_f32 v[118:119], v[118:119], v[118:119] op_sel_hi:[0,1]
	v_add_f32_e32 v117, v116, v9
	v_add_f32_e32 v121, v30, v31
	v_add_f32_e32 v123, v32, v33
	v_mov_b32_e32 v120, v58
	v_mov_b32_e32 v122, v59
	v_mov_b32_e32 v118, v60
	v_mov_b32_e32 v116, v61
	v_pk_add_f32 v[120:121], v[120:121], v[122:123]
	v_pk_add_f32 v[116:117], v[118:119], v[116:117]
	v_mov_b32_e32 v118, v55
	v_pk_add_f32 v[116:117], v[120:121], v[116:117]
	v_mov_b32_e32 v119, v56
	v_mov_b32_e32 v120, v54
	v_mov_b32_e32 v121, v57
	v_pk_add_f32 v[118:119], v[118:119], v[120:121]
	v_pk_add_f32 v[116:117], v[116:117], v[116:117] op_sel_hi:[0,1]
	v_pk_add_f32 v[118:119], v[118:119], v[118:119] op_sel_hi:[0,1]
	v_add_f32_e32 v121, v50, v51
	v_add_f32_e32 v123, v52, v53
	v_mov_b32_e32 v120, v46
	v_mov_b32_e32 v122, v47
	v_mov_b32_e32 v118, v48
	v_mov_b32_e32 v116, v49
	v_pk_add_f32 v[120:121], v[120:121], v[122:123]
	v_pk_add_f32 v[116:117], v[118:119], v[116:117]
	s_ashr_i32 s11, s10, 31
	v_pk_add_f32 v[116:117], v[120:121], v[116:117]
	s_lshl_b64 s[10:11], s[10:11], 12
	v_add_f32_e32 v9, v116, v117
	ds_bpermute_b32 v11, v110, v9
	s_waitcnt lgkmcnt(0)
; __device__ __forceinline__ void ln_apply(f32x4 (&v)[8], const float* __restrict__ g, const float* __restrict__ b, bf16_t* hb, float* fo, int lane) {
;     float s = 0.f;
; #pragma unroll
;     for (int j = 0; j < 8; ++j) s += (v[j][0] + v[j][1]) + (v[j][2] + v[j][3]);
;     const float mean = wave_sum(s) * (1.f / DM); float q = 0.f;
; #pragma unroll
;     for (int j = 0; j < 8; ++j) { v[j] = v[j] - mean; q += (v[j][0] * v[j][0] + v[j][1] * v[j][1]) + (v[j][2] * v[j][2] + v[j][3] * v[j][3]); }
;     const float rstd = rsqrtf(wave_sum(q) * (1.f / DM) + LN_EPS);
; #pragma unroll
;     for (int j = 0; j < 8; ++j) { const int c = (lane + 64 * j) * 4; const f32x4 gg = *(const f32x4*)(g + c), bb = *(const f32x4*)(b + c);
	v_add_f32_e32 v9, v9, v11
	ds_bpermute_b32 v11, v111, v9
	s_waitcnt lgkmcnt(0)
	v_add_f32_e32 v9, v9, v11
	ds_bpermute_b32 v11, v112, v9
	s_waitcnt lgkmcnt(0)
	v_add_f32_e32 v9, v9, v11
	ds_bpermute_b32 v11, v113, v9
	s_waitcnt lgkmcnt(0)
	v_add_f32_e32 v9, v9, v11
	ds_bpermute_b32 v11, v114, v9
	s_waitcnt lgkmcnt(0)
	v_add_f32_e32 v9, v9, v11
	ds_bpermute_b32 v11, v115, v9
	s_waitcnt lgkmcnt(0)
	v_add_f32_e32 v9, v9, v11
	v_fmamk_f32 v43, v9, 0xba000000, v43
	v_fmamk_f32 v39, v9, 0xba000000, v39
	v_fmamk_f32 v45, v9, 0xba000000, v45
	v_fmac_f32_e32 v42, 0xba000000, v9
	v_fmamk_f32 v41, v9, 0xba000000, v41
	v_fmac_f32_e32 v38, 0xba000000, v9
	v_mov_b32_e32 v118, v43
	v_mov_b32_e32 v119, v39
	v_fmamk_f32 v44, v9, 0xba000000, v44
	v_fmamk_f32 v40, v9, 0xba000000, v40
	v_mov_b32_e32 v116, v42
	v_mov_b32_e32 v117, v38
	v_pk_mul_f32 v[118:119], v[118:119], v[118:119]
	v_mov_b32_e32 v120, v45
	v_mov_b32_e32 v121, v41
	v_pk_fma_f32 v[116:117], v[116:117], v[116:117], v[118:119]
	v_mov_b32_e32 v118, v44
	v_mov_b32_e32 v119, v40
	v_pk_mul_f32 v[120:121], v[120:121], v[120:121]
	v_fmamk_f32 v37, v9, 0xba000000, v37
	v_pk_fma_f32 v[118:119], v[118:119], v[118:119], v[120:121]
	v_fmamk_f32 v36, v9, 0xba000000, v36
	v_pk_add_f32 v[116:117], v[116:117], v[118:119]
	v_fmamk_f32 v35, v9, 0xba000000, v35
	v_fmac_f32_e32 v34, 0xba000000, v9
	v_pk_add_f32 v[116:117], v[116:117], v[116:117] op_sel_hi:[0,1]
	v_pk_mul_f32 v[118:119], v[36:37], v[36:37]
	v_pk_mul_f32 v[120:121], v[34:35], v[34:35]
	v_fmac_f32_e32 v30, 0xba000000, v9
	v_pk_mov_b32 v[122:123], v[120:121], v[118:119] op_sel:[1,0]
	v_mov_b32_e32 v121, v119
	v_fmamk_f32 v32, v9, 0xba000000, v32
	v_fmamk_f32 v31, v9, 0xba000000, v31
	v_mul_f32_e32 v116, v30, v30
	v_pk_add_f32 v[118:119], v[122:123], v[120:121]
	v_fmamk_f32 v33, v9, 0xba000000, v33
	v_pk_fma_f32 v[120:121], v[30:31], v[30:31], v[116:117] op_sel_hi:[1,1,0]
	v_mul_f32_e32 v116, v32, v32
	v_pk_add_f32 v[118:119], v[118:119], v[118:119] op_sel_hi:[0,1]
	v_pk_fma_f32 v[122:123], v[32:33], v[32:33], v[116:117] op_sel_hi:[1,1,0]
	v_fmamk_f32 v61, v9, 0xba000000, v61
	v_fmamk_f32 v60, v9, 0xba000000, v60
	v_fmamk_f32 v59, v9, 0xba000000, v59
	v_fmac_f32_e32 v58, 0xba000000, v9
	v_mul_f32_e32 v120, v58, v58
	v_mul_f32_e32 v122, v59, v59
	v_mul_f32_e32 v118, v60, v60
	v_mul_f32_e32 v116, v61, v61
	v_pk_add_f32 v[120:121], v[120:121], v[122:123]
	v_pk_add_f32 v[116:117], v[118:119], v[116:117]
	v_fmamk_f32 v57, v9, 0xba000000, v57
	v_pk_add_f32 v[124:125], v[120:121], v[116:117]
	global_load_dwordx4 v[116:119], v[78:79], off
	global_load_dwordx4 v[120:123], v[64:65], off
	v_fmamk_f32 v56, v9, 0xba000000, v56
	v_fmamk_f32 v55, v9, 0xba000000, v55
	v_fmac_f32_e32 v54, 0xba000000, v9
	v_pk_add_f32 v[124:125], v[124:125], v[124:125] op_sel_hi:[0,1]
	v_pk_mul_f32 v[126:127], v[56:57], v[56:57]
	v_pk_mul_f32 v[128:129], v[54:55], v[54:55]
	v_fmac_f32_e32 v50, 0xba000000, v9
	v_pk_mov_b32 v[130:131], v[128:129], v[126:127] op_sel:[1,0]
	v_mov_b32_e32 v129, v127
	v_fmamk_f32 v52, v9, 0xba000000, v52
	v_fmamk_f32 v51, v9, 0xba000000, v51
	v_mul_f32_e32 v124, v50, v50
	v_pk_add_f32 v[126:127], v[130:131], v[128:129]
	v_fmamk_f32 v53, v9, 0xba000000, v53
	v_pk_fma_f32 v[128:129], v[50:51], v[50:51], v[124:125] op_sel_hi:[1,1,0]
	v_mul_f32_e32 v124, v52, v52
	v_pk_add_f32 v[126:127], v[126:127], v[126:127] op_sel_hi:[0,1]
	v_pk_fma_f32 v[130:131], v[52:53], v[52:53], v[124:125] op_sel_hi:[1,1,0]
	v_fmamk_f32 v49, v9, 0xba000000, v49
	v_fmamk_f32 v48, v9, 0xba000000, v48
	v_fmamk_f32 v47, v9, 0xba000000, v47
	v_fmac_f32_e32 v46, 0xba000000, v9
	v_mul_f32_e32 v128, v46, v46
	v_mul_f32_e32 v130, v47, v47
	v_mul_f32_e32 v126, v48, v48
	v_mul_f32_e32 v124, v49, v49
	v_pk_add_f32 v[128:129], v[128:129], v[130:131]
	v_pk_add_f32 v[124:125], v[126:127], v[124:125]
	s_nop 0
	v_pk_add_f32 v[124:125], v[128:129], v[124:125]
	s_nop 0
	v_add_f32_e32 v9, v124, v125
	ds_bpermute_b32 v11, v110, v9
	s_waitcnt lgkmcnt(0)
	v_add_f32_e32 v9, v9, v11
	ds_bpermute_b32 v11, v111, v9
	s_waitcnt lgkmcnt(0)
	v_add_f32_e32 v9, v9, v11
	ds_bpermute_b32 v11, v112, v9
	s_waitcnt lgkmcnt(0)
	v_add_f32_e32 v9, v9, v11
	ds_bpermute_b32 v11, v113, v9
	s_waitcnt lgkmcnt(0)
	v_add_f32_e32 v9, v9, v11
	ds_bpermute_b32 v11, v114, v9
	s_waitcnt lgkmcnt(0)
; __device__ __forceinline__ unsigned cvt_pk_bf16(float lo, float hi) { unsigned r; asm volatile("v_cvt_pk_bf16_f32 %0, %1, %2" : "=v"(r) : "v"(lo), "v"(hi)); return r; }
; __device__ __forceinline__ void ln_apply(f32x4 (&v)[8], const float* __restrict__ g, const float* __restrict__ b, bf16_t* hb, float* fo, int lane) {
;     ...
;     const float mean = wave_sum(s) * (1.f / DM); float q = 0.f;
; #pragma unroll
;     for (int j = 0; j < 8; ++j) { v[j] = v[j] - mean; q += (v[j][0] * v[j][0] + v[j][1] * v[j][1]) + (v[j][2] * v[j][2] + v[j][3] * v[j][3]); }
;     const float rstd = rsqrtf(wave_sum(q) * (1.f / DM) + LN_EPS);
; #pragma unroll
;     for (int j = 0; j < 8; ++j) { const int c = (lane + 64 * j) * 4; const f32x4 gg = *(const f32x4*)(g + c), bb = *(const f32x4*)(b + c);
;         const f32x4 y = v[j] * rstd * gg + bb;
;         if (hb) { u32x2 w; w.x = cvt_pk_bf16(y[0], y[1]); w.y = cvt_pk_bf16(y[2], y[3]); *(u32x2*)(hb + c) = w; }
;         if (fo) *(f32x4*)(fo + c) = y; }
	v_add_f32_e32 v9, v9, v11
	ds_bpermute_b32 v11, v115, v9
	s_waitcnt lgkmcnt(0)
	v_add_f32_e32 v9, v9, v11
	v_fmamk_f32 v9, v9, 0x3a000000, v1
	v_mul_f32_e32 v11, 0x4b800000, v9
	v_cmp_gt_f32_e32 vcc, s18, v9
	s_nop 1
	v_cndmask_b32_e32 v9, v9, v11, vcc
	v_rsq_f32_e32 v9, v9
	s_nop 0
	v_mul_f32_e32 v11, 0x45800000, v9
	v_cndmask_b32_e32 v124, v9, v11, vcc
	v_pk_mul_f32 v[126:127], v[42:43], v[124:125] op_sel_hi:[1,0]
	v_pk_mul_f32 v[128:129], v[44:45], v[124:125] op_sel_hi:[1,0]
	s_waitcnt vmcnt(0)
	v_pk_fma_f32 v[116:117], v[116:117], v[126:127], v[120:121]
	v_pk_fma_f32 v[118:119], v[118:119], v[128:129], v[122:123]
	v_cvt_pk_bf16_f32 v126, v116, v117
	v_pk_mul_f32 v[130:131], v[38:39], v[124:125] op_sel_hi:[1,0]
	v_cvt_pk_bf16_f32 v127, v118, v119
	global_load_dwordx4 v[116:119], v[80:81], off
	global_load_dwordx4 v[120:123], v[66:67], off
	v_pk_mul_f32 v[132:133], v[40:41], v[124:125] op_sel_hi:[1,0]
	v_lshl_add_u64 v[128:129], v[96:97], 0, s[10:11]
	global_store_dwordx2 v[128:129], v[126:127], off
	s_waitcnt vmcnt(0) lgkmcnt(0)
	v_pk_fma_f32 v[118:119], v[118:119], v[132:133], v[122:123]
	v_pk_fma_f32 v[116:117], v[116:117], v[130:131], v[120:121]
	v_pk_mul_f32 v[130:131], v[34:35], v[124:125] op_sel_hi:[1,0]
	v_cvt_pk_bf16_f32 v126, v116, v117
	v_cvt_pk_bf16_f32 v127, v118, v119
	global_load_dwordx4 v[116:119], v[82:83], off
	global_load_dwordx4 v[120:123], v[68:69], off
	v_pk_mul_f32 v[132:133], v[36:37], v[124:125] op_sel_hi:[1,0]
	global_store_dwordx2 v[128:129], v[126:127], off offset:512
	s_waitcnt vmcnt(0) lgkmcnt(0)
	v_pk_fma_f32 v[118:119], v[118:119], v[132:133], v[122:123]
	v_pk_fma_f32 v[116:117], v[116:117], v[130:131], v[120:121]
	v_pk_mul_f32 v[130:131], v[30:31], v[124:125] op_sel_hi:[1,0]
	v_cvt_pk_bf16_f32 v126, v116, v117
	v_cvt_pk_bf16_f32 v127, v118, v119
	global_load_dwordx4 v[116:119], v[84:85], off
	global_load_dwordx4 v[120:123], v[70:71], off
	v_pk_mul_f32 v[132:133], v[32:33], v[124:125] op_sel_hi:[1,0]
	global_store_dwordx2 v[128:129], v[126:127], off offset:1024
	s_waitcnt vmcnt(0) lgkmcnt(0)
	v_pk_fma_f32 v[118:119], v[118:119], v[132:133], v[122:123]
	v_pk_fma_f32 v[116:117], v[116:117], v[130:131], v[120:121]
	v_pk_mul_f32 v[130:131], v[58:59], v[124:125] op_sel_hi:[1,0]
	v_cvt_pk_bf16_f32 v126, v116, v117
	v_cvt_pk_bf16_f32 v127, v118, v119
	global_load_dwordx4 v[116:119], v[86:87], off
	global_load_dwordx4 v[120:123], v[72:73], off
	v_pk_mul_f32 v[132:133], v[60:61], v[124:125] op_sel_hi:[1,0]
	global_store_dwordx2 v[128:129], v[126:127], off offset:1536
	s_waitcnt vmcnt(0) lgkmcnt(0)
	v_pk_fma_f32 v[118:119], v[118:119], v[132:133], v[122:123]
	v_pk_fma_f32 v[116:117], v[116:117], v[130:131], v[120:121]
	v_pk_mul_f32 v[130:131], v[54:55], v[124:125] op_sel_hi:[1,0]
	v_cvt_pk_bf16_f32 v126, v116, v117
	v_cvt_pk_bf16_f32 v127, v118, v119
	global_load_dwordx4 v[116:119], v[88:89], off
	global_load_dwordx4 v[120:123], v[74:75], off
	v_pk_mul_f32 v[132:133], v[56:57], v[124:125] op_sel_hi:[1,0]
	global_store_dwordx2 v[128:129], v[126:127], off offset:2048
	s_waitcnt vmcnt(0) lgkmcnt(0)
	v_pk_fma_f32 v[118:119], v[118:119], v[132:133], v[122:123]
	v_pk_fma_f32 v[116:117], v[116:117], v[130:131], v[120:121]
	v_pk_mul_f32 v[130:131], v[50:51], v[124:125] op_sel_hi:[1,0]
	v_cvt_pk_bf16_f32 v126, v116, v117
	v_cvt_pk_bf16_f32 v127, v118, v119
	global_load_dwordx4 v[116:119], v[90:91], off
	global_load_dwordx4 v[120:123], v[76:77], off
	v_pk_mul_f32 v[132:133], v[52:53], v[124:125] op_sel_hi:[1,0]
	global_store_dwordx2 v[128:129], v[126:127], off offset:2560
	s_waitcnt vmcnt(0) lgkmcnt(0)
	v_pk_fma_f32 v[118:119], v[132:133], v[118:119], v[122:123]
	v_pk_fma_f32 v[116:117], v[130:131], v[116:117], v[120:121]
	v_pk_mul_f32 v[130:131], v[46:47], v[124:125] op_sel_hi:[1,0]
	v_cvt_pk_bf16_f32 v126, v116, v117
	v_cvt_pk_bf16_f32 v127, v118, v119
	global_load_dwordx4 v[116:119], v[92:93], off
	global_load_dwordx4 v[120:123], v[94:95], off
	v_pk_mul_f32 v[124:125], v[48:49], v[124:125] op_sel_hi:[1,0]
	global_store_dwordx2 v[128:129], v[126:127], off offset:3072
	s_waitcnt vmcnt(0) lgkmcnt(0)
	v_pk_fma_f32 v[116:117], v[130:131], v[116:117], v[120:121]
	v_pk_fma_f32 v[118:119], v[124:125], v[118:119], v[122:123]
	v_cvt_pk_bf16_f32 v116, v116, v117
	s_nop 0
	v_cvt_pk_bf16_f32 v117, v118, v119
	global_store_dwordx2 v[128:129], v[116:117], off offset:3584

; __device__ __forceinline__ unsigned cvt_pk_bf16(float lo, float hi) { unsigned r; asm volatile("v_cvt_pk_bf16_f32 %0, %1, %2" : "=v"(r) : "v"(lo), "v"(hi)); return r; }
; __device__ __forceinline__ void ln_load(f32x4 (&v)[8], const float* z, int lane) {
; #pragma unroll
;     for (int j = 0; j < 8; ++j) v[j] = ((const f32x4*)z)[lane + 64 * j];
; }
; __device__ __forceinline__ void ln_apply(f32x4 (&v)[8], const float* __restrict__ g, const float* __restrict__ b, bf16_t* hb, float* fo, int lane) {
;     float s = 0.f;
; #pragma unroll
;     for (int j = 0; j < 8; ++j) s += (v[j][0] + v[j][1]) + (v[j][2] + v[j][3]);
;     const float mean = wave_sum(s) * (1.f / DM); float q = 0.f;
; #pragma unroll
;     for (int j = 0; j < 8; ++j) { v[j] = v[j] - mean; q += (v[j][0] * v[j][0] + v[j][1] * v[j][1]) + (v[j][2] * v[j][2] + v[j][3] * v[j][3]); }
;     const float rstd = rsqrtf(wave_sum(q) * (1.f / DM) + LN_EPS);
; #pragma unroll
;     for (int j = 0; j < 8; ++j) { const int c = (lane + 64 * j) * 4; const f32x4 gg = *(const f32x4*)(g + c), bb = *(const f32x4*)(b + c);
;         const f32x4 y = v[j] * rstd * gg + bb;
;         if (hb) { u32x2 w; w.x = cvt_pk_bf16(y[0], y[1]); w.y = cvt_pk_bf16(y[2], y[3]); *(u32x2*)(hb + c) = w; }
;         if (fo) *(f32x4*)(fo + c) = y; }
; }
.LBB0_2627:
	s_add_i32 s10, s8, s3
	s_cmpk_gt_i32 s10, 0x400f
	s_cbranch_scc1 .LBB0_2629
	s_ashr_i32 s11, s10, 31
	s_lshl_b64 s[12:13], s[10:11], 13
	v_lshl_add_u64 v[46:47], v[62:63], 0, s[12:13]
	v_add_co_u32_e32 v116, vcc, 0x1000, v46
	global_load_dwordx4 v[42:45], v[46:47], off
	global_load_dwordx4 v[38:41], v[46:47], off offset:1024
	global_load_dwordx4 v[34:37], v[46:47], off offset:2048
	global_load_dwordx4 v[30:33], v[46:47], off offset:3072
	v_addc_co_u32_e32 v117, vcc, 0, v47, vcc
	global_load_dwordx4 v[58:61], v[116:117], off
	global_load_dwordx4 v[54:57], v[116:117], off offset:1024
	global_load_dwordx4 v[50:53], v[116:117], off offset:2048
	global_load_dwordx4 v[46:49], v[116:117], off offset:3072
.LBB0_2629:
	v_pk_add_f32 v[116:117], v[98:99], v[2:3]
	v_pk_add_f32 v[118:119], v[100:101], v[4:5]
	v_add_f32_e32 v11, v26, v27
	v_pk_add_f32 v[116:117], v[116:117], v[118:119]
	v_add_f32_e32 v23, v18, v19
	v_add_f32_e32 v9, 0, v117
	v_add_f32_e32 v105, v116, v9
	v_pk_add_f32 v[116:117], v[102:103], v[6:7]
	v_add_f32_e32 v9, v28, v29
	v_pk_add_f32 v[116:117], v[116:117], v[116:117] op_sel_hi:[0,1]
	v_mov_b32_e32 v13, v117
	v_pk_add_f32 v[118:119], v[10:11], v[8:9]
	v_pk_add_f32 v[116:117], v[12:13], v[104:105]
	v_add_f32_e32 v17, v20, v21
	v_pk_add_f32 v[116:117], v[118:119], v[116:117]
	v_pk_add_f32 v[118:119], v[106:107], v[14:15]
	v_pk_add_f32 v[116:117], v[116:117], v[116:117] op_sel_hi:[0,1]
	v_pk_add_f32 v[118:119], v[118:119], v[118:119] op_sel_hi:[0,1]
	v_mov_b32_e32 v25, v119
	v_mov_b32_e32 v109, v117
	v_pk_add_f32 v[120:121], v[22:23], v[16:17]
	v_pk_add_f32 v[116:117], v[24:25], v[108:109]
	s_ashr_i32 s9, s8, 31
	v_pk_add_f32 v[116:117], v[120:121], v[116:117]
	s_lshl_b64 s[12:13], s[8:9], 12
	v_add_f32_e32 v9, v116, v117
	ds_bpermute_b32 v11, v110, v9
	s_cmpk_gt_i32 s10, 0x400f
	s_waitcnt lgkmcnt(0)
	v_add_f32_e32 v9, v9, v11
	ds_bpermute_b32 v11, v111, v9
	s_waitcnt lgkmcnt(0)
	v_add_f32_e32 v9, v9, v11
	ds_bpermute_b32 v11, v112, v9
	s_waitcnt lgkmcnt(0)
	v_add_f32_e32 v9, v9, v11
	ds_bpermute_b32 v11, v113, v9
	s_waitcnt lgkmcnt(0)
	v_add_f32_e32 v9, v9, v11
	ds_bpermute_b32 v11, v114, v9
	s_waitcnt lgkmcnt(0)
	v_add_f32_e32 v9, v9, v11
	ds_bpermute_b32 v11, v115, v9
	s_waitcnt lgkmcnt(0)
	v_add_f32_e32 v9, v9, v11
	v_fmac_f32_e32 v3, 0xba000000, v9
	v_fmac_f32_e32 v2, 0xba000000, v9
	v_fmac_f32_e32 v99, 0xba000000, v9
	v_fmac_f32_e32 v98, 0xba000000, v9
	v_mov_b32_e32 v118, v3
	v_mov_b32_e32 v119, v2
	v_fmac_f32_e32 v5, 0xba000000, v9
	v_fmac_f32_e32 v4, 0xba000000, v9
	v_mov_b32_e32 v116, v99
	v_mov_b32_e32 v117, v98
	v_pk_mul_f32 v[118:119], v[118:119], v[118:119]
	v_fmac_f32_e32 v101, 0xba000000, v9
	v_fmac_f32_e32 v100, 0xba000000, v9
	v_pk_fma_f32 v[116:117], v[116:117], v[116:117], v[118:119]
	v_mov_b32_e32 v118, v5
	v_mov_b32_e32 v119, v4
	v_mov_b32_e32 v120, v101
	v_mov_b32_e32 v121, v100
	v_pk_mul_f32 v[118:119], v[118:119], v[118:119]
	v_fmac_f32_e32 v7, 0xba000000, v9
	v_pk_fma_f32 v[118:119], v[120:121], v[120:121], v[118:119]
	v_fmac_f32_e32 v103, 0xba000000, v9
	v_fmac_f32_e32 v102, 0xba000000, v9
	v_fmac_f32_e32 v6, 0xba000000, v9
	v_pk_add_f32 v[116:117], v[116:117], v[118:119]
	v_mov_b32_e32 v124, v103
	v_mov_b32_e32 v125, v7
	v_mov_b32_e32 v126, v6
	v_mov_b32_e32 v127, v102
	v_pk_add_f32 v[116:117], v[116:117], v[116:117] op_sel_hi:[0,1]
	v_pk_mul_f32 v[118:119], v[124:125], v[124:125]
	v_pk_mul_f32 v[120:121], v[126:127], v[126:127]
	v_fmac_f32_e32 v26, 0xba000000, v9
	v_pk_mov_b32 v[122:123], v[120:121], v[118:119] op_sel:[1,0]
	v_mov_b32_e32 v121, v119
	v_fmac_f32_e32 v28, 0xba000000, v9
	v_fmac_f32_e32 v27, 0xba000000, v9
	v_mul_f32_e32 v116, v26, v26
	v_pk_add_f32 v[118:119], v[122:123], v[120:121]
	v_fmac_f32_e32 v29, 0xba000000, v9
	v_pk_fma_f32 v[120:121], v[26:27], v[26:27], v[116:117] op_sel_hi:[1,1,0]
	v_mul_f32_e32 v116, v28, v28
	v_pk_add_f32 v[118:119], v[118:119], v[118:119] op_sel_hi:[0,1]
	v_pk_fma_f32 v[122:123], v[28:29], v[28:29], v[116:117] op_sel_hi:[1,1,0]
	v_fmac_f32_e32 v104, 0xba000000, v9
	v_fmac_f32_e32 v12, 0xba000000, v9
	v_fmac_f32_e32 v8, 0xba000000, v9
	v_fmac_f32_e32 v10, 0xba000000, v9
	v_mul_f32_e32 v120, v10, v10
	v_mul_f32_e32 v122, v8, v8
	v_mul_f32_e32 v118, v12, v12
	v_mul_f32_e32 v116, v104, v104
	v_pk_add_f32 v[120:121], v[120:121], v[122:123]
	v_pk_add_f32 v[116:117], v[118:119], v[116:117]
	v_fmac_f32_e32 v15, 0xba000000, v9
	v_pk_add_f32 v[116:117], v[120:121], v[116:117]
	v_fmac_f32_e32 v107, 0xba000000, v9
	v_pk_add_f32 v[128:129], v[116:117], v[116:117] op_sel_hi:[0,1]
	global_load_dwordx4 v[116:119], v[78:79], off
	global_load_dwordx4 v[120:123], v[64:65], off
	v_fmac_f32_e32 v106, 0xba000000, v9
	v_fmac_f32_e32 v14, 0xba000000, v9
	v_mov_b32_e32 v130, v107
	v_mov_b32_e32 v131, v15
	v_mov_b32_e32 v134, v14
	v_mov_b32_e32 v135, v106
	v_pk_mul_f32 v[132:133], v[130:131], v[130:131]
	v_pk_mul_f32 v[136:137], v[134:135], v[134:135]
	v_fmac_f32_e32 v18, 0xba000000, v9
	v_pk_mov_b32 v[138:139], v[136:137], v[132:133] op_sel:[1,0]
	v_mov_b32_e32 v137, v133
	v_fmac_f32_e32 v20, 0xba000000, v9
	v_fmac_f32_e32 v19, 0xba000000, v9
	v_mul_f32_e32 v128, v18, v18
	v_pk_add_f32 v[132:133], v[138:139], v[136:137]
	v_fmac_f32_e32 v21, 0xba000000, v9
	v_pk_fma_f32 v[136:137], v[18:19], v[18:19], v[128:129] op_sel_hi:[1,1,0]
	v_mul_f32_e32 v128, v20, v20
	v_pk_add_f32 v[132:133], v[132:133], v[132:133] op_sel_hi:[0,1]
	v_pk_fma_f32 v[138:139], v[20:21], v[20:21], v[128:129] op_sel_hi:[1,1,0]
	v_fmac_f32_e32 v108, 0xba000000, v9
	v_fmac_f32_e32 v24, 0xba000000, v9
	v_fmac_f32_e32 v16, 0xba000000, v9
	v_fmac_f32_e32 v22, 0xba000000, v9
	v_mul_f32_e32 v136, v22, v22
	v_mul_f32_e32 v138, v16, v16
	v_mul_f32_e32 v132, v24, v24
	v_mul_f32_e32 v128, v108, v108
	v_pk_add_f32 v[136:137], v[136:137], v[138:139]
	v_pk_add_f32 v[128:129], v[132:133], v[128:129]
	v_mov_b32_e32 v132, v101
	v_pk_add_f32 v[128:129], v[136:137], v[128:129]
	v_mov_b32_e32 v133, v5
	v_add_f32_e32 v9, v128, v129
	ds_bpermute_b32 v11, v110, v9
	v_mov_b32_e32 v128, v99
	v_mov_b32_e32 v129, v3
	v_mov_b32_e32 v138, v98
	v_mov_b32_e32 v139, v2
	s_waitcnt lgkmcnt(0)
; __device__ __forceinline__ unsigned cvt_pk_bf16(float lo, float hi) { unsigned r; asm volatile("v_cvt_pk_bf16_f32 %0, %1, %2" : "=v"(r) : "v"(lo), "v"(hi)); return r; }
; __device__ __forceinline__ void ln_load(f32x4 (&v)[8], const float* z, int lane) {
; #pragma unroll
;     for (int j = 0; j < 8; ++j) v[j] = ((const f32x4*)z)[lane + 64 * j];
; }
; __device__ __forceinline__ void ln_apply(f32x4 (&v)[8], const float* __restrict__ g, const float* __restrict__ b, bf16_t* hb, float* fo, int lane) {
;     float s = 0.f;
; #pragma unroll
;     for (int j = 0; j < 8; ++j) s += (v[j][0] + v[j][1]) + (v[j][2] + v[j][3]);
;     const float mean = wave_sum(s) * (1.f / DM); float q = 0.f;
; #pragma unroll
;     for (int j = 0; j < 8; ++j) { v[j] = v[j] - mean; q += (v[j][0] * v[j][0] + v[j][1] * v[j][1]) + (v[j][2] * v[j][2] + v[j][3] * v[j][3]); }
;     const float rstd = rsqrtf(wave_sum(q) * (1.f / DM) + LN_EPS);
; #pragma unroll
;     for (int j = 0; j < 8; ++j) { const int c = (lane + 64 * j) * 4; const f32x4 gg = *(const f32x4*)(g + c), bb = *(const f32x4*)(b + c);
;         const f32x4 y = v[j] * rstd * gg + bb;
;         if (hb) { u32x2 w; w.x = cvt_pk_bf16(y[0], y[1]); w.y = cvt_pk_bf16(y[2], y[3]); *(u32x2*)(hb + c) = w; }
;         if (fo) *(f32x4*)(fo + c) = y; }
; }
	v_add_f32_e32 v9, v9, v11
	ds_bpermute_b32 v11, v111, v9
	v_mov_b32_e32 v140, v100
	v_mov_b32_e32 v141, v4
	v_mov_b32_e32 v13, v104
	v_mov_b32_e32 v23, v16
	s_waitcnt lgkmcnt(0)
	v_add_f32_e32 v9, v9, v11
	ds_bpermute_b32 v11, v112, v9
	v_mov_b32_e32 v25, v108
	s_waitcnt lgkmcnt(0)
	v_add_f32_e32 v9, v9, v11
	ds_bpermute_b32 v11, v113, v9
	s_waitcnt lgkmcnt(0)
	v_add_f32_e32 v9, v9, v11
	ds_bpermute_b32 v11, v114, v9
	s_waitcnt lgkmcnt(0)
	v_add_f32_e32 v9, v9, v11
	ds_bpermute_b32 v11, v115, v9
	s_waitcnt lgkmcnt(0)
	v_add_f32_e32 v9, v9, v11
	v_fmamk_f32 v9, v9, 0x3a000000, v1
	v_mul_f32_e32 v11, 0x4b800000, v9
	v_cmp_gt_f32_e32 vcc, s18, v9
	s_nop 1
	v_cndmask_b32_e32 v9, v9, v11, vcc
	v_rsq_f32_e32 v9, v9
	s_nop 0
	v_mul_f32_e32 v11, 0x45800000, v9
	v_cndmask_b32_e32 v136, v9, v11, vcc
	v_pk_mul_f32 v[128:129], v[128:129], v[136:137] op_sel_hi:[1,0]
	v_pk_mul_f32 v[132:133], v[132:133], v[136:137] op_sel_hi:[1,0]
	s_waitcnt vmcnt(0)
	v_pk_fma_f32 v[116:117], v[116:117], v[128:129], v[120:121]
	v_pk_fma_f32 v[118:119], v[118:119], v[132:133], v[122:123]
	v_cvt_pk_bf16_f32 v128, v116, v117
	v_pk_mul_f32 v[138:139], v[138:139], v[136:137] op_sel_hi:[1,0]
	v_cvt_pk_bf16_f32 v129, v118, v119
	global_load_dwordx4 v[116:119], v[80:81], off
	global_load_dwordx4 v[120:123], v[66:67], off
	v_pk_mul_f32 v[140:141], v[140:141], v[136:137] op_sel_hi:[1,0]
	v_lshl_add_u64 v[132:133], v[96:97], 0, s[12:13]
	global_store_dwordx2 v[132:133], v[128:129], off
	v_pk_mul_f32 v[126:127], v[126:127], v[136:137] op_sel_hi:[1,0]
	v_pk_mul_f32 v[124:125], v[124:125], v[136:137] op_sel_hi:[1,0]
	v_mov_b32_e32 v11, v8
	s_mov_b64 s[12:13], -1
	s_waitcnt vmcnt(0) lgkmcnt(0)
	v_pk_fma_f32 v[118:119], v[118:119], v[140:141], v[122:123]
	v_pk_fma_f32 v[116:117], v[116:117], v[138:139], v[120:121]
	s_nop 0
	v_cvt_pk_bf16_f32 v128, v116, v117
	v_cvt_pk_bf16_f32 v129, v118, v119
	global_load_dwordx4 v[116:119], v[82:83], off
	global_load_dwordx4 v[120:123], v[68:69], off
	s_waitcnt vmcnt(0) lgkmcnt(0)
	v_pk_fma_f32 v[118:119], v[118:119], v[124:125], v[122:123]
	v_pk_fma_f32 v[116:117], v[116:117], v[126:127], v[120:121]
	global_store_dwordx2 v[132:133], v[128:129], off offset:512
	v_cvt_pk_bf16_f32 v124, v116, v117
	v_cvt_pk_bf16_f32 v125, v118, v119
	global_load_dwordx4 v[116:119], v[84:85], off
	global_load_dwordx4 v[120:123], v[70:71], off
	v_pk_mul_f32 v[126:127], v[26:27], v[136:137] op_sel_hi:[1,0]
	v_pk_mul_f32 v[128:129], v[28:29], v[136:137] op_sel_hi:[1,0]
	global_store_dwordx2 v[132:133], v[124:125], off offset:1024
	s_waitcnt vmcnt(0) lgkmcnt(0)
	v_pk_fma_f32 v[118:119], v[118:119], v[128:129], v[122:123]
	v_pk_fma_f32 v[116:117], v[116:117], v[126:127], v[120:121]
	v_pk_mul_f32 v[126:127], v[10:11], v[136:137] op_sel_hi:[1,0]
	v_cvt_pk_bf16_f32 v124, v116, v117
	v_cvt_pk_bf16_f32 v125, v118, v119
	global_load_dwordx4 v[116:119], v[86:87], off
	global_load_dwordx4 v[120:123], v[72:73], off
	v_pk_mul_f32 v[128:129], v[12:13], v[136:137] op_sel_hi:[1,0]
	global_store_dwordx2 v[132:133], v[124:125], off offset:1536
	s_waitcnt vmcnt(0) lgkmcnt(0)
	v_pk_fma_f32 v[118:119], v[118:119], v[128:129], v[122:123]
	v_pk_fma_f32 v[116:117], v[116:117], v[126:127], v[120:121]
	v_pk_mul_f32 v[126:127], v[134:135], v[136:137] op_sel_hi:[1,0]
	v_cvt_pk_bf16_f32 v124, v116, v117
	v_cvt_pk_bf16_f32 v125, v118, v119
	global_load_dwordx4 v[116:119], v[88:89], off
	global_load_dwordx4 v[120:123], v[74:75], off
	v_pk_mul_f32 v[128:129], v[130:131], v[136:137] op_sel_hi:[1,0]
	global_store_dwordx2 v[132:133], v[124:125], off offset:2048
	s_waitcnt vmcnt(0) lgkmcnt(0)
	v_pk_fma_f32 v[118:119], v[118:119], v[128:129], v[122:123]
	v_pk_fma_f32 v[116:117], v[116:117], v[126:127], v[120:121]
	v_pk_mul_f32 v[126:127], v[18:19], v[136:137] op_sel_hi:[1,0]
	v_cvt_pk_bf16_f32 v124, v116, v117
	v_cvt_pk_bf16_f32 v125, v118, v119
	global_load_dwordx4 v[116:119], v[90:91], off
	global_load_dwordx4 v[120:123], v[76:77], off
	v_pk_mul_f32 v[128:129], v[20:21], v[136:137] op_sel_hi:[1,0]
	global_store_dwordx2 v[132:133], v[124:125], off offset:2560
	s_waitcnt vmcnt(0) lgkmcnt(0)
	v_pk_fma_f32 v[118:119], v[128:129], v[118:119], v[122:123]
	v_pk_fma_f32 v[116:117], v[126:127], v[116:117], v[120:121]
	v_pk_mul_f32 v[126:127], v[22:23], v[136:137] op_sel_hi:[1,0]
	v_cvt_pk_bf16_f32 v124, v116, v117
	v_cvt_pk_bf16_f32 v125, v118, v119
	global_load_dwordx4 v[116:119], v[92:93], off
	global_load_dwordx4 v[120:123], v[94:95], off
	v_pk_mul_f32 v[128:129], v[24:25], v[136:137] op_sel_hi:[1,0]
	global_store_dwordx2 v[132:133], v[124:125], off offset:3072
	s_waitcnt vmcnt(0) lgkmcnt(0)
	v_pk_fma_f32 v[116:117], v[126:127], v[116:117], v[120:121]
	v_pk_fma_f32 v[118:119], v[128:129], v[118:119], v[122:123]
	v_cvt_pk_bf16_f32 v116, v116, v117
	s_nop 0
	v_cvt_pk_bf16_f32 v117, v118, v119
	global_store_dwordx2 v[132:133], v[116:117], off offset:3584
	s_cbranch_scc1 .LBB0_2626
	s_add_i32 s14, s10, s3
	s_cmpk_gt_i32 s14, 0x400f
	s_cselect_b64 s[12:13], -1, 0
	s_and_b64 vcc, exec, s[12:13]
	s_cbranch_vccnz .LBB0_2625
	s_ashr_i32 s15, s14, 31
	s_lshl_b64 s[8:9], s[14:15], 13
	v_lshl_add_u64 v[98:99], v[62:63], 0, s[8:9]
	global_load_dwordx4 v[2:5], v[98:99], off
	global_load_dwordx4 v[102:105], v[98:99], off offset:1024
	global_load_dwordx4 v[6:9], v[98:99], off offset:2048
	v_add_co_u32_e32 v100, vcc, 0x1000, v98
	s_mov_b32 s8, s14
	s_nop 0
	v_addc_co_u32_e32 v101, vcc, 0, v99, vcc
	global_load_dwordx4 v[10:13], v[100:101], off
	global_load_dwordx4 v[14:17], v[100:101], off offset:1024
	global_load_dwordx4 v[22:25], v[100:101], off offset:3072
	global_load_dwordx4 v[18:21], v[100:101], off offset:2048
	global_load_dwordx4 v[26:29], v[98:99], off offset:3072
	s_waitcnt vmcnt(0) lgkmcnt(0)
	v_mov_b32_e32 v99, v2
	v_mov_b32_e32 v101, v4
	v_mov_b32_e32 v98, v102
	v_mov_b32_e32 v2, v103
	v_mov_b32_e32 v100, v104
	v_mov_b32_e32 v4, v105
	v_mov_b32_e32 v102, v7
	v_mov_b32_e32 v103, v8
	v_mov_b32_e32 v7, v9
	v_mov_b32_e32 v8, v11
	v_mov_b32_e32 v104, v13
	v_mov_b32_e32 v106, v15
	v_mov_b32_e32 v107, v16
	v_mov_b32_e32 v15, v17
	v_mov_b32_e32 v16, v23
	v_mov_b32_e32 v108, v25
	s_branch .LBB0_2625

; template <int KSPLIT, class Epi>
; __device__ __forceinline__ void skinny_gemm(const bf16_t* __restrict__ A, int lda, const bf16_t* __restrict__ Wt, int K, int ntiles, char* lds, const Epi& E) {
;     ...
;     for (int base = 0; base < total; base += (int)gridDim.x * 8) {
;         const int slot = base + (int)blockIdx.x * 8 + wid, tile = slot / KSPLIT, ks = slot % KSPLIT;
;         const bool act = slot < total;
;         f32x4 acc = {0.f, 0.f, 0.f, 0.f};
;         if (act) {
;             const bf16_t* ap = A + (size_t)i * lda + ks * klen + 8 * kq;
;             const bf16_t* wp = Wt + (size_t)(tile * 16 + i) * K + ks * klen + 8 * kq;
;             for (int k = 0; k < klen; k += 256) {
;                 bf16x8 a[8], w[8];
; #pragma unroll
;                 for (int j = 0; j < 8; ++j) { a[j] = *(const bf16x8*)(ap + k + 32 * j); w[j] = *(const bf16x8*)(wp + k + 32 * j); }
; #pragma unroll
;                 for (int j = 0; j < 8; ++j) acc = __builtin_amdgcn_mfma_f32_16x16x32_bf16(w[j], a[j], acc, 0, 0, 0);
;             }
.LBB0_2693:
	s_add_i32 s21, s17, s18
	s_ashr_i32 s6, s21, 31
	s_lshr_b32 s6, s6, 30
	s_add_i32 s6, s21, s6
	s_ashr_i32 s19, s6, 2
	s_and_b32 s6, s6, -4
	s_sub_i32 s20, s21, s6
	v_mov_b32_e32 v4, v2
	v_mov_b32_e32 v5, v2
	v_mov_b32_e32 v3, v2
	s_cmpk_lt_i32 s21, 0x800
	v_mov_b64_e32 v[6:7], v[4:5]
	s_cselect_b64 s[6:7], -1, 0
	s_cmpk_gt_i32 s21, 0x7ff
	v_mov_b64_e32 v[4:5], v[2:3]
	s_cbranch_scc1 .LBB0_2695
	v_lshl_or_b32 v4, s19, 4, v1
	s_lshl_b32 s22, s20, 9
	v_ashrrev_i32_e32 v5, 31, v4
	s_ashr_i32 s23, s22, 31
	v_lshlrev_b64 v[4:5], 12, v[4:5]
	s_lshl_b64 s[22:23], s[22:23], 1
	v_lshl_add_u64 v[4:5], s[10:11], 0, v[4:5]
	v_lshl_add_u64 v[4:5], v[4:5], 0, s[22:23]
	v_mov_b32_e32 v13, v2
	v_lshl_add_u64 v[60:61], v[4:5], 0, v[12:13]
	global_load_dwordx4 v[4:7], v[60:61], off
	v_lshl_add_u64 v[62:63], v[8:9], 0, s[22:23]
	global_load_dwordx4 v[16:19], v[60:61], off offset:64
	global_load_dwordx4 v[20:23], v[62:63], off
	global_load_dwordx4 v[24:27], v[62:63], off offset:64
	global_load_dwordx4 v[28:31], v[60:61], off offset:128
	global_load_dwordx4 v[32:35], v[60:61], off offset:192
	global_load_dwordx4 v[36:39], v[62:63], off offset:128
	global_load_dwordx4 v[40:43], v[62:63], off offset:192
	global_load_dwordx4 v[44:47], v[60:61], off offset:256
	global_load_dwordx4 v[48:51], v[60:61], off offset:320
	global_load_dwordx4 v[52:55], v[62:63], off offset:256
	global_load_dwordx4 v[56:59], v[62:63], off offset:320
	s_waitcnt vmcnt(0) lgkmcnt(0)
	v_mfma_f32_16x16x32_bf16 v[4:7], v[4:7], v[20:23], 0
	global_load_dwordx4 v[20:23], v[60:61], off offset:384
	v_mfma_f32_16x16x32_bf16 v[4:7], v[16:19], v[24:27], v[4:7]
	global_load_dwordx4 v[16:19], v[62:63], off offset:384
	v_mfma_f32_16x16x32_bf16 v[4:7], v[28:31], v[36:39], v[4:7]
	global_load_dwordx4 v[24:27], v[60:61], off offset:448
	global_load_dwordx4 v[28:31], v[62:63], off offset:448
	v_mfma_f32_16x16x32_bf16 v[4:7], v[32:35], v[40:43], v[4:7]
	global_load_dwordx4 v[32:35], v[60:61], off offset:512
	global_load_dwordx4 v[36:39], v[60:61], off offset:576
	v_mfma_f32_16x16x32_bf16 v[4:7], v[44:47], v[52:55], v[4:7]
	global_load_dwordx4 v[40:43], v[62:63], off offset:512
	global_load_dwordx4 v[44:47], v[62:63], off offset:576
	v_mfma_f32_16x16x32_bf16 v[4:7], v[48:51], v[56:59], v[4:7]
	global_load_dwordx4 v[48:51], v[60:61], off offset:640
	s_waitcnt vmcnt(0) lgkmcnt(0)
	v_mfma_f32_16x16x32_bf16 v[4:7], v[20:23], v[16:19], v[4:7]
	global_load_dwordx4 v[16:19], v[62:63], off offset:640
	v_mfma_f32_16x16x32_bf16 v[4:7], v[24:27], v[28:31], v[4:7]
	global_load_dwordx4 v[20:23], v[60:61], off offset:704
	global_load_dwordx4 v[24:27], v[62:63], off offset:704
	v_mfma_f32_16x16x32_bf16 v[4:7], v[32:35], v[40:43], v[4:7]
	global_load_dwordx4 v[28:31], v[60:61], off offset:768
	global_load_dwordx4 v[32:35], v[62:63], off offset:768
	v_mfma_f32_16x16x32_bf16 v[4:7], v[36:39], v[44:47], v[4:7]
	global_load_dwordx4 v[36:39], v[60:61], off offset:832
	s_waitcnt vmcnt(0) lgkmcnt(0)
	v_mfma_f32_16x16x32_bf16 v[4:7], v[48:51], v[16:19], v[4:7]
	global_load_dwordx4 v[16:19], v[62:63], off offset:832
	v_mfma_f32_16x16x32_bf16 v[4:7], v[20:23], v[24:27], v[4:7]
	global_load_dwordx4 v[20:23], v[60:61], off offset:896
	global_load_dwordx4 v[24:27], v[62:63], off offset:896
	v_mfma_f32_16x16x32_bf16 v[4:7], v[28:31], v[32:35], v[4:7]
	global_load_dwordx4 v[28:31], v[60:61], off offset:960
	s_waitcnt vmcnt(0) lgkmcnt(0)
	v_mfma_f32_16x16x32_bf16 v[4:7], v[36:39], v[16:19], v[4:7]
	global_load_dwordx4 v[16:19], v[62:63], off offset:960
	v_mfma_f32_16x16x32_bf16 v[4:7], v[20:23], v[24:27], v[4:7]
	s_waitcnt vmcnt(0) lgkmcnt(0)
	v_mfma_f32_16x16x32_bf16 v[4:7], v[28:31], v[16:19], v[4:7]

; template <int KSPLIT, class Epi>
; __device__ __forceinline__ void skinny_gemm(const bf16_t* __restrict__ A, int lda, const bf16_t* __restrict__ Wt, int K, int ntiles, char* lds, const Epi& E) {
;     ...
;             __syncthreads();
;         }
;         if (act && ks == 0) E(tile, i, kq, acc);
;     }
; }
.LBB0_2699:
	s_and_b64 vcc, exec, s[6:7]
	s_barrier
	s_cbranch_vccnz .LBB0_2692
	v_max_f32_e32 v3, v4, v4
	v_max_f32_e32 v4, v5, v5
	v_max_f32_e32 v5, v6, v6
	v_max_f32_e32 v6, v7, v7
	v_max_f32_e32 v4, 0, v4
	v_max_f32_e32 v5, 0, v5
	v_max_f32_e32 v6, 0, v6
	s_lshl_b32 s6, s19, 4
	v_max_f32_e32 v3, 0, v3
	v_mul_f32_e32 v4, v4, v4
	v_mul_f32_e32 v5, v5, v5
	v_mul_f32_e32 v6, v6, v6
	s_ashr_i32 s7, s6, 31
	v_mul_f32_e32 v3, v3, v3
	v_cvt_pk_bf16_f32 v4, v3, v4
	v_cvt_pk_bf16_f32 v5, v5, v6
	v_lshl_add_u64 v[6:7], s[6:7], 1, v[10:11]
	global_store_dwordx2 v[6:7], v[4:5], off
	s_branch .LBB0_2692

; template <int KSPLIT, class Epi>
; __device__ __forceinline__ void skinny_gemm(const bf16_t* __restrict__ A, int lda, const bf16_t* __restrict__ Wt, int K, int ntiles, char* lds, const Epi& E) {
;     ...
;     for (int base = 0; base < total; base += (int)gridDim.x * 8) {
;         const int slot = base + (int)blockIdx.x * 8 + wid, tile = slot / KSPLIT, ks = slot % KSPLIT;
;         const bool act = slot < total;
;         f32x4 acc = {0.f, 0.f, 0.f, 0.f};
;         if (act) {
;             const bf16_t* ap = A + (size_t)i * lda + ks * klen + 8 * kq;
;             const bf16_t* wp = Wt + (size_t)(tile * 16 + i) * K + ks * klen + 8 * kq;
;             for (int k = 0; k < klen; k += 256) {
;                 bf16x8 a[8], w[8];
; #pragma unroll
;                 for (int j = 0; j < 8; ++j) { a[j] = *(const bf16x8*)(ap + k + 32 * j); w[j] = *(const bf16x8*)(wp + k + 32 * j); }
; #pragma unroll
;                 for (int j = 0; j < 8; ++j) acc = __builtin_amdgcn_mfma_f32_16x16x32_bf16(w[j], a[j], acc, 0, 0, 0);
;             }
.LBB0_2786:
	s_add_i32 s24, s20, s21
	s_ashr_i32 s6, s24, 31
	s_lshr_b32 s6, s6, 29
	s_add_i32 s6, s24, s6
	s_ashr_i32 s22, s6, 3
	s_and_b32 s6, s6, -8
	s_sub_i32 s23, s24, s6
	v_mov_b32_e32 v4, v2
	v_mov_b32_e32 v5, v2
	v_mov_b32_e32 v3, v2
	s_cmpk_lt_i32 s24, 0x400
	v_mov_b64_e32 v[6:7], v[4:5]
	s_cselect_b64 s[6:7], -1, 0
	s_cmpk_gt_i32 s24, 0x3ff
	v_mov_b64_e32 v[4:5], v[2:3]
	s_cbranch_scc1 .LBB0_2788
	v_lshl_or_b32 v4, s22, 4, v1
	s_lshl_b32 s24, s23, 10
	v_ashrrev_i32_e32 v5, 31, v4
	s_ashr_i32 s25, s24, 31
	v_lshlrev_b64 v[4:5], 14, v[4:5]
	s_lshl_b64 s[24:25], s[24:25], 1
	v_lshl_add_u64 v[4:5], s[14:15], 0, v[4:5]
	v_lshl_add_u64 v[4:5], v[4:5], 0, s[24:25]
	v_mov_b32_e32 v15, v2
	v_lshl_add_u64 v[84:85], v[4:5], 0, v[14:15]
	global_load_dwordx4 v[4:7], v[84:85], off
	v_lshl_add_u64 v[86:87], v[8:9], 0, s[24:25]
	global_load_dwordx4 v[20:23], v[84:85], off offset:64
	global_load_dwordx4 v[24:27], v[86:87], off
	global_load_dwordx4 v[28:31], v[86:87], off offset:64
	global_load_dwordx4 v[32:35], v[84:85], off offset:128
	global_load_dwordx4 v[36:39], v[84:85], off offset:192
	global_load_dwordx4 v[40:43], v[86:87], off offset:128
	global_load_dwordx4 v[44:47], v[86:87], off offset:192
	global_load_dwordx4 v[48:51], v[84:85], off offset:256
	global_load_dwordx4 v[52:55], v[86:87], off offset:256
	global_load_dwordx4 v[56:59], v[84:85], off offset:320
	global_load_dwordx4 v[60:63], v[86:87], off offset:320
	global_load_dwordx4 v[64:67], v[84:85], off offset:384
	global_load_dwordx4 v[68:71], v[84:85], off offset:448
	global_load_dwordx4 v[72:75], v[86:87], off offset:384
	global_load_dwordx4 v[76:79], v[86:87], off offset:448
	s_waitcnt vmcnt(0) lgkmcnt(0)
	v_mfma_f32_16x16x32_bf16 v[4:7], v[4:7], v[24:27], 0
	global_load_dwordx4 v[24:27], v[84:85], off offset:512
	global_load_dwordx4 v[80:83], v[84:85], off offset:576
	v_mfma_f32_16x16x32_bf16 v[4:7], v[20:23], v[28:31], v[4:7]
	global_load_dwordx4 v[20:23], v[86:87], off offset:512
	global_load_dwordx4 v[28:31], v[86:87], off offset:576
	v_mfma_f32_16x16x32_bf16 v[4:7], v[32:35], v[40:43], v[4:7]
	global_load_dwordx4 v[32:35], v[84:85], off offset:640
	global_load_dwordx4 v[40:43], v[86:87], off offset:640
	v_mfma_f32_16x16x32_bf16 v[4:7], v[36:39], v[44:47], v[4:7]
	global_load_dwordx4 v[36:39], v[84:85], off offset:704
	global_load_dwordx4 v[44:47], v[86:87], off offset:704
	v_mfma_f32_16x16x32_bf16 v[4:7], v[48:51], v[52:55], v[4:7]
	global_load_dwordx4 v[48:51], v[84:85], off offset:768
	global_load_dwordx4 v[52:55], v[84:85], off offset:832
	v_mfma_f32_16x16x32_bf16 v[4:7], v[56:59], v[60:63], v[4:7]
	global_load_dwordx4 v[56:59], v[86:87], off offset:768
	global_load_dwordx4 v[60:63], v[86:87], off offset:832
	v_mfma_f32_16x16x32_bf16 v[4:7], v[64:67], v[72:75], v[4:7]
	v_mfma_f32_16x16x32_bf16 v[4:7], v[68:71], v[76:79], v[4:7]
	global_load_dwordx4 v[64:67], v[84:85], off offset:896
	global_load_dwordx4 v[68:71], v[84:85], off offset:960
	s_waitcnt vmcnt(0) lgkmcnt(0)
	v_mfma_f32_16x16x32_bf16 v[4:7], v[24:27], v[20:23], v[4:7]
	global_load_dwordx4 v[20:23], v[86:87], off offset:896
	global_load_dwordx4 v[24:27], v[86:87], off offset:960
	v_mfma_f32_16x16x32_bf16 v[4:7], v[80:83], v[28:31], v[4:7]
	global_load_dwordx4 v[28:31], v[84:85], off offset:1024
	global_load_dwordx4 v[72:75], v[86:87], off offset:1024
	v_mfma_f32_16x16x32_bf16 v[4:7], v[32:35], v[40:43], v[4:7]
	global_load_dwordx4 v[32:35], v[84:85], off offset:1088
	v_mfma_f32_16x16x32_bf16 v[4:7], v[36:39], v[44:47], v[4:7]
	global_load_dwordx4 v[36:39], v[86:87], off offset:1088
	global_load_dwordx4 v[40:43], v[84:85], off offset:1152
	global_load_dwordx4 v[44:47], v[84:85], off offset:1216
	v_mfma_f32_16x16x32_bf16 v[4:7], v[48:51], v[56:59], v[4:7]
	v_mfma_f32_16x16x32_bf16 v[4:7], v[52:55], v[60:63], v[4:7]
	global_load_dwordx4 v[48:51], v[86:87], off offset:1152
	global_load_dwordx4 v[52:55], v[86:87], off offset:1216
	s_waitcnt vmcnt(0) lgkmcnt(0)
	v_mfma_f32_16x16x32_bf16 v[4:7], v[64:67], v[20:23], v[4:7]
	global_load_dwordx4 v[20:23], v[84:85], off offset:1280
	global_load_dwordx4 v[56:59], v[84:85], off offset:1344
	v_mfma_f32_16x16x32_bf16 v[4:7], v[68:71], v[24:27], v[4:7]
	global_load_dwordx4 v[24:27], v[86:87], off offset:1280
	global_load_dwordx4 v[60:63], v[86:87], off offset:1344
	v_mfma_f32_16x16x32_bf16 v[4:7], v[28:31], v[72:75], v[4:7]
	global_load_dwordx4 v[28:31], v[84:85], off offset:1408
	v_mfma_f32_16x16x32_bf16 v[4:7], v[32:35], v[36:39], v[4:7]
	global_load_dwordx4 v[32:35], v[86:87], off offset:1408
	v_mfma_f32_16x16x32_bf16 v[4:7], v[40:43], v[48:51], v[4:7]
	global_load_dwordx4 v[36:39], v[84:85], off offset:1472
	global_load_dwordx4 v[40:43], v[86:87], off offset:1472
	v_mfma_f32_16x16x32_bf16 v[4:7], v[44:47], v[52:55], v[4:7]
	global_load_dwordx4 v[44:47], v[84:85], off offset:1536
	global_load_dwordx4 v[48:51], v[84:85], off offset:1600
	s_waitcnt vmcnt(0) lgkmcnt(0)
	v_mfma_f32_16x16x32_bf16 v[4:7], v[20:23], v[24:27], v[4:7]
	global_load_dwordx4 v[20:23], v[86:87], off offset:1536
	global_load_dwordx4 v[24:27], v[86:87], off offset:1600
	global_load_dwordx4 v[52:55], v[84:85], off offset:1664
	v_mfma_f32_16x16x32_bf16 v[4:7], v[56:59], v[60:63], v[4:7]
	v_mfma_f32_16x16x32_bf16 v[4:7], v[28:31], v[32:35], v[4:7]
	global_load_dwordx4 v[28:31], v[86:87], off offset:1664
	v_mfma_f32_16x16x32_bf16 v[4:7], v[36:39], v[40:43], v[4:7]
	global_load_dwordx4 v[32:35], v[84:85], off offset:1728
	global_load_dwordx4 v[36:39], v[86:87], off offset:1728
	s_waitcnt vmcnt(0) lgkmcnt(0)
	v_mfma_f32_16x16x32_bf16 v[4:7], v[44:47], v[20:23], v[4:7]
	global_load_dwordx4 v[20:23], v[84:85], off offset:1792
	global_load_dwordx4 v[40:43], v[86:87], off offset:1792
	v_mfma_f32_16x16x32_bf16 v[4:7], v[48:51], v[24:27], v[4:7]
	global_load_dwordx4 v[24:27], v[84:85], off offset:1856
	v_mfma_f32_16x16x32_bf16 v[4:7], v[52:55], v[28:31], v[4:7]
	global_load_dwordx4 v[28:31], v[86:87], off offset:1856
	v_mfma_f32_16x16x32_bf16 v[4:7], v[32:35], v[36:39], v[4:7]
	global_load_dwordx4 v[32:35], v[84:85], off offset:1920
	global_load_dwordx4 v[36:39], v[86:87], off offset:1920
	s_waitcnt vmcnt(0) lgkmcnt(0)
	v_mfma_f32_16x16x32_bf16 v[4:7], v[20:23], v[40:43], v[4:7]
	global_load_dwordx4 v[20:23], v[84:85], off offset:1984
	v_mfma_f32_16x16x32_bf16 v[4:7], v[24:27], v[28:31], v[4:7]
	global_load_dwordx4 v[24:27], v[86:87], off offset:1984
	v_mfma_f32_16x16x32_bf16 v[4:7], v[32:35], v[36:39], v[4:7]
	s_waitcnt vmcnt(0) lgkmcnt(0)
	v_mfma_f32_16x16x32_bf16 v[4:7], v[20:23], v[24:27], v[4:7]

; __device__ __forceinline__ unsigned cvt_pk_bf16(float lo, float hi) { unsigned r; asm volatile("v_cvt_pk_bf16_f32 %0, %1, %2" : "=v"(r) : "v"(lo), "v"(hi)); return r; }
; __device__ __forceinline__ void ln_load(f32x4 (&v)[8], const float* z, int lane) {
; #pragma unroll
;     for (int j = 0; j < 8; ++j) v[j] = ((const f32x4*)z)[lane + 64 * j];
; }
; __device__ __forceinline__ void ln_apply(f32x4 (&v)[8], const float* __restrict__ g, const float* __restrict__ b, bf16_t* hb, float* fo, int lane) {
;     float s = 0.f;
; #pragma unroll
;     for (int j = 0; j < 8; ++j) s += (v[j][0] + v[j][1]) + (v[j][2] + v[j][3]);
;     const float mean = wave_sum(s) * (1.f / DM); float q = 0.f;
; #pragma unroll
;     for (int j = 0; j < 8; ++j) { v[j] = v[j] - mean; q += (v[j][0] * v[j][0] + v[j][1] * v[j][1]) + (v[j][2] * v[j][2] + v[j][3] * v[j][3]); }
;     const float rstd = rsqrtf(wave_sum(q) * (1.f / DM) + LN_EPS);
; #pragma unroll
;     for (int j = 0; j < 8; ++j) { const int c = (lane + 64 * j) * 4; const f32x4 gg = *(const f32x4*)(g + c), bb = *(const f32x4*)(b + c);
;         const f32x4 y = v[j] * rstd * gg + bb;
;         if (hb) { u32x2 w; w.x = cvt_pk_bf16(y[0], y[1]); w.y = cvt_pk_bf16(y[2], y[3]); *(u32x2*)(hb + c) = w; }
;         if (fo) *(f32x4*)(fo + c) = y; }
; }
; template <int L, int K>
; __device__ __forceinline__ void phase_body(char* lds, int rep_) {
;     ...
;         } else {
;             const float* lg_ = g2; const float* lb_ = b2;
;     ...
;             LN_ROWS(gw + NMETA, LTOK, NGW, ZR_, HR_, FR_);
;     ...
;         }
.LBB0_2876:
	s_cmp_lt_i32 s80, 19
	s_cselect_b64 s[4:5], -1, 0
	s_and_b64 s[4:5], s[4:5], s[36:37]
	s_andn2_b64 vcc, exec, s[4:5]
	s_cbranch_vccnz .LBB0_2889
	s_lshl_b32 s2, s2, 3
	v_readfirstlane_b32 s3, v194
	s_ashr_i32 s3, s3, 6
	s_add_i32 s2, s3, s2
	s_mov_b64 s[6:7], s[0:1]
	s_cmpk_gt_i32 s2, 0x3fff
	s_cbranch_scc1 .LBB0_2889
	s_load_dword s10, s[0:1], 0xa0
	s_load_dwordx4 s[16:19], s[6:7], 0x78
	s_load_dwordx2 s[4:5], s[6:7], 0x88
	v_and_b32_e32 v66, 63, v194
	v_lshlrev_b32_e32 v64, 4, v66
	s_waitcnt lgkmcnt(0)
	s_lshl_b32 s12, s10, 3
	s_add_u32 s0, s18, 0x2000
	s_addc_u32 s1, s19, 0
	s_add_u32 s8, s16, 0x2000
	s_addc_u32 s9, s17, 0
	s_ashr_i32 s3, s2, 31
	s_lshl_b64 s[6:7], s[2:3], 13
	s_add_u32 s6, s4, s6
	s_addc_u32 s7, s5, s7
	v_mov_b32_e32 v65, 0
	v_lshl_add_u64 v[32:33], s[6:7], 0, v[64:65]
	s_movk_i32 s3, 0x1000
	v_add_co_u32_e32 v34, vcc, s3, v32
	global_load_dwordx4 v[0:3], v[32:33], off
	global_load_dwordx4 v[4:7], v[32:33], off offset:1024
	global_load_dwordx4 v[8:11], v[32:33], off offset:2048
	v_addc_co_u32_e32 v35, vcc, 0, v33, vcc
	global_load_dwordx4 v[12:15], v[34:35], off
	global_load_dwordx4 v[16:19], v[34:35], off offset:1024
	global_load_dwordx4 v[20:23], v[34:35], off offset:2048
	global_load_dwordx4 v[24:27], v[34:35], off offset:3072
	global_load_dwordx4 v[28:31], v[32:33], off offset:3072
	v_mbcnt_lo_u32_b32 v68, -1, 0
	v_mbcnt_hi_u32_b32 v69, -1, v68
	v_and_b32_e32 v71, 64, v69
	v_xor_b32_e32 v73, 1, v69
	v_add_u32_e32 v71, 64, v71
	v_xor_b32_e32 v75, 2, v69
	v_cmp_lt_i32_e32 vcc, v73, v71
	v_xor_b32_e32 v76, 4, v69
	v_xor_b32_e32 v77, 8, v69
	v_cndmask_b32_e32 v73, v69, v73, vcc
	v_cmp_lt_i32_e32 vcc, v75, v71
	v_xor_b32_e32 v78, 16, v69
	v_xor_b32_e32 v79, 32, v69
	v_cndmask_b32_e32 v75, v69, v75, vcc
	v_cmp_lt_i32_e32 vcc, v76, v71
	v_lshlrev_b32_e32 v66, 2, v66
	v_or_b32_e32 v86, 0x400, v64
	v_cndmask_b32_e32 v80, v69, v76, vcc
	v_cmp_lt_i32_e32 vcc, v77, v71
	v_or_b32_e32 v88, 0x800, v64
	v_or_b32_e32 v68, 0x400, v66
	v_cndmask_b32_e32 v81, v69, v77, vcc
	v_cmp_lt_i32_e32 vcc, v78, v71
	v_lshl_add_u64 v[76:77], s[4:5], 0, v[64:65]
	v_lshl_add_u64 v[84:85], s[8:9], 0, v[64:65]
	v_cndmask_b32_e32 v78, v69, v78, vcc
	v_cmp_lt_i32_e32 vcc, v79, v71
	v_lshlrev_b32_e32 v118, 2, v78
	v_or_b32_e32 v70, 0x500, v66
	v_cndmask_b32_e32 v79, v69, v79, vcc
	v_lshlrev_b32_e32 v119, 2, v79
	v_lshl_add_u64 v[78:79], s[0:1], 0, v[64:65]
	v_or_b32_e32 v64, 0xc00, v64
	v_lshl_add_u64 v[90:91], s[8:9], 0, v[64:65]
	v_lshl_add_u64 v[92:93], s[0:1], 0, v[64:65]
	v_lshlrev_b32_e32 v64, 2, v68
	v_or_b32_e32 v72, 0x600, v66
	v_lshl_add_u64 v[94:95], s[8:9], 0, v[64:65]
	v_lshl_add_u64 v[96:97], s[0:1], 0, v[64:65]
	v_lshlrev_b32_e32 v64, 2, v70
	v_or_b32_e32 v74, 0x700, v66
	v_lshl_add_u64 v[98:99], s[8:9], 0, v[64:65]
	v_lshl_add_u64 v[100:101], s[0:1], 0, v[64:65]
	v_lshlrev_b32_e32 v64, 2, v72
	v_mov_b32_e32 v87, v65
	v_mov_b32_e32 v89, v65
	s_cmp_lg_u64 s[4:5], 0
	v_lshl_add_u64 v[102:103], s[8:9], 0, v[64:65]
	v_lshl_add_u64 v[104:105], s[0:1], 0, v[64:65]
	v_lshlrev_b32_e32 v64, 2, v74
	v_mov_b32_e32 v67, 0x3727c5ac
	s_mov_b32 s13, 0x800000
	v_lshlrev_b32_e32 v69, 2, v73
	v_lshlrev_b32_e32 v71, 2, v75
	v_lshlrev_b32_e32 v73, 2, v80
	v_lshlrev_b32_e32 v75, 2, v81
	v_lshl_add_u64 v[80:81], s[0:1], 0, v[86:87]
	v_lshl_add_u64 v[82:83], s[0:1], 0, v[88:89]
	v_lshl_add_u64 v[86:87], s[8:9], 0, v[86:87]
	v_lshl_add_u64 v[88:89], s[8:9], 0, v[88:89]
	s_cselect_b64 s[6:7], -1, 0
	s_lshl_b32 s14, s10, 4
	v_lshl_add_u64 v[106:107], s[8:9], 0, v[64:65]
	v_lshl_add_u64 v[108:109], s[0:1], 0, v[64:65]
	s_waitcnt vmcnt(0) lgkmcnt(0)
	v_mov_b32_e32 v111, v2
	v_mov_b32_e32 v110, v6
	v_mov_b32_e32 v2, v7
	v_mov_b32_e32 v7, v10
	v_mov_b32_e32 v112, v15
	v_mov_b32_e32 v115, v18
	v_mov_b32_e32 v116, v27
	s_branch .LBB0_2880

; __device__ __forceinline__ unsigned cvt_pk_bf16(float lo, float hi) { unsigned r; asm volatile("v_cvt_pk_bf16_f32 %0, %1, %2" : "=v"(r) : "v"(lo), "v"(hi)); return r; }
; __device__ __forceinline__ void ln_load(f32x4 (&v)[8], const float* z, int lane) {
; #pragma unroll
;     for (int j = 0; j < 8; ++j) v[j] = ((const f32x4*)z)[lane + 64 * j];
; }
; __device__ __forceinline__ void ln_apply(f32x4 (&v)[8], const float* __restrict__ g, const float* __restrict__ b, bf16_t* hb, float* fo, int lane) {
;     float s = 0.f;
; #pragma unroll
;     for (int j = 0; j < 8; ++j) s += (v[j][0] + v[j][1]) + (v[j][2] + v[j][3]);
;     const float mean = wave_sum(s) * (1.f / DM); float q = 0.f;
; #pragma unroll
;     for (int j = 0; j < 8; ++j) { v[j] = v[j] - mean; q += (v[j][0] * v[j][0] + v[j][1] * v[j][1]) + (v[j][2] * v[j][2] + v[j][3] * v[j][3]); }
;     const float rstd = rsqrtf(wave_sum(q) * (1.f / DM) + LN_EPS);
; #pragma unroll
;     for (int j = 0; j < 8; ++j) { const int c = (lane + 64 * j) * 4; const f32x4 gg = *(const f32x4*)(g + c), bb = *(const f32x4*)(b + c);
;         const f32x4 y = v[j] * rstd * gg + bb;
;         if (hb) { u32x2 w; w.x = cvt_pk_bf16(y[0], y[1]); w.y = cvt_pk_bf16(y[2], y[3]); *(u32x2*)(hb + c) = w; }
;         if (fo) *(f32x4*)(fo + c) = y; }
; }
.LBB0_2880:
	s_add_i32 s8, s12, s2
	s_add_i32 s10, s8, 16
	s_cmpk_gt_i32 s10, 0x400f
	s_cbranch_scc1 .LBB0_2882
	s_ashr_i32 s9, s8, 31
	s_lshl_b64 s[0:1], s[8:9], 13
	s_waitcnt vmcnt(0)
	v_lshl_add_u64 v[48:49], v[76:77], 0, s[0:1]
	v_add_co_u32_e32 v120, vcc, 0x1000, v48
	global_load_dwordx4 v[44:47], v[48:49], off
	global_load_dwordx4 v[40:43], v[48:49], off offset:1024
	global_load_dwordx4 v[36:39], v[48:49], off offset:2048
	global_load_dwordx4 v[32:35], v[48:49], off offset:3072
	v_addc_co_u32_e32 v121, vcc, 0, v49, vcc
	global_load_dwordx4 v[60:63], v[120:121], off
	global_load_dwordx4 v[56:59], v[120:121], off offset:1024
	global_load_dwordx4 v[52:55], v[120:121], off offset:2048
	global_load_dwordx4 v[48:51], v[120:121], off offset:3072
.LBB0_2882:
	v_mov_b32_e32 v120, v4
	v_mov_b32_e32 v121, v0
	v_mov_b32_e32 v122, v5
	v_mov_b32_e32 v123, v1
	v_pk_add_f32 v[120:121], v[120:121], v[122:123]
	v_pk_add_f32 v[122:123], v[110:111], v[2:3]
	s_waitcnt lgkmcnt(0)
	v_mov_b32_e32 v10, v8
	v_pk_add_f32 v[120:121], v[120:121], v[122:123]
	v_add_f32_e32 v123, v28, v29
	v_add_f32_e32 v6, 0, v121
	v_add_f32_e32 v113, v120, v6
	v_mov_b32_e32 v6, v9
	v_pk_add_f32 v[120:121], v[6:7], v[10:11]
	v_add_f32_e32 v125, v30, v31
	v_pk_add_f32 v[120:121], v[120:121], v[120:121] op_sel_hi:[0,1]
	v_mov_b32_e32 v122, v12
	v_mov_b32_e32 v124, v13
	v_mov_b32_e32 v15, v121
	v_pk_add_f32 v[122:123], v[122:123], v[124:125]
	v_pk_add_f32 v[120:121], v[14:15], v[112:113]
	v_mov_b32_e32 v114, v17
	v_mov_b32_e32 v18, v16
	v_pk_add_f32 v[120:121], v[122:123], v[120:121]
	v_pk_add_f32 v[122:123], v[114:115], v[18:19]
	v_pk_add_f32 v[120:121], v[120:121], v[120:121] op_sel_hi:[0,1]
	v_pk_add_f32 v[122:123], v[122:123], v[122:123] op_sel_hi:[0,1]
	v_add_f32_e32 v125, v20, v21
	v_add_f32_e32 v127, v22, v23
	v_mov_b32_e32 v124, v24
	v_mov_b32_e32 v126, v25
	v_mov_b32_e32 v27, v123
	v_mov_b32_e32 v117, v121
	v_pk_add_f32 v[124:125], v[124:125], v[126:127]
	v_pk_add_f32 v[120:121], v[26:27], v[116:117]
	s_andn2_b64 vcc, exec, s[6:7]
	v_pk_add_f32 v[120:121], v[124:125], v[120:121]
	s_nop 0
	v_add_f32_e32 v6, v120, v121
	ds_bpermute_b32 v10, v69, v6
	s_waitcnt lgkmcnt(0)
	v_add_f32_e32 v6, v6, v10
	ds_bpermute_b32 v10, v71, v6
	s_waitcnt lgkmcnt(0)
	v_add_f32_e32 v6, v6, v10
	ds_bpermute_b32 v10, v73, v6
	s_waitcnt lgkmcnt(0)
	v_add_f32_e32 v6, v6, v10
	ds_bpermute_b32 v10, v75, v6
	s_waitcnt lgkmcnt(0)
	v_add_f32_e32 v6, v6, v10
	ds_bpermute_b32 v10, v118, v6
	s_waitcnt lgkmcnt(0)
	v_add_f32_e32 v6, v6, v10
	ds_bpermute_b32 v10, v119, v6
	s_waitcnt lgkmcnt(0)
	v_add_f32_e32 v6, v6, v10
	v_fmac_f32_e32 v3, 0xba000000, v6
	v_fmac_f32_e32 v1, 0xba000000, v6
	v_fmac_f32_e32 v111, 0xba000000, v6
	v_fmac_f32_e32 v0, 0xba000000, v6
	v_mul_f32_e32 v10, v1, v1
	v_mul_f32_e32 v15, v3, v3
	v_fmac_f32_e32 v10, v0, v0
	v_fmac_f32_e32 v15, v111, v111
	v_fmac_f32_e32 v2, 0xba000000, v6
	v_fmac_f32_e32 v5, 0xba000000, v6
	v_add_f32_e32 v10, v10, v15
	v_fmac_f32_e32 v110, 0xba000000, v6
	v_fmac_f32_e32 v4, 0xba000000, v6
	v_mul_f32_e32 v15, v5, v5
	v_mul_f32_e32 v18, v2, v2
	v_fmac_f32_e32 v15, v4, v4
	v_fmac_f32_e32 v18, v110, v110
	v_add_f32_e32 v15, v15, v18
	v_fmac_f32_e32 v11, 0xba000000, v6
	v_fmac_f32_e32 v9, 0xba000000, v6
	v_add_f32_e32 v10, v10, v15
	v_fmac_f32_e32 v7, 0xba000000, v6
	v_fmac_f32_e32 v8, 0xba000000, v6
	v_mul_f32_e32 v15, v9, v9
	v_mul_f32_e32 v18, v11, v11
	v_fmac_f32_e32 v15, v8, v8
	v_fmac_f32_e32 v18, v7, v7
	v_add_f32_e32 v15, v15, v18
	v_fmac_f32_e32 v31, 0xba000000, v6
	v_fmac_f32_e32 v29, 0xba000000, v6
	v_add_f32_e32 v10, v15, v10
	v_fmac_f32_e32 v30, 0xba000000, v6
	v_fmac_f32_e32 v28, 0xba000000, v6
	v_mul_f32_e32 v15, v29, v29
	v_mul_f32_e32 v18, v31, v31
	v_fmac_f32_e32 v15, v28, v28
	v_fmac_f32_e32 v18, v30, v30
	v_add_f32_e32 v15, v15, v18
	v_fmac_f32_e32 v112, 0xba000000, v6
	v_fmac_f32_e32 v13, 0xba000000, v6
	v_add_f32_e32 v10, v15, v10
	v_fmac_f32_e32 v14, 0xba000000, v6
	v_fmac_f32_e32 v12, 0xba000000, v6
	v_mul_f32_e32 v15, v13, v13
	v_mul_f32_e32 v18, v112, v112
	v_fmac_f32_e32 v15, v12, v12
	v_fmac_f32_e32 v18, v14, v14
	v_add_f32_e32 v15, v15, v18
	v_fmac_f32_e32 v19, 0xba000000, v6
	v_fmac_f32_e32 v17, 0xba000000, v6
	v_add_f32_e32 v10, v15, v10
	v_fmac_f32_e32 v115, 0xba000000, v6
	v_fmac_f32_e32 v16, 0xba000000, v6
	v_mul_f32_e32 v15, v17, v17
	v_mul_f32_e32 v18, v19, v19
	v_fmac_f32_e32 v15, v16, v16
	v_fmac_f32_e32 v18, v115, v115
	v_add_f32_e32 v15, v15, v18
	v_fmac_f32_e32 v23, 0xba000000, v6
	v_fmac_f32_e32 v21, 0xba000000, v6
	v_add_f32_e32 v10, v15, v10
	v_fmac_f32_e32 v22, 0xba000000, v6
	v_fmac_f32_e32 v20, 0xba000000, v6
	v_mul_f32_e32 v15, v21, v21
	v_mul_f32_e32 v18, v23, v23
	v_fmac_f32_e32 v15, v20, v20
	v_fmac_f32_e32 v18, v22, v22
	v_add_f32_e32 v15, v15, v18
	v_fmac_f32_e32 v116, 0xba000000, v6
	v_fmac_f32_e32 v25, 0xba000000, v6
	v_add_f32_e32 v10, v15, v10
	v_fmac_f32_e32 v26, 0xba000000, v6
	v_fmac_f32_e32 v24, 0xba000000, v6
	v_mul_f32_e32 v6, v25, v25
	v_mul_f32_e32 v15, v116, v116
	v_fmac_f32_e32 v6, v24, v24
	v_fmac_f32_e32 v15, v26, v26
	v_add_f32_e32 v6, v6, v15
	v_add_f32_e32 v6, v6, v10
	ds_bpermute_b32 v10, v69, v6
	v_cndmask_b32_e64 v15, 0, 1, s[6:7]
	v_cmp_ne_u32_e64 s[0:1], 1, v15
	s_waitcnt lgkmcnt(0)
	v_add_f32_e32 v6, v6, v10
	ds_bpermute_b32 v10, v71, v6
	s_waitcnt lgkmcnt(0)
	v_add_f32_e32 v6, v6, v10
	ds_bpermute_b32 v10, v73, v6
	s_waitcnt lgkmcnt(0)
	v_add_f32_e32 v6, v6, v10
	ds_bpermute_b32 v10, v75, v6
	s_waitcnt lgkmcnt(0)
	v_add_f32_e32 v6, v6, v10
	ds_bpermute_b32 v10, v118, v6
	s_waitcnt lgkmcnt(0)
	v_add_f32_e32 v6, v6, v10
	ds_bpermute_b32 v10, v119, v6
	s_cbranch_vccnz .LBB0_2884
; __device__ __forceinline__ unsigned cvt_pk_bf16(float lo, float hi) { unsigned r; asm volatile("v_cvt_pk_bf16_f32 %0, %1, %2" : "=v"(r) : "v"(lo), "v"(hi)); return r; }
; __device__ __forceinline__ void ln_load(f32x4 (&v)[8], const float* z, int lane) {
; #pragma unroll
;     for (int j = 0; j < 8; ++j) v[j] = ((const f32x4*)z)[lane + 64 * j];
; }
; __device__ __forceinline__ void ln_apply(f32x4 (&v)[8], const float* __restrict__ g, const float* __restrict__ b, bf16_t* hb, float* fo, int lane) {
;     float s = 0.f;
; #pragma unroll
;     for (int j = 0; j < 8; ++j) s += (v[j][0] + v[j][1]) + (v[j][2] + v[j][3]);
;     const float mean = wave_sum(s) * (1.f / DM); float q = 0.f;
; #pragma unroll
;     for (int j = 0; j < 8; ++j) { v[j] = v[j] - mean; q += (v[j][0] * v[j][0] + v[j][1] * v[j][1]) + (v[j][2] * v[j][2] + v[j][3] * v[j][3]); }
;     const float rstd = rsqrtf(wave_sum(q) * (1.f / DM) + LN_EPS);
; #pragma unroll
;     for (int j = 0; j < 8; ++j) { const int c = (lane + 64 * j) * 4; const f32x4 gg = *(const f32x4*)(g + c), bb = *(const f32x4*)(b + c);
;         const f32x4 y = v[j] * rstd * gg + bb;
;         if (hb) { u32x2 w; w.x = cvt_pk_bf16(y[0], y[1]); w.y = cvt_pk_bf16(y[2], y[3]); *(u32x2*)(hb + c) = w; }
;         if (fo) *(f32x4*)(fo + c) = y; }
; }
	global_load_dwordx4 v[120:123], v[78:79], off
	global_load_dwordx4 v[124:127], v[84:85], off
	global_load_dwordx4 v[128:131], v[80:81], off
	global_load_dwordx4 v[132:135], v[86:87], off
	global_load_dwordx4 v[136:139], v[82:83], off
	global_load_dwordx4 v[140:143], v[88:89], off
	global_load_dwordx4 v[144:147], v[92:93], off
	global_load_dwordx4 v[148:151], v[90:91], off
	global_load_dwordx4 v[152:155], v[96:97], off
	global_load_dwordx4 v[156:159], v[94:95], off
	global_load_dwordx4 v[160:163], v[100:101], off
	global_load_dwordx4 v[164:167], v[98:99], off
	global_load_dwordx4 v[168:171], v[104:105], off
	global_load_dwordx4 v[172:175], v[102:103], off
	global_load_dwordx4 v[176:179], v[108:109], off
	global_load_dwordx4 v[180:183], v[106:107], off
	s_waitcnt lgkmcnt(0)
	v_add_f32_e32 v6, v6, v10
	v_fmamk_f32 v6, v6, 0x3a000000, v67
	v_mul_f32_e32 v113, 0x4b800000, v6
	v_cmp_gt_f32_e32 vcc, s13, v6
	s_ashr_i32 s3, s2, 31
	s_lshl_b64 s[16:17], s[2:3], 13
	v_cndmask_b32_e32 v6, v6, v113, vcc
	v_rsq_f32_e32 v6, v6
	s_add_u32 s16, s4, s16
	v_lshlrev_b32_e32 v64, 2, v66
	s_addc_u32 s17, s5, s17
	v_mul_f32_e32 v113, 0x45800000, v6
	v_mov_b32_e32 v184, v111
	v_mov_b32_e32 v185, v3
	v_lshl_add_u64 v[188:189], s[16:17], 0, v[64:65]
	v_lshlrev_b32_e32 v64, 2, v68
	v_cndmask_b32_e32 v6, v6, v113, vcc
	v_mov_b32_e32 v186, v110
	v_mov_b32_e32 v187, v2
	v_mov_b32_e32 v10, v7
	v_mov_b32_e32 v15, v112
	v_mov_b32_e32 v18, v115
	v_lshl_add_u64 v[190:191], s[16:17], 0, v[64:65]
	v_lshlrev_b32_e32 v64, 2, v70
	v_pk_mul_f32 v[198:199], v[0:1], v[6:7] op_sel_hi:[1,0]
	v_pk_mul_f32 v[184:185], v[184:185], v[6:7] op_sel_hi:[1,0]
	v_mov_b32_e32 v27, v116
	v_lshl_add_u64 v[192:193], s[16:17], 0, v[64:65]
	v_lshlrev_b32_e32 v64, 2, v72
	v_pk_mul_f32 v[200:201], v[4:5], v[6:7] op_sel_hi:[1,0]
	v_pk_mul_f32 v[186:187], v[186:187], v[6:7] op_sel_hi:[1,0]
	v_pk_mul_f32 v[202:203], v[8:9], v[6:7] op_sel_hi:[1,0]
	v_pk_mul_f32 v[204:205], v[10:11], v[6:7] op_sel_hi:[1,0]
	v_pk_mul_f32 v[206:207], v[28:29], v[6:7] op_sel_hi:[1,0]
	v_pk_mul_f32 v[208:209], v[30:31], v[6:7] op_sel_hi:[1,0]
	v_pk_mul_f32 v[210:211], v[12:13], v[6:7] op_sel_hi:[1,0]
	v_pk_mul_f32 v[212:213], v[14:15], v[6:7] op_sel_hi:[1,0]
	v_pk_mul_f32 v[214:215], v[16:17], v[6:7] op_sel_hi:[1,0]
	v_pk_mul_f32 v[216:217], v[18:19], v[6:7] op_sel_hi:[1,0]
	v_pk_mul_f32 v[218:219], v[22:23], v[6:7] op_sel_hi:[1,0]
	v_pk_mul_f32 v[220:221], v[20:21], v[6:7] op_sel_hi:[1,0]
	v_lshl_add_u64 v[194:195], s[16:17], 0, v[64:65]
	v_lshlrev_b32_e32 v64, 2, v74
	v_pk_mul_f32 v[222:223], v[26:27], v[6:7] op_sel_hi:[1,0]
	v_lshl_add_u64 v[196:197], s[16:17], 0, v[64:65]
	s_waitcnt vmcnt(0)
	v_pk_fma_f32 v[122:123], v[184:185], v[126:127], v[122:123]
	v_pk_fma_f32 v[120:121], v[198:199], v[124:125], v[120:121]
	v_pk_fma_f32 v[126:127], v[186:187], v[134:135], v[130:131]
	v_pk_fma_f32 v[124:125], v[200:201], v[132:133], v[128:129]
	v_pk_fma_f32 v[130:131], v[204:205], v[142:143], v[138:139]
	v_pk_fma_f32 v[128:129], v[202:203], v[140:141], v[136:137]
	v_pk_fma_f32 v[134:135], v[208:209], v[150:151], v[146:147]
	v_pk_fma_f32 v[132:133], v[206:207], v[148:149], v[144:145]
	v_pk_fma_f32 v[138:139], v[212:213], v[158:159], v[154:155]
	v_pk_fma_f32 v[136:137], v[210:211], v[156:157], v[152:153]
	v_pk_fma_f32 v[142:143], v[216:217], v[166:167], v[162:163]
	v_pk_fma_f32 v[140:141], v[214:215], v[164:165], v[160:161]
	v_pk_fma_f32 v[144:145], v[220:221], v[172:173], v[168:169]
	v_pk_fma_f32 v[146:147], v[218:219], v[174:175], v[170:171]
	global_store_dwordx4 v[188:189], v[120:123], off
	global_store_dwordx4 v[188:189], v[124:127], off offset:1024
	global_store_dwordx4 v[188:189], v[128:131], off offset:2048
	global_store_dwordx4 v[188:189], v[132:135], off offset:3072
	global_store_dwordx4 v[190:191], v[136:139], off
	global_store_dwordx4 v[192:193], v[140:143], off
	global_store_dwordx4 v[194:195], v[144:147], off
	v_pk_mul_f32 v[120:121], v[24:25], v[6:7] op_sel_hi:[1,0]
	v_pk_fma_f32 v[122:123], v[222:223], v[182:183], v[178:179]
	v_pk_fma_f32 v[120:121], v[120:121], v[180:181], v[176:177]
	global_store_dwordx4 v[196:197], v[120:123], off
.LBB0_2884:
	s_cmpk_gt_i32 s10, 0x400f
	s_mov_b64 s[10:11], -1
	s_cbranch_scc1 .LBB0_2879
	s_add_i32 s2, s14, s2
	s_add_i32 s3, s2, 16
	s_cmpk_gt_i32 s3, 0x400f
	s_cselect_b64 s[10:11], -1, 0
	s_and_b64 vcc, exec, s[10:11]
	s_cbranch_vccnz .LBB0_2887
	s_ashr_i32 s3, s2, 31
	s_lshl_b64 s[16:17], s[2:3], 13
	v_lshl_add_u64 v[110:111], v[76:77], 0, s[16:17]
	v_add_co_u32_e32 v112, vcc, 0x1000, v110
	global_load_dwordx4 v[0:3], v[110:111], off
	global_load_dwordx4 v[4:7], v[110:111], off offset:1024
	s_waitcnt lgkmcnt(0)
	global_load_dwordx4 v[8:11], v[110:111], off offset:2048
	v_addc_co_u32_e32 v113, vcc, 0, v111, vcc
	global_load_dwordx4 v[12:15], v[112:113], off
	global_load_dwordx4 v[16:19], v[112:113], off offset:1024
	global_load_dwordx4 v[20:23], v[112:113], off offset:2048
	global_load_dwordx4 v[24:27], v[112:113], off offset:3072
	global_load_dwordx4 v[28:31], v[110:111], off offset:3072
	s_waitcnt vmcnt(0)
	v_mov_b32_e32 v111, v2
	v_mov_b32_e32 v110, v6
	v_mov_b32_e32 v2, v7
	s_waitcnt lgkmcnt(0)
	v_mov_b32_e32 v7, v10
	v_mov_b32_e32 v112, v15
	v_mov_b32_e32 v115, v18
	v_mov_b32_e32 v116, v27
; __device__ __forceinline__ void ln_apply(f32x4 (&v)[8], const float* __restrict__ g, const float* __restrict__ b, bf16_t* hb, float* fo, int lane) {
;     float s = 0.f;
; #pragma unroll
;     for (int j = 0; j < 8; ++j) s += (v[j][0] + v[j][1]) + (v[j][2] + v[j][3]);
;     const float mean = wave_sum(s) * (1.f / DM); float q = 0.f;
; #pragma unroll
;     for (int j = 0; j < 8; ++j) { v[j] = v[j] - mean; q += (v[j][0] * v[j][0] + v[j][1] * v[j][1]) + (v[j][2] * v[j][2] + v[j][3] * v[j][3]); }
;     const float rstd = rsqrtf(wave_sum(q) * (1.f / DM) + LN_EPS);
.LBB0_2887:
	s_waitcnt vmcnt(0)
	v_mov_b32_e32 v120, v40
	v_mov_b32_e32 v121, v44
	v_mov_b32_e32 v122, v41
	v_mov_b32_e32 v123, v45
	v_pk_add_f32 v[120:121], v[120:121], v[122:123]
	v_mov_b32_e32 v122, v42
	v_mov_b32_e32 v123, v46
	v_mov_b32_e32 v124, v43
	v_mov_b32_e32 v125, v47
	v_pk_add_f32 v[122:123], v[122:123], v[124:125]
	v_mov_b32_e32 v124, v36
	v_pk_add_f32 v[120:121], v[120:121], v[122:123]
	v_mov_b32_e32 v122, v37
	v_mov_b32_e32 v123, v38
	v_mov_b32_e32 v125, v39
	v_pk_add_f32 v[122:123], v[122:123], v[124:125]
	v_add_f32_e32 v6, 0, v121
	v_pk_add_f32 v[122:123], v[122:123], v[122:123] op_sel_hi:[0,1]
	v_add_f32_e32 v121, v120, v6
	v_add_f32_e32 v125, v32, v33
	v_add_f32_e32 v127, v34, v35
	v_mov_b32_e32 v124, v60
	v_mov_b32_e32 v126, v61
	v_mov_b32_e32 v122, v62
	v_mov_b32_e32 v120, v63
	v_pk_add_f32 v[124:125], v[124:125], v[126:127]
	v_pk_add_f32 v[120:121], v[122:123], v[120:121]
	v_mov_b32_e32 v122, v57
	v_pk_add_f32 v[120:121], v[124:125], v[120:121]
	v_mov_b32_e32 v123, v58
	v_mov_b32_e32 v124, v56
	v_mov_b32_e32 v125, v59
	v_pk_add_f32 v[122:123], v[122:123], v[124:125]
	v_pk_add_f32 v[120:121], v[120:121], v[120:121] op_sel_hi:[0,1]
	v_pk_add_f32 v[122:123], v[122:123], v[122:123] op_sel_hi:[0,1]
	v_add_f32_e32 v125, v52, v53
	v_add_f32_e32 v127, v54, v55
	v_mov_b32_e32 v124, v48
	v_mov_b32_e32 v126, v49
	v_mov_b32_e32 v122, v50
	v_mov_b32_e32 v120, v51
	v_pk_add_f32 v[124:125], v[124:125], v[126:127]
	v_pk_add_f32 v[120:121], v[122:123], v[120:121]
	s_and_b64 vcc, exec, s[0:1]
	v_pk_add_f32 v[120:121], v[124:125], v[120:121]
	s_nop 0
	v_add_f32_e32 v6, v120, v121
	s_waitcnt lgkmcnt(0)
	ds_bpermute_b32 v10, v69, v6
	s_waitcnt lgkmcnt(0)
	v_add_f32_e32 v6, v6, v10
	ds_bpermute_b32 v10, v71, v6
	s_waitcnt lgkmcnt(0)
	v_add_f32_e32 v6, v6, v10
	ds_bpermute_b32 v10, v73, v6
	s_waitcnt lgkmcnt(0)
	v_add_f32_e32 v6, v6, v10
	ds_bpermute_b32 v10, v75, v6
	s_waitcnt lgkmcnt(0)
	v_add_f32_e32 v6, v6, v10
	ds_bpermute_b32 v10, v118, v6
	s_waitcnt lgkmcnt(0)
	v_add_f32_e32 v6, v6, v10
	ds_bpermute_b32 v10, v119, v6
	s_waitcnt lgkmcnt(0)
	v_add_f32_e32 v6, v6, v10
	v_fmamk_f32 v47, v6, 0xba000000, v47
	v_fmamk_f32 v45, v6, 0xba000000, v45
	v_fmamk_f32 v46, v6, 0xba000000, v46
	v_fmac_f32_e32 v44, 0xba000000, v6
	v_mul_f32_e32 v10, v45, v45
	v_mul_f32_e32 v15, v47, v47
	v_fmac_f32_e32 v10, v44, v44
	v_fmac_f32_e32 v15, v46, v46
	v_fmamk_f32 v43, v6, 0xba000000, v43
	v_fmamk_f32 v41, v6, 0xba000000, v41
	v_add_f32_e32 v10, v10, v15
	v_fmamk_f32 v42, v6, 0xba000000, v42
	v_fmac_f32_e32 v40, 0xba000000, v6
	v_mul_f32_e32 v15, v41, v41
	v_mul_f32_e32 v18, v43, v43
	v_fmac_f32_e32 v15, v40, v40
	v_fmac_f32_e32 v18, v42, v42
	v_add_f32_e32 v15, v15, v18
	v_fmamk_f32 v39, v6, 0xba000000, v39
	v_fmamk_f32 v37, v6, 0xba000000, v37
	v_add_f32_e32 v10, v10, v15
	v_fmamk_f32 v38, v6, 0xba000000, v38
	v_fmac_f32_e32 v36, 0xba000000, v6
	v_mul_f32_e32 v15, v37, v37
	v_mul_f32_e32 v18, v39, v39
	v_fmac_f32_e32 v15, v36, v36
	v_fmac_f32_e32 v18, v38, v38
	v_add_f32_e32 v15, v15, v18
	v_fmamk_f32 v35, v6, 0xba000000, v35
	v_fmamk_f32 v33, v6, 0xba000000, v33
	v_add_f32_e32 v10, v15, v10
	v_fmamk_f32 v34, v6, 0xba000000, v34
	v_fmac_f32_e32 v32, 0xba000000, v6
	v_mul_f32_e32 v15, v33, v33
	v_mul_f32_e32 v18, v35, v35
	v_fmac_f32_e32 v15, v32, v32
	v_fmac_f32_e32 v18, v34, v34
	v_add_f32_e32 v15, v15, v18
	v_fmamk_f32 v63, v6, 0xba000000, v63
	v_fmamk_f32 v61, v6, 0xba000000, v61
	v_add_f32_e32 v10, v15, v10
	v_fmamk_f32 v62, v6, 0xba000000, v62
	v_fmac_f32_e32 v60, 0xba000000, v6
	v_mul_f32_e32 v15, v61, v61
	v_mul_f32_e32 v18, v63, v63
	v_fmac_f32_e32 v15, v60, v60
	v_fmac_f32_e32 v18, v62, v62
	v_add_f32_e32 v15, v15, v18
	v_fmamk_f32 v59, v6, 0xba000000, v59
	v_fmamk_f32 v57, v6, 0xba000000, v57
	v_add_f32_e32 v10, v15, v10
	v_fmamk_f32 v58, v6, 0xba000000, v58
	v_fmac_f32_e32 v56, 0xba000000, v6
	v_mul_f32_e32 v15, v57, v57
	v_mul_f32_e32 v18, v59, v59
	v_fmac_f32_e32 v15, v56, v56
	v_fmac_f32_e32 v18, v58, v58
	v_add_f32_e32 v15, v15, v18
	v_fmamk_f32 v55, v6, 0xba000000, v55
	v_fmamk_f32 v53, v6, 0xba000000, v53
	v_add_f32_e32 v10, v15, v10
	v_fmamk_f32 v54, v6, 0xba000000, v54
	v_fmac_f32_e32 v52, 0xba000000, v6
	v_mul_f32_e32 v15, v53, v53
	v_mul_f32_e32 v18, v55, v55
	v_fmac_f32_e32 v15, v52, v52
	v_fmac_f32_e32 v18, v54, v54
	v_add_f32_e32 v15, v15, v18
	v_fmamk_f32 v51, v6, 0xba000000, v51
	v_fmamk_f32 v49, v6, 0xba000000, v49
	v_add_f32_e32 v10, v15, v10
	v_fmamk_f32 v50, v6, 0xba000000, v50
	v_fmac_f32_e32 v48, 0xba000000, v6
	v_mul_f32_e32 v6, v49, v49
	v_mul_f32_e32 v15, v51, v51
	v_fmac_f32_e32 v6, v48, v48
	v_fmac_f32_e32 v15, v50, v50
	v_add_f32_e32 v6, v6, v15
	v_add_f32_e32 v6, v6, v10
	ds_bpermute_b32 v10, v69, v6
	s_waitcnt lgkmcnt(0)
	v_add_f32_e32 v6, v6, v10
	ds_bpermute_b32 v10, v71, v6
	s_waitcnt lgkmcnt(0)
	v_add_f32_e32 v6, v6, v10
	ds_bpermute_b32 v10, v73, v6
	s_waitcnt lgkmcnt(0)
	v_add_f32_e32 v6, v6, v10
	ds_bpermute_b32 v10, v75, v6
	s_waitcnt lgkmcnt(0)
	v_add_f32_e32 v6, v6, v10
	ds_bpermute_b32 v10, v118, v6
	s_waitcnt lgkmcnt(0)
	v_add_f32_e32 v6, v6, v10
	ds_bpermute_b32 v10, v119, v6
	s_cbranch_vccnz .LBB0_2879
; __device__ __forceinline__ unsigned cvt_pk_bf16(float lo, float hi) { unsigned r; asm volatile("v_cvt_pk_bf16_f32 %0, %1, %2" : "=v"(r) : "v"(lo), "v"(hi)); return r; }
; __device__ __forceinline__ void ln_apply(f32x4 (&v)[8], const float* __restrict__ g, const float* __restrict__ b, bf16_t* hb, float* fo, int lane) {
;     ...
;     const float rstd = rsqrtf(wave_sum(q) * (1.f / DM) + LN_EPS);
; #pragma unroll
;     for (int j = 0; j < 8; ++j) { const int c = (lane + 64 * j) * 4; const f32x4 gg = *(const f32x4*)(g + c), bb = *(const f32x4*)(b + c);
;         const f32x4 y = v[j] * rstd * gg + bb;
;         if (hb) { u32x2 w; w.x = cvt_pk_bf16(y[0], y[1]); w.y = cvt_pk_bf16(y[2], y[3]); *(u32x2*)(hb + c) = w; }
;         if (fo) *(f32x4*)(fo + c) = y; }
	global_load_dwordx4 v[120:123], v[78:79], off
	global_load_dwordx4 v[124:127], v[84:85], off
	global_load_dwordx4 v[128:131], v[86:87], off
	global_load_dwordx4 v[132:135], v[80:81], off
	global_load_dwordx4 v[136:139], v[82:83], off
	global_load_dwordx4 v[140:143], v[88:89], off
	global_load_dwordx4 v[144:147], v[90:91], off
	global_load_dwordx4 v[148:151], v[92:93], off
	global_load_dwordx4 v[152:155], v[96:97], off
	global_load_dwordx4 v[156:159], v[94:95], off
	global_load_dwordx4 v[160:163], v[98:99], off
	global_load_dwordx4 v[164:167], v[100:101], off
	global_load_dwordx4 v[168:171], v[104:105], off
	global_load_dwordx4 v[172:175], v[102:103], off
	global_load_dwordx4 v[176:179], v[106:107], off
	global_load_dwordx4 v[180:183], v[108:109], off
	s_waitcnt lgkmcnt(0)
	v_add_f32_e32 v6, v6, v10
	v_fmamk_f32 v6, v6, 0x3a000000, v67
	v_mul_f32_e32 v10, 0x4b800000, v6
	v_cmp_gt_f32_e32 vcc, s13, v6
	s_ashr_i32 s9, s8, 31
	s_lshl_b64 s[0:1], s[8:9], 13
	v_cndmask_b32_e32 v6, v6, v10, vcc
	v_rsq_f32_e32 v6, v6
	s_add_u32 s0, s4, s0
	v_lshlrev_b32_e32 v64, 2, v66
	s_addc_u32 s1, s5, s1
	v_lshl_add_u64 v[184:185], s[0:1], 0, v[64:65]
	v_lshlrev_b32_e32 v64, 2, v68
	v_mul_f32_e32 v10, 0x45800000, v6
	v_lshl_add_u64 v[186:187], s[0:1], 0, v[64:65]
	v_lshlrev_b32_e32 v64, 2, v70
	v_cndmask_b32_e32 v6, v6, v10, vcc
	v_lshl_add_u64 v[188:189], s[0:1], 0, v[64:65]
	v_lshlrev_b32_e32 v64, 2, v72
	v_pk_mul_f32 v[194:195], v[44:45], v[6:7] op_sel_hi:[1,0]
	v_pk_mul_f32 v[196:197], v[46:47], v[6:7] op_sel_hi:[1,0]
	v_lshl_add_u64 v[190:191], s[0:1], 0, v[64:65]
	v_lshlrev_b32_e32 v64, 2, v74
	v_pk_mul_f32 v[198:199], v[40:41], v[6:7] op_sel_hi:[1,0]
	v_pk_mul_f32 v[200:201], v[42:43], v[6:7] op_sel_hi:[1,0]
	v_pk_mul_f32 v[202:203], v[36:37], v[6:7] op_sel_hi:[1,0]
	v_pk_mul_f32 v[204:205], v[38:39], v[6:7] op_sel_hi:[1,0]
	v_pk_mul_f32 v[206:207], v[32:33], v[6:7] op_sel_hi:[1,0]
	v_pk_mul_f32 v[208:209], v[34:35], v[6:7] op_sel_hi:[1,0]
	v_pk_mul_f32 v[210:211], v[60:61], v[6:7] op_sel_hi:[1,0]
	v_pk_mul_f32 v[212:213], v[62:63], v[6:7] op_sel_hi:[1,0]
	v_pk_mul_f32 v[214:215], v[56:57], v[6:7] op_sel_hi:[1,0]
	v_pk_mul_f32 v[216:217], v[58:59], v[6:7] op_sel_hi:[1,0]
	v_pk_mul_f32 v[218:219], v[54:55], v[6:7] op_sel_hi:[1,0]
	v_pk_mul_f32 v[220:221], v[52:53], v[6:7] op_sel_hi:[1,0]
	v_pk_mul_f32 v[222:223], v[50:51], v[6:7] op_sel_hi:[1,0]
	v_pk_mul_f32 v[224:225], v[48:49], v[6:7] op_sel_hi:[1,0]
	v_lshl_add_u64 v[192:193], s[0:1], 0, v[64:65]
	s_waitcnt vmcnt(0)
	v_pk_fma_f32 v[122:123], v[196:197], v[126:127], v[122:123]
	v_pk_fma_f32 v[120:121], v[194:195], v[124:125], v[120:121]
	v_pk_fma_f32 v[126:127], v[200:201], v[130:131], v[134:135]
	v_pk_fma_f32 v[124:125], v[198:199], v[128:129], v[132:133]
	v_pk_fma_f32 v[130:131], v[204:205], v[142:143], v[138:139]
	v_pk_fma_f32 v[128:129], v[202:203], v[140:141], v[136:137]
	v_pk_fma_f32 v[134:135], v[208:209], v[146:147], v[150:151]
	v_pk_fma_f32 v[132:133], v[206:207], v[144:145], v[148:149]
	v_pk_fma_f32 v[138:139], v[212:213], v[158:159], v[154:155]
	v_pk_fma_f32 v[136:137], v[210:211], v[156:157], v[152:153]
	v_pk_fma_f32 v[142:143], v[216:217], v[162:163], v[166:167]
	v_pk_fma_f32 v[140:141], v[214:215], v[160:161], v[164:165]
	v_pk_fma_f32 v[144:145], v[220:221], v[172:173], v[168:169]
	v_pk_fma_f32 v[146:147], v[218:219], v[174:175], v[170:171]
	v_pk_fma_f32 v[148:149], v[224:225], v[176:177], v[180:181]
	v_pk_fma_f32 v[150:151], v[222:223], v[178:179], v[182:183]
	global_store_dwordx4 v[184:185], v[120:123], off
	global_store_dwordx4 v[184:185], v[124:127], off offset:1024
	global_store_dwordx4 v[184:185], v[128:131], off offset:2048
	global_store_dwordx4 v[184:185], v[132:135], off offset:3072
	global_store_dwordx4 v[186:187], v[136:139], off
	global_store_dwordx4 v[188:189], v[140:143], off
	global_store_dwordx4 v[190:191], v[144:147], off
	global_store_dwordx4 v[192:193], v[148:151], off
	s_branch .LBB0_2879
